# stack + GEMM K-loop per-segment s_setprio flips removed (all 112 segments run at priority 0)
# speedup vs baseline: 1.0040x; 1.0040x over previous
; #define PG8_STAGE(bufoff, gbase, voff) do { _Pragma("unroll") for (int _i = 0; _i < 2; ++_i) \
;         __builtin_amdgcn_global_load_lds((const unsigned*)((const char*)(gbase) + (voff)[_i]), (LAS unsigned*)(lds + (bufoff) + ldsw + _i * 8192), 16, 0, 0); } while (0)
; #define PG8_LDA(dst, b, h) do { _Pragma("unroll") for (int m = 0; m < 4; ++m) _Pragma("unroll") for (int k = 0; k < 2; ++k) dst[m][k] = *(const LAS bf16x8*)(lds + PG8_SA(b, h) + aoff + m * 2048 + k * 1024); } while (0)
; #define PG8_LDB(dst, b, h) do { _Pragma("unroll") for (int n = 0; n < 2; ++n) _Pragma("unroll") for (int k = 0; k < 2; ++k) dst[n][k] = *(const LAS bf16x8*)(lds + PG8_SB(b, h) + boff + n * 2048 + k * 1024); } while (0)
; #define PG8_MMA(ai, bj, At, Bt) do { __builtin_amdgcn_s_setprio(1); _Pragma("unroll") for (int m = 0; m < 4; ++m) _Pragma("unroll") for (int n = 0; n < 2; ++n) _Pragma("unroll") for (int k = 0; k < 2; ++k) \
;         acc[ai][bj][m][n] = __builtin_amdgcn_mfma_f32_16x16x32_bf16(Bt[n][k], At[m][k], acc[ai][bj][m][n], 0, 0, 0); __builtin_amdgcn_s_setprio(0); } while (0)
; #define PG8_WAIT_V(n) asm volatile("s_waitcnt vmcnt(" #n ")" ::: "memory")
; #define PG8_WAIT_L(n) asm volatile("s_waitcnt lgkmcnt(" #n ")" ::: "memory")
; template <class Epi>
; DI void gemm_phase(LAS unsigned char* lds, const int wid, const Gemm g, const Order& S, const Epi& E) {
;     ...
;         const char* nA = has_next ? (const char*)(g.A + (size_t)nxt.g * g.gsA + (size_t)nxt.pm * BM * g.lda) : cA;
;         const char* nB = has_next ? (const char*)(g.Bt + (size_t)nxt.g * g.gsB + (size_t)nxt.pn * BM * g.ldb) : cB;
;         for (int t = 0; t < nt; t += 2) {
;             const bool last = (t == nt - 2);
;             const char* a1 = cA + (size_t)(t + 1) * kstep;
;             const char* a2 = last ? nA : cA + (size_t)(t + 2) * kstep; const char* b2 = last ? nB : cB + (size_t)(t + 2) * kstep;
;             const char* a3 = a2 + kstep; const char* b3 = b2 + kstep;
;             PG8_LDB(B0, 0, 0); PG8_LDB(B1, 0, 1); PG8_SCHED; PG8_LDA(At, 0, 0); PG8_STAGE(PG8_SA(1, 1), a1 + hstepA, voffA);
;             PG8_WAIT_V(8); PG8_WAIT_L(0); PG8_BAR; PG8_MMA(0, 0, At, B0); PG8_MMA(0, 1, At, B1); PG8_BAR; PG8_SCHED;
;             PG8_LDA(At, 0, 1); PG8_STAGE(PG8_SB(0, 0), b2, voffB); PG8_STAGE(PG8_SB(0, 1), b2 + hstepB, voffB); PG8_STAGE(PG8_SA(0, 0), a2, voffA);
.LBB0_227:
	s_ashr_i32 s31, s30, 31
	s_lshl_b64 s[36:37], s[30:31], 19
	s_add_u32 s36, s21, s36
	s_addc_u32 s37, s25, s37
	s_and_b64 s[38:39], s[6:7], exec
	s_cselect_b32 s31, s37, s43
	s_cselect_b32 s59, s36, s42
	s_ashr_i32 s35, s34, 31
	s_lshl_b64 s[38:39], s[34:35], 19
	s_add_u32 s38, s8, s38
	s_addc_u32 s39, s9, s39
	s_and_b64 s[46:47], s[6:7], exec
	s_cselect_b32 s35, s39, s45
	s_cselect_b32 s60, s38, s44
	s_add_u32 s42, s42, 0x40080
	s_addc_u32 s43, s43, 0
	s_add_u32 s61, s44, 0x100
	v_mov_b32_e32 v0, 0
	s_addc_u32 s62, s45, 0
	s_mov_b32 s63, -2
	s_lshl_b32 s74, s40, 8
	s_add_i32 s74, s74, s95
	v_mbcnt_lo_u32_b32 v244, -1, 0
	v_mbcnt_hi_u32_b32 v244, -1, v244
	v_and_or_b32 v244, v244, 15, s74
	v_ashrrev_i32_e32 v245, 31, v244
	v_lshl_add_u64 v[246:247], v[244:245], 2, s[12:13]
	global_load_dword v236, v[246:247], off
	global_load_dword v237, v[246:247], off offset:64
	global_load_dword v238, v[246:247], off offset:128
	global_load_dword v239, v[246:247], off offset:192
	global_load_dword v240, v[246:247], off offset:512
	global_load_dword v241, v[246:247], off offset:576
	global_load_dword v242, v[246:247], off offset:640
	global_load_dword v243, v[246:247], off offset:704
	ds_read_b128 v[164:167], v151
	ds_read_b128 v[168:171], v151 offset:1024
	ds_read_b128 v[172:175], v151 offset:2048
	ds_read_b128 v[176:179], v151 offset:3072
	ds_read_b128 v[180:183], v155
	ds_read_b128 v[184:187], v155 offset:1024
	ds_read_b128 v[188:191], v155 offset:2048
	ds_read_b128 v[192:195], v155 offset:3072
	s_add_u32 s44, s42, 0xfffc0080
	s_addc_u32 s45, s43, -1
	s_cmp_eq_u32 s63, 12
	s_cselect_b32 s47, s31, s45
	s_cselect_b32 s46, s59, s44
	s_cselect_b32 s45, s35, s62
	s_cselect_b32 s44, s60, s61
	v_lshl_add_u64 v[144:145], s[42:43], 0, v[136:137]
	s_add_i32 m0, s27, 0xc000
	ds_read_b128 v[196:199], v159
	ds_read_b128 v[200:203], v159 offset:1024
	ds_read_b128 v[204:207], v159 offset:2048
	ds_read_b128 v[208:211], v159 offset:3072
	ds_read_b128 v[216:219], v159 offset:4096
	ds_read_b128 v[220:223], v159 offset:5120
	ds_read_b128 v[224:227], v159 offset:6144
	ds_read_b128 v[228:231], v159 offset:7168
	global_load_lds_dwordx4 v[144:145], off
	v_lshl_add_u64 v[144:145], s[42:43], 0, v[138:139]
	s_add_i32 m0, s27, 0xe000
	s_nop 0
	global_load_lds_dwordx4 v[144:145], off
	s_waitcnt vmcnt(8)
	s_waitcnt lgkmcnt(0)
	s_barrier
	v_mfma_f32_16x16x32_bf16 v[124:127], v[164:167], v[196:199], 0
	v_mfma_f32_16x16x32_bf16 v[120:123], v[172:175], v[196:199], 0
	v_mfma_f32_16x16x32_bf16 v[108:111], v[164:167], v[204:207], 0
	v_mfma_f32_16x16x32_bf16 v[104:107], v[172:175], v[204:207], 0
	v_mfma_f32_16x16x32_bf16 v[92:95], v[164:167], v[216:219], 0
	v_mfma_f32_16x16x32_bf16 v[88:91], v[172:175], v[216:219], 0
	v_mfma_f32_16x16x32_bf16 v[76:79], v[164:167], v[224:227], 0
	v_mfma_f32_16x16x32_bf16 v[72:75], v[172:175], v[224:227], 0
	v_mfma_f32_16x16x32_bf16 v[124:127], v[168:171], v[200:203], v[124:127]
	v_mfma_f32_16x16x32_bf16 v[120:123], v[176:179], v[200:203], v[120:123]
	v_mfma_f32_16x16x32_bf16 v[108:111], v[168:171], v[208:211], v[108:111]
	v_mfma_f32_16x16x32_bf16 v[104:107], v[176:179], v[208:211], v[104:107]
	v_mfma_f32_16x16x32_bf16 v[92:95], v[168:171], v[220:223], v[92:95]
	v_mfma_f32_16x16x32_bf16 v[88:91], v[176:179], v[220:223], v[88:91]
	v_mfma_f32_16x16x32_bf16 v[76:79], v[168:171], v[228:231], v[76:79]
	v_mfma_f32_16x16x32_bf16 v[72:75], v[176:179], v[228:231], v[72:75]
	v_mfma_f32_16x16x32_bf16 v[116:119], v[180:183], v[196:199], 0
	v_mfma_f32_16x16x32_bf16 v[112:115], v[188:191], v[196:199], 0
	v_mfma_f32_16x16x32_bf16 v[100:103], v[180:183], v[204:207], 0
	v_mfma_f32_16x16x32_bf16 v[96:99], v[188:191], v[204:207], 0
	v_mfma_f32_16x16x32_bf16 v[84:87], v[180:183], v[216:219], 0
	v_mfma_f32_16x16x32_bf16 v[80:83], v[188:191], v[216:219], 0
	v_mfma_f32_16x16x32_bf16 v[68:71], v[180:183], v[224:227], 0
	v_mfma_f32_16x16x32_bf16 v[64:67], v[188:191], v[224:227], 0
	v_mfma_f32_16x16x32_bf16 v[116:119], v[184:187], v[200:203], v[116:119]
	v_mfma_f32_16x16x32_bf16 v[112:115], v[192:195], v[200:203], v[112:115]
	v_mfma_f32_16x16x32_bf16 v[100:103], v[184:187], v[208:211], v[100:103]
	v_mfma_f32_16x16x32_bf16 v[96:99], v[192:195], v[208:211], v[96:99]
	v_mfma_f32_16x16x32_bf16 v[84:87], v[184:187], v[220:223], v[84:87]
	v_mfma_f32_16x16x32_bf16 v[80:83], v[192:195], v[220:223], v[80:83]
	v_mfma_f32_16x16x32_bf16 v[68:71], v[184:187], v[228:231], v[68:71]
	v_mfma_f32_16x16x32_bf16 v[64:67], v[192:195], v[228:231], v[64:67]
	s_barrier
	s_add_i32 s64, s56, s94
	v_lshl_add_u64 v[144:145], s[44:45], 0, v[132:133]
	s_mov_b32 m0, s64
	ds_read_b128 v[196:199], v159 offset:16384
	ds_read_b128 v[200:203], v159 offset:17408
	ds_read_b128 v[204:207], v159 offset:18432
	ds_read_b128 v[208:211], v159 offset:19456
	ds_read_b128 v[216:219], v159 offset:20480
	ds_read_b128 v[220:223], v159 offset:21504
	ds_read_b128 v[224:227], v159 offset:22528
	ds_read_b128 v[228:231], v159 offset:23552
	global_load_lds_dwordx4 v[144:145], off
	s_add_i32 m0, s64, 0x2000
	s_add_u32 s64, s44, 0x40000
	v_lshl_add_u64 v[148:149], s[44:45], 0, v[128:129]
	s_addc_u32 s65, s45, 0
	s_add_i32 s66, s57, s94
	global_load_lds_dwordx4 v[148:149], off
	v_lshl_add_u64 v[152:153], s[64:65], 0, v[132:133]
	s_mov_b32 m0, s66
	v_lshl_add_u64 v[156:157], s[46:47], 0, v[130:131]
	global_load_lds_dwordx4 v[152:153], off
	v_lshl_add_u64 v[152:153], s[64:65], 0, v[128:129]
	s_add_i32 m0, s66, 0x2000
	s_nop 0
	global_load_lds_dwordx4 v[152:153], off
	v_lshl_add_u64 v[152:153], s[46:47], 0, v[134:135]
	s_mov_b32 m0, s27
	s_nop 0
	global_load_lds_dwordx4 v[152:153], off
	s_mov_b32 m0, s41
	s_nop 0
	global_load_lds_dwordx4 v[156:157], off
	s_waitcnt vmcnt(8)
	s_waitcnt lgkmcnt(0)
	s_barrier
; #define PG8_STAGE(bufoff, gbase, voff) do { _Pragma("unroll") for (int _i = 0; _i < 2; ++_i) \
;         __builtin_amdgcn_global_load_lds((const unsigned*)((const char*)(gbase) + (voff)[_i]), (LAS unsigned*)(lds + (bufoff) + ldsw + _i * 8192), 16, 0, 0); } while (0)
; #define PG8_LDA(dst, b, h) do { _Pragma("unroll") for (int m = 0; m < 4; ++m) _Pragma("unroll") for (int k = 0; k < 2; ++k) dst[m][k] = *(const LAS bf16x8*)(lds + PG8_SA(b, h) + aoff + m * 2048 + k * 1024); } while (0)
; #define PG8_LDB(dst, b, h) do { _Pragma("unroll") for (int n = 0; n < 2; ++n) _Pragma("unroll") for (int k = 0; k < 2; ++k) dst[n][k] = *(const LAS bf16x8*)(lds + PG8_SB(b, h) + boff + n * 2048 + k * 1024); } while (0)
; #define PG8_MMA(ai, bj, At, Bt) do { __builtin_amdgcn_s_setprio(1); _Pragma("unroll") for (int m = 0; m < 4; ++m) _Pragma("unroll") for (int n = 0; n < 2; ++n) _Pragma("unroll") for (int k = 0; k < 2; ++k) \
;         acc[ai][bj][m][n] = __builtin_amdgcn_mfma_f32_16x16x32_bf16(Bt[n][k], At[m][k], acc[ai][bj][m][n], 0, 0, 0); __builtin_amdgcn_s_setprio(0); } while (0)
; #define PG8_WAIT_V(n) asm volatile("s_waitcnt vmcnt(" #n ")" ::: "memory")
; #define PG8_WAIT_L(n) asm volatile("s_waitcnt lgkmcnt(" #n ")" ::: "memory")
; #define PG8_BAR __builtin_amdgcn_s_barrier()
; #define PG8_SCHED __builtin_amdgcn_sched_barrier(0)
; template <class Epi>
; DI void gemm_phase(LAS unsigned char* lds, const int wid, const Gemm g, const Order& S, const Epi& E) {
;     ...
;             PG8_WAIT_V(8); PG8_WAIT_L(0); PG8_BAR; PG8_MMA(1, 0, At, B0); PG8_MMA(1, 1, At, B1); PG8_BAR; PG8_SCHED;
;             PG8_LDB(B0, 1, 0); PG8_LDB(B1, 1, 1); PG8_SCHED; PG8_LDA(At, 1, 0); PG8_STAGE(PG8_SA(0, 1), a2 + hstepA, voffA);
;             PG8_WAIT_V(8); PG8_WAIT_L(0); PG8_BAR; PG8_MMA(0, 0, At, B0); PG8_MMA(0, 1, At, B1); PG8_BAR; PG8_SCHED;
	v_mfma_f32_16x16x32_bf16 v[60:63], v[164:167], v[196:199], 0
	v_mfma_f32_16x16x32_bf16 v[56:59], v[172:175], v[196:199], 0
	v_mfma_f32_16x16x32_bf16 v[44:47], v[164:167], v[204:207], 0
	v_mfma_f32_16x16x32_bf16 v[40:43], v[172:175], v[204:207], 0
	v_mfma_f32_16x16x32_bf16 v[28:31], v[164:167], v[216:219], 0
	v_mfma_f32_16x16x32_bf16 v[24:27], v[172:175], v[216:219], 0
	v_mfma_f32_16x16x32_bf16 v[12:15], v[164:167], v[224:227], 0
	v_mfma_f32_16x16x32_bf16 v[8:11], v[172:175], v[224:227], 0
	v_mfma_f32_16x16x32_bf16 v[60:63], v[168:171], v[200:203], v[60:63]
	v_mfma_f32_16x16x32_bf16 v[56:59], v[176:179], v[200:203], v[56:59]
	v_mfma_f32_16x16x32_bf16 v[44:47], v[168:171], v[208:211], v[44:47]
	v_mfma_f32_16x16x32_bf16 v[40:43], v[176:179], v[208:211], v[40:43]
	v_mfma_f32_16x16x32_bf16 v[28:31], v[168:171], v[220:223], v[28:31]
	v_mfma_f32_16x16x32_bf16 v[24:27], v[176:179], v[220:223], v[24:27]
	v_mfma_f32_16x16x32_bf16 v[12:15], v[168:171], v[228:231], v[12:15]
	v_mfma_f32_16x16x32_bf16 v[8:11], v[176:179], v[228:231], v[8:11]
	v_mfma_f32_16x16x32_bf16 v[52:55], v[180:183], v[196:199], 0
	v_mfma_f32_16x16x32_bf16 v[48:51], v[188:191], v[196:199], 0
	v_mfma_f32_16x16x32_bf16 v[36:39], v[180:183], v[204:207], 0
	v_mfma_f32_16x16x32_bf16 v[32:35], v[188:191], v[204:207], 0
	v_mfma_f32_16x16x32_bf16 v[20:23], v[180:183], v[216:219], 0
	v_mfma_f32_16x16x32_bf16 v[16:19], v[188:191], v[216:219], 0
	v_mfma_f32_16x16x32_bf16 v[4:7], v[180:183], v[224:227], 0
	v_mfma_f32_16x16x32_bf16 v[0:3], v[188:191], v[224:227], 0
	v_mfma_f32_16x16x32_bf16 v[52:55], v[184:187], v[200:203], v[52:55]
	v_mfma_f32_16x16x32_bf16 v[48:51], v[192:195], v[200:203], v[48:51]
	v_mfma_f32_16x16x32_bf16 v[36:39], v[184:187], v[208:211], v[36:39]
	v_mfma_f32_16x16x32_bf16 v[32:35], v[192:195], v[208:211], v[32:35]
	v_mfma_f32_16x16x32_bf16 v[20:23], v[184:187], v[220:223], v[20:23]
	v_mfma_f32_16x16x32_bf16 v[16:19], v[192:195], v[220:223], v[16:19]
	v_mfma_f32_16x16x32_bf16 v[4:7], v[184:187], v[228:231], v[4:7]
	v_mfma_f32_16x16x32_bf16 v[0:3], v[192:195], v[228:231], v[0:3]
	s_barrier
	s_add_i32 s64, 0, 0x18000
	v_add_u32_e32 v146, s64, v147
	s_add_i32 s65, 0, 0x1c000
	ds_read_b128 v[164:167], v146
	ds_read_b128 v[168:171], v146 offset:1024
	ds_read_b128 v[172:175], v146 offset:2048
	ds_read_b128 v[176:179], v146 offset:3072
	v_add_u32_e32 v146, s65, v147
	ds_read_b128 v[180:183], v146
	ds_read_b128 v[184:187], v146 offset:1024
	ds_read_b128 v[188:191], v146 offset:2048
	ds_read_b128 v[192:195], v146 offset:3072
	s_add_u32 s46, s46, 0x40000
	s_addc_u32 s47, s47, 0
	s_mov_b32 m0, s48
	v_lshl_add_u64 v[160:161], s[46:47], 0, v[134:135]
	ds_read_b128 v[196:199], v159 offset:32768
	ds_read_b128 v[200:203], v159 offset:33792
	ds_read_b128 v[204:207], v159 offset:34816
	ds_read_b128 v[208:211], v159 offset:35840
	ds_read_b128 v[216:219], v159 offset:36864
	ds_read_b128 v[220:223], v159 offset:37888
	ds_read_b128 v[224:227], v159 offset:38912
	ds_read_b128 v[228:231], v159 offset:39936
	global_load_lds_dwordx4 v[160:161], off
	v_lshl_add_u64 v[160:161], s[46:47], 0, v[130:131]
	s_mov_b32 m0, s49
	s_nop 0
	global_load_lds_dwordx4 v[160:161], off
	s_waitcnt vmcnt(8)
	s_waitcnt lgkmcnt(0)
	s_barrier
	v_mfma_f32_16x16x32_bf16 v[124:127], v[164:167], v[196:199], v[124:127]
	v_mfma_f32_16x16x32_bf16 v[120:123], v[172:175], v[196:199], v[120:123]
	v_mfma_f32_16x16x32_bf16 v[108:111], v[164:167], v[204:207], v[108:111]
	v_mfma_f32_16x16x32_bf16 v[104:107], v[172:175], v[204:207], v[104:107]
	v_mfma_f32_16x16x32_bf16 v[92:95], v[164:167], v[216:219], v[92:95]
	v_mfma_f32_16x16x32_bf16 v[88:91], v[172:175], v[216:219], v[88:91]
	v_mfma_f32_16x16x32_bf16 v[76:79], v[164:167], v[224:227], v[76:79]
	v_mfma_f32_16x16x32_bf16 v[72:75], v[172:175], v[224:227], v[72:75]
	v_mfma_f32_16x16x32_bf16 v[124:127], v[168:171], v[200:203], v[124:127]
	v_mfma_f32_16x16x32_bf16 v[120:123], v[176:179], v[200:203], v[120:123]
	v_mfma_f32_16x16x32_bf16 v[108:111], v[168:171], v[208:211], v[108:111]
	v_mfma_f32_16x16x32_bf16 v[104:107], v[176:179], v[208:211], v[104:107]
	v_mfma_f32_16x16x32_bf16 v[92:95], v[168:171], v[220:223], v[92:95]
	v_mfma_f32_16x16x32_bf16 v[88:91], v[176:179], v[220:223], v[88:91]
	v_mfma_f32_16x16x32_bf16 v[76:79], v[168:171], v[228:231], v[76:79]
	v_mfma_f32_16x16x32_bf16 v[72:75], v[176:179], v[228:231], v[72:75]
	v_mfma_f32_16x16x32_bf16 v[116:119], v[180:183], v[196:199], v[116:119]
	v_mfma_f32_16x16x32_bf16 v[112:115], v[188:191], v[196:199], v[112:115]
	v_mfma_f32_16x16x32_bf16 v[100:103], v[180:183], v[204:207], v[100:103]
	v_mfma_f32_16x16x32_bf16 v[96:99], v[188:191], v[204:207], v[96:99]
	v_mfma_f32_16x16x32_bf16 v[84:87], v[180:183], v[216:219], v[84:87]
	v_mfma_f32_16x16x32_bf16 v[80:83], v[188:191], v[216:219], v[80:83]
	v_mfma_f32_16x16x32_bf16 v[68:71], v[180:183], v[224:227], v[68:71]
	v_mfma_f32_16x16x32_bf16 v[64:67], v[188:191], v[224:227], v[64:67]
	v_mfma_f32_16x16x32_bf16 v[116:119], v[184:187], v[200:203], v[116:119]
	v_mfma_f32_16x16x32_bf16 v[112:115], v[192:195], v[200:203], v[112:115]
	v_mfma_f32_16x16x32_bf16 v[100:103], v[184:187], v[208:211], v[100:103]
	v_mfma_f32_16x16x32_bf16 v[96:99], v[192:195], v[208:211], v[96:99]
	v_mfma_f32_16x16x32_bf16 v[84:87], v[184:187], v[220:223], v[84:87]
	v_mfma_f32_16x16x32_bf16 v[80:83], v[192:195], v[220:223], v[80:83]
	v_mfma_f32_16x16x32_bf16 v[68:71], v[184:187], v[228:231], v[68:71]
	v_mfma_f32_16x16x32_bf16 v[64:67], v[192:195], v[228:231], v[64:67]
	s_barrier
; #define PG8_STAGE(bufoff, gbase, voff) do { _Pragma("unroll") for (int _i = 0; _i < 2; ++_i) \
;         __builtin_amdgcn_global_load_lds((const unsigned*)((const char*)(gbase) + (voff)[_i]), (LAS unsigned*)(lds + (bufoff) + ldsw + _i * 8192), 16, 0, 0); } while (0)
; #define PG8_LDA(dst, b, h) do { _Pragma("unroll") for (int m = 0; m < 4; ++m) _Pragma("unroll") for (int k = 0; k < 2; ++k) dst[m][k] = *(const LAS bf16x8*)(lds + PG8_SA(b, h) + aoff + m * 2048 + k * 1024); } while (0)
; #define PG8_LDB(dst, b, h) do { _Pragma("unroll") for (int n = 0; n < 2; ++n) _Pragma("unroll") for (int k = 0; k < 2; ++k) dst[n][k] = *(const LAS bf16x8*)(lds + PG8_SB(b, h) + boff + n * 2048 + k * 1024); } while (0)
; #define PG8_MMA(ai, bj, At, Bt) do { __builtin_amdgcn_s_setprio(1); _Pragma("unroll") for (int m = 0; m < 4; ++m) _Pragma("unroll") for (int n = 0; n < 2; ++n) _Pragma("unroll") for (int k = 0; k < 2; ++k) \
;         acc[ai][bj][m][n] = __builtin_amdgcn_mfma_f32_16x16x32_bf16(Bt[n][k], At[m][k], acc[ai][bj][m][n], 0, 0, 0); __builtin_amdgcn_s_setprio(0); } while (0)
; #define PG8_WAIT_V(n) asm volatile("s_waitcnt vmcnt(" #n ")" ::: "memory")
; #define PG8_WAIT_L(n) asm volatile("s_waitcnt lgkmcnt(" #n ")" ::: "memory")
; #define PG8_BAR __builtin_amdgcn_s_barrier()
; #define PG8_SCHED __builtin_amdgcn_sched_barrier(0)
; template <class Epi>
; DI void gemm_phase(LAS unsigned char* lds, const int wid, const Gemm g, const Order& S, const Epi& E) {
;     ...
;         for (int t = 0; t < nt; t += 2) {
;             const bool last = (t == nt - 2);
;             const char* a1 = cA + (size_t)(t + 1) * kstep;
;             const char* a2 = last ? nA : cA + (size_t)(t + 2) * kstep; const char* b2 = last ? nB : cB + (size_t)(t + 2) * kstep;
;             const char* a3 = a2 + kstep; const char* b3 = b2 + kstep;
;             PG8_LDB(B0, 0, 0); PG8_LDB(B1, 0, 1); PG8_SCHED; PG8_LDA(At, 0, 0); PG8_STAGE(PG8_SA(1, 1), a1 + hstepA, voffA);
;     ...
;             PG8_LDA(At, 1, 1); PG8_STAGE(PG8_SB(1, 0), b3, voffB); PG8_STAGE(PG8_SB(1, 1), b3 + hstepB, voffB); PG8_STAGE(PG8_SA(1, 0), a3, voffA);
;             PG8_WAIT_V(8); PG8_WAIT_L(0); PG8_BAR; PG8_MMA(1, 0, At, B0); PG8_MMA(1, 1, At, B1); PG8_BAR; PG8_SCHED;
	s_add_i32 s46, s64, s94
	v_lshl_add_u64 v[144:145], v[144:145], 0, s[16:17]
	s_mov_b32 m0, s46
	ds_read_b128 v[196:199], v159 offset:49152
	ds_read_b128 v[200:203], v159 offset:50176
	ds_read_b128 v[204:207], v159 offset:51200
	ds_read_b128 v[208:211], v159 offset:52224
	ds_read_b128 v[216:219], v159 offset:53248
	ds_read_b128 v[220:223], v159 offset:54272
	ds_read_b128 v[224:227], v159 offset:55296
	ds_read_b128 v[228:231], v159 offset:56320
	global_load_lds_dwordx4 v[144:145], off
	s_add_i32 m0, s46, 0x2000
	s_add_u32 s44, s44, 0x40080
	v_lshl_add_u64 v[144:145], v[148:149], 0, s[16:17]
	s_addc_u32 s45, s45, 0
	s_add_i32 s46, s65, s94
	global_load_lds_dwordx4 v[144:145], off
	v_lshl_add_u64 v[144:145], s[44:45], 0, v[132:133]
	s_mov_b32 m0, s46
	s_nop 0
	global_load_lds_dwordx4 v[144:145], off
	v_lshl_add_u64 v[144:145], s[44:45], 0, v[128:129]
	s_add_i32 m0, s46, 0x2000
	s_nop 0
	global_load_lds_dwordx4 v[144:145], off
	v_lshl_add_u64 v[144:145], v[152:153], 0, s[16:17]
	s_mov_b32 m0, s51
	s_nop 0
	global_load_lds_dwordx4 v[144:145], off
	v_lshl_add_u64 v[144:145], v[156:157], 0, s[16:17]
	s_mov_b32 m0, s52
	s_nop 0
	global_load_lds_dwordx4 v[144:145], off
	s_waitcnt vmcnt(8)
	s_waitcnt lgkmcnt(0)
	s_barrier
	v_mfma_f32_16x16x32_bf16 v[60:63], v[164:167], v[196:199], v[60:63]
	v_mfma_f32_16x16x32_bf16 v[56:59], v[172:175], v[196:199], v[56:59]
	v_mfma_f32_16x16x32_bf16 v[44:47], v[164:167], v[204:207], v[44:47]
	v_mfma_f32_16x16x32_bf16 v[40:43], v[172:175], v[204:207], v[40:43]
	v_mfma_f32_16x16x32_bf16 v[28:31], v[164:167], v[216:219], v[28:31]
	v_mfma_f32_16x16x32_bf16 v[24:27], v[172:175], v[216:219], v[24:27]
	v_mfma_f32_16x16x32_bf16 v[12:15], v[164:167], v[224:227], v[12:15]
	v_mfma_f32_16x16x32_bf16 v[8:11], v[172:175], v[224:227], v[8:11]
	v_mfma_f32_16x16x32_bf16 v[60:63], v[168:171], v[200:203], v[60:63]
	v_mfma_f32_16x16x32_bf16 v[56:59], v[176:179], v[200:203], v[56:59]
	v_mfma_f32_16x16x32_bf16 v[44:47], v[168:171], v[208:211], v[44:47]
	v_mfma_f32_16x16x32_bf16 v[40:43], v[176:179], v[208:211], v[40:43]
	v_mfma_f32_16x16x32_bf16 v[28:31], v[168:171], v[220:223], v[28:31]
	v_mfma_f32_16x16x32_bf16 v[24:27], v[176:179], v[220:223], v[24:27]
	v_mfma_f32_16x16x32_bf16 v[12:15], v[168:171], v[228:231], v[12:15]
	v_mfma_f32_16x16x32_bf16 v[8:11], v[176:179], v[228:231], v[8:11]
	v_mfma_f32_16x16x32_bf16 v[52:55], v[180:183], v[196:199], v[52:55]
	v_mfma_f32_16x16x32_bf16 v[48:51], v[188:191], v[196:199], v[48:51]
	v_mfma_f32_16x16x32_bf16 v[36:39], v[180:183], v[204:207], v[36:39]
	v_mfma_f32_16x16x32_bf16 v[32:35], v[188:191], v[204:207], v[32:35]
	v_mfma_f32_16x16x32_bf16 v[20:23], v[180:183], v[216:219], v[20:23]
	v_mfma_f32_16x16x32_bf16 v[16:19], v[188:191], v[216:219], v[16:19]
	v_mfma_f32_16x16x32_bf16 v[4:7], v[180:183], v[224:227], v[4:7]
	v_mfma_f32_16x16x32_bf16 v[0:3], v[188:191], v[224:227], v[0:3]
	v_mfma_f32_16x16x32_bf16 v[52:55], v[184:187], v[200:203], v[52:55]
	v_mfma_f32_16x16x32_bf16 v[48:51], v[192:195], v[200:203], v[48:51]
	v_mfma_f32_16x16x32_bf16 v[36:39], v[184:187], v[208:211], v[36:39]
	v_mfma_f32_16x16x32_bf16 v[32:35], v[192:195], v[208:211], v[32:35]
	v_mfma_f32_16x16x32_bf16 v[20:23], v[184:187], v[220:223], v[20:23]
	v_mfma_f32_16x16x32_bf16 v[16:19], v[192:195], v[220:223], v[16:19]
	v_mfma_f32_16x16x32_bf16 v[4:7], v[184:187], v[228:231], v[4:7]
	v_mfma_f32_16x16x32_bf16 v[0:3], v[192:195], v[228:231], v[0:3]
	s_barrier
	s_add_i32 s63, s63, 2
	s_add_u32 s42, s42, 0x100
	s_addc_u32 s43, s43, 0
	s_add_u32 s61, s61, 0x100
	s_addc_u32 s62, s62, 0
	s_cmp_gt_u32 s63, 13
	s_cbranch_scc0 .LBB0_228
	s_branch .Lpeel_exit_0
.LBB0_228:
	ds_read_b128 v[164:167], v151
	ds_read_b128 v[168:171], v151 offset:1024
	ds_read_b128 v[172:175], v151 offset:2048
	ds_read_b128 v[176:179], v151 offset:3072
	ds_read_b128 v[180:183], v155
	ds_read_b128 v[184:187], v155 offset:1024
	ds_read_b128 v[188:191], v155 offset:2048
	ds_read_b128 v[192:195], v155 offset:3072
	s_add_u32 s44, s42, 0xfffc0080
	s_addc_u32 s45, s43, -1
	s_cmp_eq_u32 s63, 12
	s_cselect_b32 s47, s31, s45
	s_cselect_b32 s46, s59, s44
	s_cselect_b32 s45, s35, s62
	s_cselect_b32 s44, s60, s61
	v_lshl_add_u64 v[144:145], s[42:43], 0, v[136:137]
	s_add_i32 m0, s27, 0xc000
	ds_read_b128 v[196:199], v159
	ds_read_b128 v[200:203], v159 offset:1024
	ds_read_b128 v[204:207], v159 offset:2048
	ds_read_b128 v[208:211], v159 offset:3072
	ds_read_b128 v[216:219], v159 offset:4096
	ds_read_b128 v[220:223], v159 offset:5120
	ds_read_b128 v[224:227], v159 offset:6144
	ds_read_b128 v[228:231], v159 offset:7168
	global_load_lds_dwordx4 v[144:145], off
	v_lshl_add_u64 v[144:145], s[42:43], 0, v[138:139]
	s_add_i32 m0, s27, 0xe000
	s_nop 0
	global_load_lds_dwordx4 v[144:145], off
	s_waitcnt vmcnt(8)
	s_waitcnt lgkmcnt(0)
	s_barrier
; #define PG8_STAGE(bufoff, gbase, voff) do { _Pragma("unroll") for (int _i = 0; _i < 2; ++_i) \
;         __builtin_amdgcn_global_load_lds((const unsigned*)((const char*)(gbase) + (voff)[_i]), (LAS unsigned*)(lds + (bufoff) + ldsw + _i * 8192), 16, 0, 0); } while (0)
; #define PG8_LDA(dst, b, h) do { _Pragma("unroll") for (int m = 0; m < 4; ++m) _Pragma("unroll") for (int k = 0; k < 2; ++k) dst[m][k] = *(const LAS bf16x8*)(lds + PG8_SA(b, h) + aoff + m * 2048 + k * 1024); } while (0)
; #define PG8_MMA(ai, bj, At, Bt) do { __builtin_amdgcn_s_setprio(1); _Pragma("unroll") for (int m = 0; m < 4; ++m) _Pragma("unroll") for (int n = 0; n < 2; ++n) _Pragma("unroll") for (int k = 0; k < 2; ++k) \
;         acc[ai][bj][m][n] = __builtin_amdgcn_mfma_f32_16x16x32_bf16(Bt[n][k], At[m][k], acc[ai][bj][m][n], 0, 0, 0); __builtin_amdgcn_s_setprio(0); } while (0)
; #define PG8_WAIT_V(n) asm volatile("s_waitcnt vmcnt(" #n ")" ::: "memory")
; #define PG8_WAIT_L(n) asm volatile("s_waitcnt lgkmcnt(" #n ")" ::: "memory")
; #define PG8_BAR __builtin_amdgcn_s_barrier()
; #define PG8_SCHED __builtin_amdgcn_sched_barrier(0)
; template <class Epi>
; DI void gemm_phase(LAS unsigned char* lds, const int wid, const Gemm g, const Order& S, const Epi& E) {
;     ...
;             PG8_WAIT_V(8); PG8_WAIT_L(0); PG8_BAR; PG8_MMA(0, 0, At, B0); PG8_MMA(0, 1, At, B1); PG8_BAR; PG8_SCHED;
;             PG8_LDA(At, 0, 1); PG8_STAGE(PG8_SB(0, 0), b2, voffB); PG8_STAGE(PG8_SB(0, 1), b2 + hstepB, voffB); PG8_STAGE(PG8_SA(0, 0), a2, voffA);
;             PG8_WAIT_V(8); PG8_WAIT_L(0); PG8_BAR; PG8_MMA(1, 0, At, B0); PG8_MMA(1, 1, At, B1); PG8_BAR; PG8_SCHED;
	v_mfma_f32_16x16x32_bf16 v[124:127], v[164:167], v[196:199], v[124:127]
	v_mfma_f32_16x16x32_bf16 v[120:123], v[172:175], v[196:199], v[120:123]
	v_mfma_f32_16x16x32_bf16 v[108:111], v[164:167], v[204:207], v[108:111]
	v_mfma_f32_16x16x32_bf16 v[104:107], v[172:175], v[204:207], v[104:107]
	v_mfma_f32_16x16x32_bf16 v[92:95], v[164:167], v[216:219], v[92:95]
	v_mfma_f32_16x16x32_bf16 v[88:91], v[172:175], v[216:219], v[88:91]
	v_mfma_f32_16x16x32_bf16 v[76:79], v[164:167], v[224:227], v[76:79]
	v_mfma_f32_16x16x32_bf16 v[72:75], v[172:175], v[224:227], v[72:75]
	v_mfma_f32_16x16x32_bf16 v[124:127], v[168:171], v[200:203], v[124:127]
	v_mfma_f32_16x16x32_bf16 v[120:123], v[176:179], v[200:203], v[120:123]
	v_mfma_f32_16x16x32_bf16 v[108:111], v[168:171], v[208:211], v[108:111]
	v_mfma_f32_16x16x32_bf16 v[104:107], v[176:179], v[208:211], v[104:107]
	v_mfma_f32_16x16x32_bf16 v[92:95], v[168:171], v[220:223], v[92:95]
	v_mfma_f32_16x16x32_bf16 v[88:91], v[176:179], v[220:223], v[88:91]
	v_mfma_f32_16x16x32_bf16 v[76:79], v[168:171], v[228:231], v[76:79]
	v_mfma_f32_16x16x32_bf16 v[72:75], v[176:179], v[228:231], v[72:75]
	v_mfma_f32_16x16x32_bf16 v[116:119], v[180:183], v[196:199], v[116:119]
	v_mfma_f32_16x16x32_bf16 v[112:115], v[188:191], v[196:199], v[112:115]
	v_mfma_f32_16x16x32_bf16 v[100:103], v[180:183], v[204:207], v[100:103]
	v_mfma_f32_16x16x32_bf16 v[96:99], v[188:191], v[204:207], v[96:99]
	v_mfma_f32_16x16x32_bf16 v[84:87], v[180:183], v[216:219], v[84:87]
	v_mfma_f32_16x16x32_bf16 v[80:83], v[188:191], v[216:219], v[80:83]
	v_mfma_f32_16x16x32_bf16 v[68:71], v[180:183], v[224:227], v[68:71]
	v_mfma_f32_16x16x32_bf16 v[64:67], v[188:191], v[224:227], v[64:67]
	v_mfma_f32_16x16x32_bf16 v[116:119], v[184:187], v[200:203], v[116:119]
	v_mfma_f32_16x16x32_bf16 v[112:115], v[192:195], v[200:203], v[112:115]
	v_mfma_f32_16x16x32_bf16 v[100:103], v[184:187], v[208:211], v[100:103]
	v_mfma_f32_16x16x32_bf16 v[96:99], v[192:195], v[208:211], v[96:99]
	v_mfma_f32_16x16x32_bf16 v[84:87], v[184:187], v[220:223], v[84:87]
	v_mfma_f32_16x16x32_bf16 v[80:83], v[192:195], v[220:223], v[80:83]
	v_mfma_f32_16x16x32_bf16 v[68:71], v[184:187], v[228:231], v[68:71]
	v_mfma_f32_16x16x32_bf16 v[64:67], v[192:195], v[228:231], v[64:67]
	s_barrier
	s_add_i32 s64, s56, s94
	v_lshl_add_u64 v[144:145], s[44:45], 0, v[132:133]
	s_mov_b32 m0, s64
	ds_read_b128 v[196:199], v159 offset:16384
	ds_read_b128 v[200:203], v159 offset:17408
	ds_read_b128 v[204:207], v159 offset:18432
	ds_read_b128 v[208:211], v159 offset:19456
	ds_read_b128 v[216:219], v159 offset:20480
	ds_read_b128 v[220:223], v159 offset:21504
	ds_read_b128 v[224:227], v159 offset:22528
	ds_read_b128 v[228:231], v159 offset:23552
	global_load_lds_dwordx4 v[144:145], off
	s_add_i32 m0, s64, 0x2000
	s_add_u32 s64, s44, 0x40000
	v_lshl_add_u64 v[148:149], s[44:45], 0, v[128:129]
	s_addc_u32 s65, s45, 0
	s_add_i32 s66, s57, s94
	global_load_lds_dwordx4 v[148:149], off
	v_lshl_add_u64 v[152:153], s[64:65], 0, v[132:133]
	s_mov_b32 m0, s66
	v_lshl_add_u64 v[156:157], s[46:47], 0, v[130:131]
	global_load_lds_dwordx4 v[152:153], off
	v_lshl_add_u64 v[152:153], s[64:65], 0, v[128:129]
	s_add_i32 m0, s66, 0x2000
	s_nop 0
	global_load_lds_dwordx4 v[152:153], off
	v_lshl_add_u64 v[152:153], s[46:47], 0, v[134:135]
	s_mov_b32 m0, s27
	s_nop 0
	global_load_lds_dwordx4 v[152:153], off
	s_mov_b32 m0, s41
	s_nop 0
	global_load_lds_dwordx4 v[156:157], off
	s_waitcnt vmcnt(8)
	s_waitcnt lgkmcnt(0)
	s_barrier
	v_mfma_f32_16x16x32_bf16 v[60:63], v[164:167], v[196:199], v[60:63]
	v_mfma_f32_16x16x32_bf16 v[56:59], v[172:175], v[196:199], v[56:59]
	v_mfma_f32_16x16x32_bf16 v[44:47], v[164:167], v[204:207], v[44:47]
	v_mfma_f32_16x16x32_bf16 v[40:43], v[172:175], v[204:207], v[40:43]
	v_mfma_f32_16x16x32_bf16 v[28:31], v[164:167], v[216:219], v[28:31]
	v_mfma_f32_16x16x32_bf16 v[24:27], v[172:175], v[216:219], v[24:27]
	v_mfma_f32_16x16x32_bf16 v[12:15], v[164:167], v[224:227], v[12:15]
	v_mfma_f32_16x16x32_bf16 v[8:11], v[172:175], v[224:227], v[8:11]
	v_mfma_f32_16x16x32_bf16 v[60:63], v[168:171], v[200:203], v[60:63]
	v_mfma_f32_16x16x32_bf16 v[56:59], v[176:179], v[200:203], v[56:59]
	v_mfma_f32_16x16x32_bf16 v[44:47], v[168:171], v[208:211], v[44:47]
	v_mfma_f32_16x16x32_bf16 v[40:43], v[176:179], v[208:211], v[40:43]
	v_mfma_f32_16x16x32_bf16 v[28:31], v[168:171], v[220:223], v[28:31]
	v_mfma_f32_16x16x32_bf16 v[24:27], v[176:179], v[220:223], v[24:27]
	v_mfma_f32_16x16x32_bf16 v[12:15], v[168:171], v[228:231], v[12:15]
	v_mfma_f32_16x16x32_bf16 v[8:11], v[176:179], v[228:231], v[8:11]
	v_mfma_f32_16x16x32_bf16 v[52:55], v[180:183], v[196:199], v[52:55]
	v_mfma_f32_16x16x32_bf16 v[48:51], v[188:191], v[196:199], v[48:51]
	v_mfma_f32_16x16x32_bf16 v[36:39], v[180:183], v[204:207], v[36:39]
	v_mfma_f32_16x16x32_bf16 v[32:35], v[188:191], v[204:207], v[32:35]
	v_mfma_f32_16x16x32_bf16 v[20:23], v[180:183], v[216:219], v[20:23]
	v_mfma_f32_16x16x32_bf16 v[16:19], v[188:191], v[216:219], v[16:19]
	v_mfma_f32_16x16x32_bf16 v[4:7], v[180:183], v[224:227], v[4:7]
	v_mfma_f32_16x16x32_bf16 v[0:3], v[188:191], v[224:227], v[0:3]
	v_mfma_f32_16x16x32_bf16 v[52:55], v[184:187], v[200:203], v[52:55]
	v_mfma_f32_16x16x32_bf16 v[48:51], v[192:195], v[200:203], v[48:51]
	v_mfma_f32_16x16x32_bf16 v[36:39], v[184:187], v[208:211], v[36:39]
	v_mfma_f32_16x16x32_bf16 v[32:35], v[192:195], v[208:211], v[32:35]
	v_mfma_f32_16x16x32_bf16 v[20:23], v[184:187], v[220:223], v[20:23]
	v_mfma_f32_16x16x32_bf16 v[16:19], v[192:195], v[220:223], v[16:19]
	v_mfma_f32_16x16x32_bf16 v[4:7], v[184:187], v[228:231], v[4:7]
	v_mfma_f32_16x16x32_bf16 v[0:3], v[192:195], v[228:231], v[0:3]
	s_barrier
; #define PG8_STAGE(bufoff, gbase, voff) do { _Pragma("unroll") for (int _i = 0; _i < 2; ++_i) \
;         __builtin_amdgcn_global_load_lds((const unsigned*)((const char*)(gbase) + (voff)[_i]), (LAS unsigned*)(lds + (bufoff) + ldsw + _i * 8192), 16, 0, 0); } while (0)
; #define PG8_LDA(dst, b, h) do { _Pragma("unroll") for (int m = 0; m < 4; ++m) _Pragma("unroll") for (int k = 0; k < 2; ++k) dst[m][k] = *(const LAS bf16x8*)(lds + PG8_SA(b, h) + aoff + m * 2048 + k * 1024); } while (0)
; #define PG8_LDB(dst, b, h) do { _Pragma("unroll") for (int n = 0; n < 2; ++n) _Pragma("unroll") for (int k = 0; k < 2; ++k) dst[n][k] = *(const LAS bf16x8*)(lds + PG8_SB(b, h) + boff + n * 2048 + k * 1024); } while (0)
; #define PG8_MMA(ai, bj, At, Bt) do { __builtin_amdgcn_s_setprio(1); _Pragma("unroll") for (int m = 0; m < 4; ++m) _Pragma("unroll") for (int n = 0; n < 2; ++n) _Pragma("unroll") for (int k = 0; k < 2; ++k) \
;         acc[ai][bj][m][n] = __builtin_amdgcn_mfma_f32_16x16x32_bf16(Bt[n][k], At[m][k], acc[ai][bj][m][n], 0, 0, 0); __builtin_amdgcn_s_setprio(0); } while (0)
; #define PG8_WAIT_V(n) asm volatile("s_waitcnt vmcnt(" #n ")" ::: "memory")
; #define PG8_WAIT_L(n) asm volatile("s_waitcnt lgkmcnt(" #n ")" ::: "memory")
; #define PG8_BAR __builtin_amdgcn_s_barrier()
; #define PG8_SCHED __builtin_amdgcn_sched_barrier(0)
; template <class Epi>
; DI void gemm_phase(LAS unsigned char* lds, const int wid, const Gemm g, const Order& S, const Epi& E) {
;     ...
;             PG8_LDB(B0, 1, 0); PG8_LDB(B1, 1, 1); PG8_SCHED; PG8_LDA(At, 1, 0); PG8_STAGE(PG8_SA(0, 1), a2 + hstepA, voffA);
;             PG8_WAIT_V(8); PG8_WAIT_L(0); PG8_BAR; PG8_MMA(0, 0, At, B0); PG8_MMA(0, 1, At, B1); PG8_BAR; PG8_SCHED;
;             PG8_LDA(At, 1, 1); PG8_STAGE(PG8_SB(1, 0), b3, voffB); PG8_STAGE(PG8_SB(1, 1), b3 + hstepB, voffB); PG8_STAGE(PG8_SA(1, 0), a3, voffA);
;             PG8_WAIT_V(8); PG8_WAIT_L(0); PG8_BAR; PG8_MMA(1, 0, At, B0); PG8_MMA(1, 1, At, B1); PG8_BAR; PG8_SCHED;
	s_add_i32 s64, 0, 0x18000
	v_add_u32_e32 v146, s64, v147
	s_add_i32 s65, 0, 0x1c000
	ds_read_b128 v[164:167], v146
	ds_read_b128 v[168:171], v146 offset:1024
	ds_read_b128 v[172:175], v146 offset:2048
	ds_read_b128 v[176:179], v146 offset:3072
	v_add_u32_e32 v146, s65, v147
	ds_read_b128 v[180:183], v146
	ds_read_b128 v[184:187], v146 offset:1024
	ds_read_b128 v[188:191], v146 offset:2048
	ds_read_b128 v[192:195], v146 offset:3072
	s_add_u32 s46, s46, 0x40000
	s_addc_u32 s47, s47, 0
	s_mov_b32 m0, s48
	v_lshl_add_u64 v[160:161], s[46:47], 0, v[134:135]
	ds_read_b128 v[196:199], v159 offset:32768
	ds_read_b128 v[200:203], v159 offset:33792
	ds_read_b128 v[204:207], v159 offset:34816
	ds_read_b128 v[208:211], v159 offset:35840
	ds_read_b128 v[216:219], v159 offset:36864
	ds_read_b128 v[220:223], v159 offset:37888
	ds_read_b128 v[224:227], v159 offset:38912
	ds_read_b128 v[228:231], v159 offset:39936
	global_load_lds_dwordx4 v[160:161], off
	v_lshl_add_u64 v[160:161], s[46:47], 0, v[130:131]
	s_mov_b32 m0, s49
	s_nop 0
	global_load_lds_dwordx4 v[160:161], off
	s_waitcnt vmcnt(8)
	s_waitcnt lgkmcnt(0)
	s_barrier
	v_mfma_f32_16x16x32_bf16 v[124:127], v[164:167], v[196:199], v[124:127]
	v_mfma_f32_16x16x32_bf16 v[120:123], v[172:175], v[196:199], v[120:123]
	v_mfma_f32_16x16x32_bf16 v[108:111], v[164:167], v[204:207], v[108:111]
	v_mfma_f32_16x16x32_bf16 v[104:107], v[172:175], v[204:207], v[104:107]
	v_mfma_f32_16x16x32_bf16 v[92:95], v[164:167], v[216:219], v[92:95]
	v_mfma_f32_16x16x32_bf16 v[88:91], v[172:175], v[216:219], v[88:91]
	v_mfma_f32_16x16x32_bf16 v[76:79], v[164:167], v[224:227], v[76:79]
	v_mfma_f32_16x16x32_bf16 v[72:75], v[172:175], v[224:227], v[72:75]
	v_mfma_f32_16x16x32_bf16 v[124:127], v[168:171], v[200:203], v[124:127]
	v_mfma_f32_16x16x32_bf16 v[120:123], v[176:179], v[200:203], v[120:123]
	v_mfma_f32_16x16x32_bf16 v[108:111], v[168:171], v[208:211], v[108:111]
	v_mfma_f32_16x16x32_bf16 v[104:107], v[176:179], v[208:211], v[104:107]
	v_mfma_f32_16x16x32_bf16 v[92:95], v[168:171], v[220:223], v[92:95]
	v_mfma_f32_16x16x32_bf16 v[88:91], v[176:179], v[220:223], v[88:91]
	v_mfma_f32_16x16x32_bf16 v[76:79], v[168:171], v[228:231], v[76:79]
	v_mfma_f32_16x16x32_bf16 v[72:75], v[176:179], v[228:231], v[72:75]
	v_mfma_f32_16x16x32_bf16 v[116:119], v[180:183], v[196:199], v[116:119]
	v_mfma_f32_16x16x32_bf16 v[112:115], v[188:191], v[196:199], v[112:115]
	v_mfma_f32_16x16x32_bf16 v[100:103], v[180:183], v[204:207], v[100:103]
	v_mfma_f32_16x16x32_bf16 v[96:99], v[188:191], v[204:207], v[96:99]
	v_mfma_f32_16x16x32_bf16 v[84:87], v[180:183], v[216:219], v[84:87]
	v_mfma_f32_16x16x32_bf16 v[80:83], v[188:191], v[216:219], v[80:83]
	v_mfma_f32_16x16x32_bf16 v[68:71], v[180:183], v[224:227], v[68:71]
	v_mfma_f32_16x16x32_bf16 v[64:67], v[188:191], v[224:227], v[64:67]
	v_mfma_f32_16x16x32_bf16 v[116:119], v[184:187], v[200:203], v[116:119]
	v_mfma_f32_16x16x32_bf16 v[112:115], v[192:195], v[200:203], v[112:115]
	v_mfma_f32_16x16x32_bf16 v[100:103], v[184:187], v[208:211], v[100:103]
	v_mfma_f32_16x16x32_bf16 v[96:99], v[192:195], v[208:211], v[96:99]
	v_mfma_f32_16x16x32_bf16 v[84:87], v[184:187], v[220:223], v[84:87]
	v_mfma_f32_16x16x32_bf16 v[80:83], v[192:195], v[220:223], v[80:83]
	v_mfma_f32_16x16x32_bf16 v[68:71], v[184:187], v[228:231], v[68:71]
	v_mfma_f32_16x16x32_bf16 v[64:67], v[192:195], v[228:231], v[64:67]
	s_barrier
	s_add_i32 s46, s64, s94
	v_lshl_add_u64 v[144:145], v[144:145], 0, s[16:17]
	s_mov_b32 m0, s46
	ds_read_b128 v[196:199], v159 offset:49152
	ds_read_b128 v[200:203], v159 offset:50176
	ds_read_b128 v[204:207], v159 offset:51200
	ds_read_b128 v[208:211], v159 offset:52224
	ds_read_b128 v[216:219], v159 offset:53248
	ds_read_b128 v[220:223], v159 offset:54272
	ds_read_b128 v[224:227], v159 offset:55296
	ds_read_b128 v[228:231], v159 offset:56320
	global_load_lds_dwordx4 v[144:145], off
	s_add_i32 m0, s46, 0x2000
	s_add_u32 s44, s44, 0x40080
	v_lshl_add_u64 v[144:145], v[148:149], 0, s[16:17]
	s_addc_u32 s45, s45, 0
	s_add_i32 s46, s65, s94
	global_load_lds_dwordx4 v[144:145], off
	v_lshl_add_u64 v[144:145], s[44:45], 0, v[132:133]
	s_mov_b32 m0, s46
	s_nop 0
	global_load_lds_dwordx4 v[144:145], off
	v_lshl_add_u64 v[144:145], s[44:45], 0, v[128:129]
	s_add_i32 m0, s46, 0x2000
	s_nop 0
	global_load_lds_dwordx4 v[144:145], off
	v_lshl_add_u64 v[144:145], v[152:153], 0, s[16:17]
	s_mov_b32 m0, s51
	s_nop 0
	global_load_lds_dwordx4 v[144:145], off
	v_lshl_add_u64 v[144:145], v[156:157], 0, s[16:17]
	s_mov_b32 m0, s52
	s_nop 0
	global_load_lds_dwordx4 v[144:145], off
	s_waitcnt vmcnt(8)
	s_waitcnt lgkmcnt(0)
	s_barrier
	v_mfma_f32_16x16x32_bf16 v[60:63], v[164:167], v[196:199], v[60:63]
	v_mfma_f32_16x16x32_bf16 v[56:59], v[172:175], v[196:199], v[56:59]
	v_mfma_f32_16x16x32_bf16 v[44:47], v[164:167], v[204:207], v[44:47]
	v_mfma_f32_16x16x32_bf16 v[40:43], v[172:175], v[204:207], v[40:43]
	v_mfma_f32_16x16x32_bf16 v[28:31], v[164:167], v[216:219], v[28:31]
	v_mfma_f32_16x16x32_bf16 v[24:27], v[172:175], v[216:219], v[24:27]
	v_mfma_f32_16x16x32_bf16 v[12:15], v[164:167], v[224:227], v[12:15]
	v_mfma_f32_16x16x32_bf16 v[8:11], v[172:175], v[224:227], v[8:11]
	v_mfma_f32_16x16x32_bf16 v[60:63], v[168:171], v[200:203], v[60:63]
	v_mfma_f32_16x16x32_bf16 v[56:59], v[176:179], v[200:203], v[56:59]
	v_mfma_f32_16x16x32_bf16 v[44:47], v[168:171], v[208:211], v[44:47]
	v_mfma_f32_16x16x32_bf16 v[40:43], v[176:179], v[208:211], v[40:43]
	v_mfma_f32_16x16x32_bf16 v[28:31], v[168:171], v[220:223], v[28:31]
	v_mfma_f32_16x16x32_bf16 v[24:27], v[176:179], v[220:223], v[24:27]
	v_mfma_f32_16x16x32_bf16 v[12:15], v[168:171], v[228:231], v[12:15]
	v_mfma_f32_16x16x32_bf16 v[8:11], v[176:179], v[228:231], v[8:11]
	v_mfma_f32_16x16x32_bf16 v[52:55], v[180:183], v[196:199], v[52:55]
	v_mfma_f32_16x16x32_bf16 v[48:51], v[188:191], v[196:199], v[48:51]
	v_mfma_f32_16x16x32_bf16 v[36:39], v[180:183], v[204:207], v[36:39]
	v_mfma_f32_16x16x32_bf16 v[32:35], v[188:191], v[204:207], v[32:35]
	v_mfma_f32_16x16x32_bf16 v[20:23], v[180:183], v[216:219], v[20:23]
	v_mfma_f32_16x16x32_bf16 v[16:19], v[188:191], v[216:219], v[16:19]
	v_mfma_f32_16x16x32_bf16 v[4:7], v[180:183], v[224:227], v[4:7]
	v_mfma_f32_16x16x32_bf16 v[0:3], v[188:191], v[224:227], v[0:3]
	v_mfma_f32_16x16x32_bf16 v[52:55], v[184:187], v[200:203], v[52:55]
	v_mfma_f32_16x16x32_bf16 v[48:51], v[192:195], v[200:203], v[48:51]
	v_mfma_f32_16x16x32_bf16 v[36:39], v[184:187], v[208:211], v[36:39]
	v_mfma_f32_16x16x32_bf16 v[32:35], v[192:195], v[208:211], v[32:35]
	v_mfma_f32_16x16x32_bf16 v[20:23], v[184:187], v[220:223], v[20:23]
	v_mfma_f32_16x16x32_bf16 v[16:19], v[192:195], v[220:223], v[16:19]
	v_mfma_f32_16x16x32_bf16 v[4:7], v[184:187], v[228:231], v[4:7]
	v_mfma_f32_16x16x32_bf16 v[0:3], v[192:195], v[228:231], v[0:3]
	s_barrier
	s_add_i32 s63, s63, 2
	s_add_u32 s42, s42, 0x100
	s_addc_u32 s43, s43, 0
	s_add_u32 s61, s61, 0x100
	s_addc_u32 s62, s62, 0
	s_cmp_gt_u32 s63, 13
	s_cbranch_scc0 .LBB0_228

; #define PG8_STAGE(bufoff, gbase, voff) do { _Pragma("unroll") for (int _i = 0; _i < 2; ++_i) \
;         __builtin_amdgcn_global_load_lds((const unsigned*)((const char*)(gbase) + (voff)[_i]), (LAS unsigned*)(lds + (bufoff) + ldsw + _i * 8192), 16, 0, 0); } while (0)
; #define PG8_LDA(dst, b, h) do { _Pragma("unroll") for (int m = 0; m < 4; ++m) _Pragma("unroll") for (int k = 0; k < 2; ++k) dst[m][k] = *(const LAS bf16x8*)(lds + PG8_SA(b, h) + aoff + m * 2048 + k * 1024); } while (0)
; #define PG8_LDB(dst, b, h) do { _Pragma("unroll") for (int n = 0; n < 2; ++n) _Pragma("unroll") for (int k = 0; k < 2; ++k) dst[n][k] = *(const LAS bf16x8*)(lds + PG8_SB(b, h) + boff + n * 2048 + k * 1024); } while (0)
; #define PG8_MMA(ai, bj, At, Bt) do { __builtin_amdgcn_s_setprio(1); _Pragma("unroll") for (int m = 0; m < 4; ++m) _Pragma("unroll") for (int n = 0; n < 2; ++n) _Pragma("unroll") for (int k = 0; k < 2; ++k) \
;         acc[ai][bj][m][n] = __builtin_amdgcn_mfma_f32_16x16x32_bf16(Bt[n][k], At[m][k], acc[ai][bj][m][n], 0, 0, 0); __builtin_amdgcn_s_setprio(0); } while (0)
; #define PG8_WAIT_V(n) asm volatile("s_waitcnt vmcnt(" #n ")" ::: "memory")
; #define PG8_WAIT_L(n) asm volatile("s_waitcnt lgkmcnt(" #n ")" ::: "memory")
; #define PG8_BAR __builtin_amdgcn_s_barrier()
; #define PG8_SCHED __builtin_amdgcn_sched_barrier(0)
; template <class Epi>
; DI void gemm_phase(LAS unsigned char* lds, const int wid, const Gemm g, const Order& S, const Epi& E) {
;     ...
;             const bool last = (t == nt - 2);
;             const char* a1 = cA + (size_t)(t + 1) * kstep;
;             const char* a2 = last ? nA : cA + (size_t)(t + 2) * kstep; const char* b2 = last ? nB : cB + (size_t)(t + 2) * kstep;
;             const char* a3 = a2 + kstep; const char* b3 = b2 + kstep;
;             PG8_LDB(B0, 0, 0); PG8_LDB(B1, 0, 1); PG8_SCHED; PG8_LDA(At, 0, 0); PG8_STAGE(PG8_SA(1, 1), a1 + hstepA, voffA);
;             PG8_WAIT_V(8); PG8_WAIT_L(0); PG8_BAR; PG8_MMA(0, 0, At, B0); PG8_MMA(0, 1, At, B1); PG8_BAR; PG8_SCHED;
;             PG8_LDA(At, 0, 1); PG8_STAGE(PG8_SB(0, 0), b2, voffB); PG8_STAGE(PG8_SB(0, 1), b2 + hstepB, voffB); PG8_STAGE(PG8_SA(0, 0), a2, voffA);
.LBB0_311:
	s_add_u32 s61, s44, 0x100
	v_mov_b32_e32 v0, 0
	s_addc_u32 s62, s45, 0
	s_mov_b32 s63, -2
	s_waitcnt lgkmcnt(0)
	ds_read_b128 v[128:131], v209
	ds_read_b128 v[132:135], v209 offset:1024
	ds_read_b128 v[136:139], v209 offset:2048
	ds_read_b128 v[140:143], v209 offset:3072
	ds_read_b128 v[144:147], v210
	ds_read_b128 v[148:151], v210 offset:1024
	ds_read_b128 v[152:155], v210 offset:2048
	ds_read_b128 v[156:159], v210 offset:3072
	s_add_u32 s10, s42, 0x100
	s_addc_u32 s11, s43, 0
	s_cmp_eq_u32 s63, 40
	s_cselect_b32 s47, s39, s11
	s_cselect_b32 s46, s38, s10
	s_cselect_b32 s45, s41, s62
	s_cselect_b32 s44, s40, s61
	v_lshl_add_u64 v[214:215], s[42:43], 0, v[184:185]
	s_add_i32 m0, s26, 0xc000
	ds_read_b128 v[160:163], v211
	ds_read_b128 v[164:167], v211 offset:1024
	ds_read_b128 v[168:171], v211 offset:2048
	ds_read_b128 v[172:175], v211 offset:3072
	ds_read_b128 v[192:195], v211 offset:4096
	ds_read_b128 v[196:199], v211 offset:5120
	ds_read_b128 v[200:203], v211 offset:6144
	ds_read_b128 v[204:207], v211 offset:7168
	global_load_lds_dwordx4 v[214:215], off
	v_lshl_add_u64 v[214:215], s[42:43], 0, v[186:187]
	s_add_i32 m0, s26, 0xe000
	s_nop 0
	global_load_lds_dwordx4 v[214:215], off
	s_waitcnt vmcnt(8)
	s_waitcnt lgkmcnt(0)
	s_barrier
	v_mfma_f32_16x16x32_bf16 v[124:127], v[128:131], v[160:163], 0
	v_mfma_f32_16x16x32_bf16 v[120:123], v[136:139], v[160:163], 0
	v_mfma_f32_16x16x32_bf16 v[108:111], v[128:131], v[168:171], 0
	v_mfma_f32_16x16x32_bf16 v[104:107], v[136:139], v[168:171], 0
	v_mfma_f32_16x16x32_bf16 v[92:95], v[128:131], v[192:195], 0
	v_mfma_f32_16x16x32_bf16 v[88:91], v[136:139], v[192:195], 0
	v_mfma_f32_16x16x32_bf16 v[76:79], v[128:131], v[200:203], 0
	v_mfma_f32_16x16x32_bf16 v[72:75], v[136:139], v[200:203], 0
	v_mfma_f32_16x16x32_bf16 v[124:127], v[132:135], v[164:167], v[124:127]
	v_mfma_f32_16x16x32_bf16 v[120:123], v[140:143], v[164:167], v[120:123]
	v_mfma_f32_16x16x32_bf16 v[108:111], v[132:135], v[172:175], v[108:111]
	v_mfma_f32_16x16x32_bf16 v[104:107], v[140:143], v[172:175], v[104:107]
	v_mfma_f32_16x16x32_bf16 v[92:95], v[132:135], v[196:199], v[92:95]
	v_mfma_f32_16x16x32_bf16 v[88:91], v[140:143], v[196:199], v[88:91]
	v_mfma_f32_16x16x32_bf16 v[76:79], v[132:135], v[204:207], v[76:79]
	v_mfma_f32_16x16x32_bf16 v[72:75], v[140:143], v[204:207], v[72:75]
	v_mfma_f32_16x16x32_bf16 v[116:119], v[144:147], v[160:163], 0
	v_mfma_f32_16x16x32_bf16 v[112:115], v[152:155], v[160:163], 0
	v_mfma_f32_16x16x32_bf16 v[100:103], v[144:147], v[168:171], 0
	v_mfma_f32_16x16x32_bf16 v[96:99], v[152:155], v[168:171], 0
	v_mfma_f32_16x16x32_bf16 v[84:87], v[144:147], v[192:195], 0
	v_mfma_f32_16x16x32_bf16 v[80:83], v[152:155], v[192:195], 0
	v_mfma_f32_16x16x32_bf16 v[68:71], v[144:147], v[200:203], 0
	v_mfma_f32_16x16x32_bf16 v[64:67], v[152:155], v[200:203], 0
	v_mfma_f32_16x16x32_bf16 v[116:119], v[148:151], v[164:167], v[116:119]
	v_mfma_f32_16x16x32_bf16 v[112:115], v[156:159], v[164:167], v[112:115]
	v_mfma_f32_16x16x32_bf16 v[100:103], v[148:151], v[172:175], v[100:103]
	v_mfma_f32_16x16x32_bf16 v[96:99], v[156:159], v[172:175], v[96:99]
	v_mfma_f32_16x16x32_bf16 v[84:87], v[148:151], v[196:199], v[84:87]
	v_mfma_f32_16x16x32_bf16 v[80:83], v[156:159], v[196:199], v[80:83]
	v_mfma_f32_16x16x32_bf16 v[68:71], v[148:151], v[204:207], v[68:71]
	v_mfma_f32_16x16x32_bf16 v[64:67], v[156:159], v[204:207], v[64:67]
	s_barrier
	s_add_i32 s42, s55, s94
	v_lshl_add_u64 v[214:215], s[44:45], 0, v[178:179]
	s_mov_b32 m0, s42
	ds_read_b128 v[160:163], v211 offset:16384
	ds_read_b128 v[164:167], v211 offset:17408
	ds_read_b128 v[168:171], v211 offset:18432
	ds_read_b128 v[172:175], v211 offset:19456
	ds_read_b128 v[192:195], v211 offset:20480
	ds_read_b128 v[196:199], v211 offset:21504
	ds_read_b128 v[200:203], v211 offset:22528
	ds_read_b128 v[204:207], v211 offset:23552
	global_load_lds_dwordx4 v[214:215], off
	s_add_i32 m0, s42, 0x2000
	s_add_u32 s42, s44, 0xb0000
	v_lshl_add_u64 v[216:217], s[44:45], 0, v[182:183]
	s_addc_u32 s43, s45, 0
	s_add_i32 s64, s56, s94
	global_load_lds_dwordx4 v[216:217], off
	v_lshl_add_u64 v[218:219], s[42:43], 0, v[178:179]
	s_mov_b32 m0, s64
	v_lshl_add_u64 v[220:221], s[46:47], 0, v[180:181]
	global_load_lds_dwordx4 v[218:219], off
	v_lshl_add_u64 v[218:219], s[42:43], 0, v[182:183]
	s_add_i32 m0, s64, 0x2000
	s_nop 0
	global_load_lds_dwordx4 v[218:219], off
	v_lshl_add_u64 v[218:219], s[46:47], 0, v[176:177]
	s_mov_b32 m0, s26
	s_nop 0
	global_load_lds_dwordx4 v[218:219], off
	s_mov_b32 m0, s27
	s_nop 0
	global_load_lds_dwordx4 v[220:221], off
	s_waitcnt vmcnt(8)
	s_waitcnt lgkmcnt(0)
	s_barrier
; #define PG8_STAGE(bufoff, gbase, voff) do { _Pragma("unroll") for (int _i = 0; _i < 2; ++_i) \
;         __builtin_amdgcn_global_load_lds((const unsigned*)((const char*)(gbase) + (voff)[_i]), (LAS unsigned*)(lds + (bufoff) + ldsw + _i * 8192), 16, 0, 0); } while (0)
; #define PG8_LDA(dst, b, h) do { _Pragma("unroll") for (int m = 0; m < 4; ++m) _Pragma("unroll") for (int k = 0; k < 2; ++k) dst[m][k] = *(const LAS bf16x8*)(lds + PG8_SA(b, h) + aoff + m * 2048 + k * 1024); } while (0)
; #define PG8_LDB(dst, b, h) do { _Pragma("unroll") for (int n = 0; n < 2; ++n) _Pragma("unroll") for (int k = 0; k < 2; ++k) dst[n][k] = *(const LAS bf16x8*)(lds + PG8_SB(b, h) + boff + n * 2048 + k * 1024); } while (0)
; #define PG8_MMA(ai, bj, At, Bt) do { __builtin_amdgcn_s_setprio(1); _Pragma("unroll") for (int m = 0; m < 4; ++m) _Pragma("unroll") for (int n = 0; n < 2; ++n) _Pragma("unroll") for (int k = 0; k < 2; ++k) \
;         acc[ai][bj][m][n] = __builtin_amdgcn_mfma_f32_16x16x32_bf16(Bt[n][k], At[m][k], acc[ai][bj][m][n], 0, 0, 0); __builtin_amdgcn_s_setprio(0); } while (0)
; #define PG8_WAIT_V(n) asm volatile("s_waitcnt vmcnt(" #n ")" ::: "memory")
; #define PG8_WAIT_L(n) asm volatile("s_waitcnt lgkmcnt(" #n ")" ::: "memory")
; #define PG8_BAR __builtin_amdgcn_s_barrier()
; #define PG8_SCHED __builtin_amdgcn_sched_barrier(0)
; template <class Epi>
; DI void gemm_phase(LAS unsigned char* lds, const int wid, const Gemm g, const Order& S, const Epi& E) {
;     ...
;             PG8_WAIT_V(8); PG8_WAIT_L(0); PG8_BAR; PG8_MMA(1, 0, At, B0); PG8_MMA(1, 1, At, B1); PG8_BAR; PG8_SCHED;
;             PG8_LDB(B0, 1, 0); PG8_LDB(B1, 1, 1); PG8_SCHED; PG8_LDA(At, 1, 0); PG8_STAGE(PG8_SA(0, 1), a2 + hstepA, voffA);
;             PG8_WAIT_V(8); PG8_WAIT_L(0); PG8_BAR; PG8_MMA(0, 0, At, B0); PG8_MMA(0, 1, At, B1); PG8_BAR; PG8_SCHED;
	v_mfma_f32_16x16x32_bf16 v[60:63], v[128:131], v[160:163], 0
	v_mfma_f32_16x16x32_bf16 v[56:59], v[136:139], v[160:163], 0
	v_mfma_f32_16x16x32_bf16 v[44:47], v[128:131], v[168:171], 0
	v_mfma_f32_16x16x32_bf16 v[40:43], v[136:139], v[168:171], 0
	v_mfma_f32_16x16x32_bf16 v[28:31], v[128:131], v[192:195], 0
	v_mfma_f32_16x16x32_bf16 v[24:27], v[136:139], v[192:195], 0
	v_mfma_f32_16x16x32_bf16 v[12:15], v[128:131], v[200:203], 0
	v_mfma_f32_16x16x32_bf16 v[8:11], v[136:139], v[200:203], 0
	v_mfma_f32_16x16x32_bf16 v[60:63], v[132:135], v[164:167], v[60:63]
	v_mfma_f32_16x16x32_bf16 v[56:59], v[140:143], v[164:167], v[56:59]
	v_mfma_f32_16x16x32_bf16 v[44:47], v[132:135], v[172:175], v[44:47]
	v_mfma_f32_16x16x32_bf16 v[40:43], v[140:143], v[172:175], v[40:43]
	v_mfma_f32_16x16x32_bf16 v[28:31], v[132:135], v[196:199], v[28:31]
	v_mfma_f32_16x16x32_bf16 v[24:27], v[140:143], v[196:199], v[24:27]
	v_mfma_f32_16x16x32_bf16 v[12:15], v[132:135], v[204:207], v[12:15]
	v_mfma_f32_16x16x32_bf16 v[8:11], v[140:143], v[204:207], v[8:11]
	v_mfma_f32_16x16x32_bf16 v[52:55], v[144:147], v[160:163], 0
	v_mfma_f32_16x16x32_bf16 v[48:51], v[152:155], v[160:163], 0
	v_mfma_f32_16x16x32_bf16 v[36:39], v[144:147], v[168:171], 0
	v_mfma_f32_16x16x32_bf16 v[32:35], v[152:155], v[168:171], 0
	v_mfma_f32_16x16x32_bf16 v[20:23], v[144:147], v[192:195], 0
	v_mfma_f32_16x16x32_bf16 v[16:19], v[152:155], v[192:195], 0
	v_mfma_f32_16x16x32_bf16 v[4:7], v[144:147], v[200:203], 0
	v_mfma_f32_16x16x32_bf16 v[0:3], v[152:155], v[200:203], 0
	v_mfma_f32_16x16x32_bf16 v[52:55], v[148:151], v[164:167], v[52:55]
	v_mfma_f32_16x16x32_bf16 v[48:51], v[156:159], v[164:167], v[48:51]
	v_mfma_f32_16x16x32_bf16 v[36:39], v[148:151], v[172:175], v[36:39]
	v_mfma_f32_16x16x32_bf16 v[32:35], v[156:159], v[172:175], v[32:35]
	v_mfma_f32_16x16x32_bf16 v[20:23], v[148:151], v[196:199], v[20:23]
	v_mfma_f32_16x16x32_bf16 v[16:19], v[156:159], v[196:199], v[16:19]
	v_mfma_f32_16x16x32_bf16 v[4:7], v[148:151], v[204:207], v[4:7]
	v_mfma_f32_16x16x32_bf16 v[0:3], v[156:159], v[204:207], v[0:3]
	s_barrier
	s_add_i32 s64, 0, 0x18000
	s_add_i32 s65, 0, 0x1c000
	v_add_u32_e32 v140, s64, v208
	v_add_u32_e32 v156, s65, v208
	ds_read_b128 v[128:131], v140
	ds_read_b128 v[132:135], v140 offset:1024
	ds_read_b128 v[136:139], v140 offset:2048
	ds_read_b128 v[140:143], v140 offset:3072
	ds_read_b128 v[144:147], v156
	ds_read_b128 v[148:151], v156 offset:1024
	ds_read_b128 v[152:155], v156 offset:2048
	ds_read_b128 v[156:159], v156 offset:3072
	s_add_u32 s42, s46, 0xb0000
	s_addc_u32 s43, s47, 0
	s_mov_b32 m0, s48
	v_lshl_add_u64 v[222:223], s[42:43], 0, v[176:177]
	ds_read_b128 v[160:163], v211 offset:32768
	ds_read_b128 v[164:167], v211 offset:33792
	ds_read_b128 v[168:171], v211 offset:34816
	ds_read_b128 v[172:175], v211 offset:35840
	ds_read_b128 v[192:195], v211 offset:36864
	ds_read_b128 v[196:199], v211 offset:37888
	ds_read_b128 v[200:203], v211 offset:38912
	ds_read_b128 v[204:207], v211 offset:39936
	global_load_lds_dwordx4 v[222:223], off
	v_lshl_add_u64 v[222:223], s[42:43], 0, v[180:181]
	s_mov_b32 m0, s49
	s_nop 0
	global_load_lds_dwordx4 v[222:223], off
	s_waitcnt vmcnt(8)
	s_waitcnt lgkmcnt(0)
	s_barrier
	v_mfma_f32_16x16x32_bf16 v[124:127], v[128:131], v[160:163], v[124:127]
	v_mfma_f32_16x16x32_bf16 v[120:123], v[136:139], v[160:163], v[120:123]
	v_mfma_f32_16x16x32_bf16 v[108:111], v[128:131], v[168:171], v[108:111]
	v_mfma_f32_16x16x32_bf16 v[104:107], v[136:139], v[168:171], v[104:107]
	v_mfma_f32_16x16x32_bf16 v[92:95], v[128:131], v[192:195], v[92:95]
	v_mfma_f32_16x16x32_bf16 v[88:91], v[136:139], v[192:195], v[88:91]
	v_mfma_f32_16x16x32_bf16 v[76:79], v[128:131], v[200:203], v[76:79]
	v_mfma_f32_16x16x32_bf16 v[72:75], v[136:139], v[200:203], v[72:75]
	v_mfma_f32_16x16x32_bf16 v[124:127], v[132:135], v[164:167], v[124:127]
	v_mfma_f32_16x16x32_bf16 v[120:123], v[140:143], v[164:167], v[120:123]
	v_mfma_f32_16x16x32_bf16 v[108:111], v[132:135], v[172:175], v[108:111]
	v_mfma_f32_16x16x32_bf16 v[104:107], v[140:143], v[172:175], v[104:107]
	v_mfma_f32_16x16x32_bf16 v[92:95], v[132:135], v[196:199], v[92:95]
	v_mfma_f32_16x16x32_bf16 v[88:91], v[140:143], v[196:199], v[88:91]
	v_mfma_f32_16x16x32_bf16 v[76:79], v[132:135], v[204:207], v[76:79]
	v_mfma_f32_16x16x32_bf16 v[72:75], v[140:143], v[204:207], v[72:75]
	v_mfma_f32_16x16x32_bf16 v[116:119], v[144:147], v[160:163], v[116:119]
	v_mfma_f32_16x16x32_bf16 v[112:115], v[152:155], v[160:163], v[112:115]
	v_mfma_f32_16x16x32_bf16 v[100:103], v[144:147], v[168:171], v[100:103]
	v_mfma_f32_16x16x32_bf16 v[96:99], v[152:155], v[168:171], v[96:99]
	v_mfma_f32_16x16x32_bf16 v[84:87], v[144:147], v[192:195], v[84:87]
	v_mfma_f32_16x16x32_bf16 v[80:83], v[152:155], v[192:195], v[80:83]
	v_mfma_f32_16x16x32_bf16 v[68:71], v[144:147], v[200:203], v[68:71]
	v_mfma_f32_16x16x32_bf16 v[64:67], v[152:155], v[200:203], v[64:67]
	v_mfma_f32_16x16x32_bf16 v[116:119], v[148:151], v[164:167], v[116:119]
	v_mfma_f32_16x16x32_bf16 v[112:115], v[156:159], v[164:167], v[112:115]
	v_mfma_f32_16x16x32_bf16 v[100:103], v[148:151], v[172:175], v[100:103]
	v_mfma_f32_16x16x32_bf16 v[96:99], v[156:159], v[172:175], v[96:99]
	v_mfma_f32_16x16x32_bf16 v[84:87], v[148:151], v[196:199], v[84:87]
	v_mfma_f32_16x16x32_bf16 v[80:83], v[156:159], v[196:199], v[80:83]
	v_mfma_f32_16x16x32_bf16 v[68:71], v[148:151], v[204:207], v[68:71]
	v_mfma_f32_16x16x32_bf16 v[64:67], v[156:159], v[204:207], v[64:67]
	s_barrier
; #define PG8_STAGE(bufoff, gbase, voff) do { _Pragma("unroll") for (int _i = 0; _i < 2; ++_i) \
;         __builtin_amdgcn_global_load_lds((const unsigned*)((const char*)(gbase) + (voff)[_i]), (LAS unsigned*)(lds + (bufoff) + ldsw + _i * 8192), 16, 0, 0); } while (0)
; #define PG8_LDA(dst, b, h) do { _Pragma("unroll") for (int m = 0; m < 4; ++m) _Pragma("unroll") for (int k = 0; k < 2; ++k) dst[m][k] = *(const LAS bf16x8*)(lds + PG8_SA(b, h) + aoff + m * 2048 + k * 1024); } while (0)
; #define PG8_LDB(dst, b, h) do { _Pragma("unroll") for (int n = 0; n < 2; ++n) _Pragma("unroll") for (int k = 0; k < 2; ++k) dst[n][k] = *(const LAS bf16x8*)(lds + PG8_SB(b, h) + boff + n * 2048 + k * 1024); } while (0)
; #define PG8_MMA(ai, bj, At, Bt) do { __builtin_amdgcn_s_setprio(1); _Pragma("unroll") for (int m = 0; m < 4; ++m) _Pragma("unroll") for (int n = 0; n < 2; ++n) _Pragma("unroll") for (int k = 0; k < 2; ++k) \
;         acc[ai][bj][m][n] = __builtin_amdgcn_mfma_f32_16x16x32_bf16(Bt[n][k], At[m][k], acc[ai][bj][m][n], 0, 0, 0); __builtin_amdgcn_s_setprio(0); } while (0)
; #define PG8_WAIT_V(n) asm volatile("s_waitcnt vmcnt(" #n ")" ::: "memory")
; #define PG8_WAIT_L(n) asm volatile("s_waitcnt lgkmcnt(" #n ")" ::: "memory")
; #define PG8_BAR __builtin_amdgcn_s_barrier()
; #define PG8_SCHED __builtin_amdgcn_sched_barrier(0)
; template <class Epi>
; DI void gemm_phase(LAS unsigned char* lds, const int wid, const Gemm g, const Order& S, const Epi& E) {
;     ...
;         for (int t = 0; t < nt; t += 2) {
;             const bool last = (t == nt - 2);
;             const char* a1 = cA + (size_t)(t + 1) * kstep;
;             const char* a2 = last ? nA : cA + (size_t)(t + 2) * kstep; const char* b2 = last ? nB : cB + (size_t)(t + 2) * kstep;
;             const char* a3 = a2 + kstep; const char* b3 = b2 + kstep;
;             PG8_LDB(B0, 0, 0); PG8_LDB(B1, 0, 1); PG8_SCHED; PG8_LDA(At, 0, 0); PG8_STAGE(PG8_SA(1, 1), a1 + hstepA, voffA);
;     ...
;             PG8_LDA(At, 1, 1); PG8_STAGE(PG8_SB(1, 0), b3, voffB); PG8_STAGE(PG8_SB(1, 1), b3 + hstepB, voffB); PG8_STAGE(PG8_SA(1, 0), a3, voffA);
;             PG8_WAIT_V(8); PG8_WAIT_L(0); PG8_BAR; PG8_MMA(1, 0, At, B0); PG8_MMA(1, 1, At, B1); PG8_BAR; PG8_SCHED;
	s_add_i32 s42, s64, s94
	v_lshl_add_u64 v[214:215], v[214:215], 0, s[34:35]
	s_mov_b32 m0, s42
	ds_read_b128 v[160:163], v211 offset:49152
	ds_read_b128 v[164:167], v211 offset:50176
	ds_read_b128 v[168:171], v211 offset:51200
	ds_read_b128 v[172:175], v211 offset:52224
	ds_read_b128 v[192:195], v211 offset:53248
	ds_read_b128 v[196:199], v211 offset:54272
	ds_read_b128 v[200:203], v211 offset:55296
	ds_read_b128 v[204:207], v211 offset:56320
	global_load_lds_dwordx4 v[214:215], off
	s_add_i32 m0, s42, 0x2000
	s_add_u32 s42, s44, 0xb0080
	v_lshl_add_u64 v[214:215], v[216:217], 0, s[34:35]
	s_addc_u32 s43, s45, 0
	s_add_i32 s44, s65, s94
	global_load_lds_dwordx4 v[214:215], off
	v_lshl_add_u64 v[214:215], s[42:43], 0, v[178:179]
	s_mov_b32 m0, s44
	s_nop 0
	global_load_lds_dwordx4 v[214:215], off
	v_lshl_add_u64 v[214:215], s[42:43], 0, v[182:183]
	s_add_i32 m0, s44, 0x2000
	s_nop 0
	global_load_lds_dwordx4 v[214:215], off
	v_lshl_add_u64 v[214:215], v[218:219], 0, s[34:35]
	s_mov_b32 m0, s51
	s_nop 0
	global_load_lds_dwordx4 v[214:215], off
	v_lshl_add_u64 v[214:215], v[220:221], 0, s[34:35]
	s_mov_b32 m0, s52
	s_nop 0
	global_load_lds_dwordx4 v[214:215], off
	s_waitcnt vmcnt(8)
	s_waitcnt lgkmcnt(0)
	s_barrier
	v_mfma_f32_16x16x32_bf16 v[60:63], v[128:131], v[160:163], v[60:63]
	v_mfma_f32_16x16x32_bf16 v[56:59], v[136:139], v[160:163], v[56:59]
	v_mfma_f32_16x16x32_bf16 v[44:47], v[128:131], v[168:171], v[44:47]
	v_mfma_f32_16x16x32_bf16 v[40:43], v[136:139], v[168:171], v[40:43]
	v_mfma_f32_16x16x32_bf16 v[28:31], v[128:131], v[192:195], v[28:31]
	v_mfma_f32_16x16x32_bf16 v[24:27], v[136:139], v[192:195], v[24:27]
	v_mfma_f32_16x16x32_bf16 v[12:15], v[128:131], v[200:203], v[12:15]
	v_mfma_f32_16x16x32_bf16 v[8:11], v[136:139], v[200:203], v[8:11]
	v_mfma_f32_16x16x32_bf16 v[60:63], v[132:135], v[164:167], v[60:63]
	v_mfma_f32_16x16x32_bf16 v[56:59], v[140:143], v[164:167], v[56:59]
	v_mfma_f32_16x16x32_bf16 v[44:47], v[132:135], v[172:175], v[44:47]
	v_mfma_f32_16x16x32_bf16 v[40:43], v[140:143], v[172:175], v[40:43]
	v_mfma_f32_16x16x32_bf16 v[28:31], v[132:135], v[196:199], v[28:31]
	v_mfma_f32_16x16x32_bf16 v[24:27], v[140:143], v[196:199], v[24:27]
	v_mfma_f32_16x16x32_bf16 v[12:15], v[132:135], v[204:207], v[12:15]
	v_mfma_f32_16x16x32_bf16 v[8:11], v[140:143], v[204:207], v[8:11]
	v_mfma_f32_16x16x32_bf16 v[52:55], v[144:147], v[160:163], v[52:55]
	v_mfma_f32_16x16x32_bf16 v[48:51], v[152:155], v[160:163], v[48:51]
	v_mfma_f32_16x16x32_bf16 v[36:39], v[144:147], v[168:171], v[36:39]
	v_mfma_f32_16x16x32_bf16 v[32:35], v[152:155], v[168:171], v[32:35]
	v_mfma_f32_16x16x32_bf16 v[20:23], v[144:147], v[192:195], v[20:23]
	v_mfma_f32_16x16x32_bf16 v[16:19], v[152:155], v[192:195], v[16:19]
	v_mfma_f32_16x16x32_bf16 v[4:7], v[144:147], v[200:203], v[4:7]
	v_mfma_f32_16x16x32_bf16 v[0:3], v[152:155], v[200:203], v[0:3]
	v_mfma_f32_16x16x32_bf16 v[52:55], v[148:151], v[164:167], v[52:55]
	v_mfma_f32_16x16x32_bf16 v[48:51], v[156:159], v[164:167], v[48:51]
	v_mfma_f32_16x16x32_bf16 v[36:39], v[148:151], v[172:175], v[36:39]
	v_mfma_f32_16x16x32_bf16 v[32:35], v[156:159], v[172:175], v[32:35]
	v_mfma_f32_16x16x32_bf16 v[20:23], v[148:151], v[196:199], v[20:23]
	v_mfma_f32_16x16x32_bf16 v[16:19], v[156:159], v[196:199], v[16:19]
	v_mfma_f32_16x16x32_bf16 v[4:7], v[148:151], v[204:207], v[4:7]
	v_mfma_f32_16x16x32_bf16 v[0:3], v[156:159], v[204:207], v[0:3]
	s_barrier
	s_add_i32 s63, s63, 2
	s_add_u32 s61, s61, 0x100
	s_addc_u32 s62, s62, 0
	s_cmp_gt_u32 s63, 41
	s_mov_b64 s[42:43], s[10:11]
	s_cbranch_scc0 .LBB0_312
	s_branch .Lpeel_exit_1
.LBB0_312:
	ds_read_b128 v[128:131], v209
	ds_read_b128 v[132:135], v209 offset:1024
	ds_read_b128 v[136:139], v209 offset:2048
	ds_read_b128 v[140:143], v209 offset:3072
	ds_read_b128 v[144:147], v210
	ds_read_b128 v[148:151], v210 offset:1024
	ds_read_b128 v[152:155], v210 offset:2048
	ds_read_b128 v[156:159], v210 offset:3072
	s_add_u32 s10, s42, 0x100
	s_addc_u32 s11, s43, 0
	s_cmp_eq_u32 s63, 40
	s_cselect_b32 s47, s39, s11
	s_cselect_b32 s46, s38, s10
	s_cselect_b32 s45, s41, s62
	s_cselect_b32 s44, s40, s61
	v_lshl_add_u64 v[214:215], s[42:43], 0, v[184:185]
	s_add_i32 m0, s26, 0xc000
	ds_read_b128 v[160:163], v211
	ds_read_b128 v[164:167], v211 offset:1024
	ds_read_b128 v[168:171], v211 offset:2048
	ds_read_b128 v[172:175], v211 offset:3072
	ds_read_b128 v[192:195], v211 offset:4096
	ds_read_b128 v[196:199], v211 offset:5120
	ds_read_b128 v[200:203], v211 offset:6144
	ds_read_b128 v[204:207], v211 offset:7168
	global_load_lds_dwordx4 v[214:215], off
	v_lshl_add_u64 v[214:215], s[42:43], 0, v[186:187]
	s_add_i32 m0, s26, 0xe000
	s_nop 0
	global_load_lds_dwordx4 v[214:215], off
	s_waitcnt vmcnt(8)
	s_waitcnt lgkmcnt(0)
	s_barrier
; #define PG8_STAGE(bufoff, gbase, voff) do { _Pragma("unroll") for (int _i = 0; _i < 2; ++_i) \
;         __builtin_amdgcn_global_load_lds((const unsigned*)((const char*)(gbase) + (voff)[_i]), (LAS unsigned*)(lds + (bufoff) + ldsw + _i * 8192), 16, 0, 0); } while (0)
; #define PG8_LDA(dst, b, h) do { _Pragma("unroll") for (int m = 0; m < 4; ++m) _Pragma("unroll") for (int k = 0; k < 2; ++k) dst[m][k] = *(const LAS bf16x8*)(lds + PG8_SA(b, h) + aoff + m * 2048 + k * 1024); } while (0)
; #define PG8_MMA(ai, bj, At, Bt) do { __builtin_amdgcn_s_setprio(1); _Pragma("unroll") for (int m = 0; m < 4; ++m) _Pragma("unroll") for (int n = 0; n < 2; ++n) _Pragma("unroll") for (int k = 0; k < 2; ++k) \
;         acc[ai][bj][m][n] = __builtin_amdgcn_mfma_f32_16x16x32_bf16(Bt[n][k], At[m][k], acc[ai][bj][m][n], 0, 0, 0); __builtin_amdgcn_s_setprio(0); } while (0)
; #define PG8_WAIT_V(n) asm volatile("s_waitcnt vmcnt(" #n ")" ::: "memory")
; #define PG8_WAIT_L(n) asm volatile("s_waitcnt lgkmcnt(" #n ")" ::: "memory")
; #define PG8_BAR __builtin_amdgcn_s_barrier()
; #define PG8_SCHED __builtin_amdgcn_sched_barrier(0)
; template <class Epi>
; DI void gemm_phase(LAS unsigned char* lds, const int wid, const Gemm g, const Order& S, const Epi& E) {
;     ...
;             PG8_WAIT_V(8); PG8_WAIT_L(0); PG8_BAR; PG8_MMA(0, 0, At, B0); PG8_MMA(0, 1, At, B1); PG8_BAR; PG8_SCHED;
;             PG8_LDA(At, 0, 1); PG8_STAGE(PG8_SB(0, 0), b2, voffB); PG8_STAGE(PG8_SB(0, 1), b2 + hstepB, voffB); PG8_STAGE(PG8_SA(0, 0), a2, voffA);
;             PG8_WAIT_V(8); PG8_WAIT_L(0); PG8_BAR; PG8_MMA(1, 0, At, B0); PG8_MMA(1, 1, At, B1); PG8_BAR; PG8_SCHED;
	v_mfma_f32_16x16x32_bf16 v[124:127], v[128:131], v[160:163], v[124:127]
	v_mfma_f32_16x16x32_bf16 v[120:123], v[136:139], v[160:163], v[120:123]
	v_mfma_f32_16x16x32_bf16 v[108:111], v[128:131], v[168:171], v[108:111]
	v_mfma_f32_16x16x32_bf16 v[104:107], v[136:139], v[168:171], v[104:107]
	v_mfma_f32_16x16x32_bf16 v[92:95], v[128:131], v[192:195], v[92:95]
	v_mfma_f32_16x16x32_bf16 v[88:91], v[136:139], v[192:195], v[88:91]
	v_mfma_f32_16x16x32_bf16 v[76:79], v[128:131], v[200:203], v[76:79]
	v_mfma_f32_16x16x32_bf16 v[72:75], v[136:139], v[200:203], v[72:75]
	v_mfma_f32_16x16x32_bf16 v[124:127], v[132:135], v[164:167], v[124:127]
	v_mfma_f32_16x16x32_bf16 v[120:123], v[140:143], v[164:167], v[120:123]
	v_mfma_f32_16x16x32_bf16 v[108:111], v[132:135], v[172:175], v[108:111]
	v_mfma_f32_16x16x32_bf16 v[104:107], v[140:143], v[172:175], v[104:107]
	v_mfma_f32_16x16x32_bf16 v[92:95], v[132:135], v[196:199], v[92:95]
	v_mfma_f32_16x16x32_bf16 v[88:91], v[140:143], v[196:199], v[88:91]
	v_mfma_f32_16x16x32_bf16 v[76:79], v[132:135], v[204:207], v[76:79]
	v_mfma_f32_16x16x32_bf16 v[72:75], v[140:143], v[204:207], v[72:75]
	v_mfma_f32_16x16x32_bf16 v[116:119], v[144:147], v[160:163], v[116:119]
	v_mfma_f32_16x16x32_bf16 v[112:115], v[152:155], v[160:163], v[112:115]
	v_mfma_f32_16x16x32_bf16 v[100:103], v[144:147], v[168:171], v[100:103]
	v_mfma_f32_16x16x32_bf16 v[96:99], v[152:155], v[168:171], v[96:99]
	v_mfma_f32_16x16x32_bf16 v[84:87], v[144:147], v[192:195], v[84:87]
	v_mfma_f32_16x16x32_bf16 v[80:83], v[152:155], v[192:195], v[80:83]
	v_mfma_f32_16x16x32_bf16 v[68:71], v[144:147], v[200:203], v[68:71]
	v_mfma_f32_16x16x32_bf16 v[64:67], v[152:155], v[200:203], v[64:67]
	v_mfma_f32_16x16x32_bf16 v[116:119], v[148:151], v[164:167], v[116:119]
	v_mfma_f32_16x16x32_bf16 v[112:115], v[156:159], v[164:167], v[112:115]
	v_mfma_f32_16x16x32_bf16 v[100:103], v[148:151], v[172:175], v[100:103]
	v_mfma_f32_16x16x32_bf16 v[96:99], v[156:159], v[172:175], v[96:99]
	v_mfma_f32_16x16x32_bf16 v[84:87], v[148:151], v[196:199], v[84:87]
	v_mfma_f32_16x16x32_bf16 v[80:83], v[156:159], v[196:199], v[80:83]
	v_mfma_f32_16x16x32_bf16 v[68:71], v[148:151], v[204:207], v[68:71]
	v_mfma_f32_16x16x32_bf16 v[64:67], v[156:159], v[204:207], v[64:67]
	s_barrier
	s_add_i32 s42, s55, s94
	v_lshl_add_u64 v[214:215], s[44:45], 0, v[178:179]
	s_mov_b32 m0, s42
	ds_read_b128 v[160:163], v211 offset:16384
	ds_read_b128 v[164:167], v211 offset:17408
	ds_read_b128 v[168:171], v211 offset:18432
	ds_read_b128 v[172:175], v211 offset:19456
	ds_read_b128 v[192:195], v211 offset:20480
	ds_read_b128 v[196:199], v211 offset:21504
	ds_read_b128 v[200:203], v211 offset:22528
	ds_read_b128 v[204:207], v211 offset:23552
	global_load_lds_dwordx4 v[214:215], off
	s_add_i32 m0, s42, 0x2000
	s_add_u32 s42, s44, 0xb0000
	v_lshl_add_u64 v[216:217], s[44:45], 0, v[182:183]
	s_addc_u32 s43, s45, 0
	s_add_i32 s64, s56, s94
	global_load_lds_dwordx4 v[216:217], off
	v_lshl_add_u64 v[218:219], s[42:43], 0, v[178:179]
	s_mov_b32 m0, s64
	v_lshl_add_u64 v[220:221], s[46:47], 0, v[180:181]
	global_load_lds_dwordx4 v[218:219], off
	v_lshl_add_u64 v[218:219], s[42:43], 0, v[182:183]
	s_add_i32 m0, s64, 0x2000
	s_nop 0
	global_load_lds_dwordx4 v[218:219], off
	v_lshl_add_u64 v[218:219], s[46:47], 0, v[176:177]
	s_mov_b32 m0, s26
	s_nop 0
	global_load_lds_dwordx4 v[218:219], off
	s_mov_b32 m0, s27
	s_nop 0
	global_load_lds_dwordx4 v[220:221], off
	s_waitcnt vmcnt(8)
	s_waitcnt lgkmcnt(0)
	s_barrier
	v_mfma_f32_16x16x32_bf16 v[60:63], v[128:131], v[160:163], v[60:63]
	v_mfma_f32_16x16x32_bf16 v[56:59], v[136:139], v[160:163], v[56:59]
	v_mfma_f32_16x16x32_bf16 v[44:47], v[128:131], v[168:171], v[44:47]
	v_mfma_f32_16x16x32_bf16 v[40:43], v[136:139], v[168:171], v[40:43]
	v_mfma_f32_16x16x32_bf16 v[28:31], v[128:131], v[192:195], v[28:31]
	v_mfma_f32_16x16x32_bf16 v[24:27], v[136:139], v[192:195], v[24:27]
	v_mfma_f32_16x16x32_bf16 v[12:15], v[128:131], v[200:203], v[12:15]
	v_mfma_f32_16x16x32_bf16 v[8:11], v[136:139], v[200:203], v[8:11]
	v_mfma_f32_16x16x32_bf16 v[60:63], v[132:135], v[164:167], v[60:63]
	v_mfma_f32_16x16x32_bf16 v[56:59], v[140:143], v[164:167], v[56:59]
	v_mfma_f32_16x16x32_bf16 v[44:47], v[132:135], v[172:175], v[44:47]
	v_mfma_f32_16x16x32_bf16 v[40:43], v[140:143], v[172:175], v[40:43]
	v_mfma_f32_16x16x32_bf16 v[28:31], v[132:135], v[196:199], v[28:31]
	v_mfma_f32_16x16x32_bf16 v[24:27], v[140:143], v[196:199], v[24:27]
	v_mfma_f32_16x16x32_bf16 v[12:15], v[132:135], v[204:207], v[12:15]
	v_mfma_f32_16x16x32_bf16 v[8:11], v[140:143], v[204:207], v[8:11]
	v_mfma_f32_16x16x32_bf16 v[52:55], v[144:147], v[160:163], v[52:55]
	v_mfma_f32_16x16x32_bf16 v[48:51], v[152:155], v[160:163], v[48:51]
	v_mfma_f32_16x16x32_bf16 v[36:39], v[144:147], v[168:171], v[36:39]
	v_mfma_f32_16x16x32_bf16 v[32:35], v[152:155], v[168:171], v[32:35]
	v_mfma_f32_16x16x32_bf16 v[20:23], v[144:147], v[192:195], v[20:23]
	v_mfma_f32_16x16x32_bf16 v[16:19], v[152:155], v[192:195], v[16:19]
	v_mfma_f32_16x16x32_bf16 v[4:7], v[144:147], v[200:203], v[4:7]
	v_mfma_f32_16x16x32_bf16 v[0:3], v[152:155], v[200:203], v[0:3]
	v_mfma_f32_16x16x32_bf16 v[52:55], v[148:151], v[164:167], v[52:55]
	v_mfma_f32_16x16x32_bf16 v[48:51], v[156:159], v[164:167], v[48:51]
	v_mfma_f32_16x16x32_bf16 v[36:39], v[148:151], v[172:175], v[36:39]
	v_mfma_f32_16x16x32_bf16 v[32:35], v[156:159], v[172:175], v[32:35]
	v_mfma_f32_16x16x32_bf16 v[20:23], v[148:151], v[196:199], v[20:23]
	v_mfma_f32_16x16x32_bf16 v[16:19], v[156:159], v[196:199], v[16:19]
	v_mfma_f32_16x16x32_bf16 v[4:7], v[148:151], v[204:207], v[4:7]
	v_mfma_f32_16x16x32_bf16 v[0:3], v[156:159], v[204:207], v[0:3]
	s_barrier
; #define PG8_STAGE(bufoff, gbase, voff) do { _Pragma("unroll") for (int _i = 0; _i < 2; ++_i) \
;         __builtin_amdgcn_global_load_lds((const unsigned*)((const char*)(gbase) + (voff)[_i]), (LAS unsigned*)(lds + (bufoff) + ldsw + _i * 8192), 16, 0, 0); } while (0)
; #define PG8_LDA(dst, b, h) do { _Pragma("unroll") for (int m = 0; m < 4; ++m) _Pragma("unroll") for (int k = 0; k < 2; ++k) dst[m][k] = *(const LAS bf16x8*)(lds + PG8_SA(b, h) + aoff + m * 2048 + k * 1024); } while (0)
; #define PG8_LDB(dst, b, h) do { _Pragma("unroll") for (int n = 0; n < 2; ++n) _Pragma("unroll") for (int k = 0; k < 2; ++k) dst[n][k] = *(const LAS bf16x8*)(lds + PG8_SB(b, h) + boff + n * 2048 + k * 1024); } while (0)
; #define PG8_MMA(ai, bj, At, Bt) do { __builtin_amdgcn_s_setprio(1); _Pragma("unroll") for (int m = 0; m < 4; ++m) _Pragma("unroll") for (int n = 0; n < 2; ++n) _Pragma("unroll") for (int k = 0; k < 2; ++k) \
;         acc[ai][bj][m][n] = __builtin_amdgcn_mfma_f32_16x16x32_bf16(Bt[n][k], At[m][k], acc[ai][bj][m][n], 0, 0, 0); __builtin_amdgcn_s_setprio(0); } while (0)
; #define PG8_WAIT_V(n) asm volatile("s_waitcnt vmcnt(" #n ")" ::: "memory")
; #define PG8_WAIT_L(n) asm volatile("s_waitcnt lgkmcnt(" #n ")" ::: "memory")
; #define PG8_BAR __builtin_amdgcn_s_barrier()
; #define PG8_SCHED __builtin_amdgcn_sched_barrier(0)
; template <class Epi>
; DI void gemm_phase(LAS unsigned char* lds, const int wid, const Gemm g, const Order& S, const Epi& E) {
;     ...
;             PG8_LDB(B0, 1, 0); PG8_LDB(B1, 1, 1); PG8_SCHED; PG8_LDA(At, 1, 0); PG8_STAGE(PG8_SA(0, 1), a2 + hstepA, voffA);
;             PG8_WAIT_V(8); PG8_WAIT_L(0); PG8_BAR; PG8_MMA(0, 0, At, B0); PG8_MMA(0, 1, At, B1); PG8_BAR; PG8_SCHED;
;             PG8_LDA(At, 1, 1); PG8_STAGE(PG8_SB(1, 0), b3, voffB); PG8_STAGE(PG8_SB(1, 1), b3 + hstepB, voffB); PG8_STAGE(PG8_SA(1, 0), a3, voffA);
;             PG8_WAIT_V(8); PG8_WAIT_L(0); PG8_BAR; PG8_MMA(1, 0, At, B0); PG8_MMA(1, 1, At, B1); PG8_BAR; PG8_SCHED;
	s_add_i32 s64, 0, 0x18000
	s_add_i32 s65, 0, 0x1c000
	v_add_u32_e32 v140, s64, v208
	v_add_u32_e32 v156, s65, v208
	ds_read_b128 v[128:131], v140
	ds_read_b128 v[132:135], v140 offset:1024
	ds_read_b128 v[136:139], v140 offset:2048
	ds_read_b128 v[140:143], v140 offset:3072
	ds_read_b128 v[144:147], v156
	ds_read_b128 v[148:151], v156 offset:1024
	ds_read_b128 v[152:155], v156 offset:2048
	ds_read_b128 v[156:159], v156 offset:3072
	s_add_u32 s42, s46, 0xb0000
	s_addc_u32 s43, s47, 0
	s_mov_b32 m0, s48
	v_lshl_add_u64 v[222:223], s[42:43], 0, v[176:177]
	ds_read_b128 v[160:163], v211 offset:32768
	ds_read_b128 v[164:167], v211 offset:33792
	ds_read_b128 v[168:171], v211 offset:34816
	ds_read_b128 v[172:175], v211 offset:35840
	ds_read_b128 v[192:195], v211 offset:36864
	ds_read_b128 v[196:199], v211 offset:37888
	ds_read_b128 v[200:203], v211 offset:38912
	ds_read_b128 v[204:207], v211 offset:39936
	global_load_lds_dwordx4 v[222:223], off
	v_lshl_add_u64 v[222:223], s[42:43], 0, v[180:181]
	s_mov_b32 m0, s49
	s_nop 0
	global_load_lds_dwordx4 v[222:223], off
	s_waitcnt vmcnt(8)
	s_waitcnt lgkmcnt(0)
	s_barrier
	v_mfma_f32_16x16x32_bf16 v[124:127], v[128:131], v[160:163], v[124:127]
	v_mfma_f32_16x16x32_bf16 v[120:123], v[136:139], v[160:163], v[120:123]
	v_mfma_f32_16x16x32_bf16 v[108:111], v[128:131], v[168:171], v[108:111]
	v_mfma_f32_16x16x32_bf16 v[104:107], v[136:139], v[168:171], v[104:107]
	v_mfma_f32_16x16x32_bf16 v[92:95], v[128:131], v[192:195], v[92:95]
	v_mfma_f32_16x16x32_bf16 v[88:91], v[136:139], v[192:195], v[88:91]
	v_mfma_f32_16x16x32_bf16 v[76:79], v[128:131], v[200:203], v[76:79]
	v_mfma_f32_16x16x32_bf16 v[72:75], v[136:139], v[200:203], v[72:75]
	v_mfma_f32_16x16x32_bf16 v[124:127], v[132:135], v[164:167], v[124:127]
	v_mfma_f32_16x16x32_bf16 v[120:123], v[140:143], v[164:167], v[120:123]
	v_mfma_f32_16x16x32_bf16 v[108:111], v[132:135], v[172:175], v[108:111]
	v_mfma_f32_16x16x32_bf16 v[104:107], v[140:143], v[172:175], v[104:107]
	v_mfma_f32_16x16x32_bf16 v[92:95], v[132:135], v[196:199], v[92:95]
	v_mfma_f32_16x16x32_bf16 v[88:91], v[140:143], v[196:199], v[88:91]
	v_mfma_f32_16x16x32_bf16 v[76:79], v[132:135], v[204:207], v[76:79]
	v_mfma_f32_16x16x32_bf16 v[72:75], v[140:143], v[204:207], v[72:75]
	v_mfma_f32_16x16x32_bf16 v[116:119], v[144:147], v[160:163], v[116:119]
	v_mfma_f32_16x16x32_bf16 v[112:115], v[152:155], v[160:163], v[112:115]
	v_mfma_f32_16x16x32_bf16 v[100:103], v[144:147], v[168:171], v[100:103]
	v_mfma_f32_16x16x32_bf16 v[96:99], v[152:155], v[168:171], v[96:99]
	v_mfma_f32_16x16x32_bf16 v[84:87], v[144:147], v[192:195], v[84:87]
	v_mfma_f32_16x16x32_bf16 v[80:83], v[152:155], v[192:195], v[80:83]
	v_mfma_f32_16x16x32_bf16 v[68:71], v[144:147], v[200:203], v[68:71]
	v_mfma_f32_16x16x32_bf16 v[64:67], v[152:155], v[200:203], v[64:67]
	v_mfma_f32_16x16x32_bf16 v[116:119], v[148:151], v[164:167], v[116:119]
	v_mfma_f32_16x16x32_bf16 v[112:115], v[156:159], v[164:167], v[112:115]
	v_mfma_f32_16x16x32_bf16 v[100:103], v[148:151], v[172:175], v[100:103]
	v_mfma_f32_16x16x32_bf16 v[96:99], v[156:159], v[172:175], v[96:99]
	v_mfma_f32_16x16x32_bf16 v[84:87], v[148:151], v[196:199], v[84:87]
	v_mfma_f32_16x16x32_bf16 v[80:83], v[156:159], v[196:199], v[80:83]
	v_mfma_f32_16x16x32_bf16 v[68:71], v[148:151], v[204:207], v[68:71]
	v_mfma_f32_16x16x32_bf16 v[64:67], v[156:159], v[204:207], v[64:67]
	s_barrier
	s_add_i32 s42, s64, s94
	v_lshl_add_u64 v[214:215], v[214:215], 0, s[34:35]
	s_mov_b32 m0, s42
	ds_read_b128 v[160:163], v211 offset:49152
	ds_read_b128 v[164:167], v211 offset:50176
	ds_read_b128 v[168:171], v211 offset:51200
	ds_read_b128 v[172:175], v211 offset:52224
	ds_read_b128 v[192:195], v211 offset:53248
	ds_read_b128 v[196:199], v211 offset:54272
	ds_read_b128 v[200:203], v211 offset:55296
	ds_read_b128 v[204:207], v211 offset:56320
	global_load_lds_dwordx4 v[214:215], off
	s_add_i32 m0, s42, 0x2000
	s_add_u32 s42, s44, 0xb0080
	v_lshl_add_u64 v[214:215], v[216:217], 0, s[34:35]
	s_addc_u32 s43, s45, 0
	s_add_i32 s44, s65, s94
	global_load_lds_dwordx4 v[214:215], off
	v_lshl_add_u64 v[214:215], s[42:43], 0, v[178:179]
	s_mov_b32 m0, s44
	s_nop 0
	global_load_lds_dwordx4 v[214:215], off
	v_lshl_add_u64 v[214:215], s[42:43], 0, v[182:183]
	s_add_i32 m0, s44, 0x2000
	s_nop 0
	global_load_lds_dwordx4 v[214:215], off
	v_lshl_add_u64 v[214:215], v[218:219], 0, s[34:35]
	s_mov_b32 m0, s51
	s_nop 0
	global_load_lds_dwordx4 v[214:215], off
	v_lshl_add_u64 v[214:215], v[220:221], 0, s[34:35]
	s_mov_b32 m0, s52
	s_nop 0
	global_load_lds_dwordx4 v[214:215], off
	s_waitcnt vmcnt(8)
	s_waitcnt lgkmcnt(0)
	s_barrier
	v_mfma_f32_16x16x32_bf16 v[60:63], v[128:131], v[160:163], v[60:63]
	v_mfma_f32_16x16x32_bf16 v[56:59], v[136:139], v[160:163], v[56:59]
	v_mfma_f32_16x16x32_bf16 v[44:47], v[128:131], v[168:171], v[44:47]
	v_mfma_f32_16x16x32_bf16 v[40:43], v[136:139], v[168:171], v[40:43]
	v_mfma_f32_16x16x32_bf16 v[28:31], v[128:131], v[192:195], v[28:31]
	v_mfma_f32_16x16x32_bf16 v[24:27], v[136:139], v[192:195], v[24:27]
	v_mfma_f32_16x16x32_bf16 v[12:15], v[128:131], v[200:203], v[12:15]
	v_mfma_f32_16x16x32_bf16 v[8:11], v[136:139], v[200:203], v[8:11]
	v_mfma_f32_16x16x32_bf16 v[60:63], v[132:135], v[164:167], v[60:63]
	v_mfma_f32_16x16x32_bf16 v[56:59], v[140:143], v[164:167], v[56:59]
	v_mfma_f32_16x16x32_bf16 v[44:47], v[132:135], v[172:175], v[44:47]
	v_mfma_f32_16x16x32_bf16 v[40:43], v[140:143], v[172:175], v[40:43]
	v_mfma_f32_16x16x32_bf16 v[28:31], v[132:135], v[196:199], v[28:31]
	v_mfma_f32_16x16x32_bf16 v[24:27], v[140:143], v[196:199], v[24:27]
	v_mfma_f32_16x16x32_bf16 v[12:15], v[132:135], v[204:207], v[12:15]
	v_mfma_f32_16x16x32_bf16 v[8:11], v[140:143], v[204:207], v[8:11]
	v_mfma_f32_16x16x32_bf16 v[52:55], v[144:147], v[160:163], v[52:55]
	v_mfma_f32_16x16x32_bf16 v[48:51], v[152:155], v[160:163], v[48:51]
	v_mfma_f32_16x16x32_bf16 v[36:39], v[144:147], v[168:171], v[36:39]
	v_mfma_f32_16x16x32_bf16 v[32:35], v[152:155], v[168:171], v[32:35]
	v_mfma_f32_16x16x32_bf16 v[20:23], v[144:147], v[192:195], v[20:23]
	v_mfma_f32_16x16x32_bf16 v[16:19], v[152:155], v[192:195], v[16:19]
	v_mfma_f32_16x16x32_bf16 v[4:7], v[144:147], v[200:203], v[4:7]
	v_mfma_f32_16x16x32_bf16 v[0:3], v[152:155], v[200:203], v[0:3]
	v_mfma_f32_16x16x32_bf16 v[52:55], v[148:151], v[164:167], v[52:55]
	v_mfma_f32_16x16x32_bf16 v[48:51], v[156:159], v[164:167], v[48:51]
	v_mfma_f32_16x16x32_bf16 v[36:39], v[148:151], v[172:175], v[36:39]
	v_mfma_f32_16x16x32_bf16 v[32:35], v[156:159], v[172:175], v[32:35]
	v_mfma_f32_16x16x32_bf16 v[20:23], v[148:151], v[196:199], v[20:23]
	v_mfma_f32_16x16x32_bf16 v[16:19], v[156:159], v[196:199], v[16:19]
	v_mfma_f32_16x16x32_bf16 v[4:7], v[148:151], v[204:207], v[4:7]
	v_mfma_f32_16x16x32_bf16 v[0:3], v[156:159], v[204:207], v[0:3]
	s_barrier
	s_add_i32 s63, s63, 2
	s_add_u32 s61, s61, 0x100
	s_addc_u32 s62, s62, 0
	s_cmp_gt_u32 s63, 41
	s_mov_b64 s[42:43], s[10:11]
	s_cbranch_scc0 .LBB0_312

; #define PG8_STAGE(bufoff, gbase, voff) do { _Pragma("unroll") for (int _i = 0; _i < 2; ++_i) \
;         __builtin_amdgcn_global_load_lds((const unsigned*)((const char*)(gbase) + (voff)[_i]), (LAS unsigned*)(lds + (bufoff) + ldsw + _i * 8192), 16, 0, 0); } while (0)
; #define PG8_LDA(dst, b, h) do { _Pragma("unroll") for (int m = 0; m < 4; ++m) _Pragma("unroll") for (int k = 0; k < 2; ++k) dst[m][k] = *(const LAS bf16x8*)(lds + PG8_SA(b, h) + aoff + m * 2048 + k * 1024); } while (0)
; #define PG8_LDB(dst, b, h) do { _Pragma("unroll") for (int n = 0; n < 2; ++n) _Pragma("unroll") for (int k = 0; k < 2; ++k) dst[n][k] = *(const LAS bf16x8*)(lds + PG8_SB(b, h) + boff + n * 2048 + k * 1024); } while (0)
; #define PG8_MMA(ai, bj, At, Bt) do { __builtin_amdgcn_s_setprio(1); _Pragma("unroll") for (int m = 0; m < 4; ++m) _Pragma("unroll") for (int n = 0; n < 2; ++n) _Pragma("unroll") for (int k = 0; k < 2; ++k) \
;         acc[ai][bj][m][n] = __builtin_amdgcn_mfma_f32_16x16x32_bf16(Bt[n][k], At[m][k], acc[ai][bj][m][n], 0, 0, 0); __builtin_amdgcn_s_setprio(0); } while (0)
; #define PG8_WAIT_V(n) asm volatile("s_waitcnt vmcnt(" #n ")" ::: "memory")
; #define PG8_WAIT_L(n) asm volatile("s_waitcnt lgkmcnt(" #n ")" ::: "memory")
; template <class Epi>
; DI void gemm_phase(LAS unsigned char* lds, const int wid, const Gemm g, const Order& S, const Epi& E) {
;     ...
;         const char* nA = has_next ? (const char*)(g.A + (size_t)nxt.g * g.gsA + (size_t)nxt.pm * BM * g.lda) : cA;
;         const char* nB = has_next ? (const char*)(g.Bt + (size_t)nxt.g * g.gsB + (size_t)nxt.pn * BM * g.ldb) : cB;
;         for (int t = 0; t < nt; t += 2) {
;             const bool last = (t == nt - 2);
;             const char* a1 = cA + (size_t)(t + 1) * kstep;
;             const char* a2 = last ? nA : cA + (size_t)(t + 2) * kstep; const char* b2 = last ? nB : cB + (size_t)(t + 2) * kstep;
;             const char* a3 = a2 + kstep; const char* b3 = b2 + kstep;
;             PG8_LDB(B0, 0, 0); PG8_LDB(B1, 0, 1); PG8_SCHED; PG8_LDA(At, 0, 0); PG8_STAGE(PG8_SA(1, 1), a1 + hstepA, voffA);
;             PG8_WAIT_V(8); PG8_WAIT_L(0); PG8_BAR; PG8_MMA(0, 0, At, B0); PG8_MMA(0, 1, At, B1); PG8_BAR; PG8_SCHED;
;             PG8_LDA(At, 0, 1); PG8_STAGE(PG8_SB(0, 0), b2, voffB); PG8_STAGE(PG8_SB(0, 1), b2 + hstepB, voffB); PG8_STAGE(PG8_SA(0, 0), a2, voffA);
.LBB0_399:
	s_ashr_i32 s57, s56, 31
	s_lshl_b64 s[60:61], s[56:57], 19
	s_add_u32 s60, s73, s60
	s_addc_u32 s61, s74, s61
	s_and_b64 s[62:63], s[8:9], exec
	s_cselect_b32 s11, s61, s13
	s_cselect_b32 s16, s60, s12
	s_ashr_i32 s59, s58, 31
	s_lshl_b64 s[62:63], s[58:59], 19
	s_add_u32 s62, s75, s62
	s_addc_u32 s63, s76, s63
	s_and_b64 s[66:67], s[8:9], exec
	s_cselect_b32 s57, s63, s65
	s_cselect_b32 s59, s62, s64
	s_add_u32 s12, s12, 0x40080
	s_addc_u32 s13, s13, 0
	s_add_u32 s68, s64, 0x100
	v_mov_b32_e32 v0, 0
	s_addc_u32 s69, s65, 0
	s_mov_b32 s70, -2
	s_waitcnt lgkmcnt(0)
	ds_read_b128 v[146:149], v163
	ds_read_b128 v[150:153], v163 offset:1024
	ds_read_b128 v[154:157], v163 offset:2048
	ds_read_b128 v[158:161], v163 offset:3072
	ds_read_b128 v[168:171], v164
	ds_read_b128 v[172:175], v164 offset:1024
	ds_read_b128 v[176:179], v164 offset:2048
	ds_read_b128 v[180:183], v164 offset:3072
	s_add_u32 s64, s12, 0xfffc0080
	s_addc_u32 s65, s13, -1
	s_cmp_eq_u32 s70, 12
	s_cselect_b32 s67, s11, s65
	s_cselect_b32 s66, s16, s64
	s_cselect_b32 s65, s57, s69
	s_cselect_b32 s64, s59, s68
	v_lshl_add_u64 v[212:213], s[12:13], 0, v[138:139]
	s_add_i32 m0, s6, 0xc000
	ds_read_b128 v[184:187], v165
	ds_read_b128 v[188:191], v165 offset:1024
	ds_read_b128 v[192:195], v165 offset:2048
	ds_read_b128 v[196:199], v165 offset:3072
	ds_read_b128 v[200:203], v165 offset:4096
	ds_read_b128 v[204:207], v165 offset:5120
	ds_read_b128 v[208:211], v165 offset:6144
	ds_read_b128 v[216:219], v165 offset:7168
	global_load_lds_dwordx4 v[212:213], off
	v_lshl_add_u64 v[212:213], s[12:13], 0, v[140:141]
	s_add_i32 m0, s6, 0xe000
	s_nop 0
	global_load_lds_dwordx4 v[212:213], off
	s_waitcnt vmcnt(8)
	s_waitcnt lgkmcnt(0)
	s_barrier
	v_mfma_f32_16x16x32_bf16 v[124:127], v[146:149], v[184:187], 0
	v_mfma_f32_16x16x32_bf16 v[120:123], v[154:157], v[184:187], 0
	v_mfma_f32_16x16x32_bf16 v[108:111], v[146:149], v[192:195], 0
	v_mfma_f32_16x16x32_bf16 v[104:107], v[154:157], v[192:195], 0
	v_mfma_f32_16x16x32_bf16 v[92:95], v[146:149], v[200:203], 0
	v_mfma_f32_16x16x32_bf16 v[88:91], v[154:157], v[200:203], 0
	v_mfma_f32_16x16x32_bf16 v[76:79], v[146:149], v[208:211], 0
	v_mfma_f32_16x16x32_bf16 v[72:75], v[154:157], v[208:211], 0
	v_mfma_f32_16x16x32_bf16 v[124:127], v[150:153], v[188:191], v[124:127]
	v_mfma_f32_16x16x32_bf16 v[120:123], v[158:161], v[188:191], v[120:123]
	v_mfma_f32_16x16x32_bf16 v[108:111], v[150:153], v[196:199], v[108:111]
	v_mfma_f32_16x16x32_bf16 v[104:107], v[158:161], v[196:199], v[104:107]
	v_mfma_f32_16x16x32_bf16 v[92:95], v[150:153], v[204:207], v[92:95]
	v_mfma_f32_16x16x32_bf16 v[88:91], v[158:161], v[204:207], v[88:91]
	v_mfma_f32_16x16x32_bf16 v[76:79], v[150:153], v[216:219], v[76:79]
	v_mfma_f32_16x16x32_bf16 v[72:75], v[158:161], v[216:219], v[72:75]
	v_mfma_f32_16x16x32_bf16 v[116:119], v[168:171], v[184:187], 0
	v_mfma_f32_16x16x32_bf16 v[112:115], v[176:179], v[184:187], 0
	v_mfma_f32_16x16x32_bf16 v[100:103], v[168:171], v[192:195], 0
	v_mfma_f32_16x16x32_bf16 v[96:99], v[176:179], v[192:195], 0
	v_mfma_f32_16x16x32_bf16 v[84:87], v[168:171], v[200:203], 0
	v_mfma_f32_16x16x32_bf16 v[80:83], v[176:179], v[200:203], 0
	v_mfma_f32_16x16x32_bf16 v[68:71], v[168:171], v[208:211], 0
	v_mfma_f32_16x16x32_bf16 v[64:67], v[176:179], v[208:211], 0
	v_mfma_f32_16x16x32_bf16 v[116:119], v[172:175], v[188:191], v[116:119]
	v_mfma_f32_16x16x32_bf16 v[112:115], v[180:183], v[188:191], v[112:115]
	v_mfma_f32_16x16x32_bf16 v[100:103], v[172:175], v[196:199], v[100:103]
	v_mfma_f32_16x16x32_bf16 v[96:99], v[180:183], v[196:199], v[96:99]
	v_mfma_f32_16x16x32_bf16 v[84:87], v[172:175], v[204:207], v[84:87]
	v_mfma_f32_16x16x32_bf16 v[80:83], v[180:183], v[204:207], v[80:83]
	v_mfma_f32_16x16x32_bf16 v[68:71], v[172:175], v[216:219], v[68:71]
	v_mfma_f32_16x16x32_bf16 v[64:67], v[180:183], v[216:219], v[64:67]
	s_barrier
	s_add_i32 s71, s82, s94
	v_lshl_add_u64 v[212:213], s[64:65], 0, v[130:131]
	s_mov_b32 m0, s71
	ds_read_b128 v[184:187], v165 offset:16384
	ds_read_b128 v[188:191], v165 offset:17408
	ds_read_b128 v[192:195], v165 offset:18432
	ds_read_b128 v[196:199], v165 offset:19456
	ds_read_b128 v[200:203], v165 offset:20480
	ds_read_b128 v[204:207], v165 offset:21504
	ds_read_b128 v[208:211], v165 offset:22528
	ds_read_b128 v[216:219], v165 offset:23552
	global_load_lds_dwordx4 v[212:213], off
	s_add_i32 m0, s71, 0x2000
	s_add_u32 s86, s64, 0x40000
	v_lshl_add_u64 v[214:215], s[64:65], 0, v[134:135]
	s_addc_u32 s87, s65, 0
	s_add_i32 s71, s83, s94
	global_load_lds_dwordx4 v[214:215], off
	v_lshl_add_u64 v[220:221], s[86:87], 0, v[130:131]
	s_mov_b32 m0, s71
	v_lshl_add_u64 v[222:223], s[66:67], 0, v[132:133]
	global_load_lds_dwordx4 v[220:221], off
	v_lshl_add_u64 v[220:221], s[86:87], 0, v[134:135]
	s_add_i32 m0, s71, 0x2000
	s_nop 0
	global_load_lds_dwordx4 v[220:221], off
	v_lshl_add_u64 v[220:221], s[66:67], 0, v[128:129]
	s_mov_b32 m0, s6
	s_nop 0
	global_load_lds_dwordx4 v[220:221], off
	s_mov_b32 m0, s7
	s_nop 0
	global_load_lds_dwordx4 v[222:223], off
	s_waitcnt vmcnt(8)
	s_waitcnt lgkmcnt(0)
	s_barrier
; #define PG8_STAGE(bufoff, gbase, voff) do { _Pragma("unroll") for (int _i = 0; _i < 2; ++_i) \
;         __builtin_amdgcn_global_load_lds((const unsigned*)((const char*)(gbase) + (voff)[_i]), (LAS unsigned*)(lds + (bufoff) + ldsw + _i * 8192), 16, 0, 0); } while (0)
; #define PG8_LDA(dst, b, h) do { _Pragma("unroll") for (int m = 0; m < 4; ++m) _Pragma("unroll") for (int k = 0; k < 2; ++k) dst[m][k] = *(const LAS bf16x8*)(lds + PG8_SA(b, h) + aoff + m * 2048 + k * 1024); } while (0)
; #define PG8_LDB(dst, b, h) do { _Pragma("unroll") for (int n = 0; n < 2; ++n) _Pragma("unroll") for (int k = 0; k < 2; ++k) dst[n][k] = *(const LAS bf16x8*)(lds + PG8_SB(b, h) + boff + n * 2048 + k * 1024); } while (0)
; #define PG8_MMA(ai, bj, At, Bt) do { __builtin_amdgcn_s_setprio(1); _Pragma("unroll") for (int m = 0; m < 4; ++m) _Pragma("unroll") for (int n = 0; n < 2; ++n) _Pragma("unroll") for (int k = 0; k < 2; ++k) \
;         acc[ai][bj][m][n] = __builtin_amdgcn_mfma_f32_16x16x32_bf16(Bt[n][k], At[m][k], acc[ai][bj][m][n], 0, 0, 0); __builtin_amdgcn_s_setprio(0); } while (0)
; #define PG8_WAIT_V(n) asm volatile("s_waitcnt vmcnt(" #n ")" ::: "memory")
; #define PG8_WAIT_L(n) asm volatile("s_waitcnt lgkmcnt(" #n ")" ::: "memory")
; #define PG8_BAR __builtin_amdgcn_s_barrier()
; #define PG8_SCHED __builtin_amdgcn_sched_barrier(0)
; template <class Epi>
; DI void gemm_phase(LAS unsigned char* lds, const int wid, const Gemm g, const Order& S, const Epi& E) {
;     ...
;             PG8_WAIT_V(8); PG8_WAIT_L(0); PG8_BAR; PG8_MMA(1, 0, At, B0); PG8_MMA(1, 1, At, B1); PG8_BAR; PG8_SCHED;
;             PG8_LDB(B0, 1, 0); PG8_LDB(B1, 1, 1); PG8_SCHED; PG8_LDA(At, 1, 0); PG8_STAGE(PG8_SA(0, 1), a2 + hstepA, voffA);
;             PG8_WAIT_V(8); PG8_WAIT_L(0); PG8_BAR; PG8_MMA(0, 0, At, B0); PG8_MMA(0, 1, At, B1); PG8_BAR; PG8_SCHED;
	v_mfma_f32_16x16x32_bf16 v[60:63], v[146:149], v[184:187], 0
	v_mfma_f32_16x16x32_bf16 v[56:59], v[154:157], v[184:187], 0
	v_mfma_f32_16x16x32_bf16 v[44:47], v[146:149], v[192:195], 0
	v_mfma_f32_16x16x32_bf16 v[40:43], v[154:157], v[192:195], 0
	v_mfma_f32_16x16x32_bf16 v[28:31], v[146:149], v[200:203], 0
	v_mfma_f32_16x16x32_bf16 v[24:27], v[154:157], v[200:203], 0
	v_mfma_f32_16x16x32_bf16 v[12:15], v[146:149], v[208:211], 0
	v_mfma_f32_16x16x32_bf16 v[8:11], v[154:157], v[208:211], 0
	v_mfma_f32_16x16x32_bf16 v[60:63], v[150:153], v[188:191], v[60:63]
	v_mfma_f32_16x16x32_bf16 v[56:59], v[158:161], v[188:191], v[56:59]
	v_mfma_f32_16x16x32_bf16 v[44:47], v[150:153], v[196:199], v[44:47]
	v_mfma_f32_16x16x32_bf16 v[40:43], v[158:161], v[196:199], v[40:43]
	v_mfma_f32_16x16x32_bf16 v[28:31], v[150:153], v[204:207], v[28:31]
	v_mfma_f32_16x16x32_bf16 v[24:27], v[158:161], v[204:207], v[24:27]
	v_mfma_f32_16x16x32_bf16 v[12:15], v[150:153], v[216:219], v[12:15]
	v_mfma_f32_16x16x32_bf16 v[8:11], v[158:161], v[216:219], v[8:11]
	v_mfma_f32_16x16x32_bf16 v[52:55], v[168:171], v[184:187], 0
	v_mfma_f32_16x16x32_bf16 v[48:51], v[176:179], v[184:187], 0
	v_mfma_f32_16x16x32_bf16 v[36:39], v[168:171], v[192:195], 0
	v_mfma_f32_16x16x32_bf16 v[32:35], v[176:179], v[192:195], 0
	v_mfma_f32_16x16x32_bf16 v[20:23], v[168:171], v[200:203], 0
	v_mfma_f32_16x16x32_bf16 v[16:19], v[176:179], v[200:203], 0
	v_mfma_f32_16x16x32_bf16 v[4:7], v[168:171], v[208:211], 0
	v_mfma_f32_16x16x32_bf16 v[0:3], v[176:179], v[208:211], 0
	v_mfma_f32_16x16x32_bf16 v[52:55], v[172:175], v[188:191], v[52:55]
	v_mfma_f32_16x16x32_bf16 v[48:51], v[180:183], v[188:191], v[48:51]
	v_mfma_f32_16x16x32_bf16 v[36:39], v[172:175], v[196:199], v[36:39]
	v_mfma_f32_16x16x32_bf16 v[32:35], v[180:183], v[196:199], v[32:35]
	v_mfma_f32_16x16x32_bf16 v[20:23], v[172:175], v[204:207], v[20:23]
	v_mfma_f32_16x16x32_bf16 v[16:19], v[180:183], v[204:207], v[16:19]
	v_mfma_f32_16x16x32_bf16 v[4:7], v[172:175], v[216:219], v[4:7]
	v_mfma_f32_16x16x32_bf16 v[0:3], v[180:183], v[216:219], v[0:3]
	s_barrier
	s_add_i32 s71, 0, 0x18000
	v_add_u32_e32 v136, s71, v162
	s_add_i32 s86, 0, 0x1c000
	ds_read_b128 v[146:149], v136
	ds_read_b128 v[150:153], v136 offset:1024
	ds_read_b128 v[154:157], v136 offset:2048
	ds_read_b128 v[158:161], v136 offset:3072
	v_add_u32_e32 v136, s86, v162
	ds_read_b128 v[168:171], v136
	ds_read_b128 v[172:175], v136 offset:1024
	ds_read_b128 v[176:179], v136 offset:2048
	ds_read_b128 v[180:183], v136 offset:3072
	s_add_u32 s66, s66, 0x40000
	s_addc_u32 s67, s67, 0
	s_mov_b32 m0, s21
	v_lshl_add_u64 v[224:225], s[66:67], 0, v[128:129]
	ds_read_b128 v[184:187], v165 offset:32768
	ds_read_b128 v[188:191], v165 offset:33792
	ds_read_b128 v[192:195], v165 offset:34816
	ds_read_b128 v[196:199], v165 offset:35840
	ds_read_b128 v[200:203], v165 offset:36864
	ds_read_b128 v[204:207], v165 offset:37888
	ds_read_b128 v[208:211], v165 offset:38912
	ds_read_b128 v[216:219], v165 offset:39936
	global_load_lds_dwordx4 v[224:225], off
	v_lshl_add_u64 v[224:225], s[66:67], 0, v[132:133]
	s_mov_b32 m0, s26
	s_nop 0
	global_load_lds_dwordx4 v[224:225], off
	s_waitcnt vmcnt(8)
	s_waitcnt lgkmcnt(0)
	s_barrier
	v_mfma_f32_16x16x32_bf16 v[124:127], v[146:149], v[184:187], v[124:127]
	v_mfma_f32_16x16x32_bf16 v[120:123], v[154:157], v[184:187], v[120:123]
	v_mfma_f32_16x16x32_bf16 v[108:111], v[146:149], v[192:195], v[108:111]
	v_mfma_f32_16x16x32_bf16 v[104:107], v[154:157], v[192:195], v[104:107]
	v_mfma_f32_16x16x32_bf16 v[92:95], v[146:149], v[200:203], v[92:95]
	v_mfma_f32_16x16x32_bf16 v[88:91], v[154:157], v[200:203], v[88:91]
	v_mfma_f32_16x16x32_bf16 v[76:79], v[146:149], v[208:211], v[76:79]
	v_mfma_f32_16x16x32_bf16 v[72:75], v[154:157], v[208:211], v[72:75]
	v_mfma_f32_16x16x32_bf16 v[124:127], v[150:153], v[188:191], v[124:127]
	v_mfma_f32_16x16x32_bf16 v[120:123], v[158:161], v[188:191], v[120:123]
	v_mfma_f32_16x16x32_bf16 v[108:111], v[150:153], v[196:199], v[108:111]
	v_mfma_f32_16x16x32_bf16 v[104:107], v[158:161], v[196:199], v[104:107]
	v_mfma_f32_16x16x32_bf16 v[92:95], v[150:153], v[204:207], v[92:95]
	v_mfma_f32_16x16x32_bf16 v[88:91], v[158:161], v[204:207], v[88:91]
	v_mfma_f32_16x16x32_bf16 v[76:79], v[150:153], v[216:219], v[76:79]
	v_mfma_f32_16x16x32_bf16 v[72:75], v[158:161], v[216:219], v[72:75]
	v_mfma_f32_16x16x32_bf16 v[116:119], v[168:171], v[184:187], v[116:119]
	v_mfma_f32_16x16x32_bf16 v[112:115], v[176:179], v[184:187], v[112:115]
	v_mfma_f32_16x16x32_bf16 v[100:103], v[168:171], v[192:195], v[100:103]
	v_mfma_f32_16x16x32_bf16 v[96:99], v[176:179], v[192:195], v[96:99]
	v_mfma_f32_16x16x32_bf16 v[84:87], v[168:171], v[200:203], v[84:87]
	v_mfma_f32_16x16x32_bf16 v[80:83], v[176:179], v[200:203], v[80:83]
	v_mfma_f32_16x16x32_bf16 v[68:71], v[168:171], v[208:211], v[68:71]
	v_mfma_f32_16x16x32_bf16 v[64:67], v[176:179], v[208:211], v[64:67]
	v_mfma_f32_16x16x32_bf16 v[116:119], v[172:175], v[188:191], v[116:119]
	v_mfma_f32_16x16x32_bf16 v[112:115], v[180:183], v[188:191], v[112:115]
	v_mfma_f32_16x16x32_bf16 v[100:103], v[172:175], v[196:199], v[100:103]
	v_mfma_f32_16x16x32_bf16 v[96:99], v[180:183], v[196:199], v[96:99]
	v_mfma_f32_16x16x32_bf16 v[84:87], v[172:175], v[204:207], v[84:87]
	v_mfma_f32_16x16x32_bf16 v[80:83], v[180:183], v[204:207], v[80:83]
	v_mfma_f32_16x16x32_bf16 v[68:71], v[172:175], v[216:219], v[68:71]
	v_mfma_f32_16x16x32_bf16 v[64:67], v[180:183], v[216:219], v[64:67]
	s_barrier
; #define PG8_STAGE(bufoff, gbase, voff) do { _Pragma("unroll") for (int _i = 0; _i < 2; ++_i) \
;         __builtin_amdgcn_global_load_lds((const unsigned*)((const char*)(gbase) + (voff)[_i]), (LAS unsigned*)(lds + (bufoff) + ldsw + _i * 8192), 16, 0, 0); } while (0)
; #define PG8_LDA(dst, b, h) do { _Pragma("unroll") for (int m = 0; m < 4; ++m) _Pragma("unroll") for (int k = 0; k < 2; ++k) dst[m][k] = *(const LAS bf16x8*)(lds + PG8_SA(b, h) + aoff + m * 2048 + k * 1024); } while (0)
; #define PG8_LDB(dst, b, h) do { _Pragma("unroll") for (int n = 0; n < 2; ++n) _Pragma("unroll") for (int k = 0; k < 2; ++k) dst[n][k] = *(const LAS bf16x8*)(lds + PG8_SB(b, h) + boff + n * 2048 + k * 1024); } while (0)
; #define PG8_MMA(ai, bj, At, Bt) do { __builtin_amdgcn_s_setprio(1); _Pragma("unroll") for (int m = 0; m < 4; ++m) _Pragma("unroll") for (int n = 0; n < 2; ++n) _Pragma("unroll") for (int k = 0; k < 2; ++k) \
;         acc[ai][bj][m][n] = __builtin_amdgcn_mfma_f32_16x16x32_bf16(Bt[n][k], At[m][k], acc[ai][bj][m][n], 0, 0, 0); __builtin_amdgcn_s_setprio(0); } while (0)
; #define PG8_WAIT_V(n) asm volatile("s_waitcnt vmcnt(" #n ")" ::: "memory")
; #define PG8_WAIT_L(n) asm volatile("s_waitcnt lgkmcnt(" #n ")" ::: "memory")
; #define PG8_BAR __builtin_amdgcn_s_barrier()
; #define PG8_SCHED __builtin_amdgcn_sched_barrier(0)
; template <class Epi>
; DI void gemm_phase(LAS unsigned char* lds, const int wid, const Gemm g, const Order& S, const Epi& E) {
;     ...
;         for (int t = 0; t < nt; t += 2) {
;             const bool last = (t == nt - 2);
;             const char* a1 = cA + (size_t)(t + 1) * kstep;
;             const char* a2 = last ? nA : cA + (size_t)(t + 2) * kstep; const char* b2 = last ? nB : cB + (size_t)(t + 2) * kstep;
;             const char* a3 = a2 + kstep; const char* b3 = b2 + kstep;
;             PG8_LDB(B0, 0, 0); PG8_LDB(B1, 0, 1); PG8_SCHED; PG8_LDA(At, 0, 0); PG8_STAGE(PG8_SA(1, 1), a1 + hstepA, voffA);
;     ...
;             PG8_LDA(At, 1, 1); PG8_STAGE(PG8_SB(1, 0), b3, voffB); PG8_STAGE(PG8_SB(1, 1), b3 + hstepB, voffB); PG8_STAGE(PG8_SA(1, 0), a3, voffA);
;             PG8_WAIT_V(8); PG8_WAIT_L(0); PG8_BAR; PG8_MMA(1, 0, At, B0); PG8_MMA(1, 1, At, B1); PG8_BAR; PG8_SCHED;
	s_add_i32 s66, s71, s94
	v_lshl_add_u64 v[212:213], v[212:213], 0, s[34:35]
	s_mov_b32 m0, s66
	ds_read_b128 v[184:187], v165 offset:49152
	ds_read_b128 v[188:191], v165 offset:50176
	ds_read_b128 v[192:195], v165 offset:51200
	ds_read_b128 v[196:199], v165 offset:52224
	ds_read_b128 v[200:203], v165 offset:53248
	ds_read_b128 v[204:207], v165 offset:54272
	ds_read_b128 v[208:211], v165 offset:55296
	ds_read_b128 v[216:219], v165 offset:56320
	global_load_lds_dwordx4 v[212:213], off
	s_add_i32 m0, s66, 0x2000
	s_add_u32 s64, s64, 0x40080
	v_lshl_add_u64 v[212:213], v[214:215], 0, s[34:35]
	s_addc_u32 s65, s65, 0
	s_add_i32 s66, s86, s94
	global_load_lds_dwordx4 v[212:213], off
	v_lshl_add_u64 v[212:213], s[64:65], 0, v[130:131]
	s_mov_b32 m0, s66
	s_nop 0
	global_load_lds_dwordx4 v[212:213], off
	v_lshl_add_u64 v[212:213], s[64:65], 0, v[134:135]
	s_add_i32 m0, s66, 0x2000
	s_nop 0
	global_load_lds_dwordx4 v[212:213], off
	v_lshl_add_u64 v[212:213], v[220:221], 0, s[34:35]
	s_mov_b32 m0, s27
	s_nop 0
	global_load_lds_dwordx4 v[212:213], off
	v_lshl_add_u64 v[212:213], v[222:223], 0, s[34:35]
	s_mov_b32 m0, s55
	s_nop 0
	global_load_lds_dwordx4 v[212:213], off
	s_waitcnt vmcnt(8)
	s_waitcnt lgkmcnt(0)
	s_barrier
	v_mfma_f32_16x16x32_bf16 v[60:63], v[146:149], v[184:187], v[60:63]
	v_mfma_f32_16x16x32_bf16 v[56:59], v[154:157], v[184:187], v[56:59]
	v_mfma_f32_16x16x32_bf16 v[44:47], v[146:149], v[192:195], v[44:47]
	v_mfma_f32_16x16x32_bf16 v[40:43], v[154:157], v[192:195], v[40:43]
	v_mfma_f32_16x16x32_bf16 v[28:31], v[146:149], v[200:203], v[28:31]
	v_mfma_f32_16x16x32_bf16 v[24:27], v[154:157], v[200:203], v[24:27]
	v_mfma_f32_16x16x32_bf16 v[12:15], v[146:149], v[208:211], v[12:15]
	v_mfma_f32_16x16x32_bf16 v[8:11], v[154:157], v[208:211], v[8:11]
	v_mfma_f32_16x16x32_bf16 v[60:63], v[150:153], v[188:191], v[60:63]
	v_mfma_f32_16x16x32_bf16 v[56:59], v[158:161], v[188:191], v[56:59]
	v_mfma_f32_16x16x32_bf16 v[44:47], v[150:153], v[196:199], v[44:47]
	v_mfma_f32_16x16x32_bf16 v[40:43], v[158:161], v[196:199], v[40:43]
	v_mfma_f32_16x16x32_bf16 v[28:31], v[150:153], v[204:207], v[28:31]
	v_mfma_f32_16x16x32_bf16 v[24:27], v[158:161], v[204:207], v[24:27]
	v_mfma_f32_16x16x32_bf16 v[12:15], v[150:153], v[216:219], v[12:15]
	v_mfma_f32_16x16x32_bf16 v[8:11], v[158:161], v[216:219], v[8:11]
	v_mfma_f32_16x16x32_bf16 v[52:55], v[168:171], v[184:187], v[52:55]
	v_mfma_f32_16x16x32_bf16 v[48:51], v[176:179], v[184:187], v[48:51]
	v_mfma_f32_16x16x32_bf16 v[36:39], v[168:171], v[192:195], v[36:39]
	v_mfma_f32_16x16x32_bf16 v[32:35], v[176:179], v[192:195], v[32:35]
	v_mfma_f32_16x16x32_bf16 v[20:23], v[168:171], v[200:203], v[20:23]
	v_mfma_f32_16x16x32_bf16 v[16:19], v[176:179], v[200:203], v[16:19]
	v_mfma_f32_16x16x32_bf16 v[4:7], v[168:171], v[208:211], v[4:7]
	v_mfma_f32_16x16x32_bf16 v[0:3], v[176:179], v[208:211], v[0:3]
	v_mfma_f32_16x16x32_bf16 v[52:55], v[172:175], v[188:191], v[52:55]
	v_mfma_f32_16x16x32_bf16 v[48:51], v[180:183], v[188:191], v[48:51]
	v_mfma_f32_16x16x32_bf16 v[36:39], v[172:175], v[196:199], v[36:39]
	v_mfma_f32_16x16x32_bf16 v[32:35], v[180:183], v[196:199], v[32:35]
	v_mfma_f32_16x16x32_bf16 v[20:23], v[172:175], v[204:207], v[20:23]
	v_mfma_f32_16x16x32_bf16 v[16:19], v[180:183], v[204:207], v[16:19]
	v_mfma_f32_16x16x32_bf16 v[4:7], v[172:175], v[216:219], v[4:7]
	v_mfma_f32_16x16x32_bf16 v[0:3], v[180:183], v[216:219], v[0:3]
	s_barrier
	s_add_i32 s70, s70, 2
	s_add_u32 s12, s12, 0x100
	s_addc_u32 s13, s13, 0
	s_add_u32 s68, s68, 0x100
	s_addc_u32 s69, s69, 0
	s_cmp_gt_u32 s70, 13
	s_cbranch_scc0 .LBB0_400
	s_branch .Lpeel_exit_2
.LBB0_400:
	ds_read_b128 v[146:149], v163
	ds_read_b128 v[150:153], v163 offset:1024
	ds_read_b128 v[154:157], v163 offset:2048
	ds_read_b128 v[158:161], v163 offset:3072
	ds_read_b128 v[168:171], v164
	ds_read_b128 v[172:175], v164 offset:1024
	ds_read_b128 v[176:179], v164 offset:2048
	ds_read_b128 v[180:183], v164 offset:3072
	s_add_u32 s64, s12, 0xfffc0080
	s_addc_u32 s65, s13, -1
	s_cmp_eq_u32 s70, 12
	s_cselect_b32 s67, s11, s65
	s_cselect_b32 s66, s16, s64
	s_cselect_b32 s65, s57, s69
	s_cselect_b32 s64, s59, s68
	v_lshl_add_u64 v[212:213], s[12:13], 0, v[138:139]
	s_add_i32 m0, s6, 0xc000
	ds_read_b128 v[184:187], v165
	ds_read_b128 v[188:191], v165 offset:1024
	ds_read_b128 v[192:195], v165 offset:2048
	ds_read_b128 v[196:199], v165 offset:3072
	ds_read_b128 v[200:203], v165 offset:4096
	ds_read_b128 v[204:207], v165 offset:5120
	ds_read_b128 v[208:211], v165 offset:6144
	ds_read_b128 v[216:219], v165 offset:7168
	global_load_lds_dwordx4 v[212:213], off
	v_lshl_add_u64 v[212:213], s[12:13], 0, v[140:141]
	s_add_i32 m0, s6, 0xe000
	s_nop 0
	global_load_lds_dwordx4 v[212:213], off
	s_waitcnt vmcnt(8)
	s_waitcnt lgkmcnt(0)
	s_barrier
; #define PG8_STAGE(bufoff, gbase, voff) do { _Pragma("unroll") for (int _i = 0; _i < 2; ++_i) \
;         __builtin_amdgcn_global_load_lds((const unsigned*)((const char*)(gbase) + (voff)[_i]), (LAS unsigned*)(lds + (bufoff) + ldsw + _i * 8192), 16, 0, 0); } while (0)
; #define PG8_LDA(dst, b, h) do { _Pragma("unroll") for (int m = 0; m < 4; ++m) _Pragma("unroll") for (int k = 0; k < 2; ++k) dst[m][k] = *(const LAS bf16x8*)(lds + PG8_SA(b, h) + aoff + m * 2048 + k * 1024); } while (0)
; #define PG8_MMA(ai, bj, At, Bt) do { __builtin_amdgcn_s_setprio(1); _Pragma("unroll") for (int m = 0; m < 4; ++m) _Pragma("unroll") for (int n = 0; n < 2; ++n) _Pragma("unroll") for (int k = 0; k < 2; ++k) \
;         acc[ai][bj][m][n] = __builtin_amdgcn_mfma_f32_16x16x32_bf16(Bt[n][k], At[m][k], acc[ai][bj][m][n], 0, 0, 0); __builtin_amdgcn_s_setprio(0); } while (0)
; #define PG8_WAIT_V(n) asm volatile("s_waitcnt vmcnt(" #n ")" ::: "memory")
; #define PG8_WAIT_L(n) asm volatile("s_waitcnt lgkmcnt(" #n ")" ::: "memory")
; #define PG8_BAR __builtin_amdgcn_s_barrier()
; #define PG8_SCHED __builtin_amdgcn_sched_barrier(0)
; template <class Epi>
; DI void gemm_phase(LAS unsigned char* lds, const int wid, const Gemm g, const Order& S, const Epi& E) {
;     ...
;             PG8_WAIT_V(8); PG8_WAIT_L(0); PG8_BAR; PG8_MMA(0, 0, At, B0); PG8_MMA(0, 1, At, B1); PG8_BAR; PG8_SCHED;
;             PG8_LDA(At, 0, 1); PG8_STAGE(PG8_SB(0, 0), b2, voffB); PG8_STAGE(PG8_SB(0, 1), b2 + hstepB, voffB); PG8_STAGE(PG8_SA(0, 0), a2, voffA);
;             PG8_WAIT_V(8); PG8_WAIT_L(0); PG8_BAR; PG8_MMA(1, 0, At, B0); PG8_MMA(1, 1, At, B1); PG8_BAR; PG8_SCHED;
	v_mfma_f32_16x16x32_bf16 v[124:127], v[146:149], v[184:187], v[124:127]
	v_mfma_f32_16x16x32_bf16 v[120:123], v[154:157], v[184:187], v[120:123]
	v_mfma_f32_16x16x32_bf16 v[108:111], v[146:149], v[192:195], v[108:111]
	v_mfma_f32_16x16x32_bf16 v[104:107], v[154:157], v[192:195], v[104:107]
	v_mfma_f32_16x16x32_bf16 v[92:95], v[146:149], v[200:203], v[92:95]
	v_mfma_f32_16x16x32_bf16 v[88:91], v[154:157], v[200:203], v[88:91]
	v_mfma_f32_16x16x32_bf16 v[76:79], v[146:149], v[208:211], v[76:79]
	v_mfma_f32_16x16x32_bf16 v[72:75], v[154:157], v[208:211], v[72:75]
	v_mfma_f32_16x16x32_bf16 v[124:127], v[150:153], v[188:191], v[124:127]
	v_mfma_f32_16x16x32_bf16 v[120:123], v[158:161], v[188:191], v[120:123]
	v_mfma_f32_16x16x32_bf16 v[108:111], v[150:153], v[196:199], v[108:111]
	v_mfma_f32_16x16x32_bf16 v[104:107], v[158:161], v[196:199], v[104:107]
	v_mfma_f32_16x16x32_bf16 v[92:95], v[150:153], v[204:207], v[92:95]
	v_mfma_f32_16x16x32_bf16 v[88:91], v[158:161], v[204:207], v[88:91]
	v_mfma_f32_16x16x32_bf16 v[76:79], v[150:153], v[216:219], v[76:79]
	v_mfma_f32_16x16x32_bf16 v[72:75], v[158:161], v[216:219], v[72:75]
	v_mfma_f32_16x16x32_bf16 v[116:119], v[168:171], v[184:187], v[116:119]
	v_mfma_f32_16x16x32_bf16 v[112:115], v[176:179], v[184:187], v[112:115]
	v_mfma_f32_16x16x32_bf16 v[100:103], v[168:171], v[192:195], v[100:103]
	v_mfma_f32_16x16x32_bf16 v[96:99], v[176:179], v[192:195], v[96:99]
	v_mfma_f32_16x16x32_bf16 v[84:87], v[168:171], v[200:203], v[84:87]
	v_mfma_f32_16x16x32_bf16 v[80:83], v[176:179], v[200:203], v[80:83]
	v_mfma_f32_16x16x32_bf16 v[68:71], v[168:171], v[208:211], v[68:71]
	v_mfma_f32_16x16x32_bf16 v[64:67], v[176:179], v[208:211], v[64:67]
	v_mfma_f32_16x16x32_bf16 v[116:119], v[172:175], v[188:191], v[116:119]
	v_mfma_f32_16x16x32_bf16 v[112:115], v[180:183], v[188:191], v[112:115]
	v_mfma_f32_16x16x32_bf16 v[100:103], v[172:175], v[196:199], v[100:103]
	v_mfma_f32_16x16x32_bf16 v[96:99], v[180:183], v[196:199], v[96:99]
	v_mfma_f32_16x16x32_bf16 v[84:87], v[172:175], v[204:207], v[84:87]
	v_mfma_f32_16x16x32_bf16 v[80:83], v[180:183], v[204:207], v[80:83]
	v_mfma_f32_16x16x32_bf16 v[68:71], v[172:175], v[216:219], v[68:71]
	v_mfma_f32_16x16x32_bf16 v[64:67], v[180:183], v[216:219], v[64:67]
	s_barrier
	s_add_i32 s71, s82, s94
	v_lshl_add_u64 v[212:213], s[64:65], 0, v[130:131]
	s_mov_b32 m0, s71
	ds_read_b128 v[184:187], v165 offset:16384
	ds_read_b128 v[188:191], v165 offset:17408
	ds_read_b128 v[192:195], v165 offset:18432
	ds_read_b128 v[196:199], v165 offset:19456
	ds_read_b128 v[200:203], v165 offset:20480
	ds_read_b128 v[204:207], v165 offset:21504
	ds_read_b128 v[208:211], v165 offset:22528
	ds_read_b128 v[216:219], v165 offset:23552
	global_load_lds_dwordx4 v[212:213], off
	s_add_i32 m0, s71, 0x2000
	s_add_u32 s86, s64, 0x40000
	v_lshl_add_u64 v[214:215], s[64:65], 0, v[134:135]
	s_addc_u32 s87, s65, 0
	s_add_i32 s71, s83, s94
	global_load_lds_dwordx4 v[214:215], off
	v_lshl_add_u64 v[220:221], s[86:87], 0, v[130:131]
	s_mov_b32 m0, s71
	v_lshl_add_u64 v[222:223], s[66:67], 0, v[132:133]
	global_load_lds_dwordx4 v[220:221], off
	v_lshl_add_u64 v[220:221], s[86:87], 0, v[134:135]
	s_add_i32 m0, s71, 0x2000
	s_nop 0
	global_load_lds_dwordx4 v[220:221], off
	v_lshl_add_u64 v[220:221], s[66:67], 0, v[128:129]
	s_mov_b32 m0, s6
	s_nop 0
	global_load_lds_dwordx4 v[220:221], off
	s_mov_b32 m0, s7
	s_nop 0
	global_load_lds_dwordx4 v[222:223], off
	s_waitcnt vmcnt(8)
	s_waitcnt lgkmcnt(0)
	s_barrier
	v_mfma_f32_16x16x32_bf16 v[60:63], v[146:149], v[184:187], v[60:63]
	v_mfma_f32_16x16x32_bf16 v[56:59], v[154:157], v[184:187], v[56:59]
	v_mfma_f32_16x16x32_bf16 v[44:47], v[146:149], v[192:195], v[44:47]
	v_mfma_f32_16x16x32_bf16 v[40:43], v[154:157], v[192:195], v[40:43]
	v_mfma_f32_16x16x32_bf16 v[28:31], v[146:149], v[200:203], v[28:31]
	v_mfma_f32_16x16x32_bf16 v[24:27], v[154:157], v[200:203], v[24:27]
	v_mfma_f32_16x16x32_bf16 v[12:15], v[146:149], v[208:211], v[12:15]
	v_mfma_f32_16x16x32_bf16 v[8:11], v[154:157], v[208:211], v[8:11]
	v_mfma_f32_16x16x32_bf16 v[60:63], v[150:153], v[188:191], v[60:63]
	v_mfma_f32_16x16x32_bf16 v[56:59], v[158:161], v[188:191], v[56:59]
	v_mfma_f32_16x16x32_bf16 v[44:47], v[150:153], v[196:199], v[44:47]
	v_mfma_f32_16x16x32_bf16 v[40:43], v[158:161], v[196:199], v[40:43]
	v_mfma_f32_16x16x32_bf16 v[28:31], v[150:153], v[204:207], v[28:31]
	v_mfma_f32_16x16x32_bf16 v[24:27], v[158:161], v[204:207], v[24:27]
	v_mfma_f32_16x16x32_bf16 v[12:15], v[150:153], v[216:219], v[12:15]
	v_mfma_f32_16x16x32_bf16 v[8:11], v[158:161], v[216:219], v[8:11]
	v_mfma_f32_16x16x32_bf16 v[52:55], v[168:171], v[184:187], v[52:55]
	v_mfma_f32_16x16x32_bf16 v[48:51], v[176:179], v[184:187], v[48:51]
	v_mfma_f32_16x16x32_bf16 v[36:39], v[168:171], v[192:195], v[36:39]
	v_mfma_f32_16x16x32_bf16 v[32:35], v[176:179], v[192:195], v[32:35]
	v_mfma_f32_16x16x32_bf16 v[20:23], v[168:171], v[200:203], v[20:23]
	v_mfma_f32_16x16x32_bf16 v[16:19], v[176:179], v[200:203], v[16:19]
	v_mfma_f32_16x16x32_bf16 v[4:7], v[168:171], v[208:211], v[4:7]
	v_mfma_f32_16x16x32_bf16 v[0:3], v[176:179], v[208:211], v[0:3]
	v_mfma_f32_16x16x32_bf16 v[52:55], v[172:175], v[188:191], v[52:55]
	v_mfma_f32_16x16x32_bf16 v[48:51], v[180:183], v[188:191], v[48:51]
	v_mfma_f32_16x16x32_bf16 v[36:39], v[172:175], v[196:199], v[36:39]
	v_mfma_f32_16x16x32_bf16 v[32:35], v[180:183], v[196:199], v[32:35]
	v_mfma_f32_16x16x32_bf16 v[20:23], v[172:175], v[204:207], v[20:23]
	v_mfma_f32_16x16x32_bf16 v[16:19], v[180:183], v[204:207], v[16:19]
	v_mfma_f32_16x16x32_bf16 v[4:7], v[172:175], v[216:219], v[4:7]
	v_mfma_f32_16x16x32_bf16 v[0:3], v[180:183], v[216:219], v[0:3]
	s_barrier
; #define PG8_STAGE(bufoff, gbase, voff) do { _Pragma("unroll") for (int _i = 0; _i < 2; ++_i) \
;         __builtin_amdgcn_global_load_lds((const unsigned*)((const char*)(gbase) + (voff)[_i]), (LAS unsigned*)(lds + (bufoff) + ldsw + _i * 8192), 16, 0, 0); } while (0)
; #define PG8_LDA(dst, b, h) do { _Pragma("unroll") for (int m = 0; m < 4; ++m) _Pragma("unroll") for (int k = 0; k < 2; ++k) dst[m][k] = *(const LAS bf16x8*)(lds + PG8_SA(b, h) + aoff + m * 2048 + k * 1024); } while (0)
; #define PG8_LDB(dst, b, h) do { _Pragma("unroll") for (int n = 0; n < 2; ++n) _Pragma("unroll") for (int k = 0; k < 2; ++k) dst[n][k] = *(const LAS bf16x8*)(lds + PG8_SB(b, h) + boff + n * 2048 + k * 1024); } while (0)
; #define PG8_MMA(ai, bj, At, Bt) do { __builtin_amdgcn_s_setprio(1); _Pragma("unroll") for (int m = 0; m < 4; ++m) _Pragma("unroll") for (int n = 0; n < 2; ++n) _Pragma("unroll") for (int k = 0; k < 2; ++k) \
;         acc[ai][bj][m][n] = __builtin_amdgcn_mfma_f32_16x16x32_bf16(Bt[n][k], At[m][k], acc[ai][bj][m][n], 0, 0, 0); __builtin_amdgcn_s_setprio(0); } while (0)
; #define PG8_WAIT_V(n) asm volatile("s_waitcnt vmcnt(" #n ")" ::: "memory")
; #define PG8_WAIT_L(n) asm volatile("s_waitcnt lgkmcnt(" #n ")" ::: "memory")
; #define PG8_BAR __builtin_amdgcn_s_barrier()
; #define PG8_SCHED __builtin_amdgcn_sched_barrier(0)
; template <class Epi>
; DI void gemm_phase(LAS unsigned char* lds, const int wid, const Gemm g, const Order& S, const Epi& E) {
;     ...
;             PG8_LDB(B0, 1, 0); PG8_LDB(B1, 1, 1); PG8_SCHED; PG8_LDA(At, 1, 0); PG8_STAGE(PG8_SA(0, 1), a2 + hstepA, voffA);
;             PG8_WAIT_V(8); PG8_WAIT_L(0); PG8_BAR; PG8_MMA(0, 0, At, B0); PG8_MMA(0, 1, At, B1); PG8_BAR; PG8_SCHED;
;             PG8_LDA(At, 1, 1); PG8_STAGE(PG8_SB(1, 0), b3, voffB); PG8_STAGE(PG8_SB(1, 1), b3 + hstepB, voffB); PG8_STAGE(PG8_SA(1, 0), a3, voffA);
;             PG8_WAIT_V(8); PG8_WAIT_L(0); PG8_BAR; PG8_MMA(1, 0, At, B0); PG8_MMA(1, 1, At, B1); PG8_BAR; PG8_SCHED;
	s_add_i32 s71, 0, 0x18000
	v_add_u32_e32 v136, s71, v162
	s_add_i32 s86, 0, 0x1c000
	ds_read_b128 v[146:149], v136
	ds_read_b128 v[150:153], v136 offset:1024
	ds_read_b128 v[154:157], v136 offset:2048
	ds_read_b128 v[158:161], v136 offset:3072
	v_add_u32_e32 v136, s86, v162
	ds_read_b128 v[168:171], v136
	ds_read_b128 v[172:175], v136 offset:1024
	ds_read_b128 v[176:179], v136 offset:2048
	ds_read_b128 v[180:183], v136 offset:3072
	s_add_u32 s66, s66, 0x40000
	s_addc_u32 s67, s67, 0
	s_mov_b32 m0, s21
	v_lshl_add_u64 v[224:225], s[66:67], 0, v[128:129]
	ds_read_b128 v[184:187], v165 offset:32768
	ds_read_b128 v[188:191], v165 offset:33792
	ds_read_b128 v[192:195], v165 offset:34816
	ds_read_b128 v[196:199], v165 offset:35840
	ds_read_b128 v[200:203], v165 offset:36864
	ds_read_b128 v[204:207], v165 offset:37888
	ds_read_b128 v[208:211], v165 offset:38912
	ds_read_b128 v[216:219], v165 offset:39936
	global_load_lds_dwordx4 v[224:225], off
	v_lshl_add_u64 v[224:225], s[66:67], 0, v[132:133]
	s_mov_b32 m0, s26
	s_nop 0
	global_load_lds_dwordx4 v[224:225], off
	s_waitcnt vmcnt(8)
	s_waitcnt lgkmcnt(0)
	s_barrier
	v_mfma_f32_16x16x32_bf16 v[124:127], v[146:149], v[184:187], v[124:127]
	v_mfma_f32_16x16x32_bf16 v[120:123], v[154:157], v[184:187], v[120:123]
	v_mfma_f32_16x16x32_bf16 v[108:111], v[146:149], v[192:195], v[108:111]
	v_mfma_f32_16x16x32_bf16 v[104:107], v[154:157], v[192:195], v[104:107]
	v_mfma_f32_16x16x32_bf16 v[92:95], v[146:149], v[200:203], v[92:95]
	v_mfma_f32_16x16x32_bf16 v[88:91], v[154:157], v[200:203], v[88:91]
	v_mfma_f32_16x16x32_bf16 v[76:79], v[146:149], v[208:211], v[76:79]
	v_mfma_f32_16x16x32_bf16 v[72:75], v[154:157], v[208:211], v[72:75]
	v_mfma_f32_16x16x32_bf16 v[124:127], v[150:153], v[188:191], v[124:127]
	v_mfma_f32_16x16x32_bf16 v[120:123], v[158:161], v[188:191], v[120:123]
	v_mfma_f32_16x16x32_bf16 v[108:111], v[150:153], v[196:199], v[108:111]
	v_mfma_f32_16x16x32_bf16 v[104:107], v[158:161], v[196:199], v[104:107]
	v_mfma_f32_16x16x32_bf16 v[92:95], v[150:153], v[204:207], v[92:95]
	v_mfma_f32_16x16x32_bf16 v[88:91], v[158:161], v[204:207], v[88:91]
	v_mfma_f32_16x16x32_bf16 v[76:79], v[150:153], v[216:219], v[76:79]
	v_mfma_f32_16x16x32_bf16 v[72:75], v[158:161], v[216:219], v[72:75]
	v_mfma_f32_16x16x32_bf16 v[116:119], v[168:171], v[184:187], v[116:119]
	v_mfma_f32_16x16x32_bf16 v[112:115], v[176:179], v[184:187], v[112:115]
	v_mfma_f32_16x16x32_bf16 v[100:103], v[168:171], v[192:195], v[100:103]
	v_mfma_f32_16x16x32_bf16 v[96:99], v[176:179], v[192:195], v[96:99]
	v_mfma_f32_16x16x32_bf16 v[84:87], v[168:171], v[200:203], v[84:87]
	v_mfma_f32_16x16x32_bf16 v[80:83], v[176:179], v[200:203], v[80:83]
	v_mfma_f32_16x16x32_bf16 v[68:71], v[168:171], v[208:211], v[68:71]
	v_mfma_f32_16x16x32_bf16 v[64:67], v[176:179], v[208:211], v[64:67]
	v_mfma_f32_16x16x32_bf16 v[116:119], v[172:175], v[188:191], v[116:119]
	v_mfma_f32_16x16x32_bf16 v[112:115], v[180:183], v[188:191], v[112:115]
	v_mfma_f32_16x16x32_bf16 v[100:103], v[172:175], v[196:199], v[100:103]
	v_mfma_f32_16x16x32_bf16 v[96:99], v[180:183], v[196:199], v[96:99]
	v_mfma_f32_16x16x32_bf16 v[84:87], v[172:175], v[204:207], v[84:87]
	v_mfma_f32_16x16x32_bf16 v[80:83], v[180:183], v[204:207], v[80:83]
	v_mfma_f32_16x16x32_bf16 v[68:71], v[172:175], v[216:219], v[68:71]
	v_mfma_f32_16x16x32_bf16 v[64:67], v[180:183], v[216:219], v[64:67]
	s_barrier
	s_add_i32 s66, s71, s94
	v_lshl_add_u64 v[212:213], v[212:213], 0, s[34:35]
	s_mov_b32 m0, s66
	ds_read_b128 v[184:187], v165 offset:49152
	ds_read_b128 v[188:191], v165 offset:50176
	ds_read_b128 v[192:195], v165 offset:51200
	ds_read_b128 v[196:199], v165 offset:52224
	ds_read_b128 v[200:203], v165 offset:53248
	ds_read_b128 v[204:207], v165 offset:54272
	ds_read_b128 v[208:211], v165 offset:55296
	ds_read_b128 v[216:219], v165 offset:56320
	global_load_lds_dwordx4 v[212:213], off
	s_add_i32 m0, s66, 0x2000
	s_add_u32 s64, s64, 0x40080
	v_lshl_add_u64 v[212:213], v[214:215], 0, s[34:35]
	s_addc_u32 s65, s65, 0
	s_add_i32 s66, s86, s94
	global_load_lds_dwordx4 v[212:213], off
	v_lshl_add_u64 v[212:213], s[64:65], 0, v[130:131]
	s_mov_b32 m0, s66
	s_nop 0
	global_load_lds_dwordx4 v[212:213], off
	v_lshl_add_u64 v[212:213], s[64:65], 0, v[134:135]
	s_add_i32 m0, s66, 0x2000
	s_nop 0
	global_load_lds_dwordx4 v[212:213], off
	v_lshl_add_u64 v[212:213], v[220:221], 0, s[34:35]
	s_mov_b32 m0, s27
	s_nop 0
	global_load_lds_dwordx4 v[212:213], off
	v_lshl_add_u64 v[212:213], v[222:223], 0, s[34:35]
	s_mov_b32 m0, s55
	s_nop 0
	global_load_lds_dwordx4 v[212:213], off
	s_waitcnt vmcnt(8)
	s_waitcnt lgkmcnt(0)
	s_barrier
	v_mfma_f32_16x16x32_bf16 v[60:63], v[146:149], v[184:187], v[60:63]
	v_mfma_f32_16x16x32_bf16 v[56:59], v[154:157], v[184:187], v[56:59]
	v_mfma_f32_16x16x32_bf16 v[44:47], v[146:149], v[192:195], v[44:47]
	v_mfma_f32_16x16x32_bf16 v[40:43], v[154:157], v[192:195], v[40:43]
	v_mfma_f32_16x16x32_bf16 v[28:31], v[146:149], v[200:203], v[28:31]
	v_mfma_f32_16x16x32_bf16 v[24:27], v[154:157], v[200:203], v[24:27]
	v_mfma_f32_16x16x32_bf16 v[12:15], v[146:149], v[208:211], v[12:15]
	v_mfma_f32_16x16x32_bf16 v[8:11], v[154:157], v[208:211], v[8:11]
	v_mfma_f32_16x16x32_bf16 v[60:63], v[150:153], v[188:191], v[60:63]
	v_mfma_f32_16x16x32_bf16 v[56:59], v[158:161], v[188:191], v[56:59]
	v_mfma_f32_16x16x32_bf16 v[44:47], v[150:153], v[196:199], v[44:47]
	v_mfma_f32_16x16x32_bf16 v[40:43], v[158:161], v[196:199], v[40:43]
	v_mfma_f32_16x16x32_bf16 v[28:31], v[150:153], v[204:207], v[28:31]
	v_mfma_f32_16x16x32_bf16 v[24:27], v[158:161], v[204:207], v[24:27]
	v_mfma_f32_16x16x32_bf16 v[12:15], v[150:153], v[216:219], v[12:15]
	v_mfma_f32_16x16x32_bf16 v[8:11], v[158:161], v[216:219], v[8:11]
	v_mfma_f32_16x16x32_bf16 v[52:55], v[168:171], v[184:187], v[52:55]
	v_mfma_f32_16x16x32_bf16 v[48:51], v[176:179], v[184:187], v[48:51]
	v_mfma_f32_16x16x32_bf16 v[36:39], v[168:171], v[192:195], v[36:39]
	v_mfma_f32_16x16x32_bf16 v[32:35], v[176:179], v[192:195], v[32:35]
	v_mfma_f32_16x16x32_bf16 v[20:23], v[168:171], v[200:203], v[20:23]
	v_mfma_f32_16x16x32_bf16 v[16:19], v[176:179], v[200:203], v[16:19]
	v_mfma_f32_16x16x32_bf16 v[4:7], v[168:171], v[208:211], v[4:7]
	v_mfma_f32_16x16x32_bf16 v[0:3], v[176:179], v[208:211], v[0:3]
	v_mfma_f32_16x16x32_bf16 v[52:55], v[172:175], v[188:191], v[52:55]
	v_mfma_f32_16x16x32_bf16 v[48:51], v[180:183], v[188:191], v[48:51]
	v_mfma_f32_16x16x32_bf16 v[36:39], v[172:175], v[196:199], v[36:39]
	v_mfma_f32_16x16x32_bf16 v[32:35], v[180:183], v[196:199], v[32:35]
	v_mfma_f32_16x16x32_bf16 v[20:23], v[172:175], v[204:207], v[20:23]
	v_mfma_f32_16x16x32_bf16 v[16:19], v[180:183], v[204:207], v[16:19]
	v_mfma_f32_16x16x32_bf16 v[4:7], v[172:175], v[216:219], v[4:7]
	v_mfma_f32_16x16x32_bf16 v[0:3], v[180:183], v[216:219], v[0:3]
	s_barrier
	s_add_i32 s70, s70, 2
	s_add_u32 s12, s12, 0x100
	s_addc_u32 s13, s13, 0
	s_add_u32 s68, s68, 0x100
	s_addc_u32 s69, s69, 0
	s_cmp_gt_u32 s70, 13
	s_cbranch_scc0 .LBB0_400

; #define PG8_STAGE(bufoff, gbase, voff) do { _Pragma("unroll") for (int _i = 0; _i < 2; ++_i) \
;         __builtin_amdgcn_global_load_lds((const unsigned*)((const char*)(gbase) + (voff)[_i]), (LAS unsigned*)(lds + (bufoff) + ldsw + _i * 8192), 16, 0, 0); } while (0)
; #define PG8_LDA(dst, b, h) do { _Pragma("unroll") for (int m = 0; m < 4; ++m) _Pragma("unroll") for (int k = 0; k < 2; ++k) dst[m][k] = *(const LAS bf16x8*)(lds + PG8_SA(b, h) + aoff + m * 2048 + k * 1024); } while (0)
; #define PG8_LDB(dst, b, h) do { _Pragma("unroll") for (int n = 0; n < 2; ++n) _Pragma("unroll") for (int k = 0; k < 2; ++k) dst[n][k] = *(const LAS bf16x8*)(lds + PG8_SB(b, h) + boff + n * 2048 + k * 1024); } while (0)
; #define PG8_MMA(ai, bj, At, Bt) do { __builtin_amdgcn_s_setprio(1); _Pragma("unroll") for (int m = 0; m < 4; ++m) _Pragma("unroll") for (int n = 0; n < 2; ++n) _Pragma("unroll") for (int k = 0; k < 2; ++k) \
;         acc[ai][bj][m][n] = __builtin_amdgcn_mfma_f32_16x16x32_bf16(Bt[n][k], At[m][k], acc[ai][bj][m][n], 0, 0, 0); __builtin_amdgcn_s_setprio(0); } while (0)
; #define PG8_WAIT_V(n) asm volatile("s_waitcnt vmcnt(" #n ")" ::: "memory")
; #define PG8_WAIT_L(n) asm volatile("s_waitcnt lgkmcnt(" #n ")" ::: "memory")
; template <class Epi>
; DI void gemm_phase(LAS unsigned char* lds, const int wid, const Gemm g, const Order& S, const Epi& E) {
;     ...
;         const char* nA = has_next ? (const char*)(g.A + (size_t)nxt.g * g.gsA + (size_t)nxt.pm * BM * g.lda) : cA;
;         const char* nB = has_next ? (const char*)(g.Bt + (size_t)nxt.g * g.gsB + (size_t)nxt.pn * BM * g.ldb) : cB;
;         for (int t = 0; t < nt; t += 2) {
;             const bool last = (t == nt - 2);
;             const char* a1 = cA + (size_t)(t + 1) * kstep;
;             const char* a2 = last ? nA : cA + (size_t)(t + 2) * kstep; const char* b2 = last ? nB : cB + (size_t)(t + 2) * kstep;
;             const char* a3 = a2 + kstep; const char* b3 = b2 + kstep;
;             PG8_LDB(B0, 0, 0); PG8_LDB(B1, 0, 1); PG8_SCHED; PG8_LDA(At, 0, 0); PG8_STAGE(PG8_SA(1, 1), a1 + hstepA, voffA);
;             PG8_WAIT_V(8); PG8_WAIT_L(0); PG8_BAR; PG8_MMA(0, 0, At, B0); PG8_MMA(0, 1, At, B1); PG8_BAR; PG8_SCHED;
;             PG8_LDA(At, 0, 1); PG8_STAGE(PG8_SB(0, 0), b2, voffB); PG8_STAGE(PG8_SB(0, 1), b2 + hstepB, voffB); PG8_STAGE(PG8_SA(0, 0), a2, voffA);
.LBB0_631:
	ds_read_b128 v[0:3], v205
	ds_read_b128 v[4:7], v205 offset:1024
	ds_read_b128 v[8:11], v205 offset:2048
	ds_read_b128 v[12:15], v205 offset:3072
	ds_read_b128 v[16:19], v206
	ds_read_b128 v[20:23], v206 offset:1024
	ds_read_b128 v[24:27], v206 offset:2048
	ds_read_b128 v[28:31], v206 offset:3072
	s_ashr_i32 s41, s40, 31
	s_lshl_b64 s[44:45], s[40:41], 17
	s_add_u32 s44, s6, s44
	s_addc_u32 s45, s7, s45
	s_and_b64 s[46:47], s[8:9], exec
	s_cselect_b32 s59, s45, s53
	s_cselect_b32 s58, s44, s52
	s_ashr_i32 s43, s42, 31
	s_lshl_b64 s[46:47], s[42:43], 17
	s_add_u32 s46, s21, s46
	s_addc_u32 s47, s25, s47
	s_and_b64 s[56:57], s[8:9], exec
	s_cselect_b32 s57, s47, s55
	s_cselect_b32 s56, s46, s54
	s_add_u32 s76, s52, 0x10080
	s_addc_u32 s77, s53, 0
	s_add_i32 s75, s26, 0xc000
	v_lshl_add_u64 v[64:65], s[76:77], 0, v[160:161]
	s_mov_b32 m0, s75
	s_add_i32 s41, s26, 0xe000
	s_waitcnt vmcnt(0)
	ds_read_b128 v[32:35], v207
	ds_read_b128 v[36:39], v207 offset:1024
	ds_read_b128 v[40:43], v207 offset:2048
	ds_read_b128 v[44:47], v207 offset:3072
	ds_read_b128 v[48:51], v207 offset:4096
	ds_read_b128 v[52:55], v207 offset:5120
	ds_read_b128 v[56:59], v207 offset:6144
	ds_read_b128 v[60:63], v207 offset:7168
	global_load_lds_dwordx4 v[64:65], off
	v_lshl_add_u64 v[64:65], s[76:77], 0, v[164:165]
	s_mov_b32 m0, s41
	s_nop 0
	global_load_lds_dwordx4 v[64:65], off
	s_waitcnt vmcnt(8)
	s_waitcnt lgkmcnt(0)
	s_barrier
	v_mfma_f32_16x16x32_bf16 v[64:67], v[0:3], v[32:35], 0
	v_mfma_f32_16x16x32_bf16 v[68:71], v[8:11], v[32:35], 0
	v_mfma_f32_16x16x32_bf16 v[72:75], v[0:3], v[40:43], 0
	v_mfma_f32_16x16x32_bf16 v[76:79], v[8:11], v[40:43], 0
	v_mfma_f32_16x16x32_bf16 v[80:83], v[0:3], v[48:51], 0
	v_mfma_f32_16x16x32_bf16 v[84:87], v[8:11], v[48:51], 0
	v_mfma_f32_16x16x32_bf16 v[88:91], v[0:3], v[56:59], 0
	v_mfma_f32_16x16x32_bf16 v[92:95], v[8:11], v[56:59], 0
	v_mfma_f32_16x16x32_bf16 v[64:67], v[4:7], v[36:39], v[64:67]
	v_mfma_f32_16x16x32_bf16 v[68:71], v[12:15], v[36:39], v[68:71]
	v_mfma_f32_16x16x32_bf16 v[72:75], v[4:7], v[44:47], v[72:75]
	v_mfma_f32_16x16x32_bf16 v[76:79], v[12:15], v[44:47], v[76:79]
	v_mfma_f32_16x16x32_bf16 v[80:83], v[4:7], v[52:55], v[80:83]
	v_mfma_f32_16x16x32_bf16 v[84:87], v[12:15], v[52:55], v[84:87]
	v_mfma_f32_16x16x32_bf16 v[88:91], v[4:7], v[60:63], v[88:91]
	v_mfma_f32_16x16x32_bf16 v[92:95], v[12:15], v[60:63], v[92:95]
	v_mfma_f32_16x16x32_bf16 v[96:99], v[16:19], v[32:35], 0
	v_mfma_f32_16x16x32_bf16 v[32:35], v[24:27], v[32:35], 0
	v_mfma_f32_16x16x32_bf16 v[96:99], v[20:23], v[36:39], v[96:99]
	v_mfma_f32_16x16x32_bf16 v[32:35], v[28:31], v[36:39], v[32:35]
	v_mfma_f32_16x16x32_bf16 v[36:39], v[16:19], v[40:43], 0
	v_mfma_f32_16x16x32_bf16 v[40:43], v[24:27], v[40:43], 0
	v_mfma_f32_16x16x32_bf16 v[36:39], v[20:23], v[44:47], v[36:39]
	v_mfma_f32_16x16x32_bf16 v[40:43], v[28:31], v[44:47], v[40:43]
	v_mfma_f32_16x16x32_bf16 v[44:47], v[16:19], v[48:51], 0
	v_mfma_f32_16x16x32_bf16 v[48:51], v[24:27], v[48:51], 0
	v_mfma_f32_16x16x32_bf16 v[44:47], v[20:23], v[52:55], v[44:47]
	v_mfma_f32_16x16x32_bf16 v[48:51], v[28:31], v[52:55], v[48:51]
	v_mfma_f32_16x16x32_bf16 v[52:55], v[16:19], v[56:59], 0
	v_mfma_f32_16x16x32_bf16 v[56:59], v[24:27], v[56:59], 0
	v_mfma_f32_16x16x32_bf16 v[52:55], v[20:23], v[60:63], v[52:55]
	v_mfma_f32_16x16x32_bf16 v[56:59], v[28:31], v[60:63], v[56:59]
	s_barrier
	s_add_i32 s73, s67, s94
	v_lshl_add_u64 v[170:171], s[54:55], 0, v[162:163]
	s_add_i32 s43, s73, 0x2000
	v_lshl_add_u64 v[128:129], v[170:171], 0, s[36:37]
	s_mov_b32 m0, s73
	v_lshl_add_u64 v[172:173], s[54:55], 0, v[166:167]
	s_add_u32 s76, s54, 0x10100
	ds_read_b128 v[60:63], v207 offset:16384
	ds_read_b128 v[100:103], v207 offset:17408
	ds_read_b128 v[104:107], v207 offset:18432
	ds_read_b128 v[108:111], v207 offset:19456
	ds_read_b128 v[112:115], v207 offset:20480
	ds_read_b128 v[116:119], v207 offset:21504
	ds_read_b128 v[120:123], v207 offset:22528
	ds_read_b128 v[124:127], v207 offset:23552
	global_load_lds_dwordx4 v[128:129], off
	v_lshl_add_u64 v[128:129], v[172:173], 0, s[36:37]
	s_mov_b32 m0, s43
	s_addc_u32 s77, s55, 0
	s_add_i32 s49, s68, s94
	global_load_lds_dwordx4 v[128:129], off
	v_lshl_add_u64 v[128:129], s[76:77], 0, v[162:163]
	s_mov_b32 m0, s49
	s_add_i32 s71, s49, 0x2000
	global_load_lds_dwordx4 v[128:129], off
	v_lshl_add_u64 v[128:129], s[76:77], 0, v[166:167]
	s_mov_b32 m0, s71
	v_lshl_add_u64 v[202:203], s[52:53], 0, v[160:161]
	global_load_lds_dwordx4 v[128:129], off
	v_lshl_add_u64 v[128:129], v[202:203], 0, s[36:37]
	s_mov_b32 m0, s26
	v_lshl_add_u64 v[214:215], s[52:53], 0, v[164:165]
	global_load_lds_dwordx4 v[128:129], off
	v_lshl_add_u64 v[128:129], v[214:215], 0, s[36:37]
	s_mov_b32 m0, s27
	s_nop 0
	global_load_lds_dwordx4 v[128:129], off
	s_waitcnt vmcnt(8)
	s_waitcnt lgkmcnt(0)
	s_barrier
; #define PG8_STAGE(bufoff, gbase, voff) do { _Pragma("unroll") for (int _i = 0; _i < 2; ++_i) \
;         __builtin_amdgcn_global_load_lds((const unsigned*)((const char*)(gbase) + (voff)[_i]), (LAS unsigned*)(lds + (bufoff) + ldsw + _i * 8192), 16, 0, 0); } while (0)
; #define PG8_LDA(dst, b, h) do { _Pragma("unroll") for (int m = 0; m < 4; ++m) _Pragma("unroll") for (int k = 0; k < 2; ++k) dst[m][k] = *(const LAS bf16x8*)(lds + PG8_SA(b, h) + aoff + m * 2048 + k * 1024); } while (0)
; #define PG8_LDB(dst, b, h) do { _Pragma("unroll") for (int n = 0; n < 2; ++n) _Pragma("unroll") for (int k = 0; k < 2; ++k) dst[n][k] = *(const LAS bf16x8*)(lds + PG8_SB(b, h) + boff + n * 2048 + k * 1024); } while (0)
; #define PG8_MMA(ai, bj, At, Bt) do { __builtin_amdgcn_s_setprio(1); _Pragma("unroll") for (int m = 0; m < 4; ++m) _Pragma("unroll") for (int n = 0; n < 2; ++n) _Pragma("unroll") for (int k = 0; k < 2; ++k) \
;         acc[ai][bj][m][n] = __builtin_amdgcn_mfma_f32_16x16x32_bf16(Bt[n][k], At[m][k], acc[ai][bj][m][n], 0, 0, 0); __builtin_amdgcn_s_setprio(0); } while (0)
; #define PG8_WAIT_V(n) asm volatile("s_waitcnt vmcnt(" #n ")" ::: "memory")
; #define PG8_WAIT_L(n) asm volatile("s_waitcnt lgkmcnt(" #n ")" ::: "memory")
; #define PG8_BAR __builtin_amdgcn_s_barrier()
; #define PG8_SCHED __builtin_amdgcn_sched_barrier(0)
; template <class Epi>
; DI void gemm_phase(LAS unsigned char* lds, const int wid, const Gemm g, const Order& S, const Epi& E) {
;     ...
;             PG8_WAIT_V(8); PG8_WAIT_L(0); PG8_BAR; PG8_MMA(1, 0, At, B0); PG8_MMA(1, 1, At, B1); PG8_BAR; PG8_SCHED;
;             PG8_LDB(B0, 1, 0); PG8_LDB(B1, 1, 1); PG8_SCHED; PG8_LDA(At, 1, 0); PG8_STAGE(PG8_SA(0, 1), a2 + hstepA, voffA);
;             PG8_WAIT_V(8); PG8_WAIT_L(0); PG8_BAR; PG8_MMA(0, 0, At, B0); PG8_MMA(0, 1, At, B1); PG8_BAR; PG8_SCHED;
	v_mfma_f32_16x16x32_bf16 v[128:131], v[0:3], v[60:63], 0
	v_mfma_f32_16x16x32_bf16 v[136:139], v[0:3], v[104:107], 0
	v_mfma_f32_16x16x32_bf16 v[144:147], v[0:3], v[112:115], 0
	v_mfma_f32_16x16x32_bf16 v[0:3], v[0:3], v[120:123], 0
	v_mfma_f32_16x16x32_bf16 v[128:131], v[4:7], v[100:103], v[128:131]
	v_mfma_f32_16x16x32_bf16 v[132:135], v[8:11], v[60:63], 0
	v_mfma_f32_16x16x32_bf16 v[136:139], v[4:7], v[108:111], v[136:139]
	v_mfma_f32_16x16x32_bf16 v[144:147], v[4:7], v[116:119], v[144:147]
	v_mfma_f32_16x16x32_bf16 v[0:3], v[4:7], v[124:127], v[0:3]
	v_mfma_f32_16x16x32_bf16 v[4:7], v[8:11], v[120:123], 0
	v_mfma_f32_16x16x32_bf16 v[132:135], v[12:15], v[100:103], v[132:135]
	v_mfma_f32_16x16x32_bf16 v[140:143], v[8:11], v[104:107], 0
	v_mfma_f32_16x16x32_bf16 v[148:151], v[8:11], v[112:115], 0
	v_mfma_f32_16x16x32_bf16 v[4:7], v[12:15], v[124:127], v[4:7]
	v_mfma_f32_16x16x32_bf16 v[140:143], v[12:15], v[108:111], v[140:143]
	v_mfma_f32_16x16x32_bf16 v[148:151], v[12:15], v[116:119], v[148:151]
	v_mfma_f32_16x16x32_bf16 v[8:11], v[16:19], v[60:63], 0
	v_mfma_f32_16x16x32_bf16 v[12:15], v[24:27], v[60:63], 0
	v_mfma_f32_16x16x32_bf16 v[8:11], v[20:23], v[100:103], v[8:11]
	v_mfma_f32_16x16x32_bf16 v[12:15], v[28:31], v[100:103], v[12:15]
	v_mfma_f32_16x16x32_bf16 v[60:63], v[16:19], v[104:107], 0
	v_mfma_f32_16x16x32_bf16 v[100:103], v[24:27], v[104:107], 0
	v_mfma_f32_16x16x32_bf16 v[104:107], v[16:19], v[112:115], 0
	v_mfma_f32_16x16x32_bf16 v[16:19], v[16:19], v[120:123], 0
	v_mfma_f32_16x16x32_bf16 v[60:63], v[20:23], v[108:111], v[60:63]
	v_mfma_f32_16x16x32_bf16 v[100:103], v[28:31], v[108:111], v[100:103]
	v_mfma_f32_16x16x32_bf16 v[104:107], v[20:23], v[116:119], v[104:107]
	v_mfma_f32_16x16x32_bf16 v[108:111], v[24:27], v[112:115], 0
	v_mfma_f32_16x16x32_bf16 v[16:19], v[20:23], v[124:127], v[16:19]
	v_mfma_f32_16x16x32_bf16 v[20:23], v[24:27], v[120:123], 0
	v_mfma_f32_16x16x32_bf16 v[108:111], v[28:31], v[116:119], v[108:111]
	v_mfma_f32_16x16x32_bf16 v[20:23], v[28:31], v[124:127], v[20:23]
	s_barrier
	s_add_i32 s74, 0, 0x18000
	s_add_i32 s80, 0, 0x1c000
	v_add_u32_e32 v168, s74, v204
	v_add_u32_e32 v236, s80, v204
	ds_read_b128 v[24:27], v168
	ds_read_b128 v[28:31], v168 offset:1024
	ds_read_b128 v[112:115], v168 offset:2048
	ds_read_b128 v[116:119], v168 offset:3072
	ds_read_b128 v[120:123], v236
	ds_read_b128 v[124:127], v236 offset:1024
	ds_read_b128 v[152:155], v236 offset:2048
	ds_read_b128 v[156:159], v236 offset:3072
	s_add_u32 s76, s52, 0x10100
	s_addc_u32 s77, s53, 0
	s_mov_b32 m0, s51
	v_lshl_add_u64 v[216:217], s[76:77], 0, v[160:161]
	ds_read_b128 v[174:177], v207 offset:32768
	ds_read_b128 v[178:181], v207 offset:33792
	ds_read_b128 v[182:185], v207 offset:34816
	ds_read_b128 v[186:189], v207 offset:35840
	ds_read_b128 v[190:193], v207 offset:36864
	ds_read_b128 v[194:197], v207 offset:37888
	ds_read_b128 v[198:201], v207 offset:38912
	ds_read_b128 v[210:213], v207 offset:39936
	global_load_lds_dwordx4 v[216:217], off
	v_lshl_add_u64 v[216:217], s[76:77], 0, v[164:165]
	s_mov_b32 m0, s60
	s_nop 0
	global_load_lds_dwordx4 v[216:217], off
	s_waitcnt vmcnt(8)
	s_waitcnt lgkmcnt(0)
	s_barrier
	v_mfma_f32_16x16x32_bf16 v[64:67], v[24:27], v[174:177], v[64:67]
	v_mfma_f32_16x16x32_bf16 v[68:71], v[112:115], v[174:177], v[68:71]
	v_mfma_f32_16x16x32_bf16 v[72:75], v[24:27], v[182:185], v[72:75]
	v_mfma_f32_16x16x32_bf16 v[76:79], v[112:115], v[182:185], v[76:79]
	v_mfma_f32_16x16x32_bf16 v[80:83], v[24:27], v[190:193], v[80:83]
	v_mfma_f32_16x16x32_bf16 v[84:87], v[112:115], v[190:193], v[84:87]
	v_mfma_f32_16x16x32_bf16 v[88:91], v[24:27], v[198:201], v[88:91]
	v_mfma_f32_16x16x32_bf16 v[92:95], v[112:115], v[198:201], v[92:95]
	v_mfma_f32_16x16x32_bf16 v[64:67], v[28:31], v[178:181], v[64:67]
	v_mfma_f32_16x16x32_bf16 v[68:71], v[116:119], v[178:181], v[68:71]
	v_mfma_f32_16x16x32_bf16 v[72:75], v[28:31], v[186:189], v[72:75]
	v_mfma_f32_16x16x32_bf16 v[76:79], v[116:119], v[186:189], v[76:79]
	v_mfma_f32_16x16x32_bf16 v[80:83], v[28:31], v[194:197], v[80:83]
	v_mfma_f32_16x16x32_bf16 v[84:87], v[116:119], v[194:197], v[84:87]
	v_mfma_f32_16x16x32_bf16 v[88:91], v[28:31], v[210:213], v[88:91]
	v_mfma_f32_16x16x32_bf16 v[92:95], v[116:119], v[210:213], v[92:95]
	v_mfma_f32_16x16x32_bf16 v[96:99], v[120:123], v[174:177], v[96:99]
	v_mfma_f32_16x16x32_bf16 v[32:35], v[152:155], v[174:177], v[32:35]
	v_mfma_f32_16x16x32_bf16 v[36:39], v[120:123], v[182:185], v[36:39]
	v_mfma_f32_16x16x32_bf16 v[40:43], v[152:155], v[182:185], v[40:43]
	v_mfma_f32_16x16x32_bf16 v[44:47], v[120:123], v[190:193], v[44:47]
	v_mfma_f32_16x16x32_bf16 v[48:51], v[152:155], v[190:193], v[48:51]
	v_mfma_f32_16x16x32_bf16 v[52:55], v[120:123], v[198:201], v[52:55]
	v_mfma_f32_16x16x32_bf16 v[56:59], v[152:155], v[198:201], v[56:59]
	v_mfma_f32_16x16x32_bf16 v[96:99], v[124:127], v[178:181], v[96:99]
	v_mfma_f32_16x16x32_bf16 v[32:35], v[156:159], v[178:181], v[32:35]
	v_mfma_f32_16x16x32_bf16 v[36:39], v[124:127], v[186:189], v[36:39]
	v_mfma_f32_16x16x32_bf16 v[40:43], v[156:159], v[186:189], v[40:43]
	v_mfma_f32_16x16x32_bf16 v[44:47], v[124:127], v[194:197], v[44:47]
	v_mfma_f32_16x16x32_bf16 v[48:51], v[156:159], v[194:197], v[48:51]
	v_mfma_f32_16x16x32_bf16 v[52:55], v[124:127], v[210:213], v[52:55]
	v_mfma_f32_16x16x32_bf16 v[56:59], v[156:159], v[210:213], v[56:59]
	s_barrier
; #define PG8_STAGE(bufoff, gbase, voff) do { _Pragma("unroll") for (int _i = 0; _i < 2; ++_i) \
;         __builtin_amdgcn_global_load_lds((const unsigned*)((const char*)(gbase) + (voff)[_i]), (LAS unsigned*)(lds + (bufoff) + ldsw + _i * 8192), 16, 0, 0); } while (0)
; #define PG8_LDA(dst, b, h) do { _Pragma("unroll") for (int m = 0; m < 4; ++m) _Pragma("unroll") for (int k = 0; k < 2; ++k) dst[m][k] = *(const LAS bf16x8*)(lds + PG8_SA(b, h) + aoff + m * 2048 + k * 1024); } while (0)
; #define PG8_LDB(dst, b, h) do { _Pragma("unroll") for (int n = 0; n < 2; ++n) _Pragma("unroll") for (int k = 0; k < 2; ++k) dst[n][k] = *(const LAS bf16x8*)(lds + PG8_SB(b, h) + boff + n * 2048 + k * 1024); } while (0)
; #define PG8_MMA(ai, bj, At, Bt) do { __builtin_amdgcn_s_setprio(1); _Pragma("unroll") for (int m = 0; m < 4; ++m) _Pragma("unroll") for (int n = 0; n < 2; ++n) _Pragma("unroll") for (int k = 0; k < 2; ++k) \
;         acc[ai][bj][m][n] = __builtin_amdgcn_mfma_f32_16x16x32_bf16(Bt[n][k], At[m][k], acc[ai][bj][m][n], 0, 0, 0); __builtin_amdgcn_s_setprio(0); } while (0)
; #define PG8_WAIT_V(n) asm volatile("s_waitcnt vmcnt(" #n ")" ::: "memory")
; #define PG8_WAIT_L(n) asm volatile("s_waitcnt lgkmcnt(" #n ")" ::: "memory")
; #define PG8_BAR __builtin_amdgcn_s_barrier()
; #define PG8_SCHED __builtin_amdgcn_sched_barrier(0)
; template <class Epi>
; DI void gemm_phase(LAS unsigned char* lds, const int wid, const Gemm g, const Order& S, const Epi& E) {
;     ...
;             PG8_LDB(B0, 0, 0); PG8_LDB(B1, 0, 1); PG8_SCHED; PG8_LDA(At, 0, 0); PG8_STAGE(PG8_SA(1, 1), a1 + hstepA, voffA);
;             PG8_WAIT_V(8); PG8_WAIT_L(0); PG8_BAR; PG8_MMA(0, 0, At, B0); PG8_MMA(0, 1, At, B1); PG8_BAR; PG8_SCHED;
;     ...
;             PG8_WAIT_V(8); PG8_WAIT_L(0); PG8_BAR; PG8_MMA(0, 0, At, B0); PG8_MMA(0, 1, At, B1); PG8_BAR; PG8_SCHED;
;             PG8_LDA(At, 1, 1); PG8_STAGE(PG8_SB(1, 0), b3, voffB); PG8_STAGE(PG8_SB(1, 1), b3 + hstepB, voffB); PG8_STAGE(PG8_SA(1, 0), a3, voffA);
;             PG8_WAIT_V(8); PG8_WAIT_L(0); PG8_BAR; PG8_MMA(1, 0, At, B0); PG8_MMA(1, 1, At, B1); PG8_BAR; PG8_SCHED;
	s_add_i32 s76, s74, s94
	s_add_i32 s74, s76, 0x2000
	v_lshl_add_u64 v[170:171], v[170:171], 0, s[38:39]
	s_mov_b32 m0, s76
	s_add_u32 s78, s54, 0x10180
	ds_read_b128 v[174:177], v207 offset:49152
	ds_read_b128 v[178:181], v207 offset:50176
	ds_read_b128 v[182:185], v207 offset:51200
	ds_read_b128 v[186:189], v207 offset:52224
	ds_read_b128 v[190:193], v207 offset:53248
	ds_read_b128 v[194:197], v207 offset:54272
	ds_read_b128 v[198:201], v207 offset:55296
	ds_read_b128 v[210:213], v207 offset:56320
	global_load_lds_dwordx4 v[170:171], off
	v_lshl_add_u64 v[170:171], v[172:173], 0, s[38:39]
	s_mov_b32 m0, s74
	s_addc_u32 s79, s55, 0
	s_add_i32 s54, s80, s94
	global_load_lds_dwordx4 v[170:171], off
	v_lshl_add_u64 v[170:171], s[78:79], 0, v[162:163]
	s_mov_b32 m0, s54
	s_add_i32 s55, s54, 0x2000
	global_load_lds_dwordx4 v[170:171], off
	v_lshl_add_u64 v[170:171], s[78:79], 0, v[166:167]
	s_mov_b32 m0, s55
	s_nop 0
	global_load_lds_dwordx4 v[170:171], off
	v_lshl_add_u64 v[170:171], v[202:203], 0, s[38:39]
	s_mov_b32 m0, s61
	s_nop 0
	global_load_lds_dwordx4 v[170:171], off
	v_lshl_add_u64 v[170:171], v[214:215], 0, s[38:39]
	s_mov_b32 m0, s62
	s_nop 0
	global_load_lds_dwordx4 v[170:171], off
	s_waitcnt vmcnt(8)
	s_waitcnt lgkmcnt(0)
	s_barrier
	v_mfma_f32_16x16x32_bf16 v[128:131], v[24:27], v[174:177], v[128:131]
	v_mfma_f32_16x16x32_bf16 v[132:135], v[112:115], v[174:177], v[132:135]
	v_mfma_f32_16x16x32_bf16 v[0:3], v[24:27], v[198:201], v[0:3]
	v_mfma_f32_16x16x32_bf16 v[4:7], v[112:115], v[198:201], v[4:7]
	v_mfma_f32_16x16x32_bf16 v[128:131], v[28:31], v[178:181], v[128:131]
	v_mfma_f32_16x16x32_bf16 v[132:135], v[116:119], v[178:181], v[132:135]
	v_mfma_f32_16x16x32_bf16 v[136:139], v[24:27], v[182:185], v[136:139]
	v_mfma_f32_16x16x32_bf16 v[140:143], v[112:115], v[182:185], v[140:143]
	v_mfma_f32_16x16x32_bf16 v[144:147], v[24:27], v[190:193], v[144:147]
	v_mfma_f32_16x16x32_bf16 v[148:151], v[112:115], v[190:193], v[148:151]
	v_mfma_f32_16x16x32_bf16 v[0:3], v[28:31], v[210:213], v[0:3]
	v_mfma_f32_16x16x32_bf16 v[4:7], v[116:119], v[210:213], v[4:7]
	v_mfma_f32_16x16x32_bf16 v[136:139], v[28:31], v[186:189], v[136:139]
	v_mfma_f32_16x16x32_bf16 v[140:143], v[116:119], v[186:189], v[140:143]
	v_mfma_f32_16x16x32_bf16 v[144:147], v[28:31], v[194:197], v[144:147]
	v_mfma_f32_16x16x32_bf16 v[148:151], v[116:119], v[194:197], v[148:151]
	v_mfma_f32_16x16x32_bf16 v[8:11], v[120:123], v[174:177], v[8:11]
	v_mfma_f32_16x16x32_bf16 v[12:15], v[152:155], v[174:177], v[12:15]
	v_mfma_f32_16x16x32_bf16 v[24:27], v[120:123], v[182:185], v[60:63]
	v_mfma_f32_16x16x32_bf16 v[28:31], v[152:155], v[182:185], v[100:103]
	v_mfma_f32_16x16x32_bf16 v[60:63], v[120:123], v[190:193], v[104:107]
	v_mfma_f32_16x16x32_bf16 v[100:103], v[152:155], v[190:193], v[108:111]
	v_mfma_f32_16x16x32_bf16 v[16:19], v[120:123], v[198:201], v[16:19]
	v_mfma_f32_16x16x32_bf16 v[20:23], v[152:155], v[198:201], v[20:23]
	v_mfma_f32_16x16x32_bf16 v[8:11], v[124:127], v[178:181], v[8:11]
	v_mfma_f32_16x16x32_bf16 v[12:15], v[156:159], v[178:181], v[12:15]
	v_mfma_f32_16x16x32_bf16 v[24:27], v[124:127], v[186:189], v[24:27]
	v_mfma_f32_16x16x32_bf16 v[28:31], v[156:159], v[186:189], v[28:31]
	v_mfma_f32_16x16x32_bf16 v[60:63], v[124:127], v[194:197], v[60:63]
	v_mfma_f32_16x16x32_bf16 v[100:103], v[156:159], v[194:197], v[100:103]
	v_mfma_f32_16x16x32_bf16 v[16:19], v[124:127], v[210:213], v[16:19]
	v_mfma_f32_16x16x32_bf16 v[20:23], v[156:159], v[210:213], v[20:23]
	s_barrier
	ds_read_b128 v[104:107], v205
	ds_read_b128 v[108:111], v205 offset:1024
	ds_read_b128 v[112:115], v205 offset:2048
	ds_read_b128 v[116:119], v205 offset:3072
	ds_read_b128 v[120:123], v206
	ds_read_b128 v[124:127], v206 offset:1024
	ds_read_b128 v[152:155], v206 offset:2048
	ds_read_b128 v[156:159], v206 offset:3072
	s_add_u32 s52, s52, 0x10180
	s_addc_u32 s53, s53, 0
	s_mov_b32 m0, s75
	v_lshl_add_u64 v[170:171], s[52:53], 0, v[160:161]
	ds_read_b128 v[174:177], v207
	ds_read_b128 v[178:181], v207 offset:1024
	ds_read_b128 v[182:185], v207 offset:2048
	ds_read_b128 v[186:189], v207 offset:3072
	ds_read_b128 v[190:193], v207 offset:4096
	ds_read_b128 v[194:197], v207 offset:5120
	ds_read_b128 v[198:201], v207 offset:6144
	ds_read_b128 v[210:213], v207 offset:7168
	global_load_lds_dwordx4 v[170:171], off
	v_lshl_add_u64 v[170:171], s[52:53], 0, v[164:165]
	s_mov_b32 m0, s41
	s_nop 0
	global_load_lds_dwordx4 v[170:171], off
	s_waitcnt vmcnt(8)
	s_waitcnt lgkmcnt(0)
	s_barrier
	v_mfma_f32_16x16x32_bf16 v[64:67], v[104:107], v[174:177], v[64:67]
	v_mfma_f32_16x16x32_bf16 v[68:71], v[112:115], v[174:177], v[68:71]
	v_mfma_f32_16x16x32_bf16 v[72:75], v[104:107], v[182:185], v[72:75]
	v_mfma_f32_16x16x32_bf16 v[76:79], v[112:115], v[182:185], v[76:79]
	v_mfma_f32_16x16x32_bf16 v[80:83], v[104:107], v[190:193], v[80:83]
	v_mfma_f32_16x16x32_bf16 v[84:87], v[112:115], v[190:193], v[84:87]
	v_mfma_f32_16x16x32_bf16 v[88:91], v[104:107], v[198:201], v[88:91]
	v_mfma_f32_16x16x32_bf16 v[92:95], v[112:115], v[198:201], v[92:95]
	v_mfma_f32_16x16x32_bf16 v[64:67], v[108:111], v[178:181], v[64:67]
	v_mfma_f32_16x16x32_bf16 v[68:71], v[116:119], v[178:181], v[68:71]
	v_mfma_f32_16x16x32_bf16 v[72:75], v[108:111], v[186:189], v[72:75]
	v_mfma_f32_16x16x32_bf16 v[76:79], v[116:119], v[186:189], v[76:79]
	v_mfma_f32_16x16x32_bf16 v[80:83], v[108:111], v[194:197], v[80:83]
	v_mfma_f32_16x16x32_bf16 v[84:87], v[116:119], v[194:197], v[84:87]
	v_mfma_f32_16x16x32_bf16 v[88:91], v[108:111], v[210:213], v[88:91]
	v_mfma_f32_16x16x32_bf16 v[92:95], v[116:119], v[210:213], v[92:95]
	v_mfma_f32_16x16x32_bf16 v[48:51], v[152:155], v[190:193], v[48:51]
	v_mfma_f32_16x16x32_bf16 v[96:99], v[120:123], v[174:177], v[96:99]
	v_mfma_f32_16x16x32_bf16 v[32:35], v[152:155], v[174:177], v[32:35]
	v_mfma_f32_16x16x32_bf16 v[36:39], v[120:123], v[182:185], v[36:39]
	v_mfma_f32_16x16x32_bf16 v[40:43], v[152:155], v[182:185], v[40:43]
	v_mfma_f32_16x16x32_bf16 v[44:47], v[120:123], v[190:193], v[44:47]
	v_mfma_f32_16x16x32_bf16 v[174:177], v[156:159], v[194:197], v[48:51]
	v_mfma_f32_16x16x32_bf16 v[48:51], v[120:123], v[198:201], v[52:55]
	v_mfma_f32_16x16x32_bf16 v[216:219], v[124:127], v[178:181], v[96:99]
	v_mfma_f32_16x16x32_bf16 v[32:35], v[156:159], v[178:181], v[32:35]
	v_mfma_f32_16x16x32_bf16 v[36:39], v[124:127], v[186:189], v[36:39]
	v_mfma_f32_16x16x32_bf16 v[40:43], v[156:159], v[186:189], v[40:43]
	v_mfma_f32_16x16x32_bf16 v[44:47], v[124:127], v[194:197], v[44:47]
	v_mfma_f32_16x16x32_bf16 v[178:181], v[124:127], v[210:213], v[48:51]
	v_mfma_f32_16x16x32_bf16 v[48:51], v[152:155], v[198:201], v[56:59]
	v_mfma_f32_16x16x32_bf16 v[182:185], v[156:159], v[210:213], v[48:51]
	s_barrier
; #define PG8_STAGE(bufoff, gbase, voff) do { _Pragma("unroll") for (int _i = 0; _i < 2; ++_i) \
;         __builtin_amdgcn_global_load_lds((const unsigned*)((const char*)(gbase) + (voff)[_i]), (LAS unsigned*)(lds + (bufoff) + ldsw + _i * 8192), 16, 0, 0); } while (0)
; #define PG8_LDA(dst, b, h) do { _Pragma("unroll") for (int m = 0; m < 4; ++m) _Pragma("unroll") for (int k = 0; k < 2; ++k) dst[m][k] = *(const LAS bf16x8*)(lds + PG8_SA(b, h) + aoff + m * 2048 + k * 1024); } while (0)
; #define PG8_LDB(dst, b, h) do { _Pragma("unroll") for (int n = 0; n < 2; ++n) _Pragma("unroll") for (int k = 0; k < 2; ++k) dst[n][k] = *(const LAS bf16x8*)(lds + PG8_SB(b, h) + boff + n * 2048 + k * 1024); } while (0)
; #define PG8_MMA(ai, bj, At, Bt) do { __builtin_amdgcn_s_setprio(1); _Pragma("unroll") for (int m = 0; m < 4; ++m) _Pragma("unroll") for (int n = 0; n < 2; ++n) _Pragma("unroll") for (int k = 0; k < 2; ++k) \
;         acc[ai][bj][m][n] = __builtin_amdgcn_mfma_f32_16x16x32_bf16(Bt[n][k], At[m][k], acc[ai][bj][m][n], 0, 0, 0); __builtin_amdgcn_s_setprio(0); } while (0)
; #define PG8_WAIT_V(n) asm volatile("s_waitcnt vmcnt(" #n ")" ::: "memory")
; #define PG8_WAIT_L(n) asm volatile("s_waitcnt lgkmcnt(" #n ")" ::: "memory")
; template <class Epi>
; DI void gemm_phase(LAS unsigned char* lds, const int wid, const Gemm g, const Order& S, const Epi& E) {
;     ...
;             PG8_LDB(B0, 0, 0); PG8_LDB(B1, 0, 1); PG8_SCHED; PG8_LDA(At, 0, 0); PG8_STAGE(PG8_SA(1, 1), a1 + hstepA, voffA);
;             PG8_WAIT_V(8); PG8_WAIT_L(0); PG8_BAR; PG8_MMA(0, 0, At, B0); PG8_MMA(0, 1, At, B1); PG8_BAR; PG8_SCHED;
;             PG8_LDA(At, 0, 1); PG8_STAGE(PG8_SB(0, 0), b2, voffB); PG8_STAGE(PG8_SB(0, 1), b2 + hstepB, voffB); PG8_STAGE(PG8_SA(0, 0), a2, voffA);
;             PG8_WAIT_V(8); PG8_WAIT_L(0); PG8_BAR; PG8_MMA(1, 0, At, B0); PG8_MMA(1, 1, At, B1); PG8_BAR; PG8_SCHED;
;             PG8_LDB(B0, 1, 0); PG8_LDB(B1, 1, 1); PG8_SCHED; PG8_LDA(At, 1, 0); PG8_STAGE(PG8_SA(0, 1), a2 + hstepA, voffA);
;             PG8_WAIT_V(8); PG8_WAIT_L(0); PG8_BAR; PG8_MMA(0, 0, At, B0); PG8_MMA(0, 1, At, B1); PG8_BAR; PG8_SCHED;
;             PG8_LDA(At, 1, 1); PG8_STAGE(PG8_SB(1, 0), b3, voffB); PG8_STAGE(PG8_SB(1, 1), b3 + hstepB, voffB); PG8_STAGE(PG8_SA(1, 0), a3, voffA);
;             PG8_WAIT_V(8); PG8_WAIT_L(0); PG8_BAR; PG8_MMA(1, 0, At, B0); PG8_MMA(1, 1, At, B1); PG8_BAR; PG8_SCHED;
	s_mov_b32 m0, s73
	v_lshl_add_u64 v[202:203], s[56:57], 0, v[162:163]
	s_add_u32 s52, s56, 0x10000
	s_nop 1
	ds_read_b128 v[48:51], v207 offset:16384
	ds_read_b128 v[52:55], v207 offset:17408
	ds_read_b128 v[56:59], v207 offset:18432
	ds_read_b128 v[96:99], v207 offset:19456
	ds_read_b128 v[186:189], v207 offset:20480
	ds_read_b128 v[190:193], v207 offset:21504
	ds_read_b128 v[194:197], v207 offset:22528
	ds_read_b128 v[198:201], v207 offset:23552
	global_load_lds_dwordx4 v[202:203], off
	v_lshl_add_u64 v[214:215], s[56:57], 0, v[166:167]
	s_mov_b32 m0, s43
	s_addc_u32 s53, s57, 0
	global_load_lds_dwordx4 v[214:215], off
	v_lshl_add_u64 v[170:171], s[52:53], 0, v[162:163]
	s_mov_b32 m0, s49
	v_lshl_add_u64 v[252:253], s[58:59], 0, v[160:161]
	global_load_lds_dwordx4 v[170:171], off
	v_lshl_add_u64 v[170:171], s[52:53], 0, v[166:167]
	s_mov_b32 m0, s71
	v_lshl_add_u64 v[208:209], s[58:59], 0, v[164:165]
	global_load_lds_dwordx4 v[170:171], off
	s_mov_b32 m0, s26
	s_nop 0
	global_load_lds_dwordx4 v[252:253], off
	s_mov_b32 m0, s27
	s_nop 0
	global_load_lds_dwordx4 v[208:209], off
	s_waitcnt vmcnt(8)
	s_waitcnt lgkmcnt(0)
	s_barrier
	v_mfma_f32_16x16x32_bf16 v[128:131], v[104:107], v[48:51], v[128:131]
	v_mfma_f32_16x16x32_bf16 v[210:213], v[108:111], v[52:55], v[128:131]
	v_mfma_f32_16x16x32_bf16 v[128:131], v[112:115], v[48:51], v[132:135]
	v_mfma_f32_16x16x32_bf16 v[220:223], v[116:119], v[52:55], v[128:131]
	v_mfma_f32_16x16x32_bf16 v[128:131], v[104:107], v[56:59], v[136:139]
	v_mfma_f32_16x16x32_bf16 v[136:139], v[108:111], v[96:99], v[128:131]
	v_mfma_f32_16x16x32_bf16 v[128:131], v[112:115], v[56:59], v[140:143]
	v_mfma_f32_16x16x32_bf16 v[140:143], v[116:119], v[96:99], v[128:131]
	v_mfma_f32_16x16x32_bf16 v[128:131], v[104:107], v[186:189], v[144:147]
	v_mfma_f32_16x16x32_bf16 v[0:3], v[104:107], v[194:197], v[0:3]
	v_mfma_f32_16x16x32_bf16 v[4:7], v[112:115], v[194:197], v[4:7]
	v_mfma_f32_16x16x32_bf16 v[144:147], v[108:111], v[190:193], v[128:131]
	v_mfma_f32_16x16x32_bf16 v[128:131], v[112:115], v[186:189], v[148:151]
	v_mfma_f32_16x16x32_bf16 v[0:3], v[108:111], v[198:201], v[0:3]
	v_mfma_f32_16x16x32_bf16 v[4:7], v[116:119], v[198:201], v[4:7]
	v_mfma_f32_16x16x32_bf16 v[148:151], v[116:119], v[190:193], v[128:131]
	v_mfma_f32_16x16x32_bf16 v[24:27], v[120:123], v[56:59], v[24:27]
	v_mfma_f32_16x16x32_bf16 v[224:227], v[124:127], v[96:99], v[24:27]
	v_mfma_f32_16x16x32_bf16 v[24:27], v[152:155], v[56:59], v[28:31]
	v_mfma_f32_16x16x32_bf16 v[8:11], v[120:123], v[48:51], v[8:11]
	v_mfma_f32_16x16x32_bf16 v[12:15], v[152:155], v[48:51], v[12:15]
	v_mfma_f32_16x16x32_bf16 v[228:231], v[156:159], v[96:99], v[24:27]
	v_mfma_f32_16x16x32_bf16 v[24:27], v[120:123], v[186:189], v[60:63]
	v_mfma_f32_16x16x32_bf16 v[16:19], v[120:123], v[194:197], v[16:19]
	v_mfma_f32_16x16x32_bf16 v[8:11], v[124:127], v[52:55], v[8:11]
	v_mfma_f32_16x16x32_bf16 v[12:15], v[156:159], v[52:55], v[12:15]
	v_mfma_f32_16x16x32_bf16 v[232:235], v[124:127], v[190:193], v[24:27]
	v_mfma_f32_16x16x32_bf16 v[24:27], v[152:155], v[186:189], v[100:103]
	v_mfma_f32_16x16x32_bf16 v[120:123], v[124:127], v[198:201], v[16:19]
	v_mfma_f32_16x16x32_bf16 v[16:19], v[152:155], v[194:197], v[20:23]
	v_mfma_f32_16x16x32_bf16 v[186:189], v[156:159], v[190:193], v[24:27]
	v_mfma_f32_16x16x32_bf16 v[124:127], v[156:159], v[198:201], v[16:19]
	s_barrier
	s_nop 3
	ds_read_b128 v[16:19], v168
	ds_read_b128 v[20:23], v168 offset:1024
	ds_read_b128 v[24:27], v168 offset:2048
	ds_read_b128 v[28:31], v168 offset:3072
	ds_read_b128 v[152:155], v236
	ds_read_b128 v[156:159], v236 offset:1024
	ds_read_b128 v[190:193], v236 offset:2048
	ds_read_b128 v[194:197], v236 offset:3072
	s_add_u32 s52, s58, 0x10000
	s_addc_u32 s53, s59, 0
	s_mov_b32 m0, s51
	v_lshl_add_u64 v[56:57], s[52:53], 0, v[160:161]
	ds_read_b128 v[48:51], v207 offset:32768
	ds_read_b128 v[52:55], v207 offset:33792
	ds_read_b128 v[198:201], v207 offset:34816
	ds_read_b128 v[236:239], v207 offset:35840
	ds_read_b128 v[240:243], v207 offset:36864
	ds_read_b128 v[244:247], v207 offset:37888
	ds_read_b128 v[248:251], v207 offset:38912
	ds_read_b128 v[170:173], v207 offset:39936
	global_load_lds_dwordx4 v[56:57], off
	v_lshl_add_u64 v[56:57], s[52:53], 0, v[164:165]
	s_mov_b32 m0, s60
	s_nop 0
	global_load_lds_dwordx4 v[56:57], off
	s_waitcnt vmcnt(8)
	s_waitcnt lgkmcnt(0)
	s_barrier
; #define PG8_STAGE(bufoff, gbase, voff) do { _Pragma("unroll") for (int _i = 0; _i < 2; ++_i) \
;         __builtin_amdgcn_global_load_lds((const unsigned*)((const char*)(gbase) + (voff)[_i]), (LAS unsigned*)(lds + (bufoff) + ldsw + _i * 8192), 16, 0, 0); } while (0)
; #define PG8_LDA(dst, b, h) do { _Pragma("unroll") for (int m = 0; m < 4; ++m) _Pragma("unroll") for (int k = 0; k < 2; ++k) dst[m][k] = *(const LAS bf16x8*)(lds + PG8_SA(b, h) + aoff + m * 2048 + k * 1024); } while (0)
; #define PG8_LDB(dst, b, h) do { _Pragma("unroll") for (int n = 0; n < 2; ++n) _Pragma("unroll") for (int k = 0; k < 2; ++k) dst[n][k] = *(const LAS bf16x8*)(lds + PG8_SB(b, h) + boff + n * 2048 + k * 1024); } while (0)
; #define PG8_MMA(ai, bj, At, Bt) do { __builtin_amdgcn_s_setprio(1); _Pragma("unroll") for (int m = 0; m < 4; ++m) _Pragma("unroll") for (int n = 0; n < 2; ++n) _Pragma("unroll") for (int k = 0; k < 2; ++k) \
;         acc[ai][bj][m][n] = __builtin_amdgcn_mfma_f32_16x16x32_bf16(Bt[n][k], At[m][k], acc[ai][bj][m][n], 0, 0, 0); __builtin_amdgcn_s_setprio(0); } while (0)
; #define PG8_WAIT_V(n) asm volatile("s_waitcnt vmcnt(" #n ")" ::: "memory")
; template <class Epi>
; DI void gemm_phase(LAS unsigned char* lds, const int wid, const Gemm g, const Order& S, const Epi& E) {
;     ...
;             PG8_LDB(B0, 0, 0); PG8_LDB(B1, 0, 1); PG8_SCHED; PG8_LDA(At, 0, 0); PG8_STAGE(PG8_SA(1, 1), a1 + hstepA, voffA);
;             PG8_WAIT_V(8); PG8_WAIT_L(0); PG8_BAR; PG8_MMA(0, 0, At, B0); PG8_MMA(0, 1, At, B1); PG8_BAR; PG8_SCHED;
;             PG8_LDA(At, 0, 1); PG8_STAGE(PG8_SB(0, 0), b2, voffB); PG8_STAGE(PG8_SB(0, 1), b2 + hstepB, voffB); PG8_STAGE(PG8_SA(0, 0), a2, voffA);
;             PG8_WAIT_V(8); PG8_WAIT_L(0); PG8_BAR; PG8_MMA(1, 0, At, B0); PG8_MMA(1, 1, At, B1); PG8_BAR; PG8_SCHED;
;             PG8_LDB(B0, 1, 0); PG8_LDB(B1, 1, 1); PG8_SCHED; PG8_LDA(At, 1, 0); PG8_STAGE(PG8_SA(0, 1), a2 + hstepA, voffA);
;             PG8_WAIT_V(8); PG8_WAIT_L(0); PG8_BAR; PG8_MMA(0, 0, At, B0); PG8_MMA(0, 1, At, B1); PG8_BAR; PG8_SCHED;
;             PG8_LDA(At, 1, 1); PG8_STAGE(PG8_SB(1, 0), b3, voffB); PG8_STAGE(PG8_SB(1, 1), b3 + hstepB, voffB); PG8_STAGE(PG8_SA(1, 0), a3, voffA);
;             PG8_WAIT_V(8); PG8_WAIT_L(0); PG8_BAR; PG8_MMA(1, 0, At, B0); PG8_MMA(1, 1, At, B1); PG8_BAR; PG8_SCHED;
;         }
;         if (wr == 0) PG8_BAR;
	v_mfma_f32_16x16x32_bf16 v[56:59], v[16:19], v[48:51], v[64:67]
	v_mfma_f32_16x16x32_bf16 v[132:135], v[20:23], v[52:55], v[56:59]
	v_mfma_f32_16x16x32_bf16 v[56:59], v[24:27], v[48:51], v[68:71]
	v_mfma_f32_16x16x32_bf16 v[128:131], v[28:31], v[52:55], v[56:59]
	v_mfma_f32_16x16x32_bf16 v[56:59], v[16:19], v[198:201], v[72:75]
	v_mfma_f32_16x16x32_bf16 v[116:119], v[20:23], v[236:239], v[56:59]
	v_mfma_f32_16x16x32_bf16 v[56:59], v[24:27], v[198:201], v[76:79]
	v_mfma_f32_16x16x32_bf16 v[112:115], v[28:31], v[236:239], v[56:59]
	v_mfma_f32_16x16x32_bf16 v[56:59], v[16:19], v[240:243], v[80:83]
	v_mfma_f32_16x16x32_bf16 v[108:111], v[20:23], v[244:247], v[56:59]
	v_mfma_f32_16x16x32_bf16 v[56:59], v[24:27], v[240:243], v[84:87]
	v_mfma_f32_16x16x32_bf16 v[104:107], v[28:31], v[244:247], v[56:59]
	v_mfma_f32_16x16x32_bf16 v[56:59], v[16:19], v[248:251], v[88:91]
	v_mfma_f32_16x16x32_bf16 v[100:103], v[20:23], v[170:173], v[56:59]
	v_mfma_f32_16x16x32_bf16 v[56:59], v[24:27], v[248:251], v[92:95]
	v_mfma_f32_16x16x32_bf16 v[96:99], v[28:31], v[170:173], v[56:59]
	v_mfma_f32_16x16x32_bf16 v[56:59], v[152:155], v[48:51], v[216:219]
	v_mfma_f32_16x16x32_bf16 v[32:35], v[190:193], v[48:51], v[32:35]
	v_mfma_f32_16x16x32_bf16 v[60:63], v[156:159], v[52:55], v[56:59]
	v_mfma_f32_16x16x32_bf16 v[56:59], v[194:197], v[52:55], v[32:35]
	v_mfma_f32_16x16x32_bf16 v[32:35], v[152:155], v[198:201], v[36:39]
	v_mfma_f32_16x16x32_bf16 v[52:55], v[156:159], v[236:239], v[32:35]
	v_mfma_f32_16x16x32_bf16 v[32:35], v[190:193], v[198:201], v[40:43]
	v_mfma_f32_16x16x32_bf16 v[48:51], v[194:197], v[236:239], v[32:35]
	v_mfma_f32_16x16x32_bf16 v[32:35], v[152:155], v[240:243], v[44:47]
	v_mfma_f32_16x16x32_bf16 v[44:47], v[156:159], v[244:247], v[32:35]
	v_mfma_f32_16x16x32_bf16 v[32:35], v[190:193], v[240:243], v[174:177]
	v_mfma_f32_16x16x32_bf16 v[40:43], v[194:197], v[244:247], v[32:35]
	v_mfma_f32_16x16x32_bf16 v[32:35], v[152:155], v[248:251], v[178:181]
	v_mfma_f32_16x16x32_bf16 v[36:39], v[156:159], v[170:173], v[32:35]
	v_mfma_f32_16x16x32_bf16 v[32:35], v[190:193], v[248:251], v[182:185]
	v_mfma_f32_16x16x32_bf16 v[32:35], v[194:197], v[170:173], v[32:35]
	s_barrier
	s_mov_b32 m0, s76
	v_lshl_add_u64 v[64:65], v[202:203], 0, s[28:29]
	s_add_u32 s52, s56, 0x10080
	ds_read_b128 v[170:173], v207 offset:49152
	ds_read_b128 v[174:177], v207 offset:50176
	ds_read_b128 v[178:181], v207 offset:51200
	ds_read_b128 v[182:185], v207 offset:52224
	ds_read_b128 v[198:201], v207 offset:53248
	ds_read_b128 v[216:219], v207 offset:54272
	ds_read_b128 v[236:239], v207 offset:55296
	ds_read_b128 v[240:243], v207 offset:56320
	global_load_lds_dwordx4 v[64:65], off
	v_lshl_add_u64 v[64:65], v[214:215], 0, s[28:29]
	s_mov_b32 m0, s74
	s_addc_u32 s53, s57, 0
	global_load_lds_dwordx4 v[64:65], off
	v_lshl_add_u64 v[64:65], s[52:53], 0, v[162:163]
	s_mov_b32 m0, s54
	s_nop 0
	global_load_lds_dwordx4 v[64:65], off
	v_lshl_add_u64 v[64:65], s[52:53], 0, v[166:167]
	s_mov_b32 m0, s55
	s_nop 0
	global_load_lds_dwordx4 v[64:65], off
	v_lshl_add_u64 v[64:65], v[252:253], 0, s[28:29]
	s_mov_b32 m0, s61
	s_nop 0
	global_load_lds_dwordx4 v[64:65], off
	v_lshl_add_u64 v[64:65], v[208:209], 0, s[28:29]
	s_mov_b32 m0, s62
	s_nop 0
	global_load_lds_dwordx4 v[64:65], off
	s_waitcnt vmcnt(8)
	s_waitcnt lgkmcnt(0)
	s_barrier
	v_mfma_f32_16x16x32_bf16 v[64:67], v[16:19], v[170:173], v[210:213]
	v_mfma_f32_16x16x32_bf16 v[92:95], v[20:23], v[174:177], v[64:67]
	v_mfma_f32_16x16x32_bf16 v[64:67], v[24:27], v[170:173], v[220:223]
	v_mfma_f32_16x16x32_bf16 v[88:91], v[28:31], v[174:177], v[64:67]
	v_mfma_f32_16x16x32_bf16 v[64:67], v[16:19], v[178:181], v[136:139]
	v_mfma_f32_16x16x32_bf16 v[84:87], v[20:23], v[182:185], v[64:67]
	v_mfma_f32_16x16x32_bf16 v[64:67], v[24:27], v[178:181], v[140:143]
	v_mfma_f32_16x16x32_bf16 v[80:83], v[28:31], v[182:185], v[64:67]
	v_mfma_f32_16x16x32_bf16 v[64:67], v[16:19], v[198:201], v[144:147]
	v_mfma_f32_16x16x32_bf16 v[0:3], v[16:19], v[236:239], v[0:3]
	v_mfma_f32_16x16x32_bf16 v[76:79], v[20:23], v[216:219], v[64:67]
	v_mfma_f32_16x16x32_bf16 v[64:67], v[24:27], v[198:201], v[148:151]
	v_mfma_f32_16x16x32_bf16 v[68:71], v[20:23], v[240:243], v[0:3]
	v_mfma_f32_16x16x32_bf16 v[0:3], v[24:27], v[236:239], v[4:7]
	v_mfma_f32_16x16x32_bf16 v[72:75], v[28:31], v[216:219], v[64:67]
	v_mfma_f32_16x16x32_bf16 v[64:67], v[28:31], v[240:243], v[0:3]
	v_mfma_f32_16x16x32_bf16 v[0:3], v[152:155], v[170:173], v[8:11]
	v_mfma_f32_16x16x32_bf16 v[28:31], v[156:159], v[174:177], v[0:3]
	v_mfma_f32_16x16x32_bf16 v[0:3], v[190:193], v[170:173], v[12:15]
	v_mfma_f32_16x16x32_bf16 v[24:27], v[194:197], v[174:177], v[0:3]
	v_mfma_f32_16x16x32_bf16 v[0:3], v[152:155], v[178:181], v[224:227]
	v_mfma_f32_16x16x32_bf16 v[20:23], v[156:159], v[182:185], v[0:3]
	v_mfma_f32_16x16x32_bf16 v[0:3], v[190:193], v[178:181], v[228:231]
	v_mfma_f32_16x16x32_bf16 v[16:19], v[194:197], v[182:185], v[0:3]
	v_mfma_f32_16x16x32_bf16 v[0:3], v[152:155], v[198:201], v[232:235]
	v_mfma_f32_16x16x32_bf16 v[12:15], v[156:159], v[216:219], v[0:3]
	v_mfma_f32_16x16x32_bf16 v[0:3], v[190:193], v[198:201], v[186:189]
	v_mfma_f32_16x16x32_bf16 v[8:11], v[194:197], v[216:219], v[0:3]
	v_mfma_f32_16x16x32_bf16 v[0:3], v[152:155], v[236:239], v[120:123]
	v_mfma_f32_16x16x32_bf16 v[4:7], v[156:159], v[240:243], v[0:3]
	v_mfma_f32_16x16x32_bf16 v[0:3], v[190:193], v[236:239], v[124:127]
	v_mfma_f32_16x16x32_bf16 v[0:3], v[194:197], v[240:243], v[0:3]
	s_barrier
	s_andn2_b64 vcc, exec, s[30:31]
	s_cbranch_vccnz .LBB0_633
	s_barrier

; #define PG8_STAGE(bufoff, gbase, voff) do { _Pragma("unroll") for (int _i = 0; _i < 2; ++_i) \
;         __builtin_amdgcn_global_load_lds((const unsigned*)((const char*)(gbase) + (voff)[_i]), (LAS unsigned*)(lds + (bufoff) + ldsw + _i * 8192), 16, 0, 0); } while (0)
; #define PG8_LDA(dst, b, h) do { _Pragma("unroll") for (int m = 0; m < 4; ++m) _Pragma("unroll") for (int k = 0; k < 2; ++k) dst[m][k] = *(const LAS bf16x8*)(lds + PG8_SA(b, h) + aoff + m * 2048 + k * 1024); } while (0)
; #define PG8_LDB(dst, b, h) do { _Pragma("unroll") for (int n = 0; n < 2; ++n) _Pragma("unroll") for (int k = 0; k < 2; ++k) dst[n][k] = *(const LAS bf16x8*)(lds + PG8_SB(b, h) + boff + n * 2048 + k * 1024); } while (0)
; #define PG8_MMA(ai, bj, At, Bt) do { __builtin_amdgcn_s_setprio(1); _Pragma("unroll") for (int m = 0; m < 4; ++m) _Pragma("unroll") for (int n = 0; n < 2; ++n) _Pragma("unroll") for (int k = 0; k < 2; ++k) \
;         acc[ai][bj][m][n] = __builtin_amdgcn_mfma_f32_16x16x32_bf16(Bt[n][k], At[m][k], acc[ai][bj][m][n], 0, 0, 0); __builtin_amdgcn_s_setprio(0); } while (0)
; template <class Epi>
; DI void gemm_phase(LAS unsigned char* lds, const int wid, const Gemm g, const Order& S, const Epi& E) {
;     ...
;         const bool has_next = S.next(ui + 1, nxt);
;         const char* nA = has_next ? (const char*)(g.A + (size_t)nxt.g * g.gsA + (size_t)nxt.pm * BM * g.lda) : cA;
;         const char* nB = has_next ? (const char*)(g.Bt + (size_t)nxt.g * g.gsB + (size_t)nxt.pn * BM * g.ldb) : cB;
;         for (int t = 0; t < nt; t += 2) {
;             const bool last = (t == nt - 2);
;             const char* a1 = cA + (size_t)(t + 1) * kstep;
;             const char* a2 = last ? nA : cA + (size_t)(t + 2) * kstep; const char* b2 = last ? nB : cB + (size_t)(t + 2) * kstep;
;             const char* a3 = a2 + kstep; const char* b3 = b2 + kstep;
;             PG8_LDB(B0, 0, 0); PG8_LDB(B1, 0, 1); PG8_SCHED; PG8_LDA(At, 0, 0); PG8_STAGE(PG8_SA(1, 1), a1 + hstepA, voffA);
;             PG8_WAIT_V(8); PG8_WAIT_L(0); PG8_BAR; PG8_MMA(0, 0, At, B0); PG8_MMA(0, 1, At, B1); PG8_BAR; PG8_SCHED;
;             PG8_LDA(At, 0, 1); PG8_STAGE(PG8_SB(0, 0), b2, voffB); PG8_STAGE(PG8_SB(0, 1), b2 + hstepB, voffB); PG8_STAGE(PG8_SA(0, 0), a2, voffA);
;             PG8_WAIT_V(8); PG8_WAIT_L(0); PG8_BAR; PG8_MMA(1, 0, At, B0); PG8_MMA(1, 1, At, B1); PG8_BAR; PG8_SCHED;
.LBB0_750:
	s_ashr_i32 s37, s36, 31
	s_lshl_b64 s[40:41], s[36:37], 16
	s_add_u32 s40, s6, s40
	s_addc_u32 s41, s7, s41
	s_and_b64 s[42:43], s[8:9], exec
	s_cselect_b32 s51, s41, s49
	s_cselect_b32 s50, s40, s48
	s_ashr_i32 s39, s38, 31
	s_lshl_b64 s[42:43], s[38:39], 16
	s_add_u32 s42, s21, s42
	s_addc_u32 s43, s25, s43
	s_add_u32 s64, s48, 0x8080
	ds_read_b128 v[0:3], v152
	ds_read_b128 v[4:7], v152 offset:1024
	ds_read_b128 v[8:11], v152 offset:2048
	ds_read_b128 v[12:15], v152 offset:3072
	ds_read_b128 v[16:19], v153
	ds_read_b128 v[20:23], v153 offset:1024
	ds_read_b128 v[24:27], v153 offset:2048
	ds_read_b128 v[28:31], v153 offset:3072
	s_addc_u32 s65, s49, 0
	s_add_u32 s48, s50, 0x8000
	s_addc_u32 s49, s51, 0
	s_and_b64 s[66:67], s[8:9], exec
	s_cselect_b32 s46, s42, s46
	s_cselect_b32 s47, s43, s47
	s_add_u32 s66, s46, 0x8000
	s_addc_u32 s67, s47, 0
	s_mov_b32 m0, s57
	v_lshl_add_u64 v[64:65], s[64:65], 0, v[128:129]
	s_waitcnt vmcnt(0)
	ds_read_b128 v[32:35], v154
	ds_read_b128 v[36:39], v154 offset:1024
	ds_read_b128 v[40:43], v154 offset:2048
	ds_read_b128 v[44:47], v154 offset:3072
	ds_read_b128 v[48:51], v154 offset:4096
	ds_read_b128 v[52:55], v154 offset:5120
	ds_read_b128 v[56:59], v154 offset:6144
	ds_read_b128 v[60:63], v154 offset:7168
	global_load_lds_dwordx4 v[64:65], off
	v_lshl_add_u64 v[64:65], s[64:65], 0, v[132:133]
	s_mov_b32 m0, s58
	s_nop 0
	global_load_lds_dwordx4 v[64:65], off
	s_waitcnt vmcnt(8)
	s_waitcnt lgkmcnt(0)
	s_barrier
	v_mfma_f32_16x16x32_bf16 v[64:67], v[0:3], v[32:35], 0
	v_mfma_f32_16x16x32_bf16 v[68:71], v[8:11], v[32:35], 0
	v_mfma_f32_16x16x32_bf16 v[72:75], v[0:3], v[40:43], 0
	v_mfma_f32_16x16x32_bf16 v[76:79], v[8:11], v[40:43], 0
	v_mfma_f32_16x16x32_bf16 v[80:83], v[0:3], v[48:51], 0
	v_mfma_f32_16x16x32_bf16 v[84:87], v[8:11], v[48:51], 0
	v_mfma_f32_16x16x32_bf16 v[88:91], v[0:3], v[56:59], 0
	v_mfma_f32_16x16x32_bf16 v[92:95], v[8:11], v[56:59], 0
	v_mfma_f32_16x16x32_bf16 v[64:67], v[4:7], v[36:39], v[64:67]
	v_mfma_f32_16x16x32_bf16 v[68:71], v[12:15], v[36:39], v[68:71]
	v_mfma_f32_16x16x32_bf16 v[72:75], v[4:7], v[44:47], v[72:75]
	v_mfma_f32_16x16x32_bf16 v[76:79], v[12:15], v[44:47], v[76:79]
	v_mfma_f32_16x16x32_bf16 v[80:83], v[4:7], v[52:55], v[80:83]
	v_mfma_f32_16x16x32_bf16 v[84:87], v[12:15], v[52:55], v[84:87]
	v_mfma_f32_16x16x32_bf16 v[88:91], v[4:7], v[60:63], v[88:91]
	v_mfma_f32_16x16x32_bf16 v[104:107], v[12:15], v[60:63], v[92:95]
	v_mfma_f32_16x16x32_bf16 v[92:95], v[16:19], v[32:35], 0
	v_mfma_f32_16x16x32_bf16 v[32:35], v[24:27], v[32:35], 0
	v_mfma_f32_16x16x32_bf16 v[108:111], v[20:23], v[36:39], v[92:95]
	v_mfma_f32_16x16x32_bf16 v[32:35], v[28:31], v[36:39], v[32:35]
	v_mfma_f32_16x16x32_bf16 v[36:39], v[16:19], v[40:43], 0
	v_mfma_f32_16x16x32_bf16 v[40:43], v[24:27], v[40:43], 0
	v_mfma_f32_16x16x32_bf16 v[36:39], v[20:23], v[44:47], v[36:39]
	v_mfma_f32_16x16x32_bf16 v[40:43], v[28:31], v[44:47], v[40:43]
	v_mfma_f32_16x16x32_bf16 v[44:47], v[16:19], v[48:51], 0
	v_mfma_f32_16x16x32_bf16 v[48:51], v[24:27], v[48:51], 0
	v_mfma_f32_16x16x32_bf16 v[44:47], v[20:23], v[52:55], v[44:47]
	v_mfma_f32_16x16x32_bf16 v[48:51], v[28:31], v[52:55], v[48:51]
	v_mfma_f32_16x16x32_bf16 v[52:55], v[16:19], v[56:59], 0
	v_mfma_f32_16x16x32_bf16 v[140:143], v[20:23], v[60:63], v[52:55]
	v_mfma_f32_16x16x32_bf16 v[52:55], v[24:27], v[56:59], 0
	v_mfma_f32_16x16x32_bf16 v[144:147], v[28:31], v[60:63], v[52:55]
	s_barrier
	s_mov_b32 m0, s59
	v_lshl_add_u64 v[148:149], s[46:47], 0, v[130:131]
	s_nop 2
	ds_read_b128 v[52:55], v154 offset:16384
	ds_read_b128 v[56:59], v154 offset:17408
	ds_read_b128 v[60:63], v154 offset:18432
	ds_read_b128 v[92:95], v154 offset:19456
	ds_read_b128 v[96:99], v154 offset:20480
	ds_read_b128 v[100:103], v154 offset:21504
	ds_read_b128 v[112:115], v154 offset:22528
	ds_read_b128 v[116:119], v154 offset:23552
	global_load_lds_dwordx4 v[148:149], off
	v_lshl_add_u64 v[212:213], s[46:47], 0, v[134:135]
	s_mov_b32 m0, s60
	v_lshl_add_u64 v[120:121], s[66:67], 0, v[130:131]
	global_load_lds_dwordx4 v[212:213], off
	s_mov_b32 m0, s61
	v_lshl_add_u64 v[214:215], s[50:51], 0, v[128:129]
	global_load_lds_dwordx4 v[120:121], off
	v_lshl_add_u64 v[120:121], s[66:67], 0, v[134:135]
	s_mov_b32 m0, s62
	v_lshl_add_u64 v[252:253], s[50:51], 0, v[132:133]
	global_load_lds_dwordx4 v[120:121], off
	s_mov_b32 m0, s26
	s_nop 0
	global_load_lds_dwordx4 v[214:215], off
	s_mov_b32 m0, s27
	s_nop 0
	global_load_lds_dwordx4 v[252:253], off
	s_waitcnt vmcnt(8)
	s_waitcnt lgkmcnt(0)
	s_barrier
	v_mfma_f32_16x16x32_bf16 v[120:123], v[0:3], v[52:55], 0
	v_mfma_f32_16x16x32_bf16 v[156:159], v[4:7], v[56:59], v[120:123]
	v_mfma_f32_16x16x32_bf16 v[120:123], v[8:11], v[52:55], 0
	v_mfma_f32_16x16x32_bf16 v[160:163], v[12:15], v[56:59], v[120:123]
	v_mfma_f32_16x16x32_bf16 v[120:123], v[0:3], v[60:63], 0
	v_mfma_f32_16x16x32_bf16 v[164:167], v[4:7], v[92:95], v[120:123]
	v_mfma_f32_16x16x32_bf16 v[120:123], v[8:11], v[60:63], 0
	v_mfma_f32_16x16x32_bf16 v[168:171], v[12:15], v[92:95], v[120:123]
	v_mfma_f32_16x16x32_bf16 v[120:123], v[0:3], v[96:99], 0
	v_mfma_f32_16x16x32_bf16 v[0:3], v[0:3], v[112:115], 0
	v_mfma_f32_16x16x32_bf16 v[172:175], v[4:7], v[100:103], v[120:123]
	v_mfma_f32_16x16x32_bf16 v[0:3], v[4:7], v[116:119], v[0:3]
	v_mfma_f32_16x16x32_bf16 v[4:7], v[8:11], v[112:115], 0
	v_mfma_f32_16x16x32_bf16 v[120:123], v[8:11], v[96:99], 0
	v_mfma_f32_16x16x32_bf16 v[4:7], v[12:15], v[116:119], v[4:7]
	v_mfma_f32_16x16x32_bf16 v[176:179], v[12:15], v[100:103], v[120:123]
	v_mfma_f32_16x16x32_bf16 v[12:15], v[24:27], v[52:55], 0
	v_mfma_f32_16x16x32_bf16 v[180:183], v[28:31], v[56:59], v[12:15]
	v_mfma_f32_16x16x32_bf16 v[12:15], v[16:19], v[60:63], 0
	v_mfma_f32_16x16x32_bf16 v[184:187], v[20:23], v[92:95], v[12:15]
	v_mfma_f32_16x16x32_bf16 v[12:15], v[24:27], v[60:63], 0
	v_mfma_f32_16x16x32_bf16 v[188:191], v[28:31], v[92:95], v[12:15]
	v_mfma_f32_16x16x32_bf16 v[12:15], v[16:19], v[96:99], 0
	v_mfma_f32_16x16x32_bf16 v[192:195], v[20:23], v[100:103], v[12:15]
	v_mfma_f32_16x16x32_bf16 v[12:15], v[24:27], v[96:99], 0
	v_mfma_f32_16x16x32_bf16 v[8:11], v[16:19], v[52:55], 0
	v_mfma_f32_16x16x32_bf16 v[196:199], v[28:31], v[100:103], v[12:15]
	v_mfma_f32_16x16x32_bf16 v[12:15], v[16:19], v[112:115], 0
	v_mfma_f32_16x16x32_bf16 v[8:11], v[20:23], v[56:59], v[8:11]
	v_mfma_f32_16x16x32_bf16 v[200:203], v[20:23], v[116:119], v[12:15]
	v_mfma_f32_16x16x32_bf16 v[12:15], v[24:27], v[112:115], 0
	v_mfma_f32_16x16x32_bf16 v[204:207], v[28:31], v[116:119], v[12:15]
	s_barrier
; #define PG8_STAGE(bufoff, gbase, voff) do { _Pragma("unroll") for (int _i = 0; _i < 2; ++_i) \
;         __builtin_amdgcn_global_load_lds((const unsigned*)((const char*)(gbase) + (voff)[_i]), (LAS unsigned*)(lds + (bufoff) + ldsw + _i * 8192), 16, 0, 0); } while (0)
; #define PG8_LDA(dst, b, h) do { _Pragma("unroll") for (int m = 0; m < 4; ++m) _Pragma("unroll") for (int k = 0; k < 2; ++k) dst[m][k] = *(const LAS bf16x8*)(lds + PG8_SA(b, h) + aoff + m * 2048 + k * 1024); } while (0)
; #define PG8_LDB(dst, b, h) do { _Pragma("unroll") for (int n = 0; n < 2; ++n) _Pragma("unroll") for (int k = 0; k < 2; ++k) dst[n][k] = *(const LAS bf16x8*)(lds + PG8_SB(b, h) + boff + n * 2048 + k * 1024); } while (0)
; #define PG8_MMA(ai, bj, At, Bt) do { __builtin_amdgcn_s_setprio(1); _Pragma("unroll") for (int m = 0; m < 4; ++m) _Pragma("unroll") for (int n = 0; n < 2; ++n) _Pragma("unroll") for (int k = 0; k < 2; ++k) \
;         acc[ai][bj][m][n] = __builtin_amdgcn_mfma_f32_16x16x32_bf16(Bt[n][k], At[m][k], acc[ai][bj][m][n], 0, 0, 0); __builtin_amdgcn_s_setprio(0); } while (0)
; #define PG8_WAIT_V(n) asm volatile("s_waitcnt vmcnt(" #n ")" ::: "memory")
; #define PG8_WAIT_L(n) asm volatile("s_waitcnt lgkmcnt(" #n ")" ::: "memory")
; #define PG8_BAR __builtin_amdgcn_s_barrier()
; #define PG8_SCHED __builtin_amdgcn_sched_barrier(0)
; template <class Epi>
; DI void gemm_phase(LAS unsigned char* lds, const int wid, const Gemm g, const Order& S, const Epi& E) {
;     ...
;             PG8_LDB(B0, 1, 0); PG8_LDB(B1, 1, 1); PG8_SCHED; PG8_LDA(At, 1, 0); PG8_STAGE(PG8_SA(0, 1), a2 + hstepA, voffA);
;             PG8_WAIT_V(8); PG8_WAIT_L(0); PG8_BAR; PG8_MMA(0, 0, At, B0); PG8_MMA(0, 1, At, B1); PG8_BAR; PG8_SCHED;
;             PG8_LDA(At, 1, 1); PG8_STAGE(PG8_SB(1, 0), b3, voffB); PG8_STAGE(PG8_SB(1, 1), b3 + hstepB, voffB); PG8_STAGE(PG8_SA(1, 0), a3, voffA);
;             PG8_WAIT_V(8); PG8_WAIT_L(0); PG8_BAR; PG8_MMA(1, 0, At, B0); PG8_MMA(1, 1, At, B1); PG8_BAR; PG8_SCHED;
;         }
;         if (wr == 0) PG8_BAR;
	s_add_i32 s37, 0, 0x18000
	v_add_u32_e32 v20, s37, v151
	s_add_i32 s39, 0, 0x1c000
	s_nop 1
	ds_read_b128 v[12:15], v20
	ds_read_b128 v[16:19], v20 offset:1024
	ds_read_b128 v[24:27], v20 offset:2048
	ds_read_b128 v[208:211], v20 offset:3072
	v_add_u32_e32 v20, s39, v151
	ds_read_b128 v[216:219], v20
	ds_read_b128 v[220:223], v20 offset:1024
	ds_read_b128 v[224:227], v20 offset:2048
	ds_read_b128 v[228:231], v20 offset:3072
	s_mov_b32 m0, s45
	v_lshl_add_u64 v[52:53], s[48:49], 0, v[128:129]
	ds_read_b128 v[20:23], v154 offset:32768
	ds_read_b128 v[28:31], v154 offset:33792
	ds_read_b128 v[56:59], v154 offset:34816
	ds_read_b128 v[232:235], v154 offset:35840
	ds_read_b128 v[236:239], v154 offset:36864
	ds_read_b128 v[240:243], v154 offset:37888
	ds_read_b128 v[244:247], v154 offset:38912
	ds_read_b128 v[248:251], v154 offset:39936
	global_load_lds_dwordx4 v[52:53], off
	v_lshl_add_u64 v[52:53], s[48:49], 0, v[132:133]
	s_mov_b32 m0, s52
	s_nop 0
	global_load_lds_dwordx4 v[52:53], off
	s_waitcnt vmcnt(8)
	s_waitcnt lgkmcnt(0)
	s_barrier
	v_mfma_f32_16x16x32_bf16 v[52:55], v[12:15], v[20:23], v[64:67]
	v_mfma_f32_16x16x32_bf16 v[112:115], v[16:19], v[28:31], v[52:55]
	v_mfma_f32_16x16x32_bf16 v[52:55], v[24:27], v[20:23], v[68:71]
	v_mfma_f32_16x16x32_bf16 v[116:119], v[208:211], v[28:31], v[52:55]
	v_mfma_f32_16x16x32_bf16 v[52:55], v[12:15], v[56:59], v[72:75]
	v_mfma_f32_16x16x32_bf16 v[96:99], v[16:19], v[232:235], v[52:55]
	v_mfma_f32_16x16x32_bf16 v[52:55], v[24:27], v[56:59], v[76:79]
	v_mfma_f32_16x16x32_bf16 v[100:103], v[208:211], v[232:235], v[52:55]
	v_mfma_f32_16x16x32_bf16 v[52:55], v[12:15], v[236:239], v[80:83]
	v_mfma_f32_16x16x32_bf16 v[92:95], v[16:19], v[240:243], v[52:55]
	v_mfma_f32_16x16x32_bf16 v[52:55], v[24:27], v[236:239], v[84:87]
	v_mfma_f32_16x16x32_bf16 v[84:87], v[208:211], v[240:243], v[52:55]
	v_mfma_f32_16x16x32_bf16 v[52:55], v[12:15], v[244:247], v[88:91]
	v_mfma_f32_16x16x32_bf16 v[60:63], v[16:19], v[248:251], v[52:55]
	v_mfma_f32_16x16x32_bf16 v[52:55], v[24:27], v[244:247], v[104:107]
	v_mfma_f32_16x16x32_bf16 v[52:55], v[208:211], v[248:251], v[52:55]
	v_mfma_f32_16x16x32_bf16 v[64:67], v[216:219], v[20:23], v[108:111]
	v_mfma_f32_16x16x32_bf16 v[20:23], v[224:227], v[20:23], v[32:35]
	v_mfma_f32_16x16x32_bf16 v[124:127], v[228:231], v[28:31], v[20:23]
	v_mfma_f32_16x16x32_bf16 v[20:23], v[216:219], v[56:59], v[36:39]
	v_mfma_f32_16x16x32_bf16 v[108:111], v[220:223], v[232:235], v[20:23]
	v_mfma_f32_16x16x32_bf16 v[20:23], v[224:227], v[56:59], v[40:43]
	v_mfma_f32_16x16x32_bf16 v[104:107], v[228:231], v[232:235], v[20:23]
	v_mfma_f32_16x16x32_bf16 v[20:23], v[216:219], v[236:239], v[44:47]
	v_mfma_f32_16x16x32_bf16 v[88:91], v[220:223], v[240:243], v[20:23]
	v_mfma_f32_16x16x32_bf16 v[20:23], v[224:227], v[236:239], v[48:51]
	v_mfma_f32_16x16x32_bf16 v[80:83], v[228:231], v[240:243], v[20:23]
	v_mfma_f32_16x16x32_bf16 v[20:23], v[216:219], v[244:247], v[140:143]
	v_mfma_f32_16x16x32_bf16 v[56:59], v[220:223], v[248:251], v[20:23]
	v_mfma_f32_16x16x32_bf16 v[20:23], v[224:227], v[244:247], v[144:147]
	v_mfma_f32_16x16x32_bf16 v[120:123], v[220:223], v[28:31], v[64:67]
	v_mfma_f32_16x16x32_bf16 v[48:51], v[228:231], v[248:251], v[20:23]
	s_barrier
	s_add_i32 s37, s37, s94
	s_nop 2
	v_lshl_add_u64 v[20:21], v[148:149], 0, s[28:29]
	s_mov_b32 m0, s37
	ds_read_b128 v[32:35], v154 offset:49152
	ds_read_b128 v[40:43], v154 offset:50176
	ds_read_b128 v[140:143], v154 offset:51200
	ds_read_b128 v[144:147], v154 offset:52224
	ds_read_b128 v[232:235], v154 offset:53248
	ds_read_b128 v[236:239], v154 offset:54272
	ds_read_b128 v[240:243], v154 offset:55296
	ds_read_b128 v[244:247], v154 offset:56320
	global_load_lds_dwordx4 v[20:21], off
	s_add_i32 m0, s37, 0x2000
	s_add_u32 s46, s46, 0x8080
	v_lshl_add_u64 v[20:21], v[212:213], 0, s[28:29]
	s_addc_u32 s47, s47, 0
	s_add_i32 s37, s39, s94
	global_load_lds_dwordx4 v[20:21], off
	v_lshl_add_u64 v[20:21], s[46:47], 0, v[130:131]
	s_mov_b32 m0, s37
	s_nop 0
	global_load_lds_dwordx4 v[20:21], off
	v_lshl_add_u64 v[20:21], s[46:47], 0, v[134:135]
	s_add_i32 m0, s37, 0x2000
	s_nop 0
	global_load_lds_dwordx4 v[20:21], off
	v_lshl_add_u64 v[20:21], v[214:215], 0, s[28:29]
	s_mov_b32 m0, s53
	s_nop 0
	global_load_lds_dwordx4 v[20:21], off
	v_lshl_add_u64 v[20:21], v[252:253], 0, s[28:29]
	s_mov_b32 m0, s54
	s_nop 0
	global_load_lds_dwordx4 v[20:21], off
	s_waitcnt vmcnt(8)
	s_waitcnt lgkmcnt(0)
	s_barrier
	v_mfma_f32_16x16x32_bf16 v[20:23], v[12:15], v[32:35], v[156:159]
	v_mfma_f32_16x16x32_bf16 v[76:79], v[16:19], v[40:43], v[20:23]
	v_mfma_f32_16x16x32_bf16 v[20:23], v[24:27], v[32:35], v[160:163]
	v_mfma_f32_16x16x32_bf16 v[68:71], v[208:211], v[40:43], v[20:23]
	v_mfma_f32_16x16x32_bf16 v[20:23], v[12:15], v[140:143], v[164:167]
	v_mfma_f32_16x16x32_bf16 v[44:47], v[16:19], v[144:147], v[20:23]
	v_mfma_f32_16x16x32_bf16 v[20:23], v[24:27], v[140:143], v[168:171]
	v_mfma_f32_16x16x32_bf16 v[36:39], v[208:211], v[144:147], v[20:23]
	v_mfma_f32_16x16x32_bf16 v[20:23], v[12:15], v[232:235], v[172:175]
	v_mfma_f32_16x16x32_bf16 v[0:3], v[12:15], v[240:243], v[0:3]
	v_mfma_f32_16x16x32_bf16 v[28:31], v[16:19], v[236:239], v[20:23]
	v_mfma_f32_16x16x32_bf16 v[20:23], v[24:27], v[232:235], v[176:179]
	v_mfma_f32_16x16x32_bf16 v[12:15], v[16:19], v[244:247], v[0:3]
	v_mfma_f32_16x16x32_bf16 v[0:3], v[24:27], v[240:243], v[4:7]
	v_mfma_f32_16x16x32_bf16 v[20:23], v[208:211], v[236:239], v[20:23]
	v_mfma_f32_16x16x32_bf16 v[4:7], v[208:211], v[244:247], v[0:3]
	v_mfma_f32_16x16x32_bf16 v[0:3], v[216:219], v[32:35], v[8:11]
	v_mfma_f32_16x16x32_bf16 v[72:75], v[220:223], v[40:43], v[0:3]
	v_mfma_f32_16x16x32_bf16 v[0:3], v[224:227], v[32:35], v[180:183]
	v_mfma_f32_16x16x32_bf16 v[64:67], v[228:231], v[40:43], v[0:3]
	v_mfma_f32_16x16x32_bf16 v[0:3], v[216:219], v[140:143], v[184:187]
	v_mfma_f32_16x16x32_bf16 v[40:43], v[220:223], v[144:147], v[0:3]
	v_mfma_f32_16x16x32_bf16 v[0:3], v[224:227], v[140:143], v[188:191]
	v_mfma_f32_16x16x32_bf16 v[32:35], v[228:231], v[144:147], v[0:3]
	v_mfma_f32_16x16x32_bf16 v[0:3], v[216:219], v[232:235], v[192:195]
	v_mfma_f32_16x16x32_bf16 v[24:27], v[220:223], v[236:239], v[0:3]
	v_mfma_f32_16x16x32_bf16 v[0:3], v[224:227], v[232:235], v[196:199]
	v_mfma_f32_16x16x32_bf16 v[16:19], v[228:231], v[236:239], v[0:3]
	v_mfma_f32_16x16x32_bf16 v[0:3], v[216:219], v[240:243], v[200:203]
	v_mfma_f32_16x16x32_bf16 v[8:11], v[220:223], v[244:247], v[0:3]
	v_mfma_f32_16x16x32_bf16 v[0:3], v[224:227], v[240:243], v[204:207]
	v_mfma_f32_16x16x32_bf16 v[0:3], v[228:231], v[244:247], v[0:3]
	s_barrier
	s_andn2_b64 vcc, exec, s[30:31]
	s_cbranch_vccnz .LBB0_752
	s_barrier

; #define PG8_STAGE(bufoff, gbase, voff) do { _Pragma("unroll") for (int _i = 0; _i < 2; ++_i) \
;         __builtin_amdgcn_global_load_lds((const unsigned*)((const char*)(gbase) + (voff)[_i]), (LAS unsigned*)(lds + (bufoff) + ldsw + _i * 8192), 16, 0, 0); } while (0)
; #define PG8_LDA(dst, b, h) do { _Pragma("unroll") for (int m = 0; m < 4; ++m) _Pragma("unroll") for (int k = 0; k < 2; ++k) dst[m][k] = *(const LAS bf16x8*)(lds + PG8_SA(b, h) + aoff + m * 2048 + k * 1024); } while (0)
; #define PG8_LDB(dst, b, h) do { _Pragma("unroll") for (int n = 0; n < 2; ++n) _Pragma("unroll") for (int k = 0; k < 2; ++k) dst[n][k] = *(const LAS bf16x8*)(lds + PG8_SB(b, h) + boff + n * 2048 + k * 1024); } while (0)
; #define PG8_MMA(ai, bj, At, Bt) do { __builtin_amdgcn_s_setprio(1); _Pragma("unroll") for (int m = 0; m < 4; ++m) _Pragma("unroll") for (int n = 0; n < 2; ++n) _Pragma("unroll") for (int k = 0; k < 2; ++k) \
;         acc[ai][bj][m][n] = __builtin_amdgcn_mfma_f32_16x16x32_bf16(Bt[n][k], At[m][k], acc[ai][bj][m][n], 0, 0, 0); __builtin_amdgcn_s_setprio(0); } while (0)
; template <class Epi>
; DI void gemm_phase(LAS unsigned char* lds, const int wid, const Gemm g, const Order& S, const Epi& E) {
;     ...
;         const bool has_next = S.next(ui + 1, nxt);
;         const char* nA = has_next ? (const char*)(g.A + (size_t)nxt.g * g.gsA + (size_t)nxt.pm * BM * g.lda) : cA;
;         const char* nB = has_next ? (const char*)(g.Bt + (size_t)nxt.g * g.gsB + (size_t)nxt.pn * BM * g.ldb) : cB;
;         for (int t = 0; t < nt; t += 2) {
;             const bool last = (t == nt - 2);
;             const char* a1 = cA + (size_t)(t + 1) * kstep;
;             const char* a2 = last ? nA : cA + (size_t)(t + 2) * kstep; const char* b2 = last ? nB : cB + (size_t)(t + 2) * kstep;
;             const char* a3 = a2 + kstep; const char* b3 = b2 + kstep;
;             PG8_LDB(B0, 0, 0); PG8_LDB(B1, 0, 1); PG8_SCHED; PG8_LDA(At, 0, 0); PG8_STAGE(PG8_SA(1, 1), a1 + hstepA, voffA);
;             PG8_WAIT_V(8); PG8_WAIT_L(0); PG8_BAR; PG8_MMA(0, 0, At, B0); PG8_MMA(0, 1, At, B1); PG8_BAR; PG8_SCHED;
;             PG8_LDA(At, 0, 1); PG8_STAGE(PG8_SB(0, 0), b2, voffB); PG8_STAGE(PG8_SB(0, 1), b2 + hstepB, voffB); PG8_STAGE(PG8_SA(0, 0), a2, voffA);
;             PG8_WAIT_V(8); PG8_WAIT_L(0); PG8_BAR; PG8_MMA(1, 0, At, B0); PG8_MMA(1, 1, At, B1); PG8_BAR; PG8_SCHED;
.LBB0_773:
	s_ashr_i32 s37, s36, 31
	s_lshl_b64 s[40:41], s[36:37], 16
	s_add_u32 s40, s6, s40
	s_addc_u32 s41, s7, s41
	s_and_b64 s[42:43], s[10:11], exec
	s_cselect_b32 s49, s41, s47
	s_cselect_b32 s48, s40, s46
	s_ashr_i32 s39, s38, 31
	s_lshl_b64 s[42:43], s[38:39], 16
	s_add_u32 s42, s8, s42
	s_addc_u32 s43, s9, s43
	s_add_u32 s62, s46, 0x8080
	ds_read_b128 v[0:3], v147
	ds_read_b128 v[4:7], v147 offset:1024
	ds_read_b128 v[8:11], v147 offset:2048
	ds_read_b128 v[12:15], v147 offset:3072
	ds_read_b128 v[16:19], v148
	ds_read_b128 v[20:23], v148 offset:1024
	ds_read_b128 v[24:27], v148 offset:2048
	ds_read_b128 v[28:31], v148 offset:3072
	s_addc_u32 s63, s47, 0
	s_add_u32 s46, s48, 0x8000
	s_addc_u32 s47, s49, 0
	s_and_b64 s[64:65], s[10:11], exec
	s_cselect_b32 s44, s42, s44
	s_cselect_b32 s45, s43, s45
	s_add_u32 s64, s44, 0x8000
	s_addc_u32 s65, s45, 0
	s_mov_b32 m0, s54
	v_lshl_add_u64 v[64:65], s[62:63], 0, v[128:129]
	s_waitcnt vmcnt(0)
	ds_read_b128 v[32:35], v149
	ds_read_b128 v[36:39], v149 offset:1024
	ds_read_b128 v[40:43], v149 offset:2048
	ds_read_b128 v[44:47], v149 offset:3072
	ds_read_b128 v[48:51], v149 offset:4096
	ds_read_b128 v[52:55], v149 offset:5120
	ds_read_b128 v[56:59], v149 offset:6144
	ds_read_b128 v[60:63], v149 offset:7168
	global_load_lds_dwordx4 v[64:65], off
	v_lshl_add_u64 v[64:65], s[62:63], 0, v[132:133]
	s_mov_b32 m0, s55
	s_nop 0
	global_load_lds_dwordx4 v[64:65], off
	s_waitcnt vmcnt(8)
	s_waitcnt lgkmcnt(0)
	s_barrier
	v_mfma_f32_16x16x32_bf16 v[80:83], v[0:3], v[48:51], 0
	v_mfma_f32_16x16x32_bf16 v[96:99], v[4:7], v[52:55], v[80:83]
	v_mfma_f32_16x16x32_bf16 v[80:83], v[8:11], v[48:51], 0
	v_mfma_f32_16x16x32_bf16 v[100:103], v[12:15], v[52:55], v[80:83]
	v_mfma_f32_16x16x32_bf16 v[80:83], v[0:3], v[56:59], 0
	v_mfma_f32_16x16x32_bf16 v[64:67], v[0:3], v[32:35], 0
	v_mfma_f32_16x16x32_bf16 v[68:71], v[8:11], v[32:35], 0
	v_mfma_f32_16x16x32_bf16 v[72:75], v[0:3], v[40:43], 0
	v_mfma_f32_16x16x32_bf16 v[76:79], v[8:11], v[40:43], 0
	v_mfma_f32_16x16x32_bf16 v[104:107], v[4:7], v[60:63], v[80:83]
	v_mfma_f32_16x16x32_bf16 v[80:83], v[8:11], v[56:59], 0
	v_mfma_f32_16x16x32_bf16 v[64:67], v[4:7], v[36:39], v[64:67]
	v_mfma_f32_16x16x32_bf16 v[68:71], v[12:15], v[36:39], v[68:71]
	v_mfma_f32_16x16x32_bf16 v[72:75], v[4:7], v[44:47], v[72:75]
	v_mfma_f32_16x16x32_bf16 v[76:79], v[12:15], v[44:47], v[76:79]
	v_mfma_f32_16x16x32_bf16 v[108:111], v[12:15], v[60:63], v[80:83]
	v_mfma_f32_16x16x32_bf16 v[80:83], v[16:19], v[32:35], 0
	v_mfma_f32_16x16x32_bf16 v[32:35], v[24:27], v[32:35], 0
	v_mfma_f32_16x16x32_bf16 v[112:115], v[20:23], v[36:39], v[80:83]
	v_mfma_f32_16x16x32_bf16 v[32:35], v[28:31], v[36:39], v[32:35]
	v_mfma_f32_16x16x32_bf16 v[36:39], v[16:19], v[40:43], 0
	v_mfma_f32_16x16x32_bf16 v[40:43], v[24:27], v[40:43], 0
	v_mfma_f32_16x16x32_bf16 v[36:39], v[20:23], v[44:47], v[36:39]
	v_mfma_f32_16x16x32_bf16 v[40:43], v[28:31], v[44:47], v[40:43]
	v_mfma_f32_16x16x32_bf16 v[44:47], v[16:19], v[48:51], 0
	v_mfma_f32_16x16x32_bf16 v[116:119], v[20:23], v[52:55], v[44:47]
	v_mfma_f32_16x16x32_bf16 v[44:47], v[24:27], v[48:51], 0
	v_mfma_f32_16x16x32_bf16 v[48:51], v[28:31], v[52:55], v[44:47]
	v_mfma_f32_16x16x32_bf16 v[44:47], v[16:19], v[56:59], 0
	v_mfma_f32_16x16x32_bf16 v[52:55], v[20:23], v[60:63], v[44:47]
	v_mfma_f32_16x16x32_bf16 v[44:47], v[24:27], v[56:59], 0
	v_mfma_f32_16x16x32_bf16 v[120:123], v[28:31], v[60:63], v[44:47]
	s_barrier
	s_mov_b32 m0, s56
	v_lshl_add_u64 v[144:145], s[44:45], 0, v[130:131]
	s_nop 2
	ds_read_b128 v[44:47], v149 offset:16384
	ds_read_b128 v[56:59], v149 offset:17408
	ds_read_b128 v[60:63], v149 offset:18432
	ds_read_b128 v[80:83], v149 offset:19456
	ds_read_b128 v[84:87], v149 offset:20480
	ds_read_b128 v[88:91], v149 offset:21504
	ds_read_b128 v[92:95], v149 offset:22528
	ds_read_b128 v[124:127], v149 offset:23552
	global_load_lds_dwordx4 v[144:145], off
	v_lshl_add_u64 v[252:253], s[44:45], 0, v[134:135]
	s_mov_b32 m0, s57
	v_lshl_add_u64 v[140:141], s[64:65], 0, v[130:131]
	global_load_lds_dwordx4 v[252:253], off
	s_mov_b32 m0, s58
	v_lshl_add_u64 v[136:137], s[48:49], 0, v[128:129]
	global_load_lds_dwordx4 v[140:141], off
	v_lshl_add_u64 v[140:141], s[64:65], 0, v[134:135]
	s_mov_b32 m0, s59
	v_lshl_add_u64 v[138:139], s[48:49], 0, v[132:133]
	global_load_lds_dwordx4 v[140:141], off
	s_mov_b32 m0, s21
	s_nop 0
	global_load_lds_dwordx4 v[136:137], off
	s_mov_b32 m0, s25
	s_nop 0
	global_load_lds_dwordx4 v[138:139], off
	s_waitcnt vmcnt(8)
	s_waitcnt lgkmcnt(0)
	s_barrier
	v_mfma_f32_16x16x32_bf16 v[140:143], v[0:3], v[44:47], 0
	v_mfma_f32_16x16x32_bf16 v[156:159], v[0:3], v[60:63], 0
	v_mfma_f32_16x16x32_bf16 v[164:167], v[0:3], v[84:87], 0
	v_mfma_f32_16x16x32_bf16 v[0:3], v[0:3], v[92:95], 0
	v_mfma_f32_16x16x32_bf16 v[172:175], v[4:7], v[124:127], v[0:3]
	v_mfma_f32_16x16x32_bf16 v[0:3], v[8:11], v[92:95], 0
	v_mfma_f32_16x16x32_bf16 v[152:155], v[8:11], v[44:47], 0
	v_mfma_f32_16x16x32_bf16 v[160:163], v[8:11], v[60:63], 0
	v_mfma_f32_16x16x32_bf16 v[168:171], v[8:11], v[84:87], 0
	v_mfma_f32_16x16x32_bf16 v[8:11], v[12:15], v[124:127], v[0:3]
	v_mfma_f32_16x16x32_bf16 v[140:143], v[4:7], v[56:59], v[140:143]
	v_mfma_f32_16x16x32_bf16 v[152:155], v[12:15], v[56:59], v[152:155]
	v_mfma_f32_16x16x32_bf16 v[156:159], v[4:7], v[80:83], v[156:159]
	v_mfma_f32_16x16x32_bf16 v[160:163], v[12:15], v[80:83], v[160:163]
	v_mfma_f32_16x16x32_bf16 v[164:167], v[4:7], v[88:91], v[164:167]
	v_mfma_f32_16x16x32_bf16 v[168:171], v[12:15], v[88:91], v[168:171]
	v_mfma_f32_16x16x32_bf16 v[0:3], v[16:19], v[44:47], 0
	v_mfma_f32_16x16x32_bf16 v[12:15], v[20:23], v[56:59], v[0:3]
	v_mfma_f32_16x16x32_bf16 v[0:3], v[24:27], v[44:47], 0
	v_mfma_f32_16x16x32_bf16 v[176:179], v[28:31], v[56:59], v[0:3]
	v_mfma_f32_16x16x32_bf16 v[0:3], v[16:19], v[60:63], 0
	v_mfma_f32_16x16x32_bf16 v[180:183], v[20:23], v[80:83], v[0:3]
	v_mfma_f32_16x16x32_bf16 v[0:3], v[24:27], v[60:63], 0
	v_mfma_f32_16x16x32_bf16 v[184:187], v[28:31], v[80:83], v[0:3]
	v_mfma_f32_16x16x32_bf16 v[0:3], v[16:19], v[84:87], 0
	v_mfma_f32_16x16x32_bf16 v[188:191], v[20:23], v[88:91], v[0:3]
	v_mfma_f32_16x16x32_bf16 v[0:3], v[24:27], v[84:87], 0
	v_mfma_f32_16x16x32_bf16 v[192:195], v[28:31], v[88:91], v[0:3]
	v_mfma_f32_16x16x32_bf16 v[0:3], v[16:19], v[92:95], 0
	v_mfma_f32_16x16x32_bf16 v[196:199], v[20:23], v[124:127], v[0:3]
	v_mfma_f32_16x16x32_bf16 v[0:3], v[24:27], v[92:95], 0
	v_mfma_f32_16x16x32_bf16 v[200:203], v[28:31], v[124:127], v[0:3]
	s_barrier
; #define PG8_STAGE(bufoff, gbase, voff) do { _Pragma("unroll") for (int _i = 0; _i < 2; ++_i) \
;         __builtin_amdgcn_global_load_lds((const unsigned*)((const char*)(gbase) + (voff)[_i]), (LAS unsigned*)(lds + (bufoff) + ldsw + _i * 8192), 16, 0, 0); } while (0)
; #define PG8_LDA(dst, b, h) do { _Pragma("unroll") for (int m = 0; m < 4; ++m) _Pragma("unroll") for (int k = 0; k < 2; ++k) dst[m][k] = *(const LAS bf16x8*)(lds + PG8_SA(b, h) + aoff + m * 2048 + k * 1024); } while (0)
; #define PG8_LDB(dst, b, h) do { _Pragma("unroll") for (int n = 0; n < 2; ++n) _Pragma("unroll") for (int k = 0; k < 2; ++k) dst[n][k] = *(const LAS bf16x8*)(lds + PG8_SB(b, h) + boff + n * 2048 + k * 1024); } while (0)
; #define PG8_MMA(ai, bj, At, Bt) do { __builtin_amdgcn_s_setprio(1); _Pragma("unroll") for (int m = 0; m < 4; ++m) _Pragma("unroll") for (int n = 0; n < 2; ++n) _Pragma("unroll") for (int k = 0; k < 2; ++k) \
;         acc[ai][bj][m][n] = __builtin_amdgcn_mfma_f32_16x16x32_bf16(Bt[n][k], At[m][k], acc[ai][bj][m][n], 0, 0, 0); __builtin_amdgcn_s_setprio(0); } while (0)
; #define PG8_WAIT_V(n) asm volatile("s_waitcnt vmcnt(" #n ")" ::: "memory")
; #define PG8_WAIT_L(n) asm volatile("s_waitcnt lgkmcnt(" #n ")" ::: "memory")
; #define PG8_BAR __builtin_amdgcn_s_barrier()
; #define PG8_SCHED __builtin_amdgcn_sched_barrier(0)
; template <class Epi>
; DI void gemm_phase(LAS unsigned char* lds, const int wid, const Gemm g, const Order& S, const Epi& E) {
;     ...
;             PG8_LDB(B0, 1, 0); PG8_LDB(B1, 1, 1); PG8_SCHED; PG8_LDA(At, 1, 0); PG8_STAGE(PG8_SA(0, 1), a2 + hstepA, voffA);
;             PG8_WAIT_V(8); PG8_WAIT_L(0); PG8_BAR; PG8_MMA(0, 0, At, B0); PG8_MMA(0, 1, At, B1); PG8_BAR; PG8_SCHED;
;             PG8_LDA(At, 1, 1); PG8_STAGE(PG8_SB(1, 0), b3, voffB); PG8_STAGE(PG8_SB(1, 1), b3 + hstepB, voffB); PG8_STAGE(PG8_SA(1, 0), a3, voffA);
;             PG8_WAIT_V(8); PG8_WAIT_L(0); PG8_BAR; PG8_MMA(1, 0, At, B0); PG8_MMA(1, 1, At, B1); PG8_BAR; PG8_SCHED;
;         }
;         if (wr == 0) PG8_BAR;
	s_add_i32 s37, 0, 0x18000
	s_nop 3
	v_add_u32_e32 v0, s37, v146
	s_add_i32 s39, 0, 0x1c000
	ds_read_b128 v[20:23], v0
	ds_read_b128 v[24:27], v0 offset:1024
	ds_read_b128 v[204:207], v0 offset:2048
	ds_read_b128 v[208:211], v0 offset:3072
	v_add_u32_e32 v0, s39, v146
	ds_read_b128 v[216:219], v0
	ds_read_b128 v[220:223], v0 offset:1024
	ds_read_b128 v[224:227], v0 offset:2048
	ds_read_b128 v[228:231], v0 offset:3072
	s_mov_b32 m0, s26
	v_lshl_add_u64 v[44:45], s[46:47], 0, v[128:129]
	ds_read_b128 v[0:3], v149 offset:32768
	ds_read_b128 v[4:7], v149 offset:33792
	ds_read_b128 v[16:19], v149 offset:34816
	ds_read_b128 v[28:31], v149 offset:35840
	ds_read_b128 v[124:127], v149 offset:36864
	ds_read_b128 v[232:235], v149 offset:37888
	ds_read_b128 v[236:239], v149 offset:38912
	ds_read_b128 v[240:243], v149 offset:39936
	global_load_lds_dwordx4 v[44:45], off
	v_lshl_add_u64 v[44:45], s[46:47], 0, v[132:133]
	s_mov_b32 m0, s27
	s_nop 0
	global_load_lds_dwordx4 v[44:45], off
	s_waitcnt vmcnt(8)
	s_waitcnt lgkmcnt(0)
	s_barrier
	v_mfma_f32_16x16x32_bf16 v[44:47], v[20:23], v[0:3], v[64:67]
	v_mfma_f32_16x16x32_bf16 v[80:83], v[24:27], v[4:7], v[44:47]
	v_mfma_f32_16x16x32_bf16 v[44:47], v[204:207], v[0:3], v[68:71]
	v_mfma_f32_16x16x32_bf16 v[84:87], v[208:211], v[4:7], v[44:47]
	v_mfma_f32_16x16x32_bf16 v[44:47], v[20:23], v[16:19], v[72:75]
	v_mfma_f32_16x16x32_bf16 v[88:91], v[24:27], v[28:31], v[44:47]
	v_mfma_f32_16x16x32_bf16 v[44:47], v[204:207], v[16:19], v[76:79]
	v_mfma_f32_16x16x32_bf16 v[92:95], v[208:211], v[28:31], v[44:47]
	v_mfma_f32_16x16x32_bf16 v[44:47], v[20:23], v[124:127], v[96:99]
	v_mfma_f32_16x16x32_bf16 v[96:99], v[24:27], v[232:235], v[44:47]
	v_mfma_f32_16x16x32_bf16 v[44:47], v[204:207], v[124:127], v[100:103]
	v_mfma_f32_16x16x32_bf16 v[100:103], v[208:211], v[232:235], v[44:47]
	v_mfma_f32_16x16x32_bf16 v[44:47], v[20:23], v[236:239], v[104:107]
	v_mfma_f32_16x16x32_bf16 v[104:107], v[24:27], v[240:243], v[44:47]
	v_mfma_f32_16x16x32_bf16 v[44:47], v[204:207], v[236:239], v[108:111]
	v_mfma_f32_16x16x32_bf16 v[108:111], v[208:211], v[240:243], v[44:47]
	v_mfma_f32_16x16x32_bf16 v[44:47], v[216:219], v[0:3], v[112:115]
	v_mfma_f32_16x16x32_bf16 v[0:3], v[224:227], v[0:3], v[32:35]
	v_mfma_f32_16x16x32_bf16 v[56:59], v[228:231], v[4:7], v[0:3]
	v_mfma_f32_16x16x32_bf16 v[0:3], v[216:219], v[16:19], v[36:39]
	v_mfma_f32_16x16x32_bf16 v[60:63], v[220:223], v[4:7], v[44:47]
	v_mfma_f32_16x16x32_bf16 v[44:47], v[220:223], v[28:31], v[0:3]
	v_mfma_f32_16x16x32_bf16 v[0:3], v[224:227], v[16:19], v[40:43]
	v_mfma_f32_16x16x32_bf16 v[40:43], v[228:231], v[28:31], v[0:3]
	v_mfma_f32_16x16x32_bf16 v[0:3], v[216:219], v[124:127], v[116:119]
	v_mfma_f32_16x16x32_bf16 v[28:31], v[220:223], v[232:235], v[0:3]
	v_mfma_f32_16x16x32_bf16 v[0:3], v[224:227], v[124:127], v[48:51]
	v_mfma_f32_16x16x32_bf16 v[16:19], v[228:231], v[232:235], v[0:3]
	v_mfma_f32_16x16x32_bf16 v[0:3], v[216:219], v[236:239], v[52:55]
	v_mfma_f32_16x16x32_bf16 v[4:7], v[220:223], v[240:243], v[0:3]
	v_mfma_f32_16x16x32_bf16 v[0:3], v[224:227], v[236:239], v[120:123]
	v_mfma_f32_16x16x32_bf16 v[0:3], v[228:231], v[240:243], v[0:3]
	s_barrier
	s_add_i32 s37, s37, s94
	v_lshl_add_u64 v[48:49], v[144:145], 0, s[28:29]
	s_mov_b32 m0, s37
	ds_read_b128 v[32:35], v149 offset:49152
	ds_read_b128 v[36:39], v149 offset:50176
	ds_read_b128 v[232:235], v149 offset:51200
	ds_read_b128 v[236:239], v149 offset:52224
	ds_read_b128 v[240:243], v149 offset:53248
	ds_read_b128 v[244:247], v149 offset:54272
	ds_read_b128 v[248:251], v149 offset:55296
	ds_read_b128 v[212:215], v149 offset:56320
	global_load_lds_dwordx4 v[48:49], off
	s_add_i32 m0, s37, 0x2000
	s_add_u32 s44, s44, 0x8080
	v_lshl_add_u64 v[48:49], v[252:253], 0, s[28:29]
	s_addc_u32 s45, s45, 0
	s_add_i32 s37, s39, s94
	global_load_lds_dwordx4 v[48:49], off
	v_lshl_add_u64 v[48:49], s[44:45], 0, v[130:131]
	s_mov_b32 m0, s37
	s_nop 0
	global_load_lds_dwordx4 v[48:49], off
	v_lshl_add_u64 v[48:49], s[44:45], 0, v[134:135]
	s_add_i32 m0, s37, 0x2000
	s_nop 0
	global_load_lds_dwordx4 v[48:49], off
	v_lshl_add_u64 v[48:49], v[136:137], 0, s[28:29]
	s_mov_b32 m0, s50
	s_nop 0
	global_load_lds_dwordx4 v[48:49], off
	v_lshl_add_u64 v[48:49], v[138:139], 0, s[28:29]
	s_mov_b32 m0, s51
	s_nop 0
	global_load_lds_dwordx4 v[48:49], off
	s_waitcnt vmcnt(8)
	s_waitcnt lgkmcnt(0)
	s_barrier
	v_mfma_f32_16x16x32_bf16 v[48:51], v[20:23], v[32:35], v[140:143]
	v_mfma_f32_16x16x32_bf16 v[124:127], v[24:27], v[36:39], v[48:51]
	v_mfma_f32_16x16x32_bf16 v[48:51], v[204:207], v[32:35], v[152:155]
	v_mfma_f32_16x16x32_bf16 v[120:123], v[208:211], v[36:39], v[48:51]
	v_mfma_f32_16x16x32_bf16 v[48:51], v[20:23], v[232:235], v[156:159]
	v_mfma_f32_16x16x32_bf16 v[116:119], v[24:27], v[236:239], v[48:51]
	v_mfma_f32_16x16x32_bf16 v[48:51], v[204:207], v[232:235], v[160:163]
	v_mfma_f32_16x16x32_bf16 v[112:115], v[208:211], v[236:239], v[48:51]
	v_mfma_f32_16x16x32_bf16 v[48:51], v[20:23], v[240:243], v[164:167]
	v_mfma_f32_16x16x32_bf16 v[76:79], v[24:27], v[244:247], v[48:51]
	v_mfma_f32_16x16x32_bf16 v[48:51], v[204:207], v[240:243], v[168:171]
	v_mfma_f32_16x16x32_bf16 v[20:23], v[20:23], v[248:251], v[172:175]
	v_mfma_f32_16x16x32_bf16 v[8:11], v[204:207], v[248:251], v[8:11]
	v_mfma_f32_16x16x32_bf16 v[72:75], v[208:211], v[244:247], v[48:51]
	v_mfma_f32_16x16x32_bf16 v[68:71], v[24:27], v[212:215], v[20:23]
	v_mfma_f32_16x16x32_bf16 v[64:67], v[208:211], v[212:215], v[8:11]
	v_mfma_f32_16x16x32_bf16 v[8:11], v[216:219], v[32:35], v[12:15]
	v_mfma_f32_16x16x32_bf16 v[52:55], v[220:223], v[36:39], v[8:11]
	v_mfma_f32_16x16x32_bf16 v[8:11], v[224:227], v[32:35], v[176:179]
	v_mfma_f32_16x16x32_bf16 v[48:51], v[228:231], v[36:39], v[8:11]
	v_mfma_f32_16x16x32_bf16 v[8:11], v[216:219], v[232:235], v[180:183]
	v_mfma_f32_16x16x32_bf16 v[36:39], v[220:223], v[236:239], v[8:11]
	v_mfma_f32_16x16x32_bf16 v[8:11], v[224:227], v[232:235], v[184:187]
	v_mfma_f32_16x16x32_bf16 v[32:35], v[228:231], v[236:239], v[8:11]
	v_mfma_f32_16x16x32_bf16 v[8:11], v[216:219], v[240:243], v[188:191]
	v_mfma_f32_16x16x32_bf16 v[24:27], v[220:223], v[244:247], v[8:11]
	v_mfma_f32_16x16x32_bf16 v[8:11], v[224:227], v[240:243], v[192:195]
	v_mfma_f32_16x16x32_bf16 v[20:23], v[228:231], v[244:247], v[8:11]
	v_mfma_f32_16x16x32_bf16 v[8:11], v[216:219], v[248:251], v[196:199]
	v_mfma_f32_16x16x32_bf16 v[12:15], v[220:223], v[212:215], v[8:11]
	v_mfma_f32_16x16x32_bf16 v[8:11], v[224:227], v[248:251], v[200:203]
	v_mfma_f32_16x16x32_bf16 v[8:11], v[228:231], v[212:215], v[8:11]
	s_barrier
	s_andn2_b64 vcc, exec, s[30:31]
	s_cbranch_vccnz .LBB0_775
	s_barrier

; #define PG8_STAGE(bufoff, gbase, voff) do { _Pragma("unroll") for (int _i = 0; _i < 2; ++_i) \
;         __builtin_amdgcn_global_load_lds((const unsigned*)((const char*)(gbase) + (voff)[_i]), (LAS unsigned*)(lds + (bufoff) + ldsw + _i * 8192), 16, 0, 0); } while (0)
; #define PG8_LDA(dst, b, h) do { _Pragma("unroll") for (int m = 0; m < 4; ++m) _Pragma("unroll") for (int k = 0; k < 2; ++k) dst[m][k] = *(const LAS bf16x8*)(lds + PG8_SA(b, h) + aoff + m * 2048 + k * 1024); } while (0)
; #define PG8_LDB(dst, b, h) do { _Pragma("unroll") for (int n = 0; n < 2; ++n) _Pragma("unroll") for (int k = 0; k < 2; ++k) dst[n][k] = *(const LAS bf16x8*)(lds + PG8_SB(b, h) + boff + n * 2048 + k * 1024); } while (0)
; #define PG8_MMA(ai, bj, At, Bt) do { __builtin_amdgcn_s_setprio(1); _Pragma("unroll") for (int m = 0; m < 4; ++m) _Pragma("unroll") for (int n = 0; n < 2; ++n) _Pragma("unroll") for (int k = 0; k < 2; ++k) \
;         acc[ai][bj][m][n] = __builtin_amdgcn_mfma_f32_16x16x32_bf16(Bt[n][k], At[m][k], acc[ai][bj][m][n], 0, 0, 0); __builtin_amdgcn_s_setprio(0); } while (0)
; template <class Epi>
; DI void gemm_phase(LAS unsigned char* lds, const int wid, const Gemm g, const Order& S, const Epi& E) {
;     ...
;         const bool has_next = S.next(ui + 1, nxt);
;         const char* nA = has_next ? (const char*)(g.A + (size_t)nxt.g * g.gsA + (size_t)nxt.pm * BM * g.lda) : cA;
;         const char* nB = has_next ? (const char*)(g.Bt + (size_t)nxt.g * g.gsB + (size_t)nxt.pn * BM * g.ldb) : cB;
;         for (int t = 0; t < nt; t += 2) {
;             const bool last = (t == nt - 2);
;             const char* a1 = cA + (size_t)(t + 1) * kstep;
;             const char* a2 = last ? nA : cA + (size_t)(t + 2) * kstep; const char* b2 = last ? nB : cB + (size_t)(t + 2) * kstep;
;             const char* a3 = a2 + kstep; const char* b3 = b2 + kstep;
;             PG8_LDB(B0, 0, 0); PG8_LDB(B1, 0, 1); PG8_SCHED; PG8_LDA(At, 0, 0); PG8_STAGE(PG8_SA(1, 1), a1 + hstepA, voffA);
;             PG8_WAIT_V(8); PG8_WAIT_L(0); PG8_BAR; PG8_MMA(0, 0, At, B0); PG8_MMA(0, 1, At, B1); PG8_BAR; PG8_SCHED;
;             PG8_LDA(At, 0, 1); PG8_STAGE(PG8_SB(0, 0), b2, voffB); PG8_STAGE(PG8_SB(0, 1), b2 + hstepB, voffB); PG8_STAGE(PG8_SA(0, 0), a2, voffA);
;             PG8_WAIT_V(8); PG8_WAIT_L(0); PG8_BAR; PG8_MMA(1, 0, At, B0); PG8_MMA(1, 1, At, B1); PG8_BAR; PG8_SCHED;
.LBB0_789:
	s_lshl_b64 s[42:43], s[36:37], 18
	s_add_u32 s29, s8, s42
	s_addc_u32 s37, s9, s43
	s_ashr_i32 s39, s38, 31
	s_lshl_b64 s[42:43], s[38:39], 18
	s_add_u32 s42, s29, s42
	s_addc_u32 s43, s37, s43
	s_and_b64 s[12:13], s[12:13], exec
	s_cselect_b32 s29, s43, s47
	s_cselect_b32 s37, s42, s46
	s_add_u32 s39, s46, 0x100
	v_mov_b32_e32 v0, 0
	s_addc_u32 s61, s47, 0
	s_mov_b32 s62, -2
	ds_read_b128 v[148:151], v145
	ds_read_b128 v[152:155], v145 offset:1024
	ds_read_b128 v[156:159], v145 offset:2048
	ds_read_b128 v[160:163], v145 offset:3072
	ds_read_b128 v[164:167], v146
	ds_read_b128 v[168:171], v146 offset:1024
	ds_read_b128 v[172:175], v146 offset:2048
	ds_read_b128 v[176:179], v146 offset:3072
	s_add_u32 s12, s44, 0x100
	s_addc_u32 s13, s45, 0
	s_cmp_eq_u32 s62, 4
	s_cselect_b32 s49, s41, s13
	s_cselect_b32 s48, s40, s12
	s_cselect_b32 s47, s29, s61
	s_cselect_b32 s46, s37, s39
	v_lshl_add_u64 v[212:213], s[44:45], 0, v[136:137]
	s_add_i32 m0, s21, 0xc000
	ds_read_b128 v[180:183], v147
	ds_read_b128 v[184:187], v147 offset:1024
	ds_read_b128 v[188:191], v147 offset:2048
	ds_read_b128 v[192:195], v147 offset:3072
	ds_read_b128 v[196:199], v147 offset:4096
	ds_read_b128 v[200:203], v147 offset:5120
	ds_read_b128 v[204:207], v147 offset:6144
	ds_read_b128 v[208:211], v147 offset:7168
	global_load_lds_dwordx4 v[212:213], off
	v_lshl_add_u64 v[212:213], s[44:45], 0, v[138:139]
	s_add_i32 m0, s21, 0xe000
	s_nop 0
	global_load_lds_dwordx4 v[212:213], off
	s_waitcnt vmcnt(8)
	s_waitcnt lgkmcnt(0)
	s_barrier
	v_mfma_f32_16x16x32_bf16 v[124:127], v[148:151], v[180:183], 0
	v_mfma_f32_16x16x32_bf16 v[120:123], v[156:159], v[180:183], 0
	v_mfma_f32_16x16x32_bf16 v[116:119], v[148:151], v[188:191], 0
	v_mfma_f32_16x16x32_bf16 v[112:115], v[156:159], v[188:191], 0
	v_mfma_f32_16x16x32_bf16 v[100:103], v[148:151], v[196:199], 0
	v_mfma_f32_16x16x32_bf16 v[96:99], v[156:159], v[196:199], 0
	v_mfma_f32_16x16x32_bf16 v[84:87], v[148:151], v[204:207], 0
	v_mfma_f32_16x16x32_bf16 v[80:83], v[156:159], v[204:207], 0
	v_mfma_f32_16x16x32_bf16 v[124:127], v[152:155], v[184:187], v[124:127]
	v_mfma_f32_16x16x32_bf16 v[120:123], v[160:163], v[184:187], v[120:123]
	v_mfma_f32_16x16x32_bf16 v[116:119], v[152:155], v[192:195], v[116:119]
	v_mfma_f32_16x16x32_bf16 v[112:115], v[160:163], v[192:195], v[112:115]
	v_mfma_f32_16x16x32_bf16 v[100:103], v[152:155], v[200:203], v[100:103]
	v_mfma_f32_16x16x32_bf16 v[96:99], v[160:163], v[200:203], v[96:99]
	v_mfma_f32_16x16x32_bf16 v[84:87], v[152:155], v[208:211], v[84:87]
	v_mfma_f32_16x16x32_bf16 v[80:83], v[160:163], v[208:211], v[80:83]
	v_mfma_f32_16x16x32_bf16 v[108:111], v[164:167], v[180:183], 0
	v_mfma_f32_16x16x32_bf16 v[104:107], v[172:175], v[180:183], 0
	v_mfma_f32_16x16x32_bf16 v[92:95], v[164:167], v[188:191], 0
	v_mfma_f32_16x16x32_bf16 v[88:91], v[172:175], v[188:191], 0
	v_mfma_f32_16x16x32_bf16 v[76:79], v[164:167], v[196:199], 0
	v_mfma_f32_16x16x32_bf16 v[72:75], v[172:175], v[196:199], 0
	v_mfma_f32_16x16x32_bf16 v[68:71], v[164:167], v[204:207], 0
	v_mfma_f32_16x16x32_bf16 v[64:67], v[172:175], v[204:207], 0
	v_mfma_f32_16x16x32_bf16 v[108:111], v[168:171], v[184:187], v[108:111]
	v_mfma_f32_16x16x32_bf16 v[104:107], v[176:179], v[184:187], v[104:107]
	v_mfma_f32_16x16x32_bf16 v[92:95], v[168:171], v[192:195], v[92:95]
	v_mfma_f32_16x16x32_bf16 v[88:91], v[176:179], v[192:195], v[88:91]
	v_mfma_f32_16x16x32_bf16 v[76:79], v[168:171], v[200:203], v[76:79]
	v_mfma_f32_16x16x32_bf16 v[72:75], v[176:179], v[200:203], v[72:75]
	v_mfma_f32_16x16x32_bf16 v[68:71], v[168:171], v[208:211], v[68:71]
	v_mfma_f32_16x16x32_bf16 v[64:67], v[176:179], v[208:211], v[64:67]
	s_barrier
	s_add_i32 s44, s57, s94
	v_lshl_add_u64 v[212:213], s[46:47], 0, v[132:133]
	s_mov_b32 m0, s44
	ds_read_b128 v[180:183], v147 offset:16384
	ds_read_b128 v[184:187], v147 offset:17408
	ds_read_b128 v[188:191], v147 offset:18432
	ds_read_b128 v[192:195], v147 offset:19456
	ds_read_b128 v[196:199], v147 offset:20480
	ds_read_b128 v[200:203], v147 offset:21504
	ds_read_b128 v[204:207], v147 offset:22528
	ds_read_b128 v[208:211], v147 offset:23552
	global_load_lds_dwordx4 v[212:213], off
	s_add_i32 m0, s44, 0x2000
	s_add_u32 s44, s46, 0x20000
	v_lshl_add_u64 v[214:215], s[46:47], 0, v[128:129]
	s_addc_u32 s45, s47, 0
	s_add_i32 s63, s58, s94
	global_load_lds_dwordx4 v[214:215], off
	v_lshl_add_u64 v[216:217], s[44:45], 0, v[132:133]
	s_mov_b32 m0, s63
	v_lshl_add_u64 v[218:219], s[48:49], 0, v[130:131]
	global_load_lds_dwordx4 v[216:217], off
	v_lshl_add_u64 v[216:217], s[44:45], 0, v[128:129]
	s_add_i32 m0, s63, 0x2000
	s_nop 0
	global_load_lds_dwordx4 v[216:217], off
	v_lshl_add_u64 v[216:217], s[48:49], 0, v[134:135]
	s_mov_b32 m0, s21
	s_nop 0
	global_load_lds_dwordx4 v[216:217], off
	s_mov_b32 m0, s25
	s_nop 0
	global_load_lds_dwordx4 v[218:219], off
	s_waitcnt vmcnt(8)
	s_waitcnt lgkmcnt(0)
	s_barrier
; #define PG8_STAGE(bufoff, gbase, voff) do { _Pragma("unroll") for (int _i = 0; _i < 2; ++_i) \
;         __builtin_amdgcn_global_load_lds((const unsigned*)((const char*)(gbase) + (voff)[_i]), (LAS unsigned*)(lds + (bufoff) + ldsw + _i * 8192), 16, 0, 0); } while (0)
; #define PG8_LDA(dst, b, h) do { _Pragma("unroll") for (int m = 0; m < 4; ++m) _Pragma("unroll") for (int k = 0; k < 2; ++k) dst[m][k] = *(const LAS bf16x8*)(lds + PG8_SA(b, h) + aoff + m * 2048 + k * 1024); } while (0)
; #define PG8_LDB(dst, b, h) do { _Pragma("unroll") for (int n = 0; n < 2; ++n) _Pragma("unroll") for (int k = 0; k < 2; ++k) dst[n][k] = *(const LAS bf16x8*)(lds + PG8_SB(b, h) + boff + n * 2048 + k * 1024); } while (0)
; #define PG8_MMA(ai, bj, At, Bt) do { __builtin_amdgcn_s_setprio(1); _Pragma("unroll") for (int m = 0; m < 4; ++m) _Pragma("unroll") for (int n = 0; n < 2; ++n) _Pragma("unroll") for (int k = 0; k < 2; ++k) \
;         acc[ai][bj][m][n] = __builtin_amdgcn_mfma_f32_16x16x32_bf16(Bt[n][k], At[m][k], acc[ai][bj][m][n], 0, 0, 0); __builtin_amdgcn_s_setprio(0); } while (0)
; #define PG8_WAIT_V(n) asm volatile("s_waitcnt vmcnt(" #n ")" ::: "memory")
; #define PG8_WAIT_L(n) asm volatile("s_waitcnt lgkmcnt(" #n ")" ::: "memory")
; #define PG8_BAR __builtin_amdgcn_s_barrier()
; #define PG8_SCHED __builtin_amdgcn_sched_barrier(0)
; template <class Epi>
; DI void gemm_phase(LAS unsigned char* lds, const int wid, const Gemm g, const Order& S, const Epi& E) {
;     ...
;             PG8_LDA(At, 0, 1); PG8_STAGE(PG8_SB(0, 0), b2, voffB); PG8_STAGE(PG8_SB(0, 1), b2 + hstepB, voffB); PG8_STAGE(PG8_SA(0, 0), a2, voffA);
;             PG8_WAIT_V(8); PG8_WAIT_L(0); PG8_BAR; PG8_MMA(1, 0, At, B0); PG8_MMA(1, 1, At, B1); PG8_BAR; PG8_SCHED;
;             PG8_LDB(B0, 1, 0); PG8_LDB(B1, 1, 1); PG8_SCHED; PG8_LDA(At, 1, 0); PG8_STAGE(PG8_SA(0, 1), a2 + hstepA, voffA);
;             PG8_WAIT_V(8); PG8_WAIT_L(0); PG8_BAR; PG8_MMA(0, 0, At, B0); PG8_MMA(0, 1, At, B1); PG8_BAR; PG8_SCHED;
	v_mfma_f32_16x16x32_bf16 v[60:63], v[148:151], v[180:183], 0
	v_mfma_f32_16x16x32_bf16 v[56:59], v[156:159], v[180:183], 0
	v_mfma_f32_16x16x32_bf16 v[52:55], v[148:151], v[188:191], 0
	v_mfma_f32_16x16x32_bf16 v[48:51], v[156:159], v[188:191], 0
	v_mfma_f32_16x16x32_bf16 v[36:39], v[148:151], v[196:199], 0
	v_mfma_f32_16x16x32_bf16 v[32:35], v[156:159], v[196:199], 0
	v_mfma_f32_16x16x32_bf16 v[20:23], v[148:151], v[204:207], 0
	v_mfma_f32_16x16x32_bf16 v[16:19], v[156:159], v[204:207], 0
	v_mfma_f32_16x16x32_bf16 v[60:63], v[152:155], v[184:187], v[60:63]
	v_mfma_f32_16x16x32_bf16 v[56:59], v[160:163], v[184:187], v[56:59]
	v_mfma_f32_16x16x32_bf16 v[52:55], v[152:155], v[192:195], v[52:55]
	v_mfma_f32_16x16x32_bf16 v[48:51], v[160:163], v[192:195], v[48:51]
	v_mfma_f32_16x16x32_bf16 v[36:39], v[152:155], v[200:203], v[36:39]
	v_mfma_f32_16x16x32_bf16 v[32:35], v[160:163], v[200:203], v[32:35]
	v_mfma_f32_16x16x32_bf16 v[20:23], v[152:155], v[208:211], v[20:23]
	v_mfma_f32_16x16x32_bf16 v[16:19], v[160:163], v[208:211], v[16:19]
	v_mfma_f32_16x16x32_bf16 v[44:47], v[164:167], v[180:183], 0
	v_mfma_f32_16x16x32_bf16 v[40:43], v[172:175], v[180:183], 0
	v_mfma_f32_16x16x32_bf16 v[28:31], v[164:167], v[188:191], 0
	v_mfma_f32_16x16x32_bf16 v[24:27], v[172:175], v[188:191], 0
	v_mfma_f32_16x16x32_bf16 v[12:15], v[164:167], v[196:199], 0
	v_mfma_f32_16x16x32_bf16 v[8:11], v[172:175], v[196:199], 0
	v_mfma_f32_16x16x32_bf16 v[4:7], v[164:167], v[204:207], 0
	v_mfma_f32_16x16x32_bf16 v[0:3], v[172:175], v[204:207], 0
	v_mfma_f32_16x16x32_bf16 v[44:47], v[168:171], v[184:187], v[44:47]
	v_mfma_f32_16x16x32_bf16 v[40:43], v[176:179], v[184:187], v[40:43]
	v_mfma_f32_16x16x32_bf16 v[28:31], v[168:171], v[192:195], v[28:31]
	v_mfma_f32_16x16x32_bf16 v[24:27], v[176:179], v[192:195], v[24:27]
	v_mfma_f32_16x16x32_bf16 v[12:15], v[168:171], v[200:203], v[12:15]
	v_mfma_f32_16x16x32_bf16 v[8:11], v[176:179], v[200:203], v[8:11]
	v_mfma_f32_16x16x32_bf16 v[4:7], v[168:171], v[208:211], v[4:7]
	v_mfma_f32_16x16x32_bf16 v[0:3], v[176:179], v[208:211], v[0:3]
	s_barrier
	s_add_i32 s63, 0, 0x18000
	s_add_i32 s64, 0, 0x1c000
	v_add_u32_e32 v160, s63, v144
	v_add_u32_e32 v176, s64, v144
	ds_read_b128 v[148:151], v160
	ds_read_b128 v[152:155], v160 offset:1024
	ds_read_b128 v[156:159], v160 offset:2048
	ds_read_b128 v[160:163], v160 offset:3072
	ds_read_b128 v[164:167], v176
	ds_read_b128 v[168:171], v176 offset:1024
	ds_read_b128 v[172:175], v176 offset:2048
	ds_read_b128 v[176:179], v176 offset:3072
	s_add_u32 s44, s48, 0x30000
	s_addc_u32 s45, s49, 0
	s_mov_b32 m0, s26
	v_lshl_add_u64 v[220:221], s[44:45], 0, v[134:135]
	ds_read_b128 v[180:183], v147 offset:32768
	ds_read_b128 v[184:187], v147 offset:33792
	ds_read_b128 v[188:191], v147 offset:34816
	ds_read_b128 v[192:195], v147 offset:35840
	ds_read_b128 v[196:199], v147 offset:36864
	ds_read_b128 v[200:203], v147 offset:37888
	ds_read_b128 v[204:207], v147 offset:38912
	ds_read_b128 v[208:211], v147 offset:39936
	global_load_lds_dwordx4 v[220:221], off
	v_lshl_add_u64 v[220:221], s[44:45], 0, v[130:131]
	s_mov_b32 m0, s27
	s_nop 0
	global_load_lds_dwordx4 v[220:221], off
	s_waitcnt vmcnt(8)
	s_waitcnt lgkmcnt(0)
	s_barrier
	v_mfma_f32_16x16x32_bf16 v[124:127], v[148:151], v[180:183], v[124:127]
	v_mfma_f32_16x16x32_bf16 v[120:123], v[156:159], v[180:183], v[120:123]
	v_mfma_f32_16x16x32_bf16 v[116:119], v[148:151], v[188:191], v[116:119]
	v_mfma_f32_16x16x32_bf16 v[112:115], v[156:159], v[188:191], v[112:115]
	v_mfma_f32_16x16x32_bf16 v[100:103], v[148:151], v[196:199], v[100:103]
	v_mfma_f32_16x16x32_bf16 v[96:99], v[156:159], v[196:199], v[96:99]
	v_mfma_f32_16x16x32_bf16 v[84:87], v[148:151], v[204:207], v[84:87]
	v_mfma_f32_16x16x32_bf16 v[80:83], v[156:159], v[204:207], v[80:83]
	v_mfma_f32_16x16x32_bf16 v[124:127], v[152:155], v[184:187], v[124:127]
	v_mfma_f32_16x16x32_bf16 v[120:123], v[160:163], v[184:187], v[120:123]
	v_mfma_f32_16x16x32_bf16 v[116:119], v[152:155], v[192:195], v[116:119]
	v_mfma_f32_16x16x32_bf16 v[112:115], v[160:163], v[192:195], v[112:115]
	v_mfma_f32_16x16x32_bf16 v[100:103], v[152:155], v[200:203], v[100:103]
	v_mfma_f32_16x16x32_bf16 v[96:99], v[160:163], v[200:203], v[96:99]
	v_mfma_f32_16x16x32_bf16 v[84:87], v[152:155], v[208:211], v[84:87]
	v_mfma_f32_16x16x32_bf16 v[80:83], v[160:163], v[208:211], v[80:83]
	v_mfma_f32_16x16x32_bf16 v[108:111], v[164:167], v[180:183], v[108:111]
	v_mfma_f32_16x16x32_bf16 v[104:107], v[172:175], v[180:183], v[104:107]
	v_mfma_f32_16x16x32_bf16 v[92:95], v[164:167], v[188:191], v[92:95]
	v_mfma_f32_16x16x32_bf16 v[88:91], v[172:175], v[188:191], v[88:91]
	v_mfma_f32_16x16x32_bf16 v[76:79], v[164:167], v[196:199], v[76:79]
	v_mfma_f32_16x16x32_bf16 v[72:75], v[172:175], v[196:199], v[72:75]
	v_mfma_f32_16x16x32_bf16 v[68:71], v[164:167], v[204:207], v[68:71]
	v_mfma_f32_16x16x32_bf16 v[64:67], v[172:175], v[204:207], v[64:67]
	v_mfma_f32_16x16x32_bf16 v[108:111], v[168:171], v[184:187], v[108:111]
	v_mfma_f32_16x16x32_bf16 v[104:107], v[176:179], v[184:187], v[104:107]
	v_mfma_f32_16x16x32_bf16 v[92:95], v[168:171], v[192:195], v[92:95]
	v_mfma_f32_16x16x32_bf16 v[88:91], v[176:179], v[192:195], v[88:91]
	v_mfma_f32_16x16x32_bf16 v[76:79], v[168:171], v[200:203], v[76:79]
	v_mfma_f32_16x16x32_bf16 v[72:75], v[176:179], v[200:203], v[72:75]
	v_mfma_f32_16x16x32_bf16 v[68:71], v[168:171], v[208:211], v[68:71]
	v_mfma_f32_16x16x32_bf16 v[64:67], v[176:179], v[208:211], v[64:67]
	s_barrier
; #define PG8_STAGE(bufoff, gbase, voff) do { _Pragma("unroll") for (int _i = 0; _i < 2; ++_i) \
;         __builtin_amdgcn_global_load_lds((const unsigned*)((const char*)(gbase) + (voff)[_i]), (LAS unsigned*)(lds + (bufoff) + ldsw + _i * 8192), 16, 0, 0); } while (0)
; #define PG8_LDA(dst, b, h) do { _Pragma("unroll") for (int m = 0; m < 4; ++m) _Pragma("unroll") for (int k = 0; k < 2; ++k) dst[m][k] = *(const LAS bf16x8*)(lds + PG8_SA(b, h) + aoff + m * 2048 + k * 1024); } while (0)
; #define PG8_LDB(dst, b, h) do { _Pragma("unroll") for (int n = 0; n < 2; ++n) _Pragma("unroll") for (int k = 0; k < 2; ++k) dst[n][k] = *(const LAS bf16x8*)(lds + PG8_SB(b, h) + boff + n * 2048 + k * 1024); } while (0)
; #define PG8_MMA(ai, bj, At, Bt) do { __builtin_amdgcn_s_setprio(1); _Pragma("unroll") for (int m = 0; m < 4; ++m) _Pragma("unroll") for (int n = 0; n < 2; ++n) _Pragma("unroll") for (int k = 0; k < 2; ++k) \
;         acc[ai][bj][m][n] = __builtin_amdgcn_mfma_f32_16x16x32_bf16(Bt[n][k], At[m][k], acc[ai][bj][m][n], 0, 0, 0); __builtin_amdgcn_s_setprio(0); } while (0)
; #define PG8_WAIT_V(n) asm volatile("s_waitcnt vmcnt(" #n ")" ::: "memory")
; #define PG8_WAIT_L(n) asm volatile("s_waitcnt lgkmcnt(" #n ")" ::: "memory")
; template <class Epi>
; DI void gemm_phase(LAS unsigned char* lds, const int wid, const Gemm g, const Order& S, const Epi& E) {
;     ...
;             PG8_LDB(B0, 0, 0); PG8_LDB(B1, 0, 1); PG8_SCHED; PG8_LDA(At, 0, 0); PG8_STAGE(PG8_SA(1, 1), a1 + hstepA, voffA);
;             PG8_WAIT_V(8); PG8_WAIT_L(0); PG8_BAR; PG8_MMA(0, 0, At, B0); PG8_MMA(0, 1, At, B1); PG8_BAR; PG8_SCHED;
;             PG8_LDA(At, 0, 1); PG8_STAGE(PG8_SB(0, 0), b2, voffB); PG8_STAGE(PG8_SB(0, 1), b2 + hstepB, voffB); PG8_STAGE(PG8_SA(0, 0), a2, voffA);
;             PG8_WAIT_V(8); PG8_WAIT_L(0); PG8_BAR; PG8_MMA(1, 0, At, B0); PG8_MMA(1, 1, At, B1); PG8_BAR; PG8_SCHED;
;             PG8_LDB(B0, 1, 0); PG8_LDB(B1, 1, 1); PG8_SCHED; PG8_LDA(At, 1, 0); PG8_STAGE(PG8_SA(0, 1), a2 + hstepA, voffA);
;             PG8_WAIT_V(8); PG8_WAIT_L(0); PG8_BAR; PG8_MMA(0, 0, At, B0); PG8_MMA(0, 1, At, B1); PG8_BAR; PG8_SCHED;
;             PG8_LDA(At, 1, 1); PG8_STAGE(PG8_SB(1, 0), b3, voffB); PG8_STAGE(PG8_SB(1, 1), b3 + hstepB, voffB); PG8_STAGE(PG8_SA(1, 0), a3, voffA);
;             PG8_WAIT_V(8); PG8_WAIT_L(0); PG8_BAR; PG8_MMA(1, 0, At, B0); PG8_MMA(1, 1, At, B1); PG8_BAR; PG8_SCHED;
	s_add_i32 s44, s63, s94
	v_lshl_add_u64 v[212:213], v[212:213], 0, s[30:31]
	s_mov_b32 m0, s44
	ds_read_b128 v[180:183], v147 offset:49152
	ds_read_b128 v[184:187], v147 offset:50176
	ds_read_b128 v[188:191], v147 offset:51200
	ds_read_b128 v[192:195], v147 offset:52224
	ds_read_b128 v[196:199], v147 offset:53248
	ds_read_b128 v[200:203], v147 offset:54272
	ds_read_b128 v[204:207], v147 offset:55296
	ds_read_b128 v[208:211], v147 offset:56320
	global_load_lds_dwordx4 v[212:213], off
	s_add_i32 m0, s44, 0x2000
	s_add_u32 s44, s46, 0x20080
	v_lshl_add_u64 v[212:213], v[214:215], 0, s[30:31]
	s_addc_u32 s45, s47, 0
	s_add_i32 s46, s64, s94
	global_load_lds_dwordx4 v[212:213], off
	v_lshl_add_u64 v[212:213], s[44:45], 0, v[132:133]
	s_mov_b32 m0, s46
	s_nop 0
	global_load_lds_dwordx4 v[212:213], off
	v_lshl_add_u64 v[212:213], s[44:45], 0, v[128:129]
	s_add_i32 m0, s46, 0x2000
	s_nop 0
	global_load_lds_dwordx4 v[212:213], off
	v_lshl_add_u64 v[212:213], v[216:217], 0, s[30:31]
	s_mov_b32 m0, s52
	s_nop 0
	global_load_lds_dwordx4 v[212:213], off
	v_lshl_add_u64 v[212:213], v[218:219], 0, s[30:31]
	s_mov_b32 m0, s53
	s_nop 0
	global_load_lds_dwordx4 v[212:213], off
	s_waitcnt vmcnt(8)
	s_waitcnt lgkmcnt(0)
	s_barrier
	v_mfma_f32_16x16x32_bf16 v[60:63], v[148:151], v[180:183], v[60:63]
	v_mfma_f32_16x16x32_bf16 v[56:59], v[156:159], v[180:183], v[56:59]
	v_mfma_f32_16x16x32_bf16 v[52:55], v[148:151], v[188:191], v[52:55]
	v_mfma_f32_16x16x32_bf16 v[48:51], v[156:159], v[188:191], v[48:51]
	v_mfma_f32_16x16x32_bf16 v[36:39], v[148:151], v[196:199], v[36:39]
	v_mfma_f32_16x16x32_bf16 v[32:35], v[156:159], v[196:199], v[32:35]
	v_mfma_f32_16x16x32_bf16 v[20:23], v[148:151], v[204:207], v[20:23]
	v_mfma_f32_16x16x32_bf16 v[16:19], v[156:159], v[204:207], v[16:19]
	v_mfma_f32_16x16x32_bf16 v[60:63], v[152:155], v[184:187], v[60:63]
	v_mfma_f32_16x16x32_bf16 v[56:59], v[160:163], v[184:187], v[56:59]
	v_mfma_f32_16x16x32_bf16 v[52:55], v[152:155], v[192:195], v[52:55]
	v_mfma_f32_16x16x32_bf16 v[48:51], v[160:163], v[192:195], v[48:51]
	v_mfma_f32_16x16x32_bf16 v[36:39], v[152:155], v[200:203], v[36:39]
	v_mfma_f32_16x16x32_bf16 v[32:35], v[160:163], v[200:203], v[32:35]
	v_mfma_f32_16x16x32_bf16 v[20:23], v[152:155], v[208:211], v[20:23]
	v_mfma_f32_16x16x32_bf16 v[16:19], v[160:163], v[208:211], v[16:19]
	v_mfma_f32_16x16x32_bf16 v[44:47], v[164:167], v[180:183], v[44:47]
	v_mfma_f32_16x16x32_bf16 v[40:43], v[172:175], v[180:183], v[40:43]
	v_mfma_f32_16x16x32_bf16 v[28:31], v[164:167], v[188:191], v[28:31]
	v_mfma_f32_16x16x32_bf16 v[24:27], v[172:175], v[188:191], v[24:27]
	v_mfma_f32_16x16x32_bf16 v[12:15], v[164:167], v[196:199], v[12:15]
	v_mfma_f32_16x16x32_bf16 v[8:11], v[172:175], v[196:199], v[8:11]
	v_mfma_f32_16x16x32_bf16 v[4:7], v[164:167], v[204:207], v[4:7]
	v_mfma_f32_16x16x32_bf16 v[0:3], v[172:175], v[204:207], v[0:3]
	v_mfma_f32_16x16x32_bf16 v[44:47], v[168:171], v[184:187], v[44:47]
	v_mfma_f32_16x16x32_bf16 v[40:43], v[176:179], v[184:187], v[40:43]
	v_mfma_f32_16x16x32_bf16 v[28:31], v[168:171], v[192:195], v[28:31]
	v_mfma_f32_16x16x32_bf16 v[24:27], v[176:179], v[192:195], v[24:27]
	v_mfma_f32_16x16x32_bf16 v[12:15], v[168:171], v[200:203], v[12:15]
	v_mfma_f32_16x16x32_bf16 v[8:11], v[176:179], v[200:203], v[8:11]
	v_mfma_f32_16x16x32_bf16 v[4:7], v[168:171], v[208:211], v[4:7]
	v_mfma_f32_16x16x32_bf16 v[0:3], v[176:179], v[208:211], v[0:3]
	s_barrier
	s_add_i32 s62, s62, 2
	s_add_u32 s39, s39, 0x100
	s_addc_u32 s61, s61, 0
	s_cmp_gt_u32 s62, 5
	s_mov_b64 s[44:45], s[12:13]
	s_cbranch_scc0 .LBB0_790
	s_branch .Lpeel_exit_3
.LBB0_790:
	ds_read_b128 v[148:151], v145
	ds_read_b128 v[152:155], v145 offset:1024
	ds_read_b128 v[156:159], v145 offset:2048
	ds_read_b128 v[160:163], v145 offset:3072
	ds_read_b128 v[164:167], v146
	ds_read_b128 v[168:171], v146 offset:1024
	ds_read_b128 v[172:175], v146 offset:2048
	ds_read_b128 v[176:179], v146 offset:3072
	s_add_u32 s12, s44, 0x100
	s_addc_u32 s13, s45, 0
	s_cmp_eq_u32 s62, 4
	s_cselect_b32 s49, s41, s13
	s_cselect_b32 s48, s40, s12
	s_cselect_b32 s47, s29, s61
	s_cselect_b32 s46, s37, s39
	v_lshl_add_u64 v[212:213], s[44:45], 0, v[136:137]
	s_add_i32 m0, s21, 0xc000
	ds_read_b128 v[180:183], v147
	ds_read_b128 v[184:187], v147 offset:1024
	ds_read_b128 v[188:191], v147 offset:2048
	ds_read_b128 v[192:195], v147 offset:3072
	ds_read_b128 v[196:199], v147 offset:4096
	ds_read_b128 v[200:203], v147 offset:5120
	ds_read_b128 v[204:207], v147 offset:6144
	ds_read_b128 v[208:211], v147 offset:7168
	global_load_lds_dwordx4 v[212:213], off
	v_lshl_add_u64 v[212:213], s[44:45], 0, v[138:139]
	s_add_i32 m0, s21, 0xe000
	s_nop 0
	global_load_lds_dwordx4 v[212:213], off
	s_waitcnt vmcnt(8)
	s_waitcnt lgkmcnt(0)
	s_barrier
; #define PG8_STAGE(bufoff, gbase, voff) do { _Pragma("unroll") for (int _i = 0; _i < 2; ++_i) \
;         __builtin_amdgcn_global_load_lds((const unsigned*)((const char*)(gbase) + (voff)[_i]), (LAS unsigned*)(lds + (bufoff) + ldsw + _i * 8192), 16, 0, 0); } while (0)
; #define PG8_LDA(dst, b, h) do { _Pragma("unroll") for (int m = 0; m < 4; ++m) _Pragma("unroll") for (int k = 0; k < 2; ++k) dst[m][k] = *(const LAS bf16x8*)(lds + PG8_SA(b, h) + aoff + m * 2048 + k * 1024); } while (0)
; #define PG8_LDB(dst, b, h) do { _Pragma("unroll") for (int n = 0; n < 2; ++n) _Pragma("unroll") for (int k = 0; k < 2; ++k) dst[n][k] = *(const LAS bf16x8*)(lds + PG8_SB(b, h) + boff + n * 2048 + k * 1024); } while (0)
; #define PG8_MMA(ai, bj, At, Bt) do { __builtin_amdgcn_s_setprio(1); _Pragma("unroll") for (int m = 0; m < 4; ++m) _Pragma("unroll") for (int n = 0; n < 2; ++n) _Pragma("unroll") for (int k = 0; k < 2; ++k) \
;         acc[ai][bj][m][n] = __builtin_amdgcn_mfma_f32_16x16x32_bf16(Bt[n][k], At[m][k], acc[ai][bj][m][n], 0, 0, 0); __builtin_amdgcn_s_setprio(0); } while (0)
; #define PG8_WAIT_V(n) asm volatile("s_waitcnt vmcnt(" #n ")" ::: "memory")
; #define PG8_WAIT_L(n) asm volatile("s_waitcnt lgkmcnt(" #n ")" ::: "memory")
; #define PG8_BAR __builtin_amdgcn_s_barrier()
; #define PG8_SCHED __builtin_amdgcn_sched_barrier(0)
; template <class Epi>
; DI void gemm_phase(LAS unsigned char* lds, const int wid, const Gemm g, const Order& S, const Epi& E) {
;     ...
;             PG8_LDB(B0, 0, 0); PG8_LDB(B1, 0, 1); PG8_SCHED; PG8_LDA(At, 0, 0); PG8_STAGE(PG8_SA(1, 1), a1 + hstepA, voffA);
;             PG8_WAIT_V(8); PG8_WAIT_L(0); PG8_BAR; PG8_MMA(0, 0, At, B0); PG8_MMA(0, 1, At, B1); PG8_BAR; PG8_SCHED;
;             PG8_LDA(At, 0, 1); PG8_STAGE(PG8_SB(0, 0), b2, voffB); PG8_STAGE(PG8_SB(0, 1), b2 + hstepB, voffB); PG8_STAGE(PG8_SA(0, 0), a2, voffA);
;             PG8_WAIT_V(8); PG8_WAIT_L(0); PG8_BAR; PG8_MMA(1, 0, At, B0); PG8_MMA(1, 1, At, B1); PG8_BAR; PG8_SCHED;
	v_mfma_f32_16x16x32_bf16 v[124:127], v[148:151], v[180:183], v[124:127]
	v_mfma_f32_16x16x32_bf16 v[120:123], v[156:159], v[180:183], v[120:123]
	v_mfma_f32_16x16x32_bf16 v[116:119], v[148:151], v[188:191], v[116:119]
	v_mfma_f32_16x16x32_bf16 v[112:115], v[156:159], v[188:191], v[112:115]
	v_mfma_f32_16x16x32_bf16 v[100:103], v[148:151], v[196:199], v[100:103]
	v_mfma_f32_16x16x32_bf16 v[96:99], v[156:159], v[196:199], v[96:99]
	v_mfma_f32_16x16x32_bf16 v[84:87], v[148:151], v[204:207], v[84:87]
	v_mfma_f32_16x16x32_bf16 v[80:83], v[156:159], v[204:207], v[80:83]
	v_mfma_f32_16x16x32_bf16 v[124:127], v[152:155], v[184:187], v[124:127]
	v_mfma_f32_16x16x32_bf16 v[120:123], v[160:163], v[184:187], v[120:123]
	v_mfma_f32_16x16x32_bf16 v[116:119], v[152:155], v[192:195], v[116:119]
	v_mfma_f32_16x16x32_bf16 v[112:115], v[160:163], v[192:195], v[112:115]
	v_mfma_f32_16x16x32_bf16 v[100:103], v[152:155], v[200:203], v[100:103]
	v_mfma_f32_16x16x32_bf16 v[96:99], v[160:163], v[200:203], v[96:99]
	v_mfma_f32_16x16x32_bf16 v[84:87], v[152:155], v[208:211], v[84:87]
	v_mfma_f32_16x16x32_bf16 v[80:83], v[160:163], v[208:211], v[80:83]
	v_mfma_f32_16x16x32_bf16 v[108:111], v[164:167], v[180:183], v[108:111]
	v_mfma_f32_16x16x32_bf16 v[104:107], v[172:175], v[180:183], v[104:107]
	v_mfma_f32_16x16x32_bf16 v[92:95], v[164:167], v[188:191], v[92:95]
	v_mfma_f32_16x16x32_bf16 v[88:91], v[172:175], v[188:191], v[88:91]
	v_mfma_f32_16x16x32_bf16 v[76:79], v[164:167], v[196:199], v[76:79]
	v_mfma_f32_16x16x32_bf16 v[72:75], v[172:175], v[196:199], v[72:75]
	v_mfma_f32_16x16x32_bf16 v[68:71], v[164:167], v[204:207], v[68:71]
	v_mfma_f32_16x16x32_bf16 v[64:67], v[172:175], v[204:207], v[64:67]
	v_mfma_f32_16x16x32_bf16 v[108:111], v[168:171], v[184:187], v[108:111]
	v_mfma_f32_16x16x32_bf16 v[104:107], v[176:179], v[184:187], v[104:107]
	v_mfma_f32_16x16x32_bf16 v[92:95], v[168:171], v[192:195], v[92:95]
	v_mfma_f32_16x16x32_bf16 v[88:91], v[176:179], v[192:195], v[88:91]
	v_mfma_f32_16x16x32_bf16 v[76:79], v[168:171], v[200:203], v[76:79]
	v_mfma_f32_16x16x32_bf16 v[72:75], v[176:179], v[200:203], v[72:75]
	v_mfma_f32_16x16x32_bf16 v[68:71], v[168:171], v[208:211], v[68:71]
	v_mfma_f32_16x16x32_bf16 v[64:67], v[176:179], v[208:211], v[64:67]
	s_barrier
	s_add_i32 s44, s57, s94
	v_lshl_add_u64 v[212:213], s[46:47], 0, v[132:133]
	s_mov_b32 m0, s44
	ds_read_b128 v[180:183], v147 offset:16384
	ds_read_b128 v[184:187], v147 offset:17408
	ds_read_b128 v[188:191], v147 offset:18432
	ds_read_b128 v[192:195], v147 offset:19456
	ds_read_b128 v[196:199], v147 offset:20480
	ds_read_b128 v[200:203], v147 offset:21504
	ds_read_b128 v[204:207], v147 offset:22528
	ds_read_b128 v[208:211], v147 offset:23552
	global_load_lds_dwordx4 v[212:213], off
	s_add_i32 m0, s44, 0x2000
	s_add_u32 s44, s46, 0x20000
	v_lshl_add_u64 v[214:215], s[46:47], 0, v[128:129]
	s_addc_u32 s45, s47, 0
	s_add_i32 s63, s58, s94
	global_load_lds_dwordx4 v[214:215], off
	v_lshl_add_u64 v[216:217], s[44:45], 0, v[132:133]
	s_mov_b32 m0, s63
	v_lshl_add_u64 v[218:219], s[48:49], 0, v[130:131]
	global_load_lds_dwordx4 v[216:217], off
	v_lshl_add_u64 v[216:217], s[44:45], 0, v[128:129]
	s_add_i32 m0, s63, 0x2000
	s_nop 0
	global_load_lds_dwordx4 v[216:217], off
	v_lshl_add_u64 v[216:217], s[48:49], 0, v[134:135]
	s_mov_b32 m0, s21
	s_nop 0
	global_load_lds_dwordx4 v[216:217], off
	s_mov_b32 m0, s25
	s_nop 0
	global_load_lds_dwordx4 v[218:219], off
	s_waitcnt vmcnt(8)
	s_waitcnt lgkmcnt(0)
	s_barrier
	v_mfma_f32_16x16x32_bf16 v[60:63], v[148:151], v[180:183], v[60:63]
	v_mfma_f32_16x16x32_bf16 v[56:59], v[156:159], v[180:183], v[56:59]
	v_mfma_f32_16x16x32_bf16 v[52:55], v[148:151], v[188:191], v[52:55]
	v_mfma_f32_16x16x32_bf16 v[48:51], v[156:159], v[188:191], v[48:51]
	v_mfma_f32_16x16x32_bf16 v[36:39], v[148:151], v[196:199], v[36:39]
	v_mfma_f32_16x16x32_bf16 v[32:35], v[156:159], v[196:199], v[32:35]
	v_mfma_f32_16x16x32_bf16 v[20:23], v[148:151], v[204:207], v[20:23]
	v_mfma_f32_16x16x32_bf16 v[16:19], v[156:159], v[204:207], v[16:19]
	v_mfma_f32_16x16x32_bf16 v[60:63], v[152:155], v[184:187], v[60:63]
	v_mfma_f32_16x16x32_bf16 v[56:59], v[160:163], v[184:187], v[56:59]
	v_mfma_f32_16x16x32_bf16 v[52:55], v[152:155], v[192:195], v[52:55]
	v_mfma_f32_16x16x32_bf16 v[48:51], v[160:163], v[192:195], v[48:51]
	v_mfma_f32_16x16x32_bf16 v[36:39], v[152:155], v[200:203], v[36:39]
	v_mfma_f32_16x16x32_bf16 v[32:35], v[160:163], v[200:203], v[32:35]
	v_mfma_f32_16x16x32_bf16 v[20:23], v[152:155], v[208:211], v[20:23]
	v_mfma_f32_16x16x32_bf16 v[16:19], v[160:163], v[208:211], v[16:19]
	v_mfma_f32_16x16x32_bf16 v[44:47], v[164:167], v[180:183], v[44:47]
	v_mfma_f32_16x16x32_bf16 v[40:43], v[172:175], v[180:183], v[40:43]
	v_mfma_f32_16x16x32_bf16 v[28:31], v[164:167], v[188:191], v[28:31]
	v_mfma_f32_16x16x32_bf16 v[24:27], v[172:175], v[188:191], v[24:27]
	v_mfma_f32_16x16x32_bf16 v[12:15], v[164:167], v[196:199], v[12:15]
	v_mfma_f32_16x16x32_bf16 v[8:11], v[172:175], v[196:199], v[8:11]
	v_mfma_f32_16x16x32_bf16 v[4:7], v[164:167], v[204:207], v[4:7]
	v_mfma_f32_16x16x32_bf16 v[0:3], v[172:175], v[204:207], v[0:3]
	v_mfma_f32_16x16x32_bf16 v[44:47], v[168:171], v[184:187], v[44:47]
	v_mfma_f32_16x16x32_bf16 v[40:43], v[176:179], v[184:187], v[40:43]
	v_mfma_f32_16x16x32_bf16 v[28:31], v[168:171], v[192:195], v[28:31]
	v_mfma_f32_16x16x32_bf16 v[24:27], v[176:179], v[192:195], v[24:27]
	v_mfma_f32_16x16x32_bf16 v[12:15], v[168:171], v[200:203], v[12:15]
	v_mfma_f32_16x16x32_bf16 v[8:11], v[176:179], v[200:203], v[8:11]
	v_mfma_f32_16x16x32_bf16 v[4:7], v[168:171], v[208:211], v[4:7]
	v_mfma_f32_16x16x32_bf16 v[0:3], v[176:179], v[208:211], v[0:3]
	s_barrier
; #define PG8_STAGE(bufoff, gbase, voff) do { _Pragma("unroll") for (int _i = 0; _i < 2; ++_i) \
;         __builtin_amdgcn_global_load_lds((const unsigned*)((const char*)(gbase) + (voff)[_i]), (LAS unsigned*)(lds + (bufoff) + ldsw + _i * 8192), 16, 0, 0); } while (0)
; #define PG8_LDA(dst, b, h) do { _Pragma("unroll") for (int m = 0; m < 4; ++m) _Pragma("unroll") for (int k = 0; k < 2; ++k) dst[m][k] = *(const LAS bf16x8*)(lds + PG8_SA(b, h) + aoff + m * 2048 + k * 1024); } while (0)
; #define PG8_LDB(dst, b, h) do { _Pragma("unroll") for (int n = 0; n < 2; ++n) _Pragma("unroll") for (int k = 0; k < 2; ++k) dst[n][k] = *(const LAS bf16x8*)(lds + PG8_SB(b, h) + boff + n * 2048 + k * 1024); } while (0)
; #define PG8_MMA(ai, bj, At, Bt) do { __builtin_amdgcn_s_setprio(1); _Pragma("unroll") for (int m = 0; m < 4; ++m) _Pragma("unroll") for (int n = 0; n < 2; ++n) _Pragma("unroll") for (int k = 0; k < 2; ++k) \
;         acc[ai][bj][m][n] = __builtin_amdgcn_mfma_f32_16x16x32_bf16(Bt[n][k], At[m][k], acc[ai][bj][m][n], 0, 0, 0); __builtin_amdgcn_s_setprio(0); } while (0)
; #define PG8_WAIT_V(n) asm volatile("s_waitcnt vmcnt(" #n ")" ::: "memory")
; #define PG8_WAIT_L(n) asm volatile("s_waitcnt lgkmcnt(" #n ")" ::: "memory")
; #define PG8_BAR __builtin_amdgcn_s_barrier()
; #define PG8_SCHED __builtin_amdgcn_sched_barrier(0)
; template <class Epi>
; DI void gemm_phase(LAS unsigned char* lds, const int wid, const Gemm g, const Order& S, const Epi& E) {
;     ...
;             PG8_LDB(B0, 1, 0); PG8_LDB(B1, 1, 1); PG8_SCHED; PG8_LDA(At, 1, 0); PG8_STAGE(PG8_SA(0, 1), a2 + hstepA, voffA);
;             PG8_WAIT_V(8); PG8_WAIT_L(0); PG8_BAR; PG8_MMA(0, 0, At, B0); PG8_MMA(0, 1, At, B1); PG8_BAR; PG8_SCHED;
;             PG8_LDA(At, 1, 1); PG8_STAGE(PG8_SB(1, 0), b3, voffB); PG8_STAGE(PG8_SB(1, 1), b3 + hstepB, voffB); PG8_STAGE(PG8_SA(1, 0), a3, voffA);
;             PG8_WAIT_V(8); PG8_WAIT_L(0); PG8_BAR; PG8_MMA(1, 0, At, B0); PG8_MMA(1, 1, At, B1); PG8_BAR; PG8_SCHED;
	s_add_i32 s63, 0, 0x18000
	s_add_i32 s64, 0, 0x1c000
	v_add_u32_e32 v160, s63, v144
	v_add_u32_e32 v176, s64, v144
	ds_read_b128 v[148:151], v160
	ds_read_b128 v[152:155], v160 offset:1024
	ds_read_b128 v[156:159], v160 offset:2048
	ds_read_b128 v[160:163], v160 offset:3072
	ds_read_b128 v[164:167], v176
	ds_read_b128 v[168:171], v176 offset:1024
	ds_read_b128 v[172:175], v176 offset:2048
	ds_read_b128 v[176:179], v176 offset:3072
	s_add_u32 s44, s48, 0x30000
	s_addc_u32 s45, s49, 0
	s_mov_b32 m0, s26
	v_lshl_add_u64 v[220:221], s[44:45], 0, v[134:135]
	ds_read_b128 v[180:183], v147 offset:32768
	ds_read_b128 v[184:187], v147 offset:33792
	ds_read_b128 v[188:191], v147 offset:34816
	ds_read_b128 v[192:195], v147 offset:35840
	ds_read_b128 v[196:199], v147 offset:36864
	ds_read_b128 v[200:203], v147 offset:37888
	ds_read_b128 v[204:207], v147 offset:38912
	ds_read_b128 v[208:211], v147 offset:39936
	global_load_lds_dwordx4 v[220:221], off
	v_lshl_add_u64 v[220:221], s[44:45], 0, v[130:131]
	s_mov_b32 m0, s27
	s_nop 0
	global_load_lds_dwordx4 v[220:221], off
	s_waitcnt vmcnt(8)
	s_waitcnt lgkmcnt(0)
	s_barrier
	v_mfma_f32_16x16x32_bf16 v[124:127], v[148:151], v[180:183], v[124:127]
	v_mfma_f32_16x16x32_bf16 v[120:123], v[156:159], v[180:183], v[120:123]
	v_mfma_f32_16x16x32_bf16 v[116:119], v[148:151], v[188:191], v[116:119]
	v_mfma_f32_16x16x32_bf16 v[112:115], v[156:159], v[188:191], v[112:115]
	v_mfma_f32_16x16x32_bf16 v[100:103], v[148:151], v[196:199], v[100:103]
	v_mfma_f32_16x16x32_bf16 v[96:99], v[156:159], v[196:199], v[96:99]
	v_mfma_f32_16x16x32_bf16 v[84:87], v[148:151], v[204:207], v[84:87]
	v_mfma_f32_16x16x32_bf16 v[80:83], v[156:159], v[204:207], v[80:83]
	v_mfma_f32_16x16x32_bf16 v[124:127], v[152:155], v[184:187], v[124:127]
	v_mfma_f32_16x16x32_bf16 v[120:123], v[160:163], v[184:187], v[120:123]
	v_mfma_f32_16x16x32_bf16 v[116:119], v[152:155], v[192:195], v[116:119]
	v_mfma_f32_16x16x32_bf16 v[112:115], v[160:163], v[192:195], v[112:115]
	v_mfma_f32_16x16x32_bf16 v[100:103], v[152:155], v[200:203], v[100:103]
	v_mfma_f32_16x16x32_bf16 v[96:99], v[160:163], v[200:203], v[96:99]
	v_mfma_f32_16x16x32_bf16 v[84:87], v[152:155], v[208:211], v[84:87]
	v_mfma_f32_16x16x32_bf16 v[80:83], v[160:163], v[208:211], v[80:83]
	v_mfma_f32_16x16x32_bf16 v[108:111], v[164:167], v[180:183], v[108:111]
	v_mfma_f32_16x16x32_bf16 v[104:107], v[172:175], v[180:183], v[104:107]
	v_mfma_f32_16x16x32_bf16 v[92:95], v[164:167], v[188:191], v[92:95]
	v_mfma_f32_16x16x32_bf16 v[88:91], v[172:175], v[188:191], v[88:91]
	v_mfma_f32_16x16x32_bf16 v[76:79], v[164:167], v[196:199], v[76:79]
	v_mfma_f32_16x16x32_bf16 v[72:75], v[172:175], v[196:199], v[72:75]
	v_mfma_f32_16x16x32_bf16 v[68:71], v[164:167], v[204:207], v[68:71]
	v_mfma_f32_16x16x32_bf16 v[64:67], v[172:175], v[204:207], v[64:67]
	v_mfma_f32_16x16x32_bf16 v[108:111], v[168:171], v[184:187], v[108:111]
	v_mfma_f32_16x16x32_bf16 v[104:107], v[176:179], v[184:187], v[104:107]
	v_mfma_f32_16x16x32_bf16 v[92:95], v[168:171], v[192:195], v[92:95]
	v_mfma_f32_16x16x32_bf16 v[88:91], v[176:179], v[192:195], v[88:91]
	v_mfma_f32_16x16x32_bf16 v[76:79], v[168:171], v[200:203], v[76:79]
	v_mfma_f32_16x16x32_bf16 v[72:75], v[176:179], v[200:203], v[72:75]
	v_mfma_f32_16x16x32_bf16 v[68:71], v[168:171], v[208:211], v[68:71]
	v_mfma_f32_16x16x32_bf16 v[64:67], v[176:179], v[208:211], v[64:67]
	s_barrier
	s_add_i32 s44, s63, s94
	v_lshl_add_u64 v[212:213], v[212:213], 0, s[30:31]
	s_mov_b32 m0, s44
	ds_read_b128 v[180:183], v147 offset:49152
	ds_read_b128 v[184:187], v147 offset:50176
	ds_read_b128 v[188:191], v147 offset:51200
	ds_read_b128 v[192:195], v147 offset:52224
	ds_read_b128 v[196:199], v147 offset:53248
	ds_read_b128 v[200:203], v147 offset:54272
	ds_read_b128 v[204:207], v147 offset:55296
	ds_read_b128 v[208:211], v147 offset:56320
	global_load_lds_dwordx4 v[212:213], off
	s_add_i32 m0, s44, 0x2000
	s_add_u32 s44, s46, 0x20080
	v_lshl_add_u64 v[212:213], v[214:215], 0, s[30:31]
	s_addc_u32 s45, s47, 0
	s_add_i32 s46, s64, s94
	global_load_lds_dwordx4 v[212:213], off
	v_lshl_add_u64 v[212:213], s[44:45], 0, v[132:133]
	s_mov_b32 m0, s46
	s_nop 0
	global_load_lds_dwordx4 v[212:213], off
	v_lshl_add_u64 v[212:213], s[44:45], 0, v[128:129]
	s_add_i32 m0, s46, 0x2000
	s_nop 0
	global_load_lds_dwordx4 v[212:213], off
	v_lshl_add_u64 v[212:213], v[216:217], 0, s[30:31]
	s_mov_b32 m0, s52
	s_nop 0
	global_load_lds_dwordx4 v[212:213], off
	v_lshl_add_u64 v[212:213], v[218:219], 0, s[30:31]
	s_mov_b32 m0, s53
	s_nop 0
	global_load_lds_dwordx4 v[212:213], off
	s_waitcnt vmcnt(8)
	s_waitcnt lgkmcnt(0)
	s_barrier
	v_mfma_f32_16x16x32_bf16 v[60:63], v[148:151], v[180:183], v[60:63]
	v_mfma_f32_16x16x32_bf16 v[56:59], v[156:159], v[180:183], v[56:59]
	v_mfma_f32_16x16x32_bf16 v[52:55], v[148:151], v[188:191], v[52:55]
	v_mfma_f32_16x16x32_bf16 v[48:51], v[156:159], v[188:191], v[48:51]
	v_mfma_f32_16x16x32_bf16 v[36:39], v[148:151], v[196:199], v[36:39]
	v_mfma_f32_16x16x32_bf16 v[32:35], v[156:159], v[196:199], v[32:35]
	v_mfma_f32_16x16x32_bf16 v[20:23], v[148:151], v[204:207], v[20:23]
	v_mfma_f32_16x16x32_bf16 v[16:19], v[156:159], v[204:207], v[16:19]
	v_mfma_f32_16x16x32_bf16 v[60:63], v[152:155], v[184:187], v[60:63]
	v_mfma_f32_16x16x32_bf16 v[56:59], v[160:163], v[184:187], v[56:59]
	v_mfma_f32_16x16x32_bf16 v[52:55], v[152:155], v[192:195], v[52:55]
	v_mfma_f32_16x16x32_bf16 v[48:51], v[160:163], v[192:195], v[48:51]
	v_mfma_f32_16x16x32_bf16 v[36:39], v[152:155], v[200:203], v[36:39]
	v_mfma_f32_16x16x32_bf16 v[32:35], v[160:163], v[200:203], v[32:35]
	v_mfma_f32_16x16x32_bf16 v[20:23], v[152:155], v[208:211], v[20:23]
	v_mfma_f32_16x16x32_bf16 v[16:19], v[160:163], v[208:211], v[16:19]
	v_mfma_f32_16x16x32_bf16 v[44:47], v[164:167], v[180:183], v[44:47]
	v_mfma_f32_16x16x32_bf16 v[40:43], v[172:175], v[180:183], v[40:43]
	v_mfma_f32_16x16x32_bf16 v[28:31], v[164:167], v[188:191], v[28:31]
	v_mfma_f32_16x16x32_bf16 v[24:27], v[172:175], v[188:191], v[24:27]
	v_mfma_f32_16x16x32_bf16 v[12:15], v[164:167], v[196:199], v[12:15]
	v_mfma_f32_16x16x32_bf16 v[8:11], v[172:175], v[196:199], v[8:11]
	v_mfma_f32_16x16x32_bf16 v[4:7], v[164:167], v[204:207], v[4:7]
	v_mfma_f32_16x16x32_bf16 v[0:3], v[172:175], v[204:207], v[0:3]
	v_mfma_f32_16x16x32_bf16 v[44:47], v[168:171], v[184:187], v[44:47]
	v_mfma_f32_16x16x32_bf16 v[40:43], v[176:179], v[184:187], v[40:43]
	v_mfma_f32_16x16x32_bf16 v[28:31], v[168:171], v[192:195], v[28:31]
	v_mfma_f32_16x16x32_bf16 v[24:27], v[176:179], v[192:195], v[24:27]
	v_mfma_f32_16x16x32_bf16 v[12:15], v[168:171], v[200:203], v[12:15]
	v_mfma_f32_16x16x32_bf16 v[8:11], v[176:179], v[200:203], v[8:11]
	v_mfma_f32_16x16x32_bf16 v[4:7], v[168:171], v[208:211], v[4:7]
	v_mfma_f32_16x16x32_bf16 v[0:3], v[176:179], v[208:211], v[0:3]
	s_barrier
	s_add_i32 s62, s62, 2
	s_add_u32 s39, s39, 0x100
	s_addc_u32 s61, s61, 0
	s_cmp_gt_u32 s62, 5
	s_mov_b64 s[44:45], s[12:13]
	s_cbranch_scc0 .LBB0_790

; #define PG8_STAGE(bufoff, gbase, voff) do { _Pragma("unroll") for (int _i = 0; _i < 2; ++_i) \
;         __builtin_amdgcn_global_load_lds((const unsigned*)((const char*)(gbase) + (voff)[_i]), (LAS unsigned*)(lds + (bufoff) + ldsw + _i * 8192), 16, 0, 0); } while (0)
; #define PG8_LDA(dst, b, h) do { _Pragma("unroll") for (int m = 0; m < 4; ++m) _Pragma("unroll") for (int k = 0; k < 2; ++k) dst[m][k] = *(const LAS bf16x8*)(lds + PG8_SA(b, h) + aoff + m * 2048 + k * 1024); } while (0)
; #define PG8_LDB(dst, b, h) do { _Pragma("unroll") for (int n = 0; n < 2; ++n) _Pragma("unroll") for (int k = 0; k < 2; ++k) dst[n][k] = *(const LAS bf16x8*)(lds + PG8_SB(b, h) + boff + n * 2048 + k * 1024); } while (0)
; #define PG8_MMA(ai, bj, At, Bt) do { __builtin_amdgcn_s_setprio(1); _Pragma("unroll") for (int m = 0; m < 4; ++m) _Pragma("unroll") for (int n = 0; n < 2; ++n) _Pragma("unroll") for (int k = 0; k < 2; ++k) \
;         acc[ai][bj][m][n] = __builtin_amdgcn_mfma_f32_16x16x32_bf16(Bt[n][k], At[m][k], acc[ai][bj][m][n], 0, 0, 0); __builtin_amdgcn_s_setprio(0); } while (0)
; #define PG8_WAIT_V(n) asm volatile("s_waitcnt vmcnt(" #n ")" ::: "memory")
; template <class Epi>
; DI void gemm_phase(LAS unsigned char* lds, const int wid, const Gemm g, const Order& S, const Epi& E) {
;     ...
;         const char* nA = has_next ? (const char*)(g.A + (size_t)nxt.g * g.gsA + (size_t)nxt.pm * BM * g.lda) : cA;
;         const char* nB = has_next ? (const char*)(g.Bt + (size_t)nxt.g * g.gsB + (size_t)nxt.pn * BM * g.ldb) : cB;
;         for (int t = 0; t < nt; t += 2) {
;             const bool last = (t == nt - 2);
;             const char* a1 = cA + (size_t)(t + 1) * kstep;
;             const char* a2 = last ? nA : cA + (size_t)(t + 2) * kstep; const char* b2 = last ? nB : cB + (size_t)(t + 2) * kstep;
;             const char* a3 = a2 + kstep; const char* b3 = b2 + kstep;
;             PG8_LDB(B0, 0, 0); PG8_LDB(B1, 0, 1); PG8_SCHED; PG8_LDA(At, 0, 0); PG8_STAGE(PG8_SA(1, 1), a1 + hstepA, voffA);
;             PG8_WAIT_V(8); PG8_WAIT_L(0); PG8_BAR; PG8_MMA(0, 0, At, B0); PG8_MMA(0, 1, At, B1); PG8_BAR; PG8_SCHED;
;             PG8_LDA(At, 0, 1); PG8_STAGE(PG8_SB(0, 0), b2, voffB); PG8_STAGE(PG8_SB(0, 1), b2 + hstepB, voffB); PG8_STAGE(PG8_SA(0, 0), a2, voffA);
;             PG8_WAIT_V(8); PG8_WAIT_L(0); PG8_BAR; PG8_MMA(1, 0, At, B0); PG8_MMA(1, 1, At, B1); PG8_BAR; PG8_SCHED;
.LBB0_988:
	s_add_u32 s54, s36, 0x100
	v_mov_b32_e32 v0, 0
	s_addc_u32 s55, s37, 0
	s_mov_b32 s56, -2
	ds_read_b128 v[152:155], v149
	ds_read_b128 v[156:159], v149 offset:1024
	ds_read_b128 v[160:163], v149 offset:2048
	ds_read_b128 v[164:167], v149 offset:3072
	ds_read_b128 v[168:171], v150
	ds_read_b128 v[172:175], v150 offset:1024
	ds_read_b128 v[176:179], v150 offset:2048
	ds_read_b128 v[180:183], v150 offset:3072
	s_add_u32 s36, s34, 0x100
	s_addc_u32 s37, s35, 0
	s_cmp_eq_u32 s56, 8
	s_cselect_b32 s41, s11, s37
	s_cselect_b32 s40, s10, s36
	s_cselect_b32 s39, s31, s55
	s_cselect_b32 s38, s30, s54
	v_lshl_add_u64 v[146:147], s[34:35], 0, v[138:139]
	s_add_i32 m0, s25, 0xc000
	ds_read_b128 v[184:187], v151
	ds_read_b128 v[188:191], v151 offset:1024
	ds_read_b128 v[192:195], v151 offset:2048
	ds_read_b128 v[196:199], v151 offset:3072
	ds_read_b128 v[200:203], v151 offset:4096
	ds_read_b128 v[204:207], v151 offset:5120
	ds_read_b128 v[208:211], v151 offset:6144
	ds_read_b128 v[212:215], v151 offset:7168
	global_load_lds_dwordx4 v[146:147], off
	v_lshl_add_u64 v[146:147], s[34:35], 0, v[140:141]
	s_add_i32 m0, s25, 0xe000
	s_nop 0
	global_load_lds_dwordx4 v[146:147], off
	s_waitcnt vmcnt(8)
	s_waitcnt lgkmcnt(0)
	s_barrier
	v_mfma_f32_16x16x32_bf16 v[124:127], v[152:155], v[184:187], 0
	v_mfma_f32_16x16x32_bf16 v[120:123], v[160:163], v[184:187], 0
	v_mfma_f32_16x16x32_bf16 v[108:111], v[152:155], v[192:195], 0
	v_mfma_f32_16x16x32_bf16 v[104:107], v[160:163], v[192:195], 0
	v_mfma_f32_16x16x32_bf16 v[92:95], v[152:155], v[200:203], 0
	v_mfma_f32_16x16x32_bf16 v[88:91], v[160:163], v[200:203], 0
	v_mfma_f32_16x16x32_bf16 v[76:79], v[152:155], v[208:211], 0
	v_mfma_f32_16x16x32_bf16 v[72:75], v[160:163], v[208:211], 0
	v_mfma_f32_16x16x32_bf16 v[124:127], v[156:159], v[188:191], v[124:127]
	v_mfma_f32_16x16x32_bf16 v[120:123], v[164:167], v[188:191], v[120:123]
	v_mfma_f32_16x16x32_bf16 v[108:111], v[156:159], v[196:199], v[108:111]
	v_mfma_f32_16x16x32_bf16 v[104:107], v[164:167], v[196:199], v[104:107]
	v_mfma_f32_16x16x32_bf16 v[92:95], v[156:159], v[204:207], v[92:95]
	v_mfma_f32_16x16x32_bf16 v[88:91], v[164:167], v[204:207], v[88:91]
	v_mfma_f32_16x16x32_bf16 v[76:79], v[156:159], v[212:215], v[76:79]
	v_mfma_f32_16x16x32_bf16 v[72:75], v[164:167], v[212:215], v[72:75]
	v_mfma_f32_16x16x32_bf16 v[116:119], v[168:171], v[184:187], 0
	v_mfma_f32_16x16x32_bf16 v[112:115], v[176:179], v[184:187], 0
	v_mfma_f32_16x16x32_bf16 v[100:103], v[168:171], v[192:195], 0
	v_mfma_f32_16x16x32_bf16 v[96:99], v[176:179], v[192:195], 0
	v_mfma_f32_16x16x32_bf16 v[84:87], v[168:171], v[200:203], 0
	v_mfma_f32_16x16x32_bf16 v[80:83], v[176:179], v[200:203], 0
	v_mfma_f32_16x16x32_bf16 v[68:71], v[168:171], v[208:211], 0
	v_mfma_f32_16x16x32_bf16 v[64:67], v[176:179], v[208:211], 0
	v_mfma_f32_16x16x32_bf16 v[116:119], v[172:175], v[188:191], v[116:119]
	v_mfma_f32_16x16x32_bf16 v[112:115], v[180:183], v[188:191], v[112:115]
	v_mfma_f32_16x16x32_bf16 v[100:103], v[172:175], v[196:199], v[100:103]
	v_mfma_f32_16x16x32_bf16 v[96:99], v[180:183], v[196:199], v[96:99]
	v_mfma_f32_16x16x32_bf16 v[84:87], v[172:175], v[204:207], v[84:87]
	v_mfma_f32_16x16x32_bf16 v[80:83], v[180:183], v[204:207], v[80:83]
	v_mfma_f32_16x16x32_bf16 v[68:71], v[172:175], v[212:215], v[68:71]
	v_mfma_f32_16x16x32_bf16 v[64:67], v[180:183], v[212:215], v[64:67]
	s_barrier
	s_add_i32 s34, s48, s94
	v_lshl_add_u64 v[146:147], s[38:39], 0, v[130:131]
	s_mov_b32 m0, s34
	ds_read_b128 v[184:187], v151 offset:16384
	ds_read_b128 v[188:191], v151 offset:17408
	ds_read_b128 v[192:195], v151 offset:18432
	ds_read_b128 v[196:199], v151 offset:19456
	ds_read_b128 v[200:203], v151 offset:20480
	ds_read_b128 v[204:207], v151 offset:21504
	ds_read_b128 v[208:211], v151 offset:22528
	ds_read_b128 v[212:215], v151 offset:23552
	global_load_lds_dwordx4 v[146:147], off
	s_add_i32 m0, s34, 0x2000
	s_add_u32 s34, s38, 0x30000
	v_lshl_add_u64 v[216:217], s[38:39], 0, v[134:135]
	s_addc_u32 s35, s39, 0
	s_add_i32 s57, s49, s94
	global_load_lds_dwordx4 v[216:217], off
	v_lshl_add_u64 v[218:219], s[34:35], 0, v[130:131]
	s_mov_b32 m0, s57
	v_lshl_add_u64 v[220:221], s[40:41], 0, v[132:133]
	global_load_lds_dwordx4 v[218:219], off
	v_lshl_add_u64 v[218:219], s[34:35], 0, v[134:135]
	s_add_i32 m0, s57, 0x2000
	s_nop 0
	global_load_lds_dwordx4 v[218:219], off
	v_lshl_add_u64 v[218:219], s[40:41], 0, v[128:129]
	s_mov_b32 m0, s25
	s_nop 0
	global_load_lds_dwordx4 v[218:219], off
	s_mov_b32 m0, s42
	s_nop 0
	global_load_lds_dwordx4 v[220:221], off
	s_waitcnt vmcnt(8)
	s_waitcnt lgkmcnt(0)
	s_barrier
; #define PG8_STAGE(bufoff, gbase, voff) do { _Pragma("unroll") for (int _i = 0; _i < 2; ++_i) \
;         __builtin_amdgcn_global_load_lds((const unsigned*)((const char*)(gbase) + (voff)[_i]), (LAS unsigned*)(lds + (bufoff) + ldsw + _i * 8192), 16, 0, 0); } while (0)
; #define PG8_LDA(dst, b, h) do { _Pragma("unroll") for (int m = 0; m < 4; ++m) _Pragma("unroll") for (int k = 0; k < 2; ++k) dst[m][k] = *(const LAS bf16x8*)(lds + PG8_SA(b, h) + aoff + m * 2048 + k * 1024); } while (0)
; #define PG8_LDB(dst, b, h) do { _Pragma("unroll") for (int n = 0; n < 2; ++n) _Pragma("unroll") for (int k = 0; k < 2; ++k) dst[n][k] = *(const LAS bf16x8*)(lds + PG8_SB(b, h) + boff + n * 2048 + k * 1024); } while (0)
; #define PG8_MMA(ai, bj, At, Bt) do { __builtin_amdgcn_s_setprio(1); _Pragma("unroll") for (int m = 0; m < 4; ++m) _Pragma("unroll") for (int n = 0; n < 2; ++n) _Pragma("unroll") for (int k = 0; k < 2; ++k) \
;         acc[ai][bj][m][n] = __builtin_amdgcn_mfma_f32_16x16x32_bf16(Bt[n][k], At[m][k], acc[ai][bj][m][n], 0, 0, 0); __builtin_amdgcn_s_setprio(0); } while (0)
; #define PG8_WAIT_V(n) asm volatile("s_waitcnt vmcnt(" #n ")" ::: "memory")
; #define PG8_WAIT_L(n) asm volatile("s_waitcnt lgkmcnt(" #n ")" ::: "memory")
; #define PG8_BAR __builtin_amdgcn_s_barrier()
; #define PG8_SCHED __builtin_amdgcn_sched_barrier(0)
; template <class Epi>
; DI void gemm_phase(LAS unsigned char* lds, const int wid, const Gemm g, const Order& S, const Epi& E) {
;     ...
;             PG8_LDA(At, 0, 1); PG8_STAGE(PG8_SB(0, 0), b2, voffB); PG8_STAGE(PG8_SB(0, 1), b2 + hstepB, voffB); PG8_STAGE(PG8_SA(0, 0), a2, voffA);
;             PG8_WAIT_V(8); PG8_WAIT_L(0); PG8_BAR; PG8_MMA(1, 0, At, B0); PG8_MMA(1, 1, At, B1); PG8_BAR; PG8_SCHED;
;             PG8_LDB(B0, 1, 0); PG8_LDB(B1, 1, 1); PG8_SCHED; PG8_LDA(At, 1, 0); PG8_STAGE(PG8_SA(0, 1), a2 + hstepA, voffA);
;             PG8_WAIT_V(8); PG8_WAIT_L(0); PG8_BAR; PG8_MMA(0, 0, At, B0); PG8_MMA(0, 1, At, B1); PG8_BAR; PG8_SCHED;
	v_mfma_f32_16x16x32_bf16 v[60:63], v[152:155], v[184:187], 0
	v_mfma_f32_16x16x32_bf16 v[56:59], v[160:163], v[184:187], 0
	v_mfma_f32_16x16x32_bf16 v[44:47], v[152:155], v[192:195], 0
	v_mfma_f32_16x16x32_bf16 v[40:43], v[160:163], v[192:195], 0
	v_mfma_f32_16x16x32_bf16 v[28:31], v[152:155], v[200:203], 0
	v_mfma_f32_16x16x32_bf16 v[24:27], v[160:163], v[200:203], 0
	v_mfma_f32_16x16x32_bf16 v[12:15], v[152:155], v[208:211], 0
	v_mfma_f32_16x16x32_bf16 v[8:11], v[160:163], v[208:211], 0
	v_mfma_f32_16x16x32_bf16 v[60:63], v[156:159], v[188:191], v[60:63]
	v_mfma_f32_16x16x32_bf16 v[56:59], v[164:167], v[188:191], v[56:59]
	v_mfma_f32_16x16x32_bf16 v[44:47], v[156:159], v[196:199], v[44:47]
	v_mfma_f32_16x16x32_bf16 v[40:43], v[164:167], v[196:199], v[40:43]
	v_mfma_f32_16x16x32_bf16 v[28:31], v[156:159], v[204:207], v[28:31]
	v_mfma_f32_16x16x32_bf16 v[24:27], v[164:167], v[204:207], v[24:27]
	v_mfma_f32_16x16x32_bf16 v[12:15], v[156:159], v[212:215], v[12:15]
	v_mfma_f32_16x16x32_bf16 v[8:11], v[164:167], v[212:215], v[8:11]
	v_mfma_f32_16x16x32_bf16 v[52:55], v[168:171], v[184:187], 0
	v_mfma_f32_16x16x32_bf16 v[48:51], v[176:179], v[184:187], 0
	v_mfma_f32_16x16x32_bf16 v[36:39], v[168:171], v[192:195], 0
	v_mfma_f32_16x16x32_bf16 v[32:35], v[176:179], v[192:195], 0
	v_mfma_f32_16x16x32_bf16 v[20:23], v[168:171], v[200:203], 0
	v_mfma_f32_16x16x32_bf16 v[16:19], v[176:179], v[200:203], 0
	v_mfma_f32_16x16x32_bf16 v[4:7], v[168:171], v[208:211], 0
	v_mfma_f32_16x16x32_bf16 v[0:3], v[176:179], v[208:211], 0
	v_mfma_f32_16x16x32_bf16 v[52:55], v[172:175], v[188:191], v[52:55]
	v_mfma_f32_16x16x32_bf16 v[48:51], v[180:183], v[188:191], v[48:51]
	v_mfma_f32_16x16x32_bf16 v[36:39], v[172:175], v[196:199], v[36:39]
	v_mfma_f32_16x16x32_bf16 v[32:35], v[180:183], v[196:199], v[32:35]
	v_mfma_f32_16x16x32_bf16 v[20:23], v[172:175], v[204:207], v[20:23]
	v_mfma_f32_16x16x32_bf16 v[16:19], v[180:183], v[204:207], v[16:19]
	v_mfma_f32_16x16x32_bf16 v[4:7], v[172:175], v[212:215], v[4:7]
	v_mfma_f32_16x16x32_bf16 v[0:3], v[180:183], v[212:215], v[0:3]
	s_barrier
	s_add_i32 s57, 0, 0x18000
	v_add_u32_e32 v136, s57, v148
	s_add_i32 s58, 0, 0x1c000
	ds_read_b128 v[152:155], v136
	ds_read_b128 v[156:159], v136 offset:1024
	ds_read_b128 v[160:163], v136 offset:2048
	ds_read_b128 v[164:167], v136 offset:3072
	v_add_u32_e32 v136, s58, v148
	ds_read_b128 v[168:171], v136
	ds_read_b128 v[172:175], v136 offset:1024
	ds_read_b128 v[176:179], v136 offset:2048
	ds_read_b128 v[180:183], v136 offset:3072
	s_add_u32 s34, s40, 0x30000
	s_addc_u32 s35, s41, 0
	s_mov_b32 m0, s43
	v_lshl_add_u64 v[222:223], s[34:35], 0, v[128:129]
	ds_read_b128 v[184:187], v151 offset:32768
	ds_read_b128 v[188:191], v151 offset:33792
	ds_read_b128 v[192:195], v151 offset:34816
	ds_read_b128 v[196:199], v151 offset:35840
	ds_read_b128 v[200:203], v151 offset:36864
	ds_read_b128 v[204:207], v151 offset:37888
	ds_read_b128 v[208:211], v151 offset:38912
	ds_read_b128 v[212:215], v151 offset:39936
	global_load_lds_dwordx4 v[222:223], off
	v_lshl_add_u64 v[222:223], s[34:35], 0, v[132:133]
	s_mov_b32 m0, s44
	s_nop 0
	global_load_lds_dwordx4 v[222:223], off
	s_waitcnt vmcnt(8)
	s_waitcnt lgkmcnt(0)
	s_barrier
	v_mfma_f32_16x16x32_bf16 v[124:127], v[152:155], v[184:187], v[124:127]
	v_mfma_f32_16x16x32_bf16 v[120:123], v[160:163], v[184:187], v[120:123]
	v_mfma_f32_16x16x32_bf16 v[108:111], v[152:155], v[192:195], v[108:111]
	v_mfma_f32_16x16x32_bf16 v[104:107], v[160:163], v[192:195], v[104:107]
	v_mfma_f32_16x16x32_bf16 v[92:95], v[152:155], v[200:203], v[92:95]
	v_mfma_f32_16x16x32_bf16 v[88:91], v[160:163], v[200:203], v[88:91]
	v_mfma_f32_16x16x32_bf16 v[76:79], v[152:155], v[208:211], v[76:79]
	v_mfma_f32_16x16x32_bf16 v[72:75], v[160:163], v[208:211], v[72:75]
	v_mfma_f32_16x16x32_bf16 v[124:127], v[156:159], v[188:191], v[124:127]
	v_mfma_f32_16x16x32_bf16 v[120:123], v[164:167], v[188:191], v[120:123]
	v_mfma_f32_16x16x32_bf16 v[108:111], v[156:159], v[196:199], v[108:111]
	v_mfma_f32_16x16x32_bf16 v[104:107], v[164:167], v[196:199], v[104:107]
	v_mfma_f32_16x16x32_bf16 v[92:95], v[156:159], v[204:207], v[92:95]
	v_mfma_f32_16x16x32_bf16 v[88:91], v[164:167], v[204:207], v[88:91]
	v_mfma_f32_16x16x32_bf16 v[76:79], v[156:159], v[212:215], v[76:79]
	v_mfma_f32_16x16x32_bf16 v[72:75], v[164:167], v[212:215], v[72:75]
	v_mfma_f32_16x16x32_bf16 v[116:119], v[168:171], v[184:187], v[116:119]
	v_mfma_f32_16x16x32_bf16 v[112:115], v[176:179], v[184:187], v[112:115]
	v_mfma_f32_16x16x32_bf16 v[100:103], v[168:171], v[192:195], v[100:103]
	v_mfma_f32_16x16x32_bf16 v[96:99], v[176:179], v[192:195], v[96:99]
	v_mfma_f32_16x16x32_bf16 v[84:87], v[168:171], v[200:203], v[84:87]
	v_mfma_f32_16x16x32_bf16 v[80:83], v[176:179], v[200:203], v[80:83]
	v_mfma_f32_16x16x32_bf16 v[68:71], v[168:171], v[208:211], v[68:71]
	v_mfma_f32_16x16x32_bf16 v[64:67], v[176:179], v[208:211], v[64:67]
	v_mfma_f32_16x16x32_bf16 v[116:119], v[172:175], v[188:191], v[116:119]
	v_mfma_f32_16x16x32_bf16 v[112:115], v[180:183], v[188:191], v[112:115]
	v_mfma_f32_16x16x32_bf16 v[100:103], v[172:175], v[196:199], v[100:103]
	v_mfma_f32_16x16x32_bf16 v[96:99], v[180:183], v[196:199], v[96:99]
	v_mfma_f32_16x16x32_bf16 v[84:87], v[172:175], v[204:207], v[84:87]
	v_mfma_f32_16x16x32_bf16 v[80:83], v[180:183], v[204:207], v[80:83]
	v_mfma_f32_16x16x32_bf16 v[68:71], v[172:175], v[212:215], v[68:71]
	v_mfma_f32_16x16x32_bf16 v[64:67], v[180:183], v[212:215], v[64:67]
	s_barrier
; #define PG8_STAGE(bufoff, gbase, voff) do { _Pragma("unroll") for (int _i = 0; _i < 2; ++_i) \
;         __builtin_amdgcn_global_load_lds((const unsigned*)((const char*)(gbase) + (voff)[_i]), (LAS unsigned*)(lds + (bufoff) + ldsw + _i * 8192), 16, 0, 0); } while (0)
; #define PG8_LDA(dst, b, h) do { _Pragma("unroll") for (int m = 0; m < 4; ++m) _Pragma("unroll") for (int k = 0; k < 2; ++k) dst[m][k] = *(const LAS bf16x8*)(lds + PG8_SA(b, h) + aoff + m * 2048 + k * 1024); } while (0)
; #define PG8_LDB(dst, b, h) do { _Pragma("unroll") for (int n = 0; n < 2; ++n) _Pragma("unroll") for (int k = 0; k < 2; ++k) dst[n][k] = *(const LAS bf16x8*)(lds + PG8_SB(b, h) + boff + n * 2048 + k * 1024); } while (0)
; #define PG8_MMA(ai, bj, At, Bt) do { __builtin_amdgcn_s_setprio(1); _Pragma("unroll") for (int m = 0; m < 4; ++m) _Pragma("unroll") for (int n = 0; n < 2; ++n) _Pragma("unroll") for (int k = 0; k < 2; ++k) \
;         acc[ai][bj][m][n] = __builtin_amdgcn_mfma_f32_16x16x32_bf16(Bt[n][k], At[m][k], acc[ai][bj][m][n], 0, 0, 0); __builtin_amdgcn_s_setprio(0); } while (0)
; #define PG8_WAIT_V(n) asm volatile("s_waitcnt vmcnt(" #n ")" ::: "memory")
; #define PG8_WAIT_L(n) asm volatile("s_waitcnt lgkmcnt(" #n ")" ::: "memory")
; template <class Epi>
; DI void gemm_phase(LAS unsigned char* lds, const int wid, const Gemm g, const Order& S, const Epi& E) {
;     ...
;             PG8_LDB(B0, 0, 0); PG8_LDB(B1, 0, 1); PG8_SCHED; PG8_LDA(At, 0, 0); PG8_STAGE(PG8_SA(1, 1), a1 + hstepA, voffA);
;             PG8_WAIT_V(8); PG8_WAIT_L(0); PG8_BAR; PG8_MMA(0, 0, At, B0); PG8_MMA(0, 1, At, B1); PG8_BAR; PG8_SCHED;
;             PG8_LDA(At, 0, 1); PG8_STAGE(PG8_SB(0, 0), b2, voffB); PG8_STAGE(PG8_SB(0, 1), b2 + hstepB, voffB); PG8_STAGE(PG8_SA(0, 0), a2, voffA);
;             PG8_WAIT_V(8); PG8_WAIT_L(0); PG8_BAR; PG8_MMA(1, 0, At, B0); PG8_MMA(1, 1, At, B1); PG8_BAR; PG8_SCHED;
;             PG8_LDB(B0, 1, 0); PG8_LDB(B1, 1, 1); PG8_SCHED; PG8_LDA(At, 1, 0); PG8_STAGE(PG8_SA(0, 1), a2 + hstepA, voffA);
;             PG8_WAIT_V(8); PG8_WAIT_L(0); PG8_BAR; PG8_MMA(0, 0, At, B0); PG8_MMA(0, 1, At, B1); PG8_BAR; PG8_SCHED;
;             PG8_LDA(At, 1, 1); PG8_STAGE(PG8_SB(1, 0), b3, voffB); PG8_STAGE(PG8_SB(1, 1), b3 + hstepB, voffB); PG8_STAGE(PG8_SA(1, 0), a3, voffA);
;             PG8_WAIT_V(8); PG8_WAIT_L(0); PG8_BAR; PG8_MMA(1, 0, At, B0); PG8_MMA(1, 1, At, B1); PG8_BAR; PG8_SCHED;
	s_add_i32 s34, s57, s94
	v_lshl_add_u64 v[146:147], v[146:147], 0, s[16:17]
	s_mov_b32 m0, s34
	ds_read_b128 v[184:187], v151 offset:49152
	ds_read_b128 v[188:191], v151 offset:50176
	ds_read_b128 v[192:195], v151 offset:51200
	ds_read_b128 v[196:199], v151 offset:52224
	ds_read_b128 v[200:203], v151 offset:53248
	ds_read_b128 v[204:207], v151 offset:54272
	ds_read_b128 v[208:211], v151 offset:55296
	ds_read_b128 v[212:215], v151 offset:56320
	global_load_lds_dwordx4 v[146:147], off
	s_add_i32 m0, s34, 0x2000
	s_add_u32 s34, s38, 0x30080
	v_lshl_add_u64 v[146:147], v[216:217], 0, s[16:17]
	s_addc_u32 s35, s39, 0
	s_add_i32 s38, s58, s94
	global_load_lds_dwordx4 v[146:147], off
	v_lshl_add_u64 v[146:147], s[34:35], 0, v[130:131]
	s_mov_b32 m0, s38
	s_nop 0
	global_load_lds_dwordx4 v[146:147], off
	v_lshl_add_u64 v[146:147], s[34:35], 0, v[134:135]
	s_add_i32 m0, s38, 0x2000
	s_nop 0
	global_load_lds_dwordx4 v[146:147], off
	v_lshl_add_u64 v[146:147], v[218:219], 0, s[16:17]
	s_mov_b32 m0, s46
	s_nop 0
	global_load_lds_dwordx4 v[146:147], off
	v_lshl_add_u64 v[146:147], v[220:221], 0, s[16:17]
	s_mov_b32 m0, s47
	s_nop 0
	global_load_lds_dwordx4 v[146:147], off
	s_waitcnt vmcnt(8)
	s_waitcnt lgkmcnt(0)
	s_barrier
	v_mfma_f32_16x16x32_bf16 v[60:63], v[152:155], v[184:187], v[60:63]
	v_mfma_f32_16x16x32_bf16 v[56:59], v[160:163], v[184:187], v[56:59]
	v_mfma_f32_16x16x32_bf16 v[44:47], v[152:155], v[192:195], v[44:47]
	v_mfma_f32_16x16x32_bf16 v[40:43], v[160:163], v[192:195], v[40:43]
	v_mfma_f32_16x16x32_bf16 v[28:31], v[152:155], v[200:203], v[28:31]
	v_mfma_f32_16x16x32_bf16 v[24:27], v[160:163], v[200:203], v[24:27]
	v_mfma_f32_16x16x32_bf16 v[12:15], v[152:155], v[208:211], v[12:15]
	v_mfma_f32_16x16x32_bf16 v[8:11], v[160:163], v[208:211], v[8:11]
	v_mfma_f32_16x16x32_bf16 v[60:63], v[156:159], v[188:191], v[60:63]
	v_mfma_f32_16x16x32_bf16 v[56:59], v[164:167], v[188:191], v[56:59]
	v_mfma_f32_16x16x32_bf16 v[44:47], v[156:159], v[196:199], v[44:47]
	v_mfma_f32_16x16x32_bf16 v[40:43], v[164:167], v[196:199], v[40:43]
	v_mfma_f32_16x16x32_bf16 v[28:31], v[156:159], v[204:207], v[28:31]
	v_mfma_f32_16x16x32_bf16 v[24:27], v[164:167], v[204:207], v[24:27]
	v_mfma_f32_16x16x32_bf16 v[12:15], v[156:159], v[212:215], v[12:15]
	v_mfma_f32_16x16x32_bf16 v[8:11], v[164:167], v[212:215], v[8:11]
	v_mfma_f32_16x16x32_bf16 v[52:55], v[168:171], v[184:187], v[52:55]
	v_mfma_f32_16x16x32_bf16 v[48:51], v[176:179], v[184:187], v[48:51]
	v_mfma_f32_16x16x32_bf16 v[36:39], v[168:171], v[192:195], v[36:39]
	v_mfma_f32_16x16x32_bf16 v[32:35], v[176:179], v[192:195], v[32:35]
	v_mfma_f32_16x16x32_bf16 v[20:23], v[168:171], v[200:203], v[20:23]
	v_mfma_f32_16x16x32_bf16 v[16:19], v[176:179], v[200:203], v[16:19]
	v_mfma_f32_16x16x32_bf16 v[4:7], v[168:171], v[208:211], v[4:7]
	v_mfma_f32_16x16x32_bf16 v[0:3], v[176:179], v[208:211], v[0:3]
	v_mfma_f32_16x16x32_bf16 v[52:55], v[172:175], v[188:191], v[52:55]
	v_mfma_f32_16x16x32_bf16 v[48:51], v[180:183], v[188:191], v[48:51]
	v_mfma_f32_16x16x32_bf16 v[36:39], v[172:175], v[196:199], v[36:39]
	v_mfma_f32_16x16x32_bf16 v[32:35], v[180:183], v[196:199], v[32:35]
	v_mfma_f32_16x16x32_bf16 v[20:23], v[172:175], v[204:207], v[20:23]
	v_mfma_f32_16x16x32_bf16 v[16:19], v[180:183], v[204:207], v[16:19]
	v_mfma_f32_16x16x32_bf16 v[4:7], v[172:175], v[212:215], v[4:7]
	v_mfma_f32_16x16x32_bf16 v[0:3], v[180:183], v[212:215], v[0:3]
	s_barrier
	s_add_i32 s56, s56, 2
	s_add_u32 s54, s54, 0x100
	s_addc_u32 s55, s55, 0
	s_cmp_gt_u32 s56, 9
	s_mov_b64 s[34:35], s[36:37]
	s_cbranch_scc0 .LBB0_989
	s_branch .Lpeel_exit_4
.LBB0_989:
	ds_read_b128 v[152:155], v149
	ds_read_b128 v[156:159], v149 offset:1024
	ds_read_b128 v[160:163], v149 offset:2048
	ds_read_b128 v[164:167], v149 offset:3072
	ds_read_b128 v[168:171], v150
	ds_read_b128 v[172:175], v150 offset:1024
	ds_read_b128 v[176:179], v150 offset:2048
	ds_read_b128 v[180:183], v150 offset:3072
	s_add_u32 s36, s34, 0x100
	s_addc_u32 s37, s35, 0
	s_cmp_eq_u32 s56, 8
	s_cselect_b32 s41, s11, s37
	s_cselect_b32 s40, s10, s36
	s_cselect_b32 s39, s31, s55
	s_cselect_b32 s38, s30, s54
	v_lshl_add_u64 v[146:147], s[34:35], 0, v[138:139]
	s_add_i32 m0, s25, 0xc000
	ds_read_b128 v[184:187], v151
	ds_read_b128 v[188:191], v151 offset:1024
	ds_read_b128 v[192:195], v151 offset:2048
	ds_read_b128 v[196:199], v151 offset:3072
	ds_read_b128 v[200:203], v151 offset:4096
	ds_read_b128 v[204:207], v151 offset:5120
	ds_read_b128 v[208:211], v151 offset:6144
	ds_read_b128 v[212:215], v151 offset:7168
	global_load_lds_dwordx4 v[146:147], off
	v_lshl_add_u64 v[146:147], s[34:35], 0, v[140:141]
	s_add_i32 m0, s25, 0xe000
	s_nop 0
	global_load_lds_dwordx4 v[146:147], off
	s_waitcnt vmcnt(8)
	s_waitcnt lgkmcnt(0)
	s_barrier
; #define PG8_STAGE(bufoff, gbase, voff) do { _Pragma("unroll") for (int _i = 0; _i < 2; ++_i) \
;         __builtin_amdgcn_global_load_lds((const unsigned*)((const char*)(gbase) + (voff)[_i]), (LAS unsigned*)(lds + (bufoff) + ldsw + _i * 8192), 16, 0, 0); } while (0)
; #define PG8_LDA(dst, b, h) do { _Pragma("unroll") for (int m = 0; m < 4; ++m) _Pragma("unroll") for (int k = 0; k < 2; ++k) dst[m][k] = *(const LAS bf16x8*)(lds + PG8_SA(b, h) + aoff + m * 2048 + k * 1024); } while (0)
; #define PG8_LDB(dst, b, h) do { _Pragma("unroll") for (int n = 0; n < 2; ++n) _Pragma("unroll") for (int k = 0; k < 2; ++k) dst[n][k] = *(const LAS bf16x8*)(lds + PG8_SB(b, h) + boff + n * 2048 + k * 1024); } while (0)
; #define PG8_MMA(ai, bj, At, Bt) do { __builtin_amdgcn_s_setprio(1); _Pragma("unroll") for (int m = 0; m < 4; ++m) _Pragma("unroll") for (int n = 0; n < 2; ++n) _Pragma("unroll") for (int k = 0; k < 2; ++k) \
;         acc[ai][bj][m][n] = __builtin_amdgcn_mfma_f32_16x16x32_bf16(Bt[n][k], At[m][k], acc[ai][bj][m][n], 0, 0, 0); __builtin_amdgcn_s_setprio(0); } while (0)
; #define PG8_WAIT_V(n) asm volatile("s_waitcnt vmcnt(" #n ")" ::: "memory")
; #define PG8_WAIT_L(n) asm volatile("s_waitcnt lgkmcnt(" #n ")" ::: "memory")
; #define PG8_BAR __builtin_amdgcn_s_barrier()
; #define PG8_SCHED __builtin_amdgcn_sched_barrier(0)
; template <class Epi>
; DI void gemm_phase(LAS unsigned char* lds, const int wid, const Gemm g, const Order& S, const Epi& E) {
;     ...
;             PG8_LDB(B0, 0, 0); PG8_LDB(B1, 0, 1); PG8_SCHED; PG8_LDA(At, 0, 0); PG8_STAGE(PG8_SA(1, 1), a1 + hstepA, voffA);
;             PG8_WAIT_V(8); PG8_WAIT_L(0); PG8_BAR; PG8_MMA(0, 0, At, B0); PG8_MMA(0, 1, At, B1); PG8_BAR; PG8_SCHED;
;             PG8_LDA(At, 0, 1); PG8_STAGE(PG8_SB(0, 0), b2, voffB); PG8_STAGE(PG8_SB(0, 1), b2 + hstepB, voffB); PG8_STAGE(PG8_SA(0, 0), a2, voffA);
;             PG8_WAIT_V(8); PG8_WAIT_L(0); PG8_BAR; PG8_MMA(1, 0, At, B0); PG8_MMA(1, 1, At, B1); PG8_BAR; PG8_SCHED;
	v_mfma_f32_16x16x32_bf16 v[124:127], v[152:155], v[184:187], v[124:127]
	v_mfma_f32_16x16x32_bf16 v[120:123], v[160:163], v[184:187], v[120:123]
	v_mfma_f32_16x16x32_bf16 v[108:111], v[152:155], v[192:195], v[108:111]
	v_mfma_f32_16x16x32_bf16 v[104:107], v[160:163], v[192:195], v[104:107]
	v_mfma_f32_16x16x32_bf16 v[92:95], v[152:155], v[200:203], v[92:95]
	v_mfma_f32_16x16x32_bf16 v[88:91], v[160:163], v[200:203], v[88:91]
	v_mfma_f32_16x16x32_bf16 v[76:79], v[152:155], v[208:211], v[76:79]
	v_mfma_f32_16x16x32_bf16 v[72:75], v[160:163], v[208:211], v[72:75]
	v_mfma_f32_16x16x32_bf16 v[124:127], v[156:159], v[188:191], v[124:127]
	v_mfma_f32_16x16x32_bf16 v[120:123], v[164:167], v[188:191], v[120:123]
	v_mfma_f32_16x16x32_bf16 v[108:111], v[156:159], v[196:199], v[108:111]
	v_mfma_f32_16x16x32_bf16 v[104:107], v[164:167], v[196:199], v[104:107]
	v_mfma_f32_16x16x32_bf16 v[92:95], v[156:159], v[204:207], v[92:95]
	v_mfma_f32_16x16x32_bf16 v[88:91], v[164:167], v[204:207], v[88:91]
	v_mfma_f32_16x16x32_bf16 v[76:79], v[156:159], v[212:215], v[76:79]
	v_mfma_f32_16x16x32_bf16 v[72:75], v[164:167], v[212:215], v[72:75]
	v_mfma_f32_16x16x32_bf16 v[116:119], v[168:171], v[184:187], v[116:119]
	v_mfma_f32_16x16x32_bf16 v[112:115], v[176:179], v[184:187], v[112:115]
	v_mfma_f32_16x16x32_bf16 v[100:103], v[168:171], v[192:195], v[100:103]
	v_mfma_f32_16x16x32_bf16 v[96:99], v[176:179], v[192:195], v[96:99]
	v_mfma_f32_16x16x32_bf16 v[84:87], v[168:171], v[200:203], v[84:87]
	v_mfma_f32_16x16x32_bf16 v[80:83], v[176:179], v[200:203], v[80:83]
	v_mfma_f32_16x16x32_bf16 v[68:71], v[168:171], v[208:211], v[68:71]
	v_mfma_f32_16x16x32_bf16 v[64:67], v[176:179], v[208:211], v[64:67]
	v_mfma_f32_16x16x32_bf16 v[116:119], v[172:175], v[188:191], v[116:119]
	v_mfma_f32_16x16x32_bf16 v[112:115], v[180:183], v[188:191], v[112:115]
	v_mfma_f32_16x16x32_bf16 v[100:103], v[172:175], v[196:199], v[100:103]
	v_mfma_f32_16x16x32_bf16 v[96:99], v[180:183], v[196:199], v[96:99]
	v_mfma_f32_16x16x32_bf16 v[84:87], v[172:175], v[204:207], v[84:87]
	v_mfma_f32_16x16x32_bf16 v[80:83], v[180:183], v[204:207], v[80:83]
	v_mfma_f32_16x16x32_bf16 v[68:71], v[172:175], v[212:215], v[68:71]
	v_mfma_f32_16x16x32_bf16 v[64:67], v[180:183], v[212:215], v[64:67]
	s_barrier
	s_add_i32 s34, s48, s94
	v_lshl_add_u64 v[146:147], s[38:39], 0, v[130:131]
	s_mov_b32 m0, s34
	ds_read_b128 v[184:187], v151 offset:16384
	ds_read_b128 v[188:191], v151 offset:17408
	ds_read_b128 v[192:195], v151 offset:18432
	ds_read_b128 v[196:199], v151 offset:19456
	ds_read_b128 v[200:203], v151 offset:20480
	ds_read_b128 v[204:207], v151 offset:21504
	ds_read_b128 v[208:211], v151 offset:22528
	ds_read_b128 v[212:215], v151 offset:23552
	global_load_lds_dwordx4 v[146:147], off
	s_add_i32 m0, s34, 0x2000
	s_add_u32 s34, s38, 0x30000
	v_lshl_add_u64 v[216:217], s[38:39], 0, v[134:135]
	s_addc_u32 s35, s39, 0
	s_add_i32 s57, s49, s94
	global_load_lds_dwordx4 v[216:217], off
	v_lshl_add_u64 v[218:219], s[34:35], 0, v[130:131]
	s_mov_b32 m0, s57
	v_lshl_add_u64 v[220:221], s[40:41], 0, v[132:133]
	global_load_lds_dwordx4 v[218:219], off
	v_lshl_add_u64 v[218:219], s[34:35], 0, v[134:135]
	s_add_i32 m0, s57, 0x2000
	s_nop 0
	global_load_lds_dwordx4 v[218:219], off
	v_lshl_add_u64 v[218:219], s[40:41], 0, v[128:129]
	s_mov_b32 m0, s25
	s_nop 0
	global_load_lds_dwordx4 v[218:219], off
	s_mov_b32 m0, s42
	s_nop 0
	global_load_lds_dwordx4 v[220:221], off
	s_waitcnt vmcnt(8)
	s_waitcnt lgkmcnt(0)
	s_barrier
	v_mfma_f32_16x16x32_bf16 v[60:63], v[152:155], v[184:187], v[60:63]
	v_mfma_f32_16x16x32_bf16 v[56:59], v[160:163], v[184:187], v[56:59]
	v_mfma_f32_16x16x32_bf16 v[44:47], v[152:155], v[192:195], v[44:47]
	v_mfma_f32_16x16x32_bf16 v[40:43], v[160:163], v[192:195], v[40:43]
	v_mfma_f32_16x16x32_bf16 v[28:31], v[152:155], v[200:203], v[28:31]
	v_mfma_f32_16x16x32_bf16 v[24:27], v[160:163], v[200:203], v[24:27]
	v_mfma_f32_16x16x32_bf16 v[12:15], v[152:155], v[208:211], v[12:15]
	v_mfma_f32_16x16x32_bf16 v[8:11], v[160:163], v[208:211], v[8:11]
	v_mfma_f32_16x16x32_bf16 v[60:63], v[156:159], v[188:191], v[60:63]
	v_mfma_f32_16x16x32_bf16 v[56:59], v[164:167], v[188:191], v[56:59]
	v_mfma_f32_16x16x32_bf16 v[44:47], v[156:159], v[196:199], v[44:47]
	v_mfma_f32_16x16x32_bf16 v[40:43], v[164:167], v[196:199], v[40:43]
	v_mfma_f32_16x16x32_bf16 v[28:31], v[156:159], v[204:207], v[28:31]
	v_mfma_f32_16x16x32_bf16 v[24:27], v[164:167], v[204:207], v[24:27]
	v_mfma_f32_16x16x32_bf16 v[12:15], v[156:159], v[212:215], v[12:15]
	v_mfma_f32_16x16x32_bf16 v[8:11], v[164:167], v[212:215], v[8:11]
	v_mfma_f32_16x16x32_bf16 v[52:55], v[168:171], v[184:187], v[52:55]
	v_mfma_f32_16x16x32_bf16 v[48:51], v[176:179], v[184:187], v[48:51]
	v_mfma_f32_16x16x32_bf16 v[36:39], v[168:171], v[192:195], v[36:39]
	v_mfma_f32_16x16x32_bf16 v[32:35], v[176:179], v[192:195], v[32:35]
	v_mfma_f32_16x16x32_bf16 v[20:23], v[168:171], v[200:203], v[20:23]
	v_mfma_f32_16x16x32_bf16 v[16:19], v[176:179], v[200:203], v[16:19]
	v_mfma_f32_16x16x32_bf16 v[4:7], v[168:171], v[208:211], v[4:7]
	v_mfma_f32_16x16x32_bf16 v[0:3], v[176:179], v[208:211], v[0:3]
	v_mfma_f32_16x16x32_bf16 v[52:55], v[172:175], v[188:191], v[52:55]
	v_mfma_f32_16x16x32_bf16 v[48:51], v[180:183], v[188:191], v[48:51]
	v_mfma_f32_16x16x32_bf16 v[36:39], v[172:175], v[196:199], v[36:39]
	v_mfma_f32_16x16x32_bf16 v[32:35], v[180:183], v[196:199], v[32:35]
	v_mfma_f32_16x16x32_bf16 v[20:23], v[172:175], v[204:207], v[20:23]
	v_mfma_f32_16x16x32_bf16 v[16:19], v[180:183], v[204:207], v[16:19]
	v_mfma_f32_16x16x32_bf16 v[4:7], v[172:175], v[212:215], v[4:7]
	v_mfma_f32_16x16x32_bf16 v[0:3], v[180:183], v[212:215], v[0:3]
	s_barrier
; #define PG8_STAGE(bufoff, gbase, voff) do { _Pragma("unroll") for (int _i = 0; _i < 2; ++_i) \
;         __builtin_amdgcn_global_load_lds((const unsigned*)((const char*)(gbase) + (voff)[_i]), (LAS unsigned*)(lds + (bufoff) + ldsw + _i * 8192), 16, 0, 0); } while (0)
; #define PG8_LDA(dst, b, h) do { _Pragma("unroll") for (int m = 0; m < 4; ++m) _Pragma("unroll") for (int k = 0; k < 2; ++k) dst[m][k] = *(const LAS bf16x8*)(lds + PG8_SA(b, h) + aoff + m * 2048 + k * 1024); } while (0)
; #define PG8_LDB(dst, b, h) do { _Pragma("unroll") for (int n = 0; n < 2; ++n) _Pragma("unroll") for (int k = 0; k < 2; ++k) dst[n][k] = *(const LAS bf16x8*)(lds + PG8_SB(b, h) + boff + n * 2048 + k * 1024); } while (0)
; #define PG8_MMA(ai, bj, At, Bt) do { __builtin_amdgcn_s_setprio(1); _Pragma("unroll") for (int m = 0; m < 4; ++m) _Pragma("unroll") for (int n = 0; n < 2; ++n) _Pragma("unroll") for (int k = 0; k < 2; ++k) \
;         acc[ai][bj][m][n] = __builtin_amdgcn_mfma_f32_16x16x32_bf16(Bt[n][k], At[m][k], acc[ai][bj][m][n], 0, 0, 0); __builtin_amdgcn_s_setprio(0); } while (0)
; #define PG8_WAIT_V(n) asm volatile("s_waitcnt vmcnt(" #n ")" ::: "memory")
; #define PG8_WAIT_L(n) asm volatile("s_waitcnt lgkmcnt(" #n ")" ::: "memory")
; #define PG8_BAR __builtin_amdgcn_s_barrier()
; #define PG8_SCHED __builtin_amdgcn_sched_barrier(0)
; template <class Epi>
; DI void gemm_phase(LAS unsigned char* lds, const int wid, const Gemm g, const Order& S, const Epi& E) {
;     ...
;             PG8_LDB(B0, 1, 0); PG8_LDB(B1, 1, 1); PG8_SCHED; PG8_LDA(At, 1, 0); PG8_STAGE(PG8_SA(0, 1), a2 + hstepA, voffA);
;             PG8_WAIT_V(8); PG8_WAIT_L(0); PG8_BAR; PG8_MMA(0, 0, At, B0); PG8_MMA(0, 1, At, B1); PG8_BAR; PG8_SCHED;
;             PG8_LDA(At, 1, 1); PG8_STAGE(PG8_SB(1, 0), b3, voffB); PG8_STAGE(PG8_SB(1, 1), b3 + hstepB, voffB); PG8_STAGE(PG8_SA(1, 0), a3, voffA);
;             PG8_WAIT_V(8); PG8_WAIT_L(0); PG8_BAR; PG8_MMA(1, 0, At, B0); PG8_MMA(1, 1, At, B1); PG8_BAR; PG8_SCHED;
	s_add_i32 s57, 0, 0x18000
	v_add_u32_e32 v136, s57, v148
	s_add_i32 s58, 0, 0x1c000
	ds_read_b128 v[152:155], v136
	ds_read_b128 v[156:159], v136 offset:1024
	ds_read_b128 v[160:163], v136 offset:2048
	ds_read_b128 v[164:167], v136 offset:3072
	v_add_u32_e32 v136, s58, v148
	ds_read_b128 v[168:171], v136
	ds_read_b128 v[172:175], v136 offset:1024
	ds_read_b128 v[176:179], v136 offset:2048
	ds_read_b128 v[180:183], v136 offset:3072
	s_add_u32 s34, s40, 0x30000
	s_addc_u32 s35, s41, 0
	s_mov_b32 m0, s43
	v_lshl_add_u64 v[222:223], s[34:35], 0, v[128:129]
	ds_read_b128 v[184:187], v151 offset:32768
	ds_read_b128 v[188:191], v151 offset:33792
	ds_read_b128 v[192:195], v151 offset:34816
	ds_read_b128 v[196:199], v151 offset:35840
	ds_read_b128 v[200:203], v151 offset:36864
	ds_read_b128 v[204:207], v151 offset:37888
	ds_read_b128 v[208:211], v151 offset:38912
	ds_read_b128 v[212:215], v151 offset:39936
	global_load_lds_dwordx4 v[222:223], off
	v_lshl_add_u64 v[222:223], s[34:35], 0, v[132:133]
	s_mov_b32 m0, s44
	s_nop 0
	global_load_lds_dwordx4 v[222:223], off
	s_waitcnt vmcnt(8)
	s_waitcnt lgkmcnt(0)
	s_barrier
	v_mfma_f32_16x16x32_bf16 v[124:127], v[152:155], v[184:187], v[124:127]
	v_mfma_f32_16x16x32_bf16 v[120:123], v[160:163], v[184:187], v[120:123]
	v_mfma_f32_16x16x32_bf16 v[108:111], v[152:155], v[192:195], v[108:111]
	v_mfma_f32_16x16x32_bf16 v[104:107], v[160:163], v[192:195], v[104:107]
	v_mfma_f32_16x16x32_bf16 v[92:95], v[152:155], v[200:203], v[92:95]
	v_mfma_f32_16x16x32_bf16 v[88:91], v[160:163], v[200:203], v[88:91]
	v_mfma_f32_16x16x32_bf16 v[76:79], v[152:155], v[208:211], v[76:79]
	v_mfma_f32_16x16x32_bf16 v[72:75], v[160:163], v[208:211], v[72:75]
	v_mfma_f32_16x16x32_bf16 v[124:127], v[156:159], v[188:191], v[124:127]
	v_mfma_f32_16x16x32_bf16 v[120:123], v[164:167], v[188:191], v[120:123]
	v_mfma_f32_16x16x32_bf16 v[108:111], v[156:159], v[196:199], v[108:111]
	v_mfma_f32_16x16x32_bf16 v[104:107], v[164:167], v[196:199], v[104:107]
	v_mfma_f32_16x16x32_bf16 v[92:95], v[156:159], v[204:207], v[92:95]
	v_mfma_f32_16x16x32_bf16 v[88:91], v[164:167], v[204:207], v[88:91]
	v_mfma_f32_16x16x32_bf16 v[76:79], v[156:159], v[212:215], v[76:79]
	v_mfma_f32_16x16x32_bf16 v[72:75], v[164:167], v[212:215], v[72:75]
	v_mfma_f32_16x16x32_bf16 v[116:119], v[168:171], v[184:187], v[116:119]
	v_mfma_f32_16x16x32_bf16 v[112:115], v[176:179], v[184:187], v[112:115]
	v_mfma_f32_16x16x32_bf16 v[100:103], v[168:171], v[192:195], v[100:103]
	v_mfma_f32_16x16x32_bf16 v[96:99], v[176:179], v[192:195], v[96:99]
	v_mfma_f32_16x16x32_bf16 v[84:87], v[168:171], v[200:203], v[84:87]
	v_mfma_f32_16x16x32_bf16 v[80:83], v[176:179], v[200:203], v[80:83]
	v_mfma_f32_16x16x32_bf16 v[68:71], v[168:171], v[208:211], v[68:71]
	v_mfma_f32_16x16x32_bf16 v[64:67], v[176:179], v[208:211], v[64:67]
	v_mfma_f32_16x16x32_bf16 v[116:119], v[172:175], v[188:191], v[116:119]
	v_mfma_f32_16x16x32_bf16 v[112:115], v[180:183], v[188:191], v[112:115]
	v_mfma_f32_16x16x32_bf16 v[100:103], v[172:175], v[196:199], v[100:103]
	v_mfma_f32_16x16x32_bf16 v[96:99], v[180:183], v[196:199], v[96:99]
	v_mfma_f32_16x16x32_bf16 v[84:87], v[172:175], v[204:207], v[84:87]
	v_mfma_f32_16x16x32_bf16 v[80:83], v[180:183], v[204:207], v[80:83]
	v_mfma_f32_16x16x32_bf16 v[68:71], v[172:175], v[212:215], v[68:71]
	v_mfma_f32_16x16x32_bf16 v[64:67], v[180:183], v[212:215], v[64:67]
	s_barrier
	s_add_i32 s34, s57, s94
	v_lshl_add_u64 v[146:147], v[146:147], 0, s[16:17]
	s_mov_b32 m0, s34
	ds_read_b128 v[184:187], v151 offset:49152
	ds_read_b128 v[188:191], v151 offset:50176
	ds_read_b128 v[192:195], v151 offset:51200
	ds_read_b128 v[196:199], v151 offset:52224
	ds_read_b128 v[200:203], v151 offset:53248
	ds_read_b128 v[204:207], v151 offset:54272
	ds_read_b128 v[208:211], v151 offset:55296
	ds_read_b128 v[212:215], v151 offset:56320
	global_load_lds_dwordx4 v[146:147], off
	s_add_i32 m0, s34, 0x2000
	s_add_u32 s34, s38, 0x30080
	v_lshl_add_u64 v[146:147], v[216:217], 0, s[16:17]
	s_addc_u32 s35, s39, 0
	s_add_i32 s38, s58, s94
	global_load_lds_dwordx4 v[146:147], off
	v_lshl_add_u64 v[146:147], s[34:35], 0, v[130:131]
	s_mov_b32 m0, s38
	s_nop 0
	global_load_lds_dwordx4 v[146:147], off
	v_lshl_add_u64 v[146:147], s[34:35], 0, v[134:135]
	s_add_i32 m0, s38, 0x2000
	s_nop 0
	global_load_lds_dwordx4 v[146:147], off
	v_lshl_add_u64 v[146:147], v[218:219], 0, s[16:17]
	s_mov_b32 m0, s46
	s_nop 0
	global_load_lds_dwordx4 v[146:147], off
	v_lshl_add_u64 v[146:147], v[220:221], 0, s[16:17]
	s_mov_b32 m0, s47
	s_nop 0
	global_load_lds_dwordx4 v[146:147], off
	s_waitcnt vmcnt(8)
	s_waitcnt lgkmcnt(0)
	s_barrier
	v_mfma_f32_16x16x32_bf16 v[60:63], v[152:155], v[184:187], v[60:63]
	v_mfma_f32_16x16x32_bf16 v[56:59], v[160:163], v[184:187], v[56:59]
	v_mfma_f32_16x16x32_bf16 v[44:47], v[152:155], v[192:195], v[44:47]
	v_mfma_f32_16x16x32_bf16 v[40:43], v[160:163], v[192:195], v[40:43]
	v_mfma_f32_16x16x32_bf16 v[28:31], v[152:155], v[200:203], v[28:31]
	v_mfma_f32_16x16x32_bf16 v[24:27], v[160:163], v[200:203], v[24:27]
	v_mfma_f32_16x16x32_bf16 v[12:15], v[152:155], v[208:211], v[12:15]
	v_mfma_f32_16x16x32_bf16 v[8:11], v[160:163], v[208:211], v[8:11]
	v_mfma_f32_16x16x32_bf16 v[60:63], v[156:159], v[188:191], v[60:63]
	v_mfma_f32_16x16x32_bf16 v[56:59], v[164:167], v[188:191], v[56:59]
	v_mfma_f32_16x16x32_bf16 v[44:47], v[156:159], v[196:199], v[44:47]
	v_mfma_f32_16x16x32_bf16 v[40:43], v[164:167], v[196:199], v[40:43]
	v_mfma_f32_16x16x32_bf16 v[28:31], v[156:159], v[204:207], v[28:31]
	v_mfma_f32_16x16x32_bf16 v[24:27], v[164:167], v[204:207], v[24:27]
	v_mfma_f32_16x16x32_bf16 v[12:15], v[156:159], v[212:215], v[12:15]
	v_mfma_f32_16x16x32_bf16 v[8:11], v[164:167], v[212:215], v[8:11]
	v_mfma_f32_16x16x32_bf16 v[52:55], v[168:171], v[184:187], v[52:55]
	v_mfma_f32_16x16x32_bf16 v[48:51], v[176:179], v[184:187], v[48:51]
	v_mfma_f32_16x16x32_bf16 v[36:39], v[168:171], v[192:195], v[36:39]
	v_mfma_f32_16x16x32_bf16 v[32:35], v[176:179], v[192:195], v[32:35]
	v_mfma_f32_16x16x32_bf16 v[20:23], v[168:171], v[200:203], v[20:23]
	v_mfma_f32_16x16x32_bf16 v[16:19], v[176:179], v[200:203], v[16:19]
	v_mfma_f32_16x16x32_bf16 v[4:7], v[168:171], v[208:211], v[4:7]
	v_mfma_f32_16x16x32_bf16 v[0:3], v[176:179], v[208:211], v[0:3]
	v_mfma_f32_16x16x32_bf16 v[52:55], v[172:175], v[188:191], v[52:55]
	v_mfma_f32_16x16x32_bf16 v[48:51], v[180:183], v[188:191], v[48:51]
	v_mfma_f32_16x16x32_bf16 v[36:39], v[172:175], v[196:199], v[36:39]
	v_mfma_f32_16x16x32_bf16 v[32:35], v[180:183], v[196:199], v[32:35]
	v_mfma_f32_16x16x32_bf16 v[20:23], v[172:175], v[204:207], v[20:23]
	v_mfma_f32_16x16x32_bf16 v[16:19], v[180:183], v[204:207], v[16:19]
	v_mfma_f32_16x16x32_bf16 v[4:7], v[172:175], v[212:215], v[4:7]
	v_mfma_f32_16x16x32_bf16 v[0:3], v[180:183], v[212:215], v[0:3]
	s_barrier
	s_add_i32 s56, s56, 2
	s_add_u32 s54, s54, 0x100
	s_addc_u32 s55, s55, 0
	s_cmp_gt_u32 s56, 9
	s_mov_b64 s[34:35], s[36:37]
	s_cbranch_scc0 .LBB0_989

; #define PG8_STAGE(bufoff, gbase, voff) do { _Pragma("unroll") for (int _i = 0; _i < 2; ++_i) \
;         __builtin_amdgcn_global_load_lds((const unsigned*)((const char*)(gbase) + (voff)[_i]), (LAS unsigned*)(lds + (bufoff) + ldsw + _i * 8192), 16, 0, 0); } while (0)
; #define PG8_LDA(dst, b, h) do { _Pragma("unroll") for (int m = 0; m < 4; ++m) _Pragma("unroll") for (int k = 0; k < 2; ++k) dst[m][k] = *(const LAS bf16x8*)(lds + PG8_SA(b, h) + aoff + m * 2048 + k * 1024); } while (0)
; #define PG8_LDB(dst, b, h) do { _Pragma("unroll") for (int n = 0; n < 2; ++n) _Pragma("unroll") for (int k = 0; k < 2; ++k) dst[n][k] = *(const LAS bf16x8*)(lds + PG8_SB(b, h) + boff + n * 2048 + k * 1024); } while (0)
; #define PG8_MMA(ai, bj, At, Bt) do { __builtin_amdgcn_s_setprio(1); _Pragma("unroll") for (int m = 0; m < 4; ++m) _Pragma("unroll") for (int n = 0; n < 2; ++n) _Pragma("unroll") for (int k = 0; k < 2; ++k) \
;         acc[ai][bj][m][n] = __builtin_amdgcn_mfma_f32_16x16x32_bf16(Bt[n][k], At[m][k], acc[ai][bj][m][n], 0, 0, 0); __builtin_amdgcn_s_setprio(0); } while (0)
; template <class Epi>
; DI void gemm_phase(LAS unsigned char* lds, const int wid, const Gemm g, const Order& S, const Epi& E) {
;     ...
;         const bool has_next = S.next(ui + 1, nxt);
;         const char* nA = has_next ? (const char*)(g.A + (size_t)nxt.g * g.gsA + (size_t)nxt.pm * BM * g.lda) : cA;
;         const char* nB = has_next ? (const char*)(g.Bt + (size_t)nxt.g * g.gsB + (size_t)nxt.pn * BM * g.ldb) : cB;
;         for (int t = 0; t < nt; t += 2) {
;             const bool last = (t == nt - 2);
;             const char* a1 = cA + (size_t)(t + 1) * kstep;
;             const char* a2 = last ? nA : cA + (size_t)(t + 2) * kstep; const char* b2 = last ? nB : cB + (size_t)(t + 2) * kstep;
;             const char* a3 = a2 + kstep; const char* b3 = b2 + kstep;
;             PG8_LDB(B0, 0, 0); PG8_LDB(B1, 0, 1); PG8_SCHED; PG8_LDA(At, 0, 0); PG8_STAGE(PG8_SA(1, 1), a1 + hstepA, voffA);
;             PG8_WAIT_V(8); PG8_WAIT_L(0); PG8_BAR; PG8_MMA(0, 0, At, B0); PG8_MMA(0, 1, At, B1); PG8_BAR; PG8_SCHED;
;             PG8_LDA(At, 0, 1); PG8_STAGE(PG8_SB(0, 0), b2, voffB); PG8_STAGE(PG8_SB(0, 1), b2 + hstepB, voffB); PG8_STAGE(PG8_SA(0, 0), a2, voffA);
;             PG8_WAIT_V(8); PG8_WAIT_L(0); PG8_BAR; PG8_MMA(1, 0, At, B0); PG8_MMA(1, 1, At, B1); PG8_BAR; PG8_SCHED;
.LBB0_1012:
	s_ashr_i32 s29, s28, 31
	s_lshl_b64 s[34:35], s[28:29], 18
	s_add_u32 s34, s6, s34
	s_addc_u32 s35, s7, s35
	s_and_b64 s[36:37], s[8:9], exec
	s_cselect_b32 s29, s35, s41
	s_cselect_b32 s54, s34, s40
	s_ashr_i32 s31, s30, 31
	s_lshl_b64 s[36:37], s[30:31], 18
	s_add_u32 s36, s21, s36
	s_addc_u32 s37, s24, s37
	s_and_b64 s[44:45], s[8:9], exec
	s_cselect_b32 s31, s37, s43
	s_cselect_b32 s55, s36, s42
	s_add_u32 s40, s40, 0x20080
	s_addc_u32 s41, s41, 0
	s_add_u32 s56, s42, 0x100
	v_mov_b32_e32 v0, 0
	s_addc_u32 s57, s43, 0
	s_mov_b32 s58, -2
	s_waitcnt vmcnt(0)
	ds_read_b128 v[144:147], v153
	ds_read_b128 v[148:151], v153 offset:1024
	ds_read_b128 v[156:159], v153 offset:2048
	ds_read_b128 v[160:163], v153 offset:3072
	ds_read_b128 v[164:167], v154
	ds_read_b128 v[168:171], v154 offset:1024
	ds_read_b128 v[172:175], v154 offset:2048
	ds_read_b128 v[176:179], v154 offset:3072
	s_add_u32 s42, s40, 0xfffe0080
	s_addc_u32 s43, s41, -1
	s_cmp_eq_u32 s58, 4
	s_cselect_b32 s45, s29, s43
	s_cselect_b32 s44, s54, s42
	s_cselect_b32 s43, s31, s57
	s_cselect_b32 s42, s55, s56
	v_lshl_add_u64 v[212:213], s[40:41], 0, v[136:137]
	s_add_i32 m0, s25, 0xc000
	ds_read_b128 v[180:183], v155
	ds_read_b128 v[184:187], v155 offset:1024
	ds_read_b128 v[188:191], v155 offset:2048
	ds_read_b128 v[192:195], v155 offset:3072
	ds_read_b128 v[196:199], v155 offset:4096
	ds_read_b128 v[200:203], v155 offset:5120
	ds_read_b128 v[204:207], v155 offset:6144
	ds_read_b128 v[208:211], v155 offset:7168
	global_load_lds_dwordx4 v[212:213], off
	v_lshl_add_u64 v[212:213], s[40:41], 0, v[138:139]
	s_add_i32 m0, s25, 0xe000
	s_nop 0
	global_load_lds_dwordx4 v[212:213], off
	s_waitcnt vmcnt(8)
	s_waitcnt lgkmcnt(0)
	s_barrier
	v_mfma_f32_16x16x32_bf16 v[124:127], v[144:147], v[180:183], 0
	v_mfma_f32_16x16x32_bf16 v[120:123], v[156:159], v[180:183], 0
	v_mfma_f32_16x16x32_bf16 v[116:119], v[144:147], v[188:191], 0
	v_mfma_f32_16x16x32_bf16 v[112:115], v[156:159], v[188:191], 0
	v_mfma_f32_16x16x32_bf16 v[96:99], v[144:147], v[196:199], 0
	v_mfma_f32_16x16x32_bf16 v[88:91], v[156:159], v[196:199], 0
	v_mfma_f32_16x16x32_bf16 v[80:83], v[144:147], v[204:207], 0
	v_mfma_f32_16x16x32_bf16 v[72:75], v[156:159], v[204:207], 0
	v_mfma_f32_16x16x32_bf16 v[124:127], v[148:151], v[184:187], v[124:127]
	v_mfma_f32_16x16x32_bf16 v[120:123], v[160:163], v[184:187], v[120:123]
	v_mfma_f32_16x16x32_bf16 v[116:119], v[148:151], v[192:195], v[116:119]
	v_mfma_f32_16x16x32_bf16 v[112:115], v[160:163], v[192:195], v[112:115]
	v_mfma_f32_16x16x32_bf16 v[96:99], v[148:151], v[200:203], v[96:99]
	v_mfma_f32_16x16x32_bf16 v[88:91], v[160:163], v[200:203], v[88:91]
	v_mfma_f32_16x16x32_bf16 v[80:83], v[148:151], v[208:211], v[80:83]
	v_mfma_f32_16x16x32_bf16 v[72:75], v[160:163], v[208:211], v[72:75]
	v_mfma_f32_16x16x32_bf16 v[108:111], v[164:167], v[180:183], 0
	v_mfma_f32_16x16x32_bf16 v[104:107], v[172:175], v[180:183], 0
	v_mfma_f32_16x16x32_bf16 v[100:103], v[164:167], v[188:191], 0
	v_mfma_f32_16x16x32_bf16 v[92:95], v[172:175], v[188:191], 0
	v_mfma_f32_16x16x32_bf16 v[84:87], v[164:167], v[196:199], 0
	v_mfma_f32_16x16x32_bf16 v[76:79], v[172:175], v[196:199], 0
	v_mfma_f32_16x16x32_bf16 v[68:71], v[164:167], v[204:207], 0
	v_mfma_f32_16x16x32_bf16 v[64:67], v[172:175], v[204:207], 0
	v_mfma_f32_16x16x32_bf16 v[108:111], v[168:171], v[184:187], v[108:111]
	v_mfma_f32_16x16x32_bf16 v[104:107], v[176:179], v[184:187], v[104:107]
	v_mfma_f32_16x16x32_bf16 v[100:103], v[168:171], v[192:195], v[100:103]
	v_mfma_f32_16x16x32_bf16 v[92:95], v[176:179], v[192:195], v[92:95]
	v_mfma_f32_16x16x32_bf16 v[84:87], v[168:171], v[200:203], v[84:87]
	v_mfma_f32_16x16x32_bf16 v[76:79], v[176:179], v[200:203], v[76:79]
	v_mfma_f32_16x16x32_bf16 v[68:71], v[168:171], v[208:211], v[68:71]
	v_mfma_f32_16x16x32_bf16 v[64:67], v[176:179], v[208:211], v[64:67]
	s_barrier
	s_add_i32 s59, s51, s94
	v_lshl_add_u64 v[212:213], s[42:43], 0, v[130:131]
	s_mov_b32 m0, s59
	ds_read_b128 v[180:183], v155 offset:16384
	ds_read_b128 v[184:187], v155 offset:17408
	ds_read_b128 v[188:191], v155 offset:18432
	ds_read_b128 v[192:195], v155 offset:19456
	ds_read_b128 v[196:199], v155 offset:20480
	ds_read_b128 v[200:203], v155 offset:21504
	ds_read_b128 v[204:207], v155 offset:22528
	ds_read_b128 v[208:211], v155 offset:23552
	global_load_lds_dwordx4 v[212:213], off
	s_add_i32 m0, s59, 0x2000
	s_add_u32 s60, s42, 0x20000
	v_lshl_add_u64 v[214:215], s[42:43], 0, v[134:135]
	s_addc_u32 s61, s43, 0
	s_add_i32 s59, s52, s94
	global_load_lds_dwordx4 v[214:215], off
	v_lshl_add_u64 v[216:217], s[60:61], 0, v[130:131]
	s_mov_b32 m0, s59
	v_lshl_add_u64 v[218:219], s[44:45], 0, v[132:133]
	global_load_lds_dwordx4 v[216:217], off
	v_lshl_add_u64 v[216:217], s[60:61], 0, v[134:135]
	s_add_i32 m0, s59, 0x2000
	s_nop 0
	global_load_lds_dwordx4 v[216:217], off
	v_lshl_add_u64 v[216:217], s[44:45], 0, v[128:129]
	s_mov_b32 m0, s25
	s_nop 0
	global_load_lds_dwordx4 v[216:217], off
	s_mov_b32 m0, s39
	s_nop 0
	global_load_lds_dwordx4 v[218:219], off
	s_waitcnt vmcnt(8)
	s_waitcnt lgkmcnt(0)
	s_barrier
; #define PG8_STAGE(bufoff, gbase, voff) do { _Pragma("unroll") for (int _i = 0; _i < 2; ++_i) \
;         __builtin_amdgcn_global_load_lds((const unsigned*)((const char*)(gbase) + (voff)[_i]), (LAS unsigned*)(lds + (bufoff) + ldsw + _i * 8192), 16, 0, 0); } while (0)
; #define PG8_LDA(dst, b, h) do { _Pragma("unroll") for (int m = 0; m < 4; ++m) _Pragma("unroll") for (int k = 0; k < 2; ++k) dst[m][k] = *(const LAS bf16x8*)(lds + PG8_SA(b, h) + aoff + m * 2048 + k * 1024); } while (0)
; #define PG8_LDB(dst, b, h) do { _Pragma("unroll") for (int n = 0; n < 2; ++n) _Pragma("unroll") for (int k = 0; k < 2; ++k) dst[n][k] = *(const LAS bf16x8*)(lds + PG8_SB(b, h) + boff + n * 2048 + k * 1024); } while (0)
; #define PG8_MMA(ai, bj, At, Bt) do { __builtin_amdgcn_s_setprio(1); _Pragma("unroll") for (int m = 0; m < 4; ++m) _Pragma("unroll") for (int n = 0; n < 2; ++n) _Pragma("unroll") for (int k = 0; k < 2; ++k) \
;         acc[ai][bj][m][n] = __builtin_amdgcn_mfma_f32_16x16x32_bf16(Bt[n][k], At[m][k], acc[ai][bj][m][n], 0, 0, 0); __builtin_amdgcn_s_setprio(0); } while (0)
; #define PG8_WAIT_V(n) asm volatile("s_waitcnt vmcnt(" #n ")" ::: "memory")
; #define PG8_WAIT_L(n) asm volatile("s_waitcnt lgkmcnt(" #n ")" ::: "memory")
; #define PG8_BAR __builtin_amdgcn_s_barrier()
; #define PG8_SCHED __builtin_amdgcn_sched_barrier(0)
; template <class Epi>
; DI void gemm_phase(LAS unsigned char* lds, const int wid, const Gemm g, const Order& S, const Epi& E) {
;     ...
;             PG8_LDA(At, 0, 1); PG8_STAGE(PG8_SB(0, 0), b2, voffB); PG8_STAGE(PG8_SB(0, 1), b2 + hstepB, voffB); PG8_STAGE(PG8_SA(0, 0), a2, voffA);
;             PG8_WAIT_V(8); PG8_WAIT_L(0); PG8_BAR; PG8_MMA(1, 0, At, B0); PG8_MMA(1, 1, At, B1); PG8_BAR; PG8_SCHED;
;             PG8_LDB(B0, 1, 0); PG8_LDB(B1, 1, 1); PG8_SCHED; PG8_LDA(At, 1, 0); PG8_STAGE(PG8_SA(0, 1), a2 + hstepA, voffA);
;             PG8_WAIT_V(8); PG8_WAIT_L(0); PG8_BAR; PG8_MMA(0, 0, At, B0); PG8_MMA(0, 1, At, B1); PG8_BAR; PG8_SCHED;
	v_mfma_f32_16x16x32_bf16 v[60:63], v[144:147], v[180:183], 0
	v_mfma_f32_16x16x32_bf16 v[56:59], v[156:159], v[180:183], 0
	v_mfma_f32_16x16x32_bf16 v[48:51], v[144:147], v[188:191], 0
	v_mfma_f32_16x16x32_bf16 v[40:43], v[156:159], v[188:191], 0
	v_mfma_f32_16x16x32_bf16 v[32:35], v[144:147], v[196:199], 0
	v_mfma_f32_16x16x32_bf16 v[24:27], v[156:159], v[196:199], 0
	v_mfma_f32_16x16x32_bf16 v[16:19], v[144:147], v[204:207], 0
	v_mfma_f32_16x16x32_bf16 v[8:11], v[156:159], v[204:207], 0
	v_mfma_f32_16x16x32_bf16 v[60:63], v[148:151], v[184:187], v[60:63]
	v_mfma_f32_16x16x32_bf16 v[56:59], v[160:163], v[184:187], v[56:59]
	v_mfma_f32_16x16x32_bf16 v[48:51], v[148:151], v[192:195], v[48:51]
	v_mfma_f32_16x16x32_bf16 v[40:43], v[160:163], v[192:195], v[40:43]
	v_mfma_f32_16x16x32_bf16 v[32:35], v[148:151], v[200:203], v[32:35]
	v_mfma_f32_16x16x32_bf16 v[24:27], v[160:163], v[200:203], v[24:27]
	v_mfma_f32_16x16x32_bf16 v[16:19], v[148:151], v[208:211], v[16:19]
	v_mfma_f32_16x16x32_bf16 v[8:11], v[160:163], v[208:211], v[8:11]
	v_mfma_f32_16x16x32_bf16 v[52:55], v[164:167], v[180:183], 0
	v_mfma_f32_16x16x32_bf16 v[44:47], v[172:175], v[180:183], 0
	v_mfma_f32_16x16x32_bf16 v[36:39], v[164:167], v[188:191], 0
	v_mfma_f32_16x16x32_bf16 v[28:31], v[172:175], v[188:191], 0
	v_mfma_f32_16x16x32_bf16 v[20:23], v[164:167], v[196:199], 0
	v_mfma_f32_16x16x32_bf16 v[12:15], v[172:175], v[196:199], 0
	v_mfma_f32_16x16x32_bf16 v[4:7], v[164:167], v[204:207], 0
	v_mfma_f32_16x16x32_bf16 v[0:3], v[172:175], v[204:207], 0
	v_mfma_f32_16x16x32_bf16 v[52:55], v[168:171], v[184:187], v[52:55]
	v_mfma_f32_16x16x32_bf16 v[44:47], v[176:179], v[184:187], v[44:47]
	v_mfma_f32_16x16x32_bf16 v[36:39], v[168:171], v[192:195], v[36:39]
	v_mfma_f32_16x16x32_bf16 v[28:31], v[176:179], v[192:195], v[28:31]
	v_mfma_f32_16x16x32_bf16 v[20:23], v[168:171], v[200:203], v[20:23]
	v_mfma_f32_16x16x32_bf16 v[12:15], v[176:179], v[200:203], v[12:15]
	v_mfma_f32_16x16x32_bf16 v[4:7], v[168:171], v[208:211], v[4:7]
	v_mfma_f32_16x16x32_bf16 v[0:3], v[176:179], v[208:211], v[0:3]
	s_barrier
	s_add_i32 s59, 0, 0x18000
	s_add_i32 s60, 0, 0x1c000
	v_add_u32_e32 v160, s59, v152
	v_add_u32_e32 v176, s60, v152
	ds_read_b128 v[144:147], v160
	ds_read_b128 v[148:151], v160 offset:1024
	ds_read_b128 v[156:159], v160 offset:2048
	ds_read_b128 v[160:163], v160 offset:3072
	ds_read_b128 v[164:167], v176
	ds_read_b128 v[168:171], v176 offset:1024
	ds_read_b128 v[172:175], v176 offset:2048
	ds_read_b128 v[176:179], v176 offset:3072
	s_add_u32 s44, s44, 0x20000
	s_addc_u32 s45, s45, 0
	s_mov_b32 m0, s46
	v_lshl_add_u64 v[220:221], s[44:45], 0, v[128:129]
	ds_read_b128 v[180:183], v155 offset:32768
	ds_read_b128 v[184:187], v155 offset:33792
	ds_read_b128 v[188:191], v155 offset:34816
	ds_read_b128 v[192:195], v155 offset:35840
	ds_read_b128 v[196:199], v155 offset:36864
	ds_read_b128 v[200:203], v155 offset:37888
	ds_read_b128 v[204:207], v155 offset:38912
	ds_read_b128 v[208:211], v155 offset:39936
	global_load_lds_dwordx4 v[220:221], off
	v_lshl_add_u64 v[220:221], s[44:45], 0, v[132:133]
	s_mov_b32 m0, s47
	s_nop 0
	global_load_lds_dwordx4 v[220:221], off
	s_waitcnt vmcnt(8)
	s_waitcnt lgkmcnt(0)
	s_barrier
	v_mfma_f32_16x16x32_bf16 v[124:127], v[144:147], v[180:183], v[124:127]
	v_mfma_f32_16x16x32_bf16 v[120:123], v[156:159], v[180:183], v[120:123]
	v_mfma_f32_16x16x32_bf16 v[116:119], v[144:147], v[188:191], v[116:119]
	v_mfma_f32_16x16x32_bf16 v[112:115], v[156:159], v[188:191], v[112:115]
	v_mfma_f32_16x16x32_bf16 v[96:99], v[144:147], v[196:199], v[96:99]
	v_mfma_f32_16x16x32_bf16 v[88:91], v[156:159], v[196:199], v[88:91]
	v_mfma_f32_16x16x32_bf16 v[80:83], v[144:147], v[204:207], v[80:83]
	v_mfma_f32_16x16x32_bf16 v[72:75], v[156:159], v[204:207], v[72:75]
	v_mfma_f32_16x16x32_bf16 v[124:127], v[148:151], v[184:187], v[124:127]
	v_mfma_f32_16x16x32_bf16 v[120:123], v[160:163], v[184:187], v[120:123]
	v_mfma_f32_16x16x32_bf16 v[116:119], v[148:151], v[192:195], v[116:119]
	v_mfma_f32_16x16x32_bf16 v[112:115], v[160:163], v[192:195], v[112:115]
	v_mfma_f32_16x16x32_bf16 v[96:99], v[148:151], v[200:203], v[96:99]
	v_mfma_f32_16x16x32_bf16 v[88:91], v[160:163], v[200:203], v[88:91]
	v_mfma_f32_16x16x32_bf16 v[80:83], v[148:151], v[208:211], v[80:83]
	v_mfma_f32_16x16x32_bf16 v[72:75], v[160:163], v[208:211], v[72:75]
	v_mfma_f32_16x16x32_bf16 v[108:111], v[164:167], v[180:183], v[108:111]
	v_mfma_f32_16x16x32_bf16 v[104:107], v[172:175], v[180:183], v[104:107]
	v_mfma_f32_16x16x32_bf16 v[100:103], v[164:167], v[188:191], v[100:103]
	v_mfma_f32_16x16x32_bf16 v[92:95], v[172:175], v[188:191], v[92:95]
	v_mfma_f32_16x16x32_bf16 v[84:87], v[164:167], v[196:199], v[84:87]
	v_mfma_f32_16x16x32_bf16 v[76:79], v[172:175], v[196:199], v[76:79]
	v_mfma_f32_16x16x32_bf16 v[68:71], v[164:167], v[204:207], v[68:71]
	v_mfma_f32_16x16x32_bf16 v[64:67], v[172:175], v[204:207], v[64:67]
	v_mfma_f32_16x16x32_bf16 v[108:111], v[168:171], v[184:187], v[108:111]
	v_mfma_f32_16x16x32_bf16 v[104:107], v[176:179], v[184:187], v[104:107]
	v_mfma_f32_16x16x32_bf16 v[100:103], v[168:171], v[192:195], v[100:103]
	v_mfma_f32_16x16x32_bf16 v[92:95], v[176:179], v[192:195], v[92:95]
	v_mfma_f32_16x16x32_bf16 v[84:87], v[168:171], v[200:203], v[84:87]
	v_mfma_f32_16x16x32_bf16 v[76:79], v[176:179], v[200:203], v[76:79]
	v_mfma_f32_16x16x32_bf16 v[68:71], v[168:171], v[208:211], v[68:71]
	v_mfma_f32_16x16x32_bf16 v[64:67], v[176:179], v[208:211], v[64:67]
	s_barrier
; #define PG8_STAGE(bufoff, gbase, voff) do { _Pragma("unroll") for (int _i = 0; _i < 2; ++_i) \
;         __builtin_amdgcn_global_load_lds((const unsigned*)((const char*)(gbase) + (voff)[_i]), (LAS unsigned*)(lds + (bufoff) + ldsw + _i * 8192), 16, 0, 0); } while (0)
; #define PG8_LDA(dst, b, h) do { _Pragma("unroll") for (int m = 0; m < 4; ++m) _Pragma("unroll") for (int k = 0; k < 2; ++k) dst[m][k] = *(const LAS bf16x8*)(lds + PG8_SA(b, h) + aoff + m * 2048 + k * 1024); } while (0)
; #define PG8_LDB(dst, b, h) do { _Pragma("unroll") for (int n = 0; n < 2; ++n) _Pragma("unroll") for (int k = 0; k < 2; ++k) dst[n][k] = *(const LAS bf16x8*)(lds + PG8_SB(b, h) + boff + n * 2048 + k * 1024); } while (0)
; #define PG8_MMA(ai, bj, At, Bt) do { __builtin_amdgcn_s_setprio(1); _Pragma("unroll") for (int m = 0; m < 4; ++m) _Pragma("unroll") for (int n = 0; n < 2; ++n) _Pragma("unroll") for (int k = 0; k < 2; ++k) \
;         acc[ai][bj][m][n] = __builtin_amdgcn_mfma_f32_16x16x32_bf16(Bt[n][k], At[m][k], acc[ai][bj][m][n], 0, 0, 0); __builtin_amdgcn_s_setprio(0); } while (0)
; #define PG8_WAIT_V(n) asm volatile("s_waitcnt vmcnt(" #n ")" ::: "memory")
; #define PG8_WAIT_L(n) asm volatile("s_waitcnt lgkmcnt(" #n ")" ::: "memory")
; template <class Epi>
; DI void gemm_phase(LAS unsigned char* lds, const int wid, const Gemm g, const Order& S, const Epi& E) {
;     ...
;             PG8_LDB(B0, 0, 0); PG8_LDB(B1, 0, 1); PG8_SCHED; PG8_LDA(At, 0, 0); PG8_STAGE(PG8_SA(1, 1), a1 + hstepA, voffA);
;             PG8_WAIT_V(8); PG8_WAIT_L(0); PG8_BAR; PG8_MMA(0, 0, At, B0); PG8_MMA(0, 1, At, B1); PG8_BAR; PG8_SCHED;
;             PG8_LDA(At, 0, 1); PG8_STAGE(PG8_SB(0, 0), b2, voffB); PG8_STAGE(PG8_SB(0, 1), b2 + hstepB, voffB); PG8_STAGE(PG8_SA(0, 0), a2, voffA);
;             PG8_WAIT_V(8); PG8_WAIT_L(0); PG8_BAR; PG8_MMA(1, 0, At, B0); PG8_MMA(1, 1, At, B1); PG8_BAR; PG8_SCHED;
;             PG8_LDB(B0, 1, 0); PG8_LDB(B1, 1, 1); PG8_SCHED; PG8_LDA(At, 1, 0); PG8_STAGE(PG8_SA(0, 1), a2 + hstepA, voffA);
;             PG8_WAIT_V(8); PG8_WAIT_L(0); PG8_BAR; PG8_MMA(0, 0, At, B0); PG8_MMA(0, 1, At, B1); PG8_BAR; PG8_SCHED;
;             PG8_LDA(At, 1, 1); PG8_STAGE(PG8_SB(1, 0), b3, voffB); PG8_STAGE(PG8_SB(1, 1), b3 + hstepB, voffB); PG8_STAGE(PG8_SA(1, 0), a3, voffA);
;             PG8_WAIT_V(8); PG8_WAIT_L(0); PG8_BAR; PG8_MMA(1, 0, At, B0); PG8_MMA(1, 1, At, B1); PG8_BAR; PG8_SCHED;
	s_add_i32 s44, s59, s94
	v_lshl_add_u64 v[212:213], v[212:213], 0, s[16:17]
	s_mov_b32 m0, s44
	ds_read_b128 v[180:183], v155 offset:49152
	ds_read_b128 v[184:187], v155 offset:50176
	ds_read_b128 v[188:191], v155 offset:51200
	ds_read_b128 v[192:195], v155 offset:52224
	ds_read_b128 v[196:199], v155 offset:53248
	ds_read_b128 v[200:203], v155 offset:54272
	ds_read_b128 v[204:207], v155 offset:55296
	ds_read_b128 v[208:211], v155 offset:56320
	global_load_lds_dwordx4 v[212:213], off
	s_add_i32 m0, s44, 0x2000
	s_add_u32 s42, s42, 0x20080
	v_lshl_add_u64 v[212:213], v[214:215], 0, s[16:17]
	s_addc_u32 s43, s43, 0
	s_add_i32 s44, s60, s94
	global_load_lds_dwordx4 v[212:213], off
	v_lshl_add_u64 v[212:213], s[42:43], 0, v[130:131]
	s_mov_b32 m0, s44
	s_nop 0
	global_load_lds_dwordx4 v[212:213], off
	v_lshl_add_u64 v[212:213], s[42:43], 0, v[134:135]
	s_add_i32 m0, s44, 0x2000
	s_nop 0
	global_load_lds_dwordx4 v[212:213], off
	v_lshl_add_u64 v[212:213], v[216:217], 0, s[16:17]
	s_mov_b32 m0, s49
	s_nop 0
	global_load_lds_dwordx4 v[212:213], off
	v_lshl_add_u64 v[212:213], v[218:219], 0, s[16:17]
	s_mov_b32 m0, s50
	s_nop 0
	global_load_lds_dwordx4 v[212:213], off
	s_waitcnt vmcnt(8)
	s_waitcnt lgkmcnt(0)
	s_barrier
	v_mfma_f32_16x16x32_bf16 v[60:63], v[144:147], v[180:183], v[60:63]
	v_mfma_f32_16x16x32_bf16 v[56:59], v[156:159], v[180:183], v[56:59]
	v_mfma_f32_16x16x32_bf16 v[48:51], v[144:147], v[188:191], v[48:51]
	v_mfma_f32_16x16x32_bf16 v[40:43], v[156:159], v[188:191], v[40:43]
	v_mfma_f32_16x16x32_bf16 v[32:35], v[144:147], v[196:199], v[32:35]
	v_mfma_f32_16x16x32_bf16 v[24:27], v[156:159], v[196:199], v[24:27]
	v_mfma_f32_16x16x32_bf16 v[16:19], v[144:147], v[204:207], v[16:19]
	v_mfma_f32_16x16x32_bf16 v[8:11], v[156:159], v[204:207], v[8:11]
	v_mfma_f32_16x16x32_bf16 v[60:63], v[148:151], v[184:187], v[60:63]
	v_mfma_f32_16x16x32_bf16 v[56:59], v[160:163], v[184:187], v[56:59]
	v_mfma_f32_16x16x32_bf16 v[48:51], v[148:151], v[192:195], v[48:51]
	v_mfma_f32_16x16x32_bf16 v[40:43], v[160:163], v[192:195], v[40:43]
	v_mfma_f32_16x16x32_bf16 v[32:35], v[148:151], v[200:203], v[32:35]
	v_mfma_f32_16x16x32_bf16 v[24:27], v[160:163], v[200:203], v[24:27]
	v_mfma_f32_16x16x32_bf16 v[16:19], v[148:151], v[208:211], v[16:19]
	v_mfma_f32_16x16x32_bf16 v[8:11], v[160:163], v[208:211], v[8:11]
	v_mfma_f32_16x16x32_bf16 v[52:55], v[164:167], v[180:183], v[52:55]
	v_mfma_f32_16x16x32_bf16 v[44:47], v[172:175], v[180:183], v[44:47]
	v_mfma_f32_16x16x32_bf16 v[36:39], v[164:167], v[188:191], v[36:39]
	v_mfma_f32_16x16x32_bf16 v[28:31], v[172:175], v[188:191], v[28:31]
	v_mfma_f32_16x16x32_bf16 v[20:23], v[164:167], v[196:199], v[20:23]
	v_mfma_f32_16x16x32_bf16 v[12:15], v[172:175], v[196:199], v[12:15]
	v_mfma_f32_16x16x32_bf16 v[4:7], v[164:167], v[204:207], v[4:7]
	v_mfma_f32_16x16x32_bf16 v[0:3], v[172:175], v[204:207], v[0:3]
	v_mfma_f32_16x16x32_bf16 v[52:55], v[168:171], v[184:187], v[52:55]
	v_mfma_f32_16x16x32_bf16 v[44:47], v[176:179], v[184:187], v[44:47]
	v_mfma_f32_16x16x32_bf16 v[36:39], v[168:171], v[192:195], v[36:39]
	v_mfma_f32_16x16x32_bf16 v[28:31], v[176:179], v[192:195], v[28:31]
	v_mfma_f32_16x16x32_bf16 v[20:23], v[168:171], v[200:203], v[20:23]
	v_mfma_f32_16x16x32_bf16 v[12:15], v[176:179], v[200:203], v[12:15]
	v_mfma_f32_16x16x32_bf16 v[4:7], v[168:171], v[208:211], v[4:7]
	v_mfma_f32_16x16x32_bf16 v[0:3], v[176:179], v[208:211], v[0:3]
	s_barrier
	s_add_i32 s58, s58, 2
	s_add_u32 s40, s40, 0x100
	s_addc_u32 s41, s41, 0
	s_add_u32 s56, s56, 0x100
	s_addc_u32 s57, s57, 0
	s_cmp_gt_u32 s58, 5
	s_cbranch_scc0 .LBB0_1013
	s_branch .Lpeel_exit_5
.LBB0_1013:
	ds_read_b128 v[144:147], v153
	ds_read_b128 v[148:151], v153 offset:1024
	ds_read_b128 v[156:159], v153 offset:2048
	ds_read_b128 v[160:163], v153 offset:3072
	ds_read_b128 v[164:167], v154
	ds_read_b128 v[168:171], v154 offset:1024
	ds_read_b128 v[172:175], v154 offset:2048
	ds_read_b128 v[176:179], v154 offset:3072
	s_add_u32 s42, s40, 0xfffe0080
	s_addc_u32 s43, s41, -1
	s_cmp_eq_u32 s58, 4
	s_cselect_b32 s45, s29, s43
	s_cselect_b32 s44, s54, s42
	s_cselect_b32 s43, s31, s57
	s_cselect_b32 s42, s55, s56
	v_lshl_add_u64 v[212:213], s[40:41], 0, v[136:137]
	s_add_i32 m0, s25, 0xc000
	ds_read_b128 v[180:183], v155
	ds_read_b128 v[184:187], v155 offset:1024
	ds_read_b128 v[188:191], v155 offset:2048
	ds_read_b128 v[192:195], v155 offset:3072
	ds_read_b128 v[196:199], v155 offset:4096
	ds_read_b128 v[200:203], v155 offset:5120
	ds_read_b128 v[204:207], v155 offset:6144
	ds_read_b128 v[208:211], v155 offset:7168
	global_load_lds_dwordx4 v[212:213], off
	v_lshl_add_u64 v[212:213], s[40:41], 0, v[138:139]
	s_add_i32 m0, s25, 0xe000
	s_nop 0
	global_load_lds_dwordx4 v[212:213], off
	s_waitcnt vmcnt(8)
	s_waitcnt lgkmcnt(0)
	s_barrier
; #define PG8_STAGE(bufoff, gbase, voff) do { _Pragma("unroll") for (int _i = 0; _i < 2; ++_i) \
;         __builtin_amdgcn_global_load_lds((const unsigned*)((const char*)(gbase) + (voff)[_i]), (LAS unsigned*)(lds + (bufoff) + ldsw + _i * 8192), 16, 0, 0); } while (0)
; #define PG8_LDA(dst, b, h) do { _Pragma("unroll") for (int m = 0; m < 4; ++m) _Pragma("unroll") for (int k = 0; k < 2; ++k) dst[m][k] = *(const LAS bf16x8*)(lds + PG8_SA(b, h) + aoff + m * 2048 + k * 1024); } while (0)
; #define PG8_LDB(dst, b, h) do { _Pragma("unroll") for (int n = 0; n < 2; ++n) _Pragma("unroll") for (int k = 0; k < 2; ++k) dst[n][k] = *(const LAS bf16x8*)(lds + PG8_SB(b, h) + boff + n * 2048 + k * 1024); } while (0)
; #define PG8_MMA(ai, bj, At, Bt) do { __builtin_amdgcn_s_setprio(1); _Pragma("unroll") for (int m = 0; m < 4; ++m) _Pragma("unroll") for (int n = 0; n < 2; ++n) _Pragma("unroll") for (int k = 0; k < 2; ++k) \
;         acc[ai][bj][m][n] = __builtin_amdgcn_mfma_f32_16x16x32_bf16(Bt[n][k], At[m][k], acc[ai][bj][m][n], 0, 0, 0); __builtin_amdgcn_s_setprio(0); } while (0)
; #define PG8_WAIT_V(n) asm volatile("s_waitcnt vmcnt(" #n ")" ::: "memory")
; #define PG8_WAIT_L(n) asm volatile("s_waitcnt lgkmcnt(" #n ")" ::: "memory")
; #define PG8_BAR __builtin_amdgcn_s_barrier()
; #define PG8_SCHED __builtin_amdgcn_sched_barrier(0)
; template <class Epi>
; DI void gemm_phase(LAS unsigned char* lds, const int wid, const Gemm g, const Order& S, const Epi& E) {
;     ...
;             PG8_LDB(B0, 0, 0); PG8_LDB(B1, 0, 1); PG8_SCHED; PG8_LDA(At, 0, 0); PG8_STAGE(PG8_SA(1, 1), a1 + hstepA, voffA);
;             PG8_WAIT_V(8); PG8_WAIT_L(0); PG8_BAR; PG8_MMA(0, 0, At, B0); PG8_MMA(0, 1, At, B1); PG8_BAR; PG8_SCHED;
;             PG8_LDA(At, 0, 1); PG8_STAGE(PG8_SB(0, 0), b2, voffB); PG8_STAGE(PG8_SB(0, 1), b2 + hstepB, voffB); PG8_STAGE(PG8_SA(0, 0), a2, voffA);
;             PG8_WAIT_V(8); PG8_WAIT_L(0); PG8_BAR; PG8_MMA(1, 0, At, B0); PG8_MMA(1, 1, At, B1); PG8_BAR; PG8_SCHED;
	v_mfma_f32_16x16x32_bf16 v[124:127], v[144:147], v[180:183], v[124:127]
	v_mfma_f32_16x16x32_bf16 v[120:123], v[156:159], v[180:183], v[120:123]
	v_mfma_f32_16x16x32_bf16 v[116:119], v[144:147], v[188:191], v[116:119]
	v_mfma_f32_16x16x32_bf16 v[112:115], v[156:159], v[188:191], v[112:115]
	v_mfma_f32_16x16x32_bf16 v[96:99], v[144:147], v[196:199], v[96:99]
	v_mfma_f32_16x16x32_bf16 v[88:91], v[156:159], v[196:199], v[88:91]
	v_mfma_f32_16x16x32_bf16 v[80:83], v[144:147], v[204:207], v[80:83]
	v_mfma_f32_16x16x32_bf16 v[72:75], v[156:159], v[204:207], v[72:75]
	v_mfma_f32_16x16x32_bf16 v[124:127], v[148:151], v[184:187], v[124:127]
	v_mfma_f32_16x16x32_bf16 v[120:123], v[160:163], v[184:187], v[120:123]
	v_mfma_f32_16x16x32_bf16 v[116:119], v[148:151], v[192:195], v[116:119]
	v_mfma_f32_16x16x32_bf16 v[112:115], v[160:163], v[192:195], v[112:115]
	v_mfma_f32_16x16x32_bf16 v[96:99], v[148:151], v[200:203], v[96:99]
	v_mfma_f32_16x16x32_bf16 v[88:91], v[160:163], v[200:203], v[88:91]
	v_mfma_f32_16x16x32_bf16 v[80:83], v[148:151], v[208:211], v[80:83]
	v_mfma_f32_16x16x32_bf16 v[72:75], v[160:163], v[208:211], v[72:75]
	v_mfma_f32_16x16x32_bf16 v[108:111], v[164:167], v[180:183], v[108:111]
	v_mfma_f32_16x16x32_bf16 v[104:107], v[172:175], v[180:183], v[104:107]
	v_mfma_f32_16x16x32_bf16 v[100:103], v[164:167], v[188:191], v[100:103]
	v_mfma_f32_16x16x32_bf16 v[92:95], v[172:175], v[188:191], v[92:95]
	v_mfma_f32_16x16x32_bf16 v[84:87], v[164:167], v[196:199], v[84:87]
	v_mfma_f32_16x16x32_bf16 v[76:79], v[172:175], v[196:199], v[76:79]
	v_mfma_f32_16x16x32_bf16 v[68:71], v[164:167], v[204:207], v[68:71]
	v_mfma_f32_16x16x32_bf16 v[64:67], v[172:175], v[204:207], v[64:67]
	v_mfma_f32_16x16x32_bf16 v[108:111], v[168:171], v[184:187], v[108:111]
	v_mfma_f32_16x16x32_bf16 v[104:107], v[176:179], v[184:187], v[104:107]
	v_mfma_f32_16x16x32_bf16 v[100:103], v[168:171], v[192:195], v[100:103]
	v_mfma_f32_16x16x32_bf16 v[92:95], v[176:179], v[192:195], v[92:95]
	v_mfma_f32_16x16x32_bf16 v[84:87], v[168:171], v[200:203], v[84:87]
	v_mfma_f32_16x16x32_bf16 v[76:79], v[176:179], v[200:203], v[76:79]
	v_mfma_f32_16x16x32_bf16 v[68:71], v[168:171], v[208:211], v[68:71]
	v_mfma_f32_16x16x32_bf16 v[64:67], v[176:179], v[208:211], v[64:67]
	s_barrier
	s_add_i32 s59, s51, s94
	v_lshl_add_u64 v[212:213], s[42:43], 0, v[130:131]
	s_mov_b32 m0, s59
	ds_read_b128 v[180:183], v155 offset:16384
	ds_read_b128 v[184:187], v155 offset:17408
	ds_read_b128 v[188:191], v155 offset:18432
	ds_read_b128 v[192:195], v155 offset:19456
	ds_read_b128 v[196:199], v155 offset:20480
	ds_read_b128 v[200:203], v155 offset:21504
	ds_read_b128 v[204:207], v155 offset:22528
	ds_read_b128 v[208:211], v155 offset:23552
	global_load_lds_dwordx4 v[212:213], off
	s_add_i32 m0, s59, 0x2000
	s_add_u32 s60, s42, 0x20000
	v_lshl_add_u64 v[214:215], s[42:43], 0, v[134:135]
	s_addc_u32 s61, s43, 0
	s_add_i32 s59, s52, s94
	global_load_lds_dwordx4 v[214:215], off
	v_lshl_add_u64 v[216:217], s[60:61], 0, v[130:131]
	s_mov_b32 m0, s59
	v_lshl_add_u64 v[218:219], s[44:45], 0, v[132:133]
	global_load_lds_dwordx4 v[216:217], off
	v_lshl_add_u64 v[216:217], s[60:61], 0, v[134:135]
	s_add_i32 m0, s59, 0x2000
	s_nop 0
	global_load_lds_dwordx4 v[216:217], off
	v_lshl_add_u64 v[216:217], s[44:45], 0, v[128:129]
	s_mov_b32 m0, s25
	s_nop 0
	global_load_lds_dwordx4 v[216:217], off
	s_mov_b32 m0, s39
	s_nop 0
	global_load_lds_dwordx4 v[218:219], off
	s_waitcnt vmcnt(8)
	s_waitcnt lgkmcnt(0)
	s_barrier
	v_mfma_f32_16x16x32_bf16 v[60:63], v[144:147], v[180:183], v[60:63]
	v_mfma_f32_16x16x32_bf16 v[56:59], v[156:159], v[180:183], v[56:59]
	v_mfma_f32_16x16x32_bf16 v[48:51], v[144:147], v[188:191], v[48:51]
	v_mfma_f32_16x16x32_bf16 v[40:43], v[156:159], v[188:191], v[40:43]
	v_mfma_f32_16x16x32_bf16 v[32:35], v[144:147], v[196:199], v[32:35]
	v_mfma_f32_16x16x32_bf16 v[24:27], v[156:159], v[196:199], v[24:27]
	v_mfma_f32_16x16x32_bf16 v[16:19], v[144:147], v[204:207], v[16:19]
	v_mfma_f32_16x16x32_bf16 v[8:11], v[156:159], v[204:207], v[8:11]
	v_mfma_f32_16x16x32_bf16 v[60:63], v[148:151], v[184:187], v[60:63]
	v_mfma_f32_16x16x32_bf16 v[56:59], v[160:163], v[184:187], v[56:59]
	v_mfma_f32_16x16x32_bf16 v[48:51], v[148:151], v[192:195], v[48:51]
	v_mfma_f32_16x16x32_bf16 v[40:43], v[160:163], v[192:195], v[40:43]
	v_mfma_f32_16x16x32_bf16 v[32:35], v[148:151], v[200:203], v[32:35]
	v_mfma_f32_16x16x32_bf16 v[24:27], v[160:163], v[200:203], v[24:27]
	v_mfma_f32_16x16x32_bf16 v[16:19], v[148:151], v[208:211], v[16:19]
	v_mfma_f32_16x16x32_bf16 v[8:11], v[160:163], v[208:211], v[8:11]
	v_mfma_f32_16x16x32_bf16 v[52:55], v[164:167], v[180:183], v[52:55]
	v_mfma_f32_16x16x32_bf16 v[44:47], v[172:175], v[180:183], v[44:47]
	v_mfma_f32_16x16x32_bf16 v[36:39], v[164:167], v[188:191], v[36:39]
	v_mfma_f32_16x16x32_bf16 v[28:31], v[172:175], v[188:191], v[28:31]
	v_mfma_f32_16x16x32_bf16 v[20:23], v[164:167], v[196:199], v[20:23]
	v_mfma_f32_16x16x32_bf16 v[12:15], v[172:175], v[196:199], v[12:15]
	v_mfma_f32_16x16x32_bf16 v[4:7], v[164:167], v[204:207], v[4:7]
	v_mfma_f32_16x16x32_bf16 v[0:3], v[172:175], v[204:207], v[0:3]
	v_mfma_f32_16x16x32_bf16 v[52:55], v[168:171], v[184:187], v[52:55]
	v_mfma_f32_16x16x32_bf16 v[44:47], v[176:179], v[184:187], v[44:47]
	v_mfma_f32_16x16x32_bf16 v[36:39], v[168:171], v[192:195], v[36:39]
	v_mfma_f32_16x16x32_bf16 v[28:31], v[176:179], v[192:195], v[28:31]
	v_mfma_f32_16x16x32_bf16 v[20:23], v[168:171], v[200:203], v[20:23]
	v_mfma_f32_16x16x32_bf16 v[12:15], v[176:179], v[200:203], v[12:15]
	v_mfma_f32_16x16x32_bf16 v[4:7], v[168:171], v[208:211], v[4:7]
	v_mfma_f32_16x16x32_bf16 v[0:3], v[176:179], v[208:211], v[0:3]
	s_barrier
; #define PG8_STAGE(bufoff, gbase, voff) do { _Pragma("unroll") for (int _i = 0; _i < 2; ++_i) \
;         __builtin_amdgcn_global_load_lds((const unsigned*)((const char*)(gbase) + (voff)[_i]), (LAS unsigned*)(lds + (bufoff) + ldsw + _i * 8192), 16, 0, 0); } while (0)
; #define PG8_LDA(dst, b, h) do { _Pragma("unroll") for (int m = 0; m < 4; ++m) _Pragma("unroll") for (int k = 0; k < 2; ++k) dst[m][k] = *(const LAS bf16x8*)(lds + PG8_SA(b, h) + aoff + m * 2048 + k * 1024); } while (0)
; #define PG8_LDB(dst, b, h) do { _Pragma("unroll") for (int n = 0; n < 2; ++n) _Pragma("unroll") for (int k = 0; k < 2; ++k) dst[n][k] = *(const LAS bf16x8*)(lds + PG8_SB(b, h) + boff + n * 2048 + k * 1024); } while (0)
; #define PG8_MMA(ai, bj, At, Bt) do { __builtin_amdgcn_s_setprio(1); _Pragma("unroll") for (int m = 0; m < 4; ++m) _Pragma("unroll") for (int n = 0; n < 2; ++n) _Pragma("unroll") for (int k = 0; k < 2; ++k) \
;         acc[ai][bj][m][n] = __builtin_amdgcn_mfma_f32_16x16x32_bf16(Bt[n][k], At[m][k], acc[ai][bj][m][n], 0, 0, 0); __builtin_amdgcn_s_setprio(0); } while (0)
; #define PG8_WAIT_V(n) asm volatile("s_waitcnt vmcnt(" #n ")" ::: "memory")
; #define PG8_WAIT_L(n) asm volatile("s_waitcnt lgkmcnt(" #n ")" ::: "memory")
; #define PG8_BAR __builtin_amdgcn_s_barrier()
; #define PG8_SCHED __builtin_amdgcn_sched_barrier(0)
; template <class Epi>
; DI void gemm_phase(LAS unsigned char* lds, const int wid, const Gemm g, const Order& S, const Epi& E) {
;     ...
;             PG8_LDB(B0, 1, 0); PG8_LDB(B1, 1, 1); PG8_SCHED; PG8_LDA(At, 1, 0); PG8_STAGE(PG8_SA(0, 1), a2 + hstepA, voffA);
;             PG8_WAIT_V(8); PG8_WAIT_L(0); PG8_BAR; PG8_MMA(0, 0, At, B0); PG8_MMA(0, 1, At, B1); PG8_BAR; PG8_SCHED;
;             PG8_LDA(At, 1, 1); PG8_STAGE(PG8_SB(1, 0), b3, voffB); PG8_STAGE(PG8_SB(1, 1), b3 + hstepB, voffB); PG8_STAGE(PG8_SA(1, 0), a3, voffA);
;             PG8_WAIT_V(8); PG8_WAIT_L(0); PG8_BAR; PG8_MMA(1, 0, At, B0); PG8_MMA(1, 1, At, B1); PG8_BAR; PG8_SCHED;
	s_add_i32 s59, 0, 0x18000
	s_add_i32 s60, 0, 0x1c000
	v_add_u32_e32 v160, s59, v152
	v_add_u32_e32 v176, s60, v152
	ds_read_b128 v[144:147], v160
	ds_read_b128 v[148:151], v160 offset:1024
	ds_read_b128 v[156:159], v160 offset:2048
	ds_read_b128 v[160:163], v160 offset:3072
	ds_read_b128 v[164:167], v176
	ds_read_b128 v[168:171], v176 offset:1024
	ds_read_b128 v[172:175], v176 offset:2048
	ds_read_b128 v[176:179], v176 offset:3072
	s_add_u32 s44, s44, 0x20000
	s_addc_u32 s45, s45, 0
	s_mov_b32 m0, s46
	v_lshl_add_u64 v[220:221], s[44:45], 0, v[128:129]
	ds_read_b128 v[180:183], v155 offset:32768
	ds_read_b128 v[184:187], v155 offset:33792
	ds_read_b128 v[188:191], v155 offset:34816
	ds_read_b128 v[192:195], v155 offset:35840
	ds_read_b128 v[196:199], v155 offset:36864
	ds_read_b128 v[200:203], v155 offset:37888
	ds_read_b128 v[204:207], v155 offset:38912
	ds_read_b128 v[208:211], v155 offset:39936
	global_load_lds_dwordx4 v[220:221], off
	v_lshl_add_u64 v[220:221], s[44:45], 0, v[132:133]
	s_mov_b32 m0, s47
	s_nop 0
	global_load_lds_dwordx4 v[220:221], off
	s_waitcnt vmcnt(8)
	s_waitcnt lgkmcnt(0)
	s_barrier
	v_mfma_f32_16x16x32_bf16 v[124:127], v[144:147], v[180:183], v[124:127]
	v_mfma_f32_16x16x32_bf16 v[120:123], v[156:159], v[180:183], v[120:123]
	v_mfma_f32_16x16x32_bf16 v[116:119], v[144:147], v[188:191], v[116:119]
	v_mfma_f32_16x16x32_bf16 v[112:115], v[156:159], v[188:191], v[112:115]
	v_mfma_f32_16x16x32_bf16 v[96:99], v[144:147], v[196:199], v[96:99]
	v_mfma_f32_16x16x32_bf16 v[88:91], v[156:159], v[196:199], v[88:91]
	v_mfma_f32_16x16x32_bf16 v[80:83], v[144:147], v[204:207], v[80:83]
	v_mfma_f32_16x16x32_bf16 v[72:75], v[156:159], v[204:207], v[72:75]
	v_mfma_f32_16x16x32_bf16 v[124:127], v[148:151], v[184:187], v[124:127]
	v_mfma_f32_16x16x32_bf16 v[120:123], v[160:163], v[184:187], v[120:123]
	v_mfma_f32_16x16x32_bf16 v[116:119], v[148:151], v[192:195], v[116:119]
	v_mfma_f32_16x16x32_bf16 v[112:115], v[160:163], v[192:195], v[112:115]
	v_mfma_f32_16x16x32_bf16 v[96:99], v[148:151], v[200:203], v[96:99]
	v_mfma_f32_16x16x32_bf16 v[88:91], v[160:163], v[200:203], v[88:91]
	v_mfma_f32_16x16x32_bf16 v[80:83], v[148:151], v[208:211], v[80:83]
	v_mfma_f32_16x16x32_bf16 v[72:75], v[160:163], v[208:211], v[72:75]
	v_mfma_f32_16x16x32_bf16 v[108:111], v[164:167], v[180:183], v[108:111]
	v_mfma_f32_16x16x32_bf16 v[104:107], v[172:175], v[180:183], v[104:107]
	v_mfma_f32_16x16x32_bf16 v[100:103], v[164:167], v[188:191], v[100:103]
	v_mfma_f32_16x16x32_bf16 v[92:95], v[172:175], v[188:191], v[92:95]
	v_mfma_f32_16x16x32_bf16 v[84:87], v[164:167], v[196:199], v[84:87]
	v_mfma_f32_16x16x32_bf16 v[76:79], v[172:175], v[196:199], v[76:79]
	v_mfma_f32_16x16x32_bf16 v[68:71], v[164:167], v[204:207], v[68:71]
	v_mfma_f32_16x16x32_bf16 v[64:67], v[172:175], v[204:207], v[64:67]
	v_mfma_f32_16x16x32_bf16 v[108:111], v[168:171], v[184:187], v[108:111]
	v_mfma_f32_16x16x32_bf16 v[104:107], v[176:179], v[184:187], v[104:107]
	v_mfma_f32_16x16x32_bf16 v[100:103], v[168:171], v[192:195], v[100:103]
	v_mfma_f32_16x16x32_bf16 v[92:95], v[176:179], v[192:195], v[92:95]
	v_mfma_f32_16x16x32_bf16 v[84:87], v[168:171], v[200:203], v[84:87]
	v_mfma_f32_16x16x32_bf16 v[76:79], v[176:179], v[200:203], v[76:79]
	v_mfma_f32_16x16x32_bf16 v[68:71], v[168:171], v[208:211], v[68:71]
	v_mfma_f32_16x16x32_bf16 v[64:67], v[176:179], v[208:211], v[64:67]
	s_barrier
	s_add_i32 s44, s59, s94
	v_lshl_add_u64 v[212:213], v[212:213], 0, s[16:17]
	s_mov_b32 m0, s44
	ds_read_b128 v[180:183], v155 offset:49152
	ds_read_b128 v[184:187], v155 offset:50176
	ds_read_b128 v[188:191], v155 offset:51200
	ds_read_b128 v[192:195], v155 offset:52224
	ds_read_b128 v[196:199], v155 offset:53248
	ds_read_b128 v[200:203], v155 offset:54272
	ds_read_b128 v[204:207], v155 offset:55296
	ds_read_b128 v[208:211], v155 offset:56320
	global_load_lds_dwordx4 v[212:213], off
	s_add_i32 m0, s44, 0x2000
	s_add_u32 s42, s42, 0x20080
	v_lshl_add_u64 v[212:213], v[214:215], 0, s[16:17]
	s_addc_u32 s43, s43, 0
	s_add_i32 s44, s60, s94
	global_load_lds_dwordx4 v[212:213], off
	v_lshl_add_u64 v[212:213], s[42:43], 0, v[130:131]
	s_mov_b32 m0, s44
	s_nop 0
	global_load_lds_dwordx4 v[212:213], off
	v_lshl_add_u64 v[212:213], s[42:43], 0, v[134:135]
	s_add_i32 m0, s44, 0x2000
	s_nop 0
	global_load_lds_dwordx4 v[212:213], off
	v_lshl_add_u64 v[212:213], v[216:217], 0, s[16:17]
	s_mov_b32 m0, s49
	s_nop 0
	global_load_lds_dwordx4 v[212:213], off
	v_lshl_add_u64 v[212:213], v[218:219], 0, s[16:17]
	s_mov_b32 m0, s50
	s_nop 0
	global_load_lds_dwordx4 v[212:213], off
	s_waitcnt vmcnt(8)
	s_waitcnt lgkmcnt(0)
	s_barrier
	v_mfma_f32_16x16x32_bf16 v[60:63], v[144:147], v[180:183], v[60:63]
	v_mfma_f32_16x16x32_bf16 v[56:59], v[156:159], v[180:183], v[56:59]
	v_mfma_f32_16x16x32_bf16 v[48:51], v[144:147], v[188:191], v[48:51]
	v_mfma_f32_16x16x32_bf16 v[40:43], v[156:159], v[188:191], v[40:43]
	v_mfma_f32_16x16x32_bf16 v[32:35], v[144:147], v[196:199], v[32:35]
	v_mfma_f32_16x16x32_bf16 v[24:27], v[156:159], v[196:199], v[24:27]
	v_mfma_f32_16x16x32_bf16 v[16:19], v[144:147], v[204:207], v[16:19]
	v_mfma_f32_16x16x32_bf16 v[8:11], v[156:159], v[204:207], v[8:11]
	v_mfma_f32_16x16x32_bf16 v[60:63], v[148:151], v[184:187], v[60:63]
	v_mfma_f32_16x16x32_bf16 v[56:59], v[160:163], v[184:187], v[56:59]
	v_mfma_f32_16x16x32_bf16 v[48:51], v[148:151], v[192:195], v[48:51]
	v_mfma_f32_16x16x32_bf16 v[40:43], v[160:163], v[192:195], v[40:43]
	v_mfma_f32_16x16x32_bf16 v[32:35], v[148:151], v[200:203], v[32:35]
	v_mfma_f32_16x16x32_bf16 v[24:27], v[160:163], v[200:203], v[24:27]
	v_mfma_f32_16x16x32_bf16 v[16:19], v[148:151], v[208:211], v[16:19]
	v_mfma_f32_16x16x32_bf16 v[8:11], v[160:163], v[208:211], v[8:11]
	v_mfma_f32_16x16x32_bf16 v[52:55], v[164:167], v[180:183], v[52:55]
	v_mfma_f32_16x16x32_bf16 v[44:47], v[172:175], v[180:183], v[44:47]
	v_mfma_f32_16x16x32_bf16 v[36:39], v[164:167], v[188:191], v[36:39]
	v_mfma_f32_16x16x32_bf16 v[28:31], v[172:175], v[188:191], v[28:31]
	v_mfma_f32_16x16x32_bf16 v[20:23], v[164:167], v[196:199], v[20:23]
	v_mfma_f32_16x16x32_bf16 v[12:15], v[172:175], v[196:199], v[12:15]
	v_mfma_f32_16x16x32_bf16 v[4:7], v[164:167], v[204:207], v[4:7]
	v_mfma_f32_16x16x32_bf16 v[0:3], v[172:175], v[204:207], v[0:3]
	v_mfma_f32_16x16x32_bf16 v[52:55], v[168:171], v[184:187], v[52:55]
	v_mfma_f32_16x16x32_bf16 v[44:47], v[176:179], v[184:187], v[44:47]
	v_mfma_f32_16x16x32_bf16 v[36:39], v[168:171], v[192:195], v[36:39]
	v_mfma_f32_16x16x32_bf16 v[28:31], v[176:179], v[192:195], v[28:31]
	v_mfma_f32_16x16x32_bf16 v[20:23], v[168:171], v[200:203], v[20:23]
	v_mfma_f32_16x16x32_bf16 v[12:15], v[176:179], v[200:203], v[12:15]
	v_mfma_f32_16x16x32_bf16 v[4:7], v[168:171], v[208:211], v[4:7]
	v_mfma_f32_16x16x32_bf16 v[0:3], v[176:179], v[208:211], v[0:3]
	s_barrier
	s_add_i32 s58, s58, 2
	s_add_u32 s40, s40, 0x100
	s_addc_u32 s41, s41, 0
	s_add_u32 s56, s56, 0x100
	s_addc_u32 s57, s57, 0
	s_cmp_gt_u32 s58, 5
	s_cbranch_scc0 .LBB0_1013

; #define PG8_STAGE(bufoff, gbase, voff) do { _Pragma("unroll") for (int _i = 0; _i < 2; ++_i) \
;         __builtin_amdgcn_global_load_lds((const unsigned*)((const char*)(gbase) + (voff)[_i]), (LAS unsigned*)(lds + (bufoff) + ldsw + _i * 8192), 16, 0, 0); } while (0)
; #define PG8_LDA(dst, b, h) do { _Pragma("unroll") for (int m = 0; m < 4; ++m) _Pragma("unroll") for (int k = 0; k < 2; ++k) dst[m][k] = *(const LAS bf16x8*)(lds + PG8_SA(b, h) + aoff + m * 2048 + k * 1024); } while (0)
; #define PG8_LDB(dst, b, h) do { _Pragma("unroll") for (int n = 0; n < 2; ++n) _Pragma("unroll") for (int k = 0; k < 2; ++k) dst[n][k] = *(const LAS bf16x8*)(lds + PG8_SB(b, h) + boff + n * 2048 + k * 1024); } while (0)
; #define PG8_MMA(ai, bj, At, Bt) do { __builtin_amdgcn_s_setprio(1); _Pragma("unroll") for (int m = 0; m < 4; ++m) _Pragma("unroll") for (int n = 0; n < 2; ++n) _Pragma("unroll") for (int k = 0; k < 2; ++k) \
;         acc[ai][bj][m][n] = __builtin_amdgcn_mfma_f32_16x16x32_bf16(Bt[n][k], At[m][k], acc[ai][bj][m][n], 0, 0, 0); __builtin_amdgcn_s_setprio(0); } while (0)
; template <class Epi>
; DI void gemm_phase(LAS unsigned char* lds, const int wid, const Gemm g, const Order& S, const Epi& E) {
;     ...
;         const bool has_next = S.next(ui + 1, nxt);
;         const char* nA = has_next ? (const char*)(g.A + (size_t)nxt.g * g.gsA + (size_t)nxt.pm * BM * g.lda) : cA;
;         const char* nB = has_next ? (const char*)(g.Bt + (size_t)nxt.g * g.gsB + (size_t)nxt.pn * BM * g.ldb) : cB;
;         for (int t = 0; t < nt; t += 2) {
;             const bool last = (t == nt - 2);
;             const char* a1 = cA + (size_t)(t + 1) * kstep;
;             const char* a2 = last ? nA : cA + (size_t)(t + 2) * kstep; const char* b2 = last ? nB : cB + (size_t)(t + 2) * kstep;
;             const char* a3 = a2 + kstep; const char* b3 = b2 + kstep;
;             PG8_LDB(B0, 0, 0); PG8_LDB(B1, 0, 1); PG8_SCHED; PG8_LDA(At, 0, 0); PG8_STAGE(PG8_SA(1, 1), a1 + hstepA, voffA);
;             PG8_WAIT_V(8); PG8_WAIT_L(0); PG8_BAR; PG8_MMA(0, 0, At, B0); PG8_MMA(0, 1, At, B1); PG8_BAR; PG8_SCHED;
;             PG8_LDA(At, 0, 1); PG8_STAGE(PG8_SB(0, 0), b2, voffB); PG8_STAGE(PG8_SB(0, 1), b2 + hstepB, voffB); PG8_STAGE(PG8_SA(0, 0), a2, voffA);
;             PG8_WAIT_V(8); PG8_WAIT_L(0); PG8_BAR; PG8_MMA(1, 0, At, B0); PG8_MMA(1, 1, At, B1); PG8_BAR; PG8_SCHED;
.LBB0_1090:
	s_ashr_i32 s29, s28, 31
	s_lshl_b64 s[34:35], s[28:29], 18
	s_add_u32 s34, s6, s34
	s_addc_u32 s35, s7, s35
	s_and_b64 s[36:37], s[8:9], exec
	s_cselect_b32 s29, s35, s41
	s_cselect_b32 s54, s34, s40
	s_ashr_i32 s31, s30, 31
	s_lshl_b64 s[36:37], s[30:31], 18
	s_add_u32 s36, s21, s36
	s_addc_u32 s37, s24, s37
	s_and_b64 s[44:45], s[8:9], exec
	s_cselect_b32 s31, s37, s43
	s_cselect_b32 s55, s36, s42
	s_add_u32 s40, s40, 0x20080
	s_addc_u32 s41, s41, 0
	s_add_u32 s56, s42, 0x100
	v_mov_b32_e32 v0, 0
	s_addc_u32 s57, s43, 0
	s_mov_b32 s58, -2
	ds_read_b128 v[128:131], v165
	ds_read_b128 v[132:135], v165 offset:1024
	ds_read_b128 v[136:139], v165 offset:2048
	ds_read_b128 v[140:143], v165 offset:3072
	ds_read_b128 v[160:163], v166
	ds_read_b128 v[168:171], v166 offset:1024
	ds_read_b128 v[172:175], v166 offset:2048
	ds_read_b128 v[176:179], v166 offset:3072
	s_add_u32 s42, s40, 0xfffe0080
	s_addc_u32 s43, s41, -1
	s_cmp_eq_u32 s58, 4
	s_cselect_b32 s45, s29, s43
	s_cselect_b32 s44, s54, s42
	s_cselect_b32 s43, s31, s57
	s_cselect_b32 s42, s55, s56
	v_lshl_add_u64 v[212:213], s[40:41], 0, v[152:153]
	s_add_i32 m0, s25, 0xc000
	ds_read_b128 v[180:183], v167
	ds_read_b128 v[184:187], v167 offset:1024
	ds_read_b128 v[188:191], v167 offset:2048
	ds_read_b128 v[192:195], v167 offset:3072
	ds_read_b128 v[196:199], v167 offset:4096
	ds_read_b128 v[200:203], v167 offset:5120
	ds_read_b128 v[204:207], v167 offset:6144
	ds_read_b128 v[208:211], v167 offset:7168
	global_load_lds_dwordx4 v[212:213], off
	v_lshl_add_u64 v[212:213], s[40:41], 0, v[154:155]
	s_add_i32 m0, s25, 0xe000
	s_nop 0
	global_load_lds_dwordx4 v[212:213], off
	s_waitcnt vmcnt(8)
	s_waitcnt lgkmcnt(0)
	s_barrier
	v_mfma_f32_16x16x32_bf16 v[124:127], v[128:131], v[180:183], 0
	v_mfma_f32_16x16x32_bf16 v[120:123], v[136:139], v[180:183], 0
	v_mfma_f32_16x16x32_bf16 v[116:119], v[128:131], v[188:191], 0
	v_mfma_f32_16x16x32_bf16 v[104:107], v[136:139], v[188:191], 0
	v_mfma_f32_16x16x32_bf16 v[92:95], v[128:131], v[196:199], 0
	v_mfma_f32_16x16x32_bf16 v[88:91], v[136:139], v[196:199], 0
	v_mfma_f32_16x16x32_bf16 v[76:79], v[128:131], v[204:207], 0
	v_mfma_f32_16x16x32_bf16 v[72:75], v[136:139], v[204:207], 0
	v_mfma_f32_16x16x32_bf16 v[124:127], v[132:135], v[184:187], v[124:127]
	v_mfma_f32_16x16x32_bf16 v[120:123], v[140:143], v[184:187], v[120:123]
	v_mfma_f32_16x16x32_bf16 v[116:119], v[132:135], v[192:195], v[116:119]
	v_mfma_f32_16x16x32_bf16 v[104:107], v[140:143], v[192:195], v[104:107]
	v_mfma_f32_16x16x32_bf16 v[92:95], v[132:135], v[200:203], v[92:95]
	v_mfma_f32_16x16x32_bf16 v[88:91], v[140:143], v[200:203], v[88:91]
	v_mfma_f32_16x16x32_bf16 v[76:79], v[132:135], v[208:211], v[76:79]
	v_mfma_f32_16x16x32_bf16 v[72:75], v[140:143], v[208:211], v[72:75]
	v_mfma_f32_16x16x32_bf16 v[112:115], v[160:163], v[180:183], 0
	v_mfma_f32_16x16x32_bf16 v[108:111], v[172:175], v[180:183], 0
	v_mfma_f32_16x16x32_bf16 v[100:103], v[160:163], v[188:191], 0
	v_mfma_f32_16x16x32_bf16 v[96:99], v[172:175], v[188:191], 0
	v_mfma_f32_16x16x32_bf16 v[84:87], v[160:163], v[196:199], 0
	v_mfma_f32_16x16x32_bf16 v[80:83], v[172:175], v[196:199], 0
	v_mfma_f32_16x16x32_bf16 v[68:71], v[160:163], v[204:207], 0
	v_mfma_f32_16x16x32_bf16 v[64:67], v[172:175], v[204:207], 0
	v_mfma_f32_16x16x32_bf16 v[112:115], v[168:171], v[184:187], v[112:115]
	v_mfma_f32_16x16x32_bf16 v[108:111], v[176:179], v[184:187], v[108:111]
	v_mfma_f32_16x16x32_bf16 v[100:103], v[168:171], v[192:195], v[100:103]
	v_mfma_f32_16x16x32_bf16 v[96:99], v[176:179], v[192:195], v[96:99]
	v_mfma_f32_16x16x32_bf16 v[84:87], v[168:171], v[200:203], v[84:87]
	v_mfma_f32_16x16x32_bf16 v[80:83], v[176:179], v[200:203], v[80:83]
	v_mfma_f32_16x16x32_bf16 v[68:71], v[168:171], v[208:211], v[68:71]
	v_mfma_f32_16x16x32_bf16 v[64:67], v[176:179], v[208:211], v[64:67]
	s_barrier
	s_add_i32 s59, s51, s94
	v_lshl_add_u64 v[212:213], s[42:43], 0, v[146:147]
	s_mov_b32 m0, s59
	ds_read_b128 v[180:183], v167 offset:16384
	ds_read_b128 v[184:187], v167 offset:17408
	ds_read_b128 v[188:191], v167 offset:18432
	ds_read_b128 v[192:195], v167 offset:19456
	ds_read_b128 v[196:199], v167 offset:20480
	ds_read_b128 v[200:203], v167 offset:21504
	ds_read_b128 v[204:207], v167 offset:22528
	ds_read_b128 v[208:211], v167 offset:23552
	global_load_lds_dwordx4 v[212:213], off
	s_add_i32 m0, s59, 0x2000
	s_add_u32 s60, s42, 0x20000
	v_lshl_add_u64 v[214:215], s[42:43], 0, v[150:151]
	s_addc_u32 s61, s43, 0
	s_add_i32 s59, s52, s94
	global_load_lds_dwordx4 v[214:215], off
	v_lshl_add_u64 v[216:217], s[60:61], 0, v[146:147]
	s_mov_b32 m0, s59
	v_lshl_add_u64 v[218:219], s[44:45], 0, v[148:149]
	global_load_lds_dwordx4 v[216:217], off
	v_lshl_add_u64 v[216:217], s[60:61], 0, v[150:151]
	s_add_i32 m0, s59, 0x2000
	s_nop 0
	global_load_lds_dwordx4 v[216:217], off
	v_lshl_add_u64 v[216:217], s[44:45], 0, v[144:145]
	s_mov_b32 m0, s25
	s_nop 0
	global_load_lds_dwordx4 v[216:217], off
	s_mov_b32 m0, s39
	s_nop 0
	global_load_lds_dwordx4 v[218:219], off
	s_waitcnt vmcnt(8)
	s_waitcnt lgkmcnt(0)
	s_barrier
; #define PG8_STAGE(bufoff, gbase, voff) do { _Pragma("unroll") for (int _i = 0; _i < 2; ++_i) \
;         __builtin_amdgcn_global_load_lds((const unsigned*)((const char*)(gbase) + (voff)[_i]), (LAS unsigned*)(lds + (bufoff) + ldsw + _i * 8192), 16, 0, 0); } while (0)
; #define PG8_LDA(dst, b, h) do { _Pragma("unroll") for (int m = 0; m < 4; ++m) _Pragma("unroll") for (int k = 0; k < 2; ++k) dst[m][k] = *(const LAS bf16x8*)(lds + PG8_SA(b, h) + aoff + m * 2048 + k * 1024); } while (0)
; #define PG8_LDB(dst, b, h) do { _Pragma("unroll") for (int n = 0; n < 2; ++n) _Pragma("unroll") for (int k = 0; k < 2; ++k) dst[n][k] = *(const LAS bf16x8*)(lds + PG8_SB(b, h) + boff + n * 2048 + k * 1024); } while (0)
; #define PG8_MMA(ai, bj, At, Bt) do { __builtin_amdgcn_s_setprio(1); _Pragma("unroll") for (int m = 0; m < 4; ++m) _Pragma("unroll") for (int n = 0; n < 2; ++n) _Pragma("unroll") for (int k = 0; k < 2; ++k) \
;         acc[ai][bj][m][n] = __builtin_amdgcn_mfma_f32_16x16x32_bf16(Bt[n][k], At[m][k], acc[ai][bj][m][n], 0, 0, 0); __builtin_amdgcn_s_setprio(0); } while (0)
; #define PG8_WAIT_V(n) asm volatile("s_waitcnt vmcnt(" #n ")" ::: "memory")
; #define PG8_WAIT_L(n) asm volatile("s_waitcnt lgkmcnt(" #n ")" ::: "memory")
; template <class Epi>
; DI void gemm_phase(LAS unsigned char* lds, const int wid, const Gemm g, const Order& S, const Epi& E) {
;     ...
;             PG8_LDB(B0, 0, 0); PG8_LDB(B1, 0, 1); PG8_SCHED; PG8_LDA(At, 0, 0); PG8_STAGE(PG8_SA(1, 1), a1 + hstepA, voffA);
;             PG8_WAIT_V(8); PG8_WAIT_L(0); PG8_BAR; PG8_MMA(0, 0, At, B0); PG8_MMA(0, 1, At, B1); PG8_BAR; PG8_SCHED;
;             PG8_LDA(At, 0, 1); PG8_STAGE(PG8_SB(0, 0), b2, voffB); PG8_STAGE(PG8_SB(0, 1), b2 + hstepB, voffB); PG8_STAGE(PG8_SA(0, 0), a2, voffA);
;             PG8_WAIT_V(8); PG8_WAIT_L(0); PG8_BAR; PG8_MMA(1, 0, At, B0); PG8_MMA(1, 1, At, B1); PG8_BAR; PG8_SCHED;
;             PG8_LDB(B0, 1, 0); PG8_LDB(B1, 1, 1); PG8_SCHED; PG8_LDA(At, 1, 0); PG8_STAGE(PG8_SA(0, 1), a2 + hstepA, voffA);
;             PG8_WAIT_V(8); PG8_WAIT_L(0); PG8_BAR; PG8_MMA(0, 0, At, B0); PG8_MMA(0, 1, At, B1); PG8_BAR; PG8_SCHED;
;             PG8_LDA(At, 1, 1); PG8_STAGE(PG8_SB(1, 0), b3, voffB); PG8_STAGE(PG8_SB(1, 1), b3 + hstepB, voffB); PG8_STAGE(PG8_SA(1, 0), a3, voffA);
;             PG8_WAIT_V(8); PG8_WAIT_L(0); PG8_BAR; PG8_MMA(1, 0, At, B0); PG8_MMA(1, 1, At, B1); PG8_BAR; PG8_SCHED;
	v_mfma_f32_16x16x32_bf16 v[60:63], v[128:131], v[180:183], 0
	v_mfma_f32_16x16x32_bf16 v[56:59], v[136:139], v[180:183], 0
	v_mfma_f32_16x16x32_bf16 v[44:47], v[128:131], v[188:191], 0
	v_mfma_f32_16x16x32_bf16 v[40:43], v[136:139], v[188:191], 0
	v_mfma_f32_16x16x32_bf16 v[28:31], v[128:131], v[196:199], 0
	v_mfma_f32_16x16x32_bf16 v[24:27], v[136:139], v[196:199], 0
	v_mfma_f32_16x16x32_bf16 v[12:15], v[128:131], v[204:207], 0
	v_mfma_f32_16x16x32_bf16 v[8:11], v[136:139], v[204:207], 0
	v_mfma_f32_16x16x32_bf16 v[60:63], v[132:135], v[184:187], v[60:63]
	v_mfma_f32_16x16x32_bf16 v[56:59], v[140:143], v[184:187], v[56:59]
	v_mfma_f32_16x16x32_bf16 v[44:47], v[132:135], v[192:195], v[44:47]
	v_mfma_f32_16x16x32_bf16 v[40:43], v[140:143], v[192:195], v[40:43]
	v_mfma_f32_16x16x32_bf16 v[28:31], v[132:135], v[200:203], v[28:31]
	v_mfma_f32_16x16x32_bf16 v[24:27], v[140:143], v[200:203], v[24:27]
	v_mfma_f32_16x16x32_bf16 v[12:15], v[132:135], v[208:211], v[12:15]
	v_mfma_f32_16x16x32_bf16 v[8:11], v[140:143], v[208:211], v[8:11]
	v_mfma_f32_16x16x32_bf16 v[52:55], v[160:163], v[180:183], 0
	v_mfma_f32_16x16x32_bf16 v[48:51], v[172:175], v[180:183], 0
	v_mfma_f32_16x16x32_bf16 v[36:39], v[160:163], v[188:191], 0
	v_mfma_f32_16x16x32_bf16 v[32:35], v[172:175], v[188:191], 0
	v_mfma_f32_16x16x32_bf16 v[20:23], v[160:163], v[196:199], 0
	v_mfma_f32_16x16x32_bf16 v[16:19], v[172:175], v[196:199], 0
	v_mfma_f32_16x16x32_bf16 v[4:7], v[160:163], v[204:207], 0
	v_mfma_f32_16x16x32_bf16 v[0:3], v[172:175], v[204:207], 0
	v_mfma_f32_16x16x32_bf16 v[52:55], v[168:171], v[184:187], v[52:55]
	v_mfma_f32_16x16x32_bf16 v[48:51], v[176:179], v[184:187], v[48:51]
	v_mfma_f32_16x16x32_bf16 v[36:39], v[168:171], v[192:195], v[36:39]
	v_mfma_f32_16x16x32_bf16 v[32:35], v[176:179], v[192:195], v[32:35]
	v_mfma_f32_16x16x32_bf16 v[20:23], v[168:171], v[200:203], v[20:23]
	v_mfma_f32_16x16x32_bf16 v[16:19], v[176:179], v[200:203], v[16:19]
	v_mfma_f32_16x16x32_bf16 v[4:7], v[168:171], v[208:211], v[4:7]
	v_mfma_f32_16x16x32_bf16 v[0:3], v[176:179], v[208:211], v[0:3]
	s_barrier
	s_add_i32 s59, 0, 0x18000
	s_add_i32 s60, 0, 0x1c000
	v_add_u32_e32 v140, s59, v164
	v_add_u32_e32 v176, s60, v164
	ds_read_b128 v[128:131], v140
	ds_read_b128 v[132:135], v140 offset:1024
	ds_read_b128 v[136:139], v140 offset:2048
	ds_read_b128 v[140:143], v140 offset:3072
	ds_read_b128 v[160:163], v176
	ds_read_b128 v[168:171], v176 offset:1024
	ds_read_b128 v[172:175], v176 offset:2048
	ds_read_b128 v[176:179], v176 offset:3072
	s_add_u32 s44, s44, 0x20000
	s_addc_u32 s45, s45, 0
	s_mov_b32 m0, s46
	v_lshl_add_u64 v[220:221], s[44:45], 0, v[144:145]
	ds_read_b128 v[180:183], v167 offset:32768
	ds_read_b128 v[184:187], v167 offset:33792
	ds_read_b128 v[188:191], v167 offset:34816
	ds_read_b128 v[192:195], v167 offset:35840
	ds_read_b128 v[196:199], v167 offset:36864
	ds_read_b128 v[200:203], v167 offset:37888
	ds_read_b128 v[204:207], v167 offset:38912
	ds_read_b128 v[208:211], v167 offset:39936
	global_load_lds_dwordx4 v[220:221], off
	v_lshl_add_u64 v[220:221], s[44:45], 0, v[148:149]
	s_mov_b32 m0, s47
	s_nop 0
	global_load_lds_dwordx4 v[220:221], off
	s_waitcnt vmcnt(8)
	s_waitcnt lgkmcnt(0)
	s_barrier
	v_mfma_f32_16x16x32_bf16 v[124:127], v[128:131], v[180:183], v[124:127]
	v_mfma_f32_16x16x32_bf16 v[120:123], v[136:139], v[180:183], v[120:123]
	v_mfma_f32_16x16x32_bf16 v[116:119], v[128:131], v[188:191], v[116:119]
	v_mfma_f32_16x16x32_bf16 v[104:107], v[136:139], v[188:191], v[104:107]
	v_mfma_f32_16x16x32_bf16 v[92:95], v[128:131], v[196:199], v[92:95]
	v_mfma_f32_16x16x32_bf16 v[88:91], v[136:139], v[196:199], v[88:91]
	v_mfma_f32_16x16x32_bf16 v[76:79], v[128:131], v[204:207], v[76:79]
	v_mfma_f32_16x16x32_bf16 v[72:75], v[136:139], v[204:207], v[72:75]
	v_mfma_f32_16x16x32_bf16 v[124:127], v[132:135], v[184:187], v[124:127]
	v_mfma_f32_16x16x32_bf16 v[120:123], v[140:143], v[184:187], v[120:123]
	v_mfma_f32_16x16x32_bf16 v[116:119], v[132:135], v[192:195], v[116:119]
	v_mfma_f32_16x16x32_bf16 v[104:107], v[140:143], v[192:195], v[104:107]
	v_mfma_f32_16x16x32_bf16 v[92:95], v[132:135], v[200:203], v[92:95]
	v_mfma_f32_16x16x32_bf16 v[88:91], v[140:143], v[200:203], v[88:91]
	v_mfma_f32_16x16x32_bf16 v[76:79], v[132:135], v[208:211], v[76:79]
	v_mfma_f32_16x16x32_bf16 v[72:75], v[140:143], v[208:211], v[72:75]
	v_mfma_f32_16x16x32_bf16 v[112:115], v[160:163], v[180:183], v[112:115]
	v_mfma_f32_16x16x32_bf16 v[108:111], v[172:175], v[180:183], v[108:111]
	v_mfma_f32_16x16x32_bf16 v[100:103], v[160:163], v[188:191], v[100:103]
	v_mfma_f32_16x16x32_bf16 v[96:99], v[172:175], v[188:191], v[96:99]
	v_mfma_f32_16x16x32_bf16 v[84:87], v[160:163], v[196:199], v[84:87]
	v_mfma_f32_16x16x32_bf16 v[80:83], v[172:175], v[196:199], v[80:83]
	v_mfma_f32_16x16x32_bf16 v[68:71], v[160:163], v[204:207], v[68:71]
	v_mfma_f32_16x16x32_bf16 v[64:67], v[172:175], v[204:207], v[64:67]
	v_mfma_f32_16x16x32_bf16 v[112:115], v[168:171], v[184:187], v[112:115]
	v_mfma_f32_16x16x32_bf16 v[108:111], v[176:179], v[184:187], v[108:111]
	v_mfma_f32_16x16x32_bf16 v[100:103], v[168:171], v[192:195], v[100:103]
	v_mfma_f32_16x16x32_bf16 v[96:99], v[176:179], v[192:195], v[96:99]
	v_mfma_f32_16x16x32_bf16 v[84:87], v[168:171], v[200:203], v[84:87]
	v_mfma_f32_16x16x32_bf16 v[80:83], v[176:179], v[200:203], v[80:83]
	v_mfma_f32_16x16x32_bf16 v[68:71], v[168:171], v[208:211], v[68:71]
	v_mfma_f32_16x16x32_bf16 v[64:67], v[176:179], v[208:211], v[64:67]
	s_barrier
; #define PG8_STAGE(bufoff, gbase, voff) do { _Pragma("unroll") for (int _i = 0; _i < 2; ++_i) \
;         __builtin_amdgcn_global_load_lds((const unsigned*)((const char*)(gbase) + (voff)[_i]), (LAS unsigned*)(lds + (bufoff) + ldsw + _i * 8192), 16, 0, 0); } while (0)
; #define PG8_LDA(dst, b, h) do { _Pragma("unroll") for (int m = 0; m < 4; ++m) _Pragma("unroll") for (int k = 0; k < 2; ++k) dst[m][k] = *(const LAS bf16x8*)(lds + PG8_SA(b, h) + aoff + m * 2048 + k * 1024); } while (0)
; #define PG8_LDB(dst, b, h) do { _Pragma("unroll") for (int n = 0; n < 2; ++n) _Pragma("unroll") for (int k = 0; k < 2; ++k) dst[n][k] = *(const LAS bf16x8*)(lds + PG8_SB(b, h) + boff + n * 2048 + k * 1024); } while (0)
; #define PG8_MMA(ai, bj, At, Bt) do { __builtin_amdgcn_s_setprio(1); _Pragma("unroll") for (int m = 0; m < 4; ++m) _Pragma("unroll") for (int n = 0; n < 2; ++n) _Pragma("unroll") for (int k = 0; k < 2; ++k) \
;         acc[ai][bj][m][n] = __builtin_amdgcn_mfma_f32_16x16x32_bf16(Bt[n][k], At[m][k], acc[ai][bj][m][n], 0, 0, 0); __builtin_amdgcn_s_setprio(0); } while (0)
; #define PG8_WAIT_V(n) asm volatile("s_waitcnt vmcnt(" #n ")" ::: "memory")
; #define PG8_WAIT_L(n) asm volatile("s_waitcnt lgkmcnt(" #n ")" ::: "memory")
; template <class Epi>
; DI void gemm_phase(LAS unsigned char* lds, const int wid, const Gemm g, const Order& S, const Epi& E) {
;     ...
;             PG8_LDB(B0, 0, 0); PG8_LDB(B1, 0, 1); PG8_SCHED; PG8_LDA(At, 0, 0); PG8_STAGE(PG8_SA(1, 1), a1 + hstepA, voffA);
;             PG8_WAIT_V(8); PG8_WAIT_L(0); PG8_BAR; PG8_MMA(0, 0, At, B0); PG8_MMA(0, 1, At, B1); PG8_BAR; PG8_SCHED;
;             PG8_LDA(At, 0, 1); PG8_STAGE(PG8_SB(0, 0), b2, voffB); PG8_STAGE(PG8_SB(0, 1), b2 + hstepB, voffB); PG8_STAGE(PG8_SA(0, 0), a2, voffA);
;             PG8_WAIT_V(8); PG8_WAIT_L(0); PG8_BAR; PG8_MMA(1, 0, At, B0); PG8_MMA(1, 1, At, B1); PG8_BAR; PG8_SCHED;
;             PG8_LDB(B0, 1, 0); PG8_LDB(B1, 1, 1); PG8_SCHED; PG8_LDA(At, 1, 0); PG8_STAGE(PG8_SA(0, 1), a2 + hstepA, voffA);
;             PG8_WAIT_V(8); PG8_WAIT_L(0); PG8_BAR; PG8_MMA(0, 0, At, B0); PG8_MMA(0, 1, At, B1); PG8_BAR; PG8_SCHED;
;             PG8_LDA(At, 1, 1); PG8_STAGE(PG8_SB(1, 0), b3, voffB); PG8_STAGE(PG8_SB(1, 1), b3 + hstepB, voffB); PG8_STAGE(PG8_SA(1, 0), a3, voffA);
;             PG8_WAIT_V(8); PG8_WAIT_L(0); PG8_BAR; PG8_MMA(1, 0, At, B0); PG8_MMA(1, 1, At, B1); PG8_BAR; PG8_SCHED;
	s_add_i32 s44, s59, s94
	v_lshl_add_u64 v[212:213], v[212:213], 0, s[16:17]
	s_mov_b32 m0, s44
	ds_read_b128 v[180:183], v167 offset:49152
	ds_read_b128 v[184:187], v167 offset:50176
	ds_read_b128 v[188:191], v167 offset:51200
	ds_read_b128 v[192:195], v167 offset:52224
	ds_read_b128 v[196:199], v167 offset:53248
	ds_read_b128 v[200:203], v167 offset:54272
	ds_read_b128 v[204:207], v167 offset:55296
	ds_read_b128 v[208:211], v167 offset:56320
	global_load_lds_dwordx4 v[212:213], off
	s_add_i32 m0, s44, 0x2000
	s_add_u32 s42, s42, 0x20080
	v_lshl_add_u64 v[212:213], v[214:215], 0, s[16:17]
	s_addc_u32 s43, s43, 0
	s_add_i32 s44, s60, s94
	global_load_lds_dwordx4 v[212:213], off
	v_lshl_add_u64 v[212:213], s[42:43], 0, v[146:147]
	s_mov_b32 m0, s44
	s_nop 0
	global_load_lds_dwordx4 v[212:213], off
	v_lshl_add_u64 v[212:213], s[42:43], 0, v[150:151]
	s_add_i32 m0, s44, 0x2000
	s_nop 0
	global_load_lds_dwordx4 v[212:213], off
	v_lshl_add_u64 v[212:213], v[216:217], 0, s[16:17]
	s_mov_b32 m0, s49
	s_nop 0
	global_load_lds_dwordx4 v[212:213], off
	v_lshl_add_u64 v[212:213], v[218:219], 0, s[16:17]
	s_mov_b32 m0, s50
	s_nop 0
	global_load_lds_dwordx4 v[212:213], off
	s_waitcnt vmcnt(8)
	s_waitcnt lgkmcnt(0)
	s_barrier
	v_mfma_f32_16x16x32_bf16 v[60:63], v[128:131], v[180:183], v[60:63]
	v_mfma_f32_16x16x32_bf16 v[56:59], v[136:139], v[180:183], v[56:59]
	v_mfma_f32_16x16x32_bf16 v[44:47], v[128:131], v[188:191], v[44:47]
	v_mfma_f32_16x16x32_bf16 v[40:43], v[136:139], v[188:191], v[40:43]
	v_mfma_f32_16x16x32_bf16 v[28:31], v[128:131], v[196:199], v[28:31]
	v_mfma_f32_16x16x32_bf16 v[24:27], v[136:139], v[196:199], v[24:27]
	v_mfma_f32_16x16x32_bf16 v[12:15], v[128:131], v[204:207], v[12:15]
	v_mfma_f32_16x16x32_bf16 v[8:11], v[136:139], v[204:207], v[8:11]
	v_mfma_f32_16x16x32_bf16 v[60:63], v[132:135], v[184:187], v[60:63]
	v_mfma_f32_16x16x32_bf16 v[56:59], v[140:143], v[184:187], v[56:59]
	v_mfma_f32_16x16x32_bf16 v[44:47], v[132:135], v[192:195], v[44:47]
	v_mfma_f32_16x16x32_bf16 v[40:43], v[140:143], v[192:195], v[40:43]
	v_mfma_f32_16x16x32_bf16 v[28:31], v[132:135], v[200:203], v[28:31]
	v_mfma_f32_16x16x32_bf16 v[24:27], v[140:143], v[200:203], v[24:27]
	v_mfma_f32_16x16x32_bf16 v[12:15], v[132:135], v[208:211], v[12:15]
	v_mfma_f32_16x16x32_bf16 v[8:11], v[140:143], v[208:211], v[8:11]
	v_mfma_f32_16x16x32_bf16 v[52:55], v[160:163], v[180:183], v[52:55]
	v_mfma_f32_16x16x32_bf16 v[48:51], v[172:175], v[180:183], v[48:51]
	v_mfma_f32_16x16x32_bf16 v[36:39], v[160:163], v[188:191], v[36:39]
	v_mfma_f32_16x16x32_bf16 v[32:35], v[172:175], v[188:191], v[32:35]
	v_mfma_f32_16x16x32_bf16 v[20:23], v[160:163], v[196:199], v[20:23]
	v_mfma_f32_16x16x32_bf16 v[16:19], v[172:175], v[196:199], v[16:19]
	v_mfma_f32_16x16x32_bf16 v[4:7], v[160:163], v[204:207], v[4:7]
	v_mfma_f32_16x16x32_bf16 v[0:3], v[172:175], v[204:207], v[0:3]
	v_mfma_f32_16x16x32_bf16 v[52:55], v[168:171], v[184:187], v[52:55]
	v_mfma_f32_16x16x32_bf16 v[48:51], v[176:179], v[184:187], v[48:51]
	v_mfma_f32_16x16x32_bf16 v[36:39], v[168:171], v[192:195], v[36:39]
	v_mfma_f32_16x16x32_bf16 v[32:35], v[176:179], v[192:195], v[32:35]
	v_mfma_f32_16x16x32_bf16 v[20:23], v[168:171], v[200:203], v[20:23]
	v_mfma_f32_16x16x32_bf16 v[16:19], v[176:179], v[200:203], v[16:19]
	v_mfma_f32_16x16x32_bf16 v[4:7], v[168:171], v[208:211], v[4:7]
	v_mfma_f32_16x16x32_bf16 v[0:3], v[176:179], v[208:211], v[0:3]
	s_barrier
	s_add_i32 s58, s58, 2
	s_add_u32 s40, s40, 0x100
	s_addc_u32 s41, s41, 0
	s_add_u32 s56, s56, 0x100
	s_addc_u32 s57, s57, 0
	s_cmp_gt_u32 s58, 5
	s_cbranch_scc0 .LBB0_1091
	s_branch .Lpeel_exit_6
.LBB0_1091:
	ds_read_b128 v[128:131], v165
	ds_read_b128 v[132:135], v165 offset:1024
	ds_read_b128 v[136:139], v165 offset:2048
	ds_read_b128 v[140:143], v165 offset:3072
	ds_read_b128 v[160:163], v166
	ds_read_b128 v[168:171], v166 offset:1024
	ds_read_b128 v[172:175], v166 offset:2048
	ds_read_b128 v[176:179], v166 offset:3072
	s_add_u32 s42, s40, 0xfffe0080
	s_addc_u32 s43, s41, -1
	s_cmp_eq_u32 s58, 4
	s_cselect_b32 s45, s29, s43
	s_cselect_b32 s44, s54, s42
	s_cselect_b32 s43, s31, s57
	s_cselect_b32 s42, s55, s56
	v_lshl_add_u64 v[212:213], s[40:41], 0, v[152:153]
	s_add_i32 m0, s25, 0xc000
	ds_read_b128 v[180:183], v167
	ds_read_b128 v[184:187], v167 offset:1024
	ds_read_b128 v[188:191], v167 offset:2048
	ds_read_b128 v[192:195], v167 offset:3072
	ds_read_b128 v[196:199], v167 offset:4096
	ds_read_b128 v[200:203], v167 offset:5120
	ds_read_b128 v[204:207], v167 offset:6144
	ds_read_b128 v[208:211], v167 offset:7168
	global_load_lds_dwordx4 v[212:213], off
	v_lshl_add_u64 v[212:213], s[40:41], 0, v[154:155]
	s_add_i32 m0, s25, 0xe000
	s_nop 0
	global_load_lds_dwordx4 v[212:213], off
	s_waitcnt vmcnt(8)
	s_waitcnt lgkmcnt(0)
	s_barrier
; #define PG8_STAGE(bufoff, gbase, voff) do { _Pragma("unroll") for (int _i = 0; _i < 2; ++_i) \
;         __builtin_amdgcn_global_load_lds((const unsigned*)((const char*)(gbase) + (voff)[_i]), (LAS unsigned*)(lds + (bufoff) + ldsw + _i * 8192), 16, 0, 0); } while (0)
; #define PG8_LDA(dst, b, h) do { _Pragma("unroll") for (int m = 0; m < 4; ++m) _Pragma("unroll") for (int k = 0; k < 2; ++k) dst[m][k] = *(const LAS bf16x8*)(lds + PG8_SA(b, h) + aoff + m * 2048 + k * 1024); } while (0)
; #define PG8_LDB(dst, b, h) do { _Pragma("unroll") for (int n = 0; n < 2; ++n) _Pragma("unroll") for (int k = 0; k < 2; ++k) dst[n][k] = *(const LAS bf16x8*)(lds + PG8_SB(b, h) + boff + n * 2048 + k * 1024); } while (0)
; #define PG8_MMA(ai, bj, At, Bt) do { __builtin_amdgcn_s_setprio(1); _Pragma("unroll") for (int m = 0; m < 4; ++m) _Pragma("unroll") for (int n = 0; n < 2; ++n) _Pragma("unroll") for (int k = 0; k < 2; ++k) \
;         acc[ai][bj][m][n] = __builtin_amdgcn_mfma_f32_16x16x32_bf16(Bt[n][k], At[m][k], acc[ai][bj][m][n], 0, 0, 0); __builtin_amdgcn_s_setprio(0); } while (0)
; #define PG8_WAIT_V(n) asm volatile("s_waitcnt vmcnt(" #n ")" ::: "memory")
; #define PG8_WAIT_L(n) asm volatile("s_waitcnt lgkmcnt(" #n ")" ::: "memory")
; #define PG8_BAR __builtin_amdgcn_s_barrier()
; #define PG8_SCHED __builtin_amdgcn_sched_barrier(0)
; template <class Epi>
; DI void gemm_phase(LAS unsigned char* lds, const int wid, const Gemm g, const Order& S, const Epi& E) {
;     ...
;             PG8_LDB(B0, 0, 0); PG8_LDB(B1, 0, 1); PG8_SCHED; PG8_LDA(At, 0, 0); PG8_STAGE(PG8_SA(1, 1), a1 + hstepA, voffA);
;             PG8_WAIT_V(8); PG8_WAIT_L(0); PG8_BAR; PG8_MMA(0, 0, At, B0); PG8_MMA(0, 1, At, B1); PG8_BAR; PG8_SCHED;
;             PG8_LDA(At, 0, 1); PG8_STAGE(PG8_SB(0, 0), b2, voffB); PG8_STAGE(PG8_SB(0, 1), b2 + hstepB, voffB); PG8_STAGE(PG8_SA(0, 0), a2, voffA);
;             PG8_WAIT_V(8); PG8_WAIT_L(0); PG8_BAR; PG8_MMA(1, 0, At, B0); PG8_MMA(1, 1, At, B1); PG8_BAR; PG8_SCHED;
;             PG8_LDB(B0, 1, 0); PG8_LDB(B1, 1, 1); PG8_SCHED; PG8_LDA(At, 1, 0); PG8_STAGE(PG8_SA(0, 1), a2 + hstepA, voffA);
;             PG8_WAIT_V(8); PG8_WAIT_L(0); PG8_BAR; PG8_MMA(0, 0, At, B0); PG8_MMA(0, 1, At, B1); PG8_BAR; PG8_SCHED;
	v_mfma_f32_16x16x32_bf16 v[124:127], v[128:131], v[180:183], v[124:127]
	v_mfma_f32_16x16x32_bf16 v[120:123], v[136:139], v[180:183], v[120:123]
	v_mfma_f32_16x16x32_bf16 v[116:119], v[128:131], v[188:191], v[116:119]
	v_mfma_f32_16x16x32_bf16 v[104:107], v[136:139], v[188:191], v[104:107]
	v_mfma_f32_16x16x32_bf16 v[92:95], v[128:131], v[196:199], v[92:95]
	v_mfma_f32_16x16x32_bf16 v[88:91], v[136:139], v[196:199], v[88:91]
	v_mfma_f32_16x16x32_bf16 v[76:79], v[128:131], v[204:207], v[76:79]
	v_mfma_f32_16x16x32_bf16 v[72:75], v[136:139], v[204:207], v[72:75]
	v_mfma_f32_16x16x32_bf16 v[124:127], v[132:135], v[184:187], v[124:127]
	v_mfma_f32_16x16x32_bf16 v[120:123], v[140:143], v[184:187], v[120:123]
	v_mfma_f32_16x16x32_bf16 v[116:119], v[132:135], v[192:195], v[116:119]
	v_mfma_f32_16x16x32_bf16 v[104:107], v[140:143], v[192:195], v[104:107]
	v_mfma_f32_16x16x32_bf16 v[92:95], v[132:135], v[200:203], v[92:95]
	v_mfma_f32_16x16x32_bf16 v[88:91], v[140:143], v[200:203], v[88:91]
	v_mfma_f32_16x16x32_bf16 v[76:79], v[132:135], v[208:211], v[76:79]
	v_mfma_f32_16x16x32_bf16 v[72:75], v[140:143], v[208:211], v[72:75]
	v_mfma_f32_16x16x32_bf16 v[112:115], v[160:163], v[180:183], v[112:115]
	v_mfma_f32_16x16x32_bf16 v[108:111], v[172:175], v[180:183], v[108:111]
	v_mfma_f32_16x16x32_bf16 v[100:103], v[160:163], v[188:191], v[100:103]
	v_mfma_f32_16x16x32_bf16 v[96:99], v[172:175], v[188:191], v[96:99]
	v_mfma_f32_16x16x32_bf16 v[84:87], v[160:163], v[196:199], v[84:87]
	v_mfma_f32_16x16x32_bf16 v[80:83], v[172:175], v[196:199], v[80:83]
	v_mfma_f32_16x16x32_bf16 v[68:71], v[160:163], v[204:207], v[68:71]
	v_mfma_f32_16x16x32_bf16 v[64:67], v[172:175], v[204:207], v[64:67]
	v_mfma_f32_16x16x32_bf16 v[112:115], v[168:171], v[184:187], v[112:115]
	v_mfma_f32_16x16x32_bf16 v[108:111], v[176:179], v[184:187], v[108:111]
	v_mfma_f32_16x16x32_bf16 v[100:103], v[168:171], v[192:195], v[100:103]
	v_mfma_f32_16x16x32_bf16 v[96:99], v[176:179], v[192:195], v[96:99]
	v_mfma_f32_16x16x32_bf16 v[84:87], v[168:171], v[200:203], v[84:87]
	v_mfma_f32_16x16x32_bf16 v[80:83], v[176:179], v[200:203], v[80:83]
	v_mfma_f32_16x16x32_bf16 v[68:71], v[168:171], v[208:211], v[68:71]
	v_mfma_f32_16x16x32_bf16 v[64:67], v[176:179], v[208:211], v[64:67]
	s_barrier
	s_add_i32 s59, s51, s94
	v_lshl_add_u64 v[212:213], s[42:43], 0, v[146:147]
	s_mov_b32 m0, s59
	ds_read_b128 v[180:183], v167 offset:16384
	ds_read_b128 v[184:187], v167 offset:17408
	ds_read_b128 v[188:191], v167 offset:18432
	ds_read_b128 v[192:195], v167 offset:19456
	ds_read_b128 v[196:199], v167 offset:20480
	ds_read_b128 v[200:203], v167 offset:21504
	ds_read_b128 v[204:207], v167 offset:22528
	ds_read_b128 v[208:211], v167 offset:23552
	global_load_lds_dwordx4 v[212:213], off
	s_add_i32 m0, s59, 0x2000
	s_add_u32 s60, s42, 0x20000
	v_lshl_add_u64 v[214:215], s[42:43], 0, v[150:151]
	s_addc_u32 s61, s43, 0
	s_add_i32 s59, s52, s94
	global_load_lds_dwordx4 v[214:215], off
	v_lshl_add_u64 v[216:217], s[60:61], 0, v[146:147]
	s_mov_b32 m0, s59
	v_lshl_add_u64 v[218:219], s[44:45], 0, v[148:149]
	global_load_lds_dwordx4 v[216:217], off
	v_lshl_add_u64 v[216:217], s[60:61], 0, v[150:151]
	s_add_i32 m0, s59, 0x2000
	s_nop 0
	global_load_lds_dwordx4 v[216:217], off
	v_lshl_add_u64 v[216:217], s[44:45], 0, v[144:145]
	s_mov_b32 m0, s25
	s_nop 0
	global_load_lds_dwordx4 v[216:217], off
	s_mov_b32 m0, s39
	s_nop 0
	global_load_lds_dwordx4 v[218:219], off
	s_waitcnt vmcnt(8)
	s_waitcnt lgkmcnt(0)
	s_barrier
	v_mfma_f32_16x16x32_bf16 v[60:63], v[128:131], v[180:183], v[60:63]
	v_mfma_f32_16x16x32_bf16 v[56:59], v[136:139], v[180:183], v[56:59]
	v_mfma_f32_16x16x32_bf16 v[44:47], v[128:131], v[188:191], v[44:47]
	v_mfma_f32_16x16x32_bf16 v[40:43], v[136:139], v[188:191], v[40:43]
	v_mfma_f32_16x16x32_bf16 v[28:31], v[128:131], v[196:199], v[28:31]
	v_mfma_f32_16x16x32_bf16 v[24:27], v[136:139], v[196:199], v[24:27]
	v_mfma_f32_16x16x32_bf16 v[12:15], v[128:131], v[204:207], v[12:15]
	v_mfma_f32_16x16x32_bf16 v[8:11], v[136:139], v[204:207], v[8:11]
	v_mfma_f32_16x16x32_bf16 v[60:63], v[132:135], v[184:187], v[60:63]
	v_mfma_f32_16x16x32_bf16 v[56:59], v[140:143], v[184:187], v[56:59]
	v_mfma_f32_16x16x32_bf16 v[44:47], v[132:135], v[192:195], v[44:47]
	v_mfma_f32_16x16x32_bf16 v[40:43], v[140:143], v[192:195], v[40:43]
	v_mfma_f32_16x16x32_bf16 v[28:31], v[132:135], v[200:203], v[28:31]
	v_mfma_f32_16x16x32_bf16 v[24:27], v[140:143], v[200:203], v[24:27]
	v_mfma_f32_16x16x32_bf16 v[12:15], v[132:135], v[208:211], v[12:15]
	v_mfma_f32_16x16x32_bf16 v[8:11], v[140:143], v[208:211], v[8:11]
	v_mfma_f32_16x16x32_bf16 v[52:55], v[160:163], v[180:183], v[52:55]
	v_mfma_f32_16x16x32_bf16 v[48:51], v[172:175], v[180:183], v[48:51]
	v_mfma_f32_16x16x32_bf16 v[36:39], v[160:163], v[188:191], v[36:39]
	v_mfma_f32_16x16x32_bf16 v[32:35], v[172:175], v[188:191], v[32:35]
	v_mfma_f32_16x16x32_bf16 v[20:23], v[160:163], v[196:199], v[20:23]
	v_mfma_f32_16x16x32_bf16 v[16:19], v[172:175], v[196:199], v[16:19]
	v_mfma_f32_16x16x32_bf16 v[4:7], v[160:163], v[204:207], v[4:7]
	v_mfma_f32_16x16x32_bf16 v[0:3], v[172:175], v[204:207], v[0:3]
	v_mfma_f32_16x16x32_bf16 v[52:55], v[168:171], v[184:187], v[52:55]
	v_mfma_f32_16x16x32_bf16 v[48:51], v[176:179], v[184:187], v[48:51]
	v_mfma_f32_16x16x32_bf16 v[36:39], v[168:171], v[192:195], v[36:39]
	v_mfma_f32_16x16x32_bf16 v[32:35], v[176:179], v[192:195], v[32:35]
	v_mfma_f32_16x16x32_bf16 v[20:23], v[168:171], v[200:203], v[20:23]
	v_mfma_f32_16x16x32_bf16 v[16:19], v[176:179], v[200:203], v[16:19]
	v_mfma_f32_16x16x32_bf16 v[4:7], v[168:171], v[208:211], v[4:7]
	v_mfma_f32_16x16x32_bf16 v[0:3], v[176:179], v[208:211], v[0:3]
	s_barrier
; #define PG8_STAGE(bufoff, gbase, voff) do { _Pragma("unroll") for (int _i = 0; _i < 2; ++_i) \
;         __builtin_amdgcn_global_load_lds((const unsigned*)((const char*)(gbase) + (voff)[_i]), (LAS unsigned*)(lds + (bufoff) + ldsw + _i * 8192), 16, 0, 0); } while (0)
; #define PG8_LDA(dst, b, h) do { _Pragma("unroll") for (int m = 0; m < 4; ++m) _Pragma("unroll") for (int k = 0; k < 2; ++k) dst[m][k] = *(const LAS bf16x8*)(lds + PG8_SA(b, h) + aoff + m * 2048 + k * 1024); } while (0)
; #define PG8_LDB(dst, b, h) do { _Pragma("unroll") for (int n = 0; n < 2; ++n) _Pragma("unroll") for (int k = 0; k < 2; ++k) dst[n][k] = *(const LAS bf16x8*)(lds + PG8_SB(b, h) + boff + n * 2048 + k * 1024); } while (0)
; #define PG8_MMA(ai, bj, At, Bt) do { __builtin_amdgcn_s_setprio(1); _Pragma("unroll") for (int m = 0; m < 4; ++m) _Pragma("unroll") for (int n = 0; n < 2; ++n) _Pragma("unroll") for (int k = 0; k < 2; ++k) \
;         acc[ai][bj][m][n] = __builtin_amdgcn_mfma_f32_16x16x32_bf16(Bt[n][k], At[m][k], acc[ai][bj][m][n], 0, 0, 0); __builtin_amdgcn_s_setprio(0); } while (0)
; #define PG8_WAIT_V(n) asm volatile("s_waitcnt vmcnt(" #n ")" ::: "memory")
; #define PG8_WAIT_L(n) asm volatile("s_waitcnt lgkmcnt(" #n ")" ::: "memory")
; #define PG8_BAR __builtin_amdgcn_s_barrier()
; #define PG8_SCHED __builtin_amdgcn_sched_barrier(0)
; template <class Epi>
; DI void gemm_phase(LAS unsigned char* lds, const int wid, const Gemm g, const Order& S, const Epi& E) {
;     ...
;             PG8_LDB(B0, 1, 0); PG8_LDB(B1, 1, 1); PG8_SCHED; PG8_LDA(At, 1, 0); PG8_STAGE(PG8_SA(0, 1), a2 + hstepA, voffA);
;             PG8_WAIT_V(8); PG8_WAIT_L(0); PG8_BAR; PG8_MMA(0, 0, At, B0); PG8_MMA(0, 1, At, B1); PG8_BAR; PG8_SCHED;
;             PG8_LDA(At, 1, 1); PG8_STAGE(PG8_SB(1, 0), b3, voffB); PG8_STAGE(PG8_SB(1, 1), b3 + hstepB, voffB); PG8_STAGE(PG8_SA(1, 0), a3, voffA);
;             PG8_WAIT_V(8); PG8_WAIT_L(0); PG8_BAR; PG8_MMA(1, 0, At, B0); PG8_MMA(1, 1, At, B1); PG8_BAR; PG8_SCHED;
	s_add_i32 s59, 0, 0x18000
	s_add_i32 s60, 0, 0x1c000
	v_add_u32_e32 v140, s59, v164
	v_add_u32_e32 v176, s60, v164
	ds_read_b128 v[128:131], v140
	ds_read_b128 v[132:135], v140 offset:1024
	ds_read_b128 v[136:139], v140 offset:2048
	ds_read_b128 v[140:143], v140 offset:3072
	ds_read_b128 v[160:163], v176
	ds_read_b128 v[168:171], v176 offset:1024
	ds_read_b128 v[172:175], v176 offset:2048
	ds_read_b128 v[176:179], v176 offset:3072
	s_add_u32 s44, s44, 0x20000
	s_addc_u32 s45, s45, 0
	s_mov_b32 m0, s46
	v_lshl_add_u64 v[220:221], s[44:45], 0, v[144:145]
	ds_read_b128 v[180:183], v167 offset:32768
	ds_read_b128 v[184:187], v167 offset:33792
	ds_read_b128 v[188:191], v167 offset:34816
	ds_read_b128 v[192:195], v167 offset:35840
	ds_read_b128 v[196:199], v167 offset:36864
	ds_read_b128 v[200:203], v167 offset:37888
	ds_read_b128 v[204:207], v167 offset:38912
	ds_read_b128 v[208:211], v167 offset:39936
	global_load_lds_dwordx4 v[220:221], off
	v_lshl_add_u64 v[220:221], s[44:45], 0, v[148:149]
	s_mov_b32 m0, s47
	s_nop 0
	global_load_lds_dwordx4 v[220:221], off
	s_waitcnt vmcnt(8)
	s_waitcnt lgkmcnt(0)
	s_barrier
	v_mfma_f32_16x16x32_bf16 v[124:127], v[128:131], v[180:183], v[124:127]
	v_mfma_f32_16x16x32_bf16 v[120:123], v[136:139], v[180:183], v[120:123]
	v_mfma_f32_16x16x32_bf16 v[116:119], v[128:131], v[188:191], v[116:119]
	v_mfma_f32_16x16x32_bf16 v[104:107], v[136:139], v[188:191], v[104:107]
	v_mfma_f32_16x16x32_bf16 v[92:95], v[128:131], v[196:199], v[92:95]
	v_mfma_f32_16x16x32_bf16 v[88:91], v[136:139], v[196:199], v[88:91]
	v_mfma_f32_16x16x32_bf16 v[76:79], v[128:131], v[204:207], v[76:79]
	v_mfma_f32_16x16x32_bf16 v[72:75], v[136:139], v[204:207], v[72:75]
	v_mfma_f32_16x16x32_bf16 v[124:127], v[132:135], v[184:187], v[124:127]
	v_mfma_f32_16x16x32_bf16 v[120:123], v[140:143], v[184:187], v[120:123]
	v_mfma_f32_16x16x32_bf16 v[116:119], v[132:135], v[192:195], v[116:119]
	v_mfma_f32_16x16x32_bf16 v[104:107], v[140:143], v[192:195], v[104:107]
	v_mfma_f32_16x16x32_bf16 v[92:95], v[132:135], v[200:203], v[92:95]
	v_mfma_f32_16x16x32_bf16 v[88:91], v[140:143], v[200:203], v[88:91]
	v_mfma_f32_16x16x32_bf16 v[76:79], v[132:135], v[208:211], v[76:79]
	v_mfma_f32_16x16x32_bf16 v[72:75], v[140:143], v[208:211], v[72:75]
	v_mfma_f32_16x16x32_bf16 v[112:115], v[160:163], v[180:183], v[112:115]
	v_mfma_f32_16x16x32_bf16 v[108:111], v[172:175], v[180:183], v[108:111]
	v_mfma_f32_16x16x32_bf16 v[100:103], v[160:163], v[188:191], v[100:103]
	v_mfma_f32_16x16x32_bf16 v[96:99], v[172:175], v[188:191], v[96:99]
	v_mfma_f32_16x16x32_bf16 v[84:87], v[160:163], v[196:199], v[84:87]
	v_mfma_f32_16x16x32_bf16 v[80:83], v[172:175], v[196:199], v[80:83]
	v_mfma_f32_16x16x32_bf16 v[68:71], v[160:163], v[204:207], v[68:71]
	v_mfma_f32_16x16x32_bf16 v[64:67], v[172:175], v[204:207], v[64:67]
	v_mfma_f32_16x16x32_bf16 v[112:115], v[168:171], v[184:187], v[112:115]
	v_mfma_f32_16x16x32_bf16 v[108:111], v[176:179], v[184:187], v[108:111]
	v_mfma_f32_16x16x32_bf16 v[100:103], v[168:171], v[192:195], v[100:103]
	v_mfma_f32_16x16x32_bf16 v[96:99], v[176:179], v[192:195], v[96:99]
	v_mfma_f32_16x16x32_bf16 v[84:87], v[168:171], v[200:203], v[84:87]
	v_mfma_f32_16x16x32_bf16 v[80:83], v[176:179], v[200:203], v[80:83]
	v_mfma_f32_16x16x32_bf16 v[68:71], v[168:171], v[208:211], v[68:71]
	v_mfma_f32_16x16x32_bf16 v[64:67], v[176:179], v[208:211], v[64:67]
	s_barrier
	s_add_i32 s44, s59, s94
	v_lshl_add_u64 v[212:213], v[212:213], 0, s[16:17]
	s_mov_b32 m0, s44
	ds_read_b128 v[180:183], v167 offset:49152
	ds_read_b128 v[184:187], v167 offset:50176
	ds_read_b128 v[188:191], v167 offset:51200
	ds_read_b128 v[192:195], v167 offset:52224
	ds_read_b128 v[196:199], v167 offset:53248
	ds_read_b128 v[200:203], v167 offset:54272
	ds_read_b128 v[204:207], v167 offset:55296
	ds_read_b128 v[208:211], v167 offset:56320
	global_load_lds_dwordx4 v[212:213], off
	s_add_i32 m0, s44, 0x2000
	s_add_u32 s42, s42, 0x20080
	v_lshl_add_u64 v[212:213], v[214:215], 0, s[16:17]
	s_addc_u32 s43, s43, 0
	s_add_i32 s44, s60, s94
	global_load_lds_dwordx4 v[212:213], off
	v_lshl_add_u64 v[212:213], s[42:43], 0, v[146:147]
	s_mov_b32 m0, s44
	s_nop 0
	global_load_lds_dwordx4 v[212:213], off
	v_lshl_add_u64 v[212:213], s[42:43], 0, v[150:151]
	s_add_i32 m0, s44, 0x2000
	s_nop 0
	global_load_lds_dwordx4 v[212:213], off
	v_lshl_add_u64 v[212:213], v[216:217], 0, s[16:17]
	s_mov_b32 m0, s49
	s_nop 0
	global_load_lds_dwordx4 v[212:213], off
	v_lshl_add_u64 v[212:213], v[218:219], 0, s[16:17]
	s_mov_b32 m0, s50
	s_nop 0
	global_load_lds_dwordx4 v[212:213], off
	s_waitcnt vmcnt(8)
	s_waitcnt lgkmcnt(0)
	s_barrier
	v_mfma_f32_16x16x32_bf16 v[60:63], v[128:131], v[180:183], v[60:63]
	v_mfma_f32_16x16x32_bf16 v[56:59], v[136:139], v[180:183], v[56:59]
	v_mfma_f32_16x16x32_bf16 v[44:47], v[128:131], v[188:191], v[44:47]
	v_mfma_f32_16x16x32_bf16 v[40:43], v[136:139], v[188:191], v[40:43]
	v_mfma_f32_16x16x32_bf16 v[28:31], v[128:131], v[196:199], v[28:31]
	v_mfma_f32_16x16x32_bf16 v[24:27], v[136:139], v[196:199], v[24:27]
	v_mfma_f32_16x16x32_bf16 v[12:15], v[128:131], v[204:207], v[12:15]
	v_mfma_f32_16x16x32_bf16 v[8:11], v[136:139], v[204:207], v[8:11]
	v_mfma_f32_16x16x32_bf16 v[60:63], v[132:135], v[184:187], v[60:63]
	v_mfma_f32_16x16x32_bf16 v[56:59], v[140:143], v[184:187], v[56:59]
	v_mfma_f32_16x16x32_bf16 v[44:47], v[132:135], v[192:195], v[44:47]
	v_mfma_f32_16x16x32_bf16 v[40:43], v[140:143], v[192:195], v[40:43]
	v_mfma_f32_16x16x32_bf16 v[28:31], v[132:135], v[200:203], v[28:31]
	v_mfma_f32_16x16x32_bf16 v[24:27], v[140:143], v[200:203], v[24:27]
	v_mfma_f32_16x16x32_bf16 v[12:15], v[132:135], v[208:211], v[12:15]
	v_mfma_f32_16x16x32_bf16 v[8:11], v[140:143], v[208:211], v[8:11]
	v_mfma_f32_16x16x32_bf16 v[52:55], v[160:163], v[180:183], v[52:55]
	v_mfma_f32_16x16x32_bf16 v[48:51], v[172:175], v[180:183], v[48:51]
	v_mfma_f32_16x16x32_bf16 v[36:39], v[160:163], v[188:191], v[36:39]
	v_mfma_f32_16x16x32_bf16 v[32:35], v[172:175], v[188:191], v[32:35]
	v_mfma_f32_16x16x32_bf16 v[20:23], v[160:163], v[196:199], v[20:23]
	v_mfma_f32_16x16x32_bf16 v[16:19], v[172:175], v[196:199], v[16:19]
	v_mfma_f32_16x16x32_bf16 v[4:7], v[160:163], v[204:207], v[4:7]
	v_mfma_f32_16x16x32_bf16 v[0:3], v[172:175], v[204:207], v[0:3]
	v_mfma_f32_16x16x32_bf16 v[52:55], v[168:171], v[184:187], v[52:55]
	v_mfma_f32_16x16x32_bf16 v[48:51], v[176:179], v[184:187], v[48:51]
	v_mfma_f32_16x16x32_bf16 v[36:39], v[168:171], v[192:195], v[36:39]
	v_mfma_f32_16x16x32_bf16 v[32:35], v[176:179], v[192:195], v[32:35]
	v_mfma_f32_16x16x32_bf16 v[20:23], v[168:171], v[200:203], v[20:23]
	v_mfma_f32_16x16x32_bf16 v[16:19], v[176:179], v[200:203], v[16:19]
	v_mfma_f32_16x16x32_bf16 v[4:7], v[168:171], v[208:211], v[4:7]
	v_mfma_f32_16x16x32_bf16 v[0:3], v[176:179], v[208:211], v[0:3]
	s_barrier
	s_add_i32 s58, s58, 2
	s_add_u32 s40, s40, 0x100
	s_addc_u32 s41, s41, 0
	s_add_u32 s56, s56, 0x100
	s_addc_u32 s57, s57, 0
	s_cmp_gt_u32 s58, 5
	s_cbranch_scc0 .LBB0_1091

; #define PG8_STAGE(bufoff, gbase, voff) do { _Pragma("unroll") for (int _i = 0; _i < 2; ++_i) \
;         __builtin_amdgcn_global_load_lds((const unsigned*)((const char*)(gbase) + (voff)[_i]), (LAS unsigned*)(lds + (bufoff) + ldsw + _i * 8192), 16, 0, 0); } while (0)
; #define PG8_LDA(dst, b, h) do { _Pragma("unroll") for (int m = 0; m < 4; ++m) _Pragma("unroll") for (int k = 0; k < 2; ++k) dst[m][k] = *(const LAS bf16x8*)(lds + PG8_SA(b, h) + aoff + m * 2048 + k * 1024); } while (0)
; #define PG8_LDB(dst, b, h) do { _Pragma("unroll") for (int n = 0; n < 2; ++n) _Pragma("unroll") for (int k = 0; k < 2; ++k) dst[n][k] = *(const LAS bf16x8*)(lds + PG8_SB(b, h) + boff + n * 2048 + k * 1024); } while (0)
; #define PG8_MMA(ai, bj, At, Bt) do { __builtin_amdgcn_s_setprio(1); _Pragma("unroll") for (int m = 0; m < 4; ++m) _Pragma("unroll") for (int n = 0; n < 2; ++n) _Pragma("unroll") for (int k = 0; k < 2; ++k) \
;         acc[ai][bj][m][n] = __builtin_amdgcn_mfma_f32_16x16x32_bf16(Bt[n][k], At[m][k], acc[ai][bj][m][n], 0, 0, 0); __builtin_amdgcn_s_setprio(0); } while (0)
; template <class Epi>
; DI void gemm_phase(LAS unsigned char* lds, const int wid, const Gemm g, const Order& S, const Epi& E) {
;     ...
;         const bool has_next = S.next(ui + 1, nxt);
;         const char* nA = has_next ? (const char*)(g.A + (size_t)nxt.g * g.gsA + (size_t)nxt.pm * BM * g.lda) : cA;
;         const char* nB = has_next ? (const char*)(g.Bt + (size_t)nxt.g * g.gsB + (size_t)nxt.pn * BM * g.ldb) : cB;
;         for (int t = 0; t < nt; t += 2) {
;             const bool last = (t == nt - 2);
;             const char* a1 = cA + (size_t)(t + 1) * kstep;
;             const char* a2 = last ? nA : cA + (size_t)(t + 2) * kstep; const char* b2 = last ? nB : cB + (size_t)(t + 2) * kstep;
;             const char* a3 = a2 + kstep; const char* b3 = b2 + kstep;
;             PG8_LDB(B0, 0, 0); PG8_LDB(B1, 0, 1); PG8_SCHED; PG8_LDA(At, 0, 0); PG8_STAGE(PG8_SA(1, 1), a1 + hstepA, voffA);
;             PG8_WAIT_V(8); PG8_WAIT_L(0); PG8_BAR; PG8_MMA(0, 0, At, B0); PG8_MMA(0, 1, At, B1); PG8_BAR; PG8_SCHED;
;             PG8_LDA(At, 0, 1); PG8_STAGE(PG8_SB(0, 0), b2, voffB); PG8_STAGE(PG8_SB(0, 1), b2 + hstepB, voffB); PG8_STAGE(PG8_SA(0, 0), a2, voffA);
;             PG8_WAIT_V(8); PG8_WAIT_L(0); PG8_BAR; PG8_MMA(1, 0, At, B0); PG8_MMA(1, 1, At, B1); PG8_BAR; PG8_SCHED;
.LBB0_1169:
	s_ashr_i32 s31, s30, 31
	s_lshl_b64 s[36:37], s[30:31], 18
	s_add_u32 s36, s6, s36
	s_addc_u32 s37, s7, s37
	s_and_b64 s[38:39], s[8:9], exec
	s_cselect_b32 s31, s37, s43
	s_cselect_b32 s56, s36, s42
	s_ashr_i32 s35, s34, 31
	s_lshl_b64 s[38:39], s[34:35], 18
	s_add_u32 s38, s21, s38
	s_addc_u32 s39, s24, s39
	s_and_b64 s[46:47], s[8:9], exec
	s_cselect_b32 s35, s39, s45
	s_cselect_b32 s57, s38, s44
	s_add_u32 s42, s42, 0x20080
	s_addc_u32 s43, s43, 0
	s_add_u32 s58, s44, 0x100
	v_mov_b32_e32 v0, 0
	s_addc_u32 s59, s45, 0
	s_mov_b32 s60, -2
	ds_read_b128 v[128:131], v183
	ds_read_b128 v[132:135], v183 offset:1024
	ds_read_b128 v[136:139], v183 offset:2048
	ds_read_b128 v[140:143], v183 offset:3072
	ds_read_b128 v[144:147], v184
	ds_read_b128 v[148:151], v184 offset:1024
	ds_read_b128 v[152:155], v184 offset:2048
	ds_read_b128 v[172:175], v184 offset:3072
	s_add_u32 s44, s42, 0xfffe0080
	s_addc_u32 s45, s43, -1
	s_cmp_eq_u32 s60, 4
	s_cselect_b32 s47, s31, s45
	s_cselect_b32 s46, s56, s44
	s_cselect_b32 s45, s35, s59
	s_cselect_b32 s44, s57, s58
	v_lshl_add_u64 v[180:181], s[42:43], 0, v[164:165]
	s_add_i32 m0, s25, 0xc000
	ds_read_b128 v[176:179], v185
	ds_read_b128 v[186:189], v185 offset:1024
	ds_read_b128 v[190:193], v185 offset:2048
	ds_read_b128 v[194:197], v185 offset:3072
	ds_read_b128 v[198:201], v185 offset:4096
	ds_read_b128 v[202:205], v185 offset:5120
	ds_read_b128 v[206:209], v185 offset:6144
	ds_read_b128 v[210:213], v185 offset:7168
	global_load_lds_dwordx4 v[180:181], off
	v_lshl_add_u64 v[180:181], s[42:43], 0, v[166:167]
	s_add_i32 m0, s25, 0xe000
	s_nop 0
	global_load_lds_dwordx4 v[180:181], off
	s_waitcnt vmcnt(8)
	s_waitcnt lgkmcnt(0)
	s_barrier
	v_mfma_f32_16x16x32_bf16 v[124:127], v[128:131], v[176:179], 0
	v_mfma_f32_16x16x32_bf16 v[120:123], v[136:139], v[176:179], 0
	v_mfma_f32_16x16x32_bf16 v[108:111], v[128:131], v[190:193], 0
	v_mfma_f32_16x16x32_bf16 v[104:107], v[136:139], v[190:193], 0
	v_mfma_f32_16x16x32_bf16 v[92:95], v[128:131], v[198:201], 0
	v_mfma_f32_16x16x32_bf16 v[88:91], v[136:139], v[198:201], 0
	v_mfma_f32_16x16x32_bf16 v[76:79], v[128:131], v[206:209], 0
	v_mfma_f32_16x16x32_bf16 v[72:75], v[136:139], v[206:209], 0
	v_mfma_f32_16x16x32_bf16 v[124:127], v[132:135], v[186:189], v[124:127]
	v_mfma_f32_16x16x32_bf16 v[120:123], v[140:143], v[186:189], v[120:123]
	v_mfma_f32_16x16x32_bf16 v[108:111], v[132:135], v[194:197], v[108:111]
	v_mfma_f32_16x16x32_bf16 v[104:107], v[140:143], v[194:197], v[104:107]
	v_mfma_f32_16x16x32_bf16 v[92:95], v[132:135], v[202:205], v[92:95]
	v_mfma_f32_16x16x32_bf16 v[88:91], v[140:143], v[202:205], v[88:91]
	v_mfma_f32_16x16x32_bf16 v[76:79], v[132:135], v[210:213], v[76:79]
	v_mfma_f32_16x16x32_bf16 v[72:75], v[140:143], v[210:213], v[72:75]
	v_mfma_f32_16x16x32_bf16 v[116:119], v[144:147], v[176:179], 0
	v_mfma_f32_16x16x32_bf16 v[112:115], v[152:155], v[176:179], 0
	v_mfma_f32_16x16x32_bf16 v[100:103], v[144:147], v[190:193], 0
	v_mfma_f32_16x16x32_bf16 v[96:99], v[152:155], v[190:193], 0
	v_mfma_f32_16x16x32_bf16 v[84:87], v[144:147], v[198:201], 0
	v_mfma_f32_16x16x32_bf16 v[80:83], v[152:155], v[198:201], 0
	v_mfma_f32_16x16x32_bf16 v[68:71], v[144:147], v[206:209], 0
	v_mfma_f32_16x16x32_bf16 v[64:67], v[152:155], v[206:209], 0
	v_mfma_f32_16x16x32_bf16 v[116:119], v[148:151], v[186:189], v[116:119]
	v_mfma_f32_16x16x32_bf16 v[112:115], v[172:175], v[186:189], v[112:115]
	v_mfma_f32_16x16x32_bf16 v[100:103], v[148:151], v[194:197], v[100:103]
	v_mfma_f32_16x16x32_bf16 v[96:99], v[172:175], v[194:197], v[96:99]
	v_mfma_f32_16x16x32_bf16 v[84:87], v[148:151], v[202:205], v[84:87]
	v_mfma_f32_16x16x32_bf16 v[80:83], v[172:175], v[202:205], v[80:83]
	v_mfma_f32_16x16x32_bf16 v[68:71], v[148:151], v[210:213], v[68:71]
	v_mfma_f32_16x16x32_bf16 v[64:67], v[172:175], v[210:213], v[64:67]
	s_barrier
	s_add_i32 s61, s53, s94
	v_lshl_add_u64 v[180:181], s[44:45], 0, v[158:159]
	s_mov_b32 m0, s61
	ds_read_b128 v[176:179], v185 offset:16384
	ds_read_b128 v[186:189], v185 offset:17408
	ds_read_b128 v[190:193], v185 offset:18432
	ds_read_b128 v[194:197], v185 offset:19456
	ds_read_b128 v[198:201], v185 offset:20480
	ds_read_b128 v[202:205], v185 offset:21504
	ds_read_b128 v[206:209], v185 offset:22528
	ds_read_b128 v[210:213], v185 offset:23552
	global_load_lds_dwordx4 v[180:181], off
	s_add_i32 m0, s61, 0x2000
	s_add_u32 s62, s44, 0x20000
	v_lshl_add_u64 v[214:215], s[44:45], 0, v[162:163]
	s_addc_u32 s63, s45, 0
	s_add_i32 s61, s54, s94
	global_load_lds_dwordx4 v[214:215], off
	v_lshl_add_u64 v[216:217], s[62:63], 0, v[158:159]
	s_mov_b32 m0, s61
	v_lshl_add_u64 v[218:219], s[46:47], 0, v[160:161]
	global_load_lds_dwordx4 v[216:217], off
	v_lshl_add_u64 v[216:217], s[62:63], 0, v[162:163]
	s_add_i32 m0, s61, 0x2000
	s_nop 0
	global_load_lds_dwordx4 v[216:217], off
	v_lshl_add_u64 v[216:217], s[46:47], 0, v[156:157]
	s_mov_b32 m0, s25
	s_nop 0
	global_load_lds_dwordx4 v[216:217], off
	s_mov_b32 m0, s41
	s_nop 0
	global_load_lds_dwordx4 v[218:219], off
	s_waitcnt vmcnt(8)
	s_waitcnt lgkmcnt(0)
	s_barrier
; #define PG8_STAGE(bufoff, gbase, voff) do { _Pragma("unroll") for (int _i = 0; _i < 2; ++_i) \
;         __builtin_amdgcn_global_load_lds((const unsigned*)((const char*)(gbase) + (voff)[_i]), (LAS unsigned*)(lds + (bufoff) + ldsw + _i * 8192), 16, 0, 0); } while (0)
; #define PG8_LDA(dst, b, h) do { _Pragma("unroll") for (int m = 0; m < 4; ++m) _Pragma("unroll") for (int k = 0; k < 2; ++k) dst[m][k] = *(const LAS bf16x8*)(lds + PG8_SA(b, h) + aoff + m * 2048 + k * 1024); } while (0)
; #define PG8_LDB(dst, b, h) do { _Pragma("unroll") for (int n = 0; n < 2; ++n) _Pragma("unroll") for (int k = 0; k < 2; ++k) dst[n][k] = *(const LAS bf16x8*)(lds + PG8_SB(b, h) + boff + n * 2048 + k * 1024); } while (0)
; #define PG8_MMA(ai, bj, At, Bt) do { __builtin_amdgcn_s_setprio(1); _Pragma("unroll") for (int m = 0; m < 4; ++m) _Pragma("unroll") for (int n = 0; n < 2; ++n) _Pragma("unroll") for (int k = 0; k < 2; ++k) \
;         acc[ai][bj][m][n] = __builtin_amdgcn_mfma_f32_16x16x32_bf16(Bt[n][k], At[m][k], acc[ai][bj][m][n], 0, 0, 0); __builtin_amdgcn_s_setprio(0); } while (0)
; #define PG8_WAIT_V(n) asm volatile("s_waitcnt vmcnt(" #n ")" ::: "memory")
; #define PG8_WAIT_L(n) asm volatile("s_waitcnt lgkmcnt(" #n ")" ::: "memory")
; template <class Epi>
; DI void gemm_phase(LAS unsigned char* lds, const int wid, const Gemm g, const Order& S, const Epi& E) {
;     ...
;             PG8_LDB(B0, 0, 0); PG8_LDB(B1, 0, 1); PG8_SCHED; PG8_LDA(At, 0, 0); PG8_STAGE(PG8_SA(1, 1), a1 + hstepA, voffA);
;             PG8_WAIT_V(8); PG8_WAIT_L(0); PG8_BAR; PG8_MMA(0, 0, At, B0); PG8_MMA(0, 1, At, B1); PG8_BAR; PG8_SCHED;
;             PG8_LDA(At, 0, 1); PG8_STAGE(PG8_SB(0, 0), b2, voffB); PG8_STAGE(PG8_SB(0, 1), b2 + hstepB, voffB); PG8_STAGE(PG8_SA(0, 0), a2, voffA);
;             PG8_WAIT_V(8); PG8_WAIT_L(0); PG8_BAR; PG8_MMA(1, 0, At, B0); PG8_MMA(1, 1, At, B1); PG8_BAR; PG8_SCHED;
;             PG8_LDB(B0, 1, 0); PG8_LDB(B1, 1, 1); PG8_SCHED; PG8_LDA(At, 1, 0); PG8_STAGE(PG8_SA(0, 1), a2 + hstepA, voffA);
;             PG8_WAIT_V(8); PG8_WAIT_L(0); PG8_BAR; PG8_MMA(0, 0, At, B0); PG8_MMA(0, 1, At, B1); PG8_BAR; PG8_SCHED;
;             PG8_LDA(At, 1, 1); PG8_STAGE(PG8_SB(1, 0), b3, voffB); PG8_STAGE(PG8_SB(1, 1), b3 + hstepB, voffB); PG8_STAGE(PG8_SA(1, 0), a3, voffA);
;             PG8_WAIT_V(8); PG8_WAIT_L(0); PG8_BAR; PG8_MMA(1, 0, At, B0); PG8_MMA(1, 1, At, B1); PG8_BAR; PG8_SCHED;
	v_mfma_f32_16x16x32_bf16 v[60:63], v[128:131], v[176:179], 0
	v_mfma_f32_16x16x32_bf16 v[56:59], v[136:139], v[176:179], 0
	v_mfma_f32_16x16x32_bf16 v[44:47], v[128:131], v[190:193], 0
	v_mfma_f32_16x16x32_bf16 v[40:43], v[136:139], v[190:193], 0
	v_mfma_f32_16x16x32_bf16 v[28:31], v[128:131], v[198:201], 0
	v_mfma_f32_16x16x32_bf16 v[24:27], v[136:139], v[198:201], 0
	v_mfma_f32_16x16x32_bf16 v[12:15], v[128:131], v[206:209], 0
	v_mfma_f32_16x16x32_bf16 v[8:11], v[136:139], v[206:209], 0
	v_mfma_f32_16x16x32_bf16 v[60:63], v[132:135], v[186:189], v[60:63]
	v_mfma_f32_16x16x32_bf16 v[56:59], v[140:143], v[186:189], v[56:59]
	v_mfma_f32_16x16x32_bf16 v[44:47], v[132:135], v[194:197], v[44:47]
	v_mfma_f32_16x16x32_bf16 v[40:43], v[140:143], v[194:197], v[40:43]
	v_mfma_f32_16x16x32_bf16 v[28:31], v[132:135], v[202:205], v[28:31]
	v_mfma_f32_16x16x32_bf16 v[24:27], v[140:143], v[202:205], v[24:27]
	v_mfma_f32_16x16x32_bf16 v[12:15], v[132:135], v[210:213], v[12:15]
	v_mfma_f32_16x16x32_bf16 v[8:11], v[140:143], v[210:213], v[8:11]
	v_mfma_f32_16x16x32_bf16 v[52:55], v[144:147], v[176:179], 0
	v_mfma_f32_16x16x32_bf16 v[48:51], v[152:155], v[176:179], 0
	v_mfma_f32_16x16x32_bf16 v[36:39], v[144:147], v[190:193], 0
	v_mfma_f32_16x16x32_bf16 v[32:35], v[152:155], v[190:193], 0
	v_mfma_f32_16x16x32_bf16 v[20:23], v[144:147], v[198:201], 0
	v_mfma_f32_16x16x32_bf16 v[16:19], v[152:155], v[198:201], 0
	v_mfma_f32_16x16x32_bf16 v[4:7], v[144:147], v[206:209], 0
	v_mfma_f32_16x16x32_bf16 v[0:3], v[152:155], v[206:209], 0
	v_mfma_f32_16x16x32_bf16 v[52:55], v[148:151], v[186:189], v[52:55]
	v_mfma_f32_16x16x32_bf16 v[48:51], v[172:175], v[186:189], v[48:51]
	v_mfma_f32_16x16x32_bf16 v[36:39], v[148:151], v[194:197], v[36:39]
	v_mfma_f32_16x16x32_bf16 v[32:35], v[172:175], v[194:197], v[32:35]
	v_mfma_f32_16x16x32_bf16 v[20:23], v[148:151], v[202:205], v[20:23]
	v_mfma_f32_16x16x32_bf16 v[16:19], v[172:175], v[202:205], v[16:19]
	v_mfma_f32_16x16x32_bf16 v[4:7], v[148:151], v[210:213], v[4:7]
	v_mfma_f32_16x16x32_bf16 v[0:3], v[172:175], v[210:213], v[0:3]
	s_barrier
	s_add_i32 s61, 0, 0x18000
	s_add_i32 s62, 0, 0x1c000
	v_add_u32_e32 v140, s61, v182
	v_add_u32_e32 v172, s62, v182
	ds_read_b128 v[128:131], v140
	ds_read_b128 v[132:135], v140 offset:1024
	ds_read_b128 v[136:139], v140 offset:2048
	ds_read_b128 v[140:143], v140 offset:3072
	ds_read_b128 v[144:147], v172
	ds_read_b128 v[148:151], v172 offset:1024
	ds_read_b128 v[152:155], v172 offset:2048
	ds_read_b128 v[172:175], v172 offset:3072
	s_add_u32 s46, s46, 0x20000
	s_addc_u32 s47, s47, 0
	s_mov_b32 m0, s48
	v_lshl_add_u64 v[220:221], s[46:47], 0, v[156:157]
	ds_read_b128 v[176:179], v185 offset:32768
	ds_read_b128 v[186:189], v185 offset:33792
	ds_read_b128 v[190:193], v185 offset:34816
	ds_read_b128 v[194:197], v185 offset:35840
	ds_read_b128 v[198:201], v185 offset:36864
	ds_read_b128 v[202:205], v185 offset:37888
	ds_read_b128 v[206:209], v185 offset:38912
	ds_read_b128 v[210:213], v185 offset:39936
	global_load_lds_dwordx4 v[220:221], off
	v_lshl_add_u64 v[220:221], s[46:47], 0, v[160:161]
	s_mov_b32 m0, s49
	s_nop 0
	global_load_lds_dwordx4 v[220:221], off
	s_waitcnt vmcnt(8)
	s_waitcnt lgkmcnt(0)
	s_barrier
	v_mfma_f32_16x16x32_bf16 v[124:127], v[128:131], v[176:179], v[124:127]
	v_mfma_f32_16x16x32_bf16 v[120:123], v[136:139], v[176:179], v[120:123]
	v_mfma_f32_16x16x32_bf16 v[108:111], v[128:131], v[190:193], v[108:111]
	v_mfma_f32_16x16x32_bf16 v[104:107], v[136:139], v[190:193], v[104:107]
	v_mfma_f32_16x16x32_bf16 v[92:95], v[128:131], v[198:201], v[92:95]
	v_mfma_f32_16x16x32_bf16 v[88:91], v[136:139], v[198:201], v[88:91]
	v_mfma_f32_16x16x32_bf16 v[76:79], v[128:131], v[206:209], v[76:79]
	v_mfma_f32_16x16x32_bf16 v[72:75], v[136:139], v[206:209], v[72:75]
	v_mfma_f32_16x16x32_bf16 v[124:127], v[132:135], v[186:189], v[124:127]
	v_mfma_f32_16x16x32_bf16 v[120:123], v[140:143], v[186:189], v[120:123]
	v_mfma_f32_16x16x32_bf16 v[108:111], v[132:135], v[194:197], v[108:111]
	v_mfma_f32_16x16x32_bf16 v[104:107], v[140:143], v[194:197], v[104:107]
	v_mfma_f32_16x16x32_bf16 v[92:95], v[132:135], v[202:205], v[92:95]
	v_mfma_f32_16x16x32_bf16 v[88:91], v[140:143], v[202:205], v[88:91]
	v_mfma_f32_16x16x32_bf16 v[76:79], v[132:135], v[210:213], v[76:79]
	v_mfma_f32_16x16x32_bf16 v[72:75], v[140:143], v[210:213], v[72:75]
	v_mfma_f32_16x16x32_bf16 v[116:119], v[144:147], v[176:179], v[116:119]
	v_mfma_f32_16x16x32_bf16 v[112:115], v[152:155], v[176:179], v[112:115]
	v_mfma_f32_16x16x32_bf16 v[100:103], v[144:147], v[190:193], v[100:103]
	v_mfma_f32_16x16x32_bf16 v[96:99], v[152:155], v[190:193], v[96:99]
	v_mfma_f32_16x16x32_bf16 v[84:87], v[144:147], v[198:201], v[84:87]
	v_mfma_f32_16x16x32_bf16 v[80:83], v[152:155], v[198:201], v[80:83]
	v_mfma_f32_16x16x32_bf16 v[68:71], v[144:147], v[206:209], v[68:71]
	v_mfma_f32_16x16x32_bf16 v[64:67], v[152:155], v[206:209], v[64:67]
	v_mfma_f32_16x16x32_bf16 v[116:119], v[148:151], v[186:189], v[116:119]
	v_mfma_f32_16x16x32_bf16 v[112:115], v[172:175], v[186:189], v[112:115]
	v_mfma_f32_16x16x32_bf16 v[100:103], v[148:151], v[194:197], v[100:103]
	v_mfma_f32_16x16x32_bf16 v[96:99], v[172:175], v[194:197], v[96:99]
	v_mfma_f32_16x16x32_bf16 v[84:87], v[148:151], v[202:205], v[84:87]
	v_mfma_f32_16x16x32_bf16 v[80:83], v[172:175], v[202:205], v[80:83]
	v_mfma_f32_16x16x32_bf16 v[68:71], v[148:151], v[210:213], v[68:71]
	v_mfma_f32_16x16x32_bf16 v[64:67], v[172:175], v[210:213], v[64:67]
	s_barrier
; #define PG8_STAGE(bufoff, gbase, voff) do { _Pragma("unroll") for (int _i = 0; _i < 2; ++_i) \
;         __builtin_amdgcn_global_load_lds((const unsigned*)((const char*)(gbase) + (voff)[_i]), (LAS unsigned*)(lds + (bufoff) + ldsw + _i * 8192), 16, 0, 0); } while (0)
; #define PG8_LDA(dst, b, h) do { _Pragma("unroll") for (int m = 0; m < 4; ++m) _Pragma("unroll") for (int k = 0; k < 2; ++k) dst[m][k] = *(const LAS bf16x8*)(lds + PG8_SA(b, h) + aoff + m * 2048 + k * 1024); } while (0)
; #define PG8_LDB(dst, b, h) do { _Pragma("unroll") for (int n = 0; n < 2; ++n) _Pragma("unroll") for (int k = 0; k < 2; ++k) dst[n][k] = *(const LAS bf16x8*)(lds + PG8_SB(b, h) + boff + n * 2048 + k * 1024); } while (0)
; #define PG8_MMA(ai, bj, At, Bt) do { __builtin_amdgcn_s_setprio(1); _Pragma("unroll") for (int m = 0; m < 4; ++m) _Pragma("unroll") for (int n = 0; n < 2; ++n) _Pragma("unroll") for (int k = 0; k < 2; ++k) \
;         acc[ai][bj][m][n] = __builtin_amdgcn_mfma_f32_16x16x32_bf16(Bt[n][k], At[m][k], acc[ai][bj][m][n], 0, 0, 0); __builtin_amdgcn_s_setprio(0); } while (0)
; #define PG8_WAIT_V(n) asm volatile("s_waitcnt vmcnt(" #n ")" ::: "memory")
; #define PG8_WAIT_L(n) asm volatile("s_waitcnt lgkmcnt(" #n ")" ::: "memory")
; template <class Epi>
; DI void gemm_phase(LAS unsigned char* lds, const int wid, const Gemm g, const Order& S, const Epi& E) {
;     ...
;             PG8_LDB(B0, 0, 0); PG8_LDB(B1, 0, 1); PG8_SCHED; PG8_LDA(At, 0, 0); PG8_STAGE(PG8_SA(1, 1), a1 + hstepA, voffA);
;             PG8_WAIT_V(8); PG8_WAIT_L(0); PG8_BAR; PG8_MMA(0, 0, At, B0); PG8_MMA(0, 1, At, B1); PG8_BAR; PG8_SCHED;
;             PG8_LDA(At, 0, 1); PG8_STAGE(PG8_SB(0, 0), b2, voffB); PG8_STAGE(PG8_SB(0, 1), b2 + hstepB, voffB); PG8_STAGE(PG8_SA(0, 0), a2, voffA);
;             PG8_WAIT_V(8); PG8_WAIT_L(0); PG8_BAR; PG8_MMA(1, 0, At, B0); PG8_MMA(1, 1, At, B1); PG8_BAR; PG8_SCHED;
;             PG8_LDB(B0, 1, 0); PG8_LDB(B1, 1, 1); PG8_SCHED; PG8_LDA(At, 1, 0); PG8_STAGE(PG8_SA(0, 1), a2 + hstepA, voffA);
;             PG8_WAIT_V(8); PG8_WAIT_L(0); PG8_BAR; PG8_MMA(0, 0, At, B0); PG8_MMA(0, 1, At, B1); PG8_BAR; PG8_SCHED;
;             PG8_LDA(At, 1, 1); PG8_STAGE(PG8_SB(1, 0), b3, voffB); PG8_STAGE(PG8_SB(1, 1), b3 + hstepB, voffB); PG8_STAGE(PG8_SA(1, 0), a3, voffA);
;             PG8_WAIT_V(8); PG8_WAIT_L(0); PG8_BAR; PG8_MMA(1, 0, At, B0); PG8_MMA(1, 1, At, B1); PG8_BAR; PG8_SCHED;
	s_add_i32 s46, s61, s94
	v_lshl_add_u64 v[180:181], v[180:181], 0, s[26:27]
	s_mov_b32 m0, s46
	ds_read_b128 v[176:179], v185 offset:49152
	ds_read_b128 v[186:189], v185 offset:50176
	ds_read_b128 v[190:193], v185 offset:51200
	ds_read_b128 v[194:197], v185 offset:52224
	ds_read_b128 v[198:201], v185 offset:53248
	ds_read_b128 v[202:205], v185 offset:54272
	ds_read_b128 v[206:209], v185 offset:55296
	ds_read_b128 v[210:213], v185 offset:56320
	global_load_lds_dwordx4 v[180:181], off
	s_add_i32 m0, s46, 0x2000
	s_add_u32 s44, s44, 0x20080
	v_lshl_add_u64 v[180:181], v[214:215], 0, s[26:27]
	s_addc_u32 s45, s45, 0
	s_add_i32 s46, s62, s94
	global_load_lds_dwordx4 v[180:181], off
	v_lshl_add_u64 v[180:181], s[44:45], 0, v[158:159]
	s_mov_b32 m0, s46
	s_nop 0
	global_load_lds_dwordx4 v[180:181], off
	v_lshl_add_u64 v[180:181], s[44:45], 0, v[162:163]
	s_add_i32 m0, s46, 0x2000
	s_nop 0
	global_load_lds_dwordx4 v[180:181], off
	v_lshl_add_u64 v[180:181], v[216:217], 0, s[26:27]
	s_mov_b32 m0, s51
	s_nop 0
	global_load_lds_dwordx4 v[180:181], off
	v_lshl_add_u64 v[180:181], v[218:219], 0, s[26:27]
	s_mov_b32 m0, s52
	s_nop 0
	global_load_lds_dwordx4 v[180:181], off
	s_waitcnt vmcnt(8)
	s_waitcnt lgkmcnt(0)
	s_barrier
	v_mfma_f32_16x16x32_bf16 v[60:63], v[128:131], v[176:179], v[60:63]
	v_mfma_f32_16x16x32_bf16 v[56:59], v[136:139], v[176:179], v[56:59]
	v_mfma_f32_16x16x32_bf16 v[44:47], v[128:131], v[190:193], v[44:47]
	v_mfma_f32_16x16x32_bf16 v[40:43], v[136:139], v[190:193], v[40:43]
	v_mfma_f32_16x16x32_bf16 v[28:31], v[128:131], v[198:201], v[28:31]
	v_mfma_f32_16x16x32_bf16 v[24:27], v[136:139], v[198:201], v[24:27]
	v_mfma_f32_16x16x32_bf16 v[12:15], v[128:131], v[206:209], v[12:15]
	v_mfma_f32_16x16x32_bf16 v[8:11], v[136:139], v[206:209], v[8:11]
	v_mfma_f32_16x16x32_bf16 v[60:63], v[132:135], v[186:189], v[60:63]
	v_mfma_f32_16x16x32_bf16 v[56:59], v[140:143], v[186:189], v[56:59]
	v_mfma_f32_16x16x32_bf16 v[44:47], v[132:135], v[194:197], v[44:47]
	v_mfma_f32_16x16x32_bf16 v[40:43], v[140:143], v[194:197], v[40:43]
	v_mfma_f32_16x16x32_bf16 v[28:31], v[132:135], v[202:205], v[28:31]
	v_mfma_f32_16x16x32_bf16 v[24:27], v[140:143], v[202:205], v[24:27]
	v_mfma_f32_16x16x32_bf16 v[12:15], v[132:135], v[210:213], v[12:15]
	v_mfma_f32_16x16x32_bf16 v[8:11], v[140:143], v[210:213], v[8:11]
	v_mfma_f32_16x16x32_bf16 v[52:55], v[144:147], v[176:179], v[52:55]
	v_mfma_f32_16x16x32_bf16 v[48:51], v[152:155], v[176:179], v[48:51]
	v_mfma_f32_16x16x32_bf16 v[36:39], v[144:147], v[190:193], v[36:39]
	v_mfma_f32_16x16x32_bf16 v[32:35], v[152:155], v[190:193], v[32:35]
	v_mfma_f32_16x16x32_bf16 v[20:23], v[144:147], v[198:201], v[20:23]
	v_mfma_f32_16x16x32_bf16 v[16:19], v[152:155], v[198:201], v[16:19]
	v_mfma_f32_16x16x32_bf16 v[4:7], v[144:147], v[206:209], v[4:7]
	v_mfma_f32_16x16x32_bf16 v[0:3], v[152:155], v[206:209], v[0:3]
	v_mfma_f32_16x16x32_bf16 v[52:55], v[148:151], v[186:189], v[52:55]
	v_mfma_f32_16x16x32_bf16 v[48:51], v[172:175], v[186:189], v[48:51]
	v_mfma_f32_16x16x32_bf16 v[36:39], v[148:151], v[194:197], v[36:39]
	v_mfma_f32_16x16x32_bf16 v[32:35], v[172:175], v[194:197], v[32:35]
	v_mfma_f32_16x16x32_bf16 v[20:23], v[148:151], v[202:205], v[20:23]
	v_mfma_f32_16x16x32_bf16 v[16:19], v[172:175], v[202:205], v[16:19]
	v_mfma_f32_16x16x32_bf16 v[4:7], v[148:151], v[210:213], v[4:7]
	v_mfma_f32_16x16x32_bf16 v[0:3], v[172:175], v[210:213], v[0:3]
	s_barrier
	s_add_i32 s60, s60, 2
	s_add_u32 s42, s42, 0x100
	s_addc_u32 s43, s43, 0
	s_add_u32 s58, s58, 0x100
	s_addc_u32 s59, s59, 0
	s_cmp_gt_u32 s60, 5
	s_cbranch_scc0 .LBB0_1170
	s_branch .Lpeel_exit_7
.LBB0_1170:
	ds_read_b128 v[128:131], v183
	ds_read_b128 v[132:135], v183 offset:1024
	ds_read_b128 v[136:139], v183 offset:2048
	ds_read_b128 v[140:143], v183 offset:3072
	ds_read_b128 v[144:147], v184
	ds_read_b128 v[148:151], v184 offset:1024
	ds_read_b128 v[152:155], v184 offset:2048
	ds_read_b128 v[172:175], v184 offset:3072
	s_add_u32 s44, s42, 0xfffe0080
	s_addc_u32 s45, s43, -1
	s_cmp_eq_u32 s60, 4
	s_cselect_b32 s47, s31, s45
	s_cselect_b32 s46, s56, s44
	s_cselect_b32 s45, s35, s59
	s_cselect_b32 s44, s57, s58
	v_lshl_add_u64 v[180:181], s[42:43], 0, v[164:165]
	s_add_i32 m0, s25, 0xc000
	ds_read_b128 v[176:179], v185
	ds_read_b128 v[186:189], v185 offset:1024
	ds_read_b128 v[190:193], v185 offset:2048
	ds_read_b128 v[194:197], v185 offset:3072
	ds_read_b128 v[198:201], v185 offset:4096
	ds_read_b128 v[202:205], v185 offset:5120
	ds_read_b128 v[206:209], v185 offset:6144
	ds_read_b128 v[210:213], v185 offset:7168
	global_load_lds_dwordx4 v[180:181], off
	v_lshl_add_u64 v[180:181], s[42:43], 0, v[166:167]
	s_add_i32 m0, s25, 0xe000
	s_nop 0
	global_load_lds_dwordx4 v[180:181], off
	s_waitcnt vmcnt(8)
	s_waitcnt lgkmcnt(0)
	s_barrier
; #define PG8_STAGE(bufoff, gbase, voff) do { _Pragma("unroll") for (int _i = 0; _i < 2; ++_i) \
;         __builtin_amdgcn_global_load_lds((const unsigned*)((const char*)(gbase) + (voff)[_i]), (LAS unsigned*)(lds + (bufoff) + ldsw + _i * 8192), 16, 0, 0); } while (0)
; #define PG8_LDA(dst, b, h) do { _Pragma("unroll") for (int m = 0; m < 4; ++m) _Pragma("unroll") for (int k = 0; k < 2; ++k) dst[m][k] = *(const LAS bf16x8*)(lds + PG8_SA(b, h) + aoff + m * 2048 + k * 1024); } while (0)
; #define PG8_LDB(dst, b, h) do { _Pragma("unroll") for (int n = 0; n < 2; ++n) _Pragma("unroll") for (int k = 0; k < 2; ++k) dst[n][k] = *(const LAS bf16x8*)(lds + PG8_SB(b, h) + boff + n * 2048 + k * 1024); } while (0)
; #define PG8_MMA(ai, bj, At, Bt) do { __builtin_amdgcn_s_setprio(1); _Pragma("unroll") for (int m = 0; m < 4; ++m) _Pragma("unroll") for (int n = 0; n < 2; ++n) _Pragma("unroll") for (int k = 0; k < 2; ++k) \
;         acc[ai][bj][m][n] = __builtin_amdgcn_mfma_f32_16x16x32_bf16(Bt[n][k], At[m][k], acc[ai][bj][m][n], 0, 0, 0); __builtin_amdgcn_s_setprio(0); } while (0)
; #define PG8_WAIT_V(n) asm volatile("s_waitcnt vmcnt(" #n ")" ::: "memory")
; #define PG8_WAIT_L(n) asm volatile("s_waitcnt lgkmcnt(" #n ")" ::: "memory")
; #define PG8_BAR __builtin_amdgcn_s_barrier()
; #define PG8_SCHED __builtin_amdgcn_sched_barrier(0)
; template <class Epi>
; DI void gemm_phase(LAS unsigned char* lds, const int wid, const Gemm g, const Order& S, const Epi& E) {
;     ...
;             PG8_LDB(B0, 0, 0); PG8_LDB(B1, 0, 1); PG8_SCHED; PG8_LDA(At, 0, 0); PG8_STAGE(PG8_SA(1, 1), a1 + hstepA, voffA);
;             PG8_WAIT_V(8); PG8_WAIT_L(0); PG8_BAR; PG8_MMA(0, 0, At, B0); PG8_MMA(0, 1, At, B1); PG8_BAR; PG8_SCHED;
;             PG8_LDA(At, 0, 1); PG8_STAGE(PG8_SB(0, 0), b2, voffB); PG8_STAGE(PG8_SB(0, 1), b2 + hstepB, voffB); PG8_STAGE(PG8_SA(0, 0), a2, voffA);
;             PG8_WAIT_V(8); PG8_WAIT_L(0); PG8_BAR; PG8_MMA(1, 0, At, B0); PG8_MMA(1, 1, At, B1); PG8_BAR; PG8_SCHED;
;             PG8_LDB(B0, 1, 0); PG8_LDB(B1, 1, 1); PG8_SCHED; PG8_LDA(At, 1, 0); PG8_STAGE(PG8_SA(0, 1), a2 + hstepA, voffA);
;             PG8_WAIT_V(8); PG8_WAIT_L(0); PG8_BAR; PG8_MMA(0, 0, At, B0); PG8_MMA(0, 1, At, B1); PG8_BAR; PG8_SCHED;
	v_mfma_f32_16x16x32_bf16 v[124:127], v[128:131], v[176:179], v[124:127]
	v_mfma_f32_16x16x32_bf16 v[120:123], v[136:139], v[176:179], v[120:123]
	v_mfma_f32_16x16x32_bf16 v[108:111], v[128:131], v[190:193], v[108:111]
	v_mfma_f32_16x16x32_bf16 v[104:107], v[136:139], v[190:193], v[104:107]
	v_mfma_f32_16x16x32_bf16 v[92:95], v[128:131], v[198:201], v[92:95]
	v_mfma_f32_16x16x32_bf16 v[88:91], v[136:139], v[198:201], v[88:91]
	v_mfma_f32_16x16x32_bf16 v[76:79], v[128:131], v[206:209], v[76:79]
	v_mfma_f32_16x16x32_bf16 v[72:75], v[136:139], v[206:209], v[72:75]
	v_mfma_f32_16x16x32_bf16 v[124:127], v[132:135], v[186:189], v[124:127]
	v_mfma_f32_16x16x32_bf16 v[120:123], v[140:143], v[186:189], v[120:123]
	v_mfma_f32_16x16x32_bf16 v[108:111], v[132:135], v[194:197], v[108:111]
	v_mfma_f32_16x16x32_bf16 v[104:107], v[140:143], v[194:197], v[104:107]
	v_mfma_f32_16x16x32_bf16 v[92:95], v[132:135], v[202:205], v[92:95]
	v_mfma_f32_16x16x32_bf16 v[88:91], v[140:143], v[202:205], v[88:91]
	v_mfma_f32_16x16x32_bf16 v[76:79], v[132:135], v[210:213], v[76:79]
	v_mfma_f32_16x16x32_bf16 v[72:75], v[140:143], v[210:213], v[72:75]
	v_mfma_f32_16x16x32_bf16 v[116:119], v[144:147], v[176:179], v[116:119]
	v_mfma_f32_16x16x32_bf16 v[112:115], v[152:155], v[176:179], v[112:115]
	v_mfma_f32_16x16x32_bf16 v[100:103], v[144:147], v[190:193], v[100:103]
	v_mfma_f32_16x16x32_bf16 v[96:99], v[152:155], v[190:193], v[96:99]
	v_mfma_f32_16x16x32_bf16 v[84:87], v[144:147], v[198:201], v[84:87]
	v_mfma_f32_16x16x32_bf16 v[80:83], v[152:155], v[198:201], v[80:83]
	v_mfma_f32_16x16x32_bf16 v[68:71], v[144:147], v[206:209], v[68:71]
	v_mfma_f32_16x16x32_bf16 v[64:67], v[152:155], v[206:209], v[64:67]
	v_mfma_f32_16x16x32_bf16 v[116:119], v[148:151], v[186:189], v[116:119]
	v_mfma_f32_16x16x32_bf16 v[112:115], v[172:175], v[186:189], v[112:115]
	v_mfma_f32_16x16x32_bf16 v[100:103], v[148:151], v[194:197], v[100:103]
	v_mfma_f32_16x16x32_bf16 v[96:99], v[172:175], v[194:197], v[96:99]
	v_mfma_f32_16x16x32_bf16 v[84:87], v[148:151], v[202:205], v[84:87]
	v_mfma_f32_16x16x32_bf16 v[80:83], v[172:175], v[202:205], v[80:83]
	v_mfma_f32_16x16x32_bf16 v[68:71], v[148:151], v[210:213], v[68:71]
	v_mfma_f32_16x16x32_bf16 v[64:67], v[172:175], v[210:213], v[64:67]
	s_barrier
	s_add_i32 s61, s53, s94
	v_lshl_add_u64 v[180:181], s[44:45], 0, v[158:159]
	s_mov_b32 m0, s61
	ds_read_b128 v[176:179], v185 offset:16384
	ds_read_b128 v[186:189], v185 offset:17408
	ds_read_b128 v[190:193], v185 offset:18432
	ds_read_b128 v[194:197], v185 offset:19456
	ds_read_b128 v[198:201], v185 offset:20480
	ds_read_b128 v[202:205], v185 offset:21504
	ds_read_b128 v[206:209], v185 offset:22528
	ds_read_b128 v[210:213], v185 offset:23552
	global_load_lds_dwordx4 v[180:181], off
	s_add_i32 m0, s61, 0x2000
	s_add_u32 s62, s44, 0x20000
	v_lshl_add_u64 v[214:215], s[44:45], 0, v[162:163]
	s_addc_u32 s63, s45, 0
	s_add_i32 s61, s54, s94
	global_load_lds_dwordx4 v[214:215], off
	v_lshl_add_u64 v[216:217], s[62:63], 0, v[158:159]
	s_mov_b32 m0, s61
	v_lshl_add_u64 v[218:219], s[46:47], 0, v[160:161]
	global_load_lds_dwordx4 v[216:217], off
	v_lshl_add_u64 v[216:217], s[62:63], 0, v[162:163]
	s_add_i32 m0, s61, 0x2000
	s_nop 0
	global_load_lds_dwordx4 v[216:217], off
	v_lshl_add_u64 v[216:217], s[46:47], 0, v[156:157]
	s_mov_b32 m0, s25
	s_nop 0
	global_load_lds_dwordx4 v[216:217], off
	s_mov_b32 m0, s41
	s_nop 0
	global_load_lds_dwordx4 v[218:219], off
	s_waitcnt vmcnt(8)
	s_waitcnt lgkmcnt(0)
	s_barrier
	v_mfma_f32_16x16x32_bf16 v[60:63], v[128:131], v[176:179], v[60:63]
	v_mfma_f32_16x16x32_bf16 v[56:59], v[136:139], v[176:179], v[56:59]
	v_mfma_f32_16x16x32_bf16 v[44:47], v[128:131], v[190:193], v[44:47]
	v_mfma_f32_16x16x32_bf16 v[40:43], v[136:139], v[190:193], v[40:43]
	v_mfma_f32_16x16x32_bf16 v[28:31], v[128:131], v[198:201], v[28:31]
	v_mfma_f32_16x16x32_bf16 v[24:27], v[136:139], v[198:201], v[24:27]
	v_mfma_f32_16x16x32_bf16 v[12:15], v[128:131], v[206:209], v[12:15]
	v_mfma_f32_16x16x32_bf16 v[8:11], v[136:139], v[206:209], v[8:11]
	v_mfma_f32_16x16x32_bf16 v[60:63], v[132:135], v[186:189], v[60:63]
	v_mfma_f32_16x16x32_bf16 v[56:59], v[140:143], v[186:189], v[56:59]
	v_mfma_f32_16x16x32_bf16 v[44:47], v[132:135], v[194:197], v[44:47]
	v_mfma_f32_16x16x32_bf16 v[40:43], v[140:143], v[194:197], v[40:43]
	v_mfma_f32_16x16x32_bf16 v[28:31], v[132:135], v[202:205], v[28:31]
	v_mfma_f32_16x16x32_bf16 v[24:27], v[140:143], v[202:205], v[24:27]
	v_mfma_f32_16x16x32_bf16 v[12:15], v[132:135], v[210:213], v[12:15]
	v_mfma_f32_16x16x32_bf16 v[8:11], v[140:143], v[210:213], v[8:11]
	v_mfma_f32_16x16x32_bf16 v[52:55], v[144:147], v[176:179], v[52:55]
	v_mfma_f32_16x16x32_bf16 v[48:51], v[152:155], v[176:179], v[48:51]
	v_mfma_f32_16x16x32_bf16 v[36:39], v[144:147], v[190:193], v[36:39]
	v_mfma_f32_16x16x32_bf16 v[32:35], v[152:155], v[190:193], v[32:35]
	v_mfma_f32_16x16x32_bf16 v[20:23], v[144:147], v[198:201], v[20:23]
	v_mfma_f32_16x16x32_bf16 v[16:19], v[152:155], v[198:201], v[16:19]
	v_mfma_f32_16x16x32_bf16 v[4:7], v[144:147], v[206:209], v[4:7]
	v_mfma_f32_16x16x32_bf16 v[0:3], v[152:155], v[206:209], v[0:3]
	v_mfma_f32_16x16x32_bf16 v[52:55], v[148:151], v[186:189], v[52:55]
	v_mfma_f32_16x16x32_bf16 v[48:51], v[172:175], v[186:189], v[48:51]
	v_mfma_f32_16x16x32_bf16 v[36:39], v[148:151], v[194:197], v[36:39]
	v_mfma_f32_16x16x32_bf16 v[32:35], v[172:175], v[194:197], v[32:35]
	v_mfma_f32_16x16x32_bf16 v[20:23], v[148:151], v[202:205], v[20:23]
	v_mfma_f32_16x16x32_bf16 v[16:19], v[172:175], v[202:205], v[16:19]
	v_mfma_f32_16x16x32_bf16 v[4:7], v[148:151], v[210:213], v[4:7]
	v_mfma_f32_16x16x32_bf16 v[0:3], v[172:175], v[210:213], v[0:3]
	s_barrier
; #define PG8_STAGE(bufoff, gbase, voff) do { _Pragma("unroll") for (int _i = 0; _i < 2; ++_i) \
;         __builtin_amdgcn_global_load_lds((const unsigned*)((const char*)(gbase) + (voff)[_i]), (LAS unsigned*)(lds + (bufoff) + ldsw + _i * 8192), 16, 0, 0); } while (0)
; #define PG8_LDA(dst, b, h) do { _Pragma("unroll") for (int m = 0; m < 4; ++m) _Pragma("unroll") for (int k = 0; k < 2; ++k) dst[m][k] = *(const LAS bf16x8*)(lds + PG8_SA(b, h) + aoff + m * 2048 + k * 1024); } while (0)
; #define PG8_LDB(dst, b, h) do { _Pragma("unroll") for (int n = 0; n < 2; ++n) _Pragma("unroll") for (int k = 0; k < 2; ++k) dst[n][k] = *(const LAS bf16x8*)(lds + PG8_SB(b, h) + boff + n * 2048 + k * 1024); } while (0)
; #define PG8_MMA(ai, bj, At, Bt) do { __builtin_amdgcn_s_setprio(1); _Pragma("unroll") for (int m = 0; m < 4; ++m) _Pragma("unroll") for (int n = 0; n < 2; ++n) _Pragma("unroll") for (int k = 0; k < 2; ++k) \
;         acc[ai][bj][m][n] = __builtin_amdgcn_mfma_f32_16x16x32_bf16(Bt[n][k], At[m][k], acc[ai][bj][m][n], 0, 0, 0); __builtin_amdgcn_s_setprio(0); } while (0)
; #define PG8_WAIT_V(n) asm volatile("s_waitcnt vmcnt(" #n ")" ::: "memory")
; #define PG8_WAIT_L(n) asm volatile("s_waitcnt lgkmcnt(" #n ")" ::: "memory")
; #define PG8_BAR __builtin_amdgcn_s_barrier()
; #define PG8_SCHED __builtin_amdgcn_sched_barrier(0)
; template <class Epi>
; DI void gemm_phase(LAS unsigned char* lds, const int wid, const Gemm g, const Order& S, const Epi& E) {
;     ...
;             PG8_LDB(B0, 1, 0); PG8_LDB(B1, 1, 1); PG8_SCHED; PG8_LDA(At, 1, 0); PG8_STAGE(PG8_SA(0, 1), a2 + hstepA, voffA);
;             PG8_WAIT_V(8); PG8_WAIT_L(0); PG8_BAR; PG8_MMA(0, 0, At, B0); PG8_MMA(0, 1, At, B1); PG8_BAR; PG8_SCHED;
;             PG8_LDA(At, 1, 1); PG8_STAGE(PG8_SB(1, 0), b3, voffB); PG8_STAGE(PG8_SB(1, 1), b3 + hstepB, voffB); PG8_STAGE(PG8_SA(1, 0), a3, voffA);
;             PG8_WAIT_V(8); PG8_WAIT_L(0); PG8_BAR; PG8_MMA(1, 0, At, B0); PG8_MMA(1, 1, At, B1); PG8_BAR; PG8_SCHED;
	s_add_i32 s61, 0, 0x18000
	s_add_i32 s62, 0, 0x1c000
	v_add_u32_e32 v140, s61, v182
	v_add_u32_e32 v172, s62, v182
	ds_read_b128 v[128:131], v140
	ds_read_b128 v[132:135], v140 offset:1024
	ds_read_b128 v[136:139], v140 offset:2048
	ds_read_b128 v[140:143], v140 offset:3072
	ds_read_b128 v[144:147], v172
	ds_read_b128 v[148:151], v172 offset:1024
	ds_read_b128 v[152:155], v172 offset:2048
	ds_read_b128 v[172:175], v172 offset:3072
	s_add_u32 s46, s46, 0x20000
	s_addc_u32 s47, s47, 0
	s_mov_b32 m0, s48
	v_lshl_add_u64 v[220:221], s[46:47], 0, v[156:157]
	ds_read_b128 v[176:179], v185 offset:32768
	ds_read_b128 v[186:189], v185 offset:33792
	ds_read_b128 v[190:193], v185 offset:34816
	ds_read_b128 v[194:197], v185 offset:35840
	ds_read_b128 v[198:201], v185 offset:36864
	ds_read_b128 v[202:205], v185 offset:37888
	ds_read_b128 v[206:209], v185 offset:38912
	ds_read_b128 v[210:213], v185 offset:39936
	global_load_lds_dwordx4 v[220:221], off
	v_lshl_add_u64 v[220:221], s[46:47], 0, v[160:161]
	s_mov_b32 m0, s49
	s_nop 0
	global_load_lds_dwordx4 v[220:221], off
	s_waitcnt vmcnt(8)
	s_waitcnt lgkmcnt(0)
	s_barrier
	v_mfma_f32_16x16x32_bf16 v[124:127], v[128:131], v[176:179], v[124:127]
	v_mfma_f32_16x16x32_bf16 v[120:123], v[136:139], v[176:179], v[120:123]
	v_mfma_f32_16x16x32_bf16 v[108:111], v[128:131], v[190:193], v[108:111]
	v_mfma_f32_16x16x32_bf16 v[104:107], v[136:139], v[190:193], v[104:107]
	v_mfma_f32_16x16x32_bf16 v[92:95], v[128:131], v[198:201], v[92:95]
	v_mfma_f32_16x16x32_bf16 v[88:91], v[136:139], v[198:201], v[88:91]
	v_mfma_f32_16x16x32_bf16 v[76:79], v[128:131], v[206:209], v[76:79]
	v_mfma_f32_16x16x32_bf16 v[72:75], v[136:139], v[206:209], v[72:75]
	v_mfma_f32_16x16x32_bf16 v[124:127], v[132:135], v[186:189], v[124:127]
	v_mfma_f32_16x16x32_bf16 v[120:123], v[140:143], v[186:189], v[120:123]
	v_mfma_f32_16x16x32_bf16 v[108:111], v[132:135], v[194:197], v[108:111]
	v_mfma_f32_16x16x32_bf16 v[104:107], v[140:143], v[194:197], v[104:107]
	v_mfma_f32_16x16x32_bf16 v[92:95], v[132:135], v[202:205], v[92:95]
	v_mfma_f32_16x16x32_bf16 v[88:91], v[140:143], v[202:205], v[88:91]
	v_mfma_f32_16x16x32_bf16 v[76:79], v[132:135], v[210:213], v[76:79]
	v_mfma_f32_16x16x32_bf16 v[72:75], v[140:143], v[210:213], v[72:75]
	v_mfma_f32_16x16x32_bf16 v[116:119], v[144:147], v[176:179], v[116:119]
	v_mfma_f32_16x16x32_bf16 v[112:115], v[152:155], v[176:179], v[112:115]
	v_mfma_f32_16x16x32_bf16 v[100:103], v[144:147], v[190:193], v[100:103]
	v_mfma_f32_16x16x32_bf16 v[96:99], v[152:155], v[190:193], v[96:99]
	v_mfma_f32_16x16x32_bf16 v[84:87], v[144:147], v[198:201], v[84:87]
	v_mfma_f32_16x16x32_bf16 v[80:83], v[152:155], v[198:201], v[80:83]
	v_mfma_f32_16x16x32_bf16 v[68:71], v[144:147], v[206:209], v[68:71]
	v_mfma_f32_16x16x32_bf16 v[64:67], v[152:155], v[206:209], v[64:67]
	v_mfma_f32_16x16x32_bf16 v[116:119], v[148:151], v[186:189], v[116:119]
	v_mfma_f32_16x16x32_bf16 v[112:115], v[172:175], v[186:189], v[112:115]
	v_mfma_f32_16x16x32_bf16 v[100:103], v[148:151], v[194:197], v[100:103]
	v_mfma_f32_16x16x32_bf16 v[96:99], v[172:175], v[194:197], v[96:99]
	v_mfma_f32_16x16x32_bf16 v[84:87], v[148:151], v[202:205], v[84:87]
	v_mfma_f32_16x16x32_bf16 v[80:83], v[172:175], v[202:205], v[80:83]
	v_mfma_f32_16x16x32_bf16 v[68:71], v[148:151], v[210:213], v[68:71]
	v_mfma_f32_16x16x32_bf16 v[64:67], v[172:175], v[210:213], v[64:67]
	s_barrier
	s_add_i32 s46, s61, s94
	v_lshl_add_u64 v[180:181], v[180:181], 0, s[26:27]
	s_mov_b32 m0, s46
	ds_read_b128 v[176:179], v185 offset:49152
	ds_read_b128 v[186:189], v185 offset:50176
	ds_read_b128 v[190:193], v185 offset:51200
	ds_read_b128 v[194:197], v185 offset:52224
	ds_read_b128 v[198:201], v185 offset:53248
	ds_read_b128 v[202:205], v185 offset:54272
	ds_read_b128 v[206:209], v185 offset:55296
	ds_read_b128 v[210:213], v185 offset:56320
	global_load_lds_dwordx4 v[180:181], off
	s_add_i32 m0, s46, 0x2000
	s_add_u32 s44, s44, 0x20080
	v_lshl_add_u64 v[180:181], v[214:215], 0, s[26:27]
	s_addc_u32 s45, s45, 0
	s_add_i32 s46, s62, s94
	global_load_lds_dwordx4 v[180:181], off
	v_lshl_add_u64 v[180:181], s[44:45], 0, v[158:159]
	s_mov_b32 m0, s46
	s_nop 0
	global_load_lds_dwordx4 v[180:181], off
	v_lshl_add_u64 v[180:181], s[44:45], 0, v[162:163]
	s_add_i32 m0, s46, 0x2000
	s_nop 0
	global_load_lds_dwordx4 v[180:181], off
	v_lshl_add_u64 v[180:181], v[216:217], 0, s[26:27]
	s_mov_b32 m0, s51
	s_nop 0
	global_load_lds_dwordx4 v[180:181], off
	v_lshl_add_u64 v[180:181], v[218:219], 0, s[26:27]
	s_mov_b32 m0, s52
	s_nop 0
	global_load_lds_dwordx4 v[180:181], off
	s_waitcnt vmcnt(8)
	s_waitcnt lgkmcnt(0)
	s_barrier
	v_mfma_f32_16x16x32_bf16 v[60:63], v[128:131], v[176:179], v[60:63]
	v_mfma_f32_16x16x32_bf16 v[56:59], v[136:139], v[176:179], v[56:59]
	v_mfma_f32_16x16x32_bf16 v[44:47], v[128:131], v[190:193], v[44:47]
	v_mfma_f32_16x16x32_bf16 v[40:43], v[136:139], v[190:193], v[40:43]
	v_mfma_f32_16x16x32_bf16 v[28:31], v[128:131], v[198:201], v[28:31]
	v_mfma_f32_16x16x32_bf16 v[24:27], v[136:139], v[198:201], v[24:27]
	v_mfma_f32_16x16x32_bf16 v[12:15], v[128:131], v[206:209], v[12:15]
	v_mfma_f32_16x16x32_bf16 v[8:11], v[136:139], v[206:209], v[8:11]
	v_mfma_f32_16x16x32_bf16 v[60:63], v[132:135], v[186:189], v[60:63]
	v_mfma_f32_16x16x32_bf16 v[56:59], v[140:143], v[186:189], v[56:59]
	v_mfma_f32_16x16x32_bf16 v[44:47], v[132:135], v[194:197], v[44:47]
	v_mfma_f32_16x16x32_bf16 v[40:43], v[140:143], v[194:197], v[40:43]
	v_mfma_f32_16x16x32_bf16 v[28:31], v[132:135], v[202:205], v[28:31]
	v_mfma_f32_16x16x32_bf16 v[24:27], v[140:143], v[202:205], v[24:27]
	v_mfma_f32_16x16x32_bf16 v[12:15], v[132:135], v[210:213], v[12:15]
	v_mfma_f32_16x16x32_bf16 v[8:11], v[140:143], v[210:213], v[8:11]
	v_mfma_f32_16x16x32_bf16 v[52:55], v[144:147], v[176:179], v[52:55]
	v_mfma_f32_16x16x32_bf16 v[48:51], v[152:155], v[176:179], v[48:51]
	v_mfma_f32_16x16x32_bf16 v[36:39], v[144:147], v[190:193], v[36:39]
	v_mfma_f32_16x16x32_bf16 v[32:35], v[152:155], v[190:193], v[32:35]
	v_mfma_f32_16x16x32_bf16 v[20:23], v[144:147], v[198:201], v[20:23]
	v_mfma_f32_16x16x32_bf16 v[16:19], v[152:155], v[198:201], v[16:19]
	v_mfma_f32_16x16x32_bf16 v[4:7], v[144:147], v[206:209], v[4:7]
	v_mfma_f32_16x16x32_bf16 v[0:3], v[152:155], v[206:209], v[0:3]
	v_mfma_f32_16x16x32_bf16 v[52:55], v[148:151], v[186:189], v[52:55]
	v_mfma_f32_16x16x32_bf16 v[48:51], v[172:175], v[186:189], v[48:51]
	v_mfma_f32_16x16x32_bf16 v[36:39], v[148:151], v[194:197], v[36:39]
	v_mfma_f32_16x16x32_bf16 v[32:35], v[172:175], v[194:197], v[32:35]
	v_mfma_f32_16x16x32_bf16 v[20:23], v[148:151], v[202:205], v[20:23]
	v_mfma_f32_16x16x32_bf16 v[16:19], v[172:175], v[202:205], v[16:19]
	v_mfma_f32_16x16x32_bf16 v[4:7], v[148:151], v[210:213], v[4:7]
	v_mfma_f32_16x16x32_bf16 v[0:3], v[172:175], v[210:213], v[0:3]
	s_barrier
	s_add_i32 s60, s60, 2
	s_add_u32 s42, s42, 0x100
	s_addc_u32 s43, s43, 0
	s_add_u32 s58, s58, 0x100
	s_addc_u32 s59, s59, 0
	s_cmp_gt_u32 s60, 5
	s_cbranch_scc0 .LBB0_1170

; #define PG8_STAGE(bufoff, gbase, voff) do { _Pragma("unroll") for (int _i = 0; _i < 2; ++_i) \
;         __builtin_amdgcn_global_load_lds((const unsigned*)((const char*)(gbase) + (voff)[_i]), (LAS unsigned*)(lds + (bufoff) + ldsw + _i * 8192), 16, 0, 0); } while (0)
; #define PG8_LDA(dst, b, h) do { _Pragma("unroll") for (int m = 0; m < 4; ++m) _Pragma("unroll") for (int k = 0; k < 2; ++k) dst[m][k] = *(const LAS bf16x8*)(lds + PG8_SA(b, h) + aoff + m * 2048 + k * 1024); } while (0)
; #define PG8_LDB(dst, b, h) do { _Pragma("unroll") for (int n = 0; n < 2; ++n) _Pragma("unroll") for (int k = 0; k < 2; ++k) dst[n][k] = *(const LAS bf16x8*)(lds + PG8_SB(b, h) + boff + n * 2048 + k * 1024); } while (0)
; #define PG8_MMA(ai, bj, At, Bt) do { __builtin_amdgcn_s_setprio(1); _Pragma("unroll") for (int m = 0; m < 4; ++m) _Pragma("unroll") for (int n = 0; n < 2; ++n) _Pragma("unroll") for (int k = 0; k < 2; ++k) \
;         acc[ai][bj][m][n] = __builtin_amdgcn_mfma_f32_16x16x32_bf16(Bt[n][k], At[m][k], acc[ai][bj][m][n], 0, 0, 0); __builtin_amdgcn_s_setprio(0); } while (0)
; template <class Epi>
; DI void gemm_phase(LAS unsigned char* lds, const int wid, const Gemm g, const Order& S, const Epi& E) {
;     ...
;         const bool has_next = S.next(ui + 1, nxt);
;         const char* nA = has_next ? (const char*)(g.A + (size_t)nxt.g * g.gsA + (size_t)nxt.pm * BM * g.lda) : cA;
;         const char* nB = has_next ? (const char*)(g.Bt + (size_t)nxt.g * g.gsB + (size_t)nxt.pn * BM * g.ldb) : cB;
;         for (int t = 0; t < nt; t += 2) {
;             const bool last = (t == nt - 2);
;             const char* a1 = cA + (size_t)(t + 1) * kstep;
;             const char* a2 = last ? nA : cA + (size_t)(t + 2) * kstep; const char* b2 = last ? nB : cB + (size_t)(t + 2) * kstep;
;             const char* a3 = a2 + kstep; const char* b3 = b2 + kstep;
;             PG8_LDB(B0, 0, 0); PG8_LDB(B1, 0, 1); PG8_SCHED; PG8_LDA(At, 0, 0); PG8_STAGE(PG8_SA(1, 1), a1 + hstepA, voffA);
;             PG8_WAIT_V(8); PG8_WAIT_L(0); PG8_BAR; PG8_MMA(0, 0, At, B0); PG8_MMA(0, 1, At, B1); PG8_BAR; PG8_SCHED;
;             PG8_LDA(At, 0, 1); PG8_STAGE(PG8_SB(0, 0), b2, voffB); PG8_STAGE(PG8_SB(0, 1), b2 + hstepB, voffB); PG8_STAGE(PG8_SA(0, 0), a2, voffA);
;             PG8_WAIT_V(8); PG8_WAIT_L(0); PG8_BAR; PG8_MMA(1, 0, At, B0); PG8_MMA(1, 1, At, B1); PG8_BAR; PG8_SCHED;
.LBB0_1249:
	s_ashr_i32 s37, s36, 31
	s_lshl_b64 s[40:41], s[36:37], 19
	s_add_u32 s40, s6, s40
	s_addc_u32 s41, s7, s41
	s_and_b64 s[42:43], s[8:9], exec
	s_cselect_b32 s11, s41, s47
	s_cselect_b32 s37, s40, s46
	s_ashr_i32 s39, s38, 31
	s_lshl_b64 s[42:43], s[38:39], 19
	s_add_u32 s42, s21, s42
	s_addc_u32 s43, s24, s43
	s_and_b64 s[50:51], s[8:9], exec
	s_cselect_b32 s39, s43, s49
	s_cselect_b32 s59, s42, s48
	s_add_u32 s46, s46, 0x40080
	s_addc_u32 s47, s47, 0
	s_add_u32 s60, s48, 0x100
	v_mov_b32_e32 v0, 0
	s_addc_u32 s61, s49, 0
	s_mov_b32 s62, -2
	s_waitcnt lgkmcnt(0)
	ds_read_b128 v[128:131], v209
	ds_read_b128 v[132:135], v209 offset:1024
	ds_read_b128 v[136:139], v209 offset:2048
	ds_read_b128 v[140:143], v209 offset:3072
	ds_read_b128 v[144:147], v210
	ds_read_b128 v[148:151], v210 offset:1024
	ds_read_b128 v[152:155], v210 offset:2048
	ds_read_b128 v[156:159], v210 offset:3072
	s_add_u32 s48, s46, 0xfffc0080
	s_addc_u32 s49, s47, -1
	s_cmp_eq_u32 s62, 12
	s_cselect_b32 s51, s11, s49
	s_cselect_b32 s50, s37, s48
	s_cselect_b32 s49, s39, s61
	s_cselect_b32 s48, s59, s60
	v_lshl_add_u64 v[214:215], s[46:47], 0, v[184:185]
	s_add_i32 m0, s25, 0xc000
	ds_read_b128 v[160:163], v211
	ds_read_b128 v[164:167], v211 offset:1024
	ds_read_b128 v[168:171], v211 offset:2048
	ds_read_b128 v[172:175], v211 offset:3072
	ds_read_b128 v[192:195], v211 offset:4096
	ds_read_b128 v[196:199], v211 offset:5120
	ds_read_b128 v[200:203], v211 offset:6144
	ds_read_b128 v[204:207], v211 offset:7168
	global_load_lds_dwordx4 v[214:215], off
	v_lshl_add_u64 v[214:215], s[46:47], 0, v[186:187]
	s_add_i32 m0, s25, 0xe000
	s_nop 0
	global_load_lds_dwordx4 v[214:215], off
	s_waitcnt vmcnt(8)
	s_waitcnt lgkmcnt(0)
	s_barrier
	v_mfma_f32_16x16x32_bf16 v[124:127], v[128:131], v[160:163], 0
	v_mfma_f32_16x16x32_bf16 v[120:123], v[136:139], v[160:163], 0
	v_mfma_f32_16x16x32_bf16 v[108:111], v[128:131], v[168:171], 0
	v_mfma_f32_16x16x32_bf16 v[104:107], v[136:139], v[168:171], 0
	v_mfma_f32_16x16x32_bf16 v[92:95], v[128:131], v[192:195], 0
	v_mfma_f32_16x16x32_bf16 v[88:91], v[136:139], v[192:195], 0
	v_mfma_f32_16x16x32_bf16 v[76:79], v[128:131], v[200:203], 0
	v_mfma_f32_16x16x32_bf16 v[72:75], v[136:139], v[200:203], 0
	v_mfma_f32_16x16x32_bf16 v[124:127], v[132:135], v[164:167], v[124:127]
	v_mfma_f32_16x16x32_bf16 v[120:123], v[140:143], v[164:167], v[120:123]
	v_mfma_f32_16x16x32_bf16 v[108:111], v[132:135], v[172:175], v[108:111]
	v_mfma_f32_16x16x32_bf16 v[104:107], v[140:143], v[172:175], v[104:107]
	v_mfma_f32_16x16x32_bf16 v[92:95], v[132:135], v[196:199], v[92:95]
	v_mfma_f32_16x16x32_bf16 v[88:91], v[140:143], v[196:199], v[88:91]
	v_mfma_f32_16x16x32_bf16 v[76:79], v[132:135], v[204:207], v[76:79]
	v_mfma_f32_16x16x32_bf16 v[72:75], v[140:143], v[204:207], v[72:75]
	v_mfma_f32_16x16x32_bf16 v[116:119], v[144:147], v[160:163], 0
	v_mfma_f32_16x16x32_bf16 v[112:115], v[152:155], v[160:163], 0
	v_mfma_f32_16x16x32_bf16 v[100:103], v[144:147], v[168:171], 0
	v_mfma_f32_16x16x32_bf16 v[96:99], v[152:155], v[168:171], 0
	v_mfma_f32_16x16x32_bf16 v[84:87], v[144:147], v[192:195], 0
	v_mfma_f32_16x16x32_bf16 v[80:83], v[152:155], v[192:195], 0
	v_mfma_f32_16x16x32_bf16 v[68:71], v[144:147], v[200:203], 0
	v_mfma_f32_16x16x32_bf16 v[64:67], v[152:155], v[200:203], 0
	v_mfma_f32_16x16x32_bf16 v[116:119], v[148:151], v[164:167], v[116:119]
	v_mfma_f32_16x16x32_bf16 v[112:115], v[156:159], v[164:167], v[112:115]
	v_mfma_f32_16x16x32_bf16 v[100:103], v[148:151], v[172:175], v[100:103]
	v_mfma_f32_16x16x32_bf16 v[96:99], v[156:159], v[172:175], v[96:99]
	v_mfma_f32_16x16x32_bf16 v[84:87], v[148:151], v[196:199], v[84:87]
	v_mfma_f32_16x16x32_bf16 v[80:83], v[156:159], v[196:199], v[80:83]
	v_mfma_f32_16x16x32_bf16 v[68:71], v[148:151], v[204:207], v[68:71]
	v_mfma_f32_16x16x32_bf16 v[64:67], v[156:159], v[204:207], v[64:67]
	s_barrier
	s_add_i32 s63, s57, s94
	v_lshl_add_u64 v[214:215], s[48:49], 0, v[178:179]
	s_mov_b32 m0, s63
	ds_read_b128 v[160:163], v211 offset:16384
	ds_read_b128 v[164:167], v211 offset:17408
	ds_read_b128 v[168:171], v211 offset:18432
	ds_read_b128 v[172:175], v211 offset:19456
	ds_read_b128 v[192:195], v211 offset:20480
	ds_read_b128 v[196:199], v211 offset:21504
	ds_read_b128 v[200:203], v211 offset:22528
	ds_read_b128 v[204:207], v211 offset:23552
	global_load_lds_dwordx4 v[214:215], off
	s_add_i32 m0, s63, 0x2000
	s_add_u32 s66, s48, 0x40000
	v_lshl_add_u64 v[216:217], s[48:49], 0, v[182:183]
	s_addc_u32 s67, s49, 0
	s_add_i32 s63, s58, s94
	global_load_lds_dwordx4 v[216:217], off
	v_lshl_add_u64 v[218:219], s[66:67], 0, v[178:179]
	s_mov_b32 m0, s63
	v_lshl_add_u64 v[220:221], s[50:51], 0, v[180:181]
	global_load_lds_dwordx4 v[218:219], off
	v_lshl_add_u64 v[218:219], s[66:67], 0, v[182:183]
	s_add_i32 m0, s63, 0x2000
	s_nop 0
	global_load_lds_dwordx4 v[218:219], off
	v_lshl_add_u64 v[218:219], s[50:51], 0, v[176:177]
	s_mov_b32 m0, s25
	s_nop 0
	global_load_lds_dwordx4 v[218:219], off
	s_mov_b32 m0, s45
	s_nop 0
	global_load_lds_dwordx4 v[220:221], off
	s_waitcnt vmcnt(8)
	s_waitcnt lgkmcnt(0)
	s_barrier
; #define PG8_STAGE(bufoff, gbase, voff) do { _Pragma("unroll") for (int _i = 0; _i < 2; ++_i) \
;         __builtin_amdgcn_global_load_lds((const unsigned*)((const char*)(gbase) + (voff)[_i]), (LAS unsigned*)(lds + (bufoff) + ldsw + _i * 8192), 16, 0, 0); } while (0)
; #define PG8_LDA(dst, b, h) do { _Pragma("unroll") for (int m = 0; m < 4; ++m) _Pragma("unroll") for (int k = 0; k < 2; ++k) dst[m][k] = *(const LAS bf16x8*)(lds + PG8_SA(b, h) + aoff + m * 2048 + k * 1024); } while (0)
; #define PG8_LDB(dst, b, h) do { _Pragma("unroll") for (int n = 0; n < 2; ++n) _Pragma("unroll") for (int k = 0; k < 2; ++k) dst[n][k] = *(const LAS bf16x8*)(lds + PG8_SB(b, h) + boff + n * 2048 + k * 1024); } while (0)
; #define PG8_MMA(ai, bj, At, Bt) do { __builtin_amdgcn_s_setprio(1); _Pragma("unroll") for (int m = 0; m < 4; ++m) _Pragma("unroll") for (int n = 0; n < 2; ++n) _Pragma("unroll") for (int k = 0; k < 2; ++k) \
;         acc[ai][bj][m][n] = __builtin_amdgcn_mfma_f32_16x16x32_bf16(Bt[n][k], At[m][k], acc[ai][bj][m][n], 0, 0, 0); __builtin_amdgcn_s_setprio(0); } while (0)
; #define PG8_WAIT_V(n) asm volatile("s_waitcnt vmcnt(" #n ")" ::: "memory")
; #define PG8_WAIT_L(n) asm volatile("s_waitcnt lgkmcnt(" #n ")" ::: "memory")
; template <class Epi>
; DI void gemm_phase(LAS unsigned char* lds, const int wid, const Gemm g, const Order& S, const Epi& E) {
;     ...
;             PG8_LDB(B0, 0, 0); PG8_LDB(B1, 0, 1); PG8_SCHED; PG8_LDA(At, 0, 0); PG8_STAGE(PG8_SA(1, 1), a1 + hstepA, voffA);
;             PG8_WAIT_V(8); PG8_WAIT_L(0); PG8_BAR; PG8_MMA(0, 0, At, B0); PG8_MMA(0, 1, At, B1); PG8_BAR; PG8_SCHED;
;             PG8_LDA(At, 0, 1); PG8_STAGE(PG8_SB(0, 0), b2, voffB); PG8_STAGE(PG8_SB(0, 1), b2 + hstepB, voffB); PG8_STAGE(PG8_SA(0, 0), a2, voffA);
;             PG8_WAIT_V(8); PG8_WAIT_L(0); PG8_BAR; PG8_MMA(1, 0, At, B0); PG8_MMA(1, 1, At, B1); PG8_BAR; PG8_SCHED;
;             PG8_LDB(B0, 1, 0); PG8_LDB(B1, 1, 1); PG8_SCHED; PG8_LDA(At, 1, 0); PG8_STAGE(PG8_SA(0, 1), a2 + hstepA, voffA);
;             PG8_WAIT_V(8); PG8_WAIT_L(0); PG8_BAR; PG8_MMA(0, 0, At, B0); PG8_MMA(0, 1, At, B1); PG8_BAR; PG8_SCHED;
;             PG8_LDA(At, 1, 1); PG8_STAGE(PG8_SB(1, 0), b3, voffB); PG8_STAGE(PG8_SB(1, 1), b3 + hstepB, voffB); PG8_STAGE(PG8_SA(1, 0), a3, voffA);
;             PG8_WAIT_V(8); PG8_WAIT_L(0); PG8_BAR; PG8_MMA(1, 0, At, B0); PG8_MMA(1, 1, At, B1); PG8_BAR; PG8_SCHED;
	v_mfma_f32_16x16x32_bf16 v[60:63], v[128:131], v[160:163], 0
	v_mfma_f32_16x16x32_bf16 v[56:59], v[136:139], v[160:163], 0
	v_mfma_f32_16x16x32_bf16 v[44:47], v[128:131], v[168:171], 0
	v_mfma_f32_16x16x32_bf16 v[40:43], v[136:139], v[168:171], 0
	v_mfma_f32_16x16x32_bf16 v[28:31], v[128:131], v[192:195], 0
	v_mfma_f32_16x16x32_bf16 v[24:27], v[136:139], v[192:195], 0
	v_mfma_f32_16x16x32_bf16 v[12:15], v[128:131], v[200:203], 0
	v_mfma_f32_16x16x32_bf16 v[8:11], v[136:139], v[200:203], 0
	v_mfma_f32_16x16x32_bf16 v[60:63], v[132:135], v[164:167], v[60:63]
	v_mfma_f32_16x16x32_bf16 v[56:59], v[140:143], v[164:167], v[56:59]
	v_mfma_f32_16x16x32_bf16 v[44:47], v[132:135], v[172:175], v[44:47]
	v_mfma_f32_16x16x32_bf16 v[40:43], v[140:143], v[172:175], v[40:43]
	v_mfma_f32_16x16x32_bf16 v[28:31], v[132:135], v[196:199], v[28:31]
	v_mfma_f32_16x16x32_bf16 v[24:27], v[140:143], v[196:199], v[24:27]
	v_mfma_f32_16x16x32_bf16 v[12:15], v[132:135], v[204:207], v[12:15]
	v_mfma_f32_16x16x32_bf16 v[8:11], v[140:143], v[204:207], v[8:11]
	v_mfma_f32_16x16x32_bf16 v[52:55], v[144:147], v[160:163], 0
	v_mfma_f32_16x16x32_bf16 v[48:51], v[152:155], v[160:163], 0
	v_mfma_f32_16x16x32_bf16 v[36:39], v[144:147], v[168:171], 0
	v_mfma_f32_16x16x32_bf16 v[32:35], v[152:155], v[168:171], 0
	v_mfma_f32_16x16x32_bf16 v[20:23], v[144:147], v[192:195], 0
	v_mfma_f32_16x16x32_bf16 v[16:19], v[152:155], v[192:195], 0
	v_mfma_f32_16x16x32_bf16 v[4:7], v[144:147], v[200:203], 0
	v_mfma_f32_16x16x32_bf16 v[0:3], v[152:155], v[200:203], 0
	v_mfma_f32_16x16x32_bf16 v[52:55], v[148:151], v[164:167], v[52:55]
	v_mfma_f32_16x16x32_bf16 v[48:51], v[156:159], v[164:167], v[48:51]
	v_mfma_f32_16x16x32_bf16 v[36:39], v[148:151], v[172:175], v[36:39]
	v_mfma_f32_16x16x32_bf16 v[32:35], v[156:159], v[172:175], v[32:35]
	v_mfma_f32_16x16x32_bf16 v[20:23], v[148:151], v[196:199], v[20:23]
	v_mfma_f32_16x16x32_bf16 v[16:19], v[156:159], v[196:199], v[16:19]
	v_mfma_f32_16x16x32_bf16 v[4:7], v[148:151], v[204:207], v[4:7]
	v_mfma_f32_16x16x32_bf16 v[0:3], v[156:159], v[204:207], v[0:3]
	s_barrier
	s_add_i32 s63, 0, 0x18000
	s_add_i32 s65, 0, 0x1c000
	v_add_u32_e32 v140, s63, v208
	v_add_u32_e32 v156, s65, v208
	ds_read_b128 v[128:131], v140
	ds_read_b128 v[132:135], v140 offset:1024
	ds_read_b128 v[136:139], v140 offset:2048
	ds_read_b128 v[140:143], v140 offset:3072
	ds_read_b128 v[144:147], v156
	ds_read_b128 v[148:151], v156 offset:1024
	ds_read_b128 v[152:155], v156 offset:2048
	ds_read_b128 v[156:159], v156 offset:3072
	s_add_u32 s50, s50, 0x40000
	s_addc_u32 s51, s51, 0
	s_mov_b32 m0, s52
	v_lshl_add_u64 v[222:223], s[50:51], 0, v[176:177]
	ds_read_b128 v[160:163], v211 offset:32768
	ds_read_b128 v[164:167], v211 offset:33792
	ds_read_b128 v[168:171], v211 offset:34816
	ds_read_b128 v[172:175], v211 offset:35840
	ds_read_b128 v[192:195], v211 offset:36864
	ds_read_b128 v[196:199], v211 offset:37888
	ds_read_b128 v[200:203], v211 offset:38912
	ds_read_b128 v[204:207], v211 offset:39936
	global_load_lds_dwordx4 v[222:223], off
	v_lshl_add_u64 v[222:223], s[50:51], 0, v[180:181]
	s_mov_b32 m0, s53
	s_nop 0
	global_load_lds_dwordx4 v[222:223], off
	s_waitcnt vmcnt(8)
	s_waitcnt lgkmcnt(0)
	s_barrier
	v_mfma_f32_16x16x32_bf16 v[124:127], v[128:131], v[160:163], v[124:127]
	v_mfma_f32_16x16x32_bf16 v[120:123], v[136:139], v[160:163], v[120:123]
	v_mfma_f32_16x16x32_bf16 v[108:111], v[128:131], v[168:171], v[108:111]
	v_mfma_f32_16x16x32_bf16 v[104:107], v[136:139], v[168:171], v[104:107]
	v_mfma_f32_16x16x32_bf16 v[92:95], v[128:131], v[192:195], v[92:95]
	v_mfma_f32_16x16x32_bf16 v[88:91], v[136:139], v[192:195], v[88:91]
	v_mfma_f32_16x16x32_bf16 v[76:79], v[128:131], v[200:203], v[76:79]
	v_mfma_f32_16x16x32_bf16 v[72:75], v[136:139], v[200:203], v[72:75]
	v_mfma_f32_16x16x32_bf16 v[124:127], v[132:135], v[164:167], v[124:127]
	v_mfma_f32_16x16x32_bf16 v[120:123], v[140:143], v[164:167], v[120:123]
	v_mfma_f32_16x16x32_bf16 v[108:111], v[132:135], v[172:175], v[108:111]
	v_mfma_f32_16x16x32_bf16 v[104:107], v[140:143], v[172:175], v[104:107]
	v_mfma_f32_16x16x32_bf16 v[92:95], v[132:135], v[196:199], v[92:95]
	v_mfma_f32_16x16x32_bf16 v[88:91], v[140:143], v[196:199], v[88:91]
	v_mfma_f32_16x16x32_bf16 v[76:79], v[132:135], v[204:207], v[76:79]
	v_mfma_f32_16x16x32_bf16 v[72:75], v[140:143], v[204:207], v[72:75]
	v_mfma_f32_16x16x32_bf16 v[116:119], v[144:147], v[160:163], v[116:119]
	v_mfma_f32_16x16x32_bf16 v[112:115], v[152:155], v[160:163], v[112:115]
	v_mfma_f32_16x16x32_bf16 v[100:103], v[144:147], v[168:171], v[100:103]
	v_mfma_f32_16x16x32_bf16 v[96:99], v[152:155], v[168:171], v[96:99]
	v_mfma_f32_16x16x32_bf16 v[84:87], v[144:147], v[192:195], v[84:87]
	v_mfma_f32_16x16x32_bf16 v[80:83], v[152:155], v[192:195], v[80:83]
	v_mfma_f32_16x16x32_bf16 v[68:71], v[144:147], v[200:203], v[68:71]
	v_mfma_f32_16x16x32_bf16 v[64:67], v[152:155], v[200:203], v[64:67]
	v_mfma_f32_16x16x32_bf16 v[116:119], v[148:151], v[164:167], v[116:119]
	v_mfma_f32_16x16x32_bf16 v[112:115], v[156:159], v[164:167], v[112:115]
	v_mfma_f32_16x16x32_bf16 v[100:103], v[148:151], v[172:175], v[100:103]
	v_mfma_f32_16x16x32_bf16 v[96:99], v[156:159], v[172:175], v[96:99]
	v_mfma_f32_16x16x32_bf16 v[84:87], v[148:151], v[196:199], v[84:87]
	v_mfma_f32_16x16x32_bf16 v[80:83], v[156:159], v[196:199], v[80:83]
	v_mfma_f32_16x16x32_bf16 v[68:71], v[148:151], v[204:207], v[68:71]
	v_mfma_f32_16x16x32_bf16 v[64:67], v[156:159], v[204:207], v[64:67]
	s_barrier
; #define PG8_STAGE(bufoff, gbase, voff) do { _Pragma("unroll") for (int _i = 0; _i < 2; ++_i) \
;         __builtin_amdgcn_global_load_lds((const unsigned*)((const char*)(gbase) + (voff)[_i]), (LAS unsigned*)(lds + (bufoff) + ldsw + _i * 8192), 16, 0, 0); } while (0)
; #define PG8_LDA(dst, b, h) do { _Pragma("unroll") for (int m = 0; m < 4; ++m) _Pragma("unroll") for (int k = 0; k < 2; ++k) dst[m][k] = *(const LAS bf16x8*)(lds + PG8_SA(b, h) + aoff + m * 2048 + k * 1024); } while (0)
; #define PG8_LDB(dst, b, h) do { _Pragma("unroll") for (int n = 0; n < 2; ++n) _Pragma("unroll") for (int k = 0; k < 2; ++k) dst[n][k] = *(const LAS bf16x8*)(lds + PG8_SB(b, h) + boff + n * 2048 + k * 1024); } while (0)
; #define PG8_MMA(ai, bj, At, Bt) do { __builtin_amdgcn_s_setprio(1); _Pragma("unroll") for (int m = 0; m < 4; ++m) _Pragma("unroll") for (int n = 0; n < 2; ++n) _Pragma("unroll") for (int k = 0; k < 2; ++k) \
;         acc[ai][bj][m][n] = __builtin_amdgcn_mfma_f32_16x16x32_bf16(Bt[n][k], At[m][k], acc[ai][bj][m][n], 0, 0, 0); __builtin_amdgcn_s_setprio(0); } while (0)
; #define PG8_WAIT_V(n) asm volatile("s_waitcnt vmcnt(" #n ")" ::: "memory")
; #define PG8_WAIT_L(n) asm volatile("s_waitcnt lgkmcnt(" #n ")" ::: "memory")
; template <class Epi>
; DI void gemm_phase(LAS unsigned char* lds, const int wid, const Gemm g, const Order& S, const Epi& E) {
;     ...
;             PG8_LDB(B0, 0, 0); PG8_LDB(B1, 0, 1); PG8_SCHED; PG8_LDA(At, 0, 0); PG8_STAGE(PG8_SA(1, 1), a1 + hstepA, voffA);
;             PG8_WAIT_V(8); PG8_WAIT_L(0); PG8_BAR; PG8_MMA(0, 0, At, B0); PG8_MMA(0, 1, At, B1); PG8_BAR; PG8_SCHED;
;             PG8_LDA(At, 0, 1); PG8_STAGE(PG8_SB(0, 0), b2, voffB); PG8_STAGE(PG8_SB(0, 1), b2 + hstepB, voffB); PG8_STAGE(PG8_SA(0, 0), a2, voffA);
;             PG8_WAIT_V(8); PG8_WAIT_L(0); PG8_BAR; PG8_MMA(1, 0, At, B0); PG8_MMA(1, 1, At, B1); PG8_BAR; PG8_SCHED;
;             PG8_LDB(B0, 1, 0); PG8_LDB(B1, 1, 1); PG8_SCHED; PG8_LDA(At, 1, 0); PG8_STAGE(PG8_SA(0, 1), a2 + hstepA, voffA);
;             PG8_WAIT_V(8); PG8_WAIT_L(0); PG8_BAR; PG8_MMA(0, 0, At, B0); PG8_MMA(0, 1, At, B1); PG8_BAR; PG8_SCHED;
;             PG8_LDA(At, 1, 1); PG8_STAGE(PG8_SB(1, 0), b3, voffB); PG8_STAGE(PG8_SB(1, 1), b3 + hstepB, voffB); PG8_STAGE(PG8_SA(1, 0), a3, voffA);
;             PG8_WAIT_V(8); PG8_WAIT_L(0); PG8_BAR; PG8_MMA(1, 0, At, B0); PG8_MMA(1, 1, At, B1); PG8_BAR; PG8_SCHED;
	s_add_i32 s50, s63, s94
	v_lshl_add_u64 v[214:215], v[214:215], 0, s[30:31]
	s_mov_b32 m0, s50
	ds_read_b128 v[160:163], v211 offset:49152
	ds_read_b128 v[164:167], v211 offset:50176
	ds_read_b128 v[168:171], v211 offset:51200
	ds_read_b128 v[172:175], v211 offset:52224
	ds_read_b128 v[192:195], v211 offset:53248
	ds_read_b128 v[196:199], v211 offset:54272
	ds_read_b128 v[200:203], v211 offset:55296
	ds_read_b128 v[204:207], v211 offset:56320
	global_load_lds_dwordx4 v[214:215], off
	s_add_i32 m0, s50, 0x2000
	s_add_u32 s48, s48, 0x40080
	v_lshl_add_u64 v[214:215], v[216:217], 0, s[30:31]
	s_addc_u32 s49, s49, 0
	s_add_i32 s50, s65, s94
	global_load_lds_dwordx4 v[214:215], off
	v_lshl_add_u64 v[214:215], s[48:49], 0, v[178:179]
	s_mov_b32 m0, s50
	s_nop 0
	global_load_lds_dwordx4 v[214:215], off
	v_lshl_add_u64 v[214:215], s[48:49], 0, v[182:183]
	s_add_i32 m0, s50, 0x2000
	s_nop 0
	global_load_lds_dwordx4 v[214:215], off
	v_lshl_add_u64 v[214:215], v[218:219], 0, s[30:31]
	s_mov_b32 m0, s55
	s_nop 0
	global_load_lds_dwordx4 v[214:215], off
	v_lshl_add_u64 v[214:215], v[220:221], 0, s[30:31]
	s_mov_b32 m0, s56
	s_nop 0
	global_load_lds_dwordx4 v[214:215], off
	s_waitcnt vmcnt(8)
	s_waitcnt lgkmcnt(0)
	s_barrier
	v_mfma_f32_16x16x32_bf16 v[60:63], v[128:131], v[160:163], v[60:63]
	v_mfma_f32_16x16x32_bf16 v[56:59], v[136:139], v[160:163], v[56:59]
	v_mfma_f32_16x16x32_bf16 v[44:47], v[128:131], v[168:171], v[44:47]
	v_mfma_f32_16x16x32_bf16 v[40:43], v[136:139], v[168:171], v[40:43]
	v_mfma_f32_16x16x32_bf16 v[28:31], v[128:131], v[192:195], v[28:31]
	v_mfma_f32_16x16x32_bf16 v[24:27], v[136:139], v[192:195], v[24:27]
	v_mfma_f32_16x16x32_bf16 v[12:15], v[128:131], v[200:203], v[12:15]
	v_mfma_f32_16x16x32_bf16 v[8:11], v[136:139], v[200:203], v[8:11]
	v_mfma_f32_16x16x32_bf16 v[60:63], v[132:135], v[164:167], v[60:63]
	v_mfma_f32_16x16x32_bf16 v[56:59], v[140:143], v[164:167], v[56:59]
	v_mfma_f32_16x16x32_bf16 v[44:47], v[132:135], v[172:175], v[44:47]
	v_mfma_f32_16x16x32_bf16 v[40:43], v[140:143], v[172:175], v[40:43]
	v_mfma_f32_16x16x32_bf16 v[28:31], v[132:135], v[196:199], v[28:31]
	v_mfma_f32_16x16x32_bf16 v[24:27], v[140:143], v[196:199], v[24:27]
	v_mfma_f32_16x16x32_bf16 v[12:15], v[132:135], v[204:207], v[12:15]
	v_mfma_f32_16x16x32_bf16 v[8:11], v[140:143], v[204:207], v[8:11]
	v_mfma_f32_16x16x32_bf16 v[52:55], v[144:147], v[160:163], v[52:55]
	v_mfma_f32_16x16x32_bf16 v[48:51], v[152:155], v[160:163], v[48:51]
	v_mfma_f32_16x16x32_bf16 v[36:39], v[144:147], v[168:171], v[36:39]
	v_mfma_f32_16x16x32_bf16 v[32:35], v[152:155], v[168:171], v[32:35]
	v_mfma_f32_16x16x32_bf16 v[20:23], v[144:147], v[192:195], v[20:23]
	v_mfma_f32_16x16x32_bf16 v[16:19], v[152:155], v[192:195], v[16:19]
	v_mfma_f32_16x16x32_bf16 v[4:7], v[144:147], v[200:203], v[4:7]
	v_mfma_f32_16x16x32_bf16 v[0:3], v[152:155], v[200:203], v[0:3]
	v_mfma_f32_16x16x32_bf16 v[52:55], v[148:151], v[164:167], v[52:55]
	v_mfma_f32_16x16x32_bf16 v[48:51], v[156:159], v[164:167], v[48:51]
	v_mfma_f32_16x16x32_bf16 v[36:39], v[148:151], v[172:175], v[36:39]
	v_mfma_f32_16x16x32_bf16 v[32:35], v[156:159], v[172:175], v[32:35]
	v_mfma_f32_16x16x32_bf16 v[20:23], v[148:151], v[196:199], v[20:23]
	v_mfma_f32_16x16x32_bf16 v[16:19], v[156:159], v[196:199], v[16:19]
	v_mfma_f32_16x16x32_bf16 v[4:7], v[148:151], v[204:207], v[4:7]
	v_mfma_f32_16x16x32_bf16 v[0:3], v[156:159], v[204:207], v[0:3]
	s_barrier
	s_add_i32 s62, s62, 2
	s_add_u32 s46, s46, 0x100
	s_addc_u32 s47, s47, 0
	s_add_u32 s60, s60, 0x100
	s_addc_u32 s61, s61, 0
	s_cmp_gt_u32 s62, 13
	s_cbranch_scc0 .LBB0_1250
	s_branch .Lpeel_exit_8
.LBB0_1250:
	ds_read_b128 v[128:131], v209
	ds_read_b128 v[132:135], v209 offset:1024
	ds_read_b128 v[136:139], v209 offset:2048
	ds_read_b128 v[140:143], v209 offset:3072
	ds_read_b128 v[144:147], v210
	ds_read_b128 v[148:151], v210 offset:1024
	ds_read_b128 v[152:155], v210 offset:2048
	ds_read_b128 v[156:159], v210 offset:3072
	s_add_u32 s48, s46, 0xfffc0080
	s_addc_u32 s49, s47, -1
	s_cmp_eq_u32 s62, 12
	s_cselect_b32 s51, s11, s49
	s_cselect_b32 s50, s37, s48
	s_cselect_b32 s49, s39, s61
	s_cselect_b32 s48, s59, s60
	v_lshl_add_u64 v[214:215], s[46:47], 0, v[184:185]
	s_add_i32 m0, s25, 0xc000
	ds_read_b128 v[160:163], v211
	ds_read_b128 v[164:167], v211 offset:1024
	ds_read_b128 v[168:171], v211 offset:2048
	ds_read_b128 v[172:175], v211 offset:3072
	ds_read_b128 v[192:195], v211 offset:4096
	ds_read_b128 v[196:199], v211 offset:5120
	ds_read_b128 v[200:203], v211 offset:6144
	ds_read_b128 v[204:207], v211 offset:7168
	global_load_lds_dwordx4 v[214:215], off
	v_lshl_add_u64 v[214:215], s[46:47], 0, v[186:187]
	s_add_i32 m0, s25, 0xe000
	s_nop 0
	global_load_lds_dwordx4 v[214:215], off
	s_waitcnt vmcnt(8)
	s_waitcnt lgkmcnt(0)
	s_barrier
; #define PG8_STAGE(bufoff, gbase, voff) do { _Pragma("unroll") for (int _i = 0; _i < 2; ++_i) \
;         __builtin_amdgcn_global_load_lds((const unsigned*)((const char*)(gbase) + (voff)[_i]), (LAS unsigned*)(lds + (bufoff) + ldsw + _i * 8192), 16, 0, 0); } while (0)
; #define PG8_LDA(dst, b, h) do { _Pragma("unroll") for (int m = 0; m < 4; ++m) _Pragma("unroll") for (int k = 0; k < 2; ++k) dst[m][k] = *(const LAS bf16x8*)(lds + PG8_SA(b, h) + aoff + m * 2048 + k * 1024); } while (0)
; #define PG8_LDB(dst, b, h) do { _Pragma("unroll") for (int n = 0; n < 2; ++n) _Pragma("unroll") for (int k = 0; k < 2; ++k) dst[n][k] = *(const LAS bf16x8*)(lds + PG8_SB(b, h) + boff + n * 2048 + k * 1024); } while (0)
; #define PG8_MMA(ai, bj, At, Bt) do { __builtin_amdgcn_s_setprio(1); _Pragma("unroll") for (int m = 0; m < 4; ++m) _Pragma("unroll") for (int n = 0; n < 2; ++n) _Pragma("unroll") for (int k = 0; k < 2; ++k) \
;         acc[ai][bj][m][n] = __builtin_amdgcn_mfma_f32_16x16x32_bf16(Bt[n][k], At[m][k], acc[ai][bj][m][n], 0, 0, 0); __builtin_amdgcn_s_setprio(0); } while (0)
; #define PG8_WAIT_V(n) asm volatile("s_waitcnt vmcnt(" #n ")" ::: "memory")
; #define PG8_WAIT_L(n) asm volatile("s_waitcnt lgkmcnt(" #n ")" ::: "memory")
; #define PG8_BAR __builtin_amdgcn_s_barrier()
; #define PG8_SCHED __builtin_amdgcn_sched_barrier(0)
; template <class Epi>
; DI void gemm_phase(LAS unsigned char* lds, const int wid, const Gemm g, const Order& S, const Epi& E) {
;     ...
;             PG8_LDB(B0, 0, 0); PG8_LDB(B1, 0, 1); PG8_SCHED; PG8_LDA(At, 0, 0); PG8_STAGE(PG8_SA(1, 1), a1 + hstepA, voffA);
;             PG8_WAIT_V(8); PG8_WAIT_L(0); PG8_BAR; PG8_MMA(0, 0, At, B0); PG8_MMA(0, 1, At, B1); PG8_BAR; PG8_SCHED;
;             PG8_LDA(At, 0, 1); PG8_STAGE(PG8_SB(0, 0), b2, voffB); PG8_STAGE(PG8_SB(0, 1), b2 + hstepB, voffB); PG8_STAGE(PG8_SA(0, 0), a2, voffA);
;             PG8_WAIT_V(8); PG8_WAIT_L(0); PG8_BAR; PG8_MMA(1, 0, At, B0); PG8_MMA(1, 1, At, B1); PG8_BAR; PG8_SCHED;
;             PG8_LDB(B0, 1, 0); PG8_LDB(B1, 1, 1); PG8_SCHED; PG8_LDA(At, 1, 0); PG8_STAGE(PG8_SA(0, 1), a2 + hstepA, voffA);
;             PG8_WAIT_V(8); PG8_WAIT_L(0); PG8_BAR; PG8_MMA(0, 0, At, B0); PG8_MMA(0, 1, At, B1); PG8_BAR; PG8_SCHED;
	v_mfma_f32_16x16x32_bf16 v[124:127], v[128:131], v[160:163], v[124:127]
	v_mfma_f32_16x16x32_bf16 v[120:123], v[136:139], v[160:163], v[120:123]
	v_mfma_f32_16x16x32_bf16 v[108:111], v[128:131], v[168:171], v[108:111]
	v_mfma_f32_16x16x32_bf16 v[104:107], v[136:139], v[168:171], v[104:107]
	v_mfma_f32_16x16x32_bf16 v[92:95], v[128:131], v[192:195], v[92:95]
	v_mfma_f32_16x16x32_bf16 v[88:91], v[136:139], v[192:195], v[88:91]
	v_mfma_f32_16x16x32_bf16 v[76:79], v[128:131], v[200:203], v[76:79]
	v_mfma_f32_16x16x32_bf16 v[72:75], v[136:139], v[200:203], v[72:75]
	v_mfma_f32_16x16x32_bf16 v[124:127], v[132:135], v[164:167], v[124:127]
	v_mfma_f32_16x16x32_bf16 v[120:123], v[140:143], v[164:167], v[120:123]
	v_mfma_f32_16x16x32_bf16 v[108:111], v[132:135], v[172:175], v[108:111]
	v_mfma_f32_16x16x32_bf16 v[104:107], v[140:143], v[172:175], v[104:107]
	v_mfma_f32_16x16x32_bf16 v[92:95], v[132:135], v[196:199], v[92:95]
	v_mfma_f32_16x16x32_bf16 v[88:91], v[140:143], v[196:199], v[88:91]
	v_mfma_f32_16x16x32_bf16 v[76:79], v[132:135], v[204:207], v[76:79]
	v_mfma_f32_16x16x32_bf16 v[72:75], v[140:143], v[204:207], v[72:75]
	v_mfma_f32_16x16x32_bf16 v[116:119], v[144:147], v[160:163], v[116:119]
	v_mfma_f32_16x16x32_bf16 v[112:115], v[152:155], v[160:163], v[112:115]
	v_mfma_f32_16x16x32_bf16 v[100:103], v[144:147], v[168:171], v[100:103]
	v_mfma_f32_16x16x32_bf16 v[96:99], v[152:155], v[168:171], v[96:99]
	v_mfma_f32_16x16x32_bf16 v[84:87], v[144:147], v[192:195], v[84:87]
	v_mfma_f32_16x16x32_bf16 v[80:83], v[152:155], v[192:195], v[80:83]
	v_mfma_f32_16x16x32_bf16 v[68:71], v[144:147], v[200:203], v[68:71]
	v_mfma_f32_16x16x32_bf16 v[64:67], v[152:155], v[200:203], v[64:67]
	v_mfma_f32_16x16x32_bf16 v[116:119], v[148:151], v[164:167], v[116:119]
	v_mfma_f32_16x16x32_bf16 v[112:115], v[156:159], v[164:167], v[112:115]
	v_mfma_f32_16x16x32_bf16 v[100:103], v[148:151], v[172:175], v[100:103]
	v_mfma_f32_16x16x32_bf16 v[96:99], v[156:159], v[172:175], v[96:99]
	v_mfma_f32_16x16x32_bf16 v[84:87], v[148:151], v[196:199], v[84:87]
	v_mfma_f32_16x16x32_bf16 v[80:83], v[156:159], v[196:199], v[80:83]
	v_mfma_f32_16x16x32_bf16 v[68:71], v[148:151], v[204:207], v[68:71]
	v_mfma_f32_16x16x32_bf16 v[64:67], v[156:159], v[204:207], v[64:67]
	s_barrier
	s_add_i32 s63, s57, s94
	v_lshl_add_u64 v[214:215], s[48:49], 0, v[178:179]
	s_mov_b32 m0, s63
	ds_read_b128 v[160:163], v211 offset:16384
	ds_read_b128 v[164:167], v211 offset:17408
	ds_read_b128 v[168:171], v211 offset:18432
	ds_read_b128 v[172:175], v211 offset:19456
	ds_read_b128 v[192:195], v211 offset:20480
	ds_read_b128 v[196:199], v211 offset:21504
	ds_read_b128 v[200:203], v211 offset:22528
	ds_read_b128 v[204:207], v211 offset:23552
	global_load_lds_dwordx4 v[214:215], off
	s_add_i32 m0, s63, 0x2000
	s_add_u32 s66, s48, 0x40000
	v_lshl_add_u64 v[216:217], s[48:49], 0, v[182:183]
	s_addc_u32 s67, s49, 0
	s_add_i32 s63, s58, s94
	global_load_lds_dwordx4 v[216:217], off
	v_lshl_add_u64 v[218:219], s[66:67], 0, v[178:179]
	s_mov_b32 m0, s63
	v_lshl_add_u64 v[220:221], s[50:51], 0, v[180:181]
	global_load_lds_dwordx4 v[218:219], off
	v_lshl_add_u64 v[218:219], s[66:67], 0, v[182:183]
	s_add_i32 m0, s63, 0x2000
	s_nop 0
	global_load_lds_dwordx4 v[218:219], off
	v_lshl_add_u64 v[218:219], s[50:51], 0, v[176:177]
	s_mov_b32 m0, s25
	s_nop 0
	global_load_lds_dwordx4 v[218:219], off
	s_mov_b32 m0, s45
	s_nop 0
	global_load_lds_dwordx4 v[220:221], off
	s_waitcnt vmcnt(8)
	s_waitcnt lgkmcnt(0)
	s_barrier
	v_mfma_f32_16x16x32_bf16 v[60:63], v[128:131], v[160:163], v[60:63]
	v_mfma_f32_16x16x32_bf16 v[56:59], v[136:139], v[160:163], v[56:59]
	v_mfma_f32_16x16x32_bf16 v[44:47], v[128:131], v[168:171], v[44:47]
	v_mfma_f32_16x16x32_bf16 v[40:43], v[136:139], v[168:171], v[40:43]
	v_mfma_f32_16x16x32_bf16 v[28:31], v[128:131], v[192:195], v[28:31]
	v_mfma_f32_16x16x32_bf16 v[24:27], v[136:139], v[192:195], v[24:27]
	v_mfma_f32_16x16x32_bf16 v[12:15], v[128:131], v[200:203], v[12:15]
	v_mfma_f32_16x16x32_bf16 v[8:11], v[136:139], v[200:203], v[8:11]
	v_mfma_f32_16x16x32_bf16 v[60:63], v[132:135], v[164:167], v[60:63]
	v_mfma_f32_16x16x32_bf16 v[56:59], v[140:143], v[164:167], v[56:59]
	v_mfma_f32_16x16x32_bf16 v[44:47], v[132:135], v[172:175], v[44:47]
	v_mfma_f32_16x16x32_bf16 v[40:43], v[140:143], v[172:175], v[40:43]
	v_mfma_f32_16x16x32_bf16 v[28:31], v[132:135], v[196:199], v[28:31]
	v_mfma_f32_16x16x32_bf16 v[24:27], v[140:143], v[196:199], v[24:27]
	v_mfma_f32_16x16x32_bf16 v[12:15], v[132:135], v[204:207], v[12:15]
	v_mfma_f32_16x16x32_bf16 v[8:11], v[140:143], v[204:207], v[8:11]
	v_mfma_f32_16x16x32_bf16 v[52:55], v[144:147], v[160:163], v[52:55]
	v_mfma_f32_16x16x32_bf16 v[48:51], v[152:155], v[160:163], v[48:51]
	v_mfma_f32_16x16x32_bf16 v[36:39], v[144:147], v[168:171], v[36:39]
	v_mfma_f32_16x16x32_bf16 v[32:35], v[152:155], v[168:171], v[32:35]
	v_mfma_f32_16x16x32_bf16 v[20:23], v[144:147], v[192:195], v[20:23]
	v_mfma_f32_16x16x32_bf16 v[16:19], v[152:155], v[192:195], v[16:19]
	v_mfma_f32_16x16x32_bf16 v[4:7], v[144:147], v[200:203], v[4:7]
	v_mfma_f32_16x16x32_bf16 v[0:3], v[152:155], v[200:203], v[0:3]
	v_mfma_f32_16x16x32_bf16 v[52:55], v[148:151], v[164:167], v[52:55]
	v_mfma_f32_16x16x32_bf16 v[48:51], v[156:159], v[164:167], v[48:51]
	v_mfma_f32_16x16x32_bf16 v[36:39], v[148:151], v[172:175], v[36:39]
	v_mfma_f32_16x16x32_bf16 v[32:35], v[156:159], v[172:175], v[32:35]
	v_mfma_f32_16x16x32_bf16 v[20:23], v[148:151], v[196:199], v[20:23]
	v_mfma_f32_16x16x32_bf16 v[16:19], v[156:159], v[196:199], v[16:19]
	v_mfma_f32_16x16x32_bf16 v[4:7], v[148:151], v[204:207], v[4:7]
	v_mfma_f32_16x16x32_bf16 v[0:3], v[156:159], v[204:207], v[0:3]
	s_barrier
; #define PG8_STAGE(bufoff, gbase, voff) do { _Pragma("unroll") for (int _i = 0; _i < 2; ++_i) \
;         __builtin_amdgcn_global_load_lds((const unsigned*)((const char*)(gbase) + (voff)[_i]), (LAS unsigned*)(lds + (bufoff) + ldsw + _i * 8192), 16, 0, 0); } while (0)
; #define PG8_LDA(dst, b, h) do { _Pragma("unroll") for (int m = 0; m < 4; ++m) _Pragma("unroll") for (int k = 0; k < 2; ++k) dst[m][k] = *(const LAS bf16x8*)(lds + PG8_SA(b, h) + aoff + m * 2048 + k * 1024); } while (0)
; #define PG8_LDB(dst, b, h) do { _Pragma("unroll") for (int n = 0; n < 2; ++n) _Pragma("unroll") for (int k = 0; k < 2; ++k) dst[n][k] = *(const LAS bf16x8*)(lds + PG8_SB(b, h) + boff + n * 2048 + k * 1024); } while (0)
; #define PG8_MMA(ai, bj, At, Bt) do { __builtin_amdgcn_s_setprio(1); _Pragma("unroll") for (int m = 0; m < 4; ++m) _Pragma("unroll") for (int n = 0; n < 2; ++n) _Pragma("unroll") for (int k = 0; k < 2; ++k) \
;         acc[ai][bj][m][n] = __builtin_amdgcn_mfma_f32_16x16x32_bf16(Bt[n][k], At[m][k], acc[ai][bj][m][n], 0, 0, 0); __builtin_amdgcn_s_setprio(0); } while (0)
; #define PG8_WAIT_V(n) asm volatile("s_waitcnt vmcnt(" #n ")" ::: "memory")
; #define PG8_WAIT_L(n) asm volatile("s_waitcnt lgkmcnt(" #n ")" ::: "memory")
; #define PG8_BAR __builtin_amdgcn_s_barrier()
; #define PG8_SCHED __builtin_amdgcn_sched_barrier(0)
; template <class Epi>
; DI void gemm_phase(LAS unsigned char* lds, const int wid, const Gemm g, const Order& S, const Epi& E) {
;     ...
;             PG8_LDB(B0, 1, 0); PG8_LDB(B1, 1, 1); PG8_SCHED; PG8_LDA(At, 1, 0); PG8_STAGE(PG8_SA(0, 1), a2 + hstepA, voffA);
;             PG8_WAIT_V(8); PG8_WAIT_L(0); PG8_BAR; PG8_MMA(0, 0, At, B0); PG8_MMA(0, 1, At, B1); PG8_BAR; PG8_SCHED;
;             PG8_LDA(At, 1, 1); PG8_STAGE(PG8_SB(1, 0), b3, voffB); PG8_STAGE(PG8_SB(1, 1), b3 + hstepB, voffB); PG8_STAGE(PG8_SA(1, 0), a3, voffA);
;             PG8_WAIT_V(8); PG8_WAIT_L(0); PG8_BAR; PG8_MMA(1, 0, At, B0); PG8_MMA(1, 1, At, B1); PG8_BAR; PG8_SCHED;
	s_add_i32 s63, 0, 0x18000
	s_add_i32 s65, 0, 0x1c000
	v_add_u32_e32 v140, s63, v208
	v_add_u32_e32 v156, s65, v208
	ds_read_b128 v[128:131], v140
	ds_read_b128 v[132:135], v140 offset:1024
	ds_read_b128 v[136:139], v140 offset:2048
	ds_read_b128 v[140:143], v140 offset:3072
	ds_read_b128 v[144:147], v156
	ds_read_b128 v[148:151], v156 offset:1024
	ds_read_b128 v[152:155], v156 offset:2048
	ds_read_b128 v[156:159], v156 offset:3072
	s_add_u32 s50, s50, 0x40000
	s_addc_u32 s51, s51, 0
	s_mov_b32 m0, s52
	v_lshl_add_u64 v[222:223], s[50:51], 0, v[176:177]
	ds_read_b128 v[160:163], v211 offset:32768
	ds_read_b128 v[164:167], v211 offset:33792
	ds_read_b128 v[168:171], v211 offset:34816
	ds_read_b128 v[172:175], v211 offset:35840
	ds_read_b128 v[192:195], v211 offset:36864
	ds_read_b128 v[196:199], v211 offset:37888
	ds_read_b128 v[200:203], v211 offset:38912
	ds_read_b128 v[204:207], v211 offset:39936
	global_load_lds_dwordx4 v[222:223], off
	v_lshl_add_u64 v[222:223], s[50:51], 0, v[180:181]
	s_mov_b32 m0, s53
	s_nop 0
	global_load_lds_dwordx4 v[222:223], off
	s_waitcnt vmcnt(8)
	s_waitcnt lgkmcnt(0)
	s_barrier
	v_mfma_f32_16x16x32_bf16 v[124:127], v[128:131], v[160:163], v[124:127]
	v_mfma_f32_16x16x32_bf16 v[120:123], v[136:139], v[160:163], v[120:123]
	v_mfma_f32_16x16x32_bf16 v[108:111], v[128:131], v[168:171], v[108:111]
	v_mfma_f32_16x16x32_bf16 v[104:107], v[136:139], v[168:171], v[104:107]
	v_mfma_f32_16x16x32_bf16 v[92:95], v[128:131], v[192:195], v[92:95]
	v_mfma_f32_16x16x32_bf16 v[88:91], v[136:139], v[192:195], v[88:91]
	v_mfma_f32_16x16x32_bf16 v[76:79], v[128:131], v[200:203], v[76:79]
	v_mfma_f32_16x16x32_bf16 v[72:75], v[136:139], v[200:203], v[72:75]
	v_mfma_f32_16x16x32_bf16 v[124:127], v[132:135], v[164:167], v[124:127]
	v_mfma_f32_16x16x32_bf16 v[120:123], v[140:143], v[164:167], v[120:123]
	v_mfma_f32_16x16x32_bf16 v[108:111], v[132:135], v[172:175], v[108:111]
	v_mfma_f32_16x16x32_bf16 v[104:107], v[140:143], v[172:175], v[104:107]
	v_mfma_f32_16x16x32_bf16 v[92:95], v[132:135], v[196:199], v[92:95]
	v_mfma_f32_16x16x32_bf16 v[88:91], v[140:143], v[196:199], v[88:91]
	v_mfma_f32_16x16x32_bf16 v[76:79], v[132:135], v[204:207], v[76:79]
	v_mfma_f32_16x16x32_bf16 v[72:75], v[140:143], v[204:207], v[72:75]
	v_mfma_f32_16x16x32_bf16 v[116:119], v[144:147], v[160:163], v[116:119]
	v_mfma_f32_16x16x32_bf16 v[112:115], v[152:155], v[160:163], v[112:115]
	v_mfma_f32_16x16x32_bf16 v[100:103], v[144:147], v[168:171], v[100:103]
	v_mfma_f32_16x16x32_bf16 v[96:99], v[152:155], v[168:171], v[96:99]
	v_mfma_f32_16x16x32_bf16 v[84:87], v[144:147], v[192:195], v[84:87]
	v_mfma_f32_16x16x32_bf16 v[80:83], v[152:155], v[192:195], v[80:83]
	v_mfma_f32_16x16x32_bf16 v[68:71], v[144:147], v[200:203], v[68:71]
	v_mfma_f32_16x16x32_bf16 v[64:67], v[152:155], v[200:203], v[64:67]
	v_mfma_f32_16x16x32_bf16 v[116:119], v[148:151], v[164:167], v[116:119]
	v_mfma_f32_16x16x32_bf16 v[112:115], v[156:159], v[164:167], v[112:115]
	v_mfma_f32_16x16x32_bf16 v[100:103], v[148:151], v[172:175], v[100:103]
	v_mfma_f32_16x16x32_bf16 v[96:99], v[156:159], v[172:175], v[96:99]
	v_mfma_f32_16x16x32_bf16 v[84:87], v[148:151], v[196:199], v[84:87]
	v_mfma_f32_16x16x32_bf16 v[80:83], v[156:159], v[196:199], v[80:83]
	v_mfma_f32_16x16x32_bf16 v[68:71], v[148:151], v[204:207], v[68:71]
	v_mfma_f32_16x16x32_bf16 v[64:67], v[156:159], v[204:207], v[64:67]
	s_barrier
	s_add_i32 s50, s63, s94
	v_lshl_add_u64 v[214:215], v[214:215], 0, s[30:31]
	s_mov_b32 m0, s50
	ds_read_b128 v[160:163], v211 offset:49152
	ds_read_b128 v[164:167], v211 offset:50176
	ds_read_b128 v[168:171], v211 offset:51200
	ds_read_b128 v[172:175], v211 offset:52224
	ds_read_b128 v[192:195], v211 offset:53248
	ds_read_b128 v[196:199], v211 offset:54272
	ds_read_b128 v[200:203], v211 offset:55296
	ds_read_b128 v[204:207], v211 offset:56320
	global_load_lds_dwordx4 v[214:215], off
	s_add_i32 m0, s50, 0x2000
	s_add_u32 s48, s48, 0x40080
	v_lshl_add_u64 v[214:215], v[216:217], 0, s[30:31]
	s_addc_u32 s49, s49, 0
	s_add_i32 s50, s65, s94
	global_load_lds_dwordx4 v[214:215], off
	v_lshl_add_u64 v[214:215], s[48:49], 0, v[178:179]
	s_mov_b32 m0, s50
	s_nop 0
	global_load_lds_dwordx4 v[214:215], off
	v_lshl_add_u64 v[214:215], s[48:49], 0, v[182:183]
	s_add_i32 m0, s50, 0x2000
	s_nop 0
	global_load_lds_dwordx4 v[214:215], off
	v_lshl_add_u64 v[214:215], v[218:219], 0, s[30:31]
	s_mov_b32 m0, s55
	s_nop 0
	global_load_lds_dwordx4 v[214:215], off
	v_lshl_add_u64 v[214:215], v[220:221], 0, s[30:31]
	s_mov_b32 m0, s56
	s_nop 0
	global_load_lds_dwordx4 v[214:215], off
	s_waitcnt vmcnt(8)
	s_waitcnt lgkmcnt(0)
	s_barrier
	v_mfma_f32_16x16x32_bf16 v[60:63], v[128:131], v[160:163], v[60:63]
	v_mfma_f32_16x16x32_bf16 v[56:59], v[136:139], v[160:163], v[56:59]
	v_mfma_f32_16x16x32_bf16 v[44:47], v[128:131], v[168:171], v[44:47]
	v_mfma_f32_16x16x32_bf16 v[40:43], v[136:139], v[168:171], v[40:43]
	v_mfma_f32_16x16x32_bf16 v[28:31], v[128:131], v[192:195], v[28:31]
	v_mfma_f32_16x16x32_bf16 v[24:27], v[136:139], v[192:195], v[24:27]
	v_mfma_f32_16x16x32_bf16 v[12:15], v[128:131], v[200:203], v[12:15]
	v_mfma_f32_16x16x32_bf16 v[8:11], v[136:139], v[200:203], v[8:11]
	v_mfma_f32_16x16x32_bf16 v[60:63], v[132:135], v[164:167], v[60:63]
	v_mfma_f32_16x16x32_bf16 v[56:59], v[140:143], v[164:167], v[56:59]
	v_mfma_f32_16x16x32_bf16 v[44:47], v[132:135], v[172:175], v[44:47]
	v_mfma_f32_16x16x32_bf16 v[40:43], v[140:143], v[172:175], v[40:43]
	v_mfma_f32_16x16x32_bf16 v[28:31], v[132:135], v[196:199], v[28:31]
	v_mfma_f32_16x16x32_bf16 v[24:27], v[140:143], v[196:199], v[24:27]
	v_mfma_f32_16x16x32_bf16 v[12:15], v[132:135], v[204:207], v[12:15]
	v_mfma_f32_16x16x32_bf16 v[8:11], v[140:143], v[204:207], v[8:11]
	v_mfma_f32_16x16x32_bf16 v[52:55], v[144:147], v[160:163], v[52:55]
	v_mfma_f32_16x16x32_bf16 v[48:51], v[152:155], v[160:163], v[48:51]
	v_mfma_f32_16x16x32_bf16 v[36:39], v[144:147], v[168:171], v[36:39]
	v_mfma_f32_16x16x32_bf16 v[32:35], v[152:155], v[168:171], v[32:35]
	v_mfma_f32_16x16x32_bf16 v[20:23], v[144:147], v[192:195], v[20:23]
	v_mfma_f32_16x16x32_bf16 v[16:19], v[152:155], v[192:195], v[16:19]
	v_mfma_f32_16x16x32_bf16 v[4:7], v[144:147], v[200:203], v[4:7]
	v_mfma_f32_16x16x32_bf16 v[0:3], v[152:155], v[200:203], v[0:3]
	v_mfma_f32_16x16x32_bf16 v[52:55], v[148:151], v[164:167], v[52:55]
	v_mfma_f32_16x16x32_bf16 v[48:51], v[156:159], v[164:167], v[48:51]
	v_mfma_f32_16x16x32_bf16 v[36:39], v[148:151], v[172:175], v[36:39]
	v_mfma_f32_16x16x32_bf16 v[32:35], v[156:159], v[172:175], v[32:35]
	v_mfma_f32_16x16x32_bf16 v[20:23], v[148:151], v[196:199], v[20:23]
	v_mfma_f32_16x16x32_bf16 v[16:19], v[156:159], v[196:199], v[16:19]
	v_mfma_f32_16x16x32_bf16 v[4:7], v[148:151], v[204:207], v[4:7]
	v_mfma_f32_16x16x32_bf16 v[0:3], v[156:159], v[204:207], v[0:3]
	s_barrier
	s_add_i32 s62, s62, 2
	s_add_u32 s46, s46, 0x100
	s_addc_u32 s47, s47, 0
	s_add_u32 s60, s60, 0x100
	s_addc_u32 s61, s61, 0
	s_cmp_gt_u32 s62, 13
	s_cbranch_scc0 .LBB0_1250

; #define PG8_STAGE(bufoff, gbase, voff) do { _Pragma("unroll") for (int _i = 0; _i < 2; ++_i) \
;         __builtin_amdgcn_global_load_lds((const unsigned*)((const char*)(gbase) + (voff)[_i]), (LAS unsigned*)(lds + (bufoff) + ldsw + _i * 8192), 16, 0, 0); } while (0)
; #define PG8_LDA(dst, b, h) do { _Pragma("unroll") for (int m = 0; m < 4; ++m) _Pragma("unroll") for (int k = 0; k < 2; ++k) dst[m][k] = *(const LAS bf16x8*)(lds + PG8_SA(b, h) + aoff + m * 2048 + k * 1024); } while (0)
; #define PG8_WAIT_V(n) asm volatile("s_waitcnt vmcnt(" #n ")" ::: "memory")
;     DI bool next(int i, Unit& u) const {
;         const long L = (long)i * G + c; if (L >= total) return false;
;         u.g = (int)(L / nwg); int wgid = (int)(L % nwg);
;         { const int q = nwg / NXCD, r = nwg % NXCD, xcd = wgid % NXCD, off = wgid / NXCD; wgid = (xcd < r ? xcd * (q + 1) : r * (q + 1) + (xcd - r) * q) + off; }
;         const int nig = WGM * nN, gid = wgid / nig, fm = gid * WGM, gsz = (nM - fm) < WGM ? (nM - fm) : WGM;
;         u.pm = fm + ((wgid % nig) % gsz); u.pn = (wgid % nig) / gsz; return true;
; template <class Epi>
; DI void gemm_phase(LAS unsigned char* lds, const int wid, const Gemm g, const Order& S, const Epi& E) {
;     ...
;         const bool has_next = S.next(ui + 1, nxt);
;         const char* nA = has_next ? (const char*)(g.A + (size_t)nxt.g * g.gsA + (size_t)nxt.pm * BM * g.lda) : cA;
;         const char* nB = has_next ? (const char*)(g.Bt + (size_t)nxt.g * g.gsB + (size_t)nxt.pn * BM * g.ldb) : cB;
;         for (int t = 0; t < nt; t += 2) {
;             const bool last = (t == nt - 2);
;             const char* a1 = cA + (size_t)(t + 1) * kstep;
;             const char* a2 = last ? nA : cA + (size_t)(t + 2) * kstep; const char* b2 = last ? nB : cB + (size_t)(t + 2) * kstep;
;             const char* a3 = a2 + kstep; const char* b3 = b2 + kstep;
;             PG8_LDB(B0, 0, 0); PG8_LDB(B1, 0, 1); PG8_SCHED; PG8_LDA(At, 0, 0); PG8_STAGE(PG8_SA(1, 1), a1 + hstepA, voffA);
;             PG8_WAIT_V(8); PG8_WAIT_L(0); PG8_BAR; PG8_MMA(0, 0, At, B0); PG8_MMA(0, 1, At, B1); PG8_BAR; PG8_SCHED;
;             PG8_LDA(At, 0, 1); PG8_STAGE(PG8_SB(0, 0), b2, voffB); PG8_STAGE(PG8_SB(0, 1), b2 + hstepB, voffB); PG8_STAGE(PG8_SA(0, 0), a2, voffA);
;             PG8_WAIT_V(8); PG8_WAIT_L(0); PG8_BAR; PG8_MMA(1, 0, At, B0); PG8_MMA(1, 1, At, B1); PG8_BAR; PG8_SCHED;
.LBB0_1335:
	s_ashr_i32 s27, s26, 31
	s_lshl_b64 s[30:31], s[26:27], 19
	s_add_u32 s30, s6, s30
	s_addc_u32 s31, s7, s31
	s_and_b64 s[34:35], s[8:9], exec
	s_cselect_b32 s27, s31, s39
	s_cselect_b32 s56, s30, s38
	s_ashr_i32 s29, s28, 31
	s_lshl_b64 s[34:35], s[28:29], 19
	s_add_u32 s34, s21, s34
	s_addc_u32 s35, s44, s35
	s_and_b64 s[42:43], s[8:9], exec
	s_cselect_b32 s29, s35, s41
	s_cselect_b32 s57, s34, s40
	s_add_u32 s38, s38, 0x40080
	s_addc_u32 s39, s39, 0
	s_add_u32 s58, s40, 0x100
	v_mov_b32_e32 v0, 0
	s_addc_u32 s59, s41, 0
	s_mov_b32 s60, -2
	s_lshl_b32 s65, s36, 8
	s_add_i32 s65, s65, s95
	v_mbcnt_lo_u32_b32 v244, -1, 0
	v_mbcnt_hi_u32_b32 v244, -1, v244
	v_and_or_b32 v244, v244, 15, s65
	v_ashrrev_i32_e32 v245, 31, v244
	v_lshl_add_u64 v[246:247], v[244:245], 2, s[12:13]
	global_load_dword v236, v[246:247], off
	global_load_dword v237, v[246:247], off offset:64
	global_load_dword v238, v[246:247], off offset:128
	global_load_dword v239, v[246:247], off offset:192
	global_load_dword v240, v[246:247], off offset:512
	global_load_dword v241, v[246:247], off offset:576
	global_load_dword v242, v[246:247], off offset:640
	global_load_dword v243, v[246:247], off offset:704
	ds_read_b128 v[164:167], v151
	ds_read_b128 v[168:171], v151 offset:1024
	ds_read_b128 v[172:175], v151 offset:2048
	ds_read_b128 v[176:179], v151 offset:3072
	ds_read_b128 v[180:183], v155
	ds_read_b128 v[184:187], v155 offset:1024
	ds_read_b128 v[188:191], v155 offset:2048
	ds_read_b128 v[192:195], v155 offset:3072
	s_add_u32 s40, s38, 0xfffc0080
	s_addc_u32 s41, s39, -1
	s_cmp_eq_u32 s60, 12
	s_cselect_b32 s43, s27, s41
	s_cselect_b32 s42, s56, s40
	s_cselect_b32 s41, s29, s59
	s_cselect_b32 s40, s57, s58
	v_lshl_add_u64 v[144:145], s[38:39], 0, v[136:137]
	s_add_i32 m0, s37, 0xc000
	ds_read_b128 v[196:199], v159
	ds_read_b128 v[200:203], v159 offset:1024
	ds_read_b128 v[204:207], v159 offset:2048
	ds_read_b128 v[208:211], v159 offset:3072
	ds_read_b128 v[212:215], v159 offset:4096
	ds_read_b128 v[216:219], v159 offset:5120
	ds_read_b128 v[220:223], v159 offset:6144
	ds_read_b128 v[224:227], v159 offset:7168
	global_load_lds_dwordx4 v[144:145], off
	v_lshl_add_u64 v[144:145], s[38:39], 0, v[138:139]
	s_add_i32 m0, s37, 0xe000
	s_nop 0
	global_load_lds_dwordx4 v[144:145], off
	s_waitcnt vmcnt(8)
	s_waitcnt lgkmcnt(0)
	s_barrier
	v_mfma_f32_16x16x32_bf16 v[124:127], v[164:167], v[196:199], 0
	v_mfma_f32_16x16x32_bf16 v[120:123], v[172:175], v[196:199], 0
	v_mfma_f32_16x16x32_bf16 v[108:111], v[164:167], v[204:207], 0
	v_mfma_f32_16x16x32_bf16 v[104:107], v[172:175], v[204:207], 0
	v_mfma_f32_16x16x32_bf16 v[92:95], v[164:167], v[212:215], 0
	v_mfma_f32_16x16x32_bf16 v[88:91], v[172:175], v[212:215], 0
	v_mfma_f32_16x16x32_bf16 v[76:79], v[164:167], v[220:223], 0
	v_mfma_f32_16x16x32_bf16 v[72:75], v[172:175], v[220:223], 0
	v_mfma_f32_16x16x32_bf16 v[124:127], v[168:171], v[200:203], v[124:127]
	v_mfma_f32_16x16x32_bf16 v[120:123], v[176:179], v[200:203], v[120:123]
	v_mfma_f32_16x16x32_bf16 v[108:111], v[168:171], v[208:211], v[108:111]
	v_mfma_f32_16x16x32_bf16 v[104:107], v[176:179], v[208:211], v[104:107]
	v_mfma_f32_16x16x32_bf16 v[92:95], v[168:171], v[216:219], v[92:95]
	v_mfma_f32_16x16x32_bf16 v[88:91], v[176:179], v[216:219], v[88:91]
	v_mfma_f32_16x16x32_bf16 v[76:79], v[168:171], v[224:227], v[76:79]
	v_mfma_f32_16x16x32_bf16 v[72:75], v[176:179], v[224:227], v[72:75]
	v_mfma_f32_16x16x32_bf16 v[116:119], v[180:183], v[196:199], 0
	v_mfma_f32_16x16x32_bf16 v[112:115], v[188:191], v[196:199], 0
	v_mfma_f32_16x16x32_bf16 v[100:103], v[180:183], v[204:207], 0
	v_mfma_f32_16x16x32_bf16 v[96:99], v[188:191], v[204:207], 0
	v_mfma_f32_16x16x32_bf16 v[84:87], v[180:183], v[212:215], 0
	v_mfma_f32_16x16x32_bf16 v[80:83], v[188:191], v[212:215], 0
	v_mfma_f32_16x16x32_bf16 v[68:71], v[180:183], v[220:223], 0
	v_mfma_f32_16x16x32_bf16 v[64:67], v[188:191], v[220:223], 0
	v_mfma_f32_16x16x32_bf16 v[116:119], v[184:187], v[200:203], v[116:119]
	v_mfma_f32_16x16x32_bf16 v[112:115], v[192:195], v[200:203], v[112:115]
	v_mfma_f32_16x16x32_bf16 v[100:103], v[184:187], v[208:211], v[100:103]
	v_mfma_f32_16x16x32_bf16 v[96:99], v[192:195], v[208:211], v[96:99]
	v_mfma_f32_16x16x32_bf16 v[84:87], v[184:187], v[216:219], v[84:87]
	v_mfma_f32_16x16x32_bf16 v[80:83], v[192:195], v[216:219], v[80:83]
	v_mfma_f32_16x16x32_bf16 v[68:71], v[184:187], v[224:227], v[68:71]
	v_mfma_f32_16x16x32_bf16 v[64:67], v[192:195], v[224:227], v[64:67]
	s_barrier
	s_add_i32 s61, s53, s94
	v_lshl_add_u64 v[144:145], s[40:41], 0, v[132:133]
	s_mov_b32 m0, s61
	ds_read_b128 v[196:199], v159 offset:16384
	ds_read_b128 v[200:203], v159 offset:17408
	ds_read_b128 v[204:207], v159 offset:18432
	ds_read_b128 v[208:211], v159 offset:19456
	ds_read_b128 v[212:215], v159 offset:20480
	ds_read_b128 v[216:219], v159 offset:21504
	ds_read_b128 v[220:223], v159 offset:22528
	ds_read_b128 v[224:227], v159 offset:23552
	global_load_lds_dwordx4 v[144:145], off
	s_add_i32 m0, s61, 0x2000
	s_add_u32 s62, s40, 0x40000
	v_lshl_add_u64 v[148:149], s[40:41], 0, v[128:129]
	s_addc_u32 s63, s41, 0
	s_add_i32 s61, s54, s94
	global_load_lds_dwordx4 v[148:149], off
	v_lshl_add_u64 v[152:153], s[62:63], 0, v[132:133]
	s_mov_b32 m0, s61
	v_lshl_add_u64 v[156:157], s[42:43], 0, v[130:131]
	global_load_lds_dwordx4 v[152:153], off
	v_lshl_add_u64 v[152:153], s[62:63], 0, v[128:129]
	s_add_i32 m0, s61, 0x2000
	s_nop 0
	global_load_lds_dwordx4 v[152:153], off
	v_lshl_add_u64 v[152:153], s[42:43], 0, v[134:135]
	s_mov_b32 m0, s37
	s_nop 0
	global_load_lds_dwordx4 v[152:153], off
	s_mov_b32 m0, s46
	s_nop 0
	global_load_lds_dwordx4 v[156:157], off
	s_waitcnt vmcnt(8)
	s_waitcnt lgkmcnt(0)
	s_barrier
; #define PG8_STAGE(bufoff, gbase, voff) do { _Pragma("unroll") for (int _i = 0; _i < 2; ++_i) \
;         __builtin_amdgcn_global_load_lds((const unsigned*)((const char*)(gbase) + (voff)[_i]), (LAS unsigned*)(lds + (bufoff) + ldsw + _i * 8192), 16, 0, 0); } while (0)
; #define PG8_LDA(dst, b, h) do { _Pragma("unroll") for (int m = 0; m < 4; ++m) _Pragma("unroll") for (int k = 0; k < 2; ++k) dst[m][k] = *(const LAS bf16x8*)(lds + PG8_SA(b, h) + aoff + m * 2048 + k * 1024); } while (0)
; #define PG8_LDB(dst, b, h) do { _Pragma("unroll") for (int n = 0; n < 2; ++n) _Pragma("unroll") for (int k = 0; k < 2; ++k) dst[n][k] = *(const LAS bf16x8*)(lds + PG8_SB(b, h) + boff + n * 2048 + k * 1024); } while (0)
; #define PG8_BAR __builtin_amdgcn_s_barrier()
;     DI bool next(int i, Unit& u) const {
;     ...
;         u.g = (int)(L / nwg); int wgid = (int)(L % nwg);
;         { const int q = nwg / NXCD, r = nwg % NXCD, xcd = wgid % NXCD, off = wgid / NXCD; wgid = (xcd < r ? xcd * (q + 1) : r * (q + 1) + (xcd - r) * q) + off; }
;         const int nig = WGM * nN, gid = wgid / nig, fm = gid * WGM, gsz = (nM - fm) < WGM ? (nM - fm) : WGM;
;         u.pm = fm + ((wgid % nig) % gsz); u.pn = (wgid % nig) / gsz; return true;
; template <class Epi>
; DI void gemm_phase(LAS unsigned char* lds, const int wid, const Gemm g, const Order& S, const Epi& E) {
;     ...
;             PG8_LDB(B0, 0, 0); PG8_LDB(B1, 0, 1); PG8_SCHED; PG8_LDA(At, 0, 0); PG8_STAGE(PG8_SA(1, 1), a1 + hstepA, voffA);
;             PG8_WAIT_V(8); PG8_WAIT_L(0); PG8_BAR; PG8_MMA(0, 0, At, B0); PG8_MMA(0, 1, At, B1); PG8_BAR; PG8_SCHED;
;             PG8_LDA(At, 0, 1); PG8_STAGE(PG8_SB(0, 0), b2, voffB); PG8_STAGE(PG8_SB(0, 1), b2 + hstepB, voffB); PG8_STAGE(PG8_SA(0, 0), a2, voffA);
;             PG8_WAIT_V(8); PG8_WAIT_L(0); PG8_BAR; PG8_MMA(1, 0, At, B0); PG8_MMA(1, 1, At, B1); PG8_BAR; PG8_SCHED;
;             PG8_LDB(B0, 1, 0); PG8_LDB(B1, 1, 1); PG8_SCHED; PG8_LDA(At, 1, 0); PG8_STAGE(PG8_SA(0, 1), a2 + hstepA, voffA);
;             PG8_WAIT_V(8); PG8_WAIT_L(0); PG8_BAR; PG8_MMA(0, 0, At, B0); PG8_MMA(0, 1, At, B1); PG8_BAR; PG8_SCHED;
;             PG8_LDA(At, 1, 1); PG8_STAGE(PG8_SB(1, 0), b3, voffB); PG8_STAGE(PG8_SB(1, 1), b3 + hstepB, voffB); PG8_STAGE(PG8_SA(1, 0), a3, voffA);
;             PG8_WAIT_V(8); PG8_WAIT_L(0); PG8_BAR; PG8_MMA(1, 0, At, B0); PG8_MMA(1, 1, At, B1); PG8_BAR; PG8_SCHED;
	v_mfma_f32_16x16x32_bf16 v[60:63], v[164:167], v[196:199], 0
	v_mfma_f32_16x16x32_bf16 v[56:59], v[172:175], v[196:199], 0
	v_mfma_f32_16x16x32_bf16 v[44:47], v[164:167], v[204:207], 0
	v_mfma_f32_16x16x32_bf16 v[40:43], v[172:175], v[204:207], 0
	v_mfma_f32_16x16x32_bf16 v[28:31], v[164:167], v[212:215], 0
	v_mfma_f32_16x16x32_bf16 v[24:27], v[172:175], v[212:215], 0
	v_mfma_f32_16x16x32_bf16 v[12:15], v[164:167], v[220:223], 0
	v_mfma_f32_16x16x32_bf16 v[8:11], v[172:175], v[220:223], 0
	v_mfma_f32_16x16x32_bf16 v[60:63], v[168:171], v[200:203], v[60:63]
	v_mfma_f32_16x16x32_bf16 v[56:59], v[176:179], v[200:203], v[56:59]
	v_mfma_f32_16x16x32_bf16 v[44:47], v[168:171], v[208:211], v[44:47]
	v_mfma_f32_16x16x32_bf16 v[40:43], v[176:179], v[208:211], v[40:43]
	v_mfma_f32_16x16x32_bf16 v[28:31], v[168:171], v[216:219], v[28:31]
	v_mfma_f32_16x16x32_bf16 v[24:27], v[176:179], v[216:219], v[24:27]
	v_mfma_f32_16x16x32_bf16 v[12:15], v[168:171], v[224:227], v[12:15]
	v_mfma_f32_16x16x32_bf16 v[8:11], v[176:179], v[224:227], v[8:11]
	v_mfma_f32_16x16x32_bf16 v[52:55], v[180:183], v[196:199], 0
	v_mfma_f32_16x16x32_bf16 v[48:51], v[188:191], v[196:199], 0
	v_mfma_f32_16x16x32_bf16 v[36:39], v[180:183], v[204:207], 0
	v_mfma_f32_16x16x32_bf16 v[32:35], v[188:191], v[204:207], 0
	v_mfma_f32_16x16x32_bf16 v[20:23], v[180:183], v[212:215], 0
	v_mfma_f32_16x16x32_bf16 v[16:19], v[188:191], v[212:215], 0
	v_mfma_f32_16x16x32_bf16 v[4:7], v[180:183], v[220:223], 0
	v_mfma_f32_16x16x32_bf16 v[0:3], v[188:191], v[220:223], 0
	v_mfma_f32_16x16x32_bf16 v[52:55], v[184:187], v[200:203], v[52:55]
	v_mfma_f32_16x16x32_bf16 v[48:51], v[192:195], v[200:203], v[48:51]
	v_mfma_f32_16x16x32_bf16 v[36:39], v[184:187], v[208:211], v[36:39]
	v_mfma_f32_16x16x32_bf16 v[32:35], v[192:195], v[208:211], v[32:35]
	v_mfma_f32_16x16x32_bf16 v[20:23], v[184:187], v[216:219], v[20:23]
	v_mfma_f32_16x16x32_bf16 v[16:19], v[192:195], v[216:219], v[16:19]
	v_mfma_f32_16x16x32_bf16 v[4:7], v[184:187], v[224:227], v[4:7]
	v_mfma_f32_16x16x32_bf16 v[0:3], v[192:195], v[224:227], v[0:3]
	s_barrier
	s_add_i32 s61, 0, 0x18000
	v_add_u32_e32 v146, s61, v147
	s_add_i32 s62, 0, 0x1c000
	ds_read_b128 v[164:167], v146
	ds_read_b128 v[168:171], v146 offset:1024
	ds_read_b128 v[172:175], v146 offset:2048
	ds_read_b128 v[176:179], v146 offset:3072
	v_add_u32_e32 v146, s62, v147
	ds_read_b128 v[180:183], v146
	ds_read_b128 v[184:187], v146 offset:1024
	ds_read_b128 v[188:191], v146 offset:2048
	ds_read_b128 v[192:195], v146 offset:3072
	s_add_u32 s42, s42, 0x40000
	s_addc_u32 s43, s43, 0
	s_mov_b32 m0, s47
	v_lshl_add_u64 v[160:161], s[42:43], 0, v[134:135]
	ds_read_b128 v[196:199], v159 offset:32768
	ds_read_b128 v[200:203], v159 offset:33792
	ds_read_b128 v[204:207], v159 offset:34816
	ds_read_b128 v[208:211], v159 offset:35840
	ds_read_b128 v[212:215], v159 offset:36864
	ds_read_b128 v[216:219], v159 offset:37888
	ds_read_b128 v[220:223], v159 offset:38912
	ds_read_b128 v[224:227], v159 offset:39936
	global_load_lds_dwordx4 v[160:161], off
	v_lshl_add_u64 v[160:161], s[42:43], 0, v[130:131]
	s_mov_b32 m0, s48
	s_nop 0
	global_load_lds_dwordx4 v[160:161], off
	s_waitcnt vmcnt(8)
	s_waitcnt lgkmcnt(0)
	s_barrier
	v_mfma_f32_16x16x32_bf16 v[124:127], v[164:167], v[196:199], v[124:127]
	v_mfma_f32_16x16x32_bf16 v[120:123], v[172:175], v[196:199], v[120:123]
	v_mfma_f32_16x16x32_bf16 v[108:111], v[164:167], v[204:207], v[108:111]
	v_mfma_f32_16x16x32_bf16 v[104:107], v[172:175], v[204:207], v[104:107]
	v_mfma_f32_16x16x32_bf16 v[92:95], v[164:167], v[212:215], v[92:95]
	v_mfma_f32_16x16x32_bf16 v[88:91], v[172:175], v[212:215], v[88:91]
	v_mfma_f32_16x16x32_bf16 v[76:79], v[164:167], v[220:223], v[76:79]
	v_mfma_f32_16x16x32_bf16 v[72:75], v[172:175], v[220:223], v[72:75]
	v_mfma_f32_16x16x32_bf16 v[124:127], v[168:171], v[200:203], v[124:127]
	v_mfma_f32_16x16x32_bf16 v[120:123], v[176:179], v[200:203], v[120:123]
	v_mfma_f32_16x16x32_bf16 v[108:111], v[168:171], v[208:211], v[108:111]
	v_mfma_f32_16x16x32_bf16 v[104:107], v[176:179], v[208:211], v[104:107]
	v_mfma_f32_16x16x32_bf16 v[92:95], v[168:171], v[216:219], v[92:95]
	v_mfma_f32_16x16x32_bf16 v[88:91], v[176:179], v[216:219], v[88:91]
	v_mfma_f32_16x16x32_bf16 v[76:79], v[168:171], v[224:227], v[76:79]
	v_mfma_f32_16x16x32_bf16 v[72:75], v[176:179], v[224:227], v[72:75]
	v_mfma_f32_16x16x32_bf16 v[116:119], v[180:183], v[196:199], v[116:119]
	v_mfma_f32_16x16x32_bf16 v[112:115], v[188:191], v[196:199], v[112:115]
	v_mfma_f32_16x16x32_bf16 v[100:103], v[180:183], v[204:207], v[100:103]
	v_mfma_f32_16x16x32_bf16 v[96:99], v[188:191], v[204:207], v[96:99]
	v_mfma_f32_16x16x32_bf16 v[84:87], v[180:183], v[212:215], v[84:87]
	v_mfma_f32_16x16x32_bf16 v[80:83], v[188:191], v[212:215], v[80:83]
	v_mfma_f32_16x16x32_bf16 v[68:71], v[180:183], v[220:223], v[68:71]
	v_mfma_f32_16x16x32_bf16 v[64:67], v[188:191], v[220:223], v[64:67]
	v_mfma_f32_16x16x32_bf16 v[116:119], v[184:187], v[200:203], v[116:119]
	v_mfma_f32_16x16x32_bf16 v[112:115], v[192:195], v[200:203], v[112:115]
	v_mfma_f32_16x16x32_bf16 v[100:103], v[184:187], v[208:211], v[100:103]
	v_mfma_f32_16x16x32_bf16 v[96:99], v[192:195], v[208:211], v[96:99]
	v_mfma_f32_16x16x32_bf16 v[84:87], v[184:187], v[216:219], v[84:87]
	v_mfma_f32_16x16x32_bf16 v[80:83], v[192:195], v[216:219], v[80:83]
	v_mfma_f32_16x16x32_bf16 v[68:71], v[184:187], v[224:227], v[68:71]
	v_mfma_f32_16x16x32_bf16 v[64:67], v[192:195], v[224:227], v[64:67]
	s_barrier
; #define PG8_STAGE(bufoff, gbase, voff) do { _Pragma("unroll") for (int _i = 0; _i < 2; ++_i) \
;         __builtin_amdgcn_global_load_lds((const unsigned*)((const char*)(gbase) + (voff)[_i]), (LAS unsigned*)(lds + (bufoff) + ldsw + _i * 8192), 16, 0, 0); } while (0)
; #define PG8_LDA(dst, b, h) do { _Pragma("unroll") for (int m = 0; m < 4; ++m) _Pragma("unroll") for (int k = 0; k < 2; ++k) dst[m][k] = *(const LAS bf16x8*)(lds + PG8_SA(b, h) + aoff + m * 2048 + k * 1024); } while (0)
; #define PG8_LDB(dst, b, h) do { _Pragma("unroll") for (int n = 0; n < 2; ++n) _Pragma("unroll") for (int k = 0; k < 2; ++k) dst[n][k] = *(const LAS bf16x8*)(lds + PG8_SB(b, h) + boff + n * 2048 + k * 1024); } while (0)
; #define PG8_MMA(ai, bj, At, Bt) do { __builtin_amdgcn_s_setprio(1); _Pragma("unroll") for (int m = 0; m < 4; ++m) _Pragma("unroll") for (int n = 0; n < 2; ++n) _Pragma("unroll") for (int k = 0; k < 2; ++k) \
;         acc[ai][bj][m][n] = __builtin_amdgcn_mfma_f32_16x16x32_bf16(Bt[n][k], At[m][k], acc[ai][bj][m][n], 0, 0, 0); __builtin_amdgcn_s_setprio(0); } while (0)
; #define PG8_WAIT_V(n) asm volatile("s_waitcnt vmcnt(" #n ")" ::: "memory")
; #define PG8_WAIT_L(n) asm volatile("s_waitcnt lgkmcnt(" #n ")" ::: "memory")
; template <class Epi>
; DI void gemm_phase(LAS unsigned char* lds, const int wid, const Gemm g, const Order& S, const Epi& E) {
;     ...
;             PG8_LDB(B0, 0, 0); PG8_LDB(B1, 0, 1); PG8_SCHED; PG8_LDA(At, 0, 0); PG8_STAGE(PG8_SA(1, 1), a1 + hstepA, voffA);
;             PG8_WAIT_V(8); PG8_WAIT_L(0); PG8_BAR; PG8_MMA(0, 0, At, B0); PG8_MMA(0, 1, At, B1); PG8_BAR; PG8_SCHED;
;             PG8_LDA(At, 0, 1); PG8_STAGE(PG8_SB(0, 0), b2, voffB); PG8_STAGE(PG8_SB(0, 1), b2 + hstepB, voffB); PG8_STAGE(PG8_SA(0, 0), a2, voffA);
;             PG8_WAIT_V(8); PG8_WAIT_L(0); PG8_BAR; PG8_MMA(1, 0, At, B0); PG8_MMA(1, 1, At, B1); PG8_BAR; PG8_SCHED;
;             PG8_LDB(B0, 1, 0); PG8_LDB(B1, 1, 1); PG8_SCHED; PG8_LDA(At, 1, 0); PG8_STAGE(PG8_SA(0, 1), a2 + hstepA, voffA);
;             PG8_WAIT_V(8); PG8_WAIT_L(0); PG8_BAR; PG8_MMA(0, 0, At, B0); PG8_MMA(0, 1, At, B1); PG8_BAR; PG8_SCHED;
;             PG8_LDA(At, 1, 1); PG8_STAGE(PG8_SB(1, 0), b3, voffB); PG8_STAGE(PG8_SB(1, 1), b3 + hstepB, voffB); PG8_STAGE(PG8_SA(1, 0), a3, voffA);
;             PG8_WAIT_V(8); PG8_WAIT_L(0); PG8_BAR; PG8_MMA(1, 0, At, B0); PG8_MMA(1, 1, At, B1); PG8_BAR; PG8_SCHED;
	s_add_i32 s42, s61, s94
	v_lshl_add_u64 v[144:145], v[144:145], 0, s[16:17]
	s_mov_b32 m0, s42
	ds_read_b128 v[196:199], v159 offset:49152
	ds_read_b128 v[200:203], v159 offset:50176
	ds_read_b128 v[204:207], v159 offset:51200
	ds_read_b128 v[208:211], v159 offset:52224
	ds_read_b128 v[212:215], v159 offset:53248
	ds_read_b128 v[216:219], v159 offset:54272
	ds_read_b128 v[220:223], v159 offset:55296
	ds_read_b128 v[224:227], v159 offset:56320
	global_load_lds_dwordx4 v[144:145], off
	s_add_i32 m0, s42, 0x2000
	s_add_u32 s40, s40, 0x40080
	v_lshl_add_u64 v[144:145], v[148:149], 0, s[16:17]
	s_addc_u32 s41, s41, 0
	s_add_i32 s42, s62, s94
	global_load_lds_dwordx4 v[144:145], off
	v_lshl_add_u64 v[144:145], s[40:41], 0, v[132:133]
	s_mov_b32 m0, s42
	s_nop 0
	global_load_lds_dwordx4 v[144:145], off
	v_lshl_add_u64 v[144:145], s[40:41], 0, v[128:129]
	s_add_i32 m0, s42, 0x2000
	s_nop 0
	global_load_lds_dwordx4 v[144:145], off
	v_lshl_add_u64 v[144:145], v[152:153], 0, s[16:17]
	s_mov_b32 m0, s51
	s_nop 0
	global_load_lds_dwordx4 v[144:145], off
	v_lshl_add_u64 v[144:145], v[156:157], 0, s[16:17]
	s_mov_b32 m0, s52
	s_nop 0
	global_load_lds_dwordx4 v[144:145], off
	s_waitcnt vmcnt(8)
	s_waitcnt lgkmcnt(0)
	s_barrier
	v_mfma_f32_16x16x32_bf16 v[60:63], v[164:167], v[196:199], v[60:63]
	v_mfma_f32_16x16x32_bf16 v[56:59], v[172:175], v[196:199], v[56:59]
	v_mfma_f32_16x16x32_bf16 v[44:47], v[164:167], v[204:207], v[44:47]
	v_mfma_f32_16x16x32_bf16 v[40:43], v[172:175], v[204:207], v[40:43]
	v_mfma_f32_16x16x32_bf16 v[28:31], v[164:167], v[212:215], v[28:31]
	v_mfma_f32_16x16x32_bf16 v[24:27], v[172:175], v[212:215], v[24:27]
	v_mfma_f32_16x16x32_bf16 v[12:15], v[164:167], v[220:223], v[12:15]
	v_mfma_f32_16x16x32_bf16 v[8:11], v[172:175], v[220:223], v[8:11]
	v_mfma_f32_16x16x32_bf16 v[60:63], v[168:171], v[200:203], v[60:63]
	v_mfma_f32_16x16x32_bf16 v[56:59], v[176:179], v[200:203], v[56:59]
	v_mfma_f32_16x16x32_bf16 v[44:47], v[168:171], v[208:211], v[44:47]
	v_mfma_f32_16x16x32_bf16 v[40:43], v[176:179], v[208:211], v[40:43]
	v_mfma_f32_16x16x32_bf16 v[28:31], v[168:171], v[216:219], v[28:31]
	v_mfma_f32_16x16x32_bf16 v[24:27], v[176:179], v[216:219], v[24:27]
	v_mfma_f32_16x16x32_bf16 v[12:15], v[168:171], v[224:227], v[12:15]
	v_mfma_f32_16x16x32_bf16 v[8:11], v[176:179], v[224:227], v[8:11]
	v_mfma_f32_16x16x32_bf16 v[52:55], v[180:183], v[196:199], v[52:55]
	v_mfma_f32_16x16x32_bf16 v[48:51], v[188:191], v[196:199], v[48:51]
	v_mfma_f32_16x16x32_bf16 v[36:39], v[180:183], v[204:207], v[36:39]
	v_mfma_f32_16x16x32_bf16 v[32:35], v[188:191], v[204:207], v[32:35]
	v_mfma_f32_16x16x32_bf16 v[20:23], v[180:183], v[212:215], v[20:23]
	v_mfma_f32_16x16x32_bf16 v[16:19], v[188:191], v[212:215], v[16:19]
	v_mfma_f32_16x16x32_bf16 v[4:7], v[180:183], v[220:223], v[4:7]
	v_mfma_f32_16x16x32_bf16 v[0:3], v[188:191], v[220:223], v[0:3]
	v_mfma_f32_16x16x32_bf16 v[52:55], v[184:187], v[200:203], v[52:55]
	v_mfma_f32_16x16x32_bf16 v[48:51], v[192:195], v[200:203], v[48:51]
	v_mfma_f32_16x16x32_bf16 v[36:39], v[184:187], v[208:211], v[36:39]
	v_mfma_f32_16x16x32_bf16 v[32:35], v[192:195], v[208:211], v[32:35]
	v_mfma_f32_16x16x32_bf16 v[20:23], v[184:187], v[216:219], v[20:23]
	v_mfma_f32_16x16x32_bf16 v[16:19], v[192:195], v[216:219], v[16:19]
	v_mfma_f32_16x16x32_bf16 v[4:7], v[184:187], v[224:227], v[4:7]
	v_mfma_f32_16x16x32_bf16 v[0:3], v[192:195], v[224:227], v[0:3]
	s_barrier
	s_add_i32 s60, s60, 2
	s_add_u32 s38, s38, 0x100
	s_addc_u32 s39, s39, 0
	s_add_u32 s58, s58, 0x100
	s_addc_u32 s59, s59, 0
	s_cmp_gt_u32 s60, 13
	s_cbranch_scc0 .LBB0_1336
	s_branch .Lpeel_exit_9
.LBB0_1336:
	ds_read_b128 v[164:167], v151
	ds_read_b128 v[168:171], v151 offset:1024
	ds_read_b128 v[172:175], v151 offset:2048
	ds_read_b128 v[176:179], v151 offset:3072
	ds_read_b128 v[180:183], v155
	ds_read_b128 v[184:187], v155 offset:1024
	ds_read_b128 v[188:191], v155 offset:2048
	ds_read_b128 v[192:195], v155 offset:3072
	s_add_u32 s40, s38, 0xfffc0080
	s_addc_u32 s41, s39, -1
	s_cmp_eq_u32 s60, 12
	s_cselect_b32 s43, s27, s41
	s_cselect_b32 s42, s56, s40
	s_cselect_b32 s41, s29, s59
	s_cselect_b32 s40, s57, s58
	v_lshl_add_u64 v[144:145], s[38:39], 0, v[136:137]
	s_add_i32 m0, s37, 0xc000
	ds_read_b128 v[196:199], v159
	ds_read_b128 v[200:203], v159 offset:1024
	ds_read_b128 v[204:207], v159 offset:2048
	ds_read_b128 v[208:211], v159 offset:3072
	ds_read_b128 v[212:215], v159 offset:4096
	ds_read_b128 v[216:219], v159 offset:5120
	ds_read_b128 v[220:223], v159 offset:6144
	ds_read_b128 v[224:227], v159 offset:7168
	global_load_lds_dwordx4 v[144:145], off
	v_lshl_add_u64 v[144:145], s[38:39], 0, v[138:139]
	s_add_i32 m0, s37, 0xe000
	s_nop 0
	global_load_lds_dwordx4 v[144:145], off
	s_waitcnt vmcnt(8)
	s_waitcnt lgkmcnt(0)
	s_barrier
; #define PG8_STAGE(bufoff, gbase, voff) do { _Pragma("unroll") for (int _i = 0; _i < 2; ++_i) \
;         __builtin_amdgcn_global_load_lds((const unsigned*)((const char*)(gbase) + (voff)[_i]), (LAS unsigned*)(lds + (bufoff) + ldsw + _i * 8192), 16, 0, 0); } while (0)
; #define PG8_LDA(dst, b, h) do { _Pragma("unroll") for (int m = 0; m < 4; ++m) _Pragma("unroll") for (int k = 0; k < 2; ++k) dst[m][k] = *(const LAS bf16x8*)(lds + PG8_SA(b, h) + aoff + m * 2048 + k * 1024); } while (0)
; #define PG8_LDB(dst, b, h) do { _Pragma("unroll") for (int n = 0; n < 2; ++n) _Pragma("unroll") for (int k = 0; k < 2; ++k) dst[n][k] = *(const LAS bf16x8*)(lds + PG8_SB(b, h) + boff + n * 2048 + k * 1024); } while (0)
; #define PG8_MMA(ai, bj, At, Bt) do { __builtin_amdgcn_s_setprio(1); _Pragma("unroll") for (int m = 0; m < 4; ++m) _Pragma("unroll") for (int n = 0; n < 2; ++n) _Pragma("unroll") for (int k = 0; k < 2; ++k) \
;         acc[ai][bj][m][n] = __builtin_amdgcn_mfma_f32_16x16x32_bf16(Bt[n][k], At[m][k], acc[ai][bj][m][n], 0, 0, 0); __builtin_amdgcn_s_setprio(0); } while (0)
; #define PG8_WAIT_V(n) asm volatile("s_waitcnt vmcnt(" #n ")" ::: "memory")
; #define PG8_WAIT_L(n) asm volatile("s_waitcnt lgkmcnt(" #n ")" ::: "memory")
; #define PG8_BAR __builtin_amdgcn_s_barrier()
; #define PG8_SCHED __builtin_amdgcn_sched_barrier(0)
; template <class Epi>
; DI void gemm_phase(LAS unsigned char* lds, const int wid, const Gemm g, const Order& S, const Epi& E) {
;     ...
;             PG8_LDB(B0, 0, 0); PG8_LDB(B1, 0, 1); PG8_SCHED; PG8_LDA(At, 0, 0); PG8_STAGE(PG8_SA(1, 1), a1 + hstepA, voffA);
;             PG8_WAIT_V(8); PG8_WAIT_L(0); PG8_BAR; PG8_MMA(0, 0, At, B0); PG8_MMA(0, 1, At, B1); PG8_BAR; PG8_SCHED;
;             PG8_LDA(At, 0, 1); PG8_STAGE(PG8_SB(0, 0), b2, voffB); PG8_STAGE(PG8_SB(0, 1), b2 + hstepB, voffB); PG8_STAGE(PG8_SA(0, 0), a2, voffA);
;             PG8_WAIT_V(8); PG8_WAIT_L(0); PG8_BAR; PG8_MMA(1, 0, At, B0); PG8_MMA(1, 1, At, B1); PG8_BAR; PG8_SCHED;
;             PG8_LDB(B0, 1, 0); PG8_LDB(B1, 1, 1); PG8_SCHED; PG8_LDA(At, 1, 0); PG8_STAGE(PG8_SA(0, 1), a2 + hstepA, voffA);
;             PG8_WAIT_V(8); PG8_WAIT_L(0); PG8_BAR; PG8_MMA(0, 0, At, B0); PG8_MMA(0, 1, At, B1); PG8_BAR; PG8_SCHED;
	v_mfma_f32_16x16x32_bf16 v[124:127], v[164:167], v[196:199], v[124:127]
	v_mfma_f32_16x16x32_bf16 v[120:123], v[172:175], v[196:199], v[120:123]
	v_mfma_f32_16x16x32_bf16 v[108:111], v[164:167], v[204:207], v[108:111]
	v_mfma_f32_16x16x32_bf16 v[104:107], v[172:175], v[204:207], v[104:107]
	v_mfma_f32_16x16x32_bf16 v[92:95], v[164:167], v[212:215], v[92:95]
	v_mfma_f32_16x16x32_bf16 v[88:91], v[172:175], v[212:215], v[88:91]
	v_mfma_f32_16x16x32_bf16 v[76:79], v[164:167], v[220:223], v[76:79]
	v_mfma_f32_16x16x32_bf16 v[72:75], v[172:175], v[220:223], v[72:75]
	v_mfma_f32_16x16x32_bf16 v[124:127], v[168:171], v[200:203], v[124:127]
	v_mfma_f32_16x16x32_bf16 v[120:123], v[176:179], v[200:203], v[120:123]
	v_mfma_f32_16x16x32_bf16 v[108:111], v[168:171], v[208:211], v[108:111]
	v_mfma_f32_16x16x32_bf16 v[104:107], v[176:179], v[208:211], v[104:107]
	v_mfma_f32_16x16x32_bf16 v[92:95], v[168:171], v[216:219], v[92:95]
	v_mfma_f32_16x16x32_bf16 v[88:91], v[176:179], v[216:219], v[88:91]
	v_mfma_f32_16x16x32_bf16 v[76:79], v[168:171], v[224:227], v[76:79]
	v_mfma_f32_16x16x32_bf16 v[72:75], v[176:179], v[224:227], v[72:75]
	v_mfma_f32_16x16x32_bf16 v[116:119], v[180:183], v[196:199], v[116:119]
	v_mfma_f32_16x16x32_bf16 v[112:115], v[188:191], v[196:199], v[112:115]
	v_mfma_f32_16x16x32_bf16 v[100:103], v[180:183], v[204:207], v[100:103]
	v_mfma_f32_16x16x32_bf16 v[96:99], v[188:191], v[204:207], v[96:99]
	v_mfma_f32_16x16x32_bf16 v[84:87], v[180:183], v[212:215], v[84:87]
	v_mfma_f32_16x16x32_bf16 v[80:83], v[188:191], v[212:215], v[80:83]
	v_mfma_f32_16x16x32_bf16 v[68:71], v[180:183], v[220:223], v[68:71]
	v_mfma_f32_16x16x32_bf16 v[64:67], v[188:191], v[220:223], v[64:67]
	v_mfma_f32_16x16x32_bf16 v[116:119], v[184:187], v[200:203], v[116:119]
	v_mfma_f32_16x16x32_bf16 v[112:115], v[192:195], v[200:203], v[112:115]
	v_mfma_f32_16x16x32_bf16 v[100:103], v[184:187], v[208:211], v[100:103]
	v_mfma_f32_16x16x32_bf16 v[96:99], v[192:195], v[208:211], v[96:99]
	v_mfma_f32_16x16x32_bf16 v[84:87], v[184:187], v[216:219], v[84:87]
	v_mfma_f32_16x16x32_bf16 v[80:83], v[192:195], v[216:219], v[80:83]
	v_mfma_f32_16x16x32_bf16 v[68:71], v[184:187], v[224:227], v[68:71]
	v_mfma_f32_16x16x32_bf16 v[64:67], v[192:195], v[224:227], v[64:67]
	s_barrier
	s_add_i32 s61, s53, s94
	v_lshl_add_u64 v[144:145], s[40:41], 0, v[132:133]
	s_mov_b32 m0, s61
	ds_read_b128 v[196:199], v159 offset:16384
	ds_read_b128 v[200:203], v159 offset:17408
	ds_read_b128 v[204:207], v159 offset:18432
	ds_read_b128 v[208:211], v159 offset:19456
	ds_read_b128 v[212:215], v159 offset:20480
	ds_read_b128 v[216:219], v159 offset:21504
	ds_read_b128 v[220:223], v159 offset:22528
	ds_read_b128 v[224:227], v159 offset:23552
	global_load_lds_dwordx4 v[144:145], off
	s_add_i32 m0, s61, 0x2000
	s_add_u32 s62, s40, 0x40000
	v_lshl_add_u64 v[148:149], s[40:41], 0, v[128:129]
	s_addc_u32 s63, s41, 0
	s_add_i32 s61, s54, s94
	global_load_lds_dwordx4 v[148:149], off
	v_lshl_add_u64 v[152:153], s[62:63], 0, v[132:133]
	s_mov_b32 m0, s61
	v_lshl_add_u64 v[156:157], s[42:43], 0, v[130:131]
	global_load_lds_dwordx4 v[152:153], off
	v_lshl_add_u64 v[152:153], s[62:63], 0, v[128:129]
	s_add_i32 m0, s61, 0x2000
	s_nop 0
	global_load_lds_dwordx4 v[152:153], off
	v_lshl_add_u64 v[152:153], s[42:43], 0, v[134:135]
	s_mov_b32 m0, s37
	s_nop 0
	global_load_lds_dwordx4 v[152:153], off
	s_mov_b32 m0, s46
	s_nop 0
	global_load_lds_dwordx4 v[156:157], off
	s_waitcnt vmcnt(8)
	s_waitcnt lgkmcnt(0)
	s_barrier
	v_mfma_f32_16x16x32_bf16 v[60:63], v[164:167], v[196:199], v[60:63]
	v_mfma_f32_16x16x32_bf16 v[56:59], v[172:175], v[196:199], v[56:59]
	v_mfma_f32_16x16x32_bf16 v[44:47], v[164:167], v[204:207], v[44:47]
	v_mfma_f32_16x16x32_bf16 v[40:43], v[172:175], v[204:207], v[40:43]
	v_mfma_f32_16x16x32_bf16 v[28:31], v[164:167], v[212:215], v[28:31]
	v_mfma_f32_16x16x32_bf16 v[24:27], v[172:175], v[212:215], v[24:27]
	v_mfma_f32_16x16x32_bf16 v[12:15], v[164:167], v[220:223], v[12:15]
	v_mfma_f32_16x16x32_bf16 v[8:11], v[172:175], v[220:223], v[8:11]
	v_mfma_f32_16x16x32_bf16 v[60:63], v[168:171], v[200:203], v[60:63]
	v_mfma_f32_16x16x32_bf16 v[56:59], v[176:179], v[200:203], v[56:59]
	v_mfma_f32_16x16x32_bf16 v[44:47], v[168:171], v[208:211], v[44:47]
	v_mfma_f32_16x16x32_bf16 v[40:43], v[176:179], v[208:211], v[40:43]
	v_mfma_f32_16x16x32_bf16 v[28:31], v[168:171], v[216:219], v[28:31]
	v_mfma_f32_16x16x32_bf16 v[24:27], v[176:179], v[216:219], v[24:27]
	v_mfma_f32_16x16x32_bf16 v[12:15], v[168:171], v[224:227], v[12:15]
	v_mfma_f32_16x16x32_bf16 v[8:11], v[176:179], v[224:227], v[8:11]
	v_mfma_f32_16x16x32_bf16 v[52:55], v[180:183], v[196:199], v[52:55]
	v_mfma_f32_16x16x32_bf16 v[48:51], v[188:191], v[196:199], v[48:51]
	v_mfma_f32_16x16x32_bf16 v[36:39], v[180:183], v[204:207], v[36:39]
	v_mfma_f32_16x16x32_bf16 v[32:35], v[188:191], v[204:207], v[32:35]
	v_mfma_f32_16x16x32_bf16 v[20:23], v[180:183], v[212:215], v[20:23]
	v_mfma_f32_16x16x32_bf16 v[16:19], v[188:191], v[212:215], v[16:19]
	v_mfma_f32_16x16x32_bf16 v[4:7], v[180:183], v[220:223], v[4:7]
	v_mfma_f32_16x16x32_bf16 v[0:3], v[188:191], v[220:223], v[0:3]
	v_mfma_f32_16x16x32_bf16 v[52:55], v[184:187], v[200:203], v[52:55]
	v_mfma_f32_16x16x32_bf16 v[48:51], v[192:195], v[200:203], v[48:51]
	v_mfma_f32_16x16x32_bf16 v[36:39], v[184:187], v[208:211], v[36:39]
	v_mfma_f32_16x16x32_bf16 v[32:35], v[192:195], v[208:211], v[32:35]
	v_mfma_f32_16x16x32_bf16 v[20:23], v[184:187], v[216:219], v[20:23]
	v_mfma_f32_16x16x32_bf16 v[16:19], v[192:195], v[216:219], v[16:19]
	v_mfma_f32_16x16x32_bf16 v[4:7], v[184:187], v[224:227], v[4:7]
	v_mfma_f32_16x16x32_bf16 v[0:3], v[192:195], v[224:227], v[0:3]
	s_barrier
; #define PG8_STAGE(bufoff, gbase, voff) do { _Pragma("unroll") for (int _i = 0; _i < 2; ++_i) \
;         __builtin_amdgcn_global_load_lds((const unsigned*)((const char*)(gbase) + (voff)[_i]), (LAS unsigned*)(lds + (bufoff) + ldsw + _i * 8192), 16, 0, 0); } while (0)
; #define PG8_LDA(dst, b, h) do { _Pragma("unroll") for (int m = 0; m < 4; ++m) _Pragma("unroll") for (int k = 0; k < 2; ++k) dst[m][k] = *(const LAS bf16x8*)(lds + PG8_SA(b, h) + aoff + m * 2048 + k * 1024); } while (0)
; #define PG8_LDB(dst, b, h) do { _Pragma("unroll") for (int n = 0; n < 2; ++n) _Pragma("unroll") for (int k = 0; k < 2; ++k) dst[n][k] = *(const LAS bf16x8*)(lds + PG8_SB(b, h) + boff + n * 2048 + k * 1024); } while (0)
; #define PG8_MMA(ai, bj, At, Bt) do { __builtin_amdgcn_s_setprio(1); _Pragma("unroll") for (int m = 0; m < 4; ++m) _Pragma("unroll") for (int n = 0; n < 2; ++n) _Pragma("unroll") for (int k = 0; k < 2; ++k) \
;         acc[ai][bj][m][n] = __builtin_amdgcn_mfma_f32_16x16x32_bf16(Bt[n][k], At[m][k], acc[ai][bj][m][n], 0, 0, 0); __builtin_amdgcn_s_setprio(0); } while (0)
; #define PG8_WAIT_V(n) asm volatile("s_waitcnt vmcnt(" #n ")" ::: "memory")
; #define PG8_WAIT_L(n) asm volatile("s_waitcnt lgkmcnt(" #n ")" ::: "memory")
; #define PG8_BAR __builtin_amdgcn_s_barrier()
; #define PG8_SCHED __builtin_amdgcn_sched_barrier(0)
; template <class Epi>
; DI void gemm_phase(LAS unsigned char* lds, const int wid, const Gemm g, const Order& S, const Epi& E) {
;     ...
;             PG8_LDB(B0, 1, 0); PG8_LDB(B1, 1, 1); PG8_SCHED; PG8_LDA(At, 1, 0); PG8_STAGE(PG8_SA(0, 1), a2 + hstepA, voffA);
;             PG8_WAIT_V(8); PG8_WAIT_L(0); PG8_BAR; PG8_MMA(0, 0, At, B0); PG8_MMA(0, 1, At, B1); PG8_BAR; PG8_SCHED;
;             PG8_LDA(At, 1, 1); PG8_STAGE(PG8_SB(1, 0), b3, voffB); PG8_STAGE(PG8_SB(1, 1), b3 + hstepB, voffB); PG8_STAGE(PG8_SA(1, 0), a3, voffA);
;             PG8_WAIT_V(8); PG8_WAIT_L(0); PG8_BAR; PG8_MMA(1, 0, At, B0); PG8_MMA(1, 1, At, B1); PG8_BAR; PG8_SCHED;
	s_add_i32 s61, 0, 0x18000
	v_add_u32_e32 v146, s61, v147
	s_add_i32 s62, 0, 0x1c000
	ds_read_b128 v[164:167], v146
	ds_read_b128 v[168:171], v146 offset:1024
	ds_read_b128 v[172:175], v146 offset:2048
	ds_read_b128 v[176:179], v146 offset:3072
	v_add_u32_e32 v146, s62, v147
	ds_read_b128 v[180:183], v146
	ds_read_b128 v[184:187], v146 offset:1024
	ds_read_b128 v[188:191], v146 offset:2048
	ds_read_b128 v[192:195], v146 offset:3072
	s_add_u32 s42, s42, 0x40000
	s_addc_u32 s43, s43, 0
	s_mov_b32 m0, s47
	v_lshl_add_u64 v[160:161], s[42:43], 0, v[134:135]
	ds_read_b128 v[196:199], v159 offset:32768
	ds_read_b128 v[200:203], v159 offset:33792
	ds_read_b128 v[204:207], v159 offset:34816
	ds_read_b128 v[208:211], v159 offset:35840
	ds_read_b128 v[212:215], v159 offset:36864
	ds_read_b128 v[216:219], v159 offset:37888
	ds_read_b128 v[220:223], v159 offset:38912
	ds_read_b128 v[224:227], v159 offset:39936
	global_load_lds_dwordx4 v[160:161], off
	v_lshl_add_u64 v[160:161], s[42:43], 0, v[130:131]
	s_mov_b32 m0, s48
	s_nop 0
	global_load_lds_dwordx4 v[160:161], off
	s_waitcnt vmcnt(8)
	s_waitcnt lgkmcnt(0)
	s_barrier
	v_mfma_f32_16x16x32_bf16 v[124:127], v[164:167], v[196:199], v[124:127]
	v_mfma_f32_16x16x32_bf16 v[120:123], v[172:175], v[196:199], v[120:123]
	v_mfma_f32_16x16x32_bf16 v[108:111], v[164:167], v[204:207], v[108:111]
	v_mfma_f32_16x16x32_bf16 v[104:107], v[172:175], v[204:207], v[104:107]
	v_mfma_f32_16x16x32_bf16 v[92:95], v[164:167], v[212:215], v[92:95]
	v_mfma_f32_16x16x32_bf16 v[88:91], v[172:175], v[212:215], v[88:91]
	v_mfma_f32_16x16x32_bf16 v[76:79], v[164:167], v[220:223], v[76:79]
	v_mfma_f32_16x16x32_bf16 v[72:75], v[172:175], v[220:223], v[72:75]
	v_mfma_f32_16x16x32_bf16 v[124:127], v[168:171], v[200:203], v[124:127]
	v_mfma_f32_16x16x32_bf16 v[120:123], v[176:179], v[200:203], v[120:123]
	v_mfma_f32_16x16x32_bf16 v[108:111], v[168:171], v[208:211], v[108:111]
	v_mfma_f32_16x16x32_bf16 v[104:107], v[176:179], v[208:211], v[104:107]
	v_mfma_f32_16x16x32_bf16 v[92:95], v[168:171], v[216:219], v[92:95]
	v_mfma_f32_16x16x32_bf16 v[88:91], v[176:179], v[216:219], v[88:91]
	v_mfma_f32_16x16x32_bf16 v[76:79], v[168:171], v[224:227], v[76:79]
	v_mfma_f32_16x16x32_bf16 v[72:75], v[176:179], v[224:227], v[72:75]
	v_mfma_f32_16x16x32_bf16 v[116:119], v[180:183], v[196:199], v[116:119]
	v_mfma_f32_16x16x32_bf16 v[112:115], v[188:191], v[196:199], v[112:115]
	v_mfma_f32_16x16x32_bf16 v[100:103], v[180:183], v[204:207], v[100:103]
	v_mfma_f32_16x16x32_bf16 v[96:99], v[188:191], v[204:207], v[96:99]
	v_mfma_f32_16x16x32_bf16 v[84:87], v[180:183], v[212:215], v[84:87]
	v_mfma_f32_16x16x32_bf16 v[80:83], v[188:191], v[212:215], v[80:83]
	v_mfma_f32_16x16x32_bf16 v[68:71], v[180:183], v[220:223], v[68:71]
	v_mfma_f32_16x16x32_bf16 v[64:67], v[188:191], v[220:223], v[64:67]
	v_mfma_f32_16x16x32_bf16 v[116:119], v[184:187], v[200:203], v[116:119]
	v_mfma_f32_16x16x32_bf16 v[112:115], v[192:195], v[200:203], v[112:115]
	v_mfma_f32_16x16x32_bf16 v[100:103], v[184:187], v[208:211], v[100:103]
	v_mfma_f32_16x16x32_bf16 v[96:99], v[192:195], v[208:211], v[96:99]
	v_mfma_f32_16x16x32_bf16 v[84:87], v[184:187], v[216:219], v[84:87]
	v_mfma_f32_16x16x32_bf16 v[80:83], v[192:195], v[216:219], v[80:83]
	v_mfma_f32_16x16x32_bf16 v[68:71], v[184:187], v[224:227], v[68:71]
	v_mfma_f32_16x16x32_bf16 v[64:67], v[192:195], v[224:227], v[64:67]
	s_barrier
	s_add_i32 s42, s61, s94
	v_lshl_add_u64 v[144:145], v[144:145], 0, s[16:17]
	s_mov_b32 m0, s42
	ds_read_b128 v[196:199], v159 offset:49152
	ds_read_b128 v[200:203], v159 offset:50176
	ds_read_b128 v[204:207], v159 offset:51200
	ds_read_b128 v[208:211], v159 offset:52224
	ds_read_b128 v[212:215], v159 offset:53248
	ds_read_b128 v[216:219], v159 offset:54272
	ds_read_b128 v[220:223], v159 offset:55296
	ds_read_b128 v[224:227], v159 offset:56320
	global_load_lds_dwordx4 v[144:145], off
	s_add_i32 m0, s42, 0x2000
	s_add_u32 s40, s40, 0x40080
	v_lshl_add_u64 v[144:145], v[148:149], 0, s[16:17]
	s_addc_u32 s41, s41, 0
	s_add_i32 s42, s62, s94
	global_load_lds_dwordx4 v[144:145], off
	v_lshl_add_u64 v[144:145], s[40:41], 0, v[132:133]
	s_mov_b32 m0, s42
	s_nop 0
	global_load_lds_dwordx4 v[144:145], off
	v_lshl_add_u64 v[144:145], s[40:41], 0, v[128:129]
	s_add_i32 m0, s42, 0x2000
	s_nop 0
	global_load_lds_dwordx4 v[144:145], off
	v_lshl_add_u64 v[144:145], v[152:153], 0, s[16:17]
	s_mov_b32 m0, s51
	s_nop 0
	global_load_lds_dwordx4 v[144:145], off
	v_lshl_add_u64 v[144:145], v[156:157], 0, s[16:17]
	s_mov_b32 m0, s52
	s_nop 0
	global_load_lds_dwordx4 v[144:145], off
	s_waitcnt vmcnt(8)
	s_waitcnt lgkmcnt(0)
	s_barrier
	v_mfma_f32_16x16x32_bf16 v[60:63], v[164:167], v[196:199], v[60:63]
	v_mfma_f32_16x16x32_bf16 v[56:59], v[172:175], v[196:199], v[56:59]
	v_mfma_f32_16x16x32_bf16 v[44:47], v[164:167], v[204:207], v[44:47]
	v_mfma_f32_16x16x32_bf16 v[40:43], v[172:175], v[204:207], v[40:43]
	v_mfma_f32_16x16x32_bf16 v[28:31], v[164:167], v[212:215], v[28:31]
	v_mfma_f32_16x16x32_bf16 v[24:27], v[172:175], v[212:215], v[24:27]
	v_mfma_f32_16x16x32_bf16 v[12:15], v[164:167], v[220:223], v[12:15]
	v_mfma_f32_16x16x32_bf16 v[8:11], v[172:175], v[220:223], v[8:11]
	v_mfma_f32_16x16x32_bf16 v[60:63], v[168:171], v[200:203], v[60:63]
	v_mfma_f32_16x16x32_bf16 v[56:59], v[176:179], v[200:203], v[56:59]
	v_mfma_f32_16x16x32_bf16 v[44:47], v[168:171], v[208:211], v[44:47]
	v_mfma_f32_16x16x32_bf16 v[40:43], v[176:179], v[208:211], v[40:43]
	v_mfma_f32_16x16x32_bf16 v[28:31], v[168:171], v[216:219], v[28:31]
	v_mfma_f32_16x16x32_bf16 v[24:27], v[176:179], v[216:219], v[24:27]
	v_mfma_f32_16x16x32_bf16 v[12:15], v[168:171], v[224:227], v[12:15]
	v_mfma_f32_16x16x32_bf16 v[8:11], v[176:179], v[224:227], v[8:11]
	v_mfma_f32_16x16x32_bf16 v[52:55], v[180:183], v[196:199], v[52:55]
	v_mfma_f32_16x16x32_bf16 v[48:51], v[188:191], v[196:199], v[48:51]
	v_mfma_f32_16x16x32_bf16 v[36:39], v[180:183], v[204:207], v[36:39]
	v_mfma_f32_16x16x32_bf16 v[32:35], v[188:191], v[204:207], v[32:35]
	v_mfma_f32_16x16x32_bf16 v[20:23], v[180:183], v[212:215], v[20:23]
	v_mfma_f32_16x16x32_bf16 v[16:19], v[188:191], v[212:215], v[16:19]
	v_mfma_f32_16x16x32_bf16 v[4:7], v[180:183], v[220:223], v[4:7]
	v_mfma_f32_16x16x32_bf16 v[0:3], v[188:191], v[220:223], v[0:3]
	v_mfma_f32_16x16x32_bf16 v[52:55], v[184:187], v[200:203], v[52:55]
	v_mfma_f32_16x16x32_bf16 v[48:51], v[192:195], v[200:203], v[48:51]
	v_mfma_f32_16x16x32_bf16 v[36:39], v[184:187], v[208:211], v[36:39]
	v_mfma_f32_16x16x32_bf16 v[32:35], v[192:195], v[208:211], v[32:35]
	v_mfma_f32_16x16x32_bf16 v[20:23], v[184:187], v[216:219], v[20:23]
	v_mfma_f32_16x16x32_bf16 v[16:19], v[192:195], v[216:219], v[16:19]
	v_mfma_f32_16x16x32_bf16 v[4:7], v[184:187], v[224:227], v[4:7]
	v_mfma_f32_16x16x32_bf16 v[0:3], v[192:195], v[224:227], v[0:3]
	s_barrier
	s_add_i32 s60, s60, 2
	s_add_u32 s38, s38, 0x100
	s_addc_u32 s39, s39, 0
	s_add_u32 s58, s58, 0x100
	s_addc_u32 s59, s59, 0
	s_cmp_gt_u32 s60, 13
	s_cbranch_scc0 .LBB0_1336

; #define PG8_STAGE(bufoff, gbase, voff) do { _Pragma("unroll") for (int _i = 0; _i < 2; ++_i) \
;         __builtin_amdgcn_global_load_lds((const unsigned*)((const char*)(gbase) + (voff)[_i]), (LAS unsigned*)(lds + (bufoff) + ldsw + _i * 8192), 16, 0, 0); } while (0)
; #define PG8_LDA(dst, b, h) do { _Pragma("unroll") for (int m = 0; m < 4; ++m) _Pragma("unroll") for (int k = 0; k < 2; ++k) dst[m][k] = *(const LAS bf16x8*)(lds + PG8_SA(b, h) + aoff + m * 2048 + k * 1024); } while (0)
; #define PG8_LDB(dst, b, h) do { _Pragma("unroll") for (int n = 0; n < 2; ++n) _Pragma("unroll") for (int k = 0; k < 2; ++k) dst[n][k] = *(const LAS bf16x8*)(lds + PG8_SB(b, h) + boff + n * 2048 + k * 1024); } while (0)
; #define PG8_MMA(ai, bj, At, Bt) do { __builtin_amdgcn_s_setprio(1); _Pragma("unroll") for (int m = 0; m < 4; ++m) _Pragma("unroll") for (int n = 0; n < 2; ++n) _Pragma("unroll") for (int k = 0; k < 2; ++k) \
;         acc[ai][bj][m][n] = __builtin_amdgcn_mfma_f32_16x16x32_bf16(Bt[n][k], At[m][k], acc[ai][bj][m][n], 0, 0, 0); __builtin_amdgcn_s_setprio(0); } while (0)
; #define PG8_WAIT_V(n) asm volatile("s_waitcnt vmcnt(" #n ")" ::: "memory")
; #define PG8_WAIT_L(n) asm volatile("s_waitcnt lgkmcnt(" #n ")" ::: "memory")
; #define PG8_BAR __builtin_amdgcn_s_barrier()
; #define PG8_SCHED __builtin_amdgcn_sched_barrier(0)
; template <class Epi>
; DI void gemm_phase(LAS unsigned char* lds, const int wid, const Gemm g, const Order& S, const Epi& E) {
;     ...
;         for (int t = 0; t < nt; t += 2) {
;             const bool last = (t == nt - 2);
;             const char* a1 = cA + (size_t)(t + 1) * kstep;
;             const char* a2 = last ? nA : cA + (size_t)(t + 2) * kstep; const char* b2 = last ? nB : cB + (size_t)(t + 2) * kstep;
;             const char* a3 = a2 + kstep; const char* b3 = b2 + kstep;
;             PG8_LDB(B0, 0, 0); PG8_LDB(B1, 0, 1); PG8_SCHED; PG8_LDA(At, 0, 0); PG8_STAGE(PG8_SA(1, 1), a1 + hstepA, voffA);
;             PG8_WAIT_V(8); PG8_WAIT_L(0); PG8_BAR; PG8_MMA(0, 0, At, B0); PG8_MMA(0, 1, At, B1); PG8_BAR; PG8_SCHED;
;             PG8_LDA(At, 0, 1); PG8_STAGE(PG8_SB(0, 0), b2, voffB); PG8_STAGE(PG8_SB(0, 1), b2 + hstepB, voffB); PG8_STAGE(PG8_SA(0, 0), a2, voffA);
;             PG8_WAIT_V(8); PG8_WAIT_L(0); PG8_BAR; PG8_MMA(1, 0, At, B0); PG8_MMA(1, 1, At, B1); PG8_BAR; PG8_SCHED;
.LBB0_1420:
	s_add_u32 s56, s38, 0x100
	v_mov_b32_e32 v0, 0
	s_addc_u32 s57, s39, 0
	s_mov_b32 s58, -2
	s_waitcnt lgkmcnt(0)
	ds_read_b128 v[128:131], v216
	ds_read_b128 v[132:135], v216 offset:1024
	ds_read_b128 v[136:139], v216 offset:2048
	ds_read_b128 v[140:143], v216 offset:3072
	ds_read_b128 v[144:147], v217
	ds_read_b128 v[148:151], v217 offset:1024
	ds_read_b128 v[152:155], v217 offset:2048
	ds_read_b128 v[156:159], v217 offset:3072
	s_add_u32 s10, s36, 0x100
	s_addc_u32 s11, s37, 0
	s_cmp_eq_u32 s58, 40
	s_cselect_b32 s41, s31, s11
	s_cselect_b32 s40, s30, s10
	s_cselect_b32 s39, s35, s57
	s_cselect_b32 s38, s34, s56
	v_lshl_add_u64 v[208:209], s[36:37], 0, v[184:185]
	s_add_i32 m0, s43, 0xc000
	ds_read_b128 v[160:163], v218
	ds_read_b128 v[164:167], v218 offset:1024
	ds_read_b128 v[168:171], v218 offset:2048
	ds_read_b128 v[172:175], v218 offset:3072
	ds_read_b128 v[192:195], v218 offset:4096
	ds_read_b128 v[196:199], v218 offset:5120
	ds_read_b128 v[200:203], v218 offset:6144
	ds_read_b128 v[204:207], v218 offset:7168
	global_load_lds_dwordx4 v[208:209], off
	v_lshl_add_u64 v[208:209], s[36:37], 0, v[186:187]
	s_add_i32 m0, s43, 0xe000
	s_nop 0
	global_load_lds_dwordx4 v[208:209], off
	s_waitcnt vmcnt(8)
	s_waitcnt lgkmcnt(0)
	s_barrier
	v_mfma_f32_16x16x32_bf16 v[124:127], v[128:131], v[160:163], 0
	v_mfma_f32_16x16x32_bf16 v[120:123], v[136:139], v[160:163], 0
	v_mfma_f32_16x16x32_bf16 v[108:111], v[128:131], v[168:171], 0
	v_mfma_f32_16x16x32_bf16 v[104:107], v[136:139], v[168:171], 0
	v_mfma_f32_16x16x32_bf16 v[92:95], v[128:131], v[192:195], 0
	v_mfma_f32_16x16x32_bf16 v[88:91], v[136:139], v[192:195], 0
	v_mfma_f32_16x16x32_bf16 v[76:79], v[128:131], v[200:203], 0
	v_mfma_f32_16x16x32_bf16 v[72:75], v[136:139], v[200:203], 0
	v_mfma_f32_16x16x32_bf16 v[124:127], v[132:135], v[164:167], v[124:127]
	v_mfma_f32_16x16x32_bf16 v[120:123], v[140:143], v[164:167], v[120:123]
	v_mfma_f32_16x16x32_bf16 v[108:111], v[132:135], v[172:175], v[108:111]
	v_mfma_f32_16x16x32_bf16 v[104:107], v[140:143], v[172:175], v[104:107]
	v_mfma_f32_16x16x32_bf16 v[92:95], v[132:135], v[196:199], v[92:95]
	v_mfma_f32_16x16x32_bf16 v[88:91], v[140:143], v[196:199], v[88:91]
	v_mfma_f32_16x16x32_bf16 v[76:79], v[132:135], v[204:207], v[76:79]
	v_mfma_f32_16x16x32_bf16 v[72:75], v[140:143], v[204:207], v[72:75]
	v_mfma_f32_16x16x32_bf16 v[116:119], v[144:147], v[160:163], 0
	v_mfma_f32_16x16x32_bf16 v[112:115], v[152:155], v[160:163], 0
	v_mfma_f32_16x16x32_bf16 v[100:103], v[144:147], v[168:171], 0
	v_mfma_f32_16x16x32_bf16 v[96:99], v[152:155], v[168:171], 0
	v_mfma_f32_16x16x32_bf16 v[84:87], v[144:147], v[192:195], 0
	v_mfma_f32_16x16x32_bf16 v[80:83], v[152:155], v[192:195], 0
	v_mfma_f32_16x16x32_bf16 v[68:71], v[144:147], v[200:203], 0
	v_mfma_f32_16x16x32_bf16 v[64:67], v[152:155], v[200:203], 0
	v_mfma_f32_16x16x32_bf16 v[116:119], v[148:151], v[164:167], v[116:119]
	v_mfma_f32_16x16x32_bf16 v[112:115], v[156:159], v[164:167], v[112:115]
	v_mfma_f32_16x16x32_bf16 v[100:103], v[148:151], v[172:175], v[100:103]
	v_mfma_f32_16x16x32_bf16 v[96:99], v[156:159], v[172:175], v[96:99]
	v_mfma_f32_16x16x32_bf16 v[84:87], v[148:151], v[196:199], v[84:87]
	v_mfma_f32_16x16x32_bf16 v[80:83], v[156:159], v[196:199], v[80:83]
	v_mfma_f32_16x16x32_bf16 v[68:71], v[148:151], v[204:207], v[68:71]
	v_mfma_f32_16x16x32_bf16 v[64:67], v[156:159], v[204:207], v[64:67]
	s_barrier
	s_add_i32 s36, s50, s94
	v_lshl_add_u64 v[208:209], s[38:39], 0, v[178:179]
	s_mov_b32 m0, s36
	ds_read_b128 v[160:163], v218 offset:16384
	ds_read_b128 v[164:167], v218 offset:17408
	ds_read_b128 v[168:171], v218 offset:18432
	ds_read_b128 v[172:175], v218 offset:19456
	ds_read_b128 v[192:195], v218 offset:20480
	ds_read_b128 v[196:199], v218 offset:21504
	ds_read_b128 v[200:203], v218 offset:22528
	ds_read_b128 v[204:207], v218 offset:23552
	global_load_lds_dwordx4 v[208:209], off
	s_add_i32 m0, s36, 0x2000
	s_add_u32 s36, s38, 0xb0000
	v_lshl_add_u64 v[210:211], s[38:39], 0, v[182:183]
	s_addc_u32 s37, s39, 0
	s_add_i32 s59, s51, s94
	global_load_lds_dwordx4 v[210:211], off
	v_lshl_add_u64 v[212:213], s[36:37], 0, v[178:179]
	s_mov_b32 m0, s59
	v_lshl_add_u64 v[220:221], s[40:41], 0, v[180:181]
	global_load_lds_dwordx4 v[212:213], off
	v_lshl_add_u64 v[212:213], s[36:37], 0, v[182:183]
	s_add_i32 m0, s59, 0x2000
	s_nop 0
	global_load_lds_dwordx4 v[212:213], off
	v_lshl_add_u64 v[212:213], s[40:41], 0, v[176:177]
	s_mov_b32 m0, s43
	s_nop 0
	global_load_lds_dwordx4 v[212:213], off
	s_mov_b32 m0, s44
	s_nop 0
	global_load_lds_dwordx4 v[220:221], off
	s_waitcnt vmcnt(8)
	s_waitcnt lgkmcnt(0)
	s_barrier
; #define PG8_STAGE(bufoff, gbase, voff) do { _Pragma("unroll") for (int _i = 0; _i < 2; ++_i) \
;         __builtin_amdgcn_global_load_lds((const unsigned*)((const char*)(gbase) + (voff)[_i]), (LAS unsigned*)(lds + (bufoff) + ldsw + _i * 8192), 16, 0, 0); } while (0)
; #define PG8_LDA(dst, b, h) do { _Pragma("unroll") for (int m = 0; m < 4; ++m) _Pragma("unroll") for (int k = 0; k < 2; ++k) dst[m][k] = *(const LAS bf16x8*)(lds + PG8_SA(b, h) + aoff + m * 2048 + k * 1024); } while (0)
; #define PG8_LDB(dst, b, h) do { _Pragma("unroll") for (int n = 0; n < 2; ++n) _Pragma("unroll") for (int k = 0; k < 2; ++k) dst[n][k] = *(const LAS bf16x8*)(lds + PG8_SB(b, h) + boff + n * 2048 + k * 1024); } while (0)
; #define PG8_MMA(ai, bj, At, Bt) do { __builtin_amdgcn_s_setprio(1); _Pragma("unroll") for (int m = 0; m < 4; ++m) _Pragma("unroll") for (int n = 0; n < 2; ++n) _Pragma("unroll") for (int k = 0; k < 2; ++k) \
;         acc[ai][bj][m][n] = __builtin_amdgcn_mfma_f32_16x16x32_bf16(Bt[n][k], At[m][k], acc[ai][bj][m][n], 0, 0, 0); __builtin_amdgcn_s_setprio(0); } while (0)
; #define PG8_WAIT_V(n) asm volatile("s_waitcnt vmcnt(" #n ")" ::: "memory")
; #define PG8_WAIT_L(n) asm volatile("s_waitcnt lgkmcnt(" #n ")" ::: "memory")
; template <class Epi>
; DI void gemm_phase(LAS unsigned char* lds, const int wid, const Gemm g, const Order& S, const Epi& E) {
;     ...
;             PG8_LDB(B0, 0, 0); PG8_LDB(B1, 0, 1); PG8_SCHED; PG8_LDA(At, 0, 0); PG8_STAGE(PG8_SA(1, 1), a1 + hstepA, voffA);
;             PG8_WAIT_V(8); PG8_WAIT_L(0); PG8_BAR; PG8_MMA(0, 0, At, B0); PG8_MMA(0, 1, At, B1); PG8_BAR; PG8_SCHED;
;             PG8_LDA(At, 0, 1); PG8_STAGE(PG8_SB(0, 0), b2, voffB); PG8_STAGE(PG8_SB(0, 1), b2 + hstepB, voffB); PG8_STAGE(PG8_SA(0, 0), a2, voffA);
;             PG8_WAIT_V(8); PG8_WAIT_L(0); PG8_BAR; PG8_MMA(1, 0, At, B0); PG8_MMA(1, 1, At, B1); PG8_BAR; PG8_SCHED;
;             PG8_LDB(B0, 1, 0); PG8_LDB(B1, 1, 1); PG8_SCHED; PG8_LDA(At, 1, 0); PG8_STAGE(PG8_SA(0, 1), a2 + hstepA, voffA);
;             PG8_WAIT_V(8); PG8_WAIT_L(0); PG8_BAR; PG8_MMA(0, 0, At, B0); PG8_MMA(0, 1, At, B1); PG8_BAR; PG8_SCHED;
;             PG8_LDA(At, 1, 1); PG8_STAGE(PG8_SB(1, 0), b3, voffB); PG8_STAGE(PG8_SB(1, 1), b3 + hstepB, voffB); PG8_STAGE(PG8_SA(1, 0), a3, voffA);
;             PG8_WAIT_V(8); PG8_WAIT_L(0); PG8_BAR; PG8_MMA(1, 0, At, B0); PG8_MMA(1, 1, At, B1); PG8_BAR; PG8_SCHED;
	v_mfma_f32_16x16x32_bf16 v[60:63], v[128:131], v[160:163], 0
	v_mfma_f32_16x16x32_bf16 v[56:59], v[136:139], v[160:163], 0
	v_mfma_f32_16x16x32_bf16 v[44:47], v[128:131], v[168:171], 0
	v_mfma_f32_16x16x32_bf16 v[40:43], v[136:139], v[168:171], 0
	v_mfma_f32_16x16x32_bf16 v[28:31], v[128:131], v[192:195], 0
	v_mfma_f32_16x16x32_bf16 v[24:27], v[136:139], v[192:195], 0
	v_mfma_f32_16x16x32_bf16 v[12:15], v[128:131], v[200:203], 0
	v_mfma_f32_16x16x32_bf16 v[8:11], v[136:139], v[200:203], 0
	v_mfma_f32_16x16x32_bf16 v[60:63], v[132:135], v[164:167], v[60:63]
	v_mfma_f32_16x16x32_bf16 v[56:59], v[140:143], v[164:167], v[56:59]
	v_mfma_f32_16x16x32_bf16 v[44:47], v[132:135], v[172:175], v[44:47]
	v_mfma_f32_16x16x32_bf16 v[40:43], v[140:143], v[172:175], v[40:43]
	v_mfma_f32_16x16x32_bf16 v[28:31], v[132:135], v[196:199], v[28:31]
	v_mfma_f32_16x16x32_bf16 v[24:27], v[140:143], v[196:199], v[24:27]
	v_mfma_f32_16x16x32_bf16 v[12:15], v[132:135], v[204:207], v[12:15]
	v_mfma_f32_16x16x32_bf16 v[8:11], v[140:143], v[204:207], v[8:11]
	v_mfma_f32_16x16x32_bf16 v[52:55], v[144:147], v[160:163], 0
	v_mfma_f32_16x16x32_bf16 v[48:51], v[152:155], v[160:163], 0
	v_mfma_f32_16x16x32_bf16 v[36:39], v[144:147], v[168:171], 0
	v_mfma_f32_16x16x32_bf16 v[32:35], v[152:155], v[168:171], 0
	v_mfma_f32_16x16x32_bf16 v[20:23], v[144:147], v[192:195], 0
	v_mfma_f32_16x16x32_bf16 v[16:19], v[152:155], v[192:195], 0
	v_mfma_f32_16x16x32_bf16 v[4:7], v[144:147], v[200:203], 0
	v_mfma_f32_16x16x32_bf16 v[0:3], v[152:155], v[200:203], 0
	v_mfma_f32_16x16x32_bf16 v[52:55], v[148:151], v[164:167], v[52:55]
	v_mfma_f32_16x16x32_bf16 v[48:51], v[156:159], v[164:167], v[48:51]
	v_mfma_f32_16x16x32_bf16 v[36:39], v[148:151], v[172:175], v[36:39]
	v_mfma_f32_16x16x32_bf16 v[32:35], v[156:159], v[172:175], v[32:35]
	v_mfma_f32_16x16x32_bf16 v[20:23], v[148:151], v[196:199], v[20:23]
	v_mfma_f32_16x16x32_bf16 v[16:19], v[156:159], v[196:199], v[16:19]
	v_mfma_f32_16x16x32_bf16 v[4:7], v[148:151], v[204:207], v[4:7]
	v_mfma_f32_16x16x32_bf16 v[0:3], v[156:159], v[204:207], v[0:3]
	s_barrier
	s_add_i32 s59, 0, 0x18000
	s_add_i32 s60, 0, 0x1c000
	v_add_u32_e32 v140, s59, v215
	v_add_u32_e32 v156, s60, v215
	ds_read_b128 v[128:131], v140
	ds_read_b128 v[132:135], v140 offset:1024
	ds_read_b128 v[136:139], v140 offset:2048
	ds_read_b128 v[140:143], v140 offset:3072
	ds_read_b128 v[144:147], v156
	ds_read_b128 v[148:151], v156 offset:1024
	ds_read_b128 v[152:155], v156 offset:2048
	ds_read_b128 v[156:159], v156 offset:3072
	s_add_u32 s36, s40, 0xb0000
	s_addc_u32 s37, s41, 0
	s_mov_b32 m0, s45
	v_lshl_add_u64 v[222:223], s[36:37], 0, v[176:177]
	ds_read_b128 v[160:163], v218 offset:32768
	ds_read_b128 v[164:167], v218 offset:33792
	ds_read_b128 v[168:171], v218 offset:34816
	ds_read_b128 v[172:175], v218 offset:35840
	ds_read_b128 v[192:195], v218 offset:36864
	ds_read_b128 v[196:199], v218 offset:37888
	ds_read_b128 v[200:203], v218 offset:38912
	ds_read_b128 v[204:207], v218 offset:39936
	global_load_lds_dwordx4 v[222:223], off
	v_lshl_add_u64 v[222:223], s[36:37], 0, v[180:181]
	s_mov_b32 m0, s46
	s_nop 0
	global_load_lds_dwordx4 v[222:223], off
	s_waitcnt vmcnt(8)
	s_waitcnt lgkmcnt(0)
	s_barrier
	v_mfma_f32_16x16x32_bf16 v[124:127], v[128:131], v[160:163], v[124:127]
	v_mfma_f32_16x16x32_bf16 v[120:123], v[136:139], v[160:163], v[120:123]
	v_mfma_f32_16x16x32_bf16 v[108:111], v[128:131], v[168:171], v[108:111]
	v_mfma_f32_16x16x32_bf16 v[104:107], v[136:139], v[168:171], v[104:107]
	v_mfma_f32_16x16x32_bf16 v[92:95], v[128:131], v[192:195], v[92:95]
	v_mfma_f32_16x16x32_bf16 v[88:91], v[136:139], v[192:195], v[88:91]
	v_mfma_f32_16x16x32_bf16 v[76:79], v[128:131], v[200:203], v[76:79]
	v_mfma_f32_16x16x32_bf16 v[72:75], v[136:139], v[200:203], v[72:75]
	v_mfma_f32_16x16x32_bf16 v[124:127], v[132:135], v[164:167], v[124:127]
	v_mfma_f32_16x16x32_bf16 v[120:123], v[140:143], v[164:167], v[120:123]
	v_mfma_f32_16x16x32_bf16 v[108:111], v[132:135], v[172:175], v[108:111]
	v_mfma_f32_16x16x32_bf16 v[104:107], v[140:143], v[172:175], v[104:107]
	v_mfma_f32_16x16x32_bf16 v[92:95], v[132:135], v[196:199], v[92:95]
	v_mfma_f32_16x16x32_bf16 v[88:91], v[140:143], v[196:199], v[88:91]
	v_mfma_f32_16x16x32_bf16 v[76:79], v[132:135], v[204:207], v[76:79]
	v_mfma_f32_16x16x32_bf16 v[72:75], v[140:143], v[204:207], v[72:75]
	v_mfma_f32_16x16x32_bf16 v[116:119], v[144:147], v[160:163], v[116:119]
	v_mfma_f32_16x16x32_bf16 v[112:115], v[152:155], v[160:163], v[112:115]
	v_mfma_f32_16x16x32_bf16 v[100:103], v[144:147], v[168:171], v[100:103]
	v_mfma_f32_16x16x32_bf16 v[96:99], v[152:155], v[168:171], v[96:99]
	v_mfma_f32_16x16x32_bf16 v[84:87], v[144:147], v[192:195], v[84:87]
	v_mfma_f32_16x16x32_bf16 v[80:83], v[152:155], v[192:195], v[80:83]
	v_mfma_f32_16x16x32_bf16 v[68:71], v[144:147], v[200:203], v[68:71]
	v_mfma_f32_16x16x32_bf16 v[64:67], v[152:155], v[200:203], v[64:67]
	v_mfma_f32_16x16x32_bf16 v[116:119], v[148:151], v[164:167], v[116:119]
	v_mfma_f32_16x16x32_bf16 v[112:115], v[156:159], v[164:167], v[112:115]
	v_mfma_f32_16x16x32_bf16 v[100:103], v[148:151], v[172:175], v[100:103]
	v_mfma_f32_16x16x32_bf16 v[96:99], v[156:159], v[172:175], v[96:99]
	v_mfma_f32_16x16x32_bf16 v[84:87], v[148:151], v[196:199], v[84:87]
	v_mfma_f32_16x16x32_bf16 v[80:83], v[156:159], v[196:199], v[80:83]
	v_mfma_f32_16x16x32_bf16 v[68:71], v[148:151], v[204:207], v[68:71]
	v_mfma_f32_16x16x32_bf16 v[64:67], v[156:159], v[204:207], v[64:67]
	s_barrier
; #define PG8_STAGE(bufoff, gbase, voff) do { _Pragma("unroll") for (int _i = 0; _i < 2; ++_i) \
;         __builtin_amdgcn_global_load_lds((const unsigned*)((const char*)(gbase) + (voff)[_i]), (LAS unsigned*)(lds + (bufoff) + ldsw + _i * 8192), 16, 0, 0); } while (0)
; #define PG8_LDA(dst, b, h) do { _Pragma("unroll") for (int m = 0; m < 4; ++m) _Pragma("unroll") for (int k = 0; k < 2; ++k) dst[m][k] = *(const LAS bf16x8*)(lds + PG8_SA(b, h) + aoff + m * 2048 + k * 1024); } while (0)
; #define PG8_LDB(dst, b, h) do { _Pragma("unroll") for (int n = 0; n < 2; ++n) _Pragma("unroll") for (int k = 0; k < 2; ++k) dst[n][k] = *(const LAS bf16x8*)(lds + PG8_SB(b, h) + boff + n * 2048 + k * 1024); } while (0)
; #define PG8_WAIT_V(n) asm volatile("s_waitcnt vmcnt(" #n ")" ::: "memory")
; #define PG8_WAIT_L(n) asm volatile("s_waitcnt lgkmcnt(" #n ")" ::: "memory")
; template <class Epi>
; DI void gemm_phase(LAS unsigned char* lds, const int wid, const Gemm g, const Order& S, const Epi& E) {
;     ...
;         for (int t = 0; t < nt; t += 2) {
;             const bool last = (t == nt - 2);
;             const char* a1 = cA + (size_t)(t + 1) * kstep;
;             const char* a2 = last ? nA : cA + (size_t)(t + 2) * kstep; const char* b2 = last ? nB : cB + (size_t)(t + 2) * kstep;
;             const char* a3 = a2 + kstep; const char* b3 = b2 + kstep;
;             PG8_LDB(B0, 0, 0); PG8_LDB(B1, 0, 1); PG8_SCHED; PG8_LDA(At, 0, 0); PG8_STAGE(PG8_SA(1, 1), a1 + hstepA, voffA);
;             PG8_WAIT_V(8); PG8_WAIT_L(0); PG8_BAR; PG8_MMA(0, 0, At, B0); PG8_MMA(0, 1, At, B1); PG8_BAR; PG8_SCHED;
;             PG8_LDA(At, 0, 1); PG8_STAGE(PG8_SB(0, 0), b2, voffB); PG8_STAGE(PG8_SB(0, 1), b2 + hstepB, voffB); PG8_STAGE(PG8_SA(0, 0), a2, voffA);
;             PG8_WAIT_V(8); PG8_WAIT_L(0); PG8_BAR; PG8_MMA(1, 0, At, B0); PG8_MMA(1, 1, At, B1); PG8_BAR; PG8_SCHED;
;             PG8_LDB(B0, 1, 0); PG8_LDB(B1, 1, 1); PG8_SCHED; PG8_LDA(At, 1, 0); PG8_STAGE(PG8_SA(0, 1), a2 + hstepA, voffA);
;             PG8_WAIT_V(8); PG8_WAIT_L(0); PG8_BAR; PG8_MMA(0, 0, At, B0); PG8_MMA(0, 1, At, B1); PG8_BAR; PG8_SCHED;
;             PG8_LDA(At, 1, 1); PG8_STAGE(PG8_SB(1, 0), b3, voffB); PG8_STAGE(PG8_SB(1, 1), b3 + hstepB, voffB); PG8_STAGE(PG8_SA(1, 0), a3, voffA);
;             PG8_WAIT_V(8); PG8_WAIT_L(0); PG8_BAR; PG8_MMA(1, 0, At, B0); PG8_MMA(1, 1, At, B1); PG8_BAR; PG8_SCHED;
	s_add_i32 s36, s59, s94
	v_lshl_add_u64 v[208:209], v[208:209], 0, s[26:27]
	s_mov_b32 m0, s36
	ds_read_b128 v[160:163], v218 offset:49152
	ds_read_b128 v[164:167], v218 offset:50176
	ds_read_b128 v[168:171], v218 offset:51200
	ds_read_b128 v[172:175], v218 offset:52224
	ds_read_b128 v[192:195], v218 offset:53248
	ds_read_b128 v[196:199], v218 offset:54272
	ds_read_b128 v[200:203], v218 offset:55296
	ds_read_b128 v[204:207], v218 offset:56320
	global_load_lds_dwordx4 v[208:209], off
	s_add_i32 m0, s36, 0x2000
	s_add_u32 s36, s38, 0xb0080
	v_lshl_add_u64 v[208:209], v[210:211], 0, s[26:27]
	s_addc_u32 s37, s39, 0
	s_add_i32 s38, s60, s94
	global_load_lds_dwordx4 v[208:209], off
	v_lshl_add_u64 v[208:209], s[36:37], 0, v[178:179]
	s_mov_b32 m0, s38
	s_nop 0
	global_load_lds_dwordx4 v[208:209], off
	v_lshl_add_u64 v[208:209], s[36:37], 0, v[182:183]
	s_add_i32 m0, s38, 0x2000
	s_nop 0
	global_load_lds_dwordx4 v[208:209], off
	v_lshl_add_u64 v[208:209], v[212:213], 0, s[26:27]
	s_mov_b32 m0, s48
	s_nop 0
	global_load_lds_dwordx4 v[208:209], off
	v_lshl_add_u64 v[208:209], v[220:221], 0, s[26:27]
	s_mov_b32 m0, s49
	s_nop 0
	global_load_lds_dwordx4 v[208:209], off
	s_waitcnt vmcnt(8)
	s_waitcnt lgkmcnt(0)
	s_barrier
	v_mfma_f32_16x16x32_bf16 v[60:63], v[128:131], v[160:163], v[60:63]
	v_mfma_f32_16x16x32_bf16 v[56:59], v[136:139], v[160:163], v[56:59]
	v_mfma_f32_16x16x32_bf16 v[44:47], v[128:131], v[168:171], v[44:47]
	v_mfma_f32_16x16x32_bf16 v[40:43], v[136:139], v[168:171], v[40:43]
	v_mfma_f32_16x16x32_bf16 v[28:31], v[128:131], v[192:195], v[28:31]
	v_mfma_f32_16x16x32_bf16 v[24:27], v[136:139], v[192:195], v[24:27]
	v_mfma_f32_16x16x32_bf16 v[12:15], v[128:131], v[200:203], v[12:15]
	v_mfma_f32_16x16x32_bf16 v[8:11], v[136:139], v[200:203], v[8:11]
	v_mfma_f32_16x16x32_bf16 v[60:63], v[132:135], v[164:167], v[60:63]
	v_mfma_f32_16x16x32_bf16 v[56:59], v[140:143], v[164:167], v[56:59]
	v_mfma_f32_16x16x32_bf16 v[44:47], v[132:135], v[172:175], v[44:47]
	v_mfma_f32_16x16x32_bf16 v[40:43], v[140:143], v[172:175], v[40:43]
	v_mfma_f32_16x16x32_bf16 v[28:31], v[132:135], v[196:199], v[28:31]
	v_mfma_f32_16x16x32_bf16 v[24:27], v[140:143], v[196:199], v[24:27]
	v_mfma_f32_16x16x32_bf16 v[12:15], v[132:135], v[204:207], v[12:15]
	v_mfma_f32_16x16x32_bf16 v[8:11], v[140:143], v[204:207], v[8:11]
	v_mfma_f32_16x16x32_bf16 v[52:55], v[144:147], v[160:163], v[52:55]
	v_mfma_f32_16x16x32_bf16 v[48:51], v[152:155], v[160:163], v[48:51]
	v_mfma_f32_16x16x32_bf16 v[36:39], v[144:147], v[168:171], v[36:39]
	v_mfma_f32_16x16x32_bf16 v[32:35], v[152:155], v[168:171], v[32:35]
	v_mfma_f32_16x16x32_bf16 v[20:23], v[144:147], v[192:195], v[20:23]
	v_mfma_f32_16x16x32_bf16 v[16:19], v[152:155], v[192:195], v[16:19]
	v_mfma_f32_16x16x32_bf16 v[4:7], v[144:147], v[200:203], v[4:7]
	v_mfma_f32_16x16x32_bf16 v[0:3], v[152:155], v[200:203], v[0:3]
	v_mfma_f32_16x16x32_bf16 v[52:55], v[148:151], v[164:167], v[52:55]
	v_mfma_f32_16x16x32_bf16 v[48:51], v[156:159], v[164:167], v[48:51]
	v_mfma_f32_16x16x32_bf16 v[36:39], v[148:151], v[172:175], v[36:39]
	v_mfma_f32_16x16x32_bf16 v[32:35], v[156:159], v[172:175], v[32:35]
	v_mfma_f32_16x16x32_bf16 v[20:23], v[148:151], v[196:199], v[20:23]
	v_mfma_f32_16x16x32_bf16 v[16:19], v[156:159], v[196:199], v[16:19]
	v_mfma_f32_16x16x32_bf16 v[4:7], v[148:151], v[204:207], v[4:7]
	v_mfma_f32_16x16x32_bf16 v[0:3], v[156:159], v[204:207], v[0:3]
	s_barrier
	s_add_i32 s58, s58, 2
	s_add_u32 s56, s56, 0x100
	s_addc_u32 s57, s57, 0
	s_cmp_gt_u32 s58, 41
	s_mov_b64 s[36:37], s[10:11]
	s_cbranch_scc0 .LBB0_1421
	s_branch .Lpeel_exit_10
.LBB0_1421:
	ds_read_b128 v[128:131], v216
	ds_read_b128 v[132:135], v216 offset:1024
	ds_read_b128 v[136:139], v216 offset:2048
	ds_read_b128 v[140:143], v216 offset:3072
	ds_read_b128 v[144:147], v217
	ds_read_b128 v[148:151], v217 offset:1024
	ds_read_b128 v[152:155], v217 offset:2048
	ds_read_b128 v[156:159], v217 offset:3072
	s_add_u32 s10, s36, 0x100
	s_addc_u32 s11, s37, 0
	s_cmp_eq_u32 s58, 40
	s_cselect_b32 s41, s31, s11
	s_cselect_b32 s40, s30, s10
	s_cselect_b32 s39, s35, s57
	s_cselect_b32 s38, s34, s56
	v_lshl_add_u64 v[208:209], s[36:37], 0, v[184:185]
	s_add_i32 m0, s43, 0xc000
	ds_read_b128 v[160:163], v218
	ds_read_b128 v[164:167], v218 offset:1024
	ds_read_b128 v[168:171], v218 offset:2048
	ds_read_b128 v[172:175], v218 offset:3072
	ds_read_b128 v[192:195], v218 offset:4096
	ds_read_b128 v[196:199], v218 offset:5120
	ds_read_b128 v[200:203], v218 offset:6144
	ds_read_b128 v[204:207], v218 offset:7168
	global_load_lds_dwordx4 v[208:209], off
	v_lshl_add_u64 v[208:209], s[36:37], 0, v[186:187]
	s_add_i32 m0, s43, 0xe000
	s_nop 0
	global_load_lds_dwordx4 v[208:209], off
	s_waitcnt vmcnt(8)
	s_waitcnt lgkmcnt(0)
	s_barrier
; #define PG8_STAGE(bufoff, gbase, voff) do { _Pragma("unroll") for (int _i = 0; _i < 2; ++_i) \
;         __builtin_amdgcn_global_load_lds((const unsigned*)((const char*)(gbase) + (voff)[_i]), (LAS unsigned*)(lds + (bufoff) + ldsw + _i * 8192), 16, 0, 0); } while (0)
; #define PG8_LDA(dst, b, h) do { _Pragma("unroll") for (int m = 0; m < 4; ++m) _Pragma("unroll") for (int k = 0; k < 2; ++k) dst[m][k] = *(const LAS bf16x8*)(lds + PG8_SA(b, h) + aoff + m * 2048 + k * 1024); } while (0)
; #define PG8_LDB(dst, b, h) do { _Pragma("unroll") for (int n = 0; n < 2; ++n) _Pragma("unroll") for (int k = 0; k < 2; ++k) dst[n][k] = *(const LAS bf16x8*)(lds + PG8_SB(b, h) + boff + n * 2048 + k * 1024); } while (0)
; #define PG8_MMA(ai, bj, At, Bt) do { __builtin_amdgcn_s_setprio(1); _Pragma("unroll") for (int m = 0; m < 4; ++m) _Pragma("unroll") for (int n = 0; n < 2; ++n) _Pragma("unroll") for (int k = 0; k < 2; ++k) \
;         acc[ai][bj][m][n] = __builtin_amdgcn_mfma_f32_16x16x32_bf16(Bt[n][k], At[m][k], acc[ai][bj][m][n], 0, 0, 0); __builtin_amdgcn_s_setprio(0); } while (0)
; #define PG8_WAIT_V(n) asm volatile("s_waitcnt vmcnt(" #n ")" ::: "memory")
; #define PG8_WAIT_L(n) asm volatile("s_waitcnt lgkmcnt(" #n ")" ::: "memory")
; #define PG8_BAR __builtin_amdgcn_s_barrier()
; #define PG8_SCHED __builtin_amdgcn_sched_barrier(0)
; template <class Epi>
; DI void gemm_phase(LAS unsigned char* lds, const int wid, const Gemm g, const Order& S, const Epi& E) {
;     ...
;             PG8_LDB(B0, 0, 0); PG8_LDB(B1, 0, 1); PG8_SCHED; PG8_LDA(At, 0, 0); PG8_STAGE(PG8_SA(1, 1), a1 + hstepA, voffA);
;             PG8_WAIT_V(8); PG8_WAIT_L(0); PG8_BAR; PG8_MMA(0, 0, At, B0); PG8_MMA(0, 1, At, B1); PG8_BAR; PG8_SCHED;
;             PG8_LDA(At, 0, 1); PG8_STAGE(PG8_SB(0, 0), b2, voffB); PG8_STAGE(PG8_SB(0, 1), b2 + hstepB, voffB); PG8_STAGE(PG8_SA(0, 0), a2, voffA);
;             PG8_WAIT_V(8); PG8_WAIT_L(0); PG8_BAR; PG8_MMA(1, 0, At, B0); PG8_MMA(1, 1, At, B1); PG8_BAR; PG8_SCHED;
;             PG8_LDB(B0, 1, 0); PG8_LDB(B1, 1, 1); PG8_SCHED; PG8_LDA(At, 1, 0); PG8_STAGE(PG8_SA(0, 1), a2 + hstepA, voffA);
;             PG8_WAIT_V(8); PG8_WAIT_L(0); PG8_BAR; PG8_MMA(0, 0, At, B0); PG8_MMA(0, 1, At, B1); PG8_BAR; PG8_SCHED;
	v_mfma_f32_16x16x32_bf16 v[124:127], v[128:131], v[160:163], v[124:127]
	v_mfma_f32_16x16x32_bf16 v[120:123], v[136:139], v[160:163], v[120:123]
	v_mfma_f32_16x16x32_bf16 v[108:111], v[128:131], v[168:171], v[108:111]
	v_mfma_f32_16x16x32_bf16 v[104:107], v[136:139], v[168:171], v[104:107]
	v_mfma_f32_16x16x32_bf16 v[92:95], v[128:131], v[192:195], v[92:95]
	v_mfma_f32_16x16x32_bf16 v[88:91], v[136:139], v[192:195], v[88:91]
	v_mfma_f32_16x16x32_bf16 v[76:79], v[128:131], v[200:203], v[76:79]
	v_mfma_f32_16x16x32_bf16 v[72:75], v[136:139], v[200:203], v[72:75]
	v_mfma_f32_16x16x32_bf16 v[124:127], v[132:135], v[164:167], v[124:127]
	v_mfma_f32_16x16x32_bf16 v[120:123], v[140:143], v[164:167], v[120:123]
	v_mfma_f32_16x16x32_bf16 v[108:111], v[132:135], v[172:175], v[108:111]
	v_mfma_f32_16x16x32_bf16 v[104:107], v[140:143], v[172:175], v[104:107]
	v_mfma_f32_16x16x32_bf16 v[92:95], v[132:135], v[196:199], v[92:95]
	v_mfma_f32_16x16x32_bf16 v[88:91], v[140:143], v[196:199], v[88:91]
	v_mfma_f32_16x16x32_bf16 v[76:79], v[132:135], v[204:207], v[76:79]
	v_mfma_f32_16x16x32_bf16 v[72:75], v[140:143], v[204:207], v[72:75]
	v_mfma_f32_16x16x32_bf16 v[116:119], v[144:147], v[160:163], v[116:119]
	v_mfma_f32_16x16x32_bf16 v[112:115], v[152:155], v[160:163], v[112:115]
	v_mfma_f32_16x16x32_bf16 v[100:103], v[144:147], v[168:171], v[100:103]
	v_mfma_f32_16x16x32_bf16 v[96:99], v[152:155], v[168:171], v[96:99]
	v_mfma_f32_16x16x32_bf16 v[84:87], v[144:147], v[192:195], v[84:87]
	v_mfma_f32_16x16x32_bf16 v[80:83], v[152:155], v[192:195], v[80:83]
	v_mfma_f32_16x16x32_bf16 v[68:71], v[144:147], v[200:203], v[68:71]
	v_mfma_f32_16x16x32_bf16 v[64:67], v[152:155], v[200:203], v[64:67]
	v_mfma_f32_16x16x32_bf16 v[116:119], v[148:151], v[164:167], v[116:119]
	v_mfma_f32_16x16x32_bf16 v[112:115], v[156:159], v[164:167], v[112:115]
	v_mfma_f32_16x16x32_bf16 v[100:103], v[148:151], v[172:175], v[100:103]
	v_mfma_f32_16x16x32_bf16 v[96:99], v[156:159], v[172:175], v[96:99]
	v_mfma_f32_16x16x32_bf16 v[84:87], v[148:151], v[196:199], v[84:87]
	v_mfma_f32_16x16x32_bf16 v[80:83], v[156:159], v[196:199], v[80:83]
	v_mfma_f32_16x16x32_bf16 v[68:71], v[148:151], v[204:207], v[68:71]
	v_mfma_f32_16x16x32_bf16 v[64:67], v[156:159], v[204:207], v[64:67]
	s_barrier
	s_add_i32 s36, s50, s94
	v_lshl_add_u64 v[208:209], s[38:39], 0, v[178:179]
	s_mov_b32 m0, s36
	ds_read_b128 v[160:163], v218 offset:16384
	ds_read_b128 v[164:167], v218 offset:17408
	ds_read_b128 v[168:171], v218 offset:18432
	ds_read_b128 v[172:175], v218 offset:19456
	ds_read_b128 v[192:195], v218 offset:20480
	ds_read_b128 v[196:199], v218 offset:21504
	ds_read_b128 v[200:203], v218 offset:22528
	ds_read_b128 v[204:207], v218 offset:23552
	global_load_lds_dwordx4 v[208:209], off
	s_add_i32 m0, s36, 0x2000
	s_add_u32 s36, s38, 0xb0000
	v_lshl_add_u64 v[210:211], s[38:39], 0, v[182:183]
	s_addc_u32 s37, s39, 0
	s_add_i32 s59, s51, s94
	global_load_lds_dwordx4 v[210:211], off
	v_lshl_add_u64 v[212:213], s[36:37], 0, v[178:179]
	s_mov_b32 m0, s59
	v_lshl_add_u64 v[220:221], s[40:41], 0, v[180:181]
	global_load_lds_dwordx4 v[212:213], off
	v_lshl_add_u64 v[212:213], s[36:37], 0, v[182:183]
	s_add_i32 m0, s59, 0x2000
	s_nop 0
	global_load_lds_dwordx4 v[212:213], off
	v_lshl_add_u64 v[212:213], s[40:41], 0, v[176:177]
	s_mov_b32 m0, s43
	s_nop 0
	global_load_lds_dwordx4 v[212:213], off
	s_mov_b32 m0, s44
	s_nop 0
	global_load_lds_dwordx4 v[220:221], off
	s_waitcnt vmcnt(8)
	s_waitcnt lgkmcnt(0)
	s_barrier
	v_mfma_f32_16x16x32_bf16 v[60:63], v[128:131], v[160:163], v[60:63]
	v_mfma_f32_16x16x32_bf16 v[56:59], v[136:139], v[160:163], v[56:59]
	v_mfma_f32_16x16x32_bf16 v[44:47], v[128:131], v[168:171], v[44:47]
	v_mfma_f32_16x16x32_bf16 v[40:43], v[136:139], v[168:171], v[40:43]
	v_mfma_f32_16x16x32_bf16 v[28:31], v[128:131], v[192:195], v[28:31]
	v_mfma_f32_16x16x32_bf16 v[24:27], v[136:139], v[192:195], v[24:27]
	v_mfma_f32_16x16x32_bf16 v[12:15], v[128:131], v[200:203], v[12:15]
	v_mfma_f32_16x16x32_bf16 v[8:11], v[136:139], v[200:203], v[8:11]
	v_mfma_f32_16x16x32_bf16 v[60:63], v[132:135], v[164:167], v[60:63]
	v_mfma_f32_16x16x32_bf16 v[56:59], v[140:143], v[164:167], v[56:59]
	v_mfma_f32_16x16x32_bf16 v[44:47], v[132:135], v[172:175], v[44:47]
	v_mfma_f32_16x16x32_bf16 v[40:43], v[140:143], v[172:175], v[40:43]
	v_mfma_f32_16x16x32_bf16 v[28:31], v[132:135], v[196:199], v[28:31]
	v_mfma_f32_16x16x32_bf16 v[24:27], v[140:143], v[196:199], v[24:27]
	v_mfma_f32_16x16x32_bf16 v[12:15], v[132:135], v[204:207], v[12:15]
	v_mfma_f32_16x16x32_bf16 v[8:11], v[140:143], v[204:207], v[8:11]
	v_mfma_f32_16x16x32_bf16 v[52:55], v[144:147], v[160:163], v[52:55]
	v_mfma_f32_16x16x32_bf16 v[48:51], v[152:155], v[160:163], v[48:51]
	v_mfma_f32_16x16x32_bf16 v[36:39], v[144:147], v[168:171], v[36:39]
	v_mfma_f32_16x16x32_bf16 v[32:35], v[152:155], v[168:171], v[32:35]
	v_mfma_f32_16x16x32_bf16 v[20:23], v[144:147], v[192:195], v[20:23]
	v_mfma_f32_16x16x32_bf16 v[16:19], v[152:155], v[192:195], v[16:19]
	v_mfma_f32_16x16x32_bf16 v[4:7], v[144:147], v[200:203], v[4:7]
	v_mfma_f32_16x16x32_bf16 v[0:3], v[152:155], v[200:203], v[0:3]
	v_mfma_f32_16x16x32_bf16 v[52:55], v[148:151], v[164:167], v[52:55]
	v_mfma_f32_16x16x32_bf16 v[48:51], v[156:159], v[164:167], v[48:51]
	v_mfma_f32_16x16x32_bf16 v[36:39], v[148:151], v[172:175], v[36:39]
	v_mfma_f32_16x16x32_bf16 v[32:35], v[156:159], v[172:175], v[32:35]
	v_mfma_f32_16x16x32_bf16 v[20:23], v[148:151], v[196:199], v[20:23]
	v_mfma_f32_16x16x32_bf16 v[16:19], v[156:159], v[196:199], v[16:19]
	v_mfma_f32_16x16x32_bf16 v[4:7], v[148:151], v[204:207], v[4:7]
	v_mfma_f32_16x16x32_bf16 v[0:3], v[156:159], v[204:207], v[0:3]
	s_barrier
; #define PG8_STAGE(bufoff, gbase, voff) do { _Pragma("unroll") for (int _i = 0; _i < 2; ++_i) \
;         __builtin_amdgcn_global_load_lds((const unsigned*)((const char*)(gbase) + (voff)[_i]), (LAS unsigned*)(lds + (bufoff) + ldsw + _i * 8192), 16, 0, 0); } while (0)
; #define PG8_LDA(dst, b, h) do { _Pragma("unroll") for (int m = 0; m < 4; ++m) _Pragma("unroll") for (int k = 0; k < 2; ++k) dst[m][k] = *(const LAS bf16x8*)(lds + PG8_SA(b, h) + aoff + m * 2048 + k * 1024); } while (0)
; #define PG8_LDB(dst, b, h) do { _Pragma("unroll") for (int n = 0; n < 2; ++n) _Pragma("unroll") for (int k = 0; k < 2; ++k) dst[n][k] = *(const LAS bf16x8*)(lds + PG8_SB(b, h) + boff + n * 2048 + k * 1024); } while (0)
; #define PG8_MMA(ai, bj, At, Bt) do { __builtin_amdgcn_s_setprio(1); _Pragma("unroll") for (int m = 0; m < 4; ++m) _Pragma("unroll") for (int n = 0; n < 2; ++n) _Pragma("unroll") for (int k = 0; k < 2; ++k) \
;         acc[ai][bj][m][n] = __builtin_amdgcn_mfma_f32_16x16x32_bf16(Bt[n][k], At[m][k], acc[ai][bj][m][n], 0, 0, 0); __builtin_amdgcn_s_setprio(0); } while (0)
; #define PG8_WAIT_V(n) asm volatile("s_waitcnt vmcnt(" #n ")" ::: "memory")
; #define PG8_WAIT_L(n) asm volatile("s_waitcnt lgkmcnt(" #n ")" ::: "memory")
; #define PG8_BAR __builtin_amdgcn_s_barrier()
; #define PG8_SCHED __builtin_amdgcn_sched_barrier(0)
; template <class Epi>
; DI void gemm_phase(LAS unsigned char* lds, const int wid, const Gemm g, const Order& S, const Epi& E) {
;     ...
;         for (int t = 0; t < nt; t += 2) {
;             const bool last = (t == nt - 2);
;     ...
;             PG8_LDB(B0, 1, 0); PG8_LDB(B1, 1, 1); PG8_SCHED; PG8_LDA(At, 1, 0); PG8_STAGE(PG8_SA(0, 1), a2 + hstepA, voffA);
;             PG8_WAIT_V(8); PG8_WAIT_L(0); PG8_BAR; PG8_MMA(0, 0, At, B0); PG8_MMA(0, 1, At, B1); PG8_BAR; PG8_SCHED;
;             PG8_LDA(At, 1, 1); PG8_STAGE(PG8_SB(1, 0), b3, voffB); PG8_STAGE(PG8_SB(1, 1), b3 + hstepB, voffB); PG8_STAGE(PG8_SA(1, 0), a3, voffA);
;             PG8_WAIT_V(8); PG8_WAIT_L(0); PG8_BAR; PG8_MMA(1, 0, At, B0); PG8_MMA(1, 1, At, B1); PG8_BAR; PG8_SCHED;
	s_add_i32 s59, 0, 0x18000
	s_add_i32 s60, 0, 0x1c000
	v_add_u32_e32 v140, s59, v215
	v_add_u32_e32 v156, s60, v215
	ds_read_b128 v[128:131], v140
	ds_read_b128 v[132:135], v140 offset:1024
	ds_read_b128 v[136:139], v140 offset:2048
	ds_read_b128 v[140:143], v140 offset:3072
	ds_read_b128 v[144:147], v156
	ds_read_b128 v[148:151], v156 offset:1024
	ds_read_b128 v[152:155], v156 offset:2048
	ds_read_b128 v[156:159], v156 offset:3072
	s_add_u32 s36, s40, 0xb0000
	s_addc_u32 s37, s41, 0
	s_mov_b32 m0, s45
	v_lshl_add_u64 v[222:223], s[36:37], 0, v[176:177]
	ds_read_b128 v[160:163], v218 offset:32768
	ds_read_b128 v[164:167], v218 offset:33792
	ds_read_b128 v[168:171], v218 offset:34816
	ds_read_b128 v[172:175], v218 offset:35840
	ds_read_b128 v[192:195], v218 offset:36864
	ds_read_b128 v[196:199], v218 offset:37888
	ds_read_b128 v[200:203], v218 offset:38912
	ds_read_b128 v[204:207], v218 offset:39936
	global_load_lds_dwordx4 v[222:223], off
	v_lshl_add_u64 v[222:223], s[36:37], 0, v[180:181]
	s_mov_b32 m0, s46
	s_nop 0
	global_load_lds_dwordx4 v[222:223], off
	s_waitcnt vmcnt(8)
	s_waitcnt lgkmcnt(0)
	s_barrier
	v_mfma_f32_16x16x32_bf16 v[124:127], v[128:131], v[160:163], v[124:127]
	v_mfma_f32_16x16x32_bf16 v[120:123], v[136:139], v[160:163], v[120:123]
	v_mfma_f32_16x16x32_bf16 v[108:111], v[128:131], v[168:171], v[108:111]
	v_mfma_f32_16x16x32_bf16 v[104:107], v[136:139], v[168:171], v[104:107]
	v_mfma_f32_16x16x32_bf16 v[92:95], v[128:131], v[192:195], v[92:95]
	v_mfma_f32_16x16x32_bf16 v[88:91], v[136:139], v[192:195], v[88:91]
	v_mfma_f32_16x16x32_bf16 v[76:79], v[128:131], v[200:203], v[76:79]
	v_mfma_f32_16x16x32_bf16 v[72:75], v[136:139], v[200:203], v[72:75]
	v_mfma_f32_16x16x32_bf16 v[124:127], v[132:135], v[164:167], v[124:127]
	v_mfma_f32_16x16x32_bf16 v[120:123], v[140:143], v[164:167], v[120:123]
	v_mfma_f32_16x16x32_bf16 v[108:111], v[132:135], v[172:175], v[108:111]
	v_mfma_f32_16x16x32_bf16 v[104:107], v[140:143], v[172:175], v[104:107]
	v_mfma_f32_16x16x32_bf16 v[92:95], v[132:135], v[196:199], v[92:95]
	v_mfma_f32_16x16x32_bf16 v[88:91], v[140:143], v[196:199], v[88:91]
	v_mfma_f32_16x16x32_bf16 v[76:79], v[132:135], v[204:207], v[76:79]
	v_mfma_f32_16x16x32_bf16 v[72:75], v[140:143], v[204:207], v[72:75]
	v_mfma_f32_16x16x32_bf16 v[116:119], v[144:147], v[160:163], v[116:119]
	v_mfma_f32_16x16x32_bf16 v[112:115], v[152:155], v[160:163], v[112:115]
	v_mfma_f32_16x16x32_bf16 v[100:103], v[144:147], v[168:171], v[100:103]
	v_mfma_f32_16x16x32_bf16 v[96:99], v[152:155], v[168:171], v[96:99]
	v_mfma_f32_16x16x32_bf16 v[84:87], v[144:147], v[192:195], v[84:87]
	v_mfma_f32_16x16x32_bf16 v[80:83], v[152:155], v[192:195], v[80:83]
	v_mfma_f32_16x16x32_bf16 v[68:71], v[144:147], v[200:203], v[68:71]
	v_mfma_f32_16x16x32_bf16 v[64:67], v[152:155], v[200:203], v[64:67]
	v_mfma_f32_16x16x32_bf16 v[116:119], v[148:151], v[164:167], v[116:119]
	v_mfma_f32_16x16x32_bf16 v[112:115], v[156:159], v[164:167], v[112:115]
	v_mfma_f32_16x16x32_bf16 v[100:103], v[148:151], v[172:175], v[100:103]
	v_mfma_f32_16x16x32_bf16 v[96:99], v[156:159], v[172:175], v[96:99]
	v_mfma_f32_16x16x32_bf16 v[84:87], v[148:151], v[196:199], v[84:87]
	v_mfma_f32_16x16x32_bf16 v[80:83], v[156:159], v[196:199], v[80:83]
	v_mfma_f32_16x16x32_bf16 v[68:71], v[148:151], v[204:207], v[68:71]
	v_mfma_f32_16x16x32_bf16 v[64:67], v[156:159], v[204:207], v[64:67]
	s_barrier
	s_add_i32 s36, s59, s94
	v_lshl_add_u64 v[208:209], v[208:209], 0, s[26:27]
	s_mov_b32 m0, s36
	ds_read_b128 v[160:163], v218 offset:49152
	ds_read_b128 v[164:167], v218 offset:50176
	ds_read_b128 v[168:171], v218 offset:51200
	ds_read_b128 v[172:175], v218 offset:52224
	ds_read_b128 v[192:195], v218 offset:53248
	ds_read_b128 v[196:199], v218 offset:54272
	ds_read_b128 v[200:203], v218 offset:55296
	ds_read_b128 v[204:207], v218 offset:56320
	global_load_lds_dwordx4 v[208:209], off
	s_add_i32 m0, s36, 0x2000
	s_add_u32 s36, s38, 0xb0080
	v_lshl_add_u64 v[208:209], v[210:211], 0, s[26:27]
	s_addc_u32 s37, s39, 0
	s_add_i32 s38, s60, s94
	global_load_lds_dwordx4 v[208:209], off
	v_lshl_add_u64 v[208:209], s[36:37], 0, v[178:179]
	s_mov_b32 m0, s38
	s_nop 0
	global_load_lds_dwordx4 v[208:209], off
	v_lshl_add_u64 v[208:209], s[36:37], 0, v[182:183]
	s_add_i32 m0, s38, 0x2000
	s_nop 0
	global_load_lds_dwordx4 v[208:209], off
	v_lshl_add_u64 v[208:209], v[212:213], 0, s[26:27]
	s_mov_b32 m0, s48
	s_nop 0
	global_load_lds_dwordx4 v[208:209], off
	v_lshl_add_u64 v[208:209], v[220:221], 0, s[26:27]
	s_mov_b32 m0, s49
	s_nop 0
	global_load_lds_dwordx4 v[208:209], off
	s_waitcnt vmcnt(8)
	s_waitcnt lgkmcnt(0)
	s_barrier
	v_mfma_f32_16x16x32_bf16 v[60:63], v[128:131], v[160:163], v[60:63]
	v_mfma_f32_16x16x32_bf16 v[56:59], v[136:139], v[160:163], v[56:59]
	v_mfma_f32_16x16x32_bf16 v[44:47], v[128:131], v[168:171], v[44:47]
	v_mfma_f32_16x16x32_bf16 v[40:43], v[136:139], v[168:171], v[40:43]
	v_mfma_f32_16x16x32_bf16 v[28:31], v[128:131], v[192:195], v[28:31]
	v_mfma_f32_16x16x32_bf16 v[24:27], v[136:139], v[192:195], v[24:27]
	v_mfma_f32_16x16x32_bf16 v[12:15], v[128:131], v[200:203], v[12:15]
	v_mfma_f32_16x16x32_bf16 v[8:11], v[136:139], v[200:203], v[8:11]
	v_mfma_f32_16x16x32_bf16 v[60:63], v[132:135], v[164:167], v[60:63]
	v_mfma_f32_16x16x32_bf16 v[56:59], v[140:143], v[164:167], v[56:59]
	v_mfma_f32_16x16x32_bf16 v[44:47], v[132:135], v[172:175], v[44:47]
	v_mfma_f32_16x16x32_bf16 v[40:43], v[140:143], v[172:175], v[40:43]
	v_mfma_f32_16x16x32_bf16 v[28:31], v[132:135], v[196:199], v[28:31]
	v_mfma_f32_16x16x32_bf16 v[24:27], v[140:143], v[196:199], v[24:27]
	v_mfma_f32_16x16x32_bf16 v[12:15], v[132:135], v[204:207], v[12:15]
	v_mfma_f32_16x16x32_bf16 v[8:11], v[140:143], v[204:207], v[8:11]
	v_mfma_f32_16x16x32_bf16 v[52:55], v[144:147], v[160:163], v[52:55]
	v_mfma_f32_16x16x32_bf16 v[48:51], v[152:155], v[160:163], v[48:51]
	v_mfma_f32_16x16x32_bf16 v[36:39], v[144:147], v[168:171], v[36:39]
	v_mfma_f32_16x16x32_bf16 v[32:35], v[152:155], v[168:171], v[32:35]
	v_mfma_f32_16x16x32_bf16 v[20:23], v[144:147], v[192:195], v[20:23]
	v_mfma_f32_16x16x32_bf16 v[16:19], v[152:155], v[192:195], v[16:19]
	v_mfma_f32_16x16x32_bf16 v[4:7], v[144:147], v[200:203], v[4:7]
	v_mfma_f32_16x16x32_bf16 v[0:3], v[152:155], v[200:203], v[0:3]
	v_mfma_f32_16x16x32_bf16 v[52:55], v[148:151], v[164:167], v[52:55]
	v_mfma_f32_16x16x32_bf16 v[48:51], v[156:159], v[164:167], v[48:51]
	v_mfma_f32_16x16x32_bf16 v[36:39], v[148:151], v[172:175], v[36:39]
	v_mfma_f32_16x16x32_bf16 v[32:35], v[156:159], v[172:175], v[32:35]
	v_mfma_f32_16x16x32_bf16 v[20:23], v[148:151], v[196:199], v[20:23]
	v_mfma_f32_16x16x32_bf16 v[16:19], v[156:159], v[196:199], v[16:19]
	v_mfma_f32_16x16x32_bf16 v[4:7], v[148:151], v[204:207], v[4:7]
	v_mfma_f32_16x16x32_bf16 v[0:3], v[156:159], v[204:207], v[0:3]
	s_barrier
	s_add_i32 s58, s58, 2
	s_add_u32 s56, s56, 0x100
	s_addc_u32 s57, s57, 0
	s_cmp_gt_u32 s58, 41
	s_mov_b64 s[36:37], s[10:11]
	s_cbranch_scc0 .LBB0_1421

; #define PG8_STAGE(bufoff, gbase, voff) do { _Pragma("unroll") for (int _i = 0; _i < 2; ++_i) \
;         __builtin_amdgcn_global_load_lds((const unsigned*)((const char*)(gbase) + (voff)[_i]), (LAS unsigned*)(lds + (bufoff) + ldsw + _i * 8192), 16, 0, 0); } while (0)
; #define PG8_LDA(dst, b, h) do { _Pragma("unroll") for (int m = 0; m < 4; ++m) _Pragma("unroll") for (int k = 0; k < 2; ++k) dst[m][k] = *(const LAS bf16x8*)(lds + PG8_SA(b, h) + aoff + m * 2048 + k * 1024); } while (0)
; #define PG8_LDB(dst, b, h) do { _Pragma("unroll") for (int n = 0; n < 2; ++n) _Pragma("unroll") for (int k = 0; k < 2; ++k) dst[n][k] = *(const LAS bf16x8*)(lds + PG8_SB(b, h) + boff + n * 2048 + k * 1024); } while (0)
; #define PG8_MMA(ai, bj, At, Bt) do { __builtin_amdgcn_s_setprio(1); _Pragma("unroll") for (int m = 0; m < 4; ++m) _Pragma("unroll") for (int n = 0; n < 2; ++n) _Pragma("unroll") for (int k = 0; k < 2; ++k) \
;         acc[ai][bj][m][n] = __builtin_amdgcn_mfma_f32_16x16x32_bf16(Bt[n][k], At[m][k], acc[ai][bj][m][n], 0, 0, 0); __builtin_amdgcn_s_setprio(0); } while (0)
; #define PG8_WAIT_V(n) asm volatile("s_waitcnt vmcnt(" #n ")" ::: "memory")
; #define PG8_WAIT_L(n) asm volatile("s_waitcnt lgkmcnt(" #n ")" ::: "memory")
; #define PG8_BAR __builtin_amdgcn_s_barrier()
; #define PG8_SCHED __builtin_amdgcn_sched_barrier(0)
; template <class Epi>
; DI void gemm_phase(LAS unsigned char* lds, const int wid, const Gemm g, const Order& S, const Epi& E) {
;     ...
;         for (int t = 0; t < nt; t += 2) {
;             const bool last = (t == nt - 2);
;             const char* a1 = cA + (size_t)(t + 1) * kstep;
;             const char* a2 = last ? nA : cA + (size_t)(t + 2) * kstep; const char* b2 = last ? nB : cB + (size_t)(t + 2) * kstep;
;             const char* a3 = a2 + kstep; const char* b3 = b2 + kstep;
;             PG8_LDB(B0, 0, 0); PG8_LDB(B1, 0, 1); PG8_SCHED; PG8_LDA(At, 0, 0); PG8_STAGE(PG8_SA(1, 1), a1 + hstepA, voffA);
;             PG8_WAIT_V(8); PG8_WAIT_L(0); PG8_BAR; PG8_MMA(0, 0, At, B0); PG8_MMA(0, 1, At, B1); PG8_BAR; PG8_SCHED;
;             PG8_LDA(At, 0, 1); PG8_STAGE(PG8_SB(0, 0), b2, voffB); PG8_STAGE(PG8_SB(0, 1), b2 + hstepB, voffB); PG8_STAGE(PG8_SA(0, 0), a2, voffA);
;             PG8_WAIT_V(8); PG8_WAIT_L(0); PG8_BAR; PG8_MMA(1, 0, At, B0); PG8_MMA(1, 1, At, B1); PG8_BAR; PG8_SCHED;
.LBB0_1525:
	s_add_u32 s52, s26, 0x100
	v_mov_b32_e32 v0, 0
	s_addc_u32 s53, s27, 0
	s_mov_b32 s54, -2
	ds_read_b128 v[128:131], v229
	ds_read_b128 v[132:135], v229 offset:1024
	ds_read_b128 v[136:139], v229 offset:2048
	ds_read_b128 v[140:143], v229 offset:3072
	ds_read_b128 v[144:147], v230
	ds_read_b128 v[148:151], v230 offset:1024
	ds_read_b128 v[152:155], v230 offset:2048
	ds_read_b128 v[156:159], v230 offset:3072
	s_add_u32 s4, s24, 0x100
	s_addc_u32 s5, s25, 0
	s_cmp_eq_u32 s54, 40
	s_cselect_b32 s29, s21, s5
	s_cselect_b32 s28, s20, s4
	s_cselect_b32 s27, s23, s53
	s_cselect_b32 s26, s22, s52
	v_lshl_add_u64 v[208:209], s[24:25], 0, v[184:185]
	s_add_i32 m0, s36, 0xc000
	ds_read_b128 v[160:163], v231
	ds_read_b128 v[164:167], v231 offset:1024
	ds_read_b128 v[168:171], v231 offset:2048
	ds_read_b128 v[172:175], v231 offset:3072
	ds_read_b128 v[192:195], v231 offset:4096
	ds_read_b128 v[196:199], v231 offset:5120
	ds_read_b128 v[200:203], v231 offset:6144
	ds_read_b128 v[204:207], v231 offset:7168
	global_load_lds_dwordx4 v[208:209], off
	v_lshl_add_u64 v[208:209], s[24:25], 0, v[186:187]
	s_add_i32 m0, s36, 0xe000
	s_nop 0
	global_load_lds_dwordx4 v[208:209], off
	s_waitcnt vmcnt(8)
	s_waitcnt lgkmcnt(0)
	s_barrier
	v_mfma_f32_16x16x32_bf16 v[124:127], v[128:131], v[160:163], 0
	v_mfma_f32_16x16x32_bf16 v[120:123], v[136:139], v[160:163], 0
	v_mfma_f32_16x16x32_bf16 v[108:111], v[128:131], v[168:171], 0
	v_mfma_f32_16x16x32_bf16 v[104:107], v[136:139], v[168:171], 0
	v_mfma_f32_16x16x32_bf16 v[92:95], v[128:131], v[192:195], 0
	v_mfma_f32_16x16x32_bf16 v[88:91], v[136:139], v[192:195], 0
	v_mfma_f32_16x16x32_bf16 v[76:79], v[128:131], v[200:203], 0
	v_mfma_f32_16x16x32_bf16 v[72:75], v[136:139], v[200:203], 0
	v_mfma_f32_16x16x32_bf16 v[124:127], v[132:135], v[164:167], v[124:127]
	v_mfma_f32_16x16x32_bf16 v[120:123], v[140:143], v[164:167], v[120:123]
	v_mfma_f32_16x16x32_bf16 v[108:111], v[132:135], v[172:175], v[108:111]
	v_mfma_f32_16x16x32_bf16 v[104:107], v[140:143], v[172:175], v[104:107]
	v_mfma_f32_16x16x32_bf16 v[92:95], v[132:135], v[196:199], v[92:95]
	v_mfma_f32_16x16x32_bf16 v[88:91], v[140:143], v[196:199], v[88:91]
	v_mfma_f32_16x16x32_bf16 v[76:79], v[132:135], v[204:207], v[76:79]
	v_mfma_f32_16x16x32_bf16 v[72:75], v[140:143], v[204:207], v[72:75]
	v_mfma_f32_16x16x32_bf16 v[116:119], v[144:147], v[160:163], 0
	v_mfma_f32_16x16x32_bf16 v[112:115], v[152:155], v[160:163], 0
	v_mfma_f32_16x16x32_bf16 v[100:103], v[144:147], v[168:171], 0
	v_mfma_f32_16x16x32_bf16 v[96:99], v[152:155], v[168:171], 0
	v_mfma_f32_16x16x32_bf16 v[84:87], v[144:147], v[192:195], 0
	v_mfma_f32_16x16x32_bf16 v[80:83], v[152:155], v[192:195], 0
	v_mfma_f32_16x16x32_bf16 v[68:71], v[144:147], v[200:203], 0
	v_mfma_f32_16x16x32_bf16 v[64:67], v[152:155], v[200:203], 0
	v_mfma_f32_16x16x32_bf16 v[116:119], v[148:151], v[164:167], v[116:119]
	v_mfma_f32_16x16x32_bf16 v[112:115], v[156:159], v[164:167], v[112:115]
	v_mfma_f32_16x16x32_bf16 v[100:103], v[148:151], v[172:175], v[100:103]
	v_mfma_f32_16x16x32_bf16 v[96:99], v[156:159], v[172:175], v[96:99]
	v_mfma_f32_16x16x32_bf16 v[84:87], v[148:151], v[196:199], v[84:87]
	v_mfma_f32_16x16x32_bf16 v[80:83], v[156:159], v[196:199], v[80:83]
	v_mfma_f32_16x16x32_bf16 v[68:71], v[148:151], v[204:207], v[68:71]
	v_mfma_f32_16x16x32_bf16 v[64:67], v[156:159], v[204:207], v[64:67]
	s_barrier
	s_add_i32 s24, s46, s94
	v_lshl_add_u64 v[208:209], s[26:27], 0, v[178:179]
	s_mov_b32 m0, s24
	ds_read_b128 v[160:163], v231 offset:16384
	ds_read_b128 v[164:167], v231 offset:17408
	ds_read_b128 v[168:171], v231 offset:18432
	ds_read_b128 v[172:175], v231 offset:19456
	ds_read_b128 v[192:195], v231 offset:20480
	ds_read_b128 v[196:199], v231 offset:21504
	ds_read_b128 v[200:203], v231 offset:22528
	ds_read_b128 v[204:207], v231 offset:23552
	global_load_lds_dwordx4 v[208:209], off
	s_add_i32 m0, s24, 0x2000
	s_add_u32 s24, s26, 0xb0000
	v_lshl_add_u64 v[210:211], s[26:27], 0, v[182:183]
	s_addc_u32 s25, s27, 0
	s_add_i32 s55, s47, s94
	global_load_lds_dwordx4 v[210:211], off
	v_lshl_add_u64 v[212:213], s[24:25], 0, v[178:179]
	s_mov_b32 m0, s55
	v_lshl_add_u64 v[214:215], s[28:29], 0, v[180:181]
	global_load_lds_dwordx4 v[212:213], off
	v_lshl_add_u64 v[212:213], s[24:25], 0, v[182:183]
	s_add_i32 m0, s55, 0x2000
	s_nop 0
	global_load_lds_dwordx4 v[212:213], off
	v_lshl_add_u64 v[212:213], s[28:29], 0, v[176:177]
	s_mov_b32 m0, s36
	s_nop 0
	global_load_lds_dwordx4 v[212:213], off
	s_mov_b32 m0, s37
	s_nop 0
	global_load_lds_dwordx4 v[214:215], off
	s_waitcnt vmcnt(8)
	s_waitcnt lgkmcnt(0)
	s_barrier
; #define PG8_STAGE(bufoff, gbase, voff) do { _Pragma("unroll") for (int _i = 0; _i < 2; ++_i) \
;         __builtin_amdgcn_global_load_lds((const unsigned*)((const char*)(gbase) + (voff)[_i]), (LAS unsigned*)(lds + (bufoff) + ldsw + _i * 8192), 16, 0, 0); } while (0)
; #define PG8_LDA(dst, b, h) do { _Pragma("unroll") for (int m = 0; m < 4; ++m) _Pragma("unroll") for (int k = 0; k < 2; ++k) dst[m][k] = *(const LAS bf16x8*)(lds + PG8_SA(b, h) + aoff + m * 2048 + k * 1024); } while (0)
; #define PG8_LDB(dst, b, h) do { _Pragma("unroll") for (int n = 0; n < 2; ++n) _Pragma("unroll") for (int k = 0; k < 2; ++k) dst[n][k] = *(const LAS bf16x8*)(lds + PG8_SB(b, h) + boff + n * 2048 + k * 1024); } while (0)
; #define PG8_MMA(ai, bj, At, Bt) do { __builtin_amdgcn_s_setprio(1); _Pragma("unroll") for (int m = 0; m < 4; ++m) _Pragma("unroll") for (int n = 0; n < 2; ++n) _Pragma("unroll") for (int k = 0; k < 2; ++k) \
;         acc[ai][bj][m][n] = __builtin_amdgcn_mfma_f32_16x16x32_bf16(Bt[n][k], At[m][k], acc[ai][bj][m][n], 0, 0, 0); __builtin_amdgcn_s_setprio(0); } while (0)
; #define PG8_WAIT_V(n) asm volatile("s_waitcnt vmcnt(" #n ")" ::: "memory")
; #define PG8_WAIT_L(n) asm volatile("s_waitcnt lgkmcnt(" #n ")" ::: "memory")
; #define PG8_BAR __builtin_amdgcn_s_barrier()
; #define PG8_SCHED __builtin_amdgcn_sched_barrier(0)
; template <class Epi>
; DI void gemm_phase(LAS unsigned char* lds, const int wid, const Gemm g, const Order& S, const Epi& E) {
;     ...
;             PG8_LDA(At, 0, 1); PG8_STAGE(PG8_SB(0, 0), b2, voffB); PG8_STAGE(PG8_SB(0, 1), b2 + hstepB, voffB); PG8_STAGE(PG8_SA(0, 0), a2, voffA);
;             PG8_WAIT_V(8); PG8_WAIT_L(0); PG8_BAR; PG8_MMA(1, 0, At, B0); PG8_MMA(1, 1, At, B1); PG8_BAR; PG8_SCHED;
;             PG8_LDB(B0, 1, 0); PG8_LDB(B1, 1, 1); PG8_SCHED; PG8_LDA(At, 1, 0); PG8_STAGE(PG8_SA(0, 1), a2 + hstepA, voffA);
;             PG8_WAIT_V(8); PG8_WAIT_L(0); PG8_BAR; PG8_MMA(0, 0, At, B0); PG8_MMA(0, 1, At, B1); PG8_BAR; PG8_SCHED;
	v_mfma_f32_16x16x32_bf16 v[60:63], v[128:131], v[160:163], 0
	v_mfma_f32_16x16x32_bf16 v[56:59], v[136:139], v[160:163], 0
	v_mfma_f32_16x16x32_bf16 v[44:47], v[128:131], v[168:171], 0
	v_mfma_f32_16x16x32_bf16 v[40:43], v[136:139], v[168:171], 0
	v_mfma_f32_16x16x32_bf16 v[28:31], v[128:131], v[192:195], 0
	v_mfma_f32_16x16x32_bf16 v[24:27], v[136:139], v[192:195], 0
	v_mfma_f32_16x16x32_bf16 v[12:15], v[128:131], v[200:203], 0
	v_mfma_f32_16x16x32_bf16 v[8:11], v[136:139], v[200:203], 0
	v_mfma_f32_16x16x32_bf16 v[60:63], v[132:135], v[164:167], v[60:63]
	v_mfma_f32_16x16x32_bf16 v[56:59], v[140:143], v[164:167], v[56:59]
	v_mfma_f32_16x16x32_bf16 v[44:47], v[132:135], v[172:175], v[44:47]
	v_mfma_f32_16x16x32_bf16 v[40:43], v[140:143], v[172:175], v[40:43]
	v_mfma_f32_16x16x32_bf16 v[28:31], v[132:135], v[196:199], v[28:31]
	v_mfma_f32_16x16x32_bf16 v[24:27], v[140:143], v[196:199], v[24:27]
	v_mfma_f32_16x16x32_bf16 v[12:15], v[132:135], v[204:207], v[12:15]
	v_mfma_f32_16x16x32_bf16 v[8:11], v[140:143], v[204:207], v[8:11]
	v_mfma_f32_16x16x32_bf16 v[52:55], v[144:147], v[160:163], 0
	v_mfma_f32_16x16x32_bf16 v[48:51], v[152:155], v[160:163], 0
	v_mfma_f32_16x16x32_bf16 v[36:39], v[144:147], v[168:171], 0
	v_mfma_f32_16x16x32_bf16 v[32:35], v[152:155], v[168:171], 0
	v_mfma_f32_16x16x32_bf16 v[20:23], v[144:147], v[192:195], 0
	v_mfma_f32_16x16x32_bf16 v[16:19], v[152:155], v[192:195], 0
	v_mfma_f32_16x16x32_bf16 v[4:7], v[144:147], v[200:203], 0
	v_mfma_f32_16x16x32_bf16 v[0:3], v[152:155], v[200:203], 0
	v_mfma_f32_16x16x32_bf16 v[52:55], v[148:151], v[164:167], v[52:55]
	v_mfma_f32_16x16x32_bf16 v[48:51], v[156:159], v[164:167], v[48:51]
	v_mfma_f32_16x16x32_bf16 v[36:39], v[148:151], v[172:175], v[36:39]
	v_mfma_f32_16x16x32_bf16 v[32:35], v[156:159], v[172:175], v[32:35]
	v_mfma_f32_16x16x32_bf16 v[20:23], v[148:151], v[196:199], v[20:23]
	v_mfma_f32_16x16x32_bf16 v[16:19], v[156:159], v[196:199], v[16:19]
	v_mfma_f32_16x16x32_bf16 v[4:7], v[148:151], v[204:207], v[4:7]
	v_mfma_f32_16x16x32_bf16 v[0:3], v[156:159], v[204:207], v[0:3]
	s_barrier
	s_add_i32 s55, 0, 0x18000
	s_add_i32 s56, 0, 0x1c000
	v_add_u32_e32 v140, s55, v228
	v_add_u32_e32 v156, s56, v228
	ds_read_b128 v[128:131], v140
	ds_read_b128 v[132:135], v140 offset:1024
	ds_read_b128 v[136:139], v140 offset:2048
	ds_read_b128 v[140:143], v140 offset:3072
	ds_read_b128 v[144:147], v156
	ds_read_b128 v[148:151], v156 offset:1024
	ds_read_b128 v[152:155], v156 offset:2048
	ds_read_b128 v[156:159], v156 offset:3072
	s_add_u32 s24, s28, 0xb0000
	s_addc_u32 s25, s29, 0
	s_mov_b32 m0, s38
	v_lshl_add_u64 v[216:217], s[24:25], 0, v[176:177]
	ds_read_b128 v[160:163], v231 offset:32768
	ds_read_b128 v[164:167], v231 offset:33792
	ds_read_b128 v[168:171], v231 offset:34816
	ds_read_b128 v[172:175], v231 offset:35840
	ds_read_b128 v[192:195], v231 offset:36864
	ds_read_b128 v[196:199], v231 offset:37888
	ds_read_b128 v[200:203], v231 offset:38912
	ds_read_b128 v[204:207], v231 offset:39936
	global_load_lds_dwordx4 v[216:217], off
	v_lshl_add_u64 v[216:217], s[24:25], 0, v[180:181]
	s_mov_b32 m0, s39
	s_nop 0
	global_load_lds_dwordx4 v[216:217], off
	s_waitcnt vmcnt(8)
	s_waitcnt lgkmcnt(0)
	s_barrier
	v_mfma_f32_16x16x32_bf16 v[124:127], v[128:131], v[160:163], v[124:127]
	v_mfma_f32_16x16x32_bf16 v[120:123], v[136:139], v[160:163], v[120:123]
	v_mfma_f32_16x16x32_bf16 v[108:111], v[128:131], v[168:171], v[108:111]
	v_mfma_f32_16x16x32_bf16 v[104:107], v[136:139], v[168:171], v[104:107]
	v_mfma_f32_16x16x32_bf16 v[92:95], v[128:131], v[192:195], v[92:95]
	v_mfma_f32_16x16x32_bf16 v[88:91], v[136:139], v[192:195], v[88:91]
	v_mfma_f32_16x16x32_bf16 v[76:79], v[128:131], v[200:203], v[76:79]
	v_mfma_f32_16x16x32_bf16 v[72:75], v[136:139], v[200:203], v[72:75]
	v_mfma_f32_16x16x32_bf16 v[124:127], v[132:135], v[164:167], v[124:127]
	v_mfma_f32_16x16x32_bf16 v[120:123], v[140:143], v[164:167], v[120:123]
	v_mfma_f32_16x16x32_bf16 v[108:111], v[132:135], v[172:175], v[108:111]
	v_mfma_f32_16x16x32_bf16 v[104:107], v[140:143], v[172:175], v[104:107]
	v_mfma_f32_16x16x32_bf16 v[92:95], v[132:135], v[196:199], v[92:95]
	v_mfma_f32_16x16x32_bf16 v[88:91], v[140:143], v[196:199], v[88:91]
	v_mfma_f32_16x16x32_bf16 v[76:79], v[132:135], v[204:207], v[76:79]
	v_mfma_f32_16x16x32_bf16 v[72:75], v[140:143], v[204:207], v[72:75]
	v_mfma_f32_16x16x32_bf16 v[116:119], v[144:147], v[160:163], v[116:119]
	v_mfma_f32_16x16x32_bf16 v[112:115], v[152:155], v[160:163], v[112:115]
	v_mfma_f32_16x16x32_bf16 v[100:103], v[144:147], v[168:171], v[100:103]
	v_mfma_f32_16x16x32_bf16 v[96:99], v[152:155], v[168:171], v[96:99]
	v_mfma_f32_16x16x32_bf16 v[84:87], v[144:147], v[192:195], v[84:87]
	v_mfma_f32_16x16x32_bf16 v[80:83], v[152:155], v[192:195], v[80:83]
	v_mfma_f32_16x16x32_bf16 v[68:71], v[144:147], v[200:203], v[68:71]
	v_mfma_f32_16x16x32_bf16 v[64:67], v[152:155], v[200:203], v[64:67]
	v_mfma_f32_16x16x32_bf16 v[116:119], v[148:151], v[164:167], v[116:119]
	v_mfma_f32_16x16x32_bf16 v[112:115], v[156:159], v[164:167], v[112:115]
	v_mfma_f32_16x16x32_bf16 v[100:103], v[148:151], v[172:175], v[100:103]
	v_mfma_f32_16x16x32_bf16 v[96:99], v[156:159], v[172:175], v[96:99]
	v_mfma_f32_16x16x32_bf16 v[84:87], v[148:151], v[196:199], v[84:87]
	v_mfma_f32_16x16x32_bf16 v[80:83], v[156:159], v[196:199], v[80:83]
	v_mfma_f32_16x16x32_bf16 v[68:71], v[148:151], v[204:207], v[68:71]
	v_mfma_f32_16x16x32_bf16 v[64:67], v[156:159], v[204:207], v[64:67]
	s_barrier
; #define PG8_STAGE(bufoff, gbase, voff) do { _Pragma("unroll") for (int _i = 0; _i < 2; ++_i) \
;         __builtin_amdgcn_global_load_lds((const unsigned*)((const char*)(gbase) + (voff)[_i]), (LAS unsigned*)(lds + (bufoff) + ldsw + _i * 8192), 16, 0, 0); } while (0)
; #define PG8_LDA(dst, b, h) do { _Pragma("unroll") for (int m = 0; m < 4; ++m) _Pragma("unroll") for (int k = 0; k < 2; ++k) dst[m][k] = *(const LAS bf16x8*)(lds + PG8_SA(b, h) + aoff + m * 2048 + k * 1024); } while (0)
; #define PG8_LDB(dst, b, h) do { _Pragma("unroll") for (int n = 0; n < 2; ++n) _Pragma("unroll") for (int k = 0; k < 2; ++k) dst[n][k] = *(const LAS bf16x8*)(lds + PG8_SB(b, h) + boff + n * 2048 + k * 1024); } while (0)
; #define PG8_WAIT_V(n) asm volatile("s_waitcnt vmcnt(" #n ")" ::: "memory")
; #define PG8_WAIT_L(n) asm volatile("s_waitcnt lgkmcnt(" #n ")" ::: "memory")
; template <class Epi>
; DI void gemm_phase(LAS unsigned char* lds, const int wid, const Gemm g, const Order& S, const Epi& E) {
;     ...
;         for (int t = 0; t < nt; t += 2) {
;             const bool last = (t == nt - 2);
;             const char* a1 = cA + (size_t)(t + 1) * kstep;
;             const char* a2 = last ? nA : cA + (size_t)(t + 2) * kstep; const char* b2 = last ? nB : cB + (size_t)(t + 2) * kstep;
;             const char* a3 = a2 + kstep; const char* b3 = b2 + kstep;
;             PG8_LDB(B0, 0, 0); PG8_LDB(B1, 0, 1); PG8_SCHED; PG8_LDA(At, 0, 0); PG8_STAGE(PG8_SA(1, 1), a1 + hstepA, voffA);
;             PG8_WAIT_V(8); PG8_WAIT_L(0); PG8_BAR; PG8_MMA(0, 0, At, B0); PG8_MMA(0, 1, At, B1); PG8_BAR; PG8_SCHED;
;             PG8_LDA(At, 0, 1); PG8_STAGE(PG8_SB(0, 0), b2, voffB); PG8_STAGE(PG8_SB(0, 1), b2 + hstepB, voffB); PG8_STAGE(PG8_SA(0, 0), a2, voffA);
;             PG8_WAIT_V(8); PG8_WAIT_L(0); PG8_BAR; PG8_MMA(1, 0, At, B0); PG8_MMA(1, 1, At, B1); PG8_BAR; PG8_SCHED;
;             PG8_LDB(B0, 1, 0); PG8_LDB(B1, 1, 1); PG8_SCHED; PG8_LDA(At, 1, 0); PG8_STAGE(PG8_SA(0, 1), a2 + hstepA, voffA);
;             PG8_WAIT_V(8); PG8_WAIT_L(0); PG8_BAR; PG8_MMA(0, 0, At, B0); PG8_MMA(0, 1, At, B1); PG8_BAR; PG8_SCHED;
;             PG8_LDA(At, 1, 1); PG8_STAGE(PG8_SB(1, 0), b3, voffB); PG8_STAGE(PG8_SB(1, 1), b3 + hstepB, voffB); PG8_STAGE(PG8_SA(1, 0), a3, voffA);
;             PG8_WAIT_V(8); PG8_WAIT_L(0); PG8_BAR; PG8_MMA(1, 0, At, B0); PG8_MMA(1, 1, At, B1); PG8_BAR; PG8_SCHED;
	s_add_i32 s24, s55, s94
	v_lshl_add_u64 v[208:209], v[208:209], 0, s[16:17]
	s_mov_b32 m0, s24
	ds_read_b128 v[160:163], v231 offset:49152
	ds_read_b128 v[164:167], v231 offset:50176
	ds_read_b128 v[168:171], v231 offset:51200
	ds_read_b128 v[172:175], v231 offset:52224
	ds_read_b128 v[192:195], v231 offset:53248
	ds_read_b128 v[196:199], v231 offset:54272
	ds_read_b128 v[200:203], v231 offset:55296
	ds_read_b128 v[204:207], v231 offset:56320
	global_load_lds_dwordx4 v[208:209], off
	s_add_i32 m0, s24, 0x2000
	s_add_u32 s24, s26, 0xb0080
	v_lshl_add_u64 v[208:209], v[210:211], 0, s[16:17]
	s_addc_u32 s25, s27, 0
	s_add_i32 s26, s56, s94
	global_load_lds_dwordx4 v[208:209], off
	v_lshl_add_u64 v[208:209], s[24:25], 0, v[178:179]
	s_mov_b32 m0, s26
	s_nop 0
	global_load_lds_dwordx4 v[208:209], off
	v_lshl_add_u64 v[208:209], s[24:25], 0, v[182:183]
	s_add_i32 m0, s26, 0x2000
	s_nop 0
	global_load_lds_dwordx4 v[208:209], off
	v_lshl_add_u64 v[208:209], v[212:213], 0, s[16:17]
	s_mov_b32 m0, s43
	s_nop 0
	global_load_lds_dwordx4 v[208:209], off
	v_lshl_add_u64 v[208:209], v[214:215], 0, s[16:17]
	s_mov_b32 m0, s44
	s_nop 0
	global_load_lds_dwordx4 v[208:209], off
	s_waitcnt vmcnt(8)
	s_waitcnt lgkmcnt(0)
	s_barrier
	v_mfma_f32_16x16x32_bf16 v[60:63], v[128:131], v[160:163], v[60:63]
	v_mfma_f32_16x16x32_bf16 v[56:59], v[136:139], v[160:163], v[56:59]
	v_mfma_f32_16x16x32_bf16 v[44:47], v[128:131], v[168:171], v[44:47]
	v_mfma_f32_16x16x32_bf16 v[40:43], v[136:139], v[168:171], v[40:43]
	v_mfma_f32_16x16x32_bf16 v[28:31], v[128:131], v[192:195], v[28:31]
	v_mfma_f32_16x16x32_bf16 v[24:27], v[136:139], v[192:195], v[24:27]
	v_mfma_f32_16x16x32_bf16 v[12:15], v[128:131], v[200:203], v[12:15]
	v_mfma_f32_16x16x32_bf16 v[8:11], v[136:139], v[200:203], v[8:11]
	v_mfma_f32_16x16x32_bf16 v[60:63], v[132:135], v[164:167], v[60:63]
	v_mfma_f32_16x16x32_bf16 v[56:59], v[140:143], v[164:167], v[56:59]
	v_mfma_f32_16x16x32_bf16 v[44:47], v[132:135], v[172:175], v[44:47]
	v_mfma_f32_16x16x32_bf16 v[40:43], v[140:143], v[172:175], v[40:43]
	v_mfma_f32_16x16x32_bf16 v[28:31], v[132:135], v[196:199], v[28:31]
	v_mfma_f32_16x16x32_bf16 v[24:27], v[140:143], v[196:199], v[24:27]
	v_mfma_f32_16x16x32_bf16 v[12:15], v[132:135], v[204:207], v[12:15]
	v_mfma_f32_16x16x32_bf16 v[8:11], v[140:143], v[204:207], v[8:11]
	v_mfma_f32_16x16x32_bf16 v[52:55], v[144:147], v[160:163], v[52:55]
	v_mfma_f32_16x16x32_bf16 v[48:51], v[152:155], v[160:163], v[48:51]
	v_mfma_f32_16x16x32_bf16 v[36:39], v[144:147], v[168:171], v[36:39]
	v_mfma_f32_16x16x32_bf16 v[32:35], v[152:155], v[168:171], v[32:35]
	v_mfma_f32_16x16x32_bf16 v[20:23], v[144:147], v[192:195], v[20:23]
	v_mfma_f32_16x16x32_bf16 v[16:19], v[152:155], v[192:195], v[16:19]
	v_mfma_f32_16x16x32_bf16 v[4:7], v[144:147], v[200:203], v[4:7]
	v_mfma_f32_16x16x32_bf16 v[0:3], v[152:155], v[200:203], v[0:3]
	v_mfma_f32_16x16x32_bf16 v[52:55], v[148:151], v[164:167], v[52:55]
	v_mfma_f32_16x16x32_bf16 v[48:51], v[156:159], v[164:167], v[48:51]
	v_mfma_f32_16x16x32_bf16 v[36:39], v[148:151], v[172:175], v[36:39]
	v_mfma_f32_16x16x32_bf16 v[32:35], v[156:159], v[172:175], v[32:35]
	v_mfma_f32_16x16x32_bf16 v[20:23], v[148:151], v[196:199], v[20:23]
	v_mfma_f32_16x16x32_bf16 v[16:19], v[156:159], v[196:199], v[16:19]
	v_mfma_f32_16x16x32_bf16 v[4:7], v[148:151], v[204:207], v[4:7]
	v_mfma_f32_16x16x32_bf16 v[0:3], v[156:159], v[204:207], v[0:3]
	s_barrier
	s_add_i32 s54, s54, 2
	s_add_u32 s52, s52, 0x100
	s_addc_u32 s53, s53, 0
	s_cmp_gt_u32 s54, 41
	s_mov_b64 s[24:25], s[4:5]
	s_cbranch_scc0 .LBB0_1526
	s_branch .Lpeel_exit_11
.LBB0_1526:
	ds_read_b128 v[128:131], v229
	ds_read_b128 v[132:135], v229 offset:1024
	ds_read_b128 v[136:139], v229 offset:2048
	ds_read_b128 v[140:143], v229 offset:3072
	ds_read_b128 v[144:147], v230
	ds_read_b128 v[148:151], v230 offset:1024
	ds_read_b128 v[152:155], v230 offset:2048
	ds_read_b128 v[156:159], v230 offset:3072
	s_add_u32 s4, s24, 0x100
	s_addc_u32 s5, s25, 0
	s_cmp_eq_u32 s54, 40
	s_cselect_b32 s29, s21, s5
	s_cselect_b32 s28, s20, s4
	s_cselect_b32 s27, s23, s53
	s_cselect_b32 s26, s22, s52
	v_lshl_add_u64 v[208:209], s[24:25], 0, v[184:185]
	s_add_i32 m0, s36, 0xc000
	ds_read_b128 v[160:163], v231
	ds_read_b128 v[164:167], v231 offset:1024
	ds_read_b128 v[168:171], v231 offset:2048
	ds_read_b128 v[172:175], v231 offset:3072
	ds_read_b128 v[192:195], v231 offset:4096
	ds_read_b128 v[196:199], v231 offset:5120
	ds_read_b128 v[200:203], v231 offset:6144
	ds_read_b128 v[204:207], v231 offset:7168
	global_load_lds_dwordx4 v[208:209], off
	v_lshl_add_u64 v[208:209], s[24:25], 0, v[186:187]
	s_add_i32 m0, s36, 0xe000
	s_nop 0
	global_load_lds_dwordx4 v[208:209], off
	s_waitcnt vmcnt(8)
	s_waitcnt lgkmcnt(0)
	s_barrier
; #define PG8_STAGE(bufoff, gbase, voff) do { _Pragma("unroll") for (int _i = 0; _i < 2; ++_i) \
;         __builtin_amdgcn_global_load_lds((const unsigned*)((const char*)(gbase) + (voff)[_i]), (LAS unsigned*)(lds + (bufoff) + ldsw + _i * 8192), 16, 0, 0); } while (0)
; #define PG8_LDA(dst, b, h) do { _Pragma("unroll") for (int m = 0; m < 4; ++m) _Pragma("unroll") for (int k = 0; k < 2; ++k) dst[m][k] = *(const LAS bf16x8*)(lds + PG8_SA(b, h) + aoff + m * 2048 + k * 1024); } while (0)
; #define PG8_LDB(dst, b, h) do { _Pragma("unroll") for (int n = 0; n < 2; ++n) _Pragma("unroll") for (int k = 0; k < 2; ++k) dst[n][k] = *(const LAS bf16x8*)(lds + PG8_SB(b, h) + boff + n * 2048 + k * 1024); } while (0)
; #define PG8_MMA(ai, bj, At, Bt) do { __builtin_amdgcn_s_setprio(1); _Pragma("unroll") for (int m = 0; m < 4; ++m) _Pragma("unroll") for (int n = 0; n < 2; ++n) _Pragma("unroll") for (int k = 0; k < 2; ++k) \
;         acc[ai][bj][m][n] = __builtin_amdgcn_mfma_f32_16x16x32_bf16(Bt[n][k], At[m][k], acc[ai][bj][m][n], 0, 0, 0); __builtin_amdgcn_s_setprio(0); } while (0)
; #define PG8_WAIT_V(n) asm volatile("s_waitcnt vmcnt(" #n ")" ::: "memory")
; #define PG8_WAIT_L(n) asm volatile("s_waitcnt lgkmcnt(" #n ")" ::: "memory")
; #define PG8_BAR __builtin_amdgcn_s_barrier()
; #define PG8_SCHED __builtin_amdgcn_sched_barrier(0)
; template <class Epi>
; DI void gemm_phase(LAS unsigned char* lds, const int wid, const Gemm g, const Order& S, const Epi& E) {
;     ...
;             PG8_LDB(B0, 0, 0); PG8_LDB(B1, 0, 1); PG8_SCHED; PG8_LDA(At, 0, 0); PG8_STAGE(PG8_SA(1, 1), a1 + hstepA, voffA);
;             PG8_WAIT_V(8); PG8_WAIT_L(0); PG8_BAR; PG8_MMA(0, 0, At, B0); PG8_MMA(0, 1, At, B1); PG8_BAR; PG8_SCHED;
;             PG8_LDA(At, 0, 1); PG8_STAGE(PG8_SB(0, 0), b2, voffB); PG8_STAGE(PG8_SB(0, 1), b2 + hstepB, voffB); PG8_STAGE(PG8_SA(0, 0), a2, voffA);
;             PG8_WAIT_V(8); PG8_WAIT_L(0); PG8_BAR; PG8_MMA(1, 0, At, B0); PG8_MMA(1, 1, At, B1); PG8_BAR; PG8_SCHED;
;             PG8_LDB(B0, 1, 0); PG8_LDB(B1, 1, 1); PG8_SCHED; PG8_LDA(At, 1, 0); PG8_STAGE(PG8_SA(0, 1), a2 + hstepA, voffA);
;             PG8_WAIT_V(8); PG8_WAIT_L(0); PG8_BAR; PG8_MMA(0, 0, At, B0); PG8_MMA(0, 1, At, B1); PG8_BAR; PG8_SCHED;
	v_mfma_f32_16x16x32_bf16 v[124:127], v[128:131], v[160:163], v[124:127]
	v_mfma_f32_16x16x32_bf16 v[120:123], v[136:139], v[160:163], v[120:123]
	v_mfma_f32_16x16x32_bf16 v[108:111], v[128:131], v[168:171], v[108:111]
	v_mfma_f32_16x16x32_bf16 v[104:107], v[136:139], v[168:171], v[104:107]
	v_mfma_f32_16x16x32_bf16 v[92:95], v[128:131], v[192:195], v[92:95]
	v_mfma_f32_16x16x32_bf16 v[88:91], v[136:139], v[192:195], v[88:91]
	v_mfma_f32_16x16x32_bf16 v[76:79], v[128:131], v[200:203], v[76:79]
	v_mfma_f32_16x16x32_bf16 v[72:75], v[136:139], v[200:203], v[72:75]
	v_mfma_f32_16x16x32_bf16 v[124:127], v[132:135], v[164:167], v[124:127]
	v_mfma_f32_16x16x32_bf16 v[120:123], v[140:143], v[164:167], v[120:123]
	v_mfma_f32_16x16x32_bf16 v[108:111], v[132:135], v[172:175], v[108:111]
	v_mfma_f32_16x16x32_bf16 v[104:107], v[140:143], v[172:175], v[104:107]
	v_mfma_f32_16x16x32_bf16 v[92:95], v[132:135], v[196:199], v[92:95]
	v_mfma_f32_16x16x32_bf16 v[88:91], v[140:143], v[196:199], v[88:91]
	v_mfma_f32_16x16x32_bf16 v[76:79], v[132:135], v[204:207], v[76:79]
	v_mfma_f32_16x16x32_bf16 v[72:75], v[140:143], v[204:207], v[72:75]
	v_mfma_f32_16x16x32_bf16 v[116:119], v[144:147], v[160:163], v[116:119]
	v_mfma_f32_16x16x32_bf16 v[112:115], v[152:155], v[160:163], v[112:115]
	v_mfma_f32_16x16x32_bf16 v[100:103], v[144:147], v[168:171], v[100:103]
	v_mfma_f32_16x16x32_bf16 v[96:99], v[152:155], v[168:171], v[96:99]
	v_mfma_f32_16x16x32_bf16 v[84:87], v[144:147], v[192:195], v[84:87]
	v_mfma_f32_16x16x32_bf16 v[80:83], v[152:155], v[192:195], v[80:83]
	v_mfma_f32_16x16x32_bf16 v[68:71], v[144:147], v[200:203], v[68:71]
	v_mfma_f32_16x16x32_bf16 v[64:67], v[152:155], v[200:203], v[64:67]
	v_mfma_f32_16x16x32_bf16 v[116:119], v[148:151], v[164:167], v[116:119]
	v_mfma_f32_16x16x32_bf16 v[112:115], v[156:159], v[164:167], v[112:115]
	v_mfma_f32_16x16x32_bf16 v[100:103], v[148:151], v[172:175], v[100:103]
	v_mfma_f32_16x16x32_bf16 v[96:99], v[156:159], v[172:175], v[96:99]
	v_mfma_f32_16x16x32_bf16 v[84:87], v[148:151], v[196:199], v[84:87]
	v_mfma_f32_16x16x32_bf16 v[80:83], v[156:159], v[196:199], v[80:83]
	v_mfma_f32_16x16x32_bf16 v[68:71], v[148:151], v[204:207], v[68:71]
	v_mfma_f32_16x16x32_bf16 v[64:67], v[156:159], v[204:207], v[64:67]
	s_barrier
	s_add_i32 s24, s46, s94
	v_lshl_add_u64 v[208:209], s[26:27], 0, v[178:179]
	s_mov_b32 m0, s24
	ds_read_b128 v[160:163], v231 offset:16384
	ds_read_b128 v[164:167], v231 offset:17408
	ds_read_b128 v[168:171], v231 offset:18432
	ds_read_b128 v[172:175], v231 offset:19456
	ds_read_b128 v[192:195], v231 offset:20480
	ds_read_b128 v[196:199], v231 offset:21504
	ds_read_b128 v[200:203], v231 offset:22528
	ds_read_b128 v[204:207], v231 offset:23552
	global_load_lds_dwordx4 v[208:209], off
	s_add_i32 m0, s24, 0x2000
	s_add_u32 s24, s26, 0xb0000
	v_lshl_add_u64 v[210:211], s[26:27], 0, v[182:183]
	s_addc_u32 s25, s27, 0
	s_add_i32 s55, s47, s94
	global_load_lds_dwordx4 v[210:211], off
	v_lshl_add_u64 v[212:213], s[24:25], 0, v[178:179]
	s_mov_b32 m0, s55
	v_lshl_add_u64 v[214:215], s[28:29], 0, v[180:181]
	global_load_lds_dwordx4 v[212:213], off
	v_lshl_add_u64 v[212:213], s[24:25], 0, v[182:183]
	s_add_i32 m0, s55, 0x2000
	s_nop 0
	global_load_lds_dwordx4 v[212:213], off
	v_lshl_add_u64 v[212:213], s[28:29], 0, v[176:177]
	s_mov_b32 m0, s36
	s_nop 0
	global_load_lds_dwordx4 v[212:213], off
	s_mov_b32 m0, s37
	s_nop 0
	global_load_lds_dwordx4 v[214:215], off
	s_waitcnt vmcnt(8)
	s_waitcnt lgkmcnt(0)
	s_barrier
	v_mfma_f32_16x16x32_bf16 v[60:63], v[128:131], v[160:163], v[60:63]
	v_mfma_f32_16x16x32_bf16 v[56:59], v[136:139], v[160:163], v[56:59]
	v_mfma_f32_16x16x32_bf16 v[44:47], v[128:131], v[168:171], v[44:47]
	v_mfma_f32_16x16x32_bf16 v[40:43], v[136:139], v[168:171], v[40:43]
	v_mfma_f32_16x16x32_bf16 v[28:31], v[128:131], v[192:195], v[28:31]
	v_mfma_f32_16x16x32_bf16 v[24:27], v[136:139], v[192:195], v[24:27]
	v_mfma_f32_16x16x32_bf16 v[12:15], v[128:131], v[200:203], v[12:15]
	v_mfma_f32_16x16x32_bf16 v[8:11], v[136:139], v[200:203], v[8:11]
	v_mfma_f32_16x16x32_bf16 v[60:63], v[132:135], v[164:167], v[60:63]
	v_mfma_f32_16x16x32_bf16 v[56:59], v[140:143], v[164:167], v[56:59]
	v_mfma_f32_16x16x32_bf16 v[44:47], v[132:135], v[172:175], v[44:47]
	v_mfma_f32_16x16x32_bf16 v[40:43], v[140:143], v[172:175], v[40:43]
	v_mfma_f32_16x16x32_bf16 v[28:31], v[132:135], v[196:199], v[28:31]
	v_mfma_f32_16x16x32_bf16 v[24:27], v[140:143], v[196:199], v[24:27]
	v_mfma_f32_16x16x32_bf16 v[12:15], v[132:135], v[204:207], v[12:15]
	v_mfma_f32_16x16x32_bf16 v[8:11], v[140:143], v[204:207], v[8:11]
	v_mfma_f32_16x16x32_bf16 v[52:55], v[144:147], v[160:163], v[52:55]
	v_mfma_f32_16x16x32_bf16 v[48:51], v[152:155], v[160:163], v[48:51]
	v_mfma_f32_16x16x32_bf16 v[36:39], v[144:147], v[168:171], v[36:39]
	v_mfma_f32_16x16x32_bf16 v[32:35], v[152:155], v[168:171], v[32:35]
	v_mfma_f32_16x16x32_bf16 v[20:23], v[144:147], v[192:195], v[20:23]
	v_mfma_f32_16x16x32_bf16 v[16:19], v[152:155], v[192:195], v[16:19]
	v_mfma_f32_16x16x32_bf16 v[4:7], v[144:147], v[200:203], v[4:7]
	v_mfma_f32_16x16x32_bf16 v[0:3], v[152:155], v[200:203], v[0:3]
	v_mfma_f32_16x16x32_bf16 v[52:55], v[148:151], v[164:167], v[52:55]
	v_mfma_f32_16x16x32_bf16 v[48:51], v[156:159], v[164:167], v[48:51]
	v_mfma_f32_16x16x32_bf16 v[36:39], v[148:151], v[172:175], v[36:39]
	v_mfma_f32_16x16x32_bf16 v[32:35], v[156:159], v[172:175], v[32:35]
	v_mfma_f32_16x16x32_bf16 v[20:23], v[148:151], v[196:199], v[20:23]
	v_mfma_f32_16x16x32_bf16 v[16:19], v[156:159], v[196:199], v[16:19]
	v_mfma_f32_16x16x32_bf16 v[4:7], v[148:151], v[204:207], v[4:7]
	v_mfma_f32_16x16x32_bf16 v[0:3], v[156:159], v[204:207], v[0:3]
	s_barrier
; #define PG8_STAGE(bufoff, gbase, voff) do { _Pragma("unroll") for (int _i = 0; _i < 2; ++_i) \
;         __builtin_amdgcn_global_load_lds((const unsigned*)((const char*)(gbase) + (voff)[_i]), (LAS unsigned*)(lds + (bufoff) + ldsw + _i * 8192), 16, 0, 0); } while (0)
; #define PG8_LDA(dst, b, h) do { _Pragma("unroll") for (int m = 0; m < 4; ++m) _Pragma("unroll") for (int k = 0; k < 2; ++k) dst[m][k] = *(const LAS bf16x8*)(lds + PG8_SA(b, h) + aoff + m * 2048 + k * 1024); } while (0)
; #define PG8_LDB(dst, b, h) do { _Pragma("unroll") for (int n = 0; n < 2; ++n) _Pragma("unroll") for (int k = 0; k < 2; ++k) dst[n][k] = *(const LAS bf16x8*)(lds + PG8_SB(b, h) + boff + n * 2048 + k * 1024); } while (0)
; #define PG8_MMA(ai, bj, At, Bt) do { __builtin_amdgcn_s_setprio(1); _Pragma("unroll") for (int m = 0; m < 4; ++m) _Pragma("unroll") for (int n = 0; n < 2; ++n) _Pragma("unroll") for (int k = 0; k < 2; ++k) \
;         acc[ai][bj][m][n] = __builtin_amdgcn_mfma_f32_16x16x32_bf16(Bt[n][k], At[m][k], acc[ai][bj][m][n], 0, 0, 0); __builtin_amdgcn_s_setprio(0); } while (0)
; #define PG8_WAIT_V(n) asm volatile("s_waitcnt vmcnt(" #n ")" ::: "memory")
; #define PG8_WAIT_L(n) asm volatile("s_waitcnt lgkmcnt(" #n ")" ::: "memory")
; #define PG8_BAR __builtin_amdgcn_s_barrier()
; #define PG8_SCHED __builtin_amdgcn_sched_barrier(0)
; template <class Epi>
; DI void gemm_phase(LAS unsigned char* lds, const int wid, const Gemm g, const Order& S, const Epi& E) {
;     ...
;         for (int t = 0; t < nt; t += 2) {
;             const bool last = (t == nt - 2);
;     ...
;             PG8_LDB(B0, 1, 0); PG8_LDB(B1, 1, 1); PG8_SCHED; PG8_LDA(At, 1, 0); PG8_STAGE(PG8_SA(0, 1), a2 + hstepA, voffA);
;             PG8_WAIT_V(8); PG8_WAIT_L(0); PG8_BAR; PG8_MMA(0, 0, At, B0); PG8_MMA(0, 1, At, B1); PG8_BAR; PG8_SCHED;
;             PG8_LDA(At, 1, 1); PG8_STAGE(PG8_SB(1, 0), b3, voffB); PG8_STAGE(PG8_SB(1, 1), b3 + hstepB, voffB); PG8_STAGE(PG8_SA(1, 0), a3, voffA);
;             PG8_WAIT_V(8); PG8_WAIT_L(0); PG8_BAR; PG8_MMA(1, 0, At, B0); PG8_MMA(1, 1, At, B1); PG8_BAR; PG8_SCHED;
	s_add_i32 s55, 0, 0x18000
	s_add_i32 s56, 0, 0x1c000
	v_add_u32_e32 v140, s55, v228
	v_add_u32_e32 v156, s56, v228
	ds_read_b128 v[128:131], v140
	ds_read_b128 v[132:135], v140 offset:1024
	ds_read_b128 v[136:139], v140 offset:2048
	ds_read_b128 v[140:143], v140 offset:3072
	ds_read_b128 v[144:147], v156
	ds_read_b128 v[148:151], v156 offset:1024
	ds_read_b128 v[152:155], v156 offset:2048
	ds_read_b128 v[156:159], v156 offset:3072
	s_add_u32 s24, s28, 0xb0000
	s_addc_u32 s25, s29, 0
	s_mov_b32 m0, s38
	v_lshl_add_u64 v[216:217], s[24:25], 0, v[176:177]
	ds_read_b128 v[160:163], v231 offset:32768
	ds_read_b128 v[164:167], v231 offset:33792
	ds_read_b128 v[168:171], v231 offset:34816
	ds_read_b128 v[172:175], v231 offset:35840
	ds_read_b128 v[192:195], v231 offset:36864
	ds_read_b128 v[196:199], v231 offset:37888
	ds_read_b128 v[200:203], v231 offset:38912
	ds_read_b128 v[204:207], v231 offset:39936
	global_load_lds_dwordx4 v[216:217], off
	v_lshl_add_u64 v[216:217], s[24:25], 0, v[180:181]
	s_mov_b32 m0, s39
	s_nop 0
	global_load_lds_dwordx4 v[216:217], off
	s_waitcnt vmcnt(8)
	s_waitcnt lgkmcnt(0)
	s_barrier
	v_mfma_f32_16x16x32_bf16 v[124:127], v[128:131], v[160:163], v[124:127]
	v_mfma_f32_16x16x32_bf16 v[120:123], v[136:139], v[160:163], v[120:123]
	v_mfma_f32_16x16x32_bf16 v[108:111], v[128:131], v[168:171], v[108:111]
	v_mfma_f32_16x16x32_bf16 v[104:107], v[136:139], v[168:171], v[104:107]
	v_mfma_f32_16x16x32_bf16 v[92:95], v[128:131], v[192:195], v[92:95]
	v_mfma_f32_16x16x32_bf16 v[88:91], v[136:139], v[192:195], v[88:91]
	v_mfma_f32_16x16x32_bf16 v[76:79], v[128:131], v[200:203], v[76:79]
	v_mfma_f32_16x16x32_bf16 v[72:75], v[136:139], v[200:203], v[72:75]
	v_mfma_f32_16x16x32_bf16 v[124:127], v[132:135], v[164:167], v[124:127]
	v_mfma_f32_16x16x32_bf16 v[120:123], v[140:143], v[164:167], v[120:123]
	v_mfma_f32_16x16x32_bf16 v[108:111], v[132:135], v[172:175], v[108:111]
	v_mfma_f32_16x16x32_bf16 v[104:107], v[140:143], v[172:175], v[104:107]
	v_mfma_f32_16x16x32_bf16 v[92:95], v[132:135], v[196:199], v[92:95]
	v_mfma_f32_16x16x32_bf16 v[88:91], v[140:143], v[196:199], v[88:91]
	v_mfma_f32_16x16x32_bf16 v[76:79], v[132:135], v[204:207], v[76:79]
	v_mfma_f32_16x16x32_bf16 v[72:75], v[140:143], v[204:207], v[72:75]
	v_mfma_f32_16x16x32_bf16 v[116:119], v[144:147], v[160:163], v[116:119]
	v_mfma_f32_16x16x32_bf16 v[112:115], v[152:155], v[160:163], v[112:115]
	v_mfma_f32_16x16x32_bf16 v[100:103], v[144:147], v[168:171], v[100:103]
	v_mfma_f32_16x16x32_bf16 v[96:99], v[152:155], v[168:171], v[96:99]
	v_mfma_f32_16x16x32_bf16 v[84:87], v[144:147], v[192:195], v[84:87]
	v_mfma_f32_16x16x32_bf16 v[80:83], v[152:155], v[192:195], v[80:83]
	v_mfma_f32_16x16x32_bf16 v[68:71], v[144:147], v[200:203], v[68:71]
	v_mfma_f32_16x16x32_bf16 v[64:67], v[152:155], v[200:203], v[64:67]
	v_mfma_f32_16x16x32_bf16 v[116:119], v[148:151], v[164:167], v[116:119]
	v_mfma_f32_16x16x32_bf16 v[112:115], v[156:159], v[164:167], v[112:115]
	v_mfma_f32_16x16x32_bf16 v[100:103], v[148:151], v[172:175], v[100:103]
	v_mfma_f32_16x16x32_bf16 v[96:99], v[156:159], v[172:175], v[96:99]
	v_mfma_f32_16x16x32_bf16 v[84:87], v[148:151], v[196:199], v[84:87]
	v_mfma_f32_16x16x32_bf16 v[80:83], v[156:159], v[196:199], v[80:83]
	v_mfma_f32_16x16x32_bf16 v[68:71], v[148:151], v[204:207], v[68:71]
	v_mfma_f32_16x16x32_bf16 v[64:67], v[156:159], v[204:207], v[64:67]
	s_barrier
	s_add_i32 s24, s55, s94
	v_lshl_add_u64 v[208:209], v[208:209], 0, s[16:17]
	s_mov_b32 m0, s24
	ds_read_b128 v[160:163], v231 offset:49152
	ds_read_b128 v[164:167], v231 offset:50176
	ds_read_b128 v[168:171], v231 offset:51200
	ds_read_b128 v[172:175], v231 offset:52224
	ds_read_b128 v[192:195], v231 offset:53248
	ds_read_b128 v[196:199], v231 offset:54272
	ds_read_b128 v[200:203], v231 offset:55296
	ds_read_b128 v[204:207], v231 offset:56320
	global_load_lds_dwordx4 v[208:209], off
	s_add_i32 m0, s24, 0x2000
	s_add_u32 s24, s26, 0xb0080
	v_lshl_add_u64 v[208:209], v[210:211], 0, s[16:17]
	s_addc_u32 s25, s27, 0
	s_add_i32 s26, s56, s94
	global_load_lds_dwordx4 v[208:209], off
	v_lshl_add_u64 v[208:209], s[24:25], 0, v[178:179]
	s_mov_b32 m0, s26
	s_nop 0
	global_load_lds_dwordx4 v[208:209], off
	v_lshl_add_u64 v[208:209], s[24:25], 0, v[182:183]
	s_add_i32 m0, s26, 0x2000
	s_nop 0
	global_load_lds_dwordx4 v[208:209], off
	v_lshl_add_u64 v[208:209], v[212:213], 0, s[16:17]
	s_mov_b32 m0, s43
	s_nop 0
	global_load_lds_dwordx4 v[208:209], off
	v_lshl_add_u64 v[208:209], v[214:215], 0, s[16:17]
	s_mov_b32 m0, s44
	s_nop 0
	global_load_lds_dwordx4 v[208:209], off
	s_waitcnt vmcnt(8)
	s_waitcnt lgkmcnt(0)
	s_barrier
	v_mfma_f32_16x16x32_bf16 v[60:63], v[128:131], v[160:163], v[60:63]
	v_mfma_f32_16x16x32_bf16 v[56:59], v[136:139], v[160:163], v[56:59]
	v_mfma_f32_16x16x32_bf16 v[44:47], v[128:131], v[168:171], v[44:47]
	v_mfma_f32_16x16x32_bf16 v[40:43], v[136:139], v[168:171], v[40:43]
	v_mfma_f32_16x16x32_bf16 v[28:31], v[128:131], v[192:195], v[28:31]
	v_mfma_f32_16x16x32_bf16 v[24:27], v[136:139], v[192:195], v[24:27]
	v_mfma_f32_16x16x32_bf16 v[12:15], v[128:131], v[200:203], v[12:15]
	v_mfma_f32_16x16x32_bf16 v[8:11], v[136:139], v[200:203], v[8:11]
	v_mfma_f32_16x16x32_bf16 v[60:63], v[132:135], v[164:167], v[60:63]
	v_mfma_f32_16x16x32_bf16 v[56:59], v[140:143], v[164:167], v[56:59]
	v_mfma_f32_16x16x32_bf16 v[44:47], v[132:135], v[172:175], v[44:47]
	v_mfma_f32_16x16x32_bf16 v[40:43], v[140:143], v[172:175], v[40:43]
	v_mfma_f32_16x16x32_bf16 v[28:31], v[132:135], v[196:199], v[28:31]
	v_mfma_f32_16x16x32_bf16 v[24:27], v[140:143], v[196:199], v[24:27]
	v_mfma_f32_16x16x32_bf16 v[12:15], v[132:135], v[204:207], v[12:15]
	v_mfma_f32_16x16x32_bf16 v[8:11], v[140:143], v[204:207], v[8:11]
	v_mfma_f32_16x16x32_bf16 v[52:55], v[144:147], v[160:163], v[52:55]
	v_mfma_f32_16x16x32_bf16 v[48:51], v[152:155], v[160:163], v[48:51]
	v_mfma_f32_16x16x32_bf16 v[36:39], v[144:147], v[168:171], v[36:39]
	v_mfma_f32_16x16x32_bf16 v[32:35], v[152:155], v[168:171], v[32:35]
	v_mfma_f32_16x16x32_bf16 v[20:23], v[144:147], v[192:195], v[20:23]
	v_mfma_f32_16x16x32_bf16 v[16:19], v[152:155], v[192:195], v[16:19]
	v_mfma_f32_16x16x32_bf16 v[4:7], v[144:147], v[200:203], v[4:7]
	v_mfma_f32_16x16x32_bf16 v[0:3], v[152:155], v[200:203], v[0:3]
	v_mfma_f32_16x16x32_bf16 v[52:55], v[148:151], v[164:167], v[52:55]
	v_mfma_f32_16x16x32_bf16 v[48:51], v[156:159], v[164:167], v[48:51]
	v_mfma_f32_16x16x32_bf16 v[36:39], v[148:151], v[172:175], v[36:39]
	v_mfma_f32_16x16x32_bf16 v[32:35], v[156:159], v[172:175], v[32:35]
	v_mfma_f32_16x16x32_bf16 v[20:23], v[148:151], v[196:199], v[20:23]
	v_mfma_f32_16x16x32_bf16 v[16:19], v[156:159], v[196:199], v[16:19]
	v_mfma_f32_16x16x32_bf16 v[4:7], v[148:151], v[204:207], v[4:7]
	v_mfma_f32_16x16x32_bf16 v[0:3], v[156:159], v[204:207], v[0:3]
	s_barrier
	s_add_i32 s54, s54, 2
	s_add_u32 s52, s52, 0x100
	s_addc_u32 s53, s53, 0
	s_cmp_gt_u32 s54, 41
	s_mov_b64 s[24:25], s[4:5]
	s_cbranch_scc0 .LBB0_1526
